# static priority raise (s_setprio 1) for waves 4..7 inside the hand-scheduled GEMM main loops
# speedup vs baseline: 1.0047x; 1.0047x over previous
; template <bool GATHER>
; DI void gemm256_main(const h16* __restrict__ A, int lda, const int* __restrict__ idx, int m0,
;                      const h16* __restrict__ B, int ldb, int n0, int K, h16* lds, f16v (&acc)[4][2]) {
;   const int tid = otid512(), lane = tid & 63, wv = tid >> 6, wm = wv >> 2, wn = wv & 3;
;   const int lr = tid >> 1, lc = (tid & 1) * 32;
;   unsigned ao = (unsigned)(GATHER ? idx[m0 + lr] : (m0 + lr)) * (unsigned)lda + lc;
;   unsigned bo = (unsigned)(n0 + lr) * (unsigned)ldb + lc;
;   const h16* ap = A; const h16* bp = B;
;     ...
;   u4v ra[4], rb[4];
;   const int nk = K >> 6;
;   __syncthreads();
; #pragma unroll
;   for (int i = 0; i < 4; ++i) { ra[i] = *(const u4v*)(AP_ + 8 * i); rb[i] = *(const u4v*)(BP_ + 8 * i); }
;   ao += 64; bo += 64;
; #pragma unroll
;   for (int i = 0; i < 4; ++i) { *(u4v*)&lds[lr * LDH + lc + 8 * i] = ra[i]; *(u4v*)&lds[(256 + lr) * LDH + lc + 8 * i] = rb[i]; }
; #pragma unroll
;   for (int i = 0; i < 4; ++i) { ra[i] = *(const u4v*)(AP_ + 8 * i); rb[i] = *(const u4v*)(BP_ + 8 * i); }
;   ao += 64; bo += 64;
;   __syncthreads();
;   for (int kt = 0; kt < nk; ++kt) {
;     const h16* As = lds + (kt & 1) * (512 * LDH);
;     const h16* Bs = As + 256 * LDH;
;     h16* Wn = lds + ((kt & 1) ^ 1) * (512 * LDH);
;     if (kt + 1 < nk) {
; #pragma unroll
;       for (int i = 0; i < 4; ++i) { *(u4v*)&Wn[lr * LDH + lc + 8 * i] = ra[i]; *(u4v*)&Wn[(256 + lr) * LDH + lc + 8 * i] = rb[i]; }
;     }
;     if (kt + 2 < nk) {
; #pragma unroll
;       for (int i = 0; i < 4; ++i) { ra[i] = *(const u4v*)(AP_ + 8 * i); rb[i] = *(const u4v*)(BP_ + 8 * i); }
;       ao += 64; bo += 64;
;     }
; #pragma unroll
;     for (int ks = 0; ks < 4; ++ks) {
;       h8v af[4], bf[2];
; #pragma unroll
;       for (int i = 0; i < 4; ++i) af[i] = *(const h8v*)&As[(wm * 128 + i * 32 + (lane & 31)) * LDH + ks * 16 + 8 * (lane >> 5)];
; #pragma unroll
;       for (int j = 0; j < 2; ++j) bf[j] = *(const h8v*)&Bs[(wn * 64 + j * 32 + (lane & 31)) * LDH + ks * 16 + 8 * (lane >> 5)];
; #pragma unroll
; DI void phase_p1(const Params& p, int l, int bid, int nb, int vb, int vnb, unsigned char* smem, unsigned char* smem_half) {
;     ...
;   for (int u = bid; u < 64 * 20; u += nb) {
;     const int m0 = (u / 20) * 256, n0 = (u % 20) * 256;
;     f16v acc[4][2]; acc256_zero(acc);
;     gemm256_main<false>(x16, DM, nullptr, m0, wsm, 1024, n0, 1024, (h16*)smem, acc);
.LBB0_101:
	s_mul_hi_i32 s2, s19, 0x66666667
	s_lshr_b32 s3, s2, 31
	s_ashr_i32 s2, s2, 3
	s_add_i32 s2, s2, s3
	v_mov_b32_e32 v1, v180
	s_mul_i32 s6, s2, 0x1400
	v_ashrrev_i32_e32 v66, 1, v1
	v_lshlrev_b32_e32 v2, 5, v1
	v_subrev_u32_e32 v3, s6, v66
	s_lshl_b32 s3, s2, 8
	v_and_b32_e32 v67, 32, v2
	v_add_u32_e32 v3, s18, v3
	v_add_u32_e32 v2, s3, v66
	v_lshl_or_b32 v133, v3, 10, v67
	v_readlane_b32 s8, v253, 0
	v_lshl_or_b32 v2, v2, 10, v67
	v_add_u32_e32 v18, 0x100000, v133
	v_mov_b32_e32 v3, v0
	v_mov_b32_e32 v19, v0
	v_readlane_b32 s9, v253, 1
	v_add_u32_e32 v34, 0x100040, v133
	v_mov_b32_e32 v35, v0
	v_lshl_add_u64 v[130:131], v[2:3], 1, s[40:41]
	v_lshl_add_u64 v[30:31], v[18:19], 1, s[8:9]
	v_lshl_add_u64 v[62:63], v[34:35], 1, s[8:9]
	s_barrier
	s_mulk_i32 s2, 0xec00
	s_add_i32 s2, s18, s2
	s_movk_i32 s4, 0x280
	s_cmpk_lt_u32 s2, 0x600
	v_mov_b32_e32 v248, v30
	v_mov_b32_e32 v249, v31
	s_cselect_b32 s98, 1, 0
	v_readfirstlane_b32 s99, v180
	s_nop 1
	s_cmp_lt_u32 s99, 0x100
	s_cbranch_scc1 .Lprio_skip_1
	s_setprio 1
.Lprio_skip_1:
	s_cmp_eq_u32 s98, 1
	v_lshrrev_b32_e32 v192, 1, v180
	v_and_b32_e32 v193, 1, v180
	v_mul_u32_u24_e32 v192, 0x90, v192
	v_lshl_add_u32 v178, v193, 6, v192
	v_add_u32_e32 v178, 16, v178
	v_add_u32_e32 v179, 0x12000, v178
	v_lshrrev_b32_e32 v192, 8, v180
	v_and_b32_e32 v194, 31, v180
	v_lshl_or_b32 v192, v192, 7, v194
	v_mul_u32_u24_e32 v192, 0x90, v192
	v_bfe_u32 v193, v180, 5, 1
	v_lshl_add_u32 v192, v193, 4, v192
	v_add_u32_e32 v215, 16, v192
	v_add_u32_e32 v212, 0x12000, v215
	v_bfe_u32 v192, v180, 6, 2
	v_lshl_or_b32 v192, v192, 6, v194
	v_mul_u32_u24_e32 v192, 0x90, v192
	v_lshl_add_u32 v192, v193, 4, v192
	v_add_u32_e32 v213, 0x9010, v192
	v_add_u32_e32 v214, 0x12000, v213
	global_load_dwordx4 v[134:137], v[130:131], off offset:0
	global_load_dwordx4 v[138:141], v[130:131], off offset:16
	global_load_dwordx4 v[142:145], v[130:131], off offset:32
	global_load_dwordx4 v[146:149], v[130:131], off offset:48
	global_load_dwordx4 v[150:153], v[248:249], off offset:0
	global_load_dwordx4 v[154:157], v[248:249], off offset:16
	global_load_dwordx4 v[158:161], v[248:249], off offset:32
	global_load_dwordx4 v[162:165], v[248:249], off offset:48
	s_waitcnt vmcnt(0)
	ds_write_b128 v178, v[134:137]
	ds_write_b128 v178, v[138:141] offset:16
	ds_write_b128 v178, v[142:145] offset:32
	ds_write_b128 v178, v[146:149] offset:48
	ds_write_b128 v178, v[150:153] offset:36864
	ds_write_b128 v178, v[154:157] offset:36880
	ds_write_b128 v178, v[158:161] offset:36896
	ds_write_b128 v178, v[162:165] offset:36912
	global_load_dwordx4 v[134:137], v[130:131], off offset:128
	global_load_dwordx4 v[138:141], v[130:131], off offset:144
	global_load_dwordx4 v[142:145], v[130:131], off offset:160
	global_load_dwordx4 v[146:149], v[130:131], off offset:176
	global_load_dwordx4 v[150:153], v[248:249], off offset:128
	global_load_dwordx4 v[154:157], v[248:249], off offset:144
	global_load_dwordx4 v[158:161], v[248:249], off offset:160
	global_load_dwordx4 v[162:165], v[248:249], off offset:176
	s_waitcnt lgkmcnt(0)
	s_barrier
	ds_read_b128 v[232:235], v213
	ds_read_b128 v[216:219], v215
	ds_read_b128 v[236:239], v213 offset:4608
	ds_read_b128 v[220:223], v215 offset:4608
	ds_read_b128 v[224:227], v215 offset:9216
	ds_read_b128 v[228:231], v215 offset:13824
	ds_read_b128 v[208:211], v213 offset:32
	ds_read_b128 v[240:243], v215 offset:32
	ds_read_b128 v[174:177], v213 offset:4640
	ds_read_b128 v[244:247], v215 offset:4640
	ds_read_b128 v[200:203], v215 offset:9248
	ds_read_b128 v[204:207], v215 offset:13856
	s_waitcnt vmcnt(4)
	ds_write_b128 v179, v[134:137]
	ds_write_b128 v179, v[138:141] offset:16
	ds_write_b128 v179, v[142:145] offset:32
	ds_write_b128 v179, v[146:149] offset:48
	global_load_dwordx4 v[134:137], v[130:131], off offset:256
	global_load_dwordx4 v[138:141], v[130:131], off offset:272
	global_load_dwordx4 v[142:145], v[130:131], off offset:288
	global_load_dwordx4 v[146:149], v[130:131], off offset:304
	s_waitcnt lgkmcnt(14)
	v_mfma_f32_32x32x16_f16 v[114:129], v[232:235], v[216:219], 0
	s_waitcnt lgkmcnt(13)
	v_mfma_f32_32x32x16_f16 v[98:113], v[236:239], v[216:219], 0
	s_waitcnt lgkmcnt(12)
	v_mfma_f32_32x32x16_f16 v[82:97], v[232:235], v[220:223], 0
	v_mfma_f32_32x32x16_f16 v[66:81], v[236:239], v[220:223], 0
	s_waitcnt lgkmcnt(11)
	v_mfma_f32_32x32x16_f16 v[50:65], v[232:235], v[224:227], 0
	v_mfma_f32_32x32x16_f16 v[34:49], v[236:239], v[224:227], 0
	s_waitcnt lgkmcnt(10)
	v_mfma_f32_32x32x16_f16 v[2:17], v[232:235], v[228:231], 0
	v_mfma_f32_32x32x16_f16 v[18:33], v[236:239], v[228:231], 0
	ds_read_b128 v[232:235], v213 offset:64
	ds_read_b128 v[216:219], v215 offset:64
	ds_read_b128 v[236:239], v213 offset:4672
	ds_read_b128 v[220:223], v215 offset:4672
	ds_read_b128 v[224:227], v215 offset:9280
	ds_read_b128 v[228:231], v215 offset:13888
	s_waitcnt vmcnt(4)
	ds_write_b128 v179, v[150:153] offset:36864
	ds_write_b128 v179, v[154:157] offset:36880
	ds_write_b128 v179, v[158:161] offset:36896
	ds_write_b128 v179, v[162:165] offset:36912
	global_load_dwordx4 v[150:153], v[248:249], off offset:256
	global_load_dwordx4 v[154:157], v[248:249], off offset:272
	global_load_dwordx4 v[158:161], v[248:249], off offset:288
	global_load_dwordx4 v[162:165], v[248:249], off offset:304
	s_waitcnt lgkmcnt(15)
	v_mfma_f32_32x32x16_f16 v[114:129], v[208:211], v[240:243], v[114:129]
	s_waitcnt lgkmcnt(15)
	v_mfma_f32_32x32x16_f16 v[98:113], v[174:177], v[240:243], v[98:113]
	s_waitcnt lgkmcnt(15)
	v_mfma_f32_32x32x16_f16 v[82:97], v[208:211], v[244:247], v[82:97]
	v_mfma_f32_32x32x16_f16 v[66:81], v[174:177], v[244:247], v[66:81]
	s_waitcnt lgkmcnt(15)
	v_mfma_f32_32x32x16_f16 v[50:65], v[208:211], v[200:203], v[50:65]
	v_mfma_f32_32x32x16_f16 v[34:49], v[174:177], v[200:203], v[34:49]
	s_waitcnt lgkmcnt(14)
	v_mfma_f32_32x32x16_f16 v[2:17], v[208:211], v[204:207], v[2:17]
	v_mfma_f32_32x32x16_f16 v[18:33], v[174:177], v[204:207], v[18:33]
	ds_read_b128 v[208:211], v213 offset:96
	ds_read_b128 v[240:243], v215 offset:96
	ds_read_b128 v[174:177], v213 offset:4704
	ds_read_b128 v[244:247], v215 offset:4704
	ds_read_b128 v[200:203], v215 offset:9312
	ds_read_b128 v[204:207], v215 offset:13920
	s_waitcnt lgkmcnt(14)
	v_mfma_f32_32x32x16_f16 v[114:129], v[232:235], v[216:219], v[114:129]
	s_waitcnt lgkmcnt(13)
	v_mfma_f32_32x32x16_f16 v[98:113], v[236:239], v[216:219], v[98:113]
	s_waitcnt lgkmcnt(12)
	v_mfma_f32_32x32x16_f16 v[82:97], v[232:235], v[220:223], v[82:97]
	v_mfma_f32_32x32x16_f16 v[66:81], v[236:239], v[220:223], v[66:81]
	s_waitcnt lgkmcnt(11)
	v_mfma_f32_32x32x16_f16 v[50:65], v[232:235], v[224:227], v[50:65]
	v_mfma_f32_32x32x16_f16 v[34:49], v[236:239], v[224:227], v[34:49]
	s_waitcnt lgkmcnt(10)
	v_mfma_f32_32x32x16_f16 v[2:17], v[232:235], v[228:231], v[2:17]
	v_mfma_f32_32x32x16_f16 v[18:33], v[236:239], v[228:231], v[18:33]
	s_waitcnt lgkmcnt(0)
	s_barrier
; DI f16v mfma32(h8v a, h8v b, f16v c) { return __builtin_amdgcn_mfma_f32_32x32x16_f16(a, b, c, 0, 0, 0); }
; template <bool GATHER>
; DI void gemm256_main(const h16* __restrict__ A, int lda, const int* __restrict__ idx, int m0,
;                      const h16* __restrict__ B, int ldb, int n0, int K, h16* lds, f16v (&acc)[4][2]) {
;     ...
;   for (int kt = 0; kt < nk; ++kt) {
;     const h16* As = lds + (kt & 1) * (512 * LDH);
;     const h16* Bs = As + 256 * LDH;
;     h16* Wn = lds + ((kt & 1) ^ 1) * (512 * LDH);
;     if (kt + 1 < nk) {
; #pragma unroll
;       for (int i = 0; i < 4; ++i) { *(u4v*)&Wn[lr * LDH + lc + 8 * i] = ra[i]; *(u4v*)&Wn[(256 + lr) * LDH + lc + 8 * i] = rb[i]; }
;     }
;     if (kt + 2 < nk) {
; #pragma unroll
;       for (int i = 0; i < 4; ++i) { ra[i] = *(const u4v*)(AP_ + 8 * i); rb[i] = *(const u4v*)(BP_ + 8 * i); }
;       ao += 64; bo += 64;
;     }
; #pragma unroll
;     for (int ks = 0; ks < 4; ++ks) {
;       h8v af[4], bf[2];
; #pragma unroll
;       for (int i = 0; i < 4; ++i) af[i] = *(const h8v*)&As[(wm * 128 + i * 32 + (lane & 31)) * LDH + ks * 16 + 8 * (lane >> 5)];
; #pragma unroll
;       for (int j = 0; j < 2; ++j) bf[j] = *(const h8v*)&Bs[(wn * 64 + j * 32 + (lane & 31)) * LDH + ks * 16 + 8 * (lane >> 5)];
; #pragma unroll
;       for (int i = 0; i < 4; ++i)
; #pragma unroll
;         for (int j = 0; j < 2; ++j) acc[i][j] = mfma32(bf[j], af[i], acc[i][j]);
;     }
;     __syncthreads();
	ds_read_b128 v[232:235], v214
	ds_read_b128 v[216:219], v212
	ds_read_b128 v[236:239], v214 offset:4608
	ds_read_b128 v[220:223], v212 offset:4608
	ds_read_b128 v[224:227], v212 offset:9216
	ds_read_b128 v[228:231], v212 offset:13824
	v_mfma_f32_32x32x16_f16 v[114:129], v[208:211], v[240:243], v[114:129]
	v_mfma_f32_32x32x16_f16 v[98:113], v[174:177], v[240:243], v[98:113]
	v_mfma_f32_32x32x16_f16 v[82:97], v[208:211], v[244:247], v[82:97]
	v_mfma_f32_32x32x16_f16 v[66:81], v[174:177], v[244:247], v[66:81]
	v_mfma_f32_32x32x16_f16 v[50:65], v[208:211], v[200:203], v[50:65]
	v_mfma_f32_32x32x16_f16 v[34:49], v[174:177], v[200:203], v[34:49]
	v_mfma_f32_32x32x16_f16 v[2:17], v[208:211], v[204:207], v[2:17]
	v_mfma_f32_32x32x16_f16 v[18:33], v[174:177], v[204:207], v[18:33]
	ds_read_b128 v[208:211], v214 offset:32
	ds_read_b128 v[240:243], v212 offset:32
	ds_read_b128 v[174:177], v214 offset:4640
	ds_read_b128 v[244:247], v212 offset:4640
	ds_read_b128 v[200:203], v212 offset:9248
	ds_read_b128 v[204:207], v212 offset:13856
	s_waitcnt vmcnt(4)
	ds_write_b128 v178, v[134:137]
	ds_write_b128 v178, v[138:141] offset:16
	ds_write_b128 v178, v[142:145] offset:32
	ds_write_b128 v178, v[146:149] offset:48
	global_load_dwordx4 v[134:137], v[130:131], off offset:384
	global_load_dwordx4 v[138:141], v[130:131], off offset:400
	global_load_dwordx4 v[142:145], v[130:131], off offset:416
	global_load_dwordx4 v[146:149], v[130:131], off offset:432
	s_waitcnt lgkmcnt(14)
	v_mfma_f32_32x32x16_f16 v[114:129], v[232:235], v[216:219], v[114:129]
	s_waitcnt lgkmcnt(13)
	v_mfma_f32_32x32x16_f16 v[98:113], v[236:239], v[216:219], v[98:113]
	s_waitcnt lgkmcnt(12)
	v_mfma_f32_32x32x16_f16 v[82:97], v[232:235], v[220:223], v[82:97]
	v_mfma_f32_32x32x16_f16 v[66:81], v[236:239], v[220:223], v[66:81]
	s_waitcnt lgkmcnt(11)
	v_mfma_f32_32x32x16_f16 v[50:65], v[232:235], v[224:227], v[50:65]
	v_mfma_f32_32x32x16_f16 v[34:49], v[236:239], v[224:227], v[34:49]
	s_waitcnt lgkmcnt(10)
	v_mfma_f32_32x32x16_f16 v[2:17], v[232:235], v[228:231], v[2:17]
	v_mfma_f32_32x32x16_f16 v[18:33], v[236:239], v[228:231], v[18:33]
	ds_read_b128 v[232:235], v214 offset:64
	ds_read_b128 v[216:219], v212 offset:64
	ds_read_b128 v[236:239], v214 offset:4672
	ds_read_b128 v[220:223], v212 offset:4672
	ds_read_b128 v[224:227], v212 offset:9280
	ds_read_b128 v[228:231], v212 offset:13888
	s_waitcnt vmcnt(4)
	ds_write_b128 v178, v[150:153] offset:36864
	ds_write_b128 v178, v[154:157] offset:36880
	ds_write_b128 v178, v[158:161] offset:36896
	ds_write_b128 v178, v[162:165] offset:36912
	global_load_dwordx4 v[150:153], v[248:249], off offset:384
	global_load_dwordx4 v[154:157], v[248:249], off offset:400
	global_load_dwordx4 v[158:161], v[248:249], off offset:416
	global_load_dwordx4 v[162:165], v[248:249], off offset:432
	s_waitcnt lgkmcnt(15)
	v_mfma_f32_32x32x16_f16 v[114:129], v[208:211], v[240:243], v[114:129]
	s_waitcnt lgkmcnt(15)
	v_mfma_f32_32x32x16_f16 v[98:113], v[174:177], v[240:243], v[98:113]
	s_waitcnt lgkmcnt(15)
	v_mfma_f32_32x32x16_f16 v[82:97], v[208:211], v[244:247], v[82:97]
	v_mfma_f32_32x32x16_f16 v[66:81], v[174:177], v[244:247], v[66:81]
	s_waitcnt lgkmcnt(15)
	v_mfma_f32_32x32x16_f16 v[50:65], v[208:211], v[200:203], v[50:65]
	v_mfma_f32_32x32x16_f16 v[34:49], v[174:177], v[200:203], v[34:49]
	s_waitcnt lgkmcnt(14)
	v_mfma_f32_32x32x16_f16 v[2:17], v[208:211], v[204:207], v[2:17]
	v_mfma_f32_32x32x16_f16 v[18:33], v[174:177], v[204:207], v[18:33]
	ds_read_b128 v[208:211], v214 offset:96
	ds_read_b128 v[240:243], v212 offset:96
	ds_read_b128 v[174:177], v214 offset:4704
	ds_read_b128 v[244:247], v212 offset:4704
	ds_read_b128 v[200:203], v212 offset:9312
	ds_read_b128 v[204:207], v212 offset:13920
	s_waitcnt lgkmcnt(14)
	v_mfma_f32_32x32x16_f16 v[114:129], v[232:235], v[216:219], v[114:129]
	s_waitcnt lgkmcnt(13)
	v_mfma_f32_32x32x16_f16 v[98:113], v[236:239], v[216:219], v[98:113]
	s_waitcnt lgkmcnt(12)
	v_mfma_f32_32x32x16_f16 v[82:97], v[232:235], v[220:223], v[82:97]
	v_mfma_f32_32x32x16_f16 v[66:81], v[236:239], v[220:223], v[66:81]
	s_waitcnt lgkmcnt(11)
	v_mfma_f32_32x32x16_f16 v[50:65], v[232:235], v[224:227], v[50:65]
	v_mfma_f32_32x32x16_f16 v[34:49], v[236:239], v[224:227], v[34:49]
	s_waitcnt lgkmcnt(10)
	v_mfma_f32_32x32x16_f16 v[2:17], v[232:235], v[228:231], v[2:17]
	v_mfma_f32_32x32x16_f16 v[18:33], v[236:239], v[228:231], v[18:33]
	s_waitcnt lgkmcnt(0)
	s_barrier
; DI f16v mfma32(h8v a, h8v b, f16v c) { return __builtin_amdgcn_mfma_f32_32x32x16_f16(a, b, c, 0, 0, 0); }
; template <bool GATHER>
; DI void gemm256_main(const h16* __restrict__ A, int lda, const int* __restrict__ idx, int m0,
;                      const h16* __restrict__ B, int ldb, int n0, int K, h16* lds, f16v (&acc)[4][2]) {
;     ...
;   for (int kt = 0; kt < nk; ++kt) {
;     const h16* As = lds + (kt & 1) * (512 * LDH);
;     const h16* Bs = As + 256 * LDH;
;     h16* Wn = lds + ((kt & 1) ^ 1) * (512 * LDH);
;     if (kt + 1 < nk) {
; #pragma unroll
;       for (int i = 0; i < 4; ++i) { *(u4v*)&Wn[lr * LDH + lc + 8 * i] = ra[i]; *(u4v*)&Wn[(256 + lr) * LDH + lc + 8 * i] = rb[i]; }
;     }
;     if (kt + 2 < nk) {
; #pragma unroll
;       for (int i = 0; i < 4; ++i) { ra[i] = *(const u4v*)(AP_ + 8 * i); rb[i] = *(const u4v*)(BP_ + 8 * i); }
;       ao += 64; bo += 64;
;     }
; #pragma unroll
;     for (int ks = 0; ks < 4; ++ks) {
;       h8v af[4], bf[2];
; #pragma unroll
;       for (int i = 0; i < 4; ++i) af[i] = *(const h8v*)&As[(wm * 128 + i * 32 + (lane & 31)) * LDH + ks * 16 + 8 * (lane >> 5)];
; #pragma unroll
;       for (int j = 0; j < 2; ++j) bf[j] = *(const h8v*)&Bs[(wn * 64 + j * 32 + (lane & 31)) * LDH + ks * 16 + 8 * (lane >> 5)];
; #pragma unroll
;       for (int i = 0; i < 4; ++i)
; #pragma unroll
;         for (int j = 0; j < 2; ++j) acc[i][j] = mfma32(bf[j], af[i], acc[i][j]);
;     }
;     __syncthreads();
	ds_read_b128 v[232:235], v213
	ds_read_b128 v[216:219], v215
	ds_read_b128 v[236:239], v213 offset:4608
	ds_read_b128 v[220:223], v215 offset:4608
	ds_read_b128 v[224:227], v215 offset:9216
	ds_read_b128 v[228:231], v215 offset:13824
	v_mfma_f32_32x32x16_f16 v[114:129], v[208:211], v[240:243], v[114:129]
	v_mfma_f32_32x32x16_f16 v[98:113], v[174:177], v[240:243], v[98:113]
	v_mfma_f32_32x32x16_f16 v[82:97], v[208:211], v[244:247], v[82:97]
	v_mfma_f32_32x32x16_f16 v[66:81], v[174:177], v[244:247], v[66:81]
	v_mfma_f32_32x32x16_f16 v[50:65], v[208:211], v[200:203], v[50:65]
	v_mfma_f32_32x32x16_f16 v[34:49], v[174:177], v[200:203], v[34:49]
	v_mfma_f32_32x32x16_f16 v[2:17], v[208:211], v[204:207], v[2:17]
	v_mfma_f32_32x32x16_f16 v[18:33], v[174:177], v[204:207], v[18:33]
	ds_read_b128 v[208:211], v213 offset:32
	ds_read_b128 v[240:243], v215 offset:32
	ds_read_b128 v[174:177], v213 offset:4640
	ds_read_b128 v[244:247], v215 offset:4640
	ds_read_b128 v[200:203], v215 offset:9248
	ds_read_b128 v[204:207], v215 offset:13856
	s_waitcnt vmcnt(4)
	ds_write_b128 v179, v[134:137]
	ds_write_b128 v179, v[138:141] offset:16
	ds_write_b128 v179, v[142:145] offset:32
	ds_write_b128 v179, v[146:149] offset:48
	global_load_dwordx4 v[134:137], v[130:131], off offset:512
	global_load_dwordx4 v[138:141], v[130:131], off offset:528
	global_load_dwordx4 v[142:145], v[130:131], off offset:544
	global_load_dwordx4 v[146:149], v[130:131], off offset:560
	s_waitcnt lgkmcnt(14)
	v_mfma_f32_32x32x16_f16 v[114:129], v[232:235], v[216:219], v[114:129]
	s_waitcnt lgkmcnt(13)
	v_mfma_f32_32x32x16_f16 v[98:113], v[236:239], v[216:219], v[98:113]
	s_waitcnt lgkmcnt(12)
	v_mfma_f32_32x32x16_f16 v[82:97], v[232:235], v[220:223], v[82:97]
	v_mfma_f32_32x32x16_f16 v[66:81], v[236:239], v[220:223], v[66:81]
	s_waitcnt lgkmcnt(11)
	v_mfma_f32_32x32x16_f16 v[50:65], v[232:235], v[224:227], v[50:65]
	v_mfma_f32_32x32x16_f16 v[34:49], v[236:239], v[224:227], v[34:49]
	s_waitcnt lgkmcnt(10)
	v_mfma_f32_32x32x16_f16 v[2:17], v[232:235], v[228:231], v[2:17]
	v_mfma_f32_32x32x16_f16 v[18:33], v[236:239], v[228:231], v[18:33]
	ds_read_b128 v[232:235], v213 offset:64
	ds_read_b128 v[216:219], v215 offset:64
	ds_read_b128 v[236:239], v213 offset:4672
	ds_read_b128 v[220:223], v215 offset:4672
	ds_read_b128 v[224:227], v215 offset:9280
	ds_read_b128 v[228:231], v215 offset:13888
	s_waitcnt vmcnt(4)
	ds_write_b128 v179, v[150:153] offset:36864
	ds_write_b128 v179, v[154:157] offset:36880
	ds_write_b128 v179, v[158:161] offset:36896
	ds_write_b128 v179, v[162:165] offset:36912
	global_load_dwordx4 v[150:153], v[248:249], off offset:512
	global_load_dwordx4 v[154:157], v[248:249], off offset:528
	global_load_dwordx4 v[158:161], v[248:249], off offset:544
	global_load_dwordx4 v[162:165], v[248:249], off offset:560
	s_waitcnt lgkmcnt(15)
	v_mfma_f32_32x32x16_f16 v[114:129], v[208:211], v[240:243], v[114:129]
	s_waitcnt lgkmcnt(15)
	v_mfma_f32_32x32x16_f16 v[98:113], v[174:177], v[240:243], v[98:113]
	s_waitcnt lgkmcnt(15)
	v_mfma_f32_32x32x16_f16 v[82:97], v[208:211], v[244:247], v[82:97]
	v_mfma_f32_32x32x16_f16 v[66:81], v[174:177], v[244:247], v[66:81]
	s_waitcnt lgkmcnt(15)
	v_mfma_f32_32x32x16_f16 v[50:65], v[208:211], v[200:203], v[50:65]
	v_mfma_f32_32x32x16_f16 v[34:49], v[174:177], v[200:203], v[34:49]
	s_waitcnt lgkmcnt(14)
	v_mfma_f32_32x32x16_f16 v[2:17], v[208:211], v[204:207], v[2:17]
	v_mfma_f32_32x32x16_f16 v[18:33], v[174:177], v[204:207], v[18:33]
	ds_read_b128 v[208:211], v213 offset:96
	ds_read_b128 v[240:243], v215 offset:96
	ds_read_b128 v[174:177], v213 offset:4704
	ds_read_b128 v[244:247], v215 offset:4704
	ds_read_b128 v[200:203], v215 offset:9312
	ds_read_b128 v[204:207], v215 offset:13920
	s_waitcnt lgkmcnt(14)
	v_mfma_f32_32x32x16_f16 v[114:129], v[232:235], v[216:219], v[114:129]
	s_waitcnt lgkmcnt(13)
	v_mfma_f32_32x32x16_f16 v[98:113], v[236:239], v[216:219], v[98:113]
	s_waitcnt lgkmcnt(12)
	v_mfma_f32_32x32x16_f16 v[82:97], v[232:235], v[220:223], v[82:97]
	v_mfma_f32_32x32x16_f16 v[66:81], v[236:239], v[220:223], v[66:81]
	s_waitcnt lgkmcnt(11)
	v_mfma_f32_32x32x16_f16 v[50:65], v[232:235], v[224:227], v[50:65]
	v_mfma_f32_32x32x16_f16 v[34:49], v[236:239], v[224:227], v[34:49]
	s_waitcnt lgkmcnt(10)
	v_mfma_f32_32x32x16_f16 v[2:17], v[232:235], v[228:231], v[2:17]
	v_mfma_f32_32x32x16_f16 v[18:33], v[236:239], v[228:231], v[18:33]
	s_waitcnt lgkmcnt(0)
	s_barrier
; DI f16v mfma32(h8v a, h8v b, f16v c) { return __builtin_amdgcn_mfma_f32_32x32x16_f16(a, b, c, 0, 0, 0); }
; template <bool GATHER>
; DI void gemm256_main(const h16* __restrict__ A, int lda, const int* __restrict__ idx, int m0,
;                      const h16* __restrict__ B, int ldb, int n0, int K, h16* lds, f16v (&acc)[4][2]) {
;     ...
;   for (int kt = 0; kt < nk; ++kt) {
;     const h16* As = lds + (kt & 1) * (512 * LDH);
;     const h16* Bs = As + 256 * LDH;
;     h16* Wn = lds + ((kt & 1) ^ 1) * (512 * LDH);
;     if (kt + 1 < nk) {
; #pragma unroll
;       for (int i = 0; i < 4; ++i) { *(u4v*)&Wn[lr * LDH + lc + 8 * i] = ra[i]; *(u4v*)&Wn[(256 + lr) * LDH + lc + 8 * i] = rb[i]; }
;     }
;     if (kt + 2 < nk) {
; #pragma unroll
;       for (int i = 0; i < 4; ++i) { ra[i] = *(const u4v*)(AP_ + 8 * i); rb[i] = *(const u4v*)(BP_ + 8 * i); }
;       ao += 64; bo += 64;
;     }
; #pragma unroll
;     for (int ks = 0; ks < 4; ++ks) {
;       h8v af[4], bf[2];
; #pragma unroll
;       for (int i = 0; i < 4; ++i) af[i] = *(const h8v*)&As[(wm * 128 + i * 32 + (lane & 31)) * LDH + ks * 16 + 8 * (lane >> 5)];
; #pragma unroll
;       for (int j = 0; j < 2; ++j) bf[j] = *(const h8v*)&Bs[(wn * 64 + j * 32 + (lane & 31)) * LDH + ks * 16 + 8 * (lane >> 5)];
; #pragma unroll
;       for (int i = 0; i < 4; ++i)
; #pragma unroll
;         for (int j = 0; j < 2; ++j) acc[i][j] = mfma32(bf[j], af[i], acc[i][j]);
;     }
;     __syncthreads();
	ds_read_b128 v[232:235], v214
	ds_read_b128 v[216:219], v212
	ds_read_b128 v[236:239], v214 offset:4608
	ds_read_b128 v[220:223], v212 offset:4608
	ds_read_b128 v[224:227], v212 offset:9216
	ds_read_b128 v[228:231], v212 offset:13824
	v_mfma_f32_32x32x16_f16 v[114:129], v[208:211], v[240:243], v[114:129]
	v_mfma_f32_32x32x16_f16 v[98:113], v[174:177], v[240:243], v[98:113]
	v_mfma_f32_32x32x16_f16 v[82:97], v[208:211], v[244:247], v[82:97]
	v_mfma_f32_32x32x16_f16 v[66:81], v[174:177], v[244:247], v[66:81]
	v_mfma_f32_32x32x16_f16 v[50:65], v[208:211], v[200:203], v[50:65]
	v_mfma_f32_32x32x16_f16 v[34:49], v[174:177], v[200:203], v[34:49]
	v_mfma_f32_32x32x16_f16 v[2:17], v[208:211], v[204:207], v[2:17]
	v_mfma_f32_32x32x16_f16 v[18:33], v[174:177], v[204:207], v[18:33]
	ds_read_b128 v[208:211], v214 offset:32
	ds_read_b128 v[240:243], v212 offset:32
	ds_read_b128 v[174:177], v214 offset:4640
	ds_read_b128 v[244:247], v212 offset:4640
	ds_read_b128 v[200:203], v212 offset:9248
	ds_read_b128 v[204:207], v212 offset:13856
	s_waitcnt vmcnt(4)
	ds_write_b128 v178, v[134:137]
	ds_write_b128 v178, v[138:141] offset:16
	ds_write_b128 v178, v[142:145] offset:32
	ds_write_b128 v178, v[146:149] offset:48
	global_load_dwordx4 v[134:137], v[130:131], off offset:640
	global_load_dwordx4 v[138:141], v[130:131], off offset:656
	global_load_dwordx4 v[142:145], v[130:131], off offset:672
	global_load_dwordx4 v[146:149], v[130:131], off offset:688
	s_waitcnt lgkmcnt(14)
	v_mfma_f32_32x32x16_f16 v[114:129], v[232:235], v[216:219], v[114:129]
	s_waitcnt lgkmcnt(13)
	v_mfma_f32_32x32x16_f16 v[98:113], v[236:239], v[216:219], v[98:113]
	s_waitcnt lgkmcnt(12)
	v_mfma_f32_32x32x16_f16 v[82:97], v[232:235], v[220:223], v[82:97]
	v_mfma_f32_32x32x16_f16 v[66:81], v[236:239], v[220:223], v[66:81]
	s_waitcnt lgkmcnt(11)
	v_mfma_f32_32x32x16_f16 v[50:65], v[232:235], v[224:227], v[50:65]
	v_mfma_f32_32x32x16_f16 v[34:49], v[236:239], v[224:227], v[34:49]
	s_waitcnt lgkmcnt(10)
	v_mfma_f32_32x32x16_f16 v[2:17], v[232:235], v[228:231], v[2:17]
	v_mfma_f32_32x32x16_f16 v[18:33], v[236:239], v[228:231], v[18:33]
	ds_read_b128 v[232:235], v214 offset:64
	ds_read_b128 v[216:219], v212 offset:64
	ds_read_b128 v[236:239], v214 offset:4672
	ds_read_b128 v[220:223], v212 offset:4672
	ds_read_b128 v[224:227], v212 offset:9280
	ds_read_b128 v[228:231], v212 offset:13888
	s_waitcnt vmcnt(4)
	ds_write_b128 v178, v[150:153] offset:36864
	ds_write_b128 v178, v[154:157] offset:36880
	ds_write_b128 v178, v[158:161] offset:36896
	ds_write_b128 v178, v[162:165] offset:36912
	global_load_dwordx4 v[150:153], v[248:249], off offset:640
	global_load_dwordx4 v[154:157], v[248:249], off offset:656
	global_load_dwordx4 v[158:161], v[248:249], off offset:672
	global_load_dwordx4 v[162:165], v[248:249], off offset:688
	s_waitcnt lgkmcnt(15)
	v_mfma_f32_32x32x16_f16 v[114:129], v[208:211], v[240:243], v[114:129]
	s_waitcnt lgkmcnt(15)
	v_mfma_f32_32x32x16_f16 v[98:113], v[174:177], v[240:243], v[98:113]
	s_waitcnt lgkmcnt(15)
	v_mfma_f32_32x32x16_f16 v[82:97], v[208:211], v[244:247], v[82:97]
	v_mfma_f32_32x32x16_f16 v[66:81], v[174:177], v[244:247], v[66:81]
	s_waitcnt lgkmcnt(15)
	v_mfma_f32_32x32x16_f16 v[50:65], v[208:211], v[200:203], v[50:65]
	v_mfma_f32_32x32x16_f16 v[34:49], v[174:177], v[200:203], v[34:49]
	s_waitcnt lgkmcnt(14)
	v_mfma_f32_32x32x16_f16 v[2:17], v[208:211], v[204:207], v[2:17]
	v_mfma_f32_32x32x16_f16 v[18:33], v[174:177], v[204:207], v[18:33]
	ds_read_b128 v[208:211], v214 offset:96
	ds_read_b128 v[240:243], v212 offset:96
	ds_read_b128 v[174:177], v214 offset:4704
	ds_read_b128 v[244:247], v212 offset:4704
	ds_read_b128 v[200:203], v212 offset:9312
	ds_read_b128 v[204:207], v212 offset:13920
	s_waitcnt lgkmcnt(14)
	v_mfma_f32_32x32x16_f16 v[114:129], v[232:235], v[216:219], v[114:129]
	s_waitcnt lgkmcnt(13)
	v_mfma_f32_32x32x16_f16 v[98:113], v[236:239], v[216:219], v[98:113]
	s_waitcnt lgkmcnt(12)
	v_mfma_f32_32x32x16_f16 v[82:97], v[232:235], v[220:223], v[82:97]
	v_mfma_f32_32x32x16_f16 v[66:81], v[236:239], v[220:223], v[66:81]
	s_waitcnt lgkmcnt(11)
	v_mfma_f32_32x32x16_f16 v[50:65], v[232:235], v[224:227], v[50:65]
	v_mfma_f32_32x32x16_f16 v[34:49], v[236:239], v[224:227], v[34:49]
	s_waitcnt lgkmcnt(10)
	v_mfma_f32_32x32x16_f16 v[2:17], v[232:235], v[228:231], v[2:17]
	v_mfma_f32_32x32x16_f16 v[18:33], v[236:239], v[228:231], v[18:33]
	s_waitcnt lgkmcnt(0)
	s_barrier
; DI f16v mfma32(h8v a, h8v b, f16v c) { return __builtin_amdgcn_mfma_f32_32x32x16_f16(a, b, c, 0, 0, 0); }
; template <bool GATHER>
; DI void gemm256_main(const h16* __restrict__ A, int lda, const int* __restrict__ idx, int m0,
;                      const h16* __restrict__ B, int ldb, int n0, int K, h16* lds, f16v (&acc)[4][2]) {
;     ...
;   for (int kt = 0; kt < nk; ++kt) {
;     const h16* As = lds + (kt & 1) * (512 * LDH);
;     const h16* Bs = As + 256 * LDH;
;     h16* Wn = lds + ((kt & 1) ^ 1) * (512 * LDH);
;     if (kt + 1 < nk) {
; #pragma unroll
;       for (int i = 0; i < 4; ++i) { *(u4v*)&Wn[lr * LDH + lc + 8 * i] = ra[i]; *(u4v*)&Wn[(256 + lr) * LDH + lc + 8 * i] = rb[i]; }
;     }
;     if (kt + 2 < nk) {
; #pragma unroll
;       for (int i = 0; i < 4; ++i) { ra[i] = *(const u4v*)(AP_ + 8 * i); rb[i] = *(const u4v*)(BP_ + 8 * i); }
;       ao += 64; bo += 64;
;     }
; #pragma unroll
;     for (int ks = 0; ks < 4; ++ks) {
;       h8v af[4], bf[2];
; #pragma unroll
;       for (int i = 0; i < 4; ++i) af[i] = *(const h8v*)&As[(wm * 128 + i * 32 + (lane & 31)) * LDH + ks * 16 + 8 * (lane >> 5)];
; #pragma unroll
;       for (int j = 0; j < 2; ++j) bf[j] = *(const h8v*)&Bs[(wn * 64 + j * 32 + (lane & 31)) * LDH + ks * 16 + 8 * (lane >> 5)];
; #pragma unroll
;       for (int i = 0; i < 4; ++i)
; #pragma unroll
;         for (int j = 0; j < 2; ++j) acc[i][j] = mfma32(bf[j], af[i], acc[i][j]);
;     }
;     __syncthreads();
	ds_read_b128 v[232:235], v213
	ds_read_b128 v[216:219], v215
	ds_read_b128 v[236:239], v213 offset:4608
	ds_read_b128 v[220:223], v215 offset:4608
	ds_read_b128 v[224:227], v215 offset:9216
	ds_read_b128 v[228:231], v215 offset:13824
	v_mfma_f32_32x32x16_f16 v[114:129], v[208:211], v[240:243], v[114:129]
	v_mfma_f32_32x32x16_f16 v[98:113], v[174:177], v[240:243], v[98:113]
	v_mfma_f32_32x32x16_f16 v[82:97], v[208:211], v[244:247], v[82:97]
	v_mfma_f32_32x32x16_f16 v[66:81], v[174:177], v[244:247], v[66:81]
	v_mfma_f32_32x32x16_f16 v[50:65], v[208:211], v[200:203], v[50:65]
	v_mfma_f32_32x32x16_f16 v[34:49], v[174:177], v[200:203], v[34:49]
	v_mfma_f32_32x32x16_f16 v[2:17], v[208:211], v[204:207], v[2:17]
	v_mfma_f32_32x32x16_f16 v[18:33], v[174:177], v[204:207], v[18:33]
	ds_read_b128 v[208:211], v213 offset:32
	ds_read_b128 v[240:243], v215 offset:32
	ds_read_b128 v[174:177], v213 offset:4640
	ds_read_b128 v[244:247], v215 offset:4640
	ds_read_b128 v[200:203], v215 offset:9248
	ds_read_b128 v[204:207], v215 offset:13856
	s_waitcnt vmcnt(4)
	ds_write_b128 v179, v[134:137]
	ds_write_b128 v179, v[138:141] offset:16
	ds_write_b128 v179, v[142:145] offset:32
	ds_write_b128 v179, v[146:149] offset:48
	global_load_dwordx4 v[134:137], v[130:131], off offset:768
	global_load_dwordx4 v[138:141], v[130:131], off offset:784
	global_load_dwordx4 v[142:145], v[130:131], off offset:800
	global_load_dwordx4 v[146:149], v[130:131], off offset:816
	s_waitcnt lgkmcnt(14)
	v_mfma_f32_32x32x16_f16 v[114:129], v[232:235], v[216:219], v[114:129]
	s_waitcnt lgkmcnt(13)
	v_mfma_f32_32x32x16_f16 v[98:113], v[236:239], v[216:219], v[98:113]
	s_waitcnt lgkmcnt(12)
	v_mfma_f32_32x32x16_f16 v[82:97], v[232:235], v[220:223], v[82:97]
	v_mfma_f32_32x32x16_f16 v[66:81], v[236:239], v[220:223], v[66:81]
	s_waitcnt lgkmcnt(11)
	v_mfma_f32_32x32x16_f16 v[50:65], v[232:235], v[224:227], v[50:65]
	v_mfma_f32_32x32x16_f16 v[34:49], v[236:239], v[224:227], v[34:49]
	s_waitcnt lgkmcnt(10)
	v_mfma_f32_32x32x16_f16 v[2:17], v[232:235], v[228:231], v[2:17]
	v_mfma_f32_32x32x16_f16 v[18:33], v[236:239], v[228:231], v[18:33]
	ds_read_b128 v[232:235], v213 offset:64
	ds_read_b128 v[216:219], v215 offset:64
	ds_read_b128 v[236:239], v213 offset:4672
	ds_read_b128 v[220:223], v215 offset:4672
	ds_read_b128 v[224:227], v215 offset:9280
	ds_read_b128 v[228:231], v215 offset:13888
	s_waitcnt vmcnt(4)
	ds_write_b128 v179, v[150:153] offset:36864
	ds_write_b128 v179, v[154:157] offset:36880
	ds_write_b128 v179, v[158:161] offset:36896
	ds_write_b128 v179, v[162:165] offset:36912
	global_load_dwordx4 v[150:153], v[248:249], off offset:768
	global_load_dwordx4 v[154:157], v[248:249], off offset:784
	global_load_dwordx4 v[158:161], v[248:249], off offset:800
	global_load_dwordx4 v[162:165], v[248:249], off offset:816
	s_waitcnt lgkmcnt(15)
	v_mfma_f32_32x32x16_f16 v[114:129], v[208:211], v[240:243], v[114:129]
	s_waitcnt lgkmcnt(15)
	v_mfma_f32_32x32x16_f16 v[98:113], v[174:177], v[240:243], v[98:113]
	s_waitcnt lgkmcnt(15)
	v_mfma_f32_32x32x16_f16 v[82:97], v[208:211], v[244:247], v[82:97]
	v_mfma_f32_32x32x16_f16 v[66:81], v[174:177], v[244:247], v[66:81]
	s_waitcnt lgkmcnt(15)
	v_mfma_f32_32x32x16_f16 v[50:65], v[208:211], v[200:203], v[50:65]
	v_mfma_f32_32x32x16_f16 v[34:49], v[174:177], v[200:203], v[34:49]
	s_waitcnt lgkmcnt(14)
	v_mfma_f32_32x32x16_f16 v[2:17], v[208:211], v[204:207], v[2:17]
	v_mfma_f32_32x32x16_f16 v[18:33], v[174:177], v[204:207], v[18:33]
	ds_read_b128 v[208:211], v213 offset:96
	ds_read_b128 v[240:243], v215 offset:96
	ds_read_b128 v[174:177], v213 offset:4704
	ds_read_b128 v[244:247], v215 offset:4704
	ds_read_b128 v[200:203], v215 offset:9312
	ds_read_b128 v[204:207], v215 offset:13920
	s_waitcnt lgkmcnt(14)
	v_mfma_f32_32x32x16_f16 v[114:129], v[232:235], v[216:219], v[114:129]
	s_waitcnt lgkmcnt(13)
	v_mfma_f32_32x32x16_f16 v[98:113], v[236:239], v[216:219], v[98:113]
	s_waitcnt lgkmcnt(12)
	v_mfma_f32_32x32x16_f16 v[82:97], v[232:235], v[220:223], v[82:97]
	v_mfma_f32_32x32x16_f16 v[66:81], v[236:239], v[220:223], v[66:81]
	s_waitcnt lgkmcnt(11)
	v_mfma_f32_32x32x16_f16 v[50:65], v[232:235], v[224:227], v[50:65]
	v_mfma_f32_32x32x16_f16 v[34:49], v[236:239], v[224:227], v[34:49]
	s_waitcnt lgkmcnt(10)
	v_mfma_f32_32x32x16_f16 v[2:17], v[232:235], v[228:231], v[2:17]
	v_mfma_f32_32x32x16_f16 v[18:33], v[236:239], v[228:231], v[18:33]
	s_waitcnt lgkmcnt(0)
	s_barrier
; DI f16v mfma32(h8v a, h8v b, f16v c) { return __builtin_amdgcn_mfma_f32_32x32x16_f16(a, b, c, 0, 0, 0); }
; template <bool GATHER>
; DI void gemm256_main(const h16* __restrict__ A, int lda, const int* __restrict__ idx, int m0,
;                      const h16* __restrict__ B, int ldb, int n0, int K, h16* lds, f16v (&acc)[4][2]) {
;     ...
;   for (int kt = 0; kt < nk; ++kt) {
;     const h16* As = lds + (kt & 1) * (512 * LDH);
;     const h16* Bs = As + 256 * LDH;
;     h16* Wn = lds + ((kt & 1) ^ 1) * (512 * LDH);
;     if (kt + 1 < nk) {
; #pragma unroll
;       for (int i = 0; i < 4; ++i) { *(u4v*)&Wn[lr * LDH + lc + 8 * i] = ra[i]; *(u4v*)&Wn[(256 + lr) * LDH + lc + 8 * i] = rb[i]; }
;     }
;     if (kt + 2 < nk) {
; #pragma unroll
;       for (int i = 0; i < 4; ++i) { ra[i] = *(const u4v*)(AP_ + 8 * i); rb[i] = *(const u4v*)(BP_ + 8 * i); }
;       ao += 64; bo += 64;
;     }
; #pragma unroll
;     for (int ks = 0; ks < 4; ++ks) {
;       h8v af[4], bf[2];
; #pragma unroll
;       for (int i = 0; i < 4; ++i) af[i] = *(const h8v*)&As[(wm * 128 + i * 32 + (lane & 31)) * LDH + ks * 16 + 8 * (lane >> 5)];
; #pragma unroll
;       for (int j = 0; j < 2; ++j) bf[j] = *(const h8v*)&Bs[(wn * 64 + j * 32 + (lane & 31)) * LDH + ks * 16 + 8 * (lane >> 5)];
; #pragma unroll
;       for (int i = 0; i < 4; ++i)
; #pragma unroll
;         for (int j = 0; j < 2; ++j) acc[i][j] = mfma32(bf[j], af[i], acc[i][j]);
;     }
;     __syncthreads();
	ds_read_b128 v[232:235], v214
	ds_read_b128 v[216:219], v212
	ds_read_b128 v[236:239], v214 offset:4608
	ds_read_b128 v[220:223], v212 offset:4608
	ds_read_b128 v[224:227], v212 offset:9216
	ds_read_b128 v[228:231], v212 offset:13824
	v_mfma_f32_32x32x16_f16 v[114:129], v[208:211], v[240:243], v[114:129]
	v_mfma_f32_32x32x16_f16 v[98:113], v[174:177], v[240:243], v[98:113]
	v_mfma_f32_32x32x16_f16 v[82:97], v[208:211], v[244:247], v[82:97]
	v_mfma_f32_32x32x16_f16 v[66:81], v[174:177], v[244:247], v[66:81]
	v_mfma_f32_32x32x16_f16 v[50:65], v[208:211], v[200:203], v[50:65]
	v_mfma_f32_32x32x16_f16 v[34:49], v[174:177], v[200:203], v[34:49]
	v_mfma_f32_32x32x16_f16 v[2:17], v[208:211], v[204:207], v[2:17]
	v_mfma_f32_32x32x16_f16 v[18:33], v[174:177], v[204:207], v[18:33]
	ds_read_b128 v[208:211], v214 offset:32
	ds_read_b128 v[240:243], v212 offset:32
	ds_read_b128 v[174:177], v214 offset:4640
	ds_read_b128 v[244:247], v212 offset:4640
	ds_read_b128 v[200:203], v212 offset:9248
	ds_read_b128 v[204:207], v212 offset:13856
	s_waitcnt vmcnt(4)
	ds_write_b128 v178, v[134:137]
	ds_write_b128 v178, v[138:141] offset:16
	ds_write_b128 v178, v[142:145] offset:32
	ds_write_b128 v178, v[146:149] offset:48
	global_load_dwordx4 v[134:137], v[130:131], off offset:896
	global_load_dwordx4 v[138:141], v[130:131], off offset:912
	global_load_dwordx4 v[142:145], v[130:131], off offset:928
	global_load_dwordx4 v[146:149], v[130:131], off offset:944
	s_waitcnt lgkmcnt(14)
	v_mfma_f32_32x32x16_f16 v[114:129], v[232:235], v[216:219], v[114:129]
	s_waitcnt lgkmcnt(13)
	v_mfma_f32_32x32x16_f16 v[98:113], v[236:239], v[216:219], v[98:113]
	s_waitcnt lgkmcnt(12)
	v_mfma_f32_32x32x16_f16 v[82:97], v[232:235], v[220:223], v[82:97]
	v_mfma_f32_32x32x16_f16 v[66:81], v[236:239], v[220:223], v[66:81]
	s_waitcnt lgkmcnt(11)
	v_mfma_f32_32x32x16_f16 v[50:65], v[232:235], v[224:227], v[50:65]
	v_mfma_f32_32x32x16_f16 v[34:49], v[236:239], v[224:227], v[34:49]
	s_waitcnt lgkmcnt(10)
	v_mfma_f32_32x32x16_f16 v[2:17], v[232:235], v[228:231], v[2:17]
	v_mfma_f32_32x32x16_f16 v[18:33], v[236:239], v[228:231], v[18:33]
	ds_read_b128 v[232:235], v214 offset:64
	ds_read_b128 v[216:219], v212 offset:64
	ds_read_b128 v[236:239], v214 offset:4672
	ds_read_b128 v[220:223], v212 offset:4672
	ds_read_b128 v[224:227], v212 offset:9280
	ds_read_b128 v[228:231], v212 offset:13888
	s_waitcnt vmcnt(4)
	ds_write_b128 v178, v[150:153] offset:36864
	ds_write_b128 v178, v[154:157] offset:36880
	ds_write_b128 v178, v[158:161] offset:36896
	ds_write_b128 v178, v[162:165] offset:36912
	global_load_dwordx4 v[150:153], v[248:249], off offset:896
	global_load_dwordx4 v[154:157], v[248:249], off offset:912
	global_load_dwordx4 v[158:161], v[248:249], off offset:928
	global_load_dwordx4 v[162:165], v[248:249], off offset:944
	s_waitcnt lgkmcnt(15)
	v_mfma_f32_32x32x16_f16 v[114:129], v[208:211], v[240:243], v[114:129]
	s_waitcnt lgkmcnt(15)
	v_mfma_f32_32x32x16_f16 v[98:113], v[174:177], v[240:243], v[98:113]
	s_waitcnt lgkmcnt(15)
	v_mfma_f32_32x32x16_f16 v[82:97], v[208:211], v[244:247], v[82:97]
	v_mfma_f32_32x32x16_f16 v[66:81], v[174:177], v[244:247], v[66:81]
	s_waitcnt lgkmcnt(15)
	v_mfma_f32_32x32x16_f16 v[50:65], v[208:211], v[200:203], v[50:65]
	v_mfma_f32_32x32x16_f16 v[34:49], v[174:177], v[200:203], v[34:49]
	s_waitcnt lgkmcnt(14)
	v_mfma_f32_32x32x16_f16 v[2:17], v[208:211], v[204:207], v[2:17]
	v_mfma_f32_32x32x16_f16 v[18:33], v[174:177], v[204:207], v[18:33]
	ds_read_b128 v[208:211], v214 offset:96
	ds_read_b128 v[240:243], v212 offset:96
	ds_read_b128 v[174:177], v214 offset:4704
	ds_read_b128 v[244:247], v212 offset:4704
	ds_read_b128 v[200:203], v212 offset:9312
	ds_read_b128 v[204:207], v212 offset:13920
	s_waitcnt lgkmcnt(14)
	v_mfma_f32_32x32x16_f16 v[114:129], v[232:235], v[216:219], v[114:129]
	s_waitcnt lgkmcnt(13)
	v_mfma_f32_32x32x16_f16 v[98:113], v[236:239], v[216:219], v[98:113]
	s_waitcnt lgkmcnt(12)
	v_mfma_f32_32x32x16_f16 v[82:97], v[232:235], v[220:223], v[82:97]
	v_mfma_f32_32x32x16_f16 v[66:81], v[236:239], v[220:223], v[66:81]
	s_waitcnt lgkmcnt(11)
	v_mfma_f32_32x32x16_f16 v[50:65], v[232:235], v[224:227], v[50:65]
	v_mfma_f32_32x32x16_f16 v[34:49], v[236:239], v[224:227], v[34:49]
	s_waitcnt lgkmcnt(10)
	v_mfma_f32_32x32x16_f16 v[2:17], v[232:235], v[228:231], v[2:17]
	v_mfma_f32_32x32x16_f16 v[18:33], v[236:239], v[228:231], v[18:33]
	s_waitcnt lgkmcnt(0)
	s_barrier
; DI f16v mfma32(h8v a, h8v b, f16v c) { return __builtin_amdgcn_mfma_f32_32x32x16_f16(a, b, c, 0, 0, 0); }
; template <bool GATHER>
; DI void gemm256_main(const h16* __restrict__ A, int lda, const int* __restrict__ idx, int m0,
;                      const h16* __restrict__ B, int ldb, int n0, int K, h16* lds, f16v (&acc)[4][2]) {
;     ...
;   for (int kt = 0; kt < nk; ++kt) {
;     const h16* As = lds + (kt & 1) * (512 * LDH);
;     const h16* Bs = As + 256 * LDH;
;     h16* Wn = lds + ((kt & 1) ^ 1) * (512 * LDH);
;     if (kt + 1 < nk) {
; #pragma unroll
;       for (int i = 0; i < 4; ++i) { *(u4v*)&Wn[lr * LDH + lc + 8 * i] = ra[i]; *(u4v*)&Wn[(256 + lr) * LDH + lc + 8 * i] = rb[i]; }
;     }
;     if (kt + 2 < nk) {
; #pragma unroll
;       for (int i = 0; i < 4; ++i) { ra[i] = *(const u4v*)(AP_ + 8 * i); rb[i] = *(const u4v*)(BP_ + 8 * i); }
;       ao += 64; bo += 64;
;     }
; #pragma unroll
;     for (int ks = 0; ks < 4; ++ks) {
;       h8v af[4], bf[2];
; #pragma unroll
;       for (int i = 0; i < 4; ++i) af[i] = *(const h8v*)&As[(wm * 128 + i * 32 + (lane & 31)) * LDH + ks * 16 + 8 * (lane >> 5)];
; #pragma unroll
;       for (int j = 0; j < 2; ++j) bf[j] = *(const h8v*)&Bs[(wn * 64 + j * 32 + (lane & 31)) * LDH + ks * 16 + 8 * (lane >> 5)];
; #pragma unroll
;       for (int i = 0; i < 4; ++i)
; #pragma unroll
;         for (int j = 0; j < 2; ++j) acc[i][j] = mfma32(bf[j], af[i], acc[i][j]);
;     }
;     __syncthreads();
	ds_read_b128 v[232:235], v213
	ds_read_b128 v[216:219], v215
	ds_read_b128 v[236:239], v213 offset:4608
	ds_read_b128 v[220:223], v215 offset:4608
	ds_read_b128 v[224:227], v215 offset:9216
	ds_read_b128 v[228:231], v215 offset:13824
	v_mfma_f32_32x32x16_f16 v[114:129], v[208:211], v[240:243], v[114:129]
	v_mfma_f32_32x32x16_f16 v[98:113], v[174:177], v[240:243], v[98:113]
	v_mfma_f32_32x32x16_f16 v[82:97], v[208:211], v[244:247], v[82:97]
	v_mfma_f32_32x32x16_f16 v[66:81], v[174:177], v[244:247], v[66:81]
	v_mfma_f32_32x32x16_f16 v[50:65], v[208:211], v[200:203], v[50:65]
	v_mfma_f32_32x32x16_f16 v[34:49], v[174:177], v[200:203], v[34:49]
	v_mfma_f32_32x32x16_f16 v[2:17], v[208:211], v[204:207], v[2:17]
	v_mfma_f32_32x32x16_f16 v[18:33], v[174:177], v[204:207], v[18:33]
	ds_read_b128 v[208:211], v213 offset:32
	ds_read_b128 v[240:243], v215 offset:32
	ds_read_b128 v[174:177], v213 offset:4640
	ds_read_b128 v[244:247], v215 offset:4640
	ds_read_b128 v[200:203], v215 offset:9248
	ds_read_b128 v[204:207], v215 offset:13856
	s_waitcnt vmcnt(4)
	ds_write_b128 v179, v[134:137]
	ds_write_b128 v179, v[138:141] offset:16
	ds_write_b128 v179, v[142:145] offset:32
	ds_write_b128 v179, v[146:149] offset:48
	global_load_dwordx4 v[134:137], v[130:131], off offset:1024
	global_load_dwordx4 v[138:141], v[130:131], off offset:1040
	global_load_dwordx4 v[142:145], v[130:131], off offset:1056
	global_load_dwordx4 v[146:149], v[130:131], off offset:1072
	s_waitcnt lgkmcnt(14)
	v_mfma_f32_32x32x16_f16 v[114:129], v[232:235], v[216:219], v[114:129]
	s_waitcnt lgkmcnt(13)
	v_mfma_f32_32x32x16_f16 v[98:113], v[236:239], v[216:219], v[98:113]
	s_waitcnt lgkmcnt(12)
	v_mfma_f32_32x32x16_f16 v[82:97], v[232:235], v[220:223], v[82:97]
	v_mfma_f32_32x32x16_f16 v[66:81], v[236:239], v[220:223], v[66:81]
	s_waitcnt lgkmcnt(11)
	v_mfma_f32_32x32x16_f16 v[50:65], v[232:235], v[224:227], v[50:65]
	v_mfma_f32_32x32x16_f16 v[34:49], v[236:239], v[224:227], v[34:49]
	s_waitcnt lgkmcnt(10)
	v_mfma_f32_32x32x16_f16 v[2:17], v[232:235], v[228:231], v[2:17]
	v_mfma_f32_32x32x16_f16 v[18:33], v[236:239], v[228:231], v[18:33]
	ds_read_b128 v[232:235], v213 offset:64
	ds_read_b128 v[216:219], v215 offset:64
	ds_read_b128 v[236:239], v213 offset:4672
	ds_read_b128 v[220:223], v215 offset:4672
	ds_read_b128 v[224:227], v215 offset:9280
	ds_read_b128 v[228:231], v215 offset:13888
	s_waitcnt vmcnt(4)
	ds_write_b128 v179, v[150:153] offset:36864
	ds_write_b128 v179, v[154:157] offset:36880
	ds_write_b128 v179, v[158:161] offset:36896
	ds_write_b128 v179, v[162:165] offset:36912
	global_load_dwordx4 v[150:153], v[248:249], off offset:1024
	global_load_dwordx4 v[154:157], v[248:249], off offset:1040
	global_load_dwordx4 v[158:161], v[248:249], off offset:1056
	global_load_dwordx4 v[162:165], v[248:249], off offset:1072
	s_waitcnt lgkmcnt(15)
	v_mfma_f32_32x32x16_f16 v[114:129], v[208:211], v[240:243], v[114:129]
	s_waitcnt lgkmcnt(15)
	v_mfma_f32_32x32x16_f16 v[98:113], v[174:177], v[240:243], v[98:113]
	s_waitcnt lgkmcnt(15)
	v_mfma_f32_32x32x16_f16 v[82:97], v[208:211], v[244:247], v[82:97]
	v_mfma_f32_32x32x16_f16 v[66:81], v[174:177], v[244:247], v[66:81]
	s_waitcnt lgkmcnt(15)
	v_mfma_f32_32x32x16_f16 v[50:65], v[208:211], v[200:203], v[50:65]
	v_mfma_f32_32x32x16_f16 v[34:49], v[174:177], v[200:203], v[34:49]
	s_waitcnt lgkmcnt(14)
	v_mfma_f32_32x32x16_f16 v[2:17], v[208:211], v[204:207], v[2:17]
	v_mfma_f32_32x32x16_f16 v[18:33], v[174:177], v[204:207], v[18:33]
	ds_read_b128 v[208:211], v213 offset:96
	ds_read_b128 v[240:243], v215 offset:96
	ds_read_b128 v[174:177], v213 offset:4704
	ds_read_b128 v[244:247], v215 offset:4704
	ds_read_b128 v[200:203], v215 offset:9312
	ds_read_b128 v[204:207], v215 offset:13920
	s_waitcnt lgkmcnt(14)
	v_mfma_f32_32x32x16_f16 v[114:129], v[232:235], v[216:219], v[114:129]
	s_waitcnt lgkmcnt(13)
	v_mfma_f32_32x32x16_f16 v[98:113], v[236:239], v[216:219], v[98:113]
	s_waitcnt lgkmcnt(12)
	v_mfma_f32_32x32x16_f16 v[82:97], v[232:235], v[220:223], v[82:97]
	v_mfma_f32_32x32x16_f16 v[66:81], v[236:239], v[220:223], v[66:81]
	s_waitcnt lgkmcnt(11)
	v_mfma_f32_32x32x16_f16 v[50:65], v[232:235], v[224:227], v[50:65]
	v_mfma_f32_32x32x16_f16 v[34:49], v[236:239], v[224:227], v[34:49]
	s_waitcnt lgkmcnt(10)
	v_mfma_f32_32x32x16_f16 v[2:17], v[232:235], v[228:231], v[2:17]
	v_mfma_f32_32x32x16_f16 v[18:33], v[236:239], v[228:231], v[18:33]
	s_waitcnt lgkmcnt(0)
	s_barrier
; DI f16v mfma32(h8v a, h8v b, f16v c) { return __builtin_amdgcn_mfma_f32_32x32x16_f16(a, b, c, 0, 0, 0); }
; template <bool GATHER>
; DI void gemm256_main(const h16* __restrict__ A, int lda, const int* __restrict__ idx, int m0,
;                      const h16* __restrict__ B, int ldb, int n0, int K, h16* lds, f16v (&acc)[4][2]) {
;     ...
;   for (int kt = 0; kt < nk; ++kt) {
;     const h16* As = lds + (kt & 1) * (512 * LDH);
;     const h16* Bs = As + 256 * LDH;
;     h16* Wn = lds + ((kt & 1) ^ 1) * (512 * LDH);
;     if (kt + 1 < nk) {
; #pragma unroll
;       for (int i = 0; i < 4; ++i) { *(u4v*)&Wn[lr * LDH + lc + 8 * i] = ra[i]; *(u4v*)&Wn[(256 + lr) * LDH + lc + 8 * i] = rb[i]; }
;     }
;     if (kt + 2 < nk) {
; #pragma unroll
;       for (int i = 0; i < 4; ++i) { ra[i] = *(const u4v*)(AP_ + 8 * i); rb[i] = *(const u4v*)(BP_ + 8 * i); }
;       ao += 64; bo += 64;
;     }
; #pragma unroll
;     for (int ks = 0; ks < 4; ++ks) {
;       h8v af[4], bf[2];
; #pragma unroll
;       for (int i = 0; i < 4; ++i) af[i] = *(const h8v*)&As[(wm * 128 + i * 32 + (lane & 31)) * LDH + ks * 16 + 8 * (lane >> 5)];
; #pragma unroll
;       for (int j = 0; j < 2; ++j) bf[j] = *(const h8v*)&Bs[(wn * 64 + j * 32 + (lane & 31)) * LDH + ks * 16 + 8 * (lane >> 5)];
; #pragma unroll
;       for (int i = 0; i < 4; ++i)
; #pragma unroll
;         for (int j = 0; j < 2; ++j) acc[i][j] = mfma32(bf[j], af[i], acc[i][j]);
;     }
;     __syncthreads();
	ds_read_b128 v[232:235], v214
	ds_read_b128 v[216:219], v212
	ds_read_b128 v[236:239], v214 offset:4608
	ds_read_b128 v[220:223], v212 offset:4608
	ds_read_b128 v[224:227], v212 offset:9216
	ds_read_b128 v[228:231], v212 offset:13824
	v_mfma_f32_32x32x16_f16 v[114:129], v[208:211], v[240:243], v[114:129]
	v_mfma_f32_32x32x16_f16 v[98:113], v[174:177], v[240:243], v[98:113]
	v_mfma_f32_32x32x16_f16 v[82:97], v[208:211], v[244:247], v[82:97]
	v_mfma_f32_32x32x16_f16 v[66:81], v[174:177], v[244:247], v[66:81]
	v_mfma_f32_32x32x16_f16 v[50:65], v[208:211], v[200:203], v[50:65]
	v_mfma_f32_32x32x16_f16 v[34:49], v[174:177], v[200:203], v[34:49]
	v_mfma_f32_32x32x16_f16 v[2:17], v[208:211], v[204:207], v[2:17]
	v_mfma_f32_32x32x16_f16 v[18:33], v[174:177], v[204:207], v[18:33]
	ds_read_b128 v[208:211], v214 offset:32
	ds_read_b128 v[240:243], v212 offset:32
	ds_read_b128 v[174:177], v214 offset:4640
	ds_read_b128 v[244:247], v212 offset:4640
	ds_read_b128 v[200:203], v212 offset:9248
	ds_read_b128 v[204:207], v212 offset:13856
	s_waitcnt vmcnt(4)
	ds_write_b128 v178, v[134:137]
	ds_write_b128 v178, v[138:141] offset:16
	ds_write_b128 v178, v[142:145] offset:32
	ds_write_b128 v178, v[146:149] offset:48
	global_load_dwordx4 v[134:137], v[130:131], off offset:1152
	global_load_dwordx4 v[138:141], v[130:131], off offset:1168
	global_load_dwordx4 v[142:145], v[130:131], off offset:1184
	global_load_dwordx4 v[146:149], v[130:131], off offset:1200
	s_waitcnt lgkmcnt(14)
	v_mfma_f32_32x32x16_f16 v[114:129], v[232:235], v[216:219], v[114:129]
	s_waitcnt lgkmcnt(13)
	v_mfma_f32_32x32x16_f16 v[98:113], v[236:239], v[216:219], v[98:113]
	s_waitcnt lgkmcnt(12)
	v_mfma_f32_32x32x16_f16 v[82:97], v[232:235], v[220:223], v[82:97]
	v_mfma_f32_32x32x16_f16 v[66:81], v[236:239], v[220:223], v[66:81]
	s_waitcnt lgkmcnt(11)
	v_mfma_f32_32x32x16_f16 v[50:65], v[232:235], v[224:227], v[50:65]
	v_mfma_f32_32x32x16_f16 v[34:49], v[236:239], v[224:227], v[34:49]
	s_waitcnt lgkmcnt(10)
	v_mfma_f32_32x32x16_f16 v[2:17], v[232:235], v[228:231], v[2:17]
	v_mfma_f32_32x32x16_f16 v[18:33], v[236:239], v[228:231], v[18:33]
	ds_read_b128 v[232:235], v214 offset:64
	ds_read_b128 v[216:219], v212 offset:64
	ds_read_b128 v[236:239], v214 offset:4672
	ds_read_b128 v[220:223], v212 offset:4672
	ds_read_b128 v[224:227], v212 offset:9280
	ds_read_b128 v[228:231], v212 offset:13888
	s_waitcnt vmcnt(4)
	ds_write_b128 v178, v[150:153] offset:36864
	ds_write_b128 v178, v[154:157] offset:36880
	ds_write_b128 v178, v[158:161] offset:36896
	ds_write_b128 v178, v[162:165] offset:36912
	global_load_dwordx4 v[150:153], v[248:249], off offset:1152
	global_load_dwordx4 v[154:157], v[248:249], off offset:1168
	global_load_dwordx4 v[158:161], v[248:249], off offset:1184
	global_load_dwordx4 v[162:165], v[248:249], off offset:1200
	s_waitcnt lgkmcnt(15)
	v_mfma_f32_32x32x16_f16 v[114:129], v[208:211], v[240:243], v[114:129]
	s_waitcnt lgkmcnt(15)
	v_mfma_f32_32x32x16_f16 v[98:113], v[174:177], v[240:243], v[98:113]
	s_waitcnt lgkmcnt(15)
	v_mfma_f32_32x32x16_f16 v[82:97], v[208:211], v[244:247], v[82:97]
	v_mfma_f32_32x32x16_f16 v[66:81], v[174:177], v[244:247], v[66:81]
	s_waitcnt lgkmcnt(15)
	v_mfma_f32_32x32x16_f16 v[50:65], v[208:211], v[200:203], v[50:65]
	v_mfma_f32_32x32x16_f16 v[34:49], v[174:177], v[200:203], v[34:49]
	s_waitcnt lgkmcnt(14)
	v_mfma_f32_32x32x16_f16 v[2:17], v[208:211], v[204:207], v[2:17]
	v_mfma_f32_32x32x16_f16 v[18:33], v[174:177], v[204:207], v[18:33]
	ds_read_b128 v[208:211], v214 offset:96
	ds_read_b128 v[240:243], v212 offset:96
	ds_read_b128 v[174:177], v214 offset:4704
	ds_read_b128 v[244:247], v212 offset:4704
	ds_read_b128 v[200:203], v212 offset:9312
	ds_read_b128 v[204:207], v212 offset:13920
	s_waitcnt lgkmcnt(14)
	v_mfma_f32_32x32x16_f16 v[114:129], v[232:235], v[216:219], v[114:129]
	s_waitcnt lgkmcnt(13)
	v_mfma_f32_32x32x16_f16 v[98:113], v[236:239], v[216:219], v[98:113]
	s_waitcnt lgkmcnt(12)
	v_mfma_f32_32x32x16_f16 v[82:97], v[232:235], v[220:223], v[82:97]
	v_mfma_f32_32x32x16_f16 v[66:81], v[236:239], v[220:223], v[66:81]
	s_waitcnt lgkmcnt(11)
	v_mfma_f32_32x32x16_f16 v[50:65], v[232:235], v[224:227], v[50:65]
	v_mfma_f32_32x32x16_f16 v[34:49], v[236:239], v[224:227], v[34:49]
	s_waitcnt lgkmcnt(10)
	v_mfma_f32_32x32x16_f16 v[2:17], v[232:235], v[228:231], v[2:17]
	v_mfma_f32_32x32x16_f16 v[18:33], v[236:239], v[228:231], v[18:33]
	s_waitcnt lgkmcnt(0)
	s_barrier
; DI f16v mfma32(h8v a, h8v b, f16v c) { return __builtin_amdgcn_mfma_f32_32x32x16_f16(a, b, c, 0, 0, 0); }
; template <bool GATHER>
; DI void gemm256_main(const h16* __restrict__ A, int lda, const int* __restrict__ idx, int m0,
;                      const h16* __restrict__ B, int ldb, int n0, int K, h16* lds, f16v (&acc)[4][2]) {
;     ...
;   for (int kt = 0; kt < nk; ++kt) {
;     const h16* As = lds + (kt & 1) * (512 * LDH);
;     const h16* Bs = As + 256 * LDH;
;     h16* Wn = lds + ((kt & 1) ^ 1) * (512 * LDH);
;     if (kt + 1 < nk) {
; #pragma unroll
;       for (int i = 0; i < 4; ++i) { *(u4v*)&Wn[lr * LDH + lc + 8 * i] = ra[i]; *(u4v*)&Wn[(256 + lr) * LDH + lc + 8 * i] = rb[i]; }
;     }
;     if (kt + 2 < nk) {
; #pragma unroll
;       for (int i = 0; i < 4; ++i) { ra[i] = *(const u4v*)(AP_ + 8 * i); rb[i] = *(const u4v*)(BP_ + 8 * i); }
;       ao += 64; bo += 64;
;     }
; #pragma unroll
;     for (int ks = 0; ks < 4; ++ks) {
;       h8v af[4], bf[2];
; #pragma unroll
;       for (int i = 0; i < 4; ++i) af[i] = *(const h8v*)&As[(wm * 128 + i * 32 + (lane & 31)) * LDH + ks * 16 + 8 * (lane >> 5)];
; #pragma unroll
;       for (int j = 0; j < 2; ++j) bf[j] = *(const h8v*)&Bs[(wn * 64 + j * 32 + (lane & 31)) * LDH + ks * 16 + 8 * (lane >> 5)];
; #pragma unroll
;       for (int i = 0; i < 4; ++i)
; #pragma unroll
;         for (int j = 0; j < 2; ++j) acc[i][j] = mfma32(bf[j], af[i], acc[i][j]);
;     }
;     __syncthreads();
	ds_read_b128 v[232:235], v213
	ds_read_b128 v[216:219], v215
	ds_read_b128 v[236:239], v213 offset:4608
	ds_read_b128 v[220:223], v215 offset:4608
	ds_read_b128 v[224:227], v215 offset:9216
	ds_read_b128 v[228:231], v215 offset:13824
	v_mfma_f32_32x32x16_f16 v[114:129], v[208:211], v[240:243], v[114:129]
	v_mfma_f32_32x32x16_f16 v[98:113], v[174:177], v[240:243], v[98:113]
	v_mfma_f32_32x32x16_f16 v[82:97], v[208:211], v[244:247], v[82:97]
	v_mfma_f32_32x32x16_f16 v[66:81], v[174:177], v[244:247], v[66:81]
	v_mfma_f32_32x32x16_f16 v[50:65], v[208:211], v[200:203], v[50:65]
	v_mfma_f32_32x32x16_f16 v[34:49], v[174:177], v[200:203], v[34:49]
	v_mfma_f32_32x32x16_f16 v[2:17], v[208:211], v[204:207], v[2:17]
	v_mfma_f32_32x32x16_f16 v[18:33], v[174:177], v[204:207], v[18:33]
	ds_read_b128 v[208:211], v213 offset:32
	ds_read_b128 v[240:243], v215 offset:32
	ds_read_b128 v[174:177], v213 offset:4640
	ds_read_b128 v[244:247], v215 offset:4640
	ds_read_b128 v[200:203], v215 offset:9248
	ds_read_b128 v[204:207], v215 offset:13856
	s_waitcnt vmcnt(4)
	ds_write_b128 v179, v[134:137]
	ds_write_b128 v179, v[138:141] offset:16
	ds_write_b128 v179, v[142:145] offset:32
	ds_write_b128 v179, v[146:149] offset:48
	global_load_dwordx4 v[134:137], v[130:131], off offset:1280
	global_load_dwordx4 v[138:141], v[130:131], off offset:1296
	global_load_dwordx4 v[142:145], v[130:131], off offset:1312
	global_load_dwordx4 v[146:149], v[130:131], off offset:1328
	s_waitcnt lgkmcnt(14)
	v_mfma_f32_32x32x16_f16 v[114:129], v[232:235], v[216:219], v[114:129]
	s_waitcnt lgkmcnt(13)
	v_mfma_f32_32x32x16_f16 v[98:113], v[236:239], v[216:219], v[98:113]
	s_waitcnt lgkmcnt(12)
	v_mfma_f32_32x32x16_f16 v[82:97], v[232:235], v[220:223], v[82:97]
	v_mfma_f32_32x32x16_f16 v[66:81], v[236:239], v[220:223], v[66:81]
	s_waitcnt lgkmcnt(11)
	v_mfma_f32_32x32x16_f16 v[50:65], v[232:235], v[224:227], v[50:65]
	v_mfma_f32_32x32x16_f16 v[34:49], v[236:239], v[224:227], v[34:49]
	s_waitcnt lgkmcnt(10)
	v_mfma_f32_32x32x16_f16 v[2:17], v[232:235], v[228:231], v[2:17]
	v_mfma_f32_32x32x16_f16 v[18:33], v[236:239], v[228:231], v[18:33]
	ds_read_b128 v[232:235], v213 offset:64
	ds_read_b128 v[216:219], v215 offset:64
	ds_read_b128 v[236:239], v213 offset:4672
	ds_read_b128 v[220:223], v215 offset:4672
	ds_read_b128 v[224:227], v215 offset:9280
	ds_read_b128 v[228:231], v215 offset:13888
	s_waitcnt vmcnt(4)
	ds_write_b128 v179, v[150:153] offset:36864
	ds_write_b128 v179, v[154:157] offset:36880
	ds_write_b128 v179, v[158:161] offset:36896
	ds_write_b128 v179, v[162:165] offset:36912
	global_load_dwordx4 v[150:153], v[248:249], off offset:1280
	global_load_dwordx4 v[154:157], v[248:249], off offset:1296
	global_load_dwordx4 v[158:161], v[248:249], off offset:1312
	global_load_dwordx4 v[162:165], v[248:249], off offset:1328
	s_waitcnt lgkmcnt(15)
	v_mfma_f32_32x32x16_f16 v[114:129], v[208:211], v[240:243], v[114:129]
	s_waitcnt lgkmcnt(15)
	v_mfma_f32_32x32x16_f16 v[98:113], v[174:177], v[240:243], v[98:113]
	s_waitcnt lgkmcnt(15)
	v_mfma_f32_32x32x16_f16 v[82:97], v[208:211], v[244:247], v[82:97]
	v_mfma_f32_32x32x16_f16 v[66:81], v[174:177], v[244:247], v[66:81]
	s_waitcnt lgkmcnt(15)
	v_mfma_f32_32x32x16_f16 v[50:65], v[208:211], v[200:203], v[50:65]
	v_mfma_f32_32x32x16_f16 v[34:49], v[174:177], v[200:203], v[34:49]
	s_waitcnt lgkmcnt(14)
	v_mfma_f32_32x32x16_f16 v[2:17], v[208:211], v[204:207], v[2:17]
	v_mfma_f32_32x32x16_f16 v[18:33], v[174:177], v[204:207], v[18:33]
	ds_read_b128 v[208:211], v213 offset:96
	ds_read_b128 v[240:243], v215 offset:96
	ds_read_b128 v[174:177], v213 offset:4704
	ds_read_b128 v[244:247], v215 offset:4704
	ds_read_b128 v[200:203], v215 offset:9312
	ds_read_b128 v[204:207], v215 offset:13920
	s_waitcnt lgkmcnt(14)
	v_mfma_f32_32x32x16_f16 v[114:129], v[232:235], v[216:219], v[114:129]
	s_waitcnt lgkmcnt(13)
	v_mfma_f32_32x32x16_f16 v[98:113], v[236:239], v[216:219], v[98:113]
	s_waitcnt lgkmcnt(12)
	v_mfma_f32_32x32x16_f16 v[82:97], v[232:235], v[220:223], v[82:97]
	v_mfma_f32_32x32x16_f16 v[66:81], v[236:239], v[220:223], v[66:81]
	s_waitcnt lgkmcnt(11)
	v_mfma_f32_32x32x16_f16 v[50:65], v[232:235], v[224:227], v[50:65]
	v_mfma_f32_32x32x16_f16 v[34:49], v[236:239], v[224:227], v[34:49]
	s_waitcnt lgkmcnt(10)
	v_mfma_f32_32x32x16_f16 v[2:17], v[232:235], v[228:231], v[2:17]
	v_mfma_f32_32x32x16_f16 v[18:33], v[236:239], v[228:231], v[18:33]
	s_waitcnt lgkmcnt(0)
	s_barrier
; DI f16v mfma32(h8v a, h8v b, f16v c) { return __builtin_amdgcn_mfma_f32_32x32x16_f16(a, b, c, 0, 0, 0); }
; template <bool GATHER>
; DI void gemm256_main(const h16* __restrict__ A, int lda, const int* __restrict__ idx, int m0,
;                      const h16* __restrict__ B, int ldb, int n0, int K, h16* lds, f16v (&acc)[4][2]) {
;     ...
;   for (int kt = 0; kt < nk; ++kt) {
;     const h16* As = lds + (kt & 1) * (512 * LDH);
;     const h16* Bs = As + 256 * LDH;
;     h16* Wn = lds + ((kt & 1) ^ 1) * (512 * LDH);
;     if (kt + 1 < nk) {
; #pragma unroll
;       for (int i = 0; i < 4; ++i) { *(u4v*)&Wn[lr * LDH + lc + 8 * i] = ra[i]; *(u4v*)&Wn[(256 + lr) * LDH + lc + 8 * i] = rb[i]; }
;     }
;     if (kt + 2 < nk) {
; #pragma unroll
;       for (int i = 0; i < 4; ++i) { ra[i] = *(const u4v*)(AP_ + 8 * i); rb[i] = *(const u4v*)(BP_ + 8 * i); }
;       ao += 64; bo += 64;
;     }
; #pragma unroll
;     for (int ks = 0; ks < 4; ++ks) {
;       h8v af[4], bf[2];
; #pragma unroll
;       for (int i = 0; i < 4; ++i) af[i] = *(const h8v*)&As[(wm * 128 + i * 32 + (lane & 31)) * LDH + ks * 16 + 8 * (lane >> 5)];
; #pragma unroll
;       for (int j = 0; j < 2; ++j) bf[j] = *(const h8v*)&Bs[(wn * 64 + j * 32 + (lane & 31)) * LDH + ks * 16 + 8 * (lane >> 5)];
; #pragma unroll
;       for (int i = 0; i < 4; ++i)
; #pragma unroll
;         for (int j = 0; j < 2; ++j) acc[i][j] = mfma32(bf[j], af[i], acc[i][j]);
;     }
;     __syncthreads();
	ds_read_b128 v[232:235], v214
	ds_read_b128 v[216:219], v212
	ds_read_b128 v[236:239], v214 offset:4608
	ds_read_b128 v[220:223], v212 offset:4608
	ds_read_b128 v[224:227], v212 offset:9216
	ds_read_b128 v[228:231], v212 offset:13824
	v_mfma_f32_32x32x16_f16 v[114:129], v[208:211], v[240:243], v[114:129]
	v_mfma_f32_32x32x16_f16 v[98:113], v[174:177], v[240:243], v[98:113]
	v_mfma_f32_32x32x16_f16 v[82:97], v[208:211], v[244:247], v[82:97]
	v_mfma_f32_32x32x16_f16 v[66:81], v[174:177], v[244:247], v[66:81]
	v_mfma_f32_32x32x16_f16 v[50:65], v[208:211], v[200:203], v[50:65]
	v_mfma_f32_32x32x16_f16 v[34:49], v[174:177], v[200:203], v[34:49]
	v_mfma_f32_32x32x16_f16 v[2:17], v[208:211], v[204:207], v[2:17]
	v_mfma_f32_32x32x16_f16 v[18:33], v[174:177], v[204:207], v[18:33]
	ds_read_b128 v[208:211], v214 offset:32
	ds_read_b128 v[240:243], v212 offset:32
	ds_read_b128 v[174:177], v214 offset:4640
	ds_read_b128 v[244:247], v212 offset:4640
	ds_read_b128 v[200:203], v212 offset:9248
	ds_read_b128 v[204:207], v212 offset:13856
	s_waitcnt vmcnt(4)
	ds_write_b128 v178, v[134:137]
	ds_write_b128 v178, v[138:141] offset:16
	ds_write_b128 v178, v[142:145] offset:32
	ds_write_b128 v178, v[146:149] offset:48
	global_load_dwordx4 v[134:137], v[130:131], off offset:1408
	global_load_dwordx4 v[138:141], v[130:131], off offset:1424
	global_load_dwordx4 v[142:145], v[130:131], off offset:1440
	global_load_dwordx4 v[146:149], v[130:131], off offset:1456
	s_waitcnt lgkmcnt(14)
	v_mfma_f32_32x32x16_f16 v[114:129], v[232:235], v[216:219], v[114:129]
	s_waitcnt lgkmcnt(13)
	v_mfma_f32_32x32x16_f16 v[98:113], v[236:239], v[216:219], v[98:113]
	s_waitcnt lgkmcnt(12)
	v_mfma_f32_32x32x16_f16 v[82:97], v[232:235], v[220:223], v[82:97]
	v_mfma_f32_32x32x16_f16 v[66:81], v[236:239], v[220:223], v[66:81]
	s_waitcnt lgkmcnt(11)
	v_mfma_f32_32x32x16_f16 v[50:65], v[232:235], v[224:227], v[50:65]
	v_mfma_f32_32x32x16_f16 v[34:49], v[236:239], v[224:227], v[34:49]
	s_waitcnt lgkmcnt(10)
	v_mfma_f32_32x32x16_f16 v[2:17], v[232:235], v[228:231], v[2:17]
	v_mfma_f32_32x32x16_f16 v[18:33], v[236:239], v[228:231], v[18:33]
	ds_read_b128 v[232:235], v214 offset:64
	ds_read_b128 v[216:219], v212 offset:64
	ds_read_b128 v[236:239], v214 offset:4672
	ds_read_b128 v[220:223], v212 offset:4672
	ds_read_b128 v[224:227], v212 offset:9280
	ds_read_b128 v[228:231], v212 offset:13888
	s_waitcnt vmcnt(4)
	ds_write_b128 v178, v[150:153] offset:36864
	ds_write_b128 v178, v[154:157] offset:36880
	ds_write_b128 v178, v[158:161] offset:36896
	ds_write_b128 v178, v[162:165] offset:36912
	global_load_dwordx4 v[150:153], v[248:249], off offset:1408
	global_load_dwordx4 v[154:157], v[248:249], off offset:1424
	global_load_dwordx4 v[158:161], v[248:249], off offset:1440
	global_load_dwordx4 v[162:165], v[248:249], off offset:1456
	s_waitcnt lgkmcnt(15)
	v_mfma_f32_32x32x16_f16 v[114:129], v[208:211], v[240:243], v[114:129]
	s_waitcnt lgkmcnt(15)
	v_mfma_f32_32x32x16_f16 v[98:113], v[174:177], v[240:243], v[98:113]
	s_waitcnt lgkmcnt(15)
	v_mfma_f32_32x32x16_f16 v[82:97], v[208:211], v[244:247], v[82:97]
	v_mfma_f32_32x32x16_f16 v[66:81], v[174:177], v[244:247], v[66:81]
	s_waitcnt lgkmcnt(15)
	v_mfma_f32_32x32x16_f16 v[50:65], v[208:211], v[200:203], v[50:65]
	v_mfma_f32_32x32x16_f16 v[34:49], v[174:177], v[200:203], v[34:49]
	s_waitcnt lgkmcnt(14)
	v_mfma_f32_32x32x16_f16 v[2:17], v[208:211], v[204:207], v[2:17]
	v_mfma_f32_32x32x16_f16 v[18:33], v[174:177], v[204:207], v[18:33]
	ds_read_b128 v[208:211], v214 offset:96
	ds_read_b128 v[240:243], v212 offset:96
	ds_read_b128 v[174:177], v214 offset:4704
	ds_read_b128 v[244:247], v212 offset:4704
	ds_read_b128 v[200:203], v212 offset:9312
	ds_read_b128 v[204:207], v212 offset:13920
	s_waitcnt lgkmcnt(14)
	v_mfma_f32_32x32x16_f16 v[114:129], v[232:235], v[216:219], v[114:129]
	s_waitcnt lgkmcnt(13)
	v_mfma_f32_32x32x16_f16 v[98:113], v[236:239], v[216:219], v[98:113]
	s_waitcnt lgkmcnt(12)
	v_mfma_f32_32x32x16_f16 v[82:97], v[232:235], v[220:223], v[82:97]
	v_mfma_f32_32x32x16_f16 v[66:81], v[236:239], v[220:223], v[66:81]
	s_waitcnt lgkmcnt(11)
	v_mfma_f32_32x32x16_f16 v[50:65], v[232:235], v[224:227], v[50:65]
	v_mfma_f32_32x32x16_f16 v[34:49], v[236:239], v[224:227], v[34:49]
	s_waitcnt lgkmcnt(10)
	v_mfma_f32_32x32x16_f16 v[2:17], v[232:235], v[228:231], v[2:17]
	v_mfma_f32_32x32x16_f16 v[18:33], v[236:239], v[228:231], v[18:33]
	s_waitcnt lgkmcnt(0)
	s_barrier
; DI f16v mfma32(h8v a, h8v b, f16v c) { return __builtin_amdgcn_mfma_f32_32x32x16_f16(a, b, c, 0, 0, 0); }
; template <bool GATHER>
; DI void gemm256_main(const h16* __restrict__ A, int lda, const int* __restrict__ idx, int m0,
;                      const h16* __restrict__ B, int ldb, int n0, int K, h16* lds, f16v (&acc)[4][2]) {
;     ...
;   for (int kt = 0; kt < nk; ++kt) {
;     const h16* As = lds + (kt & 1) * (512 * LDH);
;     const h16* Bs = As + 256 * LDH;
;     h16* Wn = lds + ((kt & 1) ^ 1) * (512 * LDH);
;     if (kt + 1 < nk) {
; #pragma unroll
;       for (int i = 0; i < 4; ++i) { *(u4v*)&Wn[lr * LDH + lc + 8 * i] = ra[i]; *(u4v*)&Wn[(256 + lr) * LDH + lc + 8 * i] = rb[i]; }
;     }
;     if (kt + 2 < nk) {
; #pragma unroll
;       for (int i = 0; i < 4; ++i) { ra[i] = *(const u4v*)(AP_ + 8 * i); rb[i] = *(const u4v*)(BP_ + 8 * i); }
;       ao += 64; bo += 64;
;     }
; #pragma unroll
;     for (int ks = 0; ks < 4; ++ks) {
;       h8v af[4], bf[2];
; #pragma unroll
;       for (int i = 0; i < 4; ++i) af[i] = *(const h8v*)&As[(wm * 128 + i * 32 + (lane & 31)) * LDH + ks * 16 + 8 * (lane >> 5)];
; #pragma unroll
;       for (int j = 0; j < 2; ++j) bf[j] = *(const h8v*)&Bs[(wn * 64 + j * 32 + (lane & 31)) * LDH + ks * 16 + 8 * (lane >> 5)];
; #pragma unroll
;       for (int i = 0; i < 4; ++i)
; #pragma unroll
;         for (int j = 0; j < 2; ++j) acc[i][j] = mfma32(bf[j], af[i], acc[i][j]);
;     }
;     __syncthreads();
	ds_read_b128 v[232:235], v213
	ds_read_b128 v[216:219], v215
	ds_read_b128 v[236:239], v213 offset:4608
	ds_read_b128 v[220:223], v215 offset:4608
	ds_read_b128 v[224:227], v215 offset:9216
	ds_read_b128 v[228:231], v215 offset:13824
	v_mfma_f32_32x32x16_f16 v[114:129], v[208:211], v[240:243], v[114:129]
	v_mfma_f32_32x32x16_f16 v[98:113], v[174:177], v[240:243], v[98:113]
	v_mfma_f32_32x32x16_f16 v[82:97], v[208:211], v[244:247], v[82:97]
	v_mfma_f32_32x32x16_f16 v[66:81], v[174:177], v[244:247], v[66:81]
	v_mfma_f32_32x32x16_f16 v[50:65], v[208:211], v[200:203], v[50:65]
	v_mfma_f32_32x32x16_f16 v[34:49], v[174:177], v[200:203], v[34:49]
	v_mfma_f32_32x32x16_f16 v[2:17], v[208:211], v[204:207], v[2:17]
	v_mfma_f32_32x32x16_f16 v[18:33], v[174:177], v[204:207], v[18:33]
	ds_read_b128 v[208:211], v213 offset:32
	ds_read_b128 v[240:243], v215 offset:32
	ds_read_b128 v[174:177], v213 offset:4640
	ds_read_b128 v[244:247], v215 offset:4640
	ds_read_b128 v[200:203], v215 offset:9248
	ds_read_b128 v[204:207], v215 offset:13856
	s_waitcnt vmcnt(4)
	ds_write_b128 v179, v[134:137]
	ds_write_b128 v179, v[138:141] offset:16
	ds_write_b128 v179, v[142:145] offset:32
	ds_write_b128 v179, v[146:149] offset:48
	global_load_dwordx4 v[134:137], v[130:131], off offset:1536
	global_load_dwordx4 v[138:141], v[130:131], off offset:1552
	global_load_dwordx4 v[142:145], v[130:131], off offset:1568
	global_load_dwordx4 v[146:149], v[130:131], off offset:1584
	s_waitcnt lgkmcnt(14)
	v_mfma_f32_32x32x16_f16 v[114:129], v[232:235], v[216:219], v[114:129]
	s_waitcnt lgkmcnt(13)
	v_mfma_f32_32x32x16_f16 v[98:113], v[236:239], v[216:219], v[98:113]
	s_waitcnt lgkmcnt(12)
	v_mfma_f32_32x32x16_f16 v[82:97], v[232:235], v[220:223], v[82:97]
	v_mfma_f32_32x32x16_f16 v[66:81], v[236:239], v[220:223], v[66:81]
	s_waitcnt lgkmcnt(11)
	v_mfma_f32_32x32x16_f16 v[50:65], v[232:235], v[224:227], v[50:65]
	v_mfma_f32_32x32x16_f16 v[34:49], v[236:239], v[224:227], v[34:49]
	s_waitcnt lgkmcnt(10)
	v_mfma_f32_32x32x16_f16 v[2:17], v[232:235], v[228:231], v[2:17]
	v_mfma_f32_32x32x16_f16 v[18:33], v[236:239], v[228:231], v[18:33]
	ds_read_b128 v[232:235], v213 offset:64
	ds_read_b128 v[216:219], v215 offset:64
	ds_read_b128 v[236:239], v213 offset:4672
	ds_read_b128 v[220:223], v215 offset:4672
	ds_read_b128 v[224:227], v215 offset:9280
	ds_read_b128 v[228:231], v215 offset:13888
	s_waitcnt vmcnt(4)
	ds_write_b128 v179, v[150:153] offset:36864
	ds_write_b128 v179, v[154:157] offset:36880
	ds_write_b128 v179, v[158:161] offset:36896
	ds_write_b128 v179, v[162:165] offset:36912
	global_load_dwordx4 v[150:153], v[248:249], off offset:1536
	global_load_dwordx4 v[154:157], v[248:249], off offset:1552
	global_load_dwordx4 v[158:161], v[248:249], off offset:1568
	global_load_dwordx4 v[162:165], v[248:249], off offset:1584
	s_waitcnt lgkmcnt(15)
	v_mfma_f32_32x32x16_f16 v[114:129], v[208:211], v[240:243], v[114:129]
	s_waitcnt lgkmcnt(15)
	v_mfma_f32_32x32x16_f16 v[98:113], v[174:177], v[240:243], v[98:113]
	s_waitcnt lgkmcnt(15)
	v_mfma_f32_32x32x16_f16 v[82:97], v[208:211], v[244:247], v[82:97]
	v_mfma_f32_32x32x16_f16 v[66:81], v[174:177], v[244:247], v[66:81]
	s_waitcnt lgkmcnt(15)
	v_mfma_f32_32x32x16_f16 v[50:65], v[208:211], v[200:203], v[50:65]
	v_mfma_f32_32x32x16_f16 v[34:49], v[174:177], v[200:203], v[34:49]
	s_waitcnt lgkmcnt(14)
	v_mfma_f32_32x32x16_f16 v[2:17], v[208:211], v[204:207], v[2:17]
	v_mfma_f32_32x32x16_f16 v[18:33], v[174:177], v[204:207], v[18:33]
	ds_read_b128 v[208:211], v213 offset:96
	ds_read_b128 v[240:243], v215 offset:96
	ds_read_b128 v[174:177], v213 offset:4704
	ds_read_b128 v[244:247], v215 offset:4704
	ds_read_b128 v[200:203], v215 offset:9312
	ds_read_b128 v[204:207], v215 offset:13920
	s_waitcnt lgkmcnt(14)
	v_mfma_f32_32x32x16_f16 v[114:129], v[232:235], v[216:219], v[114:129]
	s_waitcnt lgkmcnt(13)
	v_mfma_f32_32x32x16_f16 v[98:113], v[236:239], v[216:219], v[98:113]
	s_waitcnt lgkmcnt(12)
	v_mfma_f32_32x32x16_f16 v[82:97], v[232:235], v[220:223], v[82:97]
	v_mfma_f32_32x32x16_f16 v[66:81], v[236:239], v[220:223], v[66:81]
	s_waitcnt lgkmcnt(11)
	v_mfma_f32_32x32x16_f16 v[50:65], v[232:235], v[224:227], v[50:65]
	v_mfma_f32_32x32x16_f16 v[34:49], v[236:239], v[224:227], v[34:49]
	s_waitcnt lgkmcnt(10)
	v_mfma_f32_32x32x16_f16 v[2:17], v[232:235], v[228:231], v[2:17]
	v_mfma_f32_32x32x16_f16 v[18:33], v[236:239], v[228:231], v[18:33]
	s_waitcnt lgkmcnt(0)
	s_barrier
; DI f16v mfma32(h8v a, h8v b, f16v c) { return __builtin_amdgcn_mfma_f32_32x32x16_f16(a, b, c, 0, 0, 0); }
; template <bool GATHER>
; DI void gemm256_main(const h16* __restrict__ A, int lda, const int* __restrict__ idx, int m0,
;                      const h16* __restrict__ B, int ldb, int n0, int K, h16* lds, f16v (&acc)[4][2]) {
;     ...
;   for (int kt = 0; kt < nk; ++kt) {
;     const h16* As = lds + (kt & 1) * (512 * LDH);
;     const h16* Bs = As + 256 * LDH;
;     h16* Wn = lds + ((kt & 1) ^ 1) * (512 * LDH);
;     if (kt + 1 < nk) {
; #pragma unroll
;       for (int i = 0; i < 4; ++i) { *(u4v*)&Wn[lr * LDH + lc + 8 * i] = ra[i]; *(u4v*)&Wn[(256 + lr) * LDH + lc + 8 * i] = rb[i]; }
;     }
;     if (kt + 2 < nk) {
; #pragma unroll
;       for (int i = 0; i < 4; ++i) { ra[i] = *(const u4v*)(AP_ + 8 * i); rb[i] = *(const u4v*)(BP_ + 8 * i); }
;       ao += 64; bo += 64;
;     }
; #pragma unroll
;     for (int ks = 0; ks < 4; ++ks) {
;       h8v af[4], bf[2];
; #pragma unroll
;       for (int i = 0; i < 4; ++i) af[i] = *(const h8v*)&As[(wm * 128 + i * 32 + (lane & 31)) * LDH + ks * 16 + 8 * (lane >> 5)];
; #pragma unroll
;       for (int j = 0; j < 2; ++j) bf[j] = *(const h8v*)&Bs[(wn * 64 + j * 32 + (lane & 31)) * LDH + ks * 16 + 8 * (lane >> 5)];
; #pragma unroll
;       for (int i = 0; i < 4; ++i)
; #pragma unroll
;         for (int j = 0; j < 2; ++j) acc[i][j] = mfma32(bf[j], af[i], acc[i][j]);
;     }
;     __syncthreads();
	ds_read_b128 v[232:235], v214
	ds_read_b128 v[216:219], v212
	ds_read_b128 v[236:239], v214 offset:4608
	ds_read_b128 v[220:223], v212 offset:4608
	ds_read_b128 v[224:227], v212 offset:9216
	ds_read_b128 v[228:231], v212 offset:13824
	v_mfma_f32_32x32x16_f16 v[114:129], v[208:211], v[240:243], v[114:129]
	v_mfma_f32_32x32x16_f16 v[98:113], v[174:177], v[240:243], v[98:113]
	v_mfma_f32_32x32x16_f16 v[82:97], v[208:211], v[244:247], v[82:97]
	v_mfma_f32_32x32x16_f16 v[66:81], v[174:177], v[244:247], v[66:81]
	v_mfma_f32_32x32x16_f16 v[50:65], v[208:211], v[200:203], v[50:65]
	v_mfma_f32_32x32x16_f16 v[34:49], v[174:177], v[200:203], v[34:49]
	v_mfma_f32_32x32x16_f16 v[2:17], v[208:211], v[204:207], v[2:17]
	v_mfma_f32_32x32x16_f16 v[18:33], v[174:177], v[204:207], v[18:33]
	ds_read_b128 v[208:211], v214 offset:32
	ds_read_b128 v[240:243], v212 offset:32
	ds_read_b128 v[174:177], v214 offset:4640
	ds_read_b128 v[244:247], v212 offset:4640
	ds_read_b128 v[200:203], v212 offset:9248
	ds_read_b128 v[204:207], v212 offset:13856
	s_waitcnt vmcnt(4)
	ds_write_b128 v178, v[134:137]
	ds_write_b128 v178, v[138:141] offset:16
	ds_write_b128 v178, v[142:145] offset:32
	ds_write_b128 v178, v[146:149] offset:48
	global_load_dwordx4 v[134:137], v[130:131], off offset:1664
	global_load_dwordx4 v[138:141], v[130:131], off offset:1680
	global_load_dwordx4 v[142:145], v[130:131], off offset:1696
	global_load_dwordx4 v[146:149], v[130:131], off offset:1712
	s_waitcnt lgkmcnt(14)
	v_mfma_f32_32x32x16_f16 v[114:129], v[232:235], v[216:219], v[114:129]
	s_waitcnt lgkmcnt(13)
	v_mfma_f32_32x32x16_f16 v[98:113], v[236:239], v[216:219], v[98:113]
	s_waitcnt lgkmcnt(12)
	v_mfma_f32_32x32x16_f16 v[82:97], v[232:235], v[220:223], v[82:97]
	v_mfma_f32_32x32x16_f16 v[66:81], v[236:239], v[220:223], v[66:81]
	s_waitcnt lgkmcnt(11)
	v_mfma_f32_32x32x16_f16 v[50:65], v[232:235], v[224:227], v[50:65]
	v_mfma_f32_32x32x16_f16 v[34:49], v[236:239], v[224:227], v[34:49]
	s_waitcnt lgkmcnt(10)
	v_mfma_f32_32x32x16_f16 v[2:17], v[232:235], v[228:231], v[2:17]
	v_mfma_f32_32x32x16_f16 v[18:33], v[236:239], v[228:231], v[18:33]
	ds_read_b128 v[232:235], v214 offset:64
	ds_read_b128 v[216:219], v212 offset:64
	ds_read_b128 v[236:239], v214 offset:4672
	ds_read_b128 v[220:223], v212 offset:4672
	ds_read_b128 v[224:227], v212 offset:9280
	ds_read_b128 v[228:231], v212 offset:13888
	s_waitcnt vmcnt(4)
	ds_write_b128 v178, v[150:153] offset:36864
	ds_write_b128 v178, v[154:157] offset:36880
	ds_write_b128 v178, v[158:161] offset:36896
	ds_write_b128 v178, v[162:165] offset:36912
	global_load_dwordx4 v[150:153], v[248:249], off offset:1664
	global_load_dwordx4 v[154:157], v[248:249], off offset:1680
	global_load_dwordx4 v[158:161], v[248:249], off offset:1696
	global_load_dwordx4 v[162:165], v[248:249], off offset:1712
	s_waitcnt lgkmcnt(15)
	v_mfma_f32_32x32x16_f16 v[114:129], v[208:211], v[240:243], v[114:129]
	s_waitcnt lgkmcnt(15)
	v_mfma_f32_32x32x16_f16 v[98:113], v[174:177], v[240:243], v[98:113]
	s_waitcnt lgkmcnt(15)
	v_mfma_f32_32x32x16_f16 v[82:97], v[208:211], v[244:247], v[82:97]
	v_mfma_f32_32x32x16_f16 v[66:81], v[174:177], v[244:247], v[66:81]
	s_waitcnt lgkmcnt(15)
	v_mfma_f32_32x32x16_f16 v[50:65], v[208:211], v[200:203], v[50:65]
	v_mfma_f32_32x32x16_f16 v[34:49], v[174:177], v[200:203], v[34:49]
	s_waitcnt lgkmcnt(14)
	v_mfma_f32_32x32x16_f16 v[2:17], v[208:211], v[204:207], v[2:17]
	v_mfma_f32_32x32x16_f16 v[18:33], v[174:177], v[204:207], v[18:33]
	ds_read_b128 v[208:211], v214 offset:96
	ds_read_b128 v[240:243], v212 offset:96
	ds_read_b128 v[174:177], v214 offset:4704
	ds_read_b128 v[244:247], v212 offset:4704
	ds_read_b128 v[200:203], v212 offset:9312
	ds_read_b128 v[204:207], v212 offset:13920
	s_waitcnt lgkmcnt(14)
	v_mfma_f32_32x32x16_f16 v[114:129], v[232:235], v[216:219], v[114:129]
	s_waitcnt lgkmcnt(13)
	v_mfma_f32_32x32x16_f16 v[98:113], v[236:239], v[216:219], v[98:113]
	s_waitcnt lgkmcnt(12)
	v_mfma_f32_32x32x16_f16 v[82:97], v[232:235], v[220:223], v[82:97]
	v_mfma_f32_32x32x16_f16 v[66:81], v[236:239], v[220:223], v[66:81]
	s_waitcnt lgkmcnt(11)
	v_mfma_f32_32x32x16_f16 v[50:65], v[232:235], v[224:227], v[50:65]
	v_mfma_f32_32x32x16_f16 v[34:49], v[236:239], v[224:227], v[34:49]
	s_waitcnt lgkmcnt(10)
	v_mfma_f32_32x32x16_f16 v[2:17], v[232:235], v[228:231], v[2:17]
	v_mfma_f32_32x32x16_f16 v[18:33], v[236:239], v[228:231], v[18:33]
	s_waitcnt lgkmcnt(0)
	s_barrier
; DI f16v mfma32(h8v a, h8v b, f16v c) { return __builtin_amdgcn_mfma_f32_32x32x16_f16(a, b, c, 0, 0, 0); }
; template <bool GATHER>
; DI void gemm256_main(const h16* __restrict__ A, int lda, const int* __restrict__ idx, int m0,
;                      const h16* __restrict__ B, int ldb, int n0, int K, h16* lds, f16v (&acc)[4][2]) {
;     ...
;   for (int kt = 0; kt < nk; ++kt) {
;     const h16* As = lds + (kt & 1) * (512 * LDH);
;     const h16* Bs = As + 256 * LDH;
;     h16* Wn = lds + ((kt & 1) ^ 1) * (512 * LDH);
;     if (kt + 1 < nk) {
; #pragma unroll
;       for (int i = 0; i < 4; ++i) { *(u4v*)&Wn[lr * LDH + lc + 8 * i] = ra[i]; *(u4v*)&Wn[(256 + lr) * LDH + lc + 8 * i] = rb[i]; }
;     }
;     if (kt + 2 < nk) {
; #pragma unroll
;       for (int i = 0; i < 4; ++i) { ra[i] = *(const u4v*)(AP_ + 8 * i); rb[i] = *(const u4v*)(BP_ + 8 * i); }
;       ao += 64; bo += 64;
;     }
; #pragma unroll
;     for (int ks = 0; ks < 4; ++ks) {
;       h8v af[4], bf[2];
; #pragma unroll
;       for (int i = 0; i < 4; ++i) af[i] = *(const h8v*)&As[(wm * 128 + i * 32 + (lane & 31)) * LDH + ks * 16 + 8 * (lane >> 5)];
; #pragma unroll
;       for (int j = 0; j < 2; ++j) bf[j] = *(const h8v*)&Bs[(wn * 64 + j * 32 + (lane & 31)) * LDH + ks * 16 + 8 * (lane >> 5)];
; #pragma unroll
;       for (int i = 0; i < 4; ++i)
; #pragma unroll
;         for (int j = 0; j < 2; ++j) acc[i][j] = mfma32(bf[j], af[i], acc[i][j]);
;     }
;     __syncthreads();
	ds_read_b128 v[232:235], v213
	ds_read_b128 v[216:219], v215
	ds_read_b128 v[236:239], v213 offset:4608
	ds_read_b128 v[220:223], v215 offset:4608
	ds_read_b128 v[224:227], v215 offset:9216
	ds_read_b128 v[228:231], v215 offset:13824
	v_mfma_f32_32x32x16_f16 v[114:129], v[208:211], v[240:243], v[114:129]
	v_mfma_f32_32x32x16_f16 v[98:113], v[174:177], v[240:243], v[98:113]
	v_mfma_f32_32x32x16_f16 v[82:97], v[208:211], v[244:247], v[82:97]
	v_mfma_f32_32x32x16_f16 v[66:81], v[174:177], v[244:247], v[66:81]
	v_mfma_f32_32x32x16_f16 v[50:65], v[208:211], v[200:203], v[50:65]
	v_mfma_f32_32x32x16_f16 v[34:49], v[174:177], v[200:203], v[34:49]
	v_mfma_f32_32x32x16_f16 v[2:17], v[208:211], v[204:207], v[2:17]
	v_mfma_f32_32x32x16_f16 v[18:33], v[174:177], v[204:207], v[18:33]
	ds_read_b128 v[208:211], v213 offset:32
	ds_read_b128 v[240:243], v215 offset:32
	ds_read_b128 v[174:177], v213 offset:4640
	ds_read_b128 v[244:247], v215 offset:4640
	ds_read_b128 v[200:203], v215 offset:9248
	ds_read_b128 v[204:207], v215 offset:13856
	s_waitcnt vmcnt(4)
	ds_write_b128 v179, v[134:137]
	ds_write_b128 v179, v[138:141] offset:16
	ds_write_b128 v179, v[142:145] offset:32
	ds_write_b128 v179, v[146:149] offset:48
	global_load_dwordx4 v[134:137], v[130:131], off offset:1792
	global_load_dwordx4 v[138:141], v[130:131], off offset:1808
	global_load_dwordx4 v[142:145], v[130:131], off offset:1824
	global_load_dwordx4 v[146:149], v[130:131], off offset:1840
	s_waitcnt lgkmcnt(14)
	v_mfma_f32_32x32x16_f16 v[114:129], v[232:235], v[216:219], v[114:129]
	s_waitcnt lgkmcnt(13)
	v_mfma_f32_32x32x16_f16 v[98:113], v[236:239], v[216:219], v[98:113]
	s_waitcnt lgkmcnt(12)
	v_mfma_f32_32x32x16_f16 v[82:97], v[232:235], v[220:223], v[82:97]
	v_mfma_f32_32x32x16_f16 v[66:81], v[236:239], v[220:223], v[66:81]
	s_waitcnt lgkmcnt(11)
	v_mfma_f32_32x32x16_f16 v[50:65], v[232:235], v[224:227], v[50:65]
	v_mfma_f32_32x32x16_f16 v[34:49], v[236:239], v[224:227], v[34:49]
	s_waitcnt lgkmcnt(10)
	v_mfma_f32_32x32x16_f16 v[2:17], v[232:235], v[228:231], v[2:17]
	v_mfma_f32_32x32x16_f16 v[18:33], v[236:239], v[228:231], v[18:33]
	ds_read_b128 v[232:235], v213 offset:64
	ds_read_b128 v[216:219], v215 offset:64
	ds_read_b128 v[236:239], v213 offset:4672
	ds_read_b128 v[220:223], v215 offset:4672
	ds_read_b128 v[224:227], v215 offset:9280
	ds_read_b128 v[228:231], v215 offset:13888
	s_waitcnt vmcnt(4)
	ds_write_b128 v179, v[150:153] offset:36864
	ds_write_b128 v179, v[154:157] offset:36880
	ds_write_b128 v179, v[158:161] offset:36896
	ds_write_b128 v179, v[162:165] offset:36912
	global_load_dwordx4 v[150:153], v[248:249], off offset:1792
	global_load_dwordx4 v[154:157], v[248:249], off offset:1808
	global_load_dwordx4 v[158:161], v[248:249], off offset:1824
	global_load_dwordx4 v[162:165], v[248:249], off offset:1840
	s_waitcnt lgkmcnt(15)
	v_mfma_f32_32x32x16_f16 v[114:129], v[208:211], v[240:243], v[114:129]
	s_waitcnt lgkmcnt(15)
	v_mfma_f32_32x32x16_f16 v[98:113], v[174:177], v[240:243], v[98:113]
	s_waitcnt lgkmcnt(15)
	v_mfma_f32_32x32x16_f16 v[82:97], v[208:211], v[244:247], v[82:97]
	v_mfma_f32_32x32x16_f16 v[66:81], v[174:177], v[244:247], v[66:81]
	s_waitcnt lgkmcnt(15)
	v_mfma_f32_32x32x16_f16 v[50:65], v[208:211], v[200:203], v[50:65]
	v_mfma_f32_32x32x16_f16 v[34:49], v[174:177], v[200:203], v[34:49]
	s_waitcnt lgkmcnt(14)
	v_mfma_f32_32x32x16_f16 v[2:17], v[208:211], v[204:207], v[2:17]
	v_mfma_f32_32x32x16_f16 v[18:33], v[174:177], v[204:207], v[18:33]
	ds_read_b128 v[208:211], v213 offset:96
	ds_read_b128 v[240:243], v215 offset:96
	ds_read_b128 v[174:177], v213 offset:4704
	ds_read_b128 v[244:247], v215 offset:4704
	ds_read_b128 v[200:203], v215 offset:9312
	ds_read_b128 v[204:207], v215 offset:13920
	s_waitcnt lgkmcnt(14)
	v_mfma_f32_32x32x16_f16 v[114:129], v[232:235], v[216:219], v[114:129]
	s_waitcnt lgkmcnt(13)
	v_mfma_f32_32x32x16_f16 v[98:113], v[236:239], v[216:219], v[98:113]
	s_waitcnt lgkmcnt(12)
	v_mfma_f32_32x32x16_f16 v[82:97], v[232:235], v[220:223], v[82:97]
	v_mfma_f32_32x32x16_f16 v[66:81], v[236:239], v[220:223], v[66:81]
	s_waitcnt lgkmcnt(11)
	v_mfma_f32_32x32x16_f16 v[50:65], v[232:235], v[224:227], v[50:65]
	v_mfma_f32_32x32x16_f16 v[34:49], v[236:239], v[224:227], v[34:49]
	s_waitcnt lgkmcnt(10)
	v_mfma_f32_32x32x16_f16 v[2:17], v[232:235], v[228:231], v[2:17]
	v_mfma_f32_32x32x16_f16 v[18:33], v[236:239], v[228:231], v[18:33]
	s_waitcnt lgkmcnt(0)
	s_barrier
; DI f16v mfma32(h8v a, h8v b, f16v c) { return __builtin_amdgcn_mfma_f32_32x32x16_f16(a, b, c, 0, 0, 0); }
; template <bool GATHER>
; DI void gemm256_main(const h16* __restrict__ A, int lda, const int* __restrict__ idx, int m0,
;                      const h16* __restrict__ B, int ldb, int n0, int K, h16* lds, f16v (&acc)[4][2]) {
;     ...
;   for (int kt = 0; kt < nk; ++kt) {
;     const h16* As = lds + (kt & 1) * (512 * LDH);
;     const h16* Bs = As + 256 * LDH;
;     h16* Wn = lds + ((kt & 1) ^ 1) * (512 * LDH);
;     if (kt + 1 < nk) {
; #pragma unroll
;       for (int i = 0; i < 4; ++i) { *(u4v*)&Wn[lr * LDH + lc + 8 * i] = ra[i]; *(u4v*)&Wn[(256 + lr) * LDH + lc + 8 * i] = rb[i]; }
;     }
;     if (kt + 2 < nk) {
; #pragma unroll
;       for (int i = 0; i < 4; ++i) { ra[i] = *(const u4v*)(AP_ + 8 * i); rb[i] = *(const u4v*)(BP_ + 8 * i); }
;       ao += 64; bo += 64;
;     }
; #pragma unroll
;     for (int ks = 0; ks < 4; ++ks) {
;       h8v af[4], bf[2];
; #pragma unroll
;       for (int i = 0; i < 4; ++i) af[i] = *(const h8v*)&As[(wm * 128 + i * 32 + (lane & 31)) * LDH + ks * 16 + 8 * (lane >> 5)];
; #pragma unroll
;       for (int j = 0; j < 2; ++j) bf[j] = *(const h8v*)&Bs[(wn * 64 + j * 32 + (lane & 31)) * LDH + ks * 16 + 8 * (lane >> 5)];
; #pragma unroll
;       for (int i = 0; i < 4; ++i)
; #pragma unroll
;         for (int j = 0; j < 2; ++j) acc[i][j] = mfma32(bf[j], af[i], acc[i][j]);
;     }
;     __syncthreads();
	ds_read_b128 v[232:235], v214
	ds_read_b128 v[216:219], v212
	ds_read_b128 v[236:239], v214 offset:4608
	ds_read_b128 v[220:223], v212 offset:4608
	ds_read_b128 v[224:227], v212 offset:9216
	ds_read_b128 v[228:231], v212 offset:13824
	v_mfma_f32_32x32x16_f16 v[114:129], v[208:211], v[240:243], v[114:129]
	v_mfma_f32_32x32x16_f16 v[98:113], v[174:177], v[240:243], v[98:113]
	v_mfma_f32_32x32x16_f16 v[82:97], v[208:211], v[244:247], v[82:97]
	v_mfma_f32_32x32x16_f16 v[66:81], v[174:177], v[244:247], v[66:81]
	v_mfma_f32_32x32x16_f16 v[50:65], v[208:211], v[200:203], v[50:65]
	v_mfma_f32_32x32x16_f16 v[34:49], v[174:177], v[200:203], v[34:49]
	v_mfma_f32_32x32x16_f16 v[2:17], v[208:211], v[204:207], v[2:17]
	v_mfma_f32_32x32x16_f16 v[18:33], v[174:177], v[204:207], v[18:33]
	ds_read_b128 v[208:211], v214 offset:32
	ds_read_b128 v[240:243], v212 offset:32
	ds_read_b128 v[174:177], v214 offset:4640
	ds_read_b128 v[244:247], v212 offset:4640
	ds_read_b128 v[200:203], v212 offset:9248
	ds_read_b128 v[204:207], v212 offset:13856
	s_waitcnt vmcnt(4)
	ds_write_b128 v178, v[134:137]
	ds_write_b128 v178, v[138:141] offset:16
	ds_write_b128 v178, v[142:145] offset:32
	ds_write_b128 v178, v[146:149] offset:48
	global_load_dwordx4 v[134:137], v[130:131], off offset:1920
	global_load_dwordx4 v[138:141], v[130:131], off offset:1936
	global_load_dwordx4 v[142:145], v[130:131], off offset:1952
	global_load_dwordx4 v[146:149], v[130:131], off offset:1968
	s_waitcnt lgkmcnt(14)
	v_mfma_f32_32x32x16_f16 v[114:129], v[232:235], v[216:219], v[114:129]
	s_waitcnt lgkmcnt(13)
	v_mfma_f32_32x32x16_f16 v[98:113], v[236:239], v[216:219], v[98:113]
	s_waitcnt lgkmcnt(12)
	v_mfma_f32_32x32x16_f16 v[82:97], v[232:235], v[220:223], v[82:97]
	v_mfma_f32_32x32x16_f16 v[66:81], v[236:239], v[220:223], v[66:81]
	s_waitcnt lgkmcnt(11)
	v_mfma_f32_32x32x16_f16 v[50:65], v[232:235], v[224:227], v[50:65]
	v_mfma_f32_32x32x16_f16 v[34:49], v[236:239], v[224:227], v[34:49]
	s_waitcnt lgkmcnt(10)
	v_mfma_f32_32x32x16_f16 v[2:17], v[232:235], v[228:231], v[2:17]
	v_mfma_f32_32x32x16_f16 v[18:33], v[236:239], v[228:231], v[18:33]
	ds_read_b128 v[232:235], v214 offset:64
	ds_read_b128 v[216:219], v212 offset:64
	ds_read_b128 v[236:239], v214 offset:4672
	ds_read_b128 v[220:223], v212 offset:4672
	ds_read_b128 v[224:227], v212 offset:9280
	ds_read_b128 v[228:231], v212 offset:13888
	s_waitcnt vmcnt(4)
	ds_write_b128 v178, v[150:153] offset:36864
	ds_write_b128 v178, v[154:157] offset:36880
	ds_write_b128 v178, v[158:161] offset:36896
	ds_write_b128 v178, v[162:165] offset:36912
	global_load_dwordx4 v[150:153], v[248:249], off offset:1920
	global_load_dwordx4 v[154:157], v[248:249], off offset:1936
	global_load_dwordx4 v[158:161], v[248:249], off offset:1952
	global_load_dwordx4 v[162:165], v[248:249], off offset:1968
	s_waitcnt lgkmcnt(15)
	v_mfma_f32_32x32x16_f16 v[114:129], v[208:211], v[240:243], v[114:129]
	s_waitcnt lgkmcnt(15)
	v_mfma_f32_32x32x16_f16 v[98:113], v[174:177], v[240:243], v[98:113]
	s_waitcnt lgkmcnt(15)
	v_mfma_f32_32x32x16_f16 v[82:97], v[208:211], v[244:247], v[82:97]
	v_mfma_f32_32x32x16_f16 v[66:81], v[174:177], v[244:247], v[66:81]
	s_waitcnt lgkmcnt(15)
	v_mfma_f32_32x32x16_f16 v[50:65], v[208:211], v[200:203], v[50:65]
	v_mfma_f32_32x32x16_f16 v[34:49], v[174:177], v[200:203], v[34:49]
	s_waitcnt lgkmcnt(14)
	v_mfma_f32_32x32x16_f16 v[2:17], v[208:211], v[204:207], v[2:17]
	v_mfma_f32_32x32x16_f16 v[18:33], v[174:177], v[204:207], v[18:33]
	ds_read_b128 v[208:211], v214 offset:96
	ds_read_b128 v[240:243], v212 offset:96
	ds_read_b128 v[174:177], v214 offset:4704
	ds_read_b128 v[244:247], v212 offset:4704
	ds_read_b128 v[200:203], v212 offset:9312
	ds_read_b128 v[204:207], v212 offset:13920
	s_waitcnt lgkmcnt(14)
	v_mfma_f32_32x32x16_f16 v[114:129], v[232:235], v[216:219], v[114:129]
	s_waitcnt lgkmcnt(13)
	v_mfma_f32_32x32x16_f16 v[98:113], v[236:239], v[216:219], v[98:113]
	s_waitcnt lgkmcnt(12)
	v_mfma_f32_32x32x16_f16 v[82:97], v[232:235], v[220:223], v[82:97]
	v_mfma_f32_32x32x16_f16 v[66:81], v[236:239], v[220:223], v[66:81]
	s_waitcnt lgkmcnt(11)
	v_mfma_f32_32x32x16_f16 v[50:65], v[232:235], v[224:227], v[50:65]
	v_mfma_f32_32x32x16_f16 v[34:49], v[236:239], v[224:227], v[34:49]
	s_waitcnt lgkmcnt(10)
	v_mfma_f32_32x32x16_f16 v[2:17], v[232:235], v[228:231], v[2:17]
	v_mfma_f32_32x32x16_f16 v[18:33], v[236:239], v[228:231], v[18:33]
	s_waitcnt lgkmcnt(0)
	s_barrier
; DI f16v mfma32(h8v a, h8v b, f16v c) { return __builtin_amdgcn_mfma_f32_32x32x16_f16(a, b, c, 0, 0, 0); }
; template <bool GATHER>
; DI void gemm256_main(const h16* __restrict__ A, int lda, const int* __restrict__ idx, int m0,
;                      const h16* __restrict__ B, int ldb, int n0, int K, h16* lds, f16v (&acc)[4][2]) {
;     ...
;   for (int kt = 0; kt < nk; ++kt) {
;     const h16* As = lds + (kt & 1) * (512 * LDH);
;     const h16* Bs = As + 256 * LDH;
;     h16* Wn = lds + ((kt & 1) ^ 1) * (512 * LDH);
;     if (kt + 1 < nk) {
; #pragma unroll
;       for (int i = 0; i < 4; ++i) { *(u4v*)&Wn[lr * LDH + lc + 8 * i] = ra[i]; *(u4v*)&Wn[(256 + lr) * LDH + lc + 8 * i] = rb[i]; }
;     }
;     if (kt + 2 < nk) {
; #pragma unroll
;       for (int i = 0; i < 4; ++i) { ra[i] = *(const u4v*)(AP_ + 8 * i); rb[i] = *(const u4v*)(BP_ + 8 * i); }
;       ao += 64; bo += 64;
;     }
; #pragma unroll
;     for (int ks = 0; ks < 4; ++ks) {
;       h8v af[4], bf[2];
; #pragma unroll
;       for (int i = 0; i < 4; ++i) af[i] = *(const h8v*)&As[(wm * 128 + i * 32 + (lane & 31)) * LDH + ks * 16 + 8 * (lane >> 5)];
; #pragma unroll
;       for (int j = 0; j < 2; ++j) bf[j] = *(const h8v*)&Bs[(wn * 64 + j * 32 + (lane & 31)) * LDH + ks * 16 + 8 * (lane >> 5)];
; #pragma unroll
;       for (int i = 0; i < 4; ++i)
; #pragma unroll
;         for (int j = 0; j < 2; ++j) acc[i][j] = mfma32(bf[j], af[i], acc[i][j]);
;     }
;     __syncthreads();
	ds_read_b128 v[232:235], v213
	ds_read_b128 v[216:219], v215
	ds_read_b128 v[236:239], v213 offset:4608
	ds_read_b128 v[220:223], v215 offset:4608
	ds_read_b128 v[224:227], v215 offset:9216
	ds_read_b128 v[228:231], v215 offset:13824
	v_mfma_f32_32x32x16_f16 v[114:129], v[208:211], v[240:243], v[114:129]
	v_mfma_f32_32x32x16_f16 v[98:113], v[174:177], v[240:243], v[98:113]
	v_mfma_f32_32x32x16_f16 v[82:97], v[208:211], v[244:247], v[82:97]
	v_mfma_f32_32x32x16_f16 v[66:81], v[174:177], v[244:247], v[66:81]
	v_mfma_f32_32x32x16_f16 v[50:65], v[208:211], v[200:203], v[50:65]
	v_mfma_f32_32x32x16_f16 v[34:49], v[174:177], v[200:203], v[34:49]
	v_mfma_f32_32x32x16_f16 v[2:17], v[208:211], v[204:207], v[2:17]
	v_mfma_f32_32x32x16_f16 v[18:33], v[174:177], v[204:207], v[18:33]
	ds_read_b128 v[208:211], v213 offset:32
	ds_read_b128 v[240:243], v215 offset:32
	ds_read_b128 v[174:177], v213 offset:4640
	ds_read_b128 v[244:247], v215 offset:4640
	ds_read_b128 v[200:203], v215 offset:9248
	ds_read_b128 v[204:207], v215 offset:13856
	s_waitcnt vmcnt(4)
	ds_write_b128 v179, v[134:137]
	ds_write_b128 v179, v[138:141] offset:16
	ds_write_b128 v179, v[142:145] offset:32
	ds_write_b128 v179, v[146:149] offset:48
	s_waitcnt lgkmcnt(14)
	v_mfma_f32_32x32x16_f16 v[114:129], v[232:235], v[216:219], v[114:129]
	s_waitcnt lgkmcnt(13)
	v_mfma_f32_32x32x16_f16 v[98:113], v[236:239], v[216:219], v[98:113]
	s_waitcnt lgkmcnt(12)
	v_mfma_f32_32x32x16_f16 v[82:97], v[232:235], v[220:223], v[82:97]
	v_mfma_f32_32x32x16_f16 v[66:81], v[236:239], v[220:223], v[66:81]
	s_waitcnt lgkmcnt(11)
	v_mfma_f32_32x32x16_f16 v[50:65], v[232:235], v[224:227], v[50:65]
	v_mfma_f32_32x32x16_f16 v[34:49], v[236:239], v[224:227], v[34:49]
	s_waitcnt lgkmcnt(10)
	v_mfma_f32_32x32x16_f16 v[2:17], v[232:235], v[228:231], v[2:17]
	v_mfma_f32_32x32x16_f16 v[18:33], v[236:239], v[228:231], v[18:33]
	ds_read_b128 v[232:235], v213 offset:64
	ds_read_b128 v[216:219], v215 offset:64
	ds_read_b128 v[236:239], v213 offset:4672
	ds_read_b128 v[220:223], v215 offset:4672
	ds_read_b128 v[224:227], v215 offset:9280
	ds_read_b128 v[228:231], v215 offset:13888
	s_waitcnt vmcnt(0)
	ds_write_b128 v179, v[150:153] offset:36864
	ds_write_b128 v179, v[154:157] offset:36880
	ds_write_b128 v179, v[158:161] offset:36896
	ds_write_b128 v179, v[162:165] offset:36912
	s_waitcnt lgkmcnt(15)
	v_mfma_f32_32x32x16_f16 v[114:129], v[208:211], v[240:243], v[114:129]
	s_waitcnt lgkmcnt(15)
	v_mfma_f32_32x32x16_f16 v[98:113], v[174:177], v[240:243], v[98:113]
	s_waitcnt lgkmcnt(15)
	v_mfma_f32_32x32x16_f16 v[82:97], v[208:211], v[244:247], v[82:97]
	v_mfma_f32_32x32x16_f16 v[66:81], v[174:177], v[244:247], v[66:81]
	s_waitcnt lgkmcnt(15)
	v_mfma_f32_32x32x16_f16 v[50:65], v[208:211], v[200:203], v[50:65]
	v_mfma_f32_32x32x16_f16 v[34:49], v[174:177], v[200:203], v[34:49]
	s_waitcnt lgkmcnt(14)
	v_mfma_f32_32x32x16_f16 v[2:17], v[208:211], v[204:207], v[2:17]
	v_mfma_f32_32x32x16_f16 v[18:33], v[174:177], v[204:207], v[18:33]
	ds_read_b128 v[208:211], v213 offset:96
	ds_read_b128 v[240:243], v215 offset:96
	ds_read_b128 v[174:177], v213 offset:4704
	ds_read_b128 v[244:247], v215 offset:4704
	ds_read_b128 v[200:203], v215 offset:9312
	ds_read_b128 v[204:207], v215 offset:13920
	s_waitcnt lgkmcnt(14)
	v_mfma_f32_32x32x16_f16 v[114:129], v[232:235], v[216:219], v[114:129]
	s_waitcnt lgkmcnt(13)
	v_mfma_f32_32x32x16_f16 v[98:113], v[236:239], v[216:219], v[98:113]
	s_waitcnt lgkmcnt(12)
	v_mfma_f32_32x32x16_f16 v[82:97], v[232:235], v[220:223], v[82:97]
	v_mfma_f32_32x32x16_f16 v[66:81], v[236:239], v[220:223], v[66:81]
	s_waitcnt lgkmcnt(11)
	v_mfma_f32_32x32x16_f16 v[50:65], v[232:235], v[224:227], v[50:65]
	v_mfma_f32_32x32x16_f16 v[34:49], v[236:239], v[224:227], v[34:49]
	s_waitcnt lgkmcnt(10)
	v_mfma_f32_32x32x16_f16 v[2:17], v[232:235], v[228:231], v[2:17]
	v_mfma_f32_32x32x16_f16 v[18:33], v[236:239], v[228:231], v[18:33]
	s_waitcnt lgkmcnt(0)
	s_barrier
	ds_read_b128 v[232:235], v214
	ds_read_b128 v[216:219], v212
	ds_read_b128 v[236:239], v214 offset:4608
	ds_read_b128 v[220:223], v212 offset:4608
	ds_read_b128 v[224:227], v212 offset:9216
	ds_read_b128 v[228:231], v212 offset:13824
	v_mfma_f32_32x32x16_f16 v[114:129], v[208:211], v[240:243], v[114:129]
	v_mfma_f32_32x32x16_f16 v[98:113], v[174:177], v[240:243], v[98:113]
	v_mfma_f32_32x32x16_f16 v[82:97], v[208:211], v[244:247], v[82:97]
	v_mfma_f32_32x32x16_f16 v[66:81], v[174:177], v[244:247], v[66:81]
	v_mfma_f32_32x32x16_f16 v[50:65], v[208:211], v[200:203], v[50:65]
	v_mfma_f32_32x32x16_f16 v[34:49], v[174:177], v[200:203], v[34:49]
	v_mfma_f32_32x32x16_f16 v[2:17], v[208:211], v[204:207], v[2:17]
	v_mfma_f32_32x32x16_f16 v[18:33], v[174:177], v[204:207], v[18:33]
	ds_read_b128 v[208:211], v214 offset:32
	ds_read_b128 v[240:243], v212 offset:32
	ds_read_b128 v[174:177], v214 offset:4640
	ds_read_b128 v[244:247], v212 offset:4640
	ds_read_b128 v[200:203], v212 offset:9248
	ds_read_b128 v[204:207], v212 offset:13856
	s_waitcnt lgkmcnt(10)
	v_mfma_f32_32x32x16_f16 v[114:129], v[232:235], v[216:219], v[114:129]
	s_waitcnt lgkmcnt(9)
	v_mfma_f32_32x32x16_f16 v[98:113], v[236:239], v[216:219], v[98:113]
	s_waitcnt lgkmcnt(8)
	v_mfma_f32_32x32x16_f16 v[82:97], v[232:235], v[220:223], v[82:97]
	v_mfma_f32_32x32x16_f16 v[66:81], v[236:239], v[220:223], v[66:81]
	s_waitcnt lgkmcnt(7)
	v_mfma_f32_32x32x16_f16 v[50:65], v[232:235], v[224:227], v[50:65]
	v_mfma_f32_32x32x16_f16 v[34:49], v[236:239], v[224:227], v[34:49]
	s_waitcnt lgkmcnt(6)
; DI f16v mfma32(h8v a, h8v b, f16v c) { return __builtin_amdgcn_mfma_f32_32x32x16_f16(a, b, c, 0, 0, 0); }
; template <bool GATHER>
; DI void gemm256_main(const h16* __restrict__ A, int lda, const int* __restrict__ idx, int m0,
;                      const h16* __restrict__ B, int ldb, int n0, int K, h16* lds, f16v (&acc)[4][2]) {
;     ...
;     for (int ks = 0; ks < 4; ++ks) {
;       h8v af[4], bf[2];
; #pragma unroll
;       for (int i = 0; i < 4; ++i) af[i] = *(const h8v*)&As[(wm * 128 + i * 32 + (lane & 31)) * LDH + ks * 16 + 8 * (lane >> 5)];
; #pragma unroll
;       for (int j = 0; j < 2; ++j) bf[j] = *(const h8v*)&Bs[(wn * 64 + j * 32 + (lane & 31)) * LDH + ks * 16 + 8 * (lane >> 5)];
; #pragma unroll
;       for (int i = 0; i < 4; ++i)
; #pragma unroll
;         for (int j = 0; j < 2; ++j) acc[i][j] = mfma32(bf[j], af[i], acc[i][j]);
;     }
;     __syncthreads();
; DI void phase_p1(const Params& p, int l, int bid, int nb, int vb, int vnb, unsigned char* smem, unsigned char* smem_half) {
;     ...
;     gemm256_epilogue(acc, m0, n0, [&](int m, int n, f4v v0, f4v v1) {
;       const bool rope = (n >= 1024 && n < 2560) || (n >= 4352 && n < 4992);
;       if (rope) {
;         const int d = n & 31;
;         f4v c = *(const f4v*)&rc[(size_t)m * 32 + d], s = *(const f4v*)&rs[(size_t)m * 32 + d];
	v_mfma_f32_32x32x16_f16 v[2:17], v[232:235], v[228:231], v[2:17]
	v_mfma_f32_32x32x16_f16 v[18:33], v[236:239], v[228:231], v[18:33]
	ds_read_b128 v[232:235], v214 offset:64
	ds_read_b128 v[216:219], v212 offset:64
	ds_read_b128 v[236:239], v214 offset:4672
	ds_read_b128 v[220:223], v212 offset:4672
	ds_read_b128 v[224:227], v212 offset:9280
	ds_read_b128 v[228:231], v212 offset:13888
	s_waitcnt lgkmcnt(10)
	v_mfma_f32_32x32x16_f16 v[114:129], v[208:211], v[240:243], v[114:129]
	s_waitcnt lgkmcnt(9)
	v_mfma_f32_32x32x16_f16 v[98:113], v[174:177], v[240:243], v[98:113]
	s_waitcnt lgkmcnt(8)
	v_mfma_f32_32x32x16_f16 v[82:97], v[208:211], v[244:247], v[82:97]
	v_mfma_f32_32x32x16_f16 v[66:81], v[174:177], v[244:247], v[66:81]
	s_waitcnt lgkmcnt(7)
	v_mfma_f32_32x32x16_f16 v[50:65], v[208:211], v[200:203], v[50:65]
	v_mfma_f32_32x32x16_f16 v[34:49], v[174:177], v[200:203], v[34:49]
	s_waitcnt lgkmcnt(6)
	v_mfma_f32_32x32x16_f16 v[2:17], v[208:211], v[204:207], v[2:17]
	v_mfma_f32_32x32x16_f16 v[18:33], v[174:177], v[204:207], v[18:33]
	ds_read_b128 v[208:211], v214 offset:96
	ds_read_b128 v[240:243], v212 offset:96
	ds_read_b128 v[174:177], v214 offset:4704
	ds_read_b128 v[244:247], v212 offset:4704
	ds_read_b128 v[200:203], v212 offset:9312
	ds_read_b128 v[204:207], v212 offset:13920
	s_waitcnt lgkmcnt(10)
	v_mfma_f32_32x32x16_f16 v[114:129], v[232:235], v[216:219], v[114:129]
	s_waitcnt lgkmcnt(9)
	v_mfma_f32_32x32x16_f16 v[98:113], v[236:239], v[216:219], v[98:113]
	s_waitcnt lgkmcnt(8)
	v_mfma_f32_32x32x16_f16 v[82:97], v[232:235], v[220:223], v[82:97]
	v_mfma_f32_32x32x16_f16 v[66:81], v[236:239], v[220:223], v[66:81]
	s_waitcnt lgkmcnt(7)
	v_mfma_f32_32x32x16_f16 v[50:65], v[232:235], v[224:227], v[50:65]
	v_mfma_f32_32x32x16_f16 v[34:49], v[236:239], v[224:227], v[34:49]
	s_waitcnt lgkmcnt(6)
	v_mfma_f32_32x32x16_f16 v[2:17], v[232:235], v[228:231], v[2:17]
	v_mfma_f32_32x32x16_f16 v[18:33], v[236:239], v[228:231], v[18:33]
	s_waitcnt lgkmcnt(0)
	v_mfma_f32_32x32x16_f16 v[114:129], v[208:211], v[240:243], v[114:129]
	v_mfma_f32_32x32x16_f16 v[98:113], v[174:177], v[240:243], v[98:113]
	v_mfma_f32_32x32x16_f16 v[82:97], v[208:211], v[244:247], v[82:97]
	v_mfma_f32_32x32x16_f16 v[66:81], v[174:177], v[244:247], v[66:81]
	v_mfma_f32_32x32x16_f16 v[50:65], v[208:211], v[200:203], v[50:65]
	v_mfma_f32_32x32x16_f16 v[34:49], v[174:177], v[200:203], v[34:49]
	v_mfma_f32_32x32x16_f16 v[2:17], v[208:211], v[204:207], v[2:17]
	v_mfma_f32_32x32x16_f16 v[18:33], v[174:177], v[204:207], v[18:33]
	s_nop 15
	v_mov_b32_e32 v192, 0x7f800000
	v_mov_b32_e32 v193, 0x7fc00000
	v_mov_b32_e32 v194, 0xff800000
	v_mov_b32_e32 v204, 0x7fffec00
	v_mov_b32_e32 v205, 0xff7fc99e
	v_mov_b32_e32 v206, 0x840000
	v_mov_b32_e32 v207, 0xb00000
	v_mov_b32_e32 v208, 0xdc0000
	v_mov_b32_e32 v209, 0x1080000
	v_mov_b32_e32 v210, 0x1340000
	v_mov_b32_e32 v211, 0x420000
	v_mov_b32_e32 v212, 0x580000
	v_mov_b32_e32 v213, 0x6e0000
	v_mov_b32_e32 v214, 0x9a0000
	s_setprio 0
	s_barrier
	v_readfirstlane_b32 s66, v180
	s_add_i32 s69, s18, 0x400
	s_sub_i32 s69, s69, s6
	s_lshr_b32 s66, s66, 6
	s_and_b32 s67, s66, 3
	s_lshr_b32 s68, s66, 2
	s_lshl_b32 s70, s67, 6
	s_add_i32 s70, s70, s69
	s_lshl_b32 s71, s68, 7
	s_add_i32 s71, s71, s3
	s_mul_i32 s72, s66, 0x4800
	s_add_i32 s72, s72, 16
	v_and_b32_e32 v146, 63, v180
	v_and_b32_e32 v148, 31, v146
	v_lshrrev_b32_e32 v147, 5, v146
	v_mul_u32_u24_e32 v130, 0x90, v148
	v_lshl_add_u32 v130, v147, 3, v130
	v_add_u32_e32 v130, s72, v130
	v_lshrrev_b32_e32 v149, 3, v146
	v_and_b32_e32 v138, 7, v146
	v_mul_u32_u24_e32 v131, 0x90, v149
	v_lshl_add_u32 v131, v138, 4, v131
	v_add_u32_e32 v131, s72, v131
	v_add_u32_e32 v140, s71, v149
	v_lshl_add_u32 v138, v138, 3, s70
	v_mov_b64_e32 v[132:133], s[0:1]
	v_mad_u64_u32 v[132:133], s[74:75], v140, s95, v[132:133]
	v_lshlrev_b32_e32 v138, 1, v138
	v_mov_b32_e32 v139, v0
	v_lshl_add_u64 v[132:133], v[132:133], 0, v[138:139]
	s_mov_b32 s76, 0x14000
	s_mov_b32 s77, 0
	s_sub_u32 s78, s70, 0x400
	s_cmp_lt_u32 s78, 0x600
	s_cselect_b32 s79, 1, 0
	s_sub_u32 s78, s70, 0x1100
	s_cmp_lt_u32 s78, 0x280
	s_cselect_b32 s78, 1, 0
	s_or_b32 s79, s79, s78
	s_cmp_eq_u32 s79, 0
	s_cbranch_scc1 .Lp1e_norope
	v_readlane_b32 s80, v252, 60
	v_readlane_b32 s81, v252, 61
	v_readlane_b32 s82, v252, 62
	v_readlane_b32 s83, v252, 63
	v_add_u32_e32 v140, s71, v148
	v_lshlrev_b32_e32 v140, 7, v140
	v_lshl_add_u32 v140, v147, 4, v140
	v_mov_b32_e32 v141, v0
	v_lshl_add_u64 v[134:135], s[80:81], 0, v[140:141]
	v_lshl_add_u64 v[136:137], s[82:83], 0, v[140:141]
	s_mov_b32 s84, 0x1000
	s_mov_b32 s85, 0
	global_load_dwordx4 v[150:153], v[134:135], off
	global_load_dwordx4 v[154:157], v[136:137], off
	global_load_dwordx4 v[158:161], v[134:135], off offset:32
	global_load_dwordx4 v[162:165], v[136:137], off offset:32
	global_load_dwordx4 v[216:219], v[134:135], off offset:64
	global_load_dwordx4 v[220:223], v[136:137], off offset:64
	global_load_dwordx4 v[224:227], v[134:135], off offset:96
	global_load_dwordx4 v[228:231], v[136:137], off offset:96
	v_lshl_add_u64 v[134:135], v[134:135], 0, s[84:85]
	v_lshl_add_u64 v[136:137], v[136:137], 0, s[84:85]
	global_load_dwordx4 v[232:235], v[134:135], off
	global_load_dwordx4 v[236:239], v[136:137], off
	global_load_dwordx4 v[240:243], v[134:135], off offset:32
	global_load_dwordx4 v[244:247], v[136:137], off offset:32
	s_waitcnt vmcnt(10)
; DI void phase_p1(const Params& p, int l, int bid, int nb, int vb, int vnb, unsigned char* smem, unsigned char* smem_half) {
;     ...
;     gemm256_epilogue(acc, m0, n0, [&](int m, int n, f4v v0, f4v v1) {
;       const bool rope = (n >= 1024 && n < 2560) || (n >= 4352 && n < 4992);
;       if (rope) {
;         const int d = n & 31;
;         f4v c = *(const f4v*)&rc[(size_t)m * 32 + d], s = *(const f4v*)&rs[(size_t)m * 32 + d];
;         f4v o0 = v0 * c - v1 * s, o1 = v1 * c + v0 * s;
;         v0 = o0; v1 = o1;
;       }
;       st_h4(&ps[(size_t)m * NSM + n], v0);
;       st_h4(&ps[(size_t)m * NSM + n + 32], v1);
	v_pk_mul_f32 v[146:147], v[98:99], v[154:155]
	v_pk_mul_f32 v[148:149], v[114:115], v[154:155]
	v_pk_fma_f32 v[114:115], v[114:115], v[150:151], v[146:147] neg_lo:[0,0,1] neg_hi:[0,0,1]
	v_pk_fma_f32 v[98:99], v[98:99], v[150:151], v[148:149]
	v_pk_mul_f32 v[146:147], v[100:101], v[156:157]
	v_pk_mul_f32 v[148:149], v[116:117], v[156:157]
	v_pk_fma_f32 v[116:117], v[116:117], v[152:153], v[146:147] neg_lo:[0,0,1] neg_hi:[0,0,1]
	v_pk_fma_f32 v[100:101], v[100:101], v[152:153], v[148:149]
	v_cvt_pk_f16_f32 v138, v114, v115
	v_cvt_pk_f16_f32 v139, v116, v117
	ds_write_b64 v130, v[138:139] offset:0
	v_cvt_pk_f16_f32 v140, v98, v99
	v_cvt_pk_f16_f32 v141, v100, v101
	ds_write_b64 v130, v[140:141] offset:64
	global_load_dwordx4 v[150:153], v[134:135], off offset:64
	global_load_dwordx4 v[154:157], v[136:137], off offset:64
	s_waitcnt vmcnt(10)
	v_pk_mul_f32 v[146:147], v[102:103], v[162:163]
	v_pk_mul_f32 v[148:149], v[118:119], v[162:163]
	v_pk_fma_f32 v[118:119], v[118:119], v[158:159], v[146:147] neg_lo:[0,0,1] neg_hi:[0,0,1]
	v_pk_fma_f32 v[102:103], v[102:103], v[158:159], v[148:149]
	v_pk_mul_f32 v[146:147], v[104:105], v[164:165]
	v_pk_mul_f32 v[148:149], v[120:121], v[164:165]
	v_pk_fma_f32 v[120:121], v[120:121], v[160:161], v[146:147] neg_lo:[0,0,1] neg_hi:[0,0,1]
	v_pk_fma_f32 v[104:105], v[104:105], v[160:161], v[148:149]
	v_cvt_pk_f16_f32 v142, v118, v119
	v_cvt_pk_f16_f32 v143, v120, v121
	ds_write_b64 v130, v[142:143] offset:16
	v_cvt_pk_f16_f32 v144, v102, v103
	v_cvt_pk_f16_f32 v145, v104, v105
	ds_write_b64 v130, v[144:145] offset:80
	global_load_dwordx4 v[158:161], v[134:135], off offset:96
	global_load_dwordx4 v[162:165], v[136:137], off offset:96
	s_waitcnt vmcnt(10)
	v_pk_mul_f32 v[146:147], v[106:107], v[220:221]
	v_pk_mul_f32 v[148:149], v[122:123], v[220:221]
	v_pk_fma_f32 v[122:123], v[122:123], v[216:217], v[146:147] neg_lo:[0,0,1] neg_hi:[0,0,1]
	v_pk_fma_f32 v[106:107], v[106:107], v[216:217], v[148:149]
	v_pk_mul_f32 v[146:147], v[108:109], v[222:223]
	v_pk_mul_f32 v[148:149], v[124:125], v[222:223]
	v_pk_fma_f32 v[124:125], v[124:125], v[218:219], v[146:147] neg_lo:[0,0,1] neg_hi:[0,0,1]
	v_pk_fma_f32 v[108:109], v[108:109], v[218:219], v[148:149]
	v_cvt_pk_f16_f32 v138, v122, v123
	v_cvt_pk_f16_f32 v139, v124, v125
	ds_write_b64 v130, v[138:139] offset:32
	v_cvt_pk_f16_f32 v140, v106, v107
	v_cvt_pk_f16_f32 v141, v108, v109
	ds_write_b64 v130, v[140:141] offset:96
	v_lshl_add_u64 v[134:135], v[134:135], 0, s[84:85]
	v_lshl_add_u64 v[136:137], v[136:137], 0, s[84:85]
	global_load_dwordx4 v[216:219], v[134:135], off
	global_load_dwordx4 v[220:223], v[136:137], off
	s_waitcnt vmcnt(10)
	v_pk_mul_f32 v[146:147], v[110:111], v[228:229]
	v_pk_mul_f32 v[148:149], v[126:127], v[228:229]
	v_pk_fma_f32 v[126:127], v[126:127], v[224:225], v[146:147] neg_lo:[0,0,1] neg_hi:[0,0,1]
	v_pk_fma_f32 v[110:111], v[110:111], v[224:225], v[148:149]
	v_pk_mul_f32 v[146:147], v[112:113], v[230:231]
	v_pk_mul_f32 v[148:149], v[128:129], v[230:231]
	v_pk_fma_f32 v[128:129], v[128:129], v[226:227], v[146:147] neg_lo:[0,0,1] neg_hi:[0,0,1]
	v_pk_fma_f32 v[112:113], v[112:113], v[226:227], v[148:149]
	v_cvt_pk_f16_f32 v142, v126, v127
	v_cvt_pk_f16_f32 v143, v128, v129
	ds_write_b64 v130, v[142:143] offset:48
	v_cvt_pk_f16_f32 v144, v110, v111
	v_cvt_pk_f16_f32 v145, v112, v113
	ds_write_b64 v130, v[144:145] offset:112
	global_load_dwordx4 v[224:227], v[134:135], off offset:32
	global_load_dwordx4 v[228:231], v[136:137], off offset:32
	s_waitcnt vmcnt(10)
	v_pk_mul_f32 v[146:147], v[66:67], v[236:237]
	v_pk_mul_f32 v[148:149], v[82:83], v[236:237]
	v_pk_fma_f32 v[82:83], v[82:83], v[232:233], v[146:147] neg_lo:[0,0,1] neg_hi:[0,0,1]
	v_pk_fma_f32 v[66:67], v[66:67], v[232:233], v[148:149]
	v_pk_mul_f32 v[146:147], v[68:69], v[238:239]
	v_pk_mul_f32 v[148:149], v[84:85], v[238:239]
	v_pk_fma_f32 v[84:85], v[84:85], v[234:235], v[146:147] neg_lo:[0,0,1] neg_hi:[0,0,1]
	v_pk_fma_f32 v[68:69], v[68:69], v[234:235], v[148:149]
	v_cvt_pk_f16_f32 v138, v82, v83
	v_cvt_pk_f16_f32 v139, v84, v85
	ds_write_b64 v130, v[138:139] offset:4608
	v_cvt_pk_f16_f32 v140, v66, v67
	v_cvt_pk_f16_f32 v141, v68, v69
	ds_write_b64 v130, v[140:141] offset:4672
	global_load_dwordx4 v[232:235], v[134:135], off offset:64
	global_load_dwordx4 v[236:239], v[136:137], off offset:64
	s_waitcnt vmcnt(10)
	v_pk_mul_f32 v[146:147], v[70:71], v[244:245]
	v_pk_mul_f32 v[148:149], v[86:87], v[244:245]
	v_pk_fma_f32 v[86:87], v[86:87], v[240:241], v[146:147] neg_lo:[0,0,1] neg_hi:[0,0,1]
	v_pk_fma_f32 v[70:71], v[70:71], v[240:241], v[148:149]
	v_pk_mul_f32 v[146:147], v[72:73], v[246:247]
	v_pk_mul_f32 v[148:149], v[88:89], v[246:247]
	v_pk_fma_f32 v[88:89], v[88:89], v[242:243], v[146:147] neg_lo:[0,0,1] neg_hi:[0,0,1]
	v_pk_fma_f32 v[72:73], v[72:73], v[242:243], v[148:149]
	v_cvt_pk_f16_f32 v142, v86, v87
	v_cvt_pk_f16_f32 v143, v88, v89
	ds_write_b64 v130, v[142:143] offset:4624
	v_cvt_pk_f16_f32 v144, v70, v71
	v_cvt_pk_f16_f32 v145, v72, v73
	ds_write_b64 v130, v[144:145] offset:4688
	global_load_dwordx4 v[240:243], v[134:135], off offset:96
	global_load_dwordx4 v[244:247], v[136:137], off offset:96
	s_waitcnt vmcnt(10)
; DI void phase_p1(const Params& p, int l, int bid, int nb, int vb, int vnb, unsigned char* smem, unsigned char* smem_half) {
;     ...
;     gemm256_epilogue(acc, m0, n0, [&](int m, int n, f4v v0, f4v v1) {
;       const bool rope = (n >= 1024 && n < 2560) || (n >= 4352 && n < 4992);
;       if (rope) {
;         const int d = n & 31;
;         f4v c = *(const f4v*)&rc[(size_t)m * 32 + d], s = *(const f4v*)&rs[(size_t)m * 32 + d];
;         f4v o0 = v0 * c - v1 * s, o1 = v1 * c + v0 * s;
;         v0 = o0; v1 = o1;
;       }
;       st_h4(&ps[(size_t)m * NSM + n], v0);
;       st_h4(&ps[(size_t)m * NSM + n + 32], v1);
	v_pk_mul_f32 v[146:147], v[74:75], v[154:155]
	v_pk_mul_f32 v[148:149], v[90:91], v[154:155]
	v_pk_fma_f32 v[90:91], v[90:91], v[150:151], v[146:147] neg_lo:[0,0,1] neg_hi:[0,0,1]
	v_pk_fma_f32 v[74:75], v[74:75], v[150:151], v[148:149]
	v_pk_mul_f32 v[146:147], v[76:77], v[156:157]
	v_pk_mul_f32 v[148:149], v[92:93], v[156:157]
	v_pk_fma_f32 v[92:93], v[92:93], v[152:153], v[146:147] neg_lo:[0,0,1] neg_hi:[0,0,1]
	v_pk_fma_f32 v[76:77], v[76:77], v[152:153], v[148:149]
	v_cvt_pk_f16_f32 v138, v90, v91
	v_cvt_pk_f16_f32 v139, v92, v93
	ds_write_b64 v130, v[138:139] offset:4640
	v_cvt_pk_f16_f32 v140, v74, v75
	v_cvt_pk_f16_f32 v141, v76, v77
	ds_write_b64 v130, v[140:141] offset:4704
	v_lshl_add_u64 v[134:135], v[134:135], 0, s[84:85]
	v_lshl_add_u64 v[136:137], v[136:137], 0, s[84:85]
	global_load_dwordx4 v[150:153], v[134:135], off
	global_load_dwordx4 v[154:157], v[136:137], off
	s_waitcnt vmcnt(10)
	v_pk_mul_f32 v[146:147], v[78:79], v[162:163]
	v_pk_mul_f32 v[148:149], v[94:95], v[162:163]
	v_pk_fma_f32 v[94:95], v[94:95], v[158:159], v[146:147] neg_lo:[0,0,1] neg_hi:[0,0,1]
	v_pk_fma_f32 v[78:79], v[78:79], v[158:159], v[148:149]
	v_pk_mul_f32 v[146:147], v[80:81], v[164:165]
	v_pk_mul_f32 v[148:149], v[96:97], v[164:165]
	v_pk_fma_f32 v[96:97], v[96:97], v[160:161], v[146:147] neg_lo:[0,0,1] neg_hi:[0,0,1]
	v_pk_fma_f32 v[80:81], v[80:81], v[160:161], v[148:149]
	v_cvt_pk_f16_f32 v142, v94, v95
	v_cvt_pk_f16_f32 v143, v96, v97
	ds_write_b64 v130, v[142:143] offset:4656
	v_cvt_pk_f16_f32 v144, v78, v79
	v_cvt_pk_f16_f32 v145, v80, v81
	ds_write_b64 v130, v[144:145] offset:4720
	global_load_dwordx4 v[158:161], v[134:135], off offset:32
	global_load_dwordx4 v[162:165], v[136:137], off offset:32
	s_waitcnt vmcnt(10)
	v_pk_mul_f32 v[146:147], v[34:35], v[220:221]
	v_pk_mul_f32 v[148:149], v[50:51], v[220:221]
	v_pk_fma_f32 v[50:51], v[50:51], v[216:217], v[146:147] neg_lo:[0,0,1] neg_hi:[0,0,1]
	v_pk_fma_f32 v[34:35], v[34:35], v[216:217], v[148:149]
	v_pk_mul_f32 v[146:147], v[36:37], v[222:223]
	v_pk_mul_f32 v[148:149], v[52:53], v[222:223]
	v_pk_fma_f32 v[52:53], v[52:53], v[218:219], v[146:147] neg_lo:[0,0,1] neg_hi:[0,0,1]
	v_pk_fma_f32 v[36:37], v[36:37], v[218:219], v[148:149]
	v_cvt_pk_f16_f32 v138, v50, v51
	v_cvt_pk_f16_f32 v139, v52, v53
	ds_write_b64 v130, v[138:139] offset:9216
	v_cvt_pk_f16_f32 v140, v34, v35
	v_cvt_pk_f16_f32 v141, v36, v37
	ds_write_b64 v130, v[140:141] offset:9280
	global_load_dwordx4 v[216:219], v[134:135], off offset:64
	global_load_dwordx4 v[220:223], v[136:137], off offset:64
	s_waitcnt vmcnt(10)
	v_pk_mul_f32 v[146:147], v[38:39], v[228:229]
	v_pk_mul_f32 v[148:149], v[54:55], v[228:229]
	v_pk_fma_f32 v[54:55], v[54:55], v[224:225], v[146:147] neg_lo:[0,0,1] neg_hi:[0,0,1]
	v_pk_fma_f32 v[38:39], v[38:39], v[224:225], v[148:149]
	v_pk_mul_f32 v[146:147], v[40:41], v[230:231]
	v_pk_mul_f32 v[148:149], v[56:57], v[230:231]
	v_pk_fma_f32 v[56:57], v[56:57], v[226:227], v[146:147] neg_lo:[0,0,1] neg_hi:[0,0,1]
	v_pk_fma_f32 v[40:41], v[40:41], v[226:227], v[148:149]
	v_cvt_pk_f16_f32 v142, v54, v55
	v_cvt_pk_f16_f32 v143, v56, v57
	ds_write_b64 v130, v[142:143] offset:9232
	v_cvt_pk_f16_f32 v144, v38, v39
	v_cvt_pk_f16_f32 v145, v40, v41
	ds_write_b64 v130, v[144:145] offset:9296
	global_load_dwordx4 v[224:227], v[134:135], off offset:96
	global_load_dwordx4 v[228:231], v[136:137], off offset:96
	s_waitcnt vmcnt(10)
	v_pk_mul_f32 v[146:147], v[42:43], v[236:237]
	v_pk_mul_f32 v[148:149], v[58:59], v[236:237]
	v_pk_fma_f32 v[58:59], v[58:59], v[232:233], v[146:147] neg_lo:[0,0,1] neg_hi:[0,0,1]
	v_pk_fma_f32 v[42:43], v[42:43], v[232:233], v[148:149]
	v_pk_mul_f32 v[146:147], v[44:45], v[238:239]
	v_pk_mul_f32 v[148:149], v[60:61], v[238:239]
	v_pk_fma_f32 v[60:61], v[60:61], v[234:235], v[146:147] neg_lo:[0,0,1] neg_hi:[0,0,1]
	v_pk_fma_f32 v[44:45], v[44:45], v[234:235], v[148:149]
	v_cvt_pk_f16_f32 v138, v58, v59
	v_cvt_pk_f16_f32 v139, v60, v61
	ds_write_b64 v130, v[138:139] offset:9248
	v_cvt_pk_f16_f32 v140, v42, v43
	v_cvt_pk_f16_f32 v141, v44, v45
	ds_write_b64 v130, v[140:141] offset:9312
	s_waitcnt vmcnt(8)
; DI void phase_p1(const Params& p, int l, int bid, int nb, int vb, int vnb, unsigned char* smem, unsigned char* smem_half) {
;     ...
;     gemm256_epilogue(acc, m0, n0, [&](int m, int n, f4v v0, f4v v1) {
;       const bool rope = (n >= 1024 && n < 2560) || (n >= 4352 && n < 4992);
;       if (rope) {
;         const int d = n & 31;
;         f4v c = *(const f4v*)&rc[(size_t)m * 32 + d], s = *(const f4v*)&rs[(size_t)m * 32 + d];
;         f4v o0 = v0 * c - v1 * s, o1 = v1 * c + v0 * s;
;         v0 = o0; v1 = o1;
;       }
;       st_h4(&ps[(size_t)m * NSM + n], v0);
;       st_h4(&ps[(size_t)m * NSM + n + 32], v1);
	v_pk_mul_f32 v[146:147], v[46:47], v[244:245]
	v_pk_mul_f32 v[148:149], v[62:63], v[244:245]
	v_pk_fma_f32 v[62:63], v[62:63], v[240:241], v[146:147] neg_lo:[0,0,1] neg_hi:[0,0,1]
	v_pk_fma_f32 v[46:47], v[46:47], v[240:241], v[148:149]
	v_pk_mul_f32 v[146:147], v[48:49], v[246:247]
	v_pk_mul_f32 v[148:149], v[64:65], v[246:247]
	v_pk_fma_f32 v[64:65], v[64:65], v[242:243], v[146:147] neg_lo:[0,0,1] neg_hi:[0,0,1]
	v_pk_fma_f32 v[48:49], v[48:49], v[242:243], v[148:149]
	v_cvt_pk_f16_f32 v142, v62, v63
	v_cvt_pk_f16_f32 v143, v64, v65
	ds_write_b64 v130, v[142:143] offset:9264
	v_cvt_pk_f16_f32 v144, v46, v47
	v_cvt_pk_f16_f32 v145, v48, v49
	ds_write_b64 v130, v[144:145] offset:9328
	s_waitcnt vmcnt(6)
	v_pk_mul_f32 v[146:147], v[18:19], v[154:155]
	v_pk_mul_f32 v[148:149], v[2:3], v[154:155]
	v_pk_fma_f32 v[2:3], v[2:3], v[150:151], v[146:147] neg_lo:[0,0,1] neg_hi:[0,0,1]
	v_pk_fma_f32 v[18:19], v[18:19], v[150:151], v[148:149]
	v_pk_mul_f32 v[146:147], v[20:21], v[156:157]
	v_pk_mul_f32 v[148:149], v[4:5], v[156:157]
	v_pk_fma_f32 v[4:5], v[4:5], v[152:153], v[146:147] neg_lo:[0,0,1] neg_hi:[0,0,1]
	v_pk_fma_f32 v[20:21], v[20:21], v[152:153], v[148:149]
	v_cvt_pk_f16_f32 v138, v2, v3
	v_cvt_pk_f16_f32 v139, v4, v5
	ds_write_b64 v130, v[138:139] offset:13824
	v_cvt_pk_f16_f32 v140, v18, v19
	v_cvt_pk_f16_f32 v141, v20, v21
	ds_write_b64 v130, v[140:141] offset:13888
	s_waitcnt vmcnt(4)
	v_pk_mul_f32 v[146:147], v[22:23], v[162:163]
	v_pk_mul_f32 v[148:149], v[6:7], v[162:163]
	v_pk_fma_f32 v[6:7], v[6:7], v[158:159], v[146:147] neg_lo:[0,0,1] neg_hi:[0,0,1]
	v_pk_fma_f32 v[22:23], v[22:23], v[158:159], v[148:149]
	v_pk_mul_f32 v[146:147], v[24:25], v[164:165]
	v_pk_mul_f32 v[148:149], v[8:9], v[164:165]
	v_pk_fma_f32 v[8:9], v[8:9], v[160:161], v[146:147] neg_lo:[0,0,1] neg_hi:[0,0,1]
	v_pk_fma_f32 v[24:25], v[24:25], v[160:161], v[148:149]
	v_cvt_pk_f16_f32 v142, v6, v7
	v_cvt_pk_f16_f32 v143, v8, v9
	ds_write_b64 v130, v[142:143] offset:13840
	v_cvt_pk_f16_f32 v144, v22, v23
	v_cvt_pk_f16_f32 v145, v24, v25
	ds_write_b64 v130, v[144:145] offset:13904
	s_waitcnt vmcnt(2)
	v_pk_mul_f32 v[146:147], v[26:27], v[220:221]
	v_pk_mul_f32 v[148:149], v[10:11], v[220:221]
	v_pk_fma_f32 v[10:11], v[10:11], v[216:217], v[146:147] neg_lo:[0,0,1] neg_hi:[0,0,1]
	v_pk_fma_f32 v[26:27], v[26:27], v[216:217], v[148:149]
	v_pk_mul_f32 v[146:147], v[28:29], v[222:223]
	v_pk_mul_f32 v[148:149], v[12:13], v[222:223]
	v_pk_fma_f32 v[12:13], v[12:13], v[218:219], v[146:147] neg_lo:[0,0,1] neg_hi:[0,0,1]
	v_pk_fma_f32 v[28:29], v[28:29], v[218:219], v[148:149]
	v_cvt_pk_f16_f32 v138, v10, v11
	v_cvt_pk_f16_f32 v139, v12, v13
	ds_write_b64 v130, v[138:139] offset:13856
	v_cvt_pk_f16_f32 v140, v26, v27
	v_cvt_pk_f16_f32 v141, v28, v29
	ds_write_b64 v130, v[140:141] offset:13920
	s_waitcnt vmcnt(0)
	v_pk_mul_f32 v[146:147], v[30:31], v[228:229]
	v_pk_mul_f32 v[148:149], v[14:15], v[228:229]
	v_pk_fma_f32 v[14:15], v[14:15], v[224:225], v[146:147] neg_lo:[0,0,1] neg_hi:[0,0,1]
	v_pk_fma_f32 v[30:31], v[30:31], v[224:225], v[148:149]
	v_pk_mul_f32 v[146:147], v[32:33], v[230:231]
	v_pk_mul_f32 v[148:149], v[16:17], v[230:231]
	v_pk_fma_f32 v[16:17], v[16:17], v[226:227], v[146:147] neg_lo:[0,0,1] neg_hi:[0,0,1]
	v_pk_fma_f32 v[32:33], v[32:33], v[226:227], v[148:149]
	v_cvt_pk_f16_f32 v142, v14, v15
	v_cvt_pk_f16_f32 v143, v16, v17
	ds_write_b64 v130, v[142:143] offset:13872
	v_cvt_pk_f16_f32 v144, v30, v31
	v_cvt_pk_f16_f32 v145, v32, v33
	ds_write_b64 v130, v[144:145] offset:13936
	s_branch .Lp1e_store

; template <bool GATHER>
; DI void gemm256_main(const h16* __restrict__ A, int lda, const int* __restrict__ idx, int m0,
;                      const h16* __restrict__ B, int ldb, int n0, int K, h16* lds, f16v (&acc)[4][2]) {
;   const int tid = otid512(), lane = tid & 63, wv = tid >> 6, wm = wv >> 2, wn = wv & 3;
;   const int lr = tid >> 1, lc = (tid & 1) * 32;
;   unsigned ao = (unsigned)(GATHER ? idx[m0 + lr] : (m0 + lr)) * (unsigned)lda + lc;
;   unsigned bo = (unsigned)(n0 + lr) * (unsigned)ldb + lc;
;   const h16* ap = A; const h16* bp = B;
;     ...
;   u4v ra[4], rb[4];
;   const int nk = K >> 6;
;   __syncthreads();
; #pragma unroll
;   for (int i = 0; i < 4; ++i) { ra[i] = *(const u4v*)(AP_ + 8 * i); rb[i] = *(const u4v*)(BP_ + 8 * i); }
;   ao += 64; bo += 64;
; #pragma unroll
;   for (int i = 0; i < 4; ++i) { *(u4v*)&lds[lr * LDH + lc + 8 * i] = ra[i]; *(u4v*)&lds[(256 + lr) * LDH + lc + 8 * i] = rb[i]; }
; #pragma unroll
;   for (int i = 0; i < 4; ++i) { ra[i] = *(const u4v*)(AP_ + 8 * i); rb[i] = *(const u4v*)(BP_ + 8 * i); }
;   ao += 64; bo += 64;
;   __syncthreads();
;   for (int kt = 0; kt < nk; ++kt) {
;     const h16* As = lds + (kt & 1) * (512 * LDH);
;     const h16* Bs = As + 256 * LDH;
;     h16* Wn = lds + ((kt & 1) ^ 1) * (512 * LDH);
;     if (kt + 1 < nk) {
; #pragma unroll
;       for (int i = 0; i < 4; ++i) { *(u4v*)&Wn[lr * LDH + lc + 8 * i] = ra[i]; *(u4v*)&Wn[(256 + lr) * LDH + lc + 8 * i] = rb[i]; }
;     }
;     if (kt + 2 < nk) {
; #pragma unroll
;       for (int i = 0; i < 4; ++i) { ra[i] = *(const u4v*)(AP_ + 8 * i); rb[i] = *(const u4v*)(BP_ + 8 * i); }
;       ao += 64; bo += 64;
;     }
; #pragma unroll
;     for (int ks = 0; ks < 4; ++ks) {
;       h8v af[4], bf[2];
; #pragma unroll
;       for (int i = 0; i < 4; ++i) af[i] = *(const h8v*)&As[(wm * 128 + i * 32 + (lane & 31)) * LDH + ks * 16 + 8 * (lane >> 5)];
; #pragma unroll
;       for (int j = 0; j < 2; ++j) bf[j] = *(const h8v*)&Bs[(wn * 64 + j * 32 + (lane & 31)) * LDH + ks * 16 + 8 * (lane >> 5)];
; #pragma unroll
;       for (int i = 0; i < 4; ++i)
; #pragma unroll
; DI void phase_gates(const Params& p, int bid, int nb, h16* lds) {
;     ...
;   for (int u = bid; u < 64 * 16; u += nb) {
;     const int m0 = (u >> 4) * 256, n0 = (u & 15) * 256;
;     f16v acc[4][2]; acc256_zero(acc);
;     gemm256_main<false>(x16, DM, nullptr, m0, wg, 1024, n0, 1024, lds, acc);
.LBB0_1246:
	v_mov_b32_e32 v1, v180
	s_and_b32 s6, s2, 0xffffff00
	s_and_b32 s5, s3, 0xf00
	v_mov_b32_e32 v177, v0
	v_ashrrev_i32_e32 v34, 1, v1
	v_lshlrev_b32_e32 v2, 5, v1
	v_and_b32_e32 v35, 32, v2
	v_add_u32_e32 v2, s6, v34
	v_add_u32_e32 v3, s5, v34
	v_lshl_or_b32 v2, v2, 10, v35
	v_lshl_or_b32 v176, v3, 10, v35
	v_mov_b32_e32 v3, v0
	v_lshl_add_u64 v[174:175], v[2:3], 1, s[20:21]
	v_lshl_add_u64 v[30:31], v[176:177], 1, s[16:17]
	s_barrier
	s_add_i32 s4, s4, s22
	s_add_i32 s3, s3, s9
	s_add_i32 s2, s2, s35
	s_cmpk_lt_i32 s4, 0x400
	v_mov_b32_e32 v130, v174
	v_mov_b32_e32 v131, v175
	v_mov_b32_e32 v202, v30
	v_mov_b32_e32 v203, v31
	s_cselect_b32 s98, 1, 0
	v_readfirstlane_b32 s99, v180
	s_nop 1
	s_cmp_lt_u32 s99, 0x100
	s_cbranch_scc1 .Lprio_skip_2
	s_setprio 1
.Lprio_skip_2:
	s_cmp_eq_u32 s98, 1
	v_lshrrev_b32_e32 v192, 1, v180
	v_and_b32_e32 v193, 1, v180
	v_mul_u32_u24_e32 v192, 0x90, v192
	v_lshl_add_u32 v178, v193, 6, v192
	v_add_u32_e32 v178, 16, v178
	v_add_u32_e32 v179, 0x12000, v178
	v_lshrrev_b32_e32 v192, 8, v180
	v_and_b32_e32 v194, 31, v180
	v_lshl_or_b32 v192, v192, 7, v194
	v_mul_u32_u24_e32 v192, 0x90, v192
	v_bfe_u32 v193, v180, 5, 1
	v_lshl_add_u32 v192, v193, 4, v192
	v_add_u32_e32 v215, 16, v192
	v_add_u32_e32 v212, 0x12000, v215
	v_bfe_u32 v192, v180, 6, 2
	v_lshl_or_b32 v192, v192, 6, v194
	v_mul_u32_u24_e32 v192, 0x90, v192
	v_lshl_add_u32 v192, v193, 4, v192
	v_add_u32_e32 v213, 0x9010, v192
	v_add_u32_e32 v214, 0x12000, v213
	global_load_dwordx4 v[134:137], v[130:131], off offset:0
	global_load_dwordx4 v[138:141], v[130:131], off offset:16
	global_load_dwordx4 v[142:145], v[130:131], off offset:32
	global_load_dwordx4 v[146:149], v[130:131], off offset:48
	global_load_dwordx4 v[150:153], v[202:203], off offset:0
	global_load_dwordx4 v[154:157], v[202:203], off offset:16
	global_load_dwordx4 v[158:161], v[202:203], off offset:32
	global_load_dwordx4 v[162:165], v[202:203], off offset:48
	s_waitcnt vmcnt(0)
	ds_write_b128 v178, v[134:137]
	ds_write_b128 v178, v[138:141] offset:16
	ds_write_b128 v178, v[142:145] offset:32
	ds_write_b128 v178, v[146:149] offset:48
	ds_write_b128 v178, v[150:153] offset:36864
	ds_write_b128 v178, v[154:157] offset:36880
	ds_write_b128 v178, v[158:161] offset:36896
	ds_write_b128 v178, v[162:165] offset:36912
	global_load_dwordx4 v[134:137], v[130:131], off offset:128
	global_load_dwordx4 v[138:141], v[130:131], off offset:144
	global_load_dwordx4 v[142:145], v[130:131], off offset:160
	global_load_dwordx4 v[146:149], v[130:131], off offset:176
	global_load_dwordx4 v[150:153], v[202:203], off offset:128
	global_load_dwordx4 v[154:157], v[202:203], off offset:144
	global_load_dwordx4 v[158:161], v[202:203], off offset:160
	global_load_dwordx4 v[162:165], v[202:203], off offset:176
	s_waitcnt lgkmcnt(0)
	s_barrier
	ds_read_b128 v[232:235], v213
	ds_read_b128 v[216:219], v215
	ds_read_b128 v[236:239], v213 offset:4608
	ds_read_b128 v[220:223], v215 offset:4608
	ds_read_b128 v[224:227], v215 offset:9216
	ds_read_b128 v[228:231], v215 offset:13824
	ds_read_b128 v[208:211], v213 offset:32
	ds_read_b128 v[240:243], v215 offset:32
	ds_read_b128 v[174:177], v213 offset:4640
	ds_read_b128 v[244:247], v215 offset:4640
	ds_read_b128 v[248:251], v215 offset:9248
	ds_read_b128 v[204:207], v215 offset:13856
	s_waitcnt vmcnt(4)
	ds_write_b128 v179, v[134:137]
	ds_write_b128 v179, v[138:141] offset:16
	ds_write_b128 v179, v[142:145] offset:32
	ds_write_b128 v179, v[146:149] offset:48
	global_load_dwordx4 v[134:137], v[130:131], off offset:256
	global_load_dwordx4 v[138:141], v[130:131], off offset:272
	global_load_dwordx4 v[142:145], v[130:131], off offset:288
	global_load_dwordx4 v[146:149], v[130:131], off offset:304
	s_waitcnt lgkmcnt(14)
	v_mfma_f32_32x32x16_f16 v[114:129], v[232:235], v[216:219], 0
	s_waitcnt lgkmcnt(13)
	v_mfma_f32_32x32x16_f16 v[98:113], v[236:239], v[216:219], 0
	s_waitcnt lgkmcnt(12)
	v_mfma_f32_32x32x16_f16 v[82:97], v[232:235], v[220:223], 0
	v_mfma_f32_32x32x16_f16 v[66:81], v[236:239], v[220:223], 0
	s_waitcnt lgkmcnt(11)
	v_mfma_f32_32x32x16_f16 v[50:65], v[232:235], v[224:227], 0
	v_mfma_f32_32x32x16_f16 v[34:49], v[236:239], v[224:227], 0
	s_waitcnt lgkmcnt(10)
	v_mfma_f32_32x32x16_f16 v[18:33], v[232:235], v[228:231], 0
	v_mfma_f32_32x32x16_f16 v[2:17], v[236:239], v[228:231], 0
	ds_read_b128 v[232:235], v213 offset:64
	ds_read_b128 v[216:219], v215 offset:64
	ds_read_b128 v[236:239], v213 offset:4672
	ds_read_b128 v[220:223], v215 offset:4672
	ds_read_b128 v[224:227], v215 offset:9280
	ds_read_b128 v[228:231], v215 offset:13888
	s_waitcnt vmcnt(4)
	ds_write_b128 v179, v[150:153] offset:36864
	ds_write_b128 v179, v[154:157] offset:36880
	ds_write_b128 v179, v[158:161] offset:36896
	ds_write_b128 v179, v[162:165] offset:36912
	global_load_dwordx4 v[150:153], v[202:203], off offset:256
	global_load_dwordx4 v[154:157], v[202:203], off offset:272
	global_load_dwordx4 v[158:161], v[202:203], off offset:288
	global_load_dwordx4 v[162:165], v[202:203], off offset:304
	s_waitcnt lgkmcnt(15)
	v_mfma_f32_32x32x16_f16 v[114:129], v[208:211], v[240:243], v[114:129]
	s_waitcnt lgkmcnt(15)
	v_mfma_f32_32x32x16_f16 v[98:113], v[174:177], v[240:243], v[98:113]
	s_waitcnt lgkmcnt(15)
	v_mfma_f32_32x32x16_f16 v[82:97], v[208:211], v[244:247], v[82:97]
	v_mfma_f32_32x32x16_f16 v[66:81], v[174:177], v[244:247], v[66:81]
	s_waitcnt lgkmcnt(15)
	v_mfma_f32_32x32x16_f16 v[50:65], v[208:211], v[248:251], v[50:65]
	v_mfma_f32_32x32x16_f16 v[34:49], v[174:177], v[248:251], v[34:49]
	s_waitcnt lgkmcnt(14)
	v_mfma_f32_32x32x16_f16 v[18:33], v[208:211], v[204:207], v[18:33]
	v_mfma_f32_32x32x16_f16 v[2:17], v[174:177], v[204:207], v[2:17]
	ds_read_b128 v[208:211], v213 offset:96
	ds_read_b128 v[240:243], v215 offset:96
	ds_read_b128 v[174:177], v213 offset:4704
	ds_read_b128 v[244:247], v215 offset:4704
	ds_read_b128 v[248:251], v215 offset:9312
	ds_read_b128 v[204:207], v215 offset:13920
	s_waitcnt lgkmcnt(14)
	v_mfma_f32_32x32x16_f16 v[114:129], v[232:235], v[216:219], v[114:129]
	s_waitcnt lgkmcnt(13)
	v_mfma_f32_32x32x16_f16 v[98:113], v[236:239], v[216:219], v[98:113]
	s_waitcnt lgkmcnt(12)
	v_mfma_f32_32x32x16_f16 v[82:97], v[232:235], v[220:223], v[82:97]
	v_mfma_f32_32x32x16_f16 v[66:81], v[236:239], v[220:223], v[66:81]
	s_waitcnt lgkmcnt(11)
	v_mfma_f32_32x32x16_f16 v[50:65], v[232:235], v[224:227], v[50:65]
	v_mfma_f32_32x32x16_f16 v[34:49], v[236:239], v[224:227], v[34:49]
	s_waitcnt lgkmcnt(10)
	v_mfma_f32_32x32x16_f16 v[18:33], v[232:235], v[228:231], v[18:33]
	v_mfma_f32_32x32x16_f16 v[2:17], v[236:239], v[228:231], v[2:17]
	s_waitcnt lgkmcnt(0)
	s_barrier
; DI f16v mfma32(h8v a, h8v b, f16v c) { return __builtin_amdgcn_mfma_f32_32x32x16_f16(a, b, c, 0, 0, 0); }
; template <bool GATHER>
; DI void gemm256_main(const h16* __restrict__ A, int lda, const int* __restrict__ idx, int m0,
;                      const h16* __restrict__ B, int ldb, int n0, int K, h16* lds, f16v (&acc)[4][2]) {
;     ...
;   for (int kt = 0; kt < nk; ++kt) {
;     const h16* As = lds + (kt & 1) * (512 * LDH);
;     const h16* Bs = As + 256 * LDH;
;     h16* Wn = lds + ((kt & 1) ^ 1) * (512 * LDH);
;     if (kt + 1 < nk) {
; #pragma unroll
;       for (int i = 0; i < 4; ++i) { *(u4v*)&Wn[lr * LDH + lc + 8 * i] = ra[i]; *(u4v*)&Wn[(256 + lr) * LDH + lc + 8 * i] = rb[i]; }
;     }
;     if (kt + 2 < nk) {
; #pragma unroll
;       for (int i = 0; i < 4; ++i) { ra[i] = *(const u4v*)(AP_ + 8 * i); rb[i] = *(const u4v*)(BP_ + 8 * i); }
;       ao += 64; bo += 64;
;     }
; #pragma unroll
;     for (int ks = 0; ks < 4; ++ks) {
;       h8v af[4], bf[2];
; #pragma unroll
;       for (int i = 0; i < 4; ++i) af[i] = *(const h8v*)&As[(wm * 128 + i * 32 + (lane & 31)) * LDH + ks * 16 + 8 * (lane >> 5)];
; #pragma unroll
;       for (int j = 0; j < 2; ++j) bf[j] = *(const h8v*)&Bs[(wn * 64 + j * 32 + (lane & 31)) * LDH + ks * 16 + 8 * (lane >> 5)];
; #pragma unroll
;       for (int i = 0; i < 4; ++i)
; #pragma unroll
;         for (int j = 0; j < 2; ++j) acc[i][j] = mfma32(bf[j], af[i], acc[i][j]);
;     }
;     __syncthreads();
	ds_read_b128 v[232:235], v214
	ds_read_b128 v[216:219], v212
	ds_read_b128 v[236:239], v214 offset:4608
	ds_read_b128 v[220:223], v212 offset:4608
	ds_read_b128 v[224:227], v212 offset:9216
	ds_read_b128 v[228:231], v212 offset:13824
	v_mfma_f32_32x32x16_f16 v[114:129], v[208:211], v[240:243], v[114:129]
	v_mfma_f32_32x32x16_f16 v[98:113], v[174:177], v[240:243], v[98:113]
	v_mfma_f32_32x32x16_f16 v[82:97], v[208:211], v[244:247], v[82:97]
	v_mfma_f32_32x32x16_f16 v[66:81], v[174:177], v[244:247], v[66:81]
	v_mfma_f32_32x32x16_f16 v[50:65], v[208:211], v[248:251], v[50:65]
	v_mfma_f32_32x32x16_f16 v[34:49], v[174:177], v[248:251], v[34:49]
	v_mfma_f32_32x32x16_f16 v[18:33], v[208:211], v[204:207], v[18:33]
	v_mfma_f32_32x32x16_f16 v[2:17], v[174:177], v[204:207], v[2:17]
	ds_read_b128 v[208:211], v214 offset:32
	ds_read_b128 v[240:243], v212 offset:32
	ds_read_b128 v[174:177], v214 offset:4640
	ds_read_b128 v[244:247], v212 offset:4640
	ds_read_b128 v[248:251], v212 offset:9248
	ds_read_b128 v[204:207], v212 offset:13856
	s_waitcnt vmcnt(4)
	ds_write_b128 v178, v[134:137]
	ds_write_b128 v178, v[138:141] offset:16
	ds_write_b128 v178, v[142:145] offset:32
	ds_write_b128 v178, v[146:149] offset:48
	global_load_dwordx4 v[134:137], v[130:131], off offset:384
	global_load_dwordx4 v[138:141], v[130:131], off offset:400
	global_load_dwordx4 v[142:145], v[130:131], off offset:416
	global_load_dwordx4 v[146:149], v[130:131], off offset:432
	s_waitcnt lgkmcnt(14)
	v_mfma_f32_32x32x16_f16 v[114:129], v[232:235], v[216:219], v[114:129]
	s_waitcnt lgkmcnt(13)
	v_mfma_f32_32x32x16_f16 v[98:113], v[236:239], v[216:219], v[98:113]
	s_waitcnt lgkmcnt(12)
	v_mfma_f32_32x32x16_f16 v[82:97], v[232:235], v[220:223], v[82:97]
	v_mfma_f32_32x32x16_f16 v[66:81], v[236:239], v[220:223], v[66:81]
	s_waitcnt lgkmcnt(11)
	v_mfma_f32_32x32x16_f16 v[50:65], v[232:235], v[224:227], v[50:65]
	v_mfma_f32_32x32x16_f16 v[34:49], v[236:239], v[224:227], v[34:49]
	s_waitcnt lgkmcnt(10)
	v_mfma_f32_32x32x16_f16 v[18:33], v[232:235], v[228:231], v[18:33]
	v_mfma_f32_32x32x16_f16 v[2:17], v[236:239], v[228:231], v[2:17]
	ds_read_b128 v[232:235], v214 offset:64
	ds_read_b128 v[216:219], v212 offset:64
	ds_read_b128 v[236:239], v214 offset:4672
	ds_read_b128 v[220:223], v212 offset:4672
	ds_read_b128 v[224:227], v212 offset:9280
	ds_read_b128 v[228:231], v212 offset:13888
	s_waitcnt vmcnt(4)
	ds_write_b128 v178, v[150:153] offset:36864
	ds_write_b128 v178, v[154:157] offset:36880
	ds_write_b128 v178, v[158:161] offset:36896
	ds_write_b128 v178, v[162:165] offset:36912
	global_load_dwordx4 v[150:153], v[202:203], off offset:384
	global_load_dwordx4 v[154:157], v[202:203], off offset:400
	global_load_dwordx4 v[158:161], v[202:203], off offset:416
	global_load_dwordx4 v[162:165], v[202:203], off offset:432
	s_waitcnt lgkmcnt(15)
	v_mfma_f32_32x32x16_f16 v[114:129], v[208:211], v[240:243], v[114:129]
	s_waitcnt lgkmcnt(15)
	v_mfma_f32_32x32x16_f16 v[98:113], v[174:177], v[240:243], v[98:113]
	s_waitcnt lgkmcnt(15)
	v_mfma_f32_32x32x16_f16 v[82:97], v[208:211], v[244:247], v[82:97]
	v_mfma_f32_32x32x16_f16 v[66:81], v[174:177], v[244:247], v[66:81]
	s_waitcnt lgkmcnt(15)
	v_mfma_f32_32x32x16_f16 v[50:65], v[208:211], v[248:251], v[50:65]
	v_mfma_f32_32x32x16_f16 v[34:49], v[174:177], v[248:251], v[34:49]
	s_waitcnt lgkmcnt(14)
	v_mfma_f32_32x32x16_f16 v[18:33], v[208:211], v[204:207], v[18:33]
	v_mfma_f32_32x32x16_f16 v[2:17], v[174:177], v[204:207], v[2:17]
	ds_read_b128 v[208:211], v214 offset:96
	ds_read_b128 v[240:243], v212 offset:96
	ds_read_b128 v[174:177], v214 offset:4704
	ds_read_b128 v[244:247], v212 offset:4704
	ds_read_b128 v[248:251], v212 offset:9312
	ds_read_b128 v[204:207], v212 offset:13920
	s_waitcnt lgkmcnt(14)
	v_mfma_f32_32x32x16_f16 v[114:129], v[232:235], v[216:219], v[114:129]
	s_waitcnt lgkmcnt(13)
	v_mfma_f32_32x32x16_f16 v[98:113], v[236:239], v[216:219], v[98:113]
	s_waitcnt lgkmcnt(12)
	v_mfma_f32_32x32x16_f16 v[82:97], v[232:235], v[220:223], v[82:97]
	v_mfma_f32_32x32x16_f16 v[66:81], v[236:239], v[220:223], v[66:81]
	s_waitcnt lgkmcnt(11)
	v_mfma_f32_32x32x16_f16 v[50:65], v[232:235], v[224:227], v[50:65]
	v_mfma_f32_32x32x16_f16 v[34:49], v[236:239], v[224:227], v[34:49]
	s_waitcnt lgkmcnt(10)
	v_mfma_f32_32x32x16_f16 v[18:33], v[232:235], v[228:231], v[18:33]
	v_mfma_f32_32x32x16_f16 v[2:17], v[236:239], v[228:231], v[2:17]
	s_waitcnt lgkmcnt(0)
	s_barrier
; DI f16v mfma32(h8v a, h8v b, f16v c) { return __builtin_amdgcn_mfma_f32_32x32x16_f16(a, b, c, 0, 0, 0); }
; template <bool GATHER>
; DI void gemm256_main(const h16* __restrict__ A, int lda, const int* __restrict__ idx, int m0,
;                      const h16* __restrict__ B, int ldb, int n0, int K, h16* lds, f16v (&acc)[4][2]) {
;     ...
;   for (int kt = 0; kt < nk; ++kt) {
;     const h16* As = lds + (kt & 1) * (512 * LDH);
;     const h16* Bs = As + 256 * LDH;
;     h16* Wn = lds + ((kt & 1) ^ 1) * (512 * LDH);
;     if (kt + 1 < nk) {
; #pragma unroll
;       for (int i = 0; i < 4; ++i) { *(u4v*)&Wn[lr * LDH + lc + 8 * i] = ra[i]; *(u4v*)&Wn[(256 + lr) * LDH + lc + 8 * i] = rb[i]; }
;     }
;     if (kt + 2 < nk) {
; #pragma unroll
;       for (int i = 0; i < 4; ++i) { ra[i] = *(const u4v*)(AP_ + 8 * i); rb[i] = *(const u4v*)(BP_ + 8 * i); }
;       ao += 64; bo += 64;
;     }
; #pragma unroll
;     for (int ks = 0; ks < 4; ++ks) {
;       h8v af[4], bf[2];
; #pragma unroll
;       for (int i = 0; i < 4; ++i) af[i] = *(const h8v*)&As[(wm * 128 + i * 32 + (lane & 31)) * LDH + ks * 16 + 8 * (lane >> 5)];
; #pragma unroll
;       for (int j = 0; j < 2; ++j) bf[j] = *(const h8v*)&Bs[(wn * 64 + j * 32 + (lane & 31)) * LDH + ks * 16 + 8 * (lane >> 5)];
; #pragma unroll
;       for (int i = 0; i < 4; ++i)
; #pragma unroll
;         for (int j = 0; j < 2; ++j) acc[i][j] = mfma32(bf[j], af[i], acc[i][j]);
;     }
;     __syncthreads();
	ds_read_b128 v[232:235], v213
	ds_read_b128 v[216:219], v215
	ds_read_b128 v[236:239], v213 offset:4608
	ds_read_b128 v[220:223], v215 offset:4608
	ds_read_b128 v[224:227], v215 offset:9216
	ds_read_b128 v[228:231], v215 offset:13824
	v_mfma_f32_32x32x16_f16 v[114:129], v[208:211], v[240:243], v[114:129]
	v_mfma_f32_32x32x16_f16 v[98:113], v[174:177], v[240:243], v[98:113]
	v_mfma_f32_32x32x16_f16 v[82:97], v[208:211], v[244:247], v[82:97]
	v_mfma_f32_32x32x16_f16 v[66:81], v[174:177], v[244:247], v[66:81]
	v_mfma_f32_32x32x16_f16 v[50:65], v[208:211], v[248:251], v[50:65]
	v_mfma_f32_32x32x16_f16 v[34:49], v[174:177], v[248:251], v[34:49]
	v_mfma_f32_32x32x16_f16 v[18:33], v[208:211], v[204:207], v[18:33]
	v_mfma_f32_32x32x16_f16 v[2:17], v[174:177], v[204:207], v[2:17]
	ds_read_b128 v[208:211], v213 offset:32
	ds_read_b128 v[240:243], v215 offset:32
	ds_read_b128 v[174:177], v213 offset:4640
	ds_read_b128 v[244:247], v215 offset:4640
	ds_read_b128 v[248:251], v215 offset:9248
	ds_read_b128 v[204:207], v215 offset:13856
	s_waitcnt vmcnt(4)
	ds_write_b128 v179, v[134:137]
	ds_write_b128 v179, v[138:141] offset:16
	ds_write_b128 v179, v[142:145] offset:32
	ds_write_b128 v179, v[146:149] offset:48
	global_load_dwordx4 v[134:137], v[130:131], off offset:512
	global_load_dwordx4 v[138:141], v[130:131], off offset:528
	global_load_dwordx4 v[142:145], v[130:131], off offset:544
	global_load_dwordx4 v[146:149], v[130:131], off offset:560
	s_waitcnt lgkmcnt(14)
	v_mfma_f32_32x32x16_f16 v[114:129], v[232:235], v[216:219], v[114:129]
	s_waitcnt lgkmcnt(13)
	v_mfma_f32_32x32x16_f16 v[98:113], v[236:239], v[216:219], v[98:113]
	s_waitcnt lgkmcnt(12)
	v_mfma_f32_32x32x16_f16 v[82:97], v[232:235], v[220:223], v[82:97]
	v_mfma_f32_32x32x16_f16 v[66:81], v[236:239], v[220:223], v[66:81]
	s_waitcnt lgkmcnt(11)
	v_mfma_f32_32x32x16_f16 v[50:65], v[232:235], v[224:227], v[50:65]
	v_mfma_f32_32x32x16_f16 v[34:49], v[236:239], v[224:227], v[34:49]
	s_waitcnt lgkmcnt(10)
	v_mfma_f32_32x32x16_f16 v[18:33], v[232:235], v[228:231], v[18:33]
	v_mfma_f32_32x32x16_f16 v[2:17], v[236:239], v[228:231], v[2:17]
	ds_read_b128 v[232:235], v213 offset:64
	ds_read_b128 v[216:219], v215 offset:64
	ds_read_b128 v[236:239], v213 offset:4672
	ds_read_b128 v[220:223], v215 offset:4672
	ds_read_b128 v[224:227], v215 offset:9280
	ds_read_b128 v[228:231], v215 offset:13888
	s_waitcnt vmcnt(4)
	ds_write_b128 v179, v[150:153] offset:36864
	ds_write_b128 v179, v[154:157] offset:36880
	ds_write_b128 v179, v[158:161] offset:36896
	ds_write_b128 v179, v[162:165] offset:36912
	global_load_dwordx4 v[150:153], v[202:203], off offset:512
	global_load_dwordx4 v[154:157], v[202:203], off offset:528
	global_load_dwordx4 v[158:161], v[202:203], off offset:544
	global_load_dwordx4 v[162:165], v[202:203], off offset:560
	s_waitcnt lgkmcnt(15)
	v_mfma_f32_32x32x16_f16 v[114:129], v[208:211], v[240:243], v[114:129]
	s_waitcnt lgkmcnt(15)
	v_mfma_f32_32x32x16_f16 v[98:113], v[174:177], v[240:243], v[98:113]
	s_waitcnt lgkmcnt(15)
	v_mfma_f32_32x32x16_f16 v[82:97], v[208:211], v[244:247], v[82:97]
	v_mfma_f32_32x32x16_f16 v[66:81], v[174:177], v[244:247], v[66:81]
	s_waitcnt lgkmcnt(15)
	v_mfma_f32_32x32x16_f16 v[50:65], v[208:211], v[248:251], v[50:65]
	v_mfma_f32_32x32x16_f16 v[34:49], v[174:177], v[248:251], v[34:49]
	s_waitcnt lgkmcnt(14)
	v_mfma_f32_32x32x16_f16 v[18:33], v[208:211], v[204:207], v[18:33]
	v_mfma_f32_32x32x16_f16 v[2:17], v[174:177], v[204:207], v[2:17]
	ds_read_b128 v[208:211], v213 offset:96
	ds_read_b128 v[240:243], v215 offset:96
	ds_read_b128 v[174:177], v213 offset:4704
	ds_read_b128 v[244:247], v215 offset:4704
	ds_read_b128 v[248:251], v215 offset:9312
	ds_read_b128 v[204:207], v215 offset:13920
	s_waitcnt lgkmcnt(14)
	v_mfma_f32_32x32x16_f16 v[114:129], v[232:235], v[216:219], v[114:129]
	s_waitcnt lgkmcnt(13)
	v_mfma_f32_32x32x16_f16 v[98:113], v[236:239], v[216:219], v[98:113]
	s_waitcnt lgkmcnt(12)
	v_mfma_f32_32x32x16_f16 v[82:97], v[232:235], v[220:223], v[82:97]
	v_mfma_f32_32x32x16_f16 v[66:81], v[236:239], v[220:223], v[66:81]
	s_waitcnt lgkmcnt(11)
	v_mfma_f32_32x32x16_f16 v[50:65], v[232:235], v[224:227], v[50:65]
	v_mfma_f32_32x32x16_f16 v[34:49], v[236:239], v[224:227], v[34:49]
	s_waitcnt lgkmcnt(10)
	v_mfma_f32_32x32x16_f16 v[18:33], v[232:235], v[228:231], v[18:33]
	v_mfma_f32_32x32x16_f16 v[2:17], v[236:239], v[228:231], v[2:17]
	s_waitcnt lgkmcnt(0)
	s_barrier
; DI f16v mfma32(h8v a, h8v b, f16v c) { return __builtin_amdgcn_mfma_f32_32x32x16_f16(a, b, c, 0, 0, 0); }
; template <bool GATHER>
; DI void gemm256_main(const h16* __restrict__ A, int lda, const int* __restrict__ idx, int m0,
;                      const h16* __restrict__ B, int ldb, int n0, int K, h16* lds, f16v (&acc)[4][2]) {
;     ...
;   for (int kt = 0; kt < nk; ++kt) {
;     const h16* As = lds + (kt & 1) * (512 * LDH);
;     const h16* Bs = As + 256 * LDH;
;     h16* Wn = lds + ((kt & 1) ^ 1) * (512 * LDH);
;     if (kt + 1 < nk) {
; #pragma unroll
;       for (int i = 0; i < 4; ++i) { *(u4v*)&Wn[lr * LDH + lc + 8 * i] = ra[i]; *(u4v*)&Wn[(256 + lr) * LDH + lc + 8 * i] = rb[i]; }
;     }
;     if (kt + 2 < nk) {
; #pragma unroll
;       for (int i = 0; i < 4; ++i) { ra[i] = *(const u4v*)(AP_ + 8 * i); rb[i] = *(const u4v*)(BP_ + 8 * i); }
;       ao += 64; bo += 64;
;     }
; #pragma unroll
;     for (int ks = 0; ks < 4; ++ks) {
;       h8v af[4], bf[2];
; #pragma unroll
;       for (int i = 0; i < 4; ++i) af[i] = *(const h8v*)&As[(wm * 128 + i * 32 + (lane & 31)) * LDH + ks * 16 + 8 * (lane >> 5)];
; #pragma unroll
;       for (int j = 0; j < 2; ++j) bf[j] = *(const h8v*)&Bs[(wn * 64 + j * 32 + (lane & 31)) * LDH + ks * 16 + 8 * (lane >> 5)];
; #pragma unroll
;       for (int i = 0; i < 4; ++i)
; #pragma unroll
;         for (int j = 0; j < 2; ++j) acc[i][j] = mfma32(bf[j], af[i], acc[i][j]);
;     }
;     __syncthreads();
	ds_read_b128 v[232:235], v214
	ds_read_b128 v[216:219], v212
	ds_read_b128 v[236:239], v214 offset:4608
	ds_read_b128 v[220:223], v212 offset:4608
	ds_read_b128 v[224:227], v212 offset:9216
	ds_read_b128 v[228:231], v212 offset:13824
	v_mfma_f32_32x32x16_f16 v[114:129], v[208:211], v[240:243], v[114:129]
	v_mfma_f32_32x32x16_f16 v[98:113], v[174:177], v[240:243], v[98:113]
	v_mfma_f32_32x32x16_f16 v[82:97], v[208:211], v[244:247], v[82:97]
	v_mfma_f32_32x32x16_f16 v[66:81], v[174:177], v[244:247], v[66:81]
	v_mfma_f32_32x32x16_f16 v[50:65], v[208:211], v[248:251], v[50:65]
	v_mfma_f32_32x32x16_f16 v[34:49], v[174:177], v[248:251], v[34:49]
	v_mfma_f32_32x32x16_f16 v[18:33], v[208:211], v[204:207], v[18:33]
	v_mfma_f32_32x32x16_f16 v[2:17], v[174:177], v[204:207], v[2:17]
	ds_read_b128 v[208:211], v214 offset:32
	ds_read_b128 v[240:243], v212 offset:32
	ds_read_b128 v[174:177], v214 offset:4640
	ds_read_b128 v[244:247], v212 offset:4640
	ds_read_b128 v[248:251], v212 offset:9248
	ds_read_b128 v[204:207], v212 offset:13856
	s_waitcnt vmcnt(4)
	ds_write_b128 v178, v[134:137]
	ds_write_b128 v178, v[138:141] offset:16
	ds_write_b128 v178, v[142:145] offset:32
	ds_write_b128 v178, v[146:149] offset:48
	global_load_dwordx4 v[134:137], v[130:131], off offset:640
	global_load_dwordx4 v[138:141], v[130:131], off offset:656
	global_load_dwordx4 v[142:145], v[130:131], off offset:672
	global_load_dwordx4 v[146:149], v[130:131], off offset:688
	s_waitcnt lgkmcnt(14)
	v_mfma_f32_32x32x16_f16 v[114:129], v[232:235], v[216:219], v[114:129]
	s_waitcnt lgkmcnt(13)
	v_mfma_f32_32x32x16_f16 v[98:113], v[236:239], v[216:219], v[98:113]
	s_waitcnt lgkmcnt(12)
	v_mfma_f32_32x32x16_f16 v[82:97], v[232:235], v[220:223], v[82:97]
	v_mfma_f32_32x32x16_f16 v[66:81], v[236:239], v[220:223], v[66:81]
	s_waitcnt lgkmcnt(11)
	v_mfma_f32_32x32x16_f16 v[50:65], v[232:235], v[224:227], v[50:65]
	v_mfma_f32_32x32x16_f16 v[34:49], v[236:239], v[224:227], v[34:49]
	s_waitcnt lgkmcnt(10)
	v_mfma_f32_32x32x16_f16 v[18:33], v[232:235], v[228:231], v[18:33]
	v_mfma_f32_32x32x16_f16 v[2:17], v[236:239], v[228:231], v[2:17]
	ds_read_b128 v[232:235], v214 offset:64
	ds_read_b128 v[216:219], v212 offset:64
	ds_read_b128 v[236:239], v214 offset:4672
	ds_read_b128 v[220:223], v212 offset:4672
	ds_read_b128 v[224:227], v212 offset:9280
	ds_read_b128 v[228:231], v212 offset:13888
	s_waitcnt vmcnt(4)
	ds_write_b128 v178, v[150:153] offset:36864
	ds_write_b128 v178, v[154:157] offset:36880
	ds_write_b128 v178, v[158:161] offset:36896
	ds_write_b128 v178, v[162:165] offset:36912
	global_load_dwordx4 v[150:153], v[202:203], off offset:640
	global_load_dwordx4 v[154:157], v[202:203], off offset:656
	global_load_dwordx4 v[158:161], v[202:203], off offset:672
	global_load_dwordx4 v[162:165], v[202:203], off offset:688
	s_waitcnt lgkmcnt(15)
	v_mfma_f32_32x32x16_f16 v[114:129], v[208:211], v[240:243], v[114:129]
	s_waitcnt lgkmcnt(15)
	v_mfma_f32_32x32x16_f16 v[98:113], v[174:177], v[240:243], v[98:113]
	s_waitcnt lgkmcnt(15)
	v_mfma_f32_32x32x16_f16 v[82:97], v[208:211], v[244:247], v[82:97]
	v_mfma_f32_32x32x16_f16 v[66:81], v[174:177], v[244:247], v[66:81]
	s_waitcnt lgkmcnt(15)
	v_mfma_f32_32x32x16_f16 v[50:65], v[208:211], v[248:251], v[50:65]
	v_mfma_f32_32x32x16_f16 v[34:49], v[174:177], v[248:251], v[34:49]
	s_waitcnt lgkmcnt(14)
	v_mfma_f32_32x32x16_f16 v[18:33], v[208:211], v[204:207], v[18:33]
	v_mfma_f32_32x32x16_f16 v[2:17], v[174:177], v[204:207], v[2:17]
	ds_read_b128 v[208:211], v214 offset:96
	ds_read_b128 v[240:243], v212 offset:96
	ds_read_b128 v[174:177], v214 offset:4704
	ds_read_b128 v[244:247], v212 offset:4704
	ds_read_b128 v[248:251], v212 offset:9312
	ds_read_b128 v[204:207], v212 offset:13920
	s_waitcnt lgkmcnt(14)
	v_mfma_f32_32x32x16_f16 v[114:129], v[232:235], v[216:219], v[114:129]
	s_waitcnt lgkmcnt(13)
	v_mfma_f32_32x32x16_f16 v[98:113], v[236:239], v[216:219], v[98:113]
	s_waitcnt lgkmcnt(12)
	v_mfma_f32_32x32x16_f16 v[82:97], v[232:235], v[220:223], v[82:97]
	v_mfma_f32_32x32x16_f16 v[66:81], v[236:239], v[220:223], v[66:81]
	s_waitcnt lgkmcnt(11)
	v_mfma_f32_32x32x16_f16 v[50:65], v[232:235], v[224:227], v[50:65]
	v_mfma_f32_32x32x16_f16 v[34:49], v[236:239], v[224:227], v[34:49]
	s_waitcnt lgkmcnt(10)
	v_mfma_f32_32x32x16_f16 v[18:33], v[232:235], v[228:231], v[18:33]
	v_mfma_f32_32x32x16_f16 v[2:17], v[236:239], v[228:231], v[2:17]
	s_waitcnt lgkmcnt(0)
	s_barrier
; DI f16v mfma32(h8v a, h8v b, f16v c) { return __builtin_amdgcn_mfma_f32_32x32x16_f16(a, b, c, 0, 0, 0); }
; template <bool GATHER>
; DI void gemm256_main(const h16* __restrict__ A, int lda, const int* __restrict__ idx, int m0,
;                      const h16* __restrict__ B, int ldb, int n0, int K, h16* lds, f16v (&acc)[4][2]) {
;     ...
;   for (int kt = 0; kt < nk; ++kt) {
;     const h16* As = lds + (kt & 1) * (512 * LDH);
;     const h16* Bs = As + 256 * LDH;
;     h16* Wn = lds + ((kt & 1) ^ 1) * (512 * LDH);
;     if (kt + 1 < nk) {
; #pragma unroll
;       for (int i = 0; i < 4; ++i) { *(u4v*)&Wn[lr * LDH + lc + 8 * i] = ra[i]; *(u4v*)&Wn[(256 + lr) * LDH + lc + 8 * i] = rb[i]; }
;     }
;     if (kt + 2 < nk) {
; #pragma unroll
;       for (int i = 0; i < 4; ++i) { ra[i] = *(const u4v*)(AP_ + 8 * i); rb[i] = *(const u4v*)(BP_ + 8 * i); }
;       ao += 64; bo += 64;
;     }
; #pragma unroll
;     for (int ks = 0; ks < 4; ++ks) {
;       h8v af[4], bf[2];
; #pragma unroll
;       for (int i = 0; i < 4; ++i) af[i] = *(const h8v*)&As[(wm * 128 + i * 32 + (lane & 31)) * LDH + ks * 16 + 8 * (lane >> 5)];
; #pragma unroll
;       for (int j = 0; j < 2; ++j) bf[j] = *(const h8v*)&Bs[(wn * 64 + j * 32 + (lane & 31)) * LDH + ks * 16 + 8 * (lane >> 5)];
; #pragma unroll
;       for (int i = 0; i < 4; ++i)
; #pragma unroll
;         for (int j = 0; j < 2; ++j) acc[i][j] = mfma32(bf[j], af[i], acc[i][j]);
;     }
;     __syncthreads();
	ds_read_b128 v[232:235], v213
	ds_read_b128 v[216:219], v215
	ds_read_b128 v[236:239], v213 offset:4608
	ds_read_b128 v[220:223], v215 offset:4608
	ds_read_b128 v[224:227], v215 offset:9216
	ds_read_b128 v[228:231], v215 offset:13824
	v_mfma_f32_32x32x16_f16 v[114:129], v[208:211], v[240:243], v[114:129]
	v_mfma_f32_32x32x16_f16 v[98:113], v[174:177], v[240:243], v[98:113]
	v_mfma_f32_32x32x16_f16 v[82:97], v[208:211], v[244:247], v[82:97]
	v_mfma_f32_32x32x16_f16 v[66:81], v[174:177], v[244:247], v[66:81]
	v_mfma_f32_32x32x16_f16 v[50:65], v[208:211], v[248:251], v[50:65]
	v_mfma_f32_32x32x16_f16 v[34:49], v[174:177], v[248:251], v[34:49]
	v_mfma_f32_32x32x16_f16 v[18:33], v[208:211], v[204:207], v[18:33]
	v_mfma_f32_32x32x16_f16 v[2:17], v[174:177], v[204:207], v[2:17]
	ds_read_b128 v[208:211], v213 offset:32
	ds_read_b128 v[240:243], v215 offset:32
	ds_read_b128 v[174:177], v213 offset:4640
	ds_read_b128 v[244:247], v215 offset:4640
	ds_read_b128 v[248:251], v215 offset:9248
	ds_read_b128 v[204:207], v215 offset:13856
	s_waitcnt vmcnt(4)
	ds_write_b128 v179, v[134:137]
	ds_write_b128 v179, v[138:141] offset:16
	ds_write_b128 v179, v[142:145] offset:32
	ds_write_b128 v179, v[146:149] offset:48
	global_load_dwordx4 v[134:137], v[130:131], off offset:768
	global_load_dwordx4 v[138:141], v[130:131], off offset:784
	global_load_dwordx4 v[142:145], v[130:131], off offset:800
	global_load_dwordx4 v[146:149], v[130:131], off offset:816
	s_waitcnt lgkmcnt(14)
	v_mfma_f32_32x32x16_f16 v[114:129], v[232:235], v[216:219], v[114:129]
	s_waitcnt lgkmcnt(13)
	v_mfma_f32_32x32x16_f16 v[98:113], v[236:239], v[216:219], v[98:113]
	s_waitcnt lgkmcnt(12)
	v_mfma_f32_32x32x16_f16 v[82:97], v[232:235], v[220:223], v[82:97]
	v_mfma_f32_32x32x16_f16 v[66:81], v[236:239], v[220:223], v[66:81]
	s_waitcnt lgkmcnt(11)
	v_mfma_f32_32x32x16_f16 v[50:65], v[232:235], v[224:227], v[50:65]
	v_mfma_f32_32x32x16_f16 v[34:49], v[236:239], v[224:227], v[34:49]
	s_waitcnt lgkmcnt(10)
	v_mfma_f32_32x32x16_f16 v[18:33], v[232:235], v[228:231], v[18:33]
	v_mfma_f32_32x32x16_f16 v[2:17], v[236:239], v[228:231], v[2:17]
	ds_read_b128 v[232:235], v213 offset:64
	ds_read_b128 v[216:219], v215 offset:64
	ds_read_b128 v[236:239], v213 offset:4672
	ds_read_b128 v[220:223], v215 offset:4672
	ds_read_b128 v[224:227], v215 offset:9280
	ds_read_b128 v[228:231], v215 offset:13888
	s_waitcnt vmcnt(4)
	ds_write_b128 v179, v[150:153] offset:36864
	ds_write_b128 v179, v[154:157] offset:36880
	ds_write_b128 v179, v[158:161] offset:36896
	ds_write_b128 v179, v[162:165] offset:36912
	global_load_dwordx4 v[150:153], v[202:203], off offset:768
	global_load_dwordx4 v[154:157], v[202:203], off offset:784
	global_load_dwordx4 v[158:161], v[202:203], off offset:800
	global_load_dwordx4 v[162:165], v[202:203], off offset:816
	s_waitcnt lgkmcnt(15)
	v_mfma_f32_32x32x16_f16 v[114:129], v[208:211], v[240:243], v[114:129]
	s_waitcnt lgkmcnt(15)
	v_mfma_f32_32x32x16_f16 v[98:113], v[174:177], v[240:243], v[98:113]
	s_waitcnt lgkmcnt(15)
	v_mfma_f32_32x32x16_f16 v[82:97], v[208:211], v[244:247], v[82:97]
	v_mfma_f32_32x32x16_f16 v[66:81], v[174:177], v[244:247], v[66:81]
	s_waitcnt lgkmcnt(15)
	v_mfma_f32_32x32x16_f16 v[50:65], v[208:211], v[248:251], v[50:65]
	v_mfma_f32_32x32x16_f16 v[34:49], v[174:177], v[248:251], v[34:49]
	s_waitcnt lgkmcnt(14)
	v_mfma_f32_32x32x16_f16 v[18:33], v[208:211], v[204:207], v[18:33]
	v_mfma_f32_32x32x16_f16 v[2:17], v[174:177], v[204:207], v[2:17]
	ds_read_b128 v[208:211], v213 offset:96
	ds_read_b128 v[240:243], v215 offset:96
	ds_read_b128 v[174:177], v213 offset:4704
	ds_read_b128 v[244:247], v215 offset:4704
	ds_read_b128 v[248:251], v215 offset:9312
	ds_read_b128 v[204:207], v215 offset:13920
	s_waitcnt lgkmcnt(14)
	v_mfma_f32_32x32x16_f16 v[114:129], v[232:235], v[216:219], v[114:129]
	s_waitcnt lgkmcnt(13)
	v_mfma_f32_32x32x16_f16 v[98:113], v[236:239], v[216:219], v[98:113]
	s_waitcnt lgkmcnt(12)
	v_mfma_f32_32x32x16_f16 v[82:97], v[232:235], v[220:223], v[82:97]
	v_mfma_f32_32x32x16_f16 v[66:81], v[236:239], v[220:223], v[66:81]
	s_waitcnt lgkmcnt(11)
	v_mfma_f32_32x32x16_f16 v[50:65], v[232:235], v[224:227], v[50:65]
	v_mfma_f32_32x32x16_f16 v[34:49], v[236:239], v[224:227], v[34:49]
	s_waitcnt lgkmcnt(10)
	v_mfma_f32_32x32x16_f16 v[18:33], v[232:235], v[228:231], v[18:33]
	v_mfma_f32_32x32x16_f16 v[2:17], v[236:239], v[228:231], v[2:17]
	s_waitcnt lgkmcnt(0)
	s_barrier
; DI f16v mfma32(h8v a, h8v b, f16v c) { return __builtin_amdgcn_mfma_f32_32x32x16_f16(a, b, c, 0, 0, 0); }
; template <bool GATHER>
; DI void gemm256_main(const h16* __restrict__ A, int lda, const int* __restrict__ idx, int m0,
;                      const h16* __restrict__ B, int ldb, int n0, int K, h16* lds, f16v (&acc)[4][2]) {
;     ...
;   for (int kt = 0; kt < nk; ++kt) {
;     const h16* As = lds + (kt & 1) * (512 * LDH);
;     const h16* Bs = As + 256 * LDH;
;     h16* Wn = lds + ((kt & 1) ^ 1) * (512 * LDH);
;     if (kt + 1 < nk) {
; #pragma unroll
;       for (int i = 0; i < 4; ++i) { *(u4v*)&Wn[lr * LDH + lc + 8 * i] = ra[i]; *(u4v*)&Wn[(256 + lr) * LDH + lc + 8 * i] = rb[i]; }
;     }
;     if (kt + 2 < nk) {
; #pragma unroll
;       for (int i = 0; i < 4; ++i) { ra[i] = *(const u4v*)(AP_ + 8 * i); rb[i] = *(const u4v*)(BP_ + 8 * i); }
;       ao += 64; bo += 64;
;     }
; #pragma unroll
;     for (int ks = 0; ks < 4; ++ks) {
;       h8v af[4], bf[2];
; #pragma unroll
;       for (int i = 0; i < 4; ++i) af[i] = *(const h8v*)&As[(wm * 128 + i * 32 + (lane & 31)) * LDH + ks * 16 + 8 * (lane >> 5)];
; #pragma unroll
;       for (int j = 0; j < 2; ++j) bf[j] = *(const h8v*)&Bs[(wn * 64 + j * 32 + (lane & 31)) * LDH + ks * 16 + 8 * (lane >> 5)];
; #pragma unroll
;       for (int i = 0; i < 4; ++i)
; #pragma unroll
;         for (int j = 0; j < 2; ++j) acc[i][j] = mfma32(bf[j], af[i], acc[i][j]);
;     }
;     __syncthreads();
	ds_read_b128 v[232:235], v214
	ds_read_b128 v[216:219], v212
	ds_read_b128 v[236:239], v214 offset:4608
	ds_read_b128 v[220:223], v212 offset:4608
	ds_read_b128 v[224:227], v212 offset:9216
	ds_read_b128 v[228:231], v212 offset:13824
	v_mfma_f32_32x32x16_f16 v[114:129], v[208:211], v[240:243], v[114:129]
	v_mfma_f32_32x32x16_f16 v[98:113], v[174:177], v[240:243], v[98:113]
	v_mfma_f32_32x32x16_f16 v[82:97], v[208:211], v[244:247], v[82:97]
	v_mfma_f32_32x32x16_f16 v[66:81], v[174:177], v[244:247], v[66:81]
	v_mfma_f32_32x32x16_f16 v[50:65], v[208:211], v[248:251], v[50:65]
	v_mfma_f32_32x32x16_f16 v[34:49], v[174:177], v[248:251], v[34:49]
	v_mfma_f32_32x32x16_f16 v[18:33], v[208:211], v[204:207], v[18:33]
	v_mfma_f32_32x32x16_f16 v[2:17], v[174:177], v[204:207], v[2:17]
	ds_read_b128 v[208:211], v214 offset:32
	ds_read_b128 v[240:243], v212 offset:32
	ds_read_b128 v[174:177], v214 offset:4640
	ds_read_b128 v[244:247], v212 offset:4640
	ds_read_b128 v[248:251], v212 offset:9248
	ds_read_b128 v[204:207], v212 offset:13856
	s_waitcnt vmcnt(4)
	ds_write_b128 v178, v[134:137]
	ds_write_b128 v178, v[138:141] offset:16
	ds_write_b128 v178, v[142:145] offset:32
	ds_write_b128 v178, v[146:149] offset:48
	global_load_dwordx4 v[134:137], v[130:131], off offset:896
	global_load_dwordx4 v[138:141], v[130:131], off offset:912
	global_load_dwordx4 v[142:145], v[130:131], off offset:928
	global_load_dwordx4 v[146:149], v[130:131], off offset:944
	s_waitcnt lgkmcnt(14)
	v_mfma_f32_32x32x16_f16 v[114:129], v[232:235], v[216:219], v[114:129]
	s_waitcnt lgkmcnt(13)
	v_mfma_f32_32x32x16_f16 v[98:113], v[236:239], v[216:219], v[98:113]
	s_waitcnt lgkmcnt(12)
	v_mfma_f32_32x32x16_f16 v[82:97], v[232:235], v[220:223], v[82:97]
	v_mfma_f32_32x32x16_f16 v[66:81], v[236:239], v[220:223], v[66:81]
	s_waitcnt lgkmcnt(11)
	v_mfma_f32_32x32x16_f16 v[50:65], v[232:235], v[224:227], v[50:65]
	v_mfma_f32_32x32x16_f16 v[34:49], v[236:239], v[224:227], v[34:49]
	s_waitcnt lgkmcnt(10)
	v_mfma_f32_32x32x16_f16 v[18:33], v[232:235], v[228:231], v[18:33]
	v_mfma_f32_32x32x16_f16 v[2:17], v[236:239], v[228:231], v[2:17]
	ds_read_b128 v[232:235], v214 offset:64
	ds_read_b128 v[216:219], v212 offset:64
	ds_read_b128 v[236:239], v214 offset:4672
	ds_read_b128 v[220:223], v212 offset:4672
	ds_read_b128 v[224:227], v212 offset:9280
	ds_read_b128 v[228:231], v212 offset:13888
	s_waitcnt vmcnt(4)
	ds_write_b128 v178, v[150:153] offset:36864
	ds_write_b128 v178, v[154:157] offset:36880
	ds_write_b128 v178, v[158:161] offset:36896
	ds_write_b128 v178, v[162:165] offset:36912
	global_load_dwordx4 v[150:153], v[202:203], off offset:896
	global_load_dwordx4 v[154:157], v[202:203], off offset:912
	global_load_dwordx4 v[158:161], v[202:203], off offset:928
	global_load_dwordx4 v[162:165], v[202:203], off offset:944
	s_waitcnt lgkmcnt(15)
	v_mfma_f32_32x32x16_f16 v[114:129], v[208:211], v[240:243], v[114:129]
	s_waitcnt lgkmcnt(15)
	v_mfma_f32_32x32x16_f16 v[98:113], v[174:177], v[240:243], v[98:113]
	s_waitcnt lgkmcnt(15)
	v_mfma_f32_32x32x16_f16 v[82:97], v[208:211], v[244:247], v[82:97]
	v_mfma_f32_32x32x16_f16 v[66:81], v[174:177], v[244:247], v[66:81]
	s_waitcnt lgkmcnt(15)
	v_mfma_f32_32x32x16_f16 v[50:65], v[208:211], v[248:251], v[50:65]
	v_mfma_f32_32x32x16_f16 v[34:49], v[174:177], v[248:251], v[34:49]
	s_waitcnt lgkmcnt(14)
	v_mfma_f32_32x32x16_f16 v[18:33], v[208:211], v[204:207], v[18:33]
	v_mfma_f32_32x32x16_f16 v[2:17], v[174:177], v[204:207], v[2:17]
	ds_read_b128 v[208:211], v214 offset:96
	ds_read_b128 v[240:243], v212 offset:96
	ds_read_b128 v[174:177], v214 offset:4704
	ds_read_b128 v[244:247], v212 offset:4704
	ds_read_b128 v[248:251], v212 offset:9312
	ds_read_b128 v[204:207], v212 offset:13920
	s_waitcnt lgkmcnt(14)
	v_mfma_f32_32x32x16_f16 v[114:129], v[232:235], v[216:219], v[114:129]
	s_waitcnt lgkmcnt(13)
	v_mfma_f32_32x32x16_f16 v[98:113], v[236:239], v[216:219], v[98:113]
	s_waitcnt lgkmcnt(12)
	v_mfma_f32_32x32x16_f16 v[82:97], v[232:235], v[220:223], v[82:97]
	v_mfma_f32_32x32x16_f16 v[66:81], v[236:239], v[220:223], v[66:81]
	s_waitcnt lgkmcnt(11)
	v_mfma_f32_32x32x16_f16 v[50:65], v[232:235], v[224:227], v[50:65]
	v_mfma_f32_32x32x16_f16 v[34:49], v[236:239], v[224:227], v[34:49]
	s_waitcnt lgkmcnt(10)
	v_mfma_f32_32x32x16_f16 v[18:33], v[232:235], v[228:231], v[18:33]
	v_mfma_f32_32x32x16_f16 v[2:17], v[236:239], v[228:231], v[2:17]
	s_waitcnt lgkmcnt(0)
	s_barrier
; DI f16v mfma32(h8v a, h8v b, f16v c) { return __builtin_amdgcn_mfma_f32_32x32x16_f16(a, b, c, 0, 0, 0); }
; template <bool GATHER>
; DI void gemm256_main(const h16* __restrict__ A, int lda, const int* __restrict__ idx, int m0,
;                      const h16* __restrict__ B, int ldb, int n0, int K, h16* lds, f16v (&acc)[4][2]) {
;     ...
;   for (int kt = 0; kt < nk; ++kt) {
;     const h16* As = lds + (kt & 1) * (512 * LDH);
;     const h16* Bs = As + 256 * LDH;
;     h16* Wn = lds + ((kt & 1) ^ 1) * (512 * LDH);
;     if (kt + 1 < nk) {
; #pragma unroll
;       for (int i = 0; i < 4; ++i) { *(u4v*)&Wn[lr * LDH + lc + 8 * i] = ra[i]; *(u4v*)&Wn[(256 + lr) * LDH + lc + 8 * i] = rb[i]; }
;     }
;     if (kt + 2 < nk) {
; #pragma unroll
;       for (int i = 0; i < 4; ++i) { ra[i] = *(const u4v*)(AP_ + 8 * i); rb[i] = *(const u4v*)(BP_ + 8 * i); }
;       ao += 64; bo += 64;
;     }
; #pragma unroll
;     for (int ks = 0; ks < 4; ++ks) {
;       h8v af[4], bf[2];
; #pragma unroll
;       for (int i = 0; i < 4; ++i) af[i] = *(const h8v*)&As[(wm * 128 + i * 32 + (lane & 31)) * LDH + ks * 16 + 8 * (lane >> 5)];
; #pragma unroll
;       for (int j = 0; j < 2; ++j) bf[j] = *(const h8v*)&Bs[(wn * 64 + j * 32 + (lane & 31)) * LDH + ks * 16 + 8 * (lane >> 5)];
; #pragma unroll
;       for (int i = 0; i < 4; ++i)
; #pragma unroll
;         for (int j = 0; j < 2; ++j) acc[i][j] = mfma32(bf[j], af[i], acc[i][j]);
;     }
;     __syncthreads();
;   }
	ds_read_b128 v[232:235], v213
	ds_read_b128 v[216:219], v215
	ds_read_b128 v[236:239], v213 offset:4608
	ds_read_b128 v[220:223], v215 offset:4608
	ds_read_b128 v[224:227], v215 offset:9216
	ds_read_b128 v[228:231], v215 offset:13824
	v_mfma_f32_32x32x16_f16 v[114:129], v[208:211], v[240:243], v[114:129]
	v_mfma_f32_32x32x16_f16 v[98:113], v[174:177], v[240:243], v[98:113]
	v_mfma_f32_32x32x16_f16 v[82:97], v[208:211], v[244:247], v[82:97]
	v_mfma_f32_32x32x16_f16 v[66:81], v[174:177], v[244:247], v[66:81]
	v_mfma_f32_32x32x16_f16 v[50:65], v[208:211], v[248:251], v[50:65]
	v_mfma_f32_32x32x16_f16 v[34:49], v[174:177], v[248:251], v[34:49]
	v_mfma_f32_32x32x16_f16 v[18:33], v[208:211], v[204:207], v[18:33]
	v_mfma_f32_32x32x16_f16 v[2:17], v[174:177], v[204:207], v[2:17]
	ds_read_b128 v[208:211], v213 offset:32
	ds_read_b128 v[240:243], v215 offset:32
	ds_read_b128 v[174:177], v213 offset:4640
	ds_read_b128 v[244:247], v215 offset:4640
	ds_read_b128 v[248:251], v215 offset:9248
	ds_read_b128 v[204:207], v215 offset:13856
	s_waitcnt vmcnt(4)
	ds_write_b128 v179, v[134:137]
	ds_write_b128 v179, v[138:141] offset:16
	ds_write_b128 v179, v[142:145] offset:32
	ds_write_b128 v179, v[146:149] offset:48
	global_load_dwordx4 v[134:137], v[130:131], off offset:1024
	global_load_dwordx4 v[138:141], v[130:131], off offset:1040
	global_load_dwordx4 v[142:145], v[130:131], off offset:1056
	global_load_dwordx4 v[146:149], v[130:131], off offset:1072
	s_waitcnt lgkmcnt(14)
	v_mfma_f32_32x32x16_f16 v[114:129], v[232:235], v[216:219], v[114:129]
	s_waitcnt lgkmcnt(13)
	v_mfma_f32_32x32x16_f16 v[98:113], v[236:239], v[216:219], v[98:113]
	s_waitcnt lgkmcnt(12)
	v_mfma_f32_32x32x16_f16 v[82:97], v[232:235], v[220:223], v[82:97]
	v_mfma_f32_32x32x16_f16 v[66:81], v[236:239], v[220:223], v[66:81]
	s_waitcnt lgkmcnt(11)
	v_mfma_f32_32x32x16_f16 v[50:65], v[232:235], v[224:227], v[50:65]
	v_mfma_f32_32x32x16_f16 v[34:49], v[236:239], v[224:227], v[34:49]
	s_waitcnt lgkmcnt(10)
	v_mfma_f32_32x32x16_f16 v[18:33], v[232:235], v[228:231], v[18:33]
	v_mfma_f32_32x32x16_f16 v[2:17], v[236:239], v[228:231], v[2:17]
	ds_read_b128 v[232:235], v213 offset:64
	ds_read_b128 v[216:219], v215 offset:64
	ds_read_b128 v[236:239], v213 offset:4672
	ds_read_b128 v[220:223], v215 offset:4672
	ds_read_b128 v[224:227], v215 offset:9280
	ds_read_b128 v[228:231], v215 offset:13888
	s_waitcnt vmcnt(4)
	ds_write_b128 v179, v[150:153] offset:36864
	ds_write_b128 v179, v[154:157] offset:36880
	ds_write_b128 v179, v[158:161] offset:36896
	ds_write_b128 v179, v[162:165] offset:36912
	global_load_dwordx4 v[150:153], v[202:203], off offset:1024
	global_load_dwordx4 v[154:157], v[202:203], off offset:1040
	global_load_dwordx4 v[158:161], v[202:203], off offset:1056
	global_load_dwordx4 v[162:165], v[202:203], off offset:1072
	s_waitcnt lgkmcnt(15)
	v_mfma_f32_32x32x16_f16 v[114:129], v[208:211], v[240:243], v[114:129]
	s_waitcnt lgkmcnt(15)
	v_mfma_f32_32x32x16_f16 v[98:113], v[174:177], v[240:243], v[98:113]
	s_waitcnt lgkmcnt(15)
	v_mfma_f32_32x32x16_f16 v[82:97], v[208:211], v[244:247], v[82:97]
	v_mfma_f32_32x32x16_f16 v[66:81], v[174:177], v[244:247], v[66:81]
	s_waitcnt lgkmcnt(15)
	v_mfma_f32_32x32x16_f16 v[50:65], v[208:211], v[248:251], v[50:65]
	v_mfma_f32_32x32x16_f16 v[34:49], v[174:177], v[248:251], v[34:49]
	s_waitcnt lgkmcnt(14)
	v_mfma_f32_32x32x16_f16 v[18:33], v[208:211], v[204:207], v[18:33]
	v_mfma_f32_32x32x16_f16 v[2:17], v[174:177], v[204:207], v[2:17]
	ds_read_b128 v[208:211], v213 offset:96
	ds_read_b128 v[240:243], v215 offset:96
	ds_read_b128 v[174:177], v213 offset:4704
	ds_read_b128 v[244:247], v215 offset:4704
	ds_read_b128 v[248:251], v215 offset:9312
	ds_read_b128 v[204:207], v215 offset:13920
	s_waitcnt lgkmcnt(14)
	v_mfma_f32_32x32x16_f16 v[114:129], v[232:235], v[216:219], v[114:129]
	s_waitcnt lgkmcnt(13)
	v_mfma_f32_32x32x16_f16 v[98:113], v[236:239], v[216:219], v[98:113]
	s_waitcnt lgkmcnt(12)
	v_mfma_f32_32x32x16_f16 v[82:97], v[232:235], v[220:223], v[82:97]
	v_mfma_f32_32x32x16_f16 v[66:81], v[236:239], v[220:223], v[66:81]
	s_waitcnt lgkmcnt(11)
	v_mfma_f32_32x32x16_f16 v[50:65], v[232:235], v[224:227], v[50:65]
	v_mfma_f32_32x32x16_f16 v[34:49], v[236:239], v[224:227], v[34:49]
	s_waitcnt lgkmcnt(10)
	v_mfma_f32_32x32x16_f16 v[18:33], v[232:235], v[228:231], v[18:33]
	v_mfma_f32_32x32x16_f16 v[2:17], v[236:239], v[228:231], v[2:17]
	s_waitcnt lgkmcnt(0)
	s_barrier
; DI f16v mfma32(h8v a, h8v b, f16v c) { return __builtin_amdgcn_mfma_f32_32x32x16_f16(a, b, c, 0, 0, 0); }
; template <bool GATHER>
; DI void gemm256_main(const h16* __restrict__ A, int lda, const int* __restrict__ idx, int m0,
;                      const h16* __restrict__ B, int ldb, int n0, int K, h16* lds, f16v (&acc)[4][2]) {
;     ...
;   for (int kt = 0; kt < nk; ++kt) {
;     const h16* As = lds + (kt & 1) * (512 * LDH);
;     const h16* Bs = As + 256 * LDH;
;     h16* Wn = lds + ((kt & 1) ^ 1) * (512 * LDH);
;     if (kt + 1 < nk) {
; #pragma unroll
;       for (int i = 0; i < 4; ++i) { *(u4v*)&Wn[lr * LDH + lc + 8 * i] = ra[i]; *(u4v*)&Wn[(256 + lr) * LDH + lc + 8 * i] = rb[i]; }
;     }
;     if (kt + 2 < nk) {
; #pragma unroll
;       for (int i = 0; i < 4; ++i) { ra[i] = *(const u4v*)(AP_ + 8 * i); rb[i] = *(const u4v*)(BP_ + 8 * i); }
;       ao += 64; bo += 64;
;     }
; #pragma unroll
;     for (int ks = 0; ks < 4; ++ks) {
;       h8v af[4], bf[2];
; #pragma unroll
;       for (int i = 0; i < 4; ++i) af[i] = *(const h8v*)&As[(wm * 128 + i * 32 + (lane & 31)) * LDH + ks * 16 + 8 * (lane >> 5)];
; #pragma unroll
;       for (int j = 0; j < 2; ++j) bf[j] = *(const h8v*)&Bs[(wn * 64 + j * 32 + (lane & 31)) * LDH + ks * 16 + 8 * (lane >> 5)];
; #pragma unroll
;       for (int i = 0; i < 4; ++i)
; #pragma unroll
;         for (int j = 0; j < 2; ++j) acc[i][j] = mfma32(bf[j], af[i], acc[i][j]);
;     }
;     __syncthreads();
;   }
	ds_read_b128 v[232:235], v214
	ds_read_b128 v[216:219], v212
	ds_read_b128 v[236:239], v214 offset:4608
	ds_read_b128 v[220:223], v212 offset:4608
	ds_read_b128 v[224:227], v212 offset:9216
	ds_read_b128 v[228:231], v212 offset:13824
	v_mfma_f32_32x32x16_f16 v[114:129], v[208:211], v[240:243], v[114:129]
	v_mfma_f32_32x32x16_f16 v[98:113], v[174:177], v[240:243], v[98:113]
	v_mfma_f32_32x32x16_f16 v[82:97], v[208:211], v[244:247], v[82:97]
	v_mfma_f32_32x32x16_f16 v[66:81], v[174:177], v[244:247], v[66:81]
	v_mfma_f32_32x32x16_f16 v[50:65], v[208:211], v[248:251], v[50:65]
	v_mfma_f32_32x32x16_f16 v[34:49], v[174:177], v[248:251], v[34:49]
	v_mfma_f32_32x32x16_f16 v[18:33], v[208:211], v[204:207], v[18:33]
	v_mfma_f32_32x32x16_f16 v[2:17], v[174:177], v[204:207], v[2:17]
	ds_read_b128 v[208:211], v214 offset:32
	ds_read_b128 v[240:243], v212 offset:32
	ds_read_b128 v[174:177], v214 offset:4640
	ds_read_b128 v[244:247], v212 offset:4640
	ds_read_b128 v[248:251], v212 offset:9248
	ds_read_b128 v[204:207], v212 offset:13856
	s_waitcnt vmcnt(4)
	ds_write_b128 v178, v[134:137]
	ds_write_b128 v178, v[138:141] offset:16
	ds_write_b128 v178, v[142:145] offset:32
	ds_write_b128 v178, v[146:149] offset:48
	global_load_dwordx4 v[134:137], v[130:131], off offset:1152
	global_load_dwordx4 v[138:141], v[130:131], off offset:1168
	global_load_dwordx4 v[142:145], v[130:131], off offset:1184
	global_load_dwordx4 v[146:149], v[130:131], off offset:1200
	s_waitcnt lgkmcnt(14)
	v_mfma_f32_32x32x16_f16 v[114:129], v[232:235], v[216:219], v[114:129]
	s_waitcnt lgkmcnt(13)
	v_mfma_f32_32x32x16_f16 v[98:113], v[236:239], v[216:219], v[98:113]
	s_waitcnt lgkmcnt(12)
	v_mfma_f32_32x32x16_f16 v[82:97], v[232:235], v[220:223], v[82:97]
	v_mfma_f32_32x32x16_f16 v[66:81], v[236:239], v[220:223], v[66:81]
	s_waitcnt lgkmcnt(11)
	v_mfma_f32_32x32x16_f16 v[50:65], v[232:235], v[224:227], v[50:65]
	v_mfma_f32_32x32x16_f16 v[34:49], v[236:239], v[224:227], v[34:49]
	s_waitcnt lgkmcnt(10)
	v_mfma_f32_32x32x16_f16 v[18:33], v[232:235], v[228:231], v[18:33]
	v_mfma_f32_32x32x16_f16 v[2:17], v[236:239], v[228:231], v[2:17]
	ds_read_b128 v[232:235], v214 offset:64
	ds_read_b128 v[216:219], v212 offset:64
	ds_read_b128 v[236:239], v214 offset:4672
	ds_read_b128 v[220:223], v212 offset:4672
	ds_read_b128 v[224:227], v212 offset:9280
	ds_read_b128 v[228:231], v212 offset:13888
	s_waitcnt vmcnt(4)
	ds_write_b128 v178, v[150:153] offset:36864
	ds_write_b128 v178, v[154:157] offset:36880
	ds_write_b128 v178, v[158:161] offset:36896
	ds_write_b128 v178, v[162:165] offset:36912
	global_load_dwordx4 v[150:153], v[202:203], off offset:1152
	global_load_dwordx4 v[154:157], v[202:203], off offset:1168
	global_load_dwordx4 v[158:161], v[202:203], off offset:1184
	global_load_dwordx4 v[162:165], v[202:203], off offset:1200
	s_waitcnt lgkmcnt(15)
	v_mfma_f32_32x32x16_f16 v[114:129], v[208:211], v[240:243], v[114:129]
	s_waitcnt lgkmcnt(15)
	v_mfma_f32_32x32x16_f16 v[98:113], v[174:177], v[240:243], v[98:113]
	s_waitcnt lgkmcnt(15)
	v_mfma_f32_32x32x16_f16 v[82:97], v[208:211], v[244:247], v[82:97]
	v_mfma_f32_32x32x16_f16 v[66:81], v[174:177], v[244:247], v[66:81]
	s_waitcnt lgkmcnt(15)
	v_mfma_f32_32x32x16_f16 v[50:65], v[208:211], v[248:251], v[50:65]
	v_mfma_f32_32x32x16_f16 v[34:49], v[174:177], v[248:251], v[34:49]
	s_waitcnt lgkmcnt(14)
	v_mfma_f32_32x32x16_f16 v[18:33], v[208:211], v[204:207], v[18:33]
	v_mfma_f32_32x32x16_f16 v[2:17], v[174:177], v[204:207], v[2:17]
	ds_read_b128 v[208:211], v214 offset:96
	ds_read_b128 v[240:243], v212 offset:96
	ds_read_b128 v[174:177], v214 offset:4704
	ds_read_b128 v[244:247], v212 offset:4704
	ds_read_b128 v[248:251], v212 offset:9312
	ds_read_b128 v[204:207], v212 offset:13920
	s_waitcnt lgkmcnt(14)
	v_mfma_f32_32x32x16_f16 v[114:129], v[232:235], v[216:219], v[114:129]
	s_waitcnt lgkmcnt(13)
	v_mfma_f32_32x32x16_f16 v[98:113], v[236:239], v[216:219], v[98:113]
	s_waitcnt lgkmcnt(12)
	v_mfma_f32_32x32x16_f16 v[82:97], v[232:235], v[220:223], v[82:97]
	v_mfma_f32_32x32x16_f16 v[66:81], v[236:239], v[220:223], v[66:81]
	s_waitcnt lgkmcnt(11)
	v_mfma_f32_32x32x16_f16 v[50:65], v[232:235], v[224:227], v[50:65]
	v_mfma_f32_32x32x16_f16 v[34:49], v[236:239], v[224:227], v[34:49]
	s_waitcnt lgkmcnt(10)
	v_mfma_f32_32x32x16_f16 v[18:33], v[232:235], v[228:231], v[18:33]
	v_mfma_f32_32x32x16_f16 v[2:17], v[236:239], v[228:231], v[2:17]
	s_waitcnt lgkmcnt(0)
	s_barrier
; DI f16v mfma32(h8v a, h8v b, f16v c) { return __builtin_amdgcn_mfma_f32_32x32x16_f16(a, b, c, 0, 0, 0); }
; template <bool GATHER>
; DI void gemm256_main(const h16* __restrict__ A, int lda, const int* __restrict__ idx, int m0,
;                      const h16* __restrict__ B, int ldb, int n0, int K, h16* lds, f16v (&acc)[4][2]) {
;     ...
;   for (int kt = 0; kt < nk; ++kt) {
;     const h16* As = lds + (kt & 1) * (512 * LDH);
;     const h16* Bs = As + 256 * LDH;
;     h16* Wn = lds + ((kt & 1) ^ 1) * (512 * LDH);
;     if (kt + 1 < nk) {
; #pragma unroll
;       for (int i = 0; i < 4; ++i) { *(u4v*)&Wn[lr * LDH + lc + 8 * i] = ra[i]; *(u4v*)&Wn[(256 + lr) * LDH + lc + 8 * i] = rb[i]; }
;     }
;     if (kt + 2 < nk) {
; #pragma unroll
;       for (int i = 0; i < 4; ++i) { ra[i] = *(const u4v*)(AP_ + 8 * i); rb[i] = *(const u4v*)(BP_ + 8 * i); }
;       ao += 64; bo += 64;
;     }
; #pragma unroll
;     for (int ks = 0; ks < 4; ++ks) {
;       h8v af[4], bf[2];
; #pragma unroll
;       for (int i = 0; i < 4; ++i) af[i] = *(const h8v*)&As[(wm * 128 + i * 32 + (lane & 31)) * LDH + ks * 16 + 8 * (lane >> 5)];
; #pragma unroll
;       for (int j = 0; j < 2; ++j) bf[j] = *(const h8v*)&Bs[(wn * 64 + j * 32 + (lane & 31)) * LDH + ks * 16 + 8 * (lane >> 5)];
; #pragma unroll
;       for (int i = 0; i < 4; ++i)
; #pragma unroll
;         for (int j = 0; j < 2; ++j) acc[i][j] = mfma32(bf[j], af[i], acc[i][j]);
;     }
;     __syncthreads();
;   }
	ds_read_b128 v[232:235], v213
	ds_read_b128 v[216:219], v215
	ds_read_b128 v[236:239], v213 offset:4608
	ds_read_b128 v[220:223], v215 offset:4608
	ds_read_b128 v[224:227], v215 offset:9216
	ds_read_b128 v[228:231], v215 offset:13824
	v_mfma_f32_32x32x16_f16 v[114:129], v[208:211], v[240:243], v[114:129]
	v_mfma_f32_32x32x16_f16 v[98:113], v[174:177], v[240:243], v[98:113]
	v_mfma_f32_32x32x16_f16 v[82:97], v[208:211], v[244:247], v[82:97]
	v_mfma_f32_32x32x16_f16 v[66:81], v[174:177], v[244:247], v[66:81]
	v_mfma_f32_32x32x16_f16 v[50:65], v[208:211], v[248:251], v[50:65]
	v_mfma_f32_32x32x16_f16 v[34:49], v[174:177], v[248:251], v[34:49]
	v_mfma_f32_32x32x16_f16 v[18:33], v[208:211], v[204:207], v[18:33]
	v_mfma_f32_32x32x16_f16 v[2:17], v[174:177], v[204:207], v[2:17]
	ds_read_b128 v[208:211], v213 offset:32
	ds_read_b128 v[240:243], v215 offset:32
	ds_read_b128 v[174:177], v213 offset:4640
	ds_read_b128 v[244:247], v215 offset:4640
	ds_read_b128 v[248:251], v215 offset:9248
	ds_read_b128 v[204:207], v215 offset:13856
	s_waitcnt vmcnt(4)
	ds_write_b128 v179, v[134:137]
	ds_write_b128 v179, v[138:141] offset:16
	ds_write_b128 v179, v[142:145] offset:32
	ds_write_b128 v179, v[146:149] offset:48
	global_load_dwordx4 v[134:137], v[130:131], off offset:1280
	global_load_dwordx4 v[138:141], v[130:131], off offset:1296
	global_load_dwordx4 v[142:145], v[130:131], off offset:1312
	global_load_dwordx4 v[146:149], v[130:131], off offset:1328
	s_waitcnt lgkmcnt(14)
	v_mfma_f32_32x32x16_f16 v[114:129], v[232:235], v[216:219], v[114:129]
	s_waitcnt lgkmcnt(13)
	v_mfma_f32_32x32x16_f16 v[98:113], v[236:239], v[216:219], v[98:113]
	s_waitcnt lgkmcnt(12)
	v_mfma_f32_32x32x16_f16 v[82:97], v[232:235], v[220:223], v[82:97]
	v_mfma_f32_32x32x16_f16 v[66:81], v[236:239], v[220:223], v[66:81]
	s_waitcnt lgkmcnt(11)
	v_mfma_f32_32x32x16_f16 v[50:65], v[232:235], v[224:227], v[50:65]
	v_mfma_f32_32x32x16_f16 v[34:49], v[236:239], v[224:227], v[34:49]
	s_waitcnt lgkmcnt(10)
	v_mfma_f32_32x32x16_f16 v[18:33], v[232:235], v[228:231], v[18:33]
	v_mfma_f32_32x32x16_f16 v[2:17], v[236:239], v[228:231], v[2:17]
	ds_read_b128 v[232:235], v213 offset:64
	ds_read_b128 v[216:219], v215 offset:64
	ds_read_b128 v[236:239], v213 offset:4672
	ds_read_b128 v[220:223], v215 offset:4672
	ds_read_b128 v[224:227], v215 offset:9280
	ds_read_b128 v[228:231], v215 offset:13888
	s_waitcnt vmcnt(4)
	ds_write_b128 v179, v[150:153] offset:36864
	ds_write_b128 v179, v[154:157] offset:36880
	ds_write_b128 v179, v[158:161] offset:36896
	ds_write_b128 v179, v[162:165] offset:36912
	global_load_dwordx4 v[150:153], v[202:203], off offset:1280
	global_load_dwordx4 v[154:157], v[202:203], off offset:1296
	global_load_dwordx4 v[158:161], v[202:203], off offset:1312
	global_load_dwordx4 v[162:165], v[202:203], off offset:1328
	s_waitcnt lgkmcnt(15)
	v_mfma_f32_32x32x16_f16 v[114:129], v[208:211], v[240:243], v[114:129]
	s_waitcnt lgkmcnt(15)
	v_mfma_f32_32x32x16_f16 v[98:113], v[174:177], v[240:243], v[98:113]
	s_waitcnt lgkmcnt(15)
	v_mfma_f32_32x32x16_f16 v[82:97], v[208:211], v[244:247], v[82:97]
	v_mfma_f32_32x32x16_f16 v[66:81], v[174:177], v[244:247], v[66:81]
	s_waitcnt lgkmcnt(15)
	v_mfma_f32_32x32x16_f16 v[50:65], v[208:211], v[248:251], v[50:65]
	v_mfma_f32_32x32x16_f16 v[34:49], v[174:177], v[248:251], v[34:49]
	s_waitcnt lgkmcnt(14)
	v_mfma_f32_32x32x16_f16 v[18:33], v[208:211], v[204:207], v[18:33]
	v_mfma_f32_32x32x16_f16 v[2:17], v[174:177], v[204:207], v[2:17]
	ds_read_b128 v[208:211], v213 offset:96
	ds_read_b128 v[240:243], v215 offset:96
	ds_read_b128 v[174:177], v213 offset:4704
	ds_read_b128 v[244:247], v215 offset:4704
	ds_read_b128 v[248:251], v215 offset:9312
	ds_read_b128 v[204:207], v215 offset:13920
	s_waitcnt lgkmcnt(14)
	v_mfma_f32_32x32x16_f16 v[114:129], v[232:235], v[216:219], v[114:129]
	s_waitcnt lgkmcnt(13)
	v_mfma_f32_32x32x16_f16 v[98:113], v[236:239], v[216:219], v[98:113]
	s_waitcnt lgkmcnt(12)
	v_mfma_f32_32x32x16_f16 v[82:97], v[232:235], v[220:223], v[82:97]
	v_mfma_f32_32x32x16_f16 v[66:81], v[236:239], v[220:223], v[66:81]
	s_waitcnt lgkmcnt(11)
	v_mfma_f32_32x32x16_f16 v[50:65], v[232:235], v[224:227], v[50:65]
	v_mfma_f32_32x32x16_f16 v[34:49], v[236:239], v[224:227], v[34:49]
	s_waitcnt lgkmcnt(10)
	v_mfma_f32_32x32x16_f16 v[18:33], v[232:235], v[228:231], v[18:33]
	v_mfma_f32_32x32x16_f16 v[2:17], v[236:239], v[228:231], v[2:17]
	s_waitcnt lgkmcnt(0)
	s_barrier
; DI f16v mfma32(h8v a, h8v b, f16v c) { return __builtin_amdgcn_mfma_f32_32x32x16_f16(a, b, c, 0, 0, 0); }
; template <bool GATHER>
; DI void gemm256_main(const h16* __restrict__ A, int lda, const int* __restrict__ idx, int m0,
;                      const h16* __restrict__ B, int ldb, int n0, int K, h16* lds, f16v (&acc)[4][2]) {
;     ...
;   for (int kt = 0; kt < nk; ++kt) {
;     const h16* As = lds + (kt & 1) * (512 * LDH);
;     const h16* Bs = As + 256 * LDH;
;     h16* Wn = lds + ((kt & 1) ^ 1) * (512 * LDH);
;     if (kt + 1 < nk) {
; #pragma unroll
;       for (int i = 0; i < 4; ++i) { *(u4v*)&Wn[lr * LDH + lc + 8 * i] = ra[i]; *(u4v*)&Wn[(256 + lr) * LDH + lc + 8 * i] = rb[i]; }
;     }
;     if (kt + 2 < nk) {
; #pragma unroll
;       for (int i = 0; i < 4; ++i) { ra[i] = *(const u4v*)(AP_ + 8 * i); rb[i] = *(const u4v*)(BP_ + 8 * i); }
;       ao += 64; bo += 64;
;     }
; #pragma unroll
;     for (int ks = 0; ks < 4; ++ks) {
;       h8v af[4], bf[2];
; #pragma unroll
;       for (int i = 0; i < 4; ++i) af[i] = *(const h8v*)&As[(wm * 128 + i * 32 + (lane & 31)) * LDH + ks * 16 + 8 * (lane >> 5)];
; #pragma unroll
;       for (int j = 0; j < 2; ++j) bf[j] = *(const h8v*)&Bs[(wn * 64 + j * 32 + (lane & 31)) * LDH + ks * 16 + 8 * (lane >> 5)];
; #pragma unroll
;       for (int i = 0; i < 4; ++i)
; #pragma unroll
;         for (int j = 0; j < 2; ++j) acc[i][j] = mfma32(bf[j], af[i], acc[i][j]);
;     }
;     __syncthreads();
;   }
	ds_read_b128 v[232:235], v214
	ds_read_b128 v[216:219], v212
	ds_read_b128 v[236:239], v214 offset:4608
	ds_read_b128 v[220:223], v212 offset:4608
	ds_read_b128 v[224:227], v212 offset:9216
	ds_read_b128 v[228:231], v212 offset:13824
	v_mfma_f32_32x32x16_f16 v[114:129], v[208:211], v[240:243], v[114:129]
	v_mfma_f32_32x32x16_f16 v[98:113], v[174:177], v[240:243], v[98:113]
	v_mfma_f32_32x32x16_f16 v[82:97], v[208:211], v[244:247], v[82:97]
	v_mfma_f32_32x32x16_f16 v[66:81], v[174:177], v[244:247], v[66:81]
	v_mfma_f32_32x32x16_f16 v[50:65], v[208:211], v[248:251], v[50:65]
	v_mfma_f32_32x32x16_f16 v[34:49], v[174:177], v[248:251], v[34:49]
	v_mfma_f32_32x32x16_f16 v[18:33], v[208:211], v[204:207], v[18:33]
	v_mfma_f32_32x32x16_f16 v[2:17], v[174:177], v[204:207], v[2:17]
	ds_read_b128 v[208:211], v214 offset:32
	ds_read_b128 v[240:243], v212 offset:32
	ds_read_b128 v[174:177], v214 offset:4640
	ds_read_b128 v[244:247], v212 offset:4640
	ds_read_b128 v[248:251], v212 offset:9248
	ds_read_b128 v[204:207], v212 offset:13856
	s_waitcnt vmcnt(4)
	ds_write_b128 v178, v[134:137]
	ds_write_b128 v178, v[138:141] offset:16
	ds_write_b128 v178, v[142:145] offset:32
	ds_write_b128 v178, v[146:149] offset:48
	global_load_dwordx4 v[134:137], v[130:131], off offset:1408
	global_load_dwordx4 v[138:141], v[130:131], off offset:1424
	global_load_dwordx4 v[142:145], v[130:131], off offset:1440
	global_load_dwordx4 v[146:149], v[130:131], off offset:1456
	s_waitcnt lgkmcnt(14)
	v_mfma_f32_32x32x16_f16 v[114:129], v[232:235], v[216:219], v[114:129]
	s_waitcnt lgkmcnt(13)
	v_mfma_f32_32x32x16_f16 v[98:113], v[236:239], v[216:219], v[98:113]
	s_waitcnt lgkmcnt(12)
	v_mfma_f32_32x32x16_f16 v[82:97], v[232:235], v[220:223], v[82:97]
	v_mfma_f32_32x32x16_f16 v[66:81], v[236:239], v[220:223], v[66:81]
	s_waitcnt lgkmcnt(11)
	v_mfma_f32_32x32x16_f16 v[50:65], v[232:235], v[224:227], v[50:65]
	v_mfma_f32_32x32x16_f16 v[34:49], v[236:239], v[224:227], v[34:49]
	s_waitcnt lgkmcnt(10)
	v_mfma_f32_32x32x16_f16 v[18:33], v[232:235], v[228:231], v[18:33]
	v_mfma_f32_32x32x16_f16 v[2:17], v[236:239], v[228:231], v[2:17]
	ds_read_b128 v[232:235], v214 offset:64
	ds_read_b128 v[216:219], v212 offset:64
	ds_read_b128 v[236:239], v214 offset:4672
	ds_read_b128 v[220:223], v212 offset:4672
	ds_read_b128 v[224:227], v212 offset:9280
	ds_read_b128 v[228:231], v212 offset:13888
	s_waitcnt vmcnt(4)
	ds_write_b128 v178, v[150:153] offset:36864
	ds_write_b128 v178, v[154:157] offset:36880
	ds_write_b128 v178, v[158:161] offset:36896
	ds_write_b128 v178, v[162:165] offset:36912
	global_load_dwordx4 v[150:153], v[202:203], off offset:1408
	global_load_dwordx4 v[154:157], v[202:203], off offset:1424
	global_load_dwordx4 v[158:161], v[202:203], off offset:1440
	global_load_dwordx4 v[162:165], v[202:203], off offset:1456
	s_waitcnt lgkmcnt(15)
	v_mfma_f32_32x32x16_f16 v[114:129], v[208:211], v[240:243], v[114:129]
	s_waitcnt lgkmcnt(15)
	v_mfma_f32_32x32x16_f16 v[98:113], v[174:177], v[240:243], v[98:113]
	s_waitcnt lgkmcnt(15)
	v_mfma_f32_32x32x16_f16 v[82:97], v[208:211], v[244:247], v[82:97]
	v_mfma_f32_32x32x16_f16 v[66:81], v[174:177], v[244:247], v[66:81]
	s_waitcnt lgkmcnt(15)
	v_mfma_f32_32x32x16_f16 v[50:65], v[208:211], v[248:251], v[50:65]
	v_mfma_f32_32x32x16_f16 v[34:49], v[174:177], v[248:251], v[34:49]
	s_waitcnt lgkmcnt(14)
	v_mfma_f32_32x32x16_f16 v[18:33], v[208:211], v[204:207], v[18:33]
	v_mfma_f32_32x32x16_f16 v[2:17], v[174:177], v[204:207], v[2:17]
	ds_read_b128 v[208:211], v214 offset:96
	ds_read_b128 v[240:243], v212 offset:96
	ds_read_b128 v[174:177], v214 offset:4704
	ds_read_b128 v[244:247], v212 offset:4704
	ds_read_b128 v[248:251], v212 offset:9312
	ds_read_b128 v[204:207], v212 offset:13920
	s_waitcnt lgkmcnt(14)
	v_mfma_f32_32x32x16_f16 v[114:129], v[232:235], v[216:219], v[114:129]
	s_waitcnt lgkmcnt(13)
	v_mfma_f32_32x32x16_f16 v[98:113], v[236:239], v[216:219], v[98:113]
	s_waitcnt lgkmcnt(12)
	v_mfma_f32_32x32x16_f16 v[82:97], v[232:235], v[220:223], v[82:97]
	v_mfma_f32_32x32x16_f16 v[66:81], v[236:239], v[220:223], v[66:81]
	s_waitcnt lgkmcnt(11)
	v_mfma_f32_32x32x16_f16 v[50:65], v[232:235], v[224:227], v[50:65]
	v_mfma_f32_32x32x16_f16 v[34:49], v[236:239], v[224:227], v[34:49]
	s_waitcnt lgkmcnt(10)
	v_mfma_f32_32x32x16_f16 v[18:33], v[232:235], v[228:231], v[18:33]
	v_mfma_f32_32x32x16_f16 v[2:17], v[236:239], v[228:231], v[2:17]
	s_waitcnt lgkmcnt(0)
	s_barrier
; DI f16v mfma32(h8v a, h8v b, f16v c) { return __builtin_amdgcn_mfma_f32_32x32x16_f16(a, b, c, 0, 0, 0); }
; template <bool GATHER>
; DI void gemm256_main(const h16* __restrict__ A, int lda, const int* __restrict__ idx, int m0,
;                      const h16* __restrict__ B, int ldb, int n0, int K, h16* lds, f16v (&acc)[4][2]) {
;     ...
;   for (int kt = 0; kt < nk; ++kt) {
;     const h16* As = lds + (kt & 1) * (512 * LDH);
;     const h16* Bs = As + 256 * LDH;
;     h16* Wn = lds + ((kt & 1) ^ 1) * (512 * LDH);
;     if (kt + 1 < nk) {
; #pragma unroll
;       for (int i = 0; i < 4; ++i) { *(u4v*)&Wn[lr * LDH + lc + 8 * i] = ra[i]; *(u4v*)&Wn[(256 + lr) * LDH + lc + 8 * i] = rb[i]; }
;     }
;     if (kt + 2 < nk) {
; #pragma unroll
;       for (int i = 0; i < 4; ++i) { ra[i] = *(const u4v*)(AP_ + 8 * i); rb[i] = *(const u4v*)(BP_ + 8 * i); }
;       ao += 64; bo += 64;
;     }
; #pragma unroll
;     for (int ks = 0; ks < 4; ++ks) {
;       h8v af[4], bf[2];
; #pragma unroll
;       for (int i = 0; i < 4; ++i) af[i] = *(const h8v*)&As[(wm * 128 + i * 32 + (lane & 31)) * LDH + ks * 16 + 8 * (lane >> 5)];
; #pragma unroll
;       for (int j = 0; j < 2; ++j) bf[j] = *(const h8v*)&Bs[(wn * 64 + j * 32 + (lane & 31)) * LDH + ks * 16 + 8 * (lane >> 5)];
; #pragma unroll
;       for (int i = 0; i < 4; ++i)
; #pragma unroll
;         for (int j = 0; j < 2; ++j) acc[i][j] = mfma32(bf[j], af[i], acc[i][j]);
;     }
;     __syncthreads();
;   }
	ds_read_b128 v[232:235], v213
	ds_read_b128 v[216:219], v215
	ds_read_b128 v[236:239], v213 offset:4608
	ds_read_b128 v[220:223], v215 offset:4608
	ds_read_b128 v[224:227], v215 offset:9216
	ds_read_b128 v[228:231], v215 offset:13824
	v_mfma_f32_32x32x16_f16 v[114:129], v[208:211], v[240:243], v[114:129]
	v_mfma_f32_32x32x16_f16 v[98:113], v[174:177], v[240:243], v[98:113]
	v_mfma_f32_32x32x16_f16 v[82:97], v[208:211], v[244:247], v[82:97]
	v_mfma_f32_32x32x16_f16 v[66:81], v[174:177], v[244:247], v[66:81]
	v_mfma_f32_32x32x16_f16 v[50:65], v[208:211], v[248:251], v[50:65]
	v_mfma_f32_32x32x16_f16 v[34:49], v[174:177], v[248:251], v[34:49]
	v_mfma_f32_32x32x16_f16 v[18:33], v[208:211], v[204:207], v[18:33]
	v_mfma_f32_32x32x16_f16 v[2:17], v[174:177], v[204:207], v[2:17]
	ds_read_b128 v[208:211], v213 offset:32
	ds_read_b128 v[240:243], v215 offset:32
	ds_read_b128 v[174:177], v213 offset:4640
	ds_read_b128 v[244:247], v215 offset:4640
	ds_read_b128 v[248:251], v215 offset:9248
	ds_read_b128 v[204:207], v215 offset:13856
	s_waitcnt vmcnt(4)
	ds_write_b128 v179, v[134:137]
	ds_write_b128 v179, v[138:141] offset:16
	ds_write_b128 v179, v[142:145] offset:32
	ds_write_b128 v179, v[146:149] offset:48
	global_load_dwordx4 v[134:137], v[130:131], off offset:1536
	global_load_dwordx4 v[138:141], v[130:131], off offset:1552
	global_load_dwordx4 v[142:145], v[130:131], off offset:1568
	global_load_dwordx4 v[146:149], v[130:131], off offset:1584
	s_waitcnt lgkmcnt(14)
	v_mfma_f32_32x32x16_f16 v[114:129], v[232:235], v[216:219], v[114:129]
	s_waitcnt lgkmcnt(13)
	v_mfma_f32_32x32x16_f16 v[98:113], v[236:239], v[216:219], v[98:113]
	s_waitcnt lgkmcnt(12)
	v_mfma_f32_32x32x16_f16 v[82:97], v[232:235], v[220:223], v[82:97]
	v_mfma_f32_32x32x16_f16 v[66:81], v[236:239], v[220:223], v[66:81]
	s_waitcnt lgkmcnt(11)
	v_mfma_f32_32x32x16_f16 v[50:65], v[232:235], v[224:227], v[50:65]
	v_mfma_f32_32x32x16_f16 v[34:49], v[236:239], v[224:227], v[34:49]
	s_waitcnt lgkmcnt(10)
	v_mfma_f32_32x32x16_f16 v[18:33], v[232:235], v[228:231], v[18:33]
	v_mfma_f32_32x32x16_f16 v[2:17], v[236:239], v[228:231], v[2:17]
	ds_read_b128 v[232:235], v213 offset:64
	ds_read_b128 v[216:219], v215 offset:64
	ds_read_b128 v[236:239], v213 offset:4672
	ds_read_b128 v[220:223], v215 offset:4672
	ds_read_b128 v[224:227], v215 offset:9280
	ds_read_b128 v[228:231], v215 offset:13888
	s_waitcnt vmcnt(4)
	ds_write_b128 v179, v[150:153] offset:36864
	ds_write_b128 v179, v[154:157] offset:36880
	ds_write_b128 v179, v[158:161] offset:36896
	ds_write_b128 v179, v[162:165] offset:36912
	global_load_dwordx4 v[150:153], v[202:203], off offset:1536
	global_load_dwordx4 v[154:157], v[202:203], off offset:1552
	global_load_dwordx4 v[158:161], v[202:203], off offset:1568
	global_load_dwordx4 v[162:165], v[202:203], off offset:1584
	s_waitcnt lgkmcnt(15)
	v_mfma_f32_32x32x16_f16 v[114:129], v[208:211], v[240:243], v[114:129]
	s_waitcnt lgkmcnt(15)
	v_mfma_f32_32x32x16_f16 v[98:113], v[174:177], v[240:243], v[98:113]
	s_waitcnt lgkmcnt(15)
	v_mfma_f32_32x32x16_f16 v[82:97], v[208:211], v[244:247], v[82:97]
	v_mfma_f32_32x32x16_f16 v[66:81], v[174:177], v[244:247], v[66:81]
	s_waitcnt lgkmcnt(15)
	v_mfma_f32_32x32x16_f16 v[50:65], v[208:211], v[248:251], v[50:65]
	v_mfma_f32_32x32x16_f16 v[34:49], v[174:177], v[248:251], v[34:49]
	s_waitcnt lgkmcnt(14)
	v_mfma_f32_32x32x16_f16 v[18:33], v[208:211], v[204:207], v[18:33]
	v_mfma_f32_32x32x16_f16 v[2:17], v[174:177], v[204:207], v[2:17]
	ds_read_b128 v[208:211], v213 offset:96
	ds_read_b128 v[240:243], v215 offset:96
	ds_read_b128 v[174:177], v213 offset:4704
	ds_read_b128 v[244:247], v215 offset:4704
	ds_read_b128 v[248:251], v215 offset:9312
	ds_read_b128 v[204:207], v215 offset:13920
	s_waitcnt lgkmcnt(14)
	v_mfma_f32_32x32x16_f16 v[114:129], v[232:235], v[216:219], v[114:129]
	s_waitcnt lgkmcnt(13)
	v_mfma_f32_32x32x16_f16 v[98:113], v[236:239], v[216:219], v[98:113]
	s_waitcnt lgkmcnt(12)
	v_mfma_f32_32x32x16_f16 v[82:97], v[232:235], v[220:223], v[82:97]
	v_mfma_f32_32x32x16_f16 v[66:81], v[236:239], v[220:223], v[66:81]
	s_waitcnt lgkmcnt(11)
	v_mfma_f32_32x32x16_f16 v[50:65], v[232:235], v[224:227], v[50:65]
	v_mfma_f32_32x32x16_f16 v[34:49], v[236:239], v[224:227], v[34:49]
	s_waitcnt lgkmcnt(10)
	v_mfma_f32_32x32x16_f16 v[18:33], v[232:235], v[228:231], v[18:33]
	v_mfma_f32_32x32x16_f16 v[2:17], v[236:239], v[228:231], v[2:17]
	s_waitcnt lgkmcnt(0)
	s_barrier
; DI f16v mfma32(h8v a, h8v b, f16v c) { return __builtin_amdgcn_mfma_f32_32x32x16_f16(a, b, c, 0, 0, 0); }
; template <bool GATHER>
; DI void gemm256_main(const h16* __restrict__ A, int lda, const int* __restrict__ idx, int m0,
;                      const h16* __restrict__ B, int ldb, int n0, int K, h16* lds, f16v (&acc)[4][2]) {
;     ...
;   for (int kt = 0; kt < nk; ++kt) {
;     const h16* As = lds + (kt & 1) * (512 * LDH);
;     const h16* Bs = As + 256 * LDH;
;     h16* Wn = lds + ((kt & 1) ^ 1) * (512 * LDH);
;     if (kt + 1 < nk) {
; #pragma unroll
;       for (int i = 0; i < 4; ++i) { *(u4v*)&Wn[lr * LDH + lc + 8 * i] = ra[i]; *(u4v*)&Wn[(256 + lr) * LDH + lc + 8 * i] = rb[i]; }
;     }
;     if (kt + 2 < nk) {
; #pragma unroll
;       for (int i = 0; i < 4; ++i) { ra[i] = *(const u4v*)(AP_ + 8 * i); rb[i] = *(const u4v*)(BP_ + 8 * i); }
;       ao += 64; bo += 64;
;     }
; #pragma unroll
;     for (int ks = 0; ks < 4; ++ks) {
;       h8v af[4], bf[2];
; #pragma unroll
;       for (int i = 0; i < 4; ++i) af[i] = *(const h8v*)&As[(wm * 128 + i * 32 + (lane & 31)) * LDH + ks * 16 + 8 * (lane >> 5)];
; #pragma unroll
;       for (int j = 0; j < 2; ++j) bf[j] = *(const h8v*)&Bs[(wn * 64 + j * 32 + (lane & 31)) * LDH + ks * 16 + 8 * (lane >> 5)];
; #pragma unroll
;       for (int i = 0; i < 4; ++i)
; #pragma unroll
;         for (int j = 0; j < 2; ++j) acc[i][j] = mfma32(bf[j], af[i], acc[i][j]);
;     }
;     __syncthreads();
;   }
	ds_read_b128 v[232:235], v214
	ds_read_b128 v[216:219], v212
	ds_read_b128 v[236:239], v214 offset:4608
	ds_read_b128 v[220:223], v212 offset:4608
	ds_read_b128 v[224:227], v212 offset:9216
	ds_read_b128 v[228:231], v212 offset:13824
	v_mfma_f32_32x32x16_f16 v[114:129], v[208:211], v[240:243], v[114:129]
	v_mfma_f32_32x32x16_f16 v[98:113], v[174:177], v[240:243], v[98:113]
	v_mfma_f32_32x32x16_f16 v[82:97], v[208:211], v[244:247], v[82:97]
	v_mfma_f32_32x32x16_f16 v[66:81], v[174:177], v[244:247], v[66:81]
	v_mfma_f32_32x32x16_f16 v[50:65], v[208:211], v[248:251], v[50:65]
	v_mfma_f32_32x32x16_f16 v[34:49], v[174:177], v[248:251], v[34:49]
	v_mfma_f32_32x32x16_f16 v[18:33], v[208:211], v[204:207], v[18:33]
	v_mfma_f32_32x32x16_f16 v[2:17], v[174:177], v[204:207], v[2:17]
	ds_read_b128 v[208:211], v214 offset:32
	ds_read_b128 v[240:243], v212 offset:32
	ds_read_b128 v[174:177], v214 offset:4640
	ds_read_b128 v[244:247], v212 offset:4640
	ds_read_b128 v[248:251], v212 offset:9248
	ds_read_b128 v[204:207], v212 offset:13856
	s_waitcnt vmcnt(4)
	ds_write_b128 v178, v[134:137]
	ds_write_b128 v178, v[138:141] offset:16
	ds_write_b128 v178, v[142:145] offset:32
	ds_write_b128 v178, v[146:149] offset:48
	global_load_dwordx4 v[134:137], v[130:131], off offset:1664
	global_load_dwordx4 v[138:141], v[130:131], off offset:1680
	global_load_dwordx4 v[142:145], v[130:131], off offset:1696
	global_load_dwordx4 v[146:149], v[130:131], off offset:1712
	s_waitcnt lgkmcnt(14)
	v_mfma_f32_32x32x16_f16 v[114:129], v[232:235], v[216:219], v[114:129]
	s_waitcnt lgkmcnt(13)
	v_mfma_f32_32x32x16_f16 v[98:113], v[236:239], v[216:219], v[98:113]
	s_waitcnt lgkmcnt(12)
	v_mfma_f32_32x32x16_f16 v[82:97], v[232:235], v[220:223], v[82:97]
	v_mfma_f32_32x32x16_f16 v[66:81], v[236:239], v[220:223], v[66:81]
	s_waitcnt lgkmcnt(11)
	v_mfma_f32_32x32x16_f16 v[50:65], v[232:235], v[224:227], v[50:65]
	v_mfma_f32_32x32x16_f16 v[34:49], v[236:239], v[224:227], v[34:49]
	s_waitcnt lgkmcnt(10)
	v_mfma_f32_32x32x16_f16 v[18:33], v[232:235], v[228:231], v[18:33]
	v_mfma_f32_32x32x16_f16 v[2:17], v[236:239], v[228:231], v[2:17]
	ds_read_b128 v[232:235], v214 offset:64
	ds_read_b128 v[216:219], v212 offset:64
	ds_read_b128 v[236:239], v214 offset:4672
	ds_read_b128 v[220:223], v212 offset:4672
	ds_read_b128 v[224:227], v212 offset:9280
	ds_read_b128 v[228:231], v212 offset:13888
	s_waitcnt vmcnt(4)
	ds_write_b128 v178, v[150:153] offset:36864
	ds_write_b128 v178, v[154:157] offset:36880
	ds_write_b128 v178, v[158:161] offset:36896
	ds_write_b128 v178, v[162:165] offset:36912
	global_load_dwordx4 v[150:153], v[202:203], off offset:1664
	global_load_dwordx4 v[154:157], v[202:203], off offset:1680
	global_load_dwordx4 v[158:161], v[202:203], off offset:1696
	global_load_dwordx4 v[162:165], v[202:203], off offset:1712
	s_waitcnt lgkmcnt(15)
	v_mfma_f32_32x32x16_f16 v[114:129], v[208:211], v[240:243], v[114:129]
	s_waitcnt lgkmcnt(15)
	v_mfma_f32_32x32x16_f16 v[98:113], v[174:177], v[240:243], v[98:113]
	s_waitcnt lgkmcnt(15)
	v_mfma_f32_32x32x16_f16 v[82:97], v[208:211], v[244:247], v[82:97]
	v_mfma_f32_32x32x16_f16 v[66:81], v[174:177], v[244:247], v[66:81]
	s_waitcnt lgkmcnt(15)
	v_mfma_f32_32x32x16_f16 v[50:65], v[208:211], v[248:251], v[50:65]
	v_mfma_f32_32x32x16_f16 v[34:49], v[174:177], v[248:251], v[34:49]
	s_waitcnt lgkmcnt(14)
	v_mfma_f32_32x32x16_f16 v[18:33], v[208:211], v[204:207], v[18:33]
	v_mfma_f32_32x32x16_f16 v[2:17], v[174:177], v[204:207], v[2:17]
	ds_read_b128 v[208:211], v214 offset:96
	ds_read_b128 v[240:243], v212 offset:96
	ds_read_b128 v[174:177], v214 offset:4704
	ds_read_b128 v[244:247], v212 offset:4704
	ds_read_b128 v[248:251], v212 offset:9312
	ds_read_b128 v[204:207], v212 offset:13920
	s_waitcnt lgkmcnt(14)
	v_mfma_f32_32x32x16_f16 v[114:129], v[232:235], v[216:219], v[114:129]
	s_waitcnt lgkmcnt(13)
	v_mfma_f32_32x32x16_f16 v[98:113], v[236:239], v[216:219], v[98:113]
	s_waitcnt lgkmcnt(12)
	v_mfma_f32_32x32x16_f16 v[82:97], v[232:235], v[220:223], v[82:97]
	v_mfma_f32_32x32x16_f16 v[66:81], v[236:239], v[220:223], v[66:81]
	s_waitcnt lgkmcnt(11)
	v_mfma_f32_32x32x16_f16 v[50:65], v[232:235], v[224:227], v[50:65]
	v_mfma_f32_32x32x16_f16 v[34:49], v[236:239], v[224:227], v[34:49]
	s_waitcnt lgkmcnt(10)
	v_mfma_f32_32x32x16_f16 v[18:33], v[232:235], v[228:231], v[18:33]
	v_mfma_f32_32x32x16_f16 v[2:17], v[236:239], v[228:231], v[2:17]
	s_waitcnt lgkmcnt(0)
	s_barrier
; DI f16v mfma32(h8v a, h8v b, f16v c) { return __builtin_amdgcn_mfma_f32_32x32x16_f16(a, b, c, 0, 0, 0); }
; template <bool GATHER>
; DI void gemm256_main(const h16* __restrict__ A, int lda, const int* __restrict__ idx, int m0,
;                      const h16* __restrict__ B, int ldb, int n0, int K, h16* lds, f16v (&acc)[4][2]) {
;     ...
;   for (int kt = 0; kt < nk; ++kt) {
;     const h16* As = lds + (kt & 1) * (512 * LDH);
;     const h16* Bs = As + 256 * LDH;
;     h16* Wn = lds + ((kt & 1) ^ 1) * (512 * LDH);
;     if (kt + 1 < nk) {
; #pragma unroll
;       for (int i = 0; i < 4; ++i) { *(u4v*)&Wn[lr * LDH + lc + 8 * i] = ra[i]; *(u4v*)&Wn[(256 + lr) * LDH + lc + 8 * i] = rb[i]; }
;     }
;     if (kt + 2 < nk) {
; #pragma unroll
;       for (int i = 0; i < 4; ++i) { ra[i] = *(const u4v*)(AP_ + 8 * i); rb[i] = *(const u4v*)(BP_ + 8 * i); }
;       ao += 64; bo += 64;
;     }
; #pragma unroll
;     for (int ks = 0; ks < 4; ++ks) {
;       h8v af[4], bf[2];
; #pragma unroll
;       for (int i = 0; i < 4; ++i) af[i] = *(const h8v*)&As[(wm * 128 + i * 32 + (lane & 31)) * LDH + ks * 16 + 8 * (lane >> 5)];
; #pragma unroll
;       for (int j = 0; j < 2; ++j) bf[j] = *(const h8v*)&Bs[(wn * 64 + j * 32 + (lane & 31)) * LDH + ks * 16 + 8 * (lane >> 5)];
; #pragma unroll
;       for (int i = 0; i < 4; ++i)
; #pragma unroll
;         for (int j = 0; j < 2; ++j) acc[i][j] = mfma32(bf[j], af[i], acc[i][j]);
;     }
;     __syncthreads();
;   }
	ds_read_b128 v[232:235], v213
	ds_read_b128 v[216:219], v215
	ds_read_b128 v[236:239], v213 offset:4608
	ds_read_b128 v[220:223], v215 offset:4608
	ds_read_b128 v[224:227], v215 offset:9216
	ds_read_b128 v[228:231], v215 offset:13824
	v_mfma_f32_32x32x16_f16 v[114:129], v[208:211], v[240:243], v[114:129]
	v_mfma_f32_32x32x16_f16 v[98:113], v[174:177], v[240:243], v[98:113]
	v_mfma_f32_32x32x16_f16 v[82:97], v[208:211], v[244:247], v[82:97]
	v_mfma_f32_32x32x16_f16 v[66:81], v[174:177], v[244:247], v[66:81]
	v_mfma_f32_32x32x16_f16 v[50:65], v[208:211], v[248:251], v[50:65]
	v_mfma_f32_32x32x16_f16 v[34:49], v[174:177], v[248:251], v[34:49]
	v_mfma_f32_32x32x16_f16 v[18:33], v[208:211], v[204:207], v[18:33]
	v_mfma_f32_32x32x16_f16 v[2:17], v[174:177], v[204:207], v[2:17]
	ds_read_b128 v[208:211], v213 offset:32
	ds_read_b128 v[240:243], v215 offset:32
	ds_read_b128 v[174:177], v213 offset:4640
	ds_read_b128 v[244:247], v215 offset:4640
	ds_read_b128 v[248:251], v215 offset:9248
	ds_read_b128 v[204:207], v215 offset:13856
	s_waitcnt vmcnt(4)
	ds_write_b128 v179, v[134:137]
	ds_write_b128 v179, v[138:141] offset:16
	ds_write_b128 v179, v[142:145] offset:32
	ds_write_b128 v179, v[146:149] offset:48
	global_load_dwordx4 v[134:137], v[130:131], off offset:1792
	global_load_dwordx4 v[138:141], v[130:131], off offset:1808
	global_load_dwordx4 v[142:145], v[130:131], off offset:1824
	global_load_dwordx4 v[146:149], v[130:131], off offset:1840
	s_waitcnt lgkmcnt(14)
	v_mfma_f32_32x32x16_f16 v[114:129], v[232:235], v[216:219], v[114:129]
	s_waitcnt lgkmcnt(13)
	v_mfma_f32_32x32x16_f16 v[98:113], v[236:239], v[216:219], v[98:113]
	s_waitcnt lgkmcnt(12)
	v_mfma_f32_32x32x16_f16 v[82:97], v[232:235], v[220:223], v[82:97]
	v_mfma_f32_32x32x16_f16 v[66:81], v[236:239], v[220:223], v[66:81]
	s_waitcnt lgkmcnt(11)
	v_mfma_f32_32x32x16_f16 v[50:65], v[232:235], v[224:227], v[50:65]
	v_mfma_f32_32x32x16_f16 v[34:49], v[236:239], v[224:227], v[34:49]
	s_waitcnt lgkmcnt(10)
	v_mfma_f32_32x32x16_f16 v[18:33], v[232:235], v[228:231], v[18:33]
	v_mfma_f32_32x32x16_f16 v[2:17], v[236:239], v[228:231], v[2:17]
	ds_read_b128 v[232:235], v213 offset:64
	ds_read_b128 v[216:219], v215 offset:64
	ds_read_b128 v[236:239], v213 offset:4672
	ds_read_b128 v[220:223], v215 offset:4672
	ds_read_b128 v[224:227], v215 offset:9280
	ds_read_b128 v[228:231], v215 offset:13888
	s_waitcnt vmcnt(4)
	ds_write_b128 v179, v[150:153] offset:36864
	ds_write_b128 v179, v[154:157] offset:36880
	ds_write_b128 v179, v[158:161] offset:36896
	ds_write_b128 v179, v[162:165] offset:36912
	global_load_dwordx4 v[150:153], v[202:203], off offset:1792
	global_load_dwordx4 v[154:157], v[202:203], off offset:1808
	global_load_dwordx4 v[158:161], v[202:203], off offset:1824
	global_load_dwordx4 v[162:165], v[202:203], off offset:1840
	s_waitcnt lgkmcnt(15)
	v_mfma_f32_32x32x16_f16 v[114:129], v[208:211], v[240:243], v[114:129]
	s_waitcnt lgkmcnt(15)
	v_mfma_f32_32x32x16_f16 v[98:113], v[174:177], v[240:243], v[98:113]
	s_waitcnt lgkmcnt(15)
	v_mfma_f32_32x32x16_f16 v[82:97], v[208:211], v[244:247], v[82:97]
	v_mfma_f32_32x32x16_f16 v[66:81], v[174:177], v[244:247], v[66:81]
	s_waitcnt lgkmcnt(15)
	v_mfma_f32_32x32x16_f16 v[50:65], v[208:211], v[248:251], v[50:65]
	v_mfma_f32_32x32x16_f16 v[34:49], v[174:177], v[248:251], v[34:49]
	s_waitcnt lgkmcnt(14)
	v_mfma_f32_32x32x16_f16 v[18:33], v[208:211], v[204:207], v[18:33]
	v_mfma_f32_32x32x16_f16 v[2:17], v[174:177], v[204:207], v[2:17]
	ds_read_b128 v[208:211], v213 offset:96
	ds_read_b128 v[240:243], v215 offset:96
	ds_read_b128 v[174:177], v213 offset:4704
	ds_read_b128 v[244:247], v215 offset:4704
	ds_read_b128 v[248:251], v215 offset:9312
	ds_read_b128 v[204:207], v215 offset:13920
	s_waitcnt lgkmcnt(14)
	v_mfma_f32_32x32x16_f16 v[114:129], v[232:235], v[216:219], v[114:129]
	s_waitcnt lgkmcnt(13)
	v_mfma_f32_32x32x16_f16 v[98:113], v[236:239], v[216:219], v[98:113]
	s_waitcnt lgkmcnt(12)
	v_mfma_f32_32x32x16_f16 v[82:97], v[232:235], v[220:223], v[82:97]
	v_mfma_f32_32x32x16_f16 v[66:81], v[236:239], v[220:223], v[66:81]
	s_waitcnt lgkmcnt(11)
	v_mfma_f32_32x32x16_f16 v[50:65], v[232:235], v[224:227], v[50:65]
	v_mfma_f32_32x32x16_f16 v[34:49], v[236:239], v[224:227], v[34:49]
	s_waitcnt lgkmcnt(10)
	v_mfma_f32_32x32x16_f16 v[18:33], v[232:235], v[228:231], v[18:33]
	v_mfma_f32_32x32x16_f16 v[2:17], v[236:239], v[228:231], v[2:17]
	s_waitcnt lgkmcnt(0)
	s_barrier
; DI f16v mfma32(h8v a, h8v b, f16v c) { return __builtin_amdgcn_mfma_f32_32x32x16_f16(a, b, c, 0, 0, 0); }
; template <bool GATHER>
; DI void gemm256_main(const h16* __restrict__ A, int lda, const int* __restrict__ idx, int m0,
;                      const h16* __restrict__ B, int ldb, int n0, int K, h16* lds, f16v (&acc)[4][2]) {
;     ...
;   for (int kt = 0; kt < nk; ++kt) {
;     const h16* As = lds + (kt & 1) * (512 * LDH);
;     const h16* Bs = As + 256 * LDH;
;     h16* Wn = lds + ((kt & 1) ^ 1) * (512 * LDH);
;     if (kt + 1 < nk) {
; #pragma unroll
;       for (int i = 0; i < 4; ++i) { *(u4v*)&Wn[lr * LDH + lc + 8 * i] = ra[i]; *(u4v*)&Wn[(256 + lr) * LDH + lc + 8 * i] = rb[i]; }
;     }
;     if (kt + 2 < nk) {
; #pragma unroll
;       for (int i = 0; i < 4; ++i) { ra[i] = *(const u4v*)(AP_ + 8 * i); rb[i] = *(const u4v*)(BP_ + 8 * i); }
;       ao += 64; bo += 64;
;     }
; #pragma unroll
;     for (int ks = 0; ks < 4; ++ks) {
;       h8v af[4], bf[2];
; #pragma unroll
;       for (int i = 0; i < 4; ++i) af[i] = *(const h8v*)&As[(wm * 128 + i * 32 + (lane & 31)) * LDH + ks * 16 + 8 * (lane >> 5)];
; #pragma unroll
;       for (int j = 0; j < 2; ++j) bf[j] = *(const h8v*)&Bs[(wn * 64 + j * 32 + (lane & 31)) * LDH + ks * 16 + 8 * (lane >> 5)];
; #pragma unroll
;       for (int i = 0; i < 4; ++i)
; #pragma unroll
;         for (int j = 0; j < 2; ++j) acc[i][j] = mfma32(bf[j], af[i], acc[i][j]);
;     }
;     __syncthreads();
;   }
	ds_read_b128 v[232:235], v214
	ds_read_b128 v[216:219], v212
	ds_read_b128 v[236:239], v214 offset:4608
	ds_read_b128 v[220:223], v212 offset:4608
	ds_read_b128 v[224:227], v212 offset:9216
	ds_read_b128 v[228:231], v212 offset:13824
	v_mfma_f32_32x32x16_f16 v[114:129], v[208:211], v[240:243], v[114:129]
	v_mfma_f32_32x32x16_f16 v[98:113], v[174:177], v[240:243], v[98:113]
	v_mfma_f32_32x32x16_f16 v[82:97], v[208:211], v[244:247], v[82:97]
	v_mfma_f32_32x32x16_f16 v[66:81], v[174:177], v[244:247], v[66:81]
	v_mfma_f32_32x32x16_f16 v[50:65], v[208:211], v[248:251], v[50:65]
	v_mfma_f32_32x32x16_f16 v[34:49], v[174:177], v[248:251], v[34:49]
	v_mfma_f32_32x32x16_f16 v[18:33], v[208:211], v[204:207], v[18:33]
	v_mfma_f32_32x32x16_f16 v[2:17], v[174:177], v[204:207], v[2:17]
	ds_read_b128 v[208:211], v214 offset:32
	ds_read_b128 v[240:243], v212 offset:32
	ds_read_b128 v[174:177], v214 offset:4640
	ds_read_b128 v[244:247], v212 offset:4640
	ds_read_b128 v[248:251], v212 offset:9248
	ds_read_b128 v[204:207], v212 offset:13856
	s_waitcnt vmcnt(4)
	ds_write_b128 v178, v[134:137]
	ds_write_b128 v178, v[138:141] offset:16
	ds_write_b128 v178, v[142:145] offset:32
	ds_write_b128 v178, v[146:149] offset:48
	global_load_dwordx4 v[134:137], v[130:131], off offset:1920
	global_load_dwordx4 v[138:141], v[130:131], off offset:1936
	global_load_dwordx4 v[142:145], v[130:131], off offset:1952
	global_load_dwordx4 v[146:149], v[130:131], off offset:1968
	s_waitcnt lgkmcnt(14)
	v_mfma_f32_32x32x16_f16 v[114:129], v[232:235], v[216:219], v[114:129]
	s_waitcnt lgkmcnt(13)
	v_mfma_f32_32x32x16_f16 v[98:113], v[236:239], v[216:219], v[98:113]
	s_waitcnt lgkmcnt(12)
	v_mfma_f32_32x32x16_f16 v[82:97], v[232:235], v[220:223], v[82:97]
	v_mfma_f32_32x32x16_f16 v[66:81], v[236:239], v[220:223], v[66:81]
	s_waitcnt lgkmcnt(11)
	v_mfma_f32_32x32x16_f16 v[50:65], v[232:235], v[224:227], v[50:65]
	v_mfma_f32_32x32x16_f16 v[34:49], v[236:239], v[224:227], v[34:49]
	s_waitcnt lgkmcnt(10)
	v_mfma_f32_32x32x16_f16 v[18:33], v[232:235], v[228:231], v[18:33]
	v_mfma_f32_32x32x16_f16 v[2:17], v[236:239], v[228:231], v[2:17]
	ds_read_b128 v[232:235], v214 offset:64
	ds_read_b128 v[216:219], v212 offset:64
	ds_read_b128 v[236:239], v214 offset:4672
	ds_read_b128 v[220:223], v212 offset:4672
	ds_read_b128 v[224:227], v212 offset:9280
	ds_read_b128 v[228:231], v212 offset:13888
	s_waitcnt vmcnt(4)
	ds_write_b128 v178, v[150:153] offset:36864
	ds_write_b128 v178, v[154:157] offset:36880
	ds_write_b128 v178, v[158:161] offset:36896
	ds_write_b128 v178, v[162:165] offset:36912
	global_load_dwordx4 v[150:153], v[202:203], off offset:1920
	global_load_dwordx4 v[154:157], v[202:203], off offset:1936
	global_load_dwordx4 v[158:161], v[202:203], off offset:1952
	global_load_dwordx4 v[162:165], v[202:203], off offset:1968
	s_waitcnt lgkmcnt(15)
	v_mfma_f32_32x32x16_f16 v[114:129], v[208:211], v[240:243], v[114:129]
	s_waitcnt lgkmcnt(15)
	v_mfma_f32_32x32x16_f16 v[98:113], v[174:177], v[240:243], v[98:113]
	s_waitcnt lgkmcnt(15)
	v_mfma_f32_32x32x16_f16 v[82:97], v[208:211], v[244:247], v[82:97]
	v_mfma_f32_32x32x16_f16 v[66:81], v[174:177], v[244:247], v[66:81]
	s_waitcnt lgkmcnt(15)
	v_mfma_f32_32x32x16_f16 v[50:65], v[208:211], v[248:251], v[50:65]
	v_mfma_f32_32x32x16_f16 v[34:49], v[174:177], v[248:251], v[34:49]
	s_waitcnt lgkmcnt(14)
	v_mfma_f32_32x32x16_f16 v[18:33], v[208:211], v[204:207], v[18:33]
	v_mfma_f32_32x32x16_f16 v[2:17], v[174:177], v[204:207], v[2:17]
	ds_read_b128 v[208:211], v214 offset:96
	ds_read_b128 v[240:243], v212 offset:96
	ds_read_b128 v[174:177], v214 offset:4704
	ds_read_b128 v[244:247], v212 offset:4704
	ds_read_b128 v[248:251], v212 offset:9312
	ds_read_b128 v[204:207], v212 offset:13920
	s_waitcnt lgkmcnt(14)
	v_mfma_f32_32x32x16_f16 v[114:129], v[232:235], v[216:219], v[114:129]
	s_waitcnt lgkmcnt(13)
	v_mfma_f32_32x32x16_f16 v[98:113], v[236:239], v[216:219], v[98:113]
	s_waitcnt lgkmcnt(12)
	v_mfma_f32_32x32x16_f16 v[82:97], v[232:235], v[220:223], v[82:97]
	v_mfma_f32_32x32x16_f16 v[66:81], v[236:239], v[220:223], v[66:81]
	s_waitcnt lgkmcnt(11)
	v_mfma_f32_32x32x16_f16 v[50:65], v[232:235], v[224:227], v[50:65]
	v_mfma_f32_32x32x16_f16 v[34:49], v[236:239], v[224:227], v[34:49]
	s_waitcnt lgkmcnt(10)
	v_mfma_f32_32x32x16_f16 v[18:33], v[232:235], v[228:231], v[18:33]
	v_mfma_f32_32x32x16_f16 v[2:17], v[236:239], v[228:231], v[2:17]
	s_waitcnt lgkmcnt(0)
	s_barrier
; DI f16v mfma32(h8v a, h8v b, f16v c) { return __builtin_amdgcn_mfma_f32_32x32x16_f16(a, b, c, 0, 0, 0); }
; template <bool GATHER>
; DI void gemm256_main(const h16* __restrict__ A, int lda, const int* __restrict__ idx, int m0,
;                      const h16* __restrict__ B, int ldb, int n0, int K, h16* lds, f16v (&acc)[4][2]) {
;     ...
;   for (int kt = 0; kt < nk; ++kt) {
;     const h16* As = lds + (kt & 1) * (512 * LDH);
;     const h16* Bs = As + 256 * LDH;
;     h16* Wn = lds + ((kt & 1) ^ 1) * (512 * LDH);
;     if (kt + 1 < nk) {
; #pragma unroll
;       for (int i = 0; i < 4; ++i) { *(u4v*)&Wn[lr * LDH + lc + 8 * i] = ra[i]; *(u4v*)&Wn[(256 + lr) * LDH + lc + 8 * i] = rb[i]; }
;     }
;     if (kt + 2 < nk) {
; #pragma unroll
;       for (int i = 0; i < 4; ++i) { ra[i] = *(const u4v*)(AP_ + 8 * i); rb[i] = *(const u4v*)(BP_ + 8 * i); }
;       ao += 64; bo += 64;
;     }
; #pragma unroll
;     for (int ks = 0; ks < 4; ++ks) {
;       h8v af[4], bf[2];
; #pragma unroll
;       for (int i = 0; i < 4; ++i) af[i] = *(const h8v*)&As[(wm * 128 + i * 32 + (lane & 31)) * LDH + ks * 16 + 8 * (lane >> 5)];
; #pragma unroll
;       for (int j = 0; j < 2; ++j) bf[j] = *(const h8v*)&Bs[(wn * 64 + j * 32 + (lane & 31)) * LDH + ks * 16 + 8 * (lane >> 5)];
; #pragma unroll
;       for (int i = 0; i < 4; ++i)
; #pragma unroll
;         for (int j = 0; j < 2; ++j) acc[i][j] = mfma32(bf[j], af[i], acc[i][j]);
;     }
;     __syncthreads();
;   }
	ds_read_b128 v[232:235], v213
	ds_read_b128 v[216:219], v215
	ds_read_b128 v[236:239], v213 offset:4608
	ds_read_b128 v[220:223], v215 offset:4608
	ds_read_b128 v[224:227], v215 offset:9216
	ds_read_b128 v[228:231], v215 offset:13824
	v_mfma_f32_32x32x16_f16 v[114:129], v[208:211], v[240:243], v[114:129]
	v_mfma_f32_32x32x16_f16 v[98:113], v[174:177], v[240:243], v[98:113]
	v_mfma_f32_32x32x16_f16 v[82:97], v[208:211], v[244:247], v[82:97]
	v_mfma_f32_32x32x16_f16 v[66:81], v[174:177], v[244:247], v[66:81]
	v_mfma_f32_32x32x16_f16 v[50:65], v[208:211], v[248:251], v[50:65]
	v_mfma_f32_32x32x16_f16 v[34:49], v[174:177], v[248:251], v[34:49]
	v_mfma_f32_32x32x16_f16 v[18:33], v[208:211], v[204:207], v[18:33]
	v_mfma_f32_32x32x16_f16 v[2:17], v[174:177], v[204:207], v[2:17]
	ds_read_b128 v[208:211], v213 offset:32
	ds_read_b128 v[240:243], v215 offset:32
	ds_read_b128 v[174:177], v213 offset:4640
	ds_read_b128 v[244:247], v215 offset:4640
	ds_read_b128 v[248:251], v215 offset:9248
	ds_read_b128 v[204:207], v215 offset:13856
	s_waitcnt vmcnt(4)
	ds_write_b128 v179, v[134:137]
	ds_write_b128 v179, v[138:141] offset:16
	ds_write_b128 v179, v[142:145] offset:32
	ds_write_b128 v179, v[146:149] offset:48
	s_waitcnt lgkmcnt(14)
	v_mfma_f32_32x32x16_f16 v[114:129], v[232:235], v[216:219], v[114:129]
	s_waitcnt lgkmcnt(13)
	v_mfma_f32_32x32x16_f16 v[98:113], v[236:239], v[216:219], v[98:113]
	s_waitcnt lgkmcnt(12)
	v_mfma_f32_32x32x16_f16 v[82:97], v[232:235], v[220:223], v[82:97]
	v_mfma_f32_32x32x16_f16 v[66:81], v[236:239], v[220:223], v[66:81]
	s_waitcnt lgkmcnt(11)
	v_mfma_f32_32x32x16_f16 v[50:65], v[232:235], v[224:227], v[50:65]
	v_mfma_f32_32x32x16_f16 v[34:49], v[236:239], v[224:227], v[34:49]
	s_waitcnt lgkmcnt(10)
	v_mfma_f32_32x32x16_f16 v[18:33], v[232:235], v[228:231], v[18:33]
	v_mfma_f32_32x32x16_f16 v[2:17], v[236:239], v[228:231], v[2:17]
	ds_read_b128 v[232:235], v213 offset:64
	ds_read_b128 v[216:219], v215 offset:64
	ds_read_b128 v[236:239], v213 offset:4672
	ds_read_b128 v[220:223], v215 offset:4672
	ds_read_b128 v[224:227], v215 offset:9280
	ds_read_b128 v[228:231], v215 offset:13888
	s_waitcnt vmcnt(0)
	ds_write_b128 v179, v[150:153] offset:36864
	ds_write_b128 v179, v[154:157] offset:36880
	ds_write_b128 v179, v[158:161] offset:36896
	ds_write_b128 v179, v[162:165] offset:36912
	s_waitcnt lgkmcnt(15)
	v_mfma_f32_32x32x16_f16 v[114:129], v[208:211], v[240:243], v[114:129]
	s_waitcnt lgkmcnt(15)
	v_mfma_f32_32x32x16_f16 v[98:113], v[174:177], v[240:243], v[98:113]
	s_waitcnt lgkmcnt(15)
	v_mfma_f32_32x32x16_f16 v[82:97], v[208:211], v[244:247], v[82:97]
	v_mfma_f32_32x32x16_f16 v[66:81], v[174:177], v[244:247], v[66:81]
	s_waitcnt lgkmcnt(15)
	v_mfma_f32_32x32x16_f16 v[50:65], v[208:211], v[248:251], v[50:65]
	v_mfma_f32_32x32x16_f16 v[34:49], v[174:177], v[248:251], v[34:49]
	s_waitcnt lgkmcnt(14)
	v_mfma_f32_32x32x16_f16 v[18:33], v[208:211], v[204:207], v[18:33]
	v_mfma_f32_32x32x16_f16 v[2:17], v[174:177], v[204:207], v[2:17]
	ds_read_b128 v[208:211], v213 offset:96
	ds_read_b128 v[240:243], v215 offset:96
	ds_read_b128 v[174:177], v213 offset:4704
	ds_read_b128 v[244:247], v215 offset:4704
	ds_read_b128 v[248:251], v215 offset:9312
	ds_read_b128 v[204:207], v215 offset:13920
	s_waitcnt lgkmcnt(14)
	v_mfma_f32_32x32x16_f16 v[114:129], v[232:235], v[216:219], v[114:129]
	s_waitcnt lgkmcnt(13)
	v_mfma_f32_32x32x16_f16 v[98:113], v[236:239], v[216:219], v[98:113]
	s_waitcnt lgkmcnt(12)
	v_mfma_f32_32x32x16_f16 v[82:97], v[232:235], v[220:223], v[82:97]
	v_mfma_f32_32x32x16_f16 v[66:81], v[236:239], v[220:223], v[66:81]
	s_waitcnt lgkmcnt(11)
	v_mfma_f32_32x32x16_f16 v[50:65], v[232:235], v[224:227], v[50:65]
	v_mfma_f32_32x32x16_f16 v[34:49], v[236:239], v[224:227], v[34:49]
	s_waitcnt lgkmcnt(10)
	v_mfma_f32_32x32x16_f16 v[18:33], v[232:235], v[228:231], v[18:33]
	v_mfma_f32_32x32x16_f16 v[2:17], v[236:239], v[228:231], v[2:17]
	s_waitcnt lgkmcnt(0)
	s_barrier
	ds_read_b128 v[232:235], v214
	ds_read_b128 v[216:219], v212
	ds_read_b128 v[236:239], v214 offset:4608
	ds_read_b128 v[220:223], v212 offset:4608
	ds_read_b128 v[224:227], v212 offset:9216
	ds_read_b128 v[228:231], v212 offset:13824
	v_mfma_f32_32x32x16_f16 v[114:129], v[208:211], v[240:243], v[114:129]
	v_mfma_f32_32x32x16_f16 v[98:113], v[174:177], v[240:243], v[98:113]
	v_mfma_f32_32x32x16_f16 v[82:97], v[208:211], v[244:247], v[82:97]
	v_mfma_f32_32x32x16_f16 v[66:81], v[174:177], v[244:247], v[66:81]
	v_mfma_f32_32x32x16_f16 v[50:65], v[208:211], v[248:251], v[50:65]
	v_mfma_f32_32x32x16_f16 v[34:49], v[174:177], v[248:251], v[34:49]
	v_mfma_f32_32x32x16_f16 v[18:33], v[208:211], v[204:207], v[18:33]
	v_mfma_f32_32x32x16_f16 v[2:17], v[174:177], v[204:207], v[2:17]
	ds_read_b128 v[208:211], v214 offset:32
	ds_read_b128 v[240:243], v212 offset:32
	ds_read_b128 v[174:177], v214 offset:4640
	ds_read_b128 v[244:247], v212 offset:4640
	ds_read_b128 v[248:251], v212 offset:9248
	ds_read_b128 v[204:207], v212 offset:13856
	s_waitcnt lgkmcnt(10)
	v_mfma_f32_32x32x16_f16 v[114:129], v[232:235], v[216:219], v[114:129]
	s_waitcnt lgkmcnt(9)
	v_mfma_f32_32x32x16_f16 v[98:113], v[236:239], v[216:219], v[98:113]
	s_waitcnt lgkmcnt(8)
	v_mfma_f32_32x32x16_f16 v[82:97], v[232:235], v[220:223], v[82:97]
	v_mfma_f32_32x32x16_f16 v[66:81], v[236:239], v[220:223], v[66:81]
	s_waitcnt lgkmcnt(7)
	v_mfma_f32_32x32x16_f16 v[50:65], v[232:235], v[224:227], v[50:65]
	v_mfma_f32_32x32x16_f16 v[34:49], v[236:239], v[224:227], v[34:49]
	s_waitcnt lgkmcnt(6)
; DI float sigmoid_(float x) { return 1.f / (1.f + __expf(-x)); }
; DI f16v mfma32(h8v a, h8v b, f16v c) { return __builtin_amdgcn_mfma_f32_32x32x16_f16(a, b, c, 0, 0, 0); }
; template <bool GATHER>
; DI void gemm256_main(const h16* __restrict__ A, int lda, const int* __restrict__ idx, int m0,
;                      const h16* __restrict__ B, int ldb, int n0, int K, h16* lds, f16v (&acc)[4][2]) {
;     ...
;     for (int ks = 0; ks < 4; ++ks) {
;       h8v af[4], bf[2];
; #pragma unroll
;       for (int i = 0; i < 4; ++i) af[i] = *(const h8v*)&As[(wm * 128 + i * 32 + (lane & 31)) * LDH + ks * 16 + 8 * (lane >> 5)];
; #pragma unroll
;       for (int j = 0; j < 2; ++j) bf[j] = *(const h8v*)&Bs[(wn * 64 + j * 32 + (lane & 31)) * LDH + ks * 16 + 8 * (lane >> 5)];
; #pragma unroll
;       for (int i = 0; i < 4; ++i)
; #pragma unroll
;         for (int j = 0; j < 2; ++j) acc[i][j] = mfma32(bf[j], af[i], acc[i][j]);
;     }
;     __syncthreads();
;   }
; DI void phase_gates(const Params& p, int bid, int nb, h16* lds) {
;     ...
;     gemm256_epilogue(acc, m0, n0, [&](int m, int n, f4v v0, f4v v1) {
;       f4v a, b;
; #pragma unroll
;       for (int i = 0; i < 4; ++i) { a[i] = sigmoid_(v0[i]); b[i] = sigmoid_(v1[i]); }
;       st_h4(&G[(size_t)m * 4096 + n], a); st_h4(&G[(size_t)m * 4096 + n + 32], b);
	v_mfma_f32_32x32x16_f16 v[18:33], v[232:235], v[228:231], v[18:33]
	v_mfma_f32_32x32x16_f16 v[2:17], v[236:239], v[228:231], v[2:17]
	ds_read_b128 v[232:235], v214 offset:64
	ds_read_b128 v[216:219], v212 offset:64
	ds_read_b128 v[236:239], v214 offset:4672
	ds_read_b128 v[220:223], v212 offset:4672
	ds_read_b128 v[224:227], v212 offset:9280
	ds_read_b128 v[228:231], v212 offset:13888
	s_waitcnt lgkmcnt(10)
	v_mfma_f32_32x32x16_f16 v[114:129], v[208:211], v[240:243], v[114:129]
	s_waitcnt lgkmcnt(9)
	v_mfma_f32_32x32x16_f16 v[98:113], v[174:177], v[240:243], v[98:113]
	s_waitcnt lgkmcnt(8)
	v_mfma_f32_32x32x16_f16 v[82:97], v[208:211], v[244:247], v[82:97]
	v_mfma_f32_32x32x16_f16 v[66:81], v[174:177], v[244:247], v[66:81]
	s_waitcnt lgkmcnt(7)
	v_mfma_f32_32x32x16_f16 v[50:65], v[208:211], v[248:251], v[50:65]
	v_mfma_f32_32x32x16_f16 v[34:49], v[174:177], v[248:251], v[34:49]
	s_waitcnt lgkmcnt(6)
	v_mfma_f32_32x32x16_f16 v[18:33], v[208:211], v[204:207], v[18:33]
	v_mfma_f32_32x32x16_f16 v[2:17], v[174:177], v[204:207], v[2:17]
	ds_read_b128 v[208:211], v214 offset:96
	ds_read_b128 v[240:243], v212 offset:96
	ds_read_b128 v[174:177], v214 offset:4704
	ds_read_b128 v[244:247], v212 offset:4704
	ds_read_b128 v[248:251], v212 offset:9312
	ds_read_b128 v[204:207], v212 offset:13920
	s_waitcnt lgkmcnt(10)
	v_mfma_f32_32x32x16_f16 v[114:129], v[232:235], v[216:219], v[114:129]
	s_waitcnt lgkmcnt(9)
	v_mfma_f32_32x32x16_f16 v[98:113], v[236:239], v[216:219], v[98:113]
	s_waitcnt lgkmcnt(8)
	v_mfma_f32_32x32x16_f16 v[82:97], v[232:235], v[220:223], v[82:97]
	v_mfma_f32_32x32x16_f16 v[66:81], v[236:239], v[220:223], v[66:81]
	s_waitcnt lgkmcnt(7)
	v_mfma_f32_32x32x16_f16 v[50:65], v[232:235], v[224:227], v[50:65]
	v_mfma_f32_32x32x16_f16 v[34:49], v[236:239], v[224:227], v[34:49]
	s_waitcnt lgkmcnt(6)
	v_mfma_f32_32x32x16_f16 v[18:33], v[232:235], v[228:231], v[18:33]
	v_mfma_f32_32x32x16_f16 v[2:17], v[236:239], v[228:231], v[2:17]
	s_waitcnt lgkmcnt(0)
	v_mfma_f32_32x32x16_f16 v[114:129], v[208:211], v[240:243], v[114:129]
	v_mfma_f32_32x32x16_f16 v[98:113], v[174:177], v[240:243], v[98:113]
	v_mfma_f32_32x32x16_f16 v[82:97], v[208:211], v[244:247], v[82:97]
	v_mfma_f32_32x32x16_f16 v[66:81], v[174:177], v[244:247], v[66:81]
	v_mfma_f32_32x32x16_f16 v[50:65], v[208:211], v[248:251], v[50:65]
	v_mfma_f32_32x32x16_f16 v[34:49], v[174:177], v[248:251], v[34:49]
	v_mfma_f32_32x32x16_f16 v[18:33], v[208:211], v[204:207], v[18:33]
	v_mfma_f32_32x32x16_f16 v[2:17], v[174:177], v[204:207], v[2:17]
	s_nop 15
	v_mov_b32_e32 v192, 0x7f800000
	v_mov_b32_e32 v193, 0x7fc00000
	v_mov_b32_e32 v194, 0xff800000
	v_mov_b32_e32 v204, 0x7fffec00
	v_mov_b32_e32 v205, 0xff7fc99e
	v_mov_b32_e32 v206, 0x840000
	v_mov_b32_e32 v207, 0xb00000
	v_mov_b32_e32 v208, 0xdc0000
	v_mov_b32_e32 v209, 0x1080000
	v_mov_b32_e32 v210, 0x1340000
	v_mov_b32_e32 v211, 0x420000
	v_mov_b32_e32 v212, 0x580000
	v_mov_b32_e32 v213, 0x6e0000
	v_mov_b32_e32 v214, 0x9a0000
	s_setprio 0
	s_cselect_b32 s60, 1, 0
	s_barrier
	v_readfirstlane_b32 s66, v180
	s_mov_b32 s69, s5
	s_mov_b32 s65, s6
	s_lshr_b32 s66, s66, 6
	s_and_b32 s67, s66, 3
	s_lshr_b32 s68, s66, 2
	s_lshl_b32 s70, s67, 6
	s_add_i32 s70, s70, s69
	s_lshl_b32 s71, s68, 7
	s_add_i32 s71, s71, s65
	s_mul_i32 s72, s66, 0x4800
	s_add_i32 s72, s72, 16
	s_mov_b32 s73, 0x2000
	v_and_b32_e32 v146, 63, v180
	v_and_b32_e32 v148, 31, v146
	v_lshrrev_b32_e32 v147, 5, v146
	v_mul_u32_u24_e32 v130, 0x90, v148
	v_lshl_add_u32 v130, v147, 3, v130
	v_add_u32_e32 v130, s72, v130
	v_lshrrev_b32_e32 v149, 3, v146
	v_and_b32_e32 v138, 7, v146
	v_mul_u32_u24_e32 v131, 0x90, v149
	v_lshl_add_u32 v131, v138, 4, v131
	v_add_u32_e32 v131, s72, v131
	v_add_u32_e32 v140, s71, v149
	v_lshl_add_u32 v138, v138, 3, s70
	v_mov_b64_e32 v[132:133], s[0:1]
	v_mad_u64_u32 v[132:133], s[74:75], v140, s73, v[132:133]
	v_lshlrev_b32_e32 v138, 1, v138
	v_mov_b32_e32 v139, v0
	v_lshl_add_u64 v[132:133], v[132:133], 0, v[138:139]
	s_mov_b32 s76, 0x10000
	s_mov_b32 s77, 0
	v_mul_f32_e32 v114, 0xbfb8aa3b, v114
	v_mul_f32_e32 v115, 0xbfb8aa3b, v115
	v_mul_f32_e32 v116, 0xbfb8aa3b, v116
	v_mul_f32_e32 v117, 0xbfb8aa3b, v117
	v_exp_f32_e32 v114, v114
	v_exp_f32_e32 v115, v115
	v_exp_f32_e32 v116, v116
	v_exp_f32_e32 v117, v117
	v_add_f32_e32 v114, 1.0, v114
	v_add_f32_e32 v115, 1.0, v115
	v_add_f32_e32 v116, 1.0, v116
	v_add_f32_e32 v117, 1.0, v117
	v_rcp_f32_e32 v114, v114
	v_rcp_f32_e32 v115, v115
	v_rcp_f32_e32 v116, v116
	v_rcp_f32_e32 v117, v117
	v_cvt_pk_f16_f32 v138, v114, v115
	v_cvt_pk_f16_f32 v139, v116, v117
	ds_write_b64 v130, v[138:139] offset:0
	v_mul_f32_e32 v98, 0xbfb8aa3b, v98
	v_mul_f32_e32 v99, 0xbfb8aa3b, v99
	v_mul_f32_e32 v100, 0xbfb8aa3b, v100
	v_mul_f32_e32 v101, 0xbfb8aa3b, v101
	v_exp_f32_e32 v98, v98
	v_exp_f32_e32 v99, v99
	v_exp_f32_e32 v100, v100
	v_exp_f32_e32 v101, v101
	v_add_f32_e32 v98, 1.0, v98
	v_add_f32_e32 v99, 1.0, v99
	v_add_f32_e32 v100, 1.0, v100
	v_add_f32_e32 v101, 1.0, v101
	v_rcp_f32_e32 v98, v98
	v_rcp_f32_e32 v99, v99
	v_rcp_f32_e32 v100, v100
	v_rcp_f32_e32 v101, v101
	v_cvt_pk_f16_f32 v140, v98, v99
	v_cvt_pk_f16_f32 v141, v100, v101
	ds_write_b64 v130, v[140:141] offset:64
	v_mul_f32_e32 v118, 0xbfb8aa3b, v118
	v_mul_f32_e32 v119, 0xbfb8aa3b, v119
	v_mul_f32_e32 v120, 0xbfb8aa3b, v120
	v_mul_f32_e32 v121, 0xbfb8aa3b, v121
	v_exp_f32_e32 v118, v118
	v_exp_f32_e32 v119, v119
	v_exp_f32_e32 v120, v120
	v_exp_f32_e32 v121, v121
	v_add_f32_e32 v118, 1.0, v118
	v_add_f32_e32 v119, 1.0, v119
	v_add_f32_e32 v120, 1.0, v120
	v_add_f32_e32 v121, 1.0, v121
	v_rcp_f32_e32 v118, v118
	v_rcp_f32_e32 v119, v119
	v_rcp_f32_e32 v120, v120
; DI int otid512() { int t = threadIdx.x; asm volatile("" : "+v"(t)); return t; }
; DI float sigmoid_(float x) { return 1.f / (1.f + __expf(-x)); }
; template <class Epi>
; DI void gemm256_epilogue(f16v (&acc)[4][2], int m0, int n0, Epi epi) {
;   const int tid = otid512(), lane = tid & 63, wv = tid >> 6, wm = wv >> 2, wn = wv & 3, h = lane >> 5;
; #pragma unroll
;   for (int i = 0; i < 4; ++i) {
;     const int m = m0 + wm * 128 + i * 32 + (lane & 31);
; #pragma unroll
;     for (int g = 0; g < 4; ++g) {
;       const int n = n0 + wn * 64 + 8 * g + 4 * h;
;       f4v v0 = {acc[i][0][4 * g], acc[i][0][4 * g + 1], acc[i][0][4 * g + 2], acc[i][0][4 * g + 3]};
;       f4v v1 = {acc[i][1][4 * g], acc[i][1][4 * g + 1], acc[i][1][4 * g + 2], acc[i][1][4 * g + 3]};
;       epi(m, n, v0, v1);
;     }
;   }
; }
; DI void phase_gates(const Params& p, int bid, int nb, h16* lds) {
;     ...
;     gemm256_epilogue(acc, m0, n0, [&](int m, int n, f4v v0, f4v v1) {
;       f4v a, b;
; #pragma unroll
;       for (int i = 0; i < 4; ++i) { a[i] = sigmoid_(v0[i]); b[i] = sigmoid_(v1[i]); }
;       st_h4(&G[(size_t)m * 4096 + n], a); st_h4(&G[(size_t)m * 4096 + n + 32], b);
	v_rcp_f32_e32 v121, v121
	v_cvt_pk_f16_f32 v142, v118, v119
	v_cvt_pk_f16_f32 v143, v120, v121
	ds_write_b64 v130, v[142:143] offset:16
	v_mul_f32_e32 v102, 0xbfb8aa3b, v102
	v_mul_f32_e32 v103, 0xbfb8aa3b, v103
	v_mul_f32_e32 v104, 0xbfb8aa3b, v104
	v_mul_f32_e32 v105, 0xbfb8aa3b, v105
	v_exp_f32_e32 v102, v102
	v_exp_f32_e32 v103, v103
	v_exp_f32_e32 v104, v104
	v_exp_f32_e32 v105, v105
	v_add_f32_e32 v102, 1.0, v102
	v_add_f32_e32 v103, 1.0, v103
	v_add_f32_e32 v104, 1.0, v104
	v_add_f32_e32 v105, 1.0, v105
	v_rcp_f32_e32 v102, v102
	v_rcp_f32_e32 v103, v103
	v_rcp_f32_e32 v104, v104
	v_rcp_f32_e32 v105, v105
	v_cvt_pk_f16_f32 v144, v102, v103
	v_cvt_pk_f16_f32 v145, v104, v105
	ds_write_b64 v130, v[144:145] offset:80
	v_mul_f32_e32 v122, 0xbfb8aa3b, v122
	v_mul_f32_e32 v123, 0xbfb8aa3b, v123
	v_mul_f32_e32 v124, 0xbfb8aa3b, v124
	v_mul_f32_e32 v125, 0xbfb8aa3b, v125
	v_exp_f32_e32 v122, v122
	v_exp_f32_e32 v123, v123
	v_exp_f32_e32 v124, v124
	v_exp_f32_e32 v125, v125
	v_add_f32_e32 v122, 1.0, v122
	v_add_f32_e32 v123, 1.0, v123
	v_add_f32_e32 v124, 1.0, v124
	v_add_f32_e32 v125, 1.0, v125
	v_rcp_f32_e32 v122, v122
	v_rcp_f32_e32 v123, v123
	v_rcp_f32_e32 v124, v124
	v_rcp_f32_e32 v125, v125
	v_cvt_pk_f16_f32 v138, v122, v123
	v_cvt_pk_f16_f32 v139, v124, v125
	ds_write_b64 v130, v[138:139] offset:32
	v_mul_f32_e32 v106, 0xbfb8aa3b, v106
	v_mul_f32_e32 v107, 0xbfb8aa3b, v107
	v_mul_f32_e32 v108, 0xbfb8aa3b, v108
	v_mul_f32_e32 v109, 0xbfb8aa3b, v109
	v_exp_f32_e32 v106, v106
	v_exp_f32_e32 v107, v107
	v_exp_f32_e32 v108, v108
	v_exp_f32_e32 v109, v109
	v_add_f32_e32 v106, 1.0, v106
	v_add_f32_e32 v107, 1.0, v107
	v_add_f32_e32 v108, 1.0, v108
	v_add_f32_e32 v109, 1.0, v109
	v_rcp_f32_e32 v106, v106
	v_rcp_f32_e32 v107, v107
	v_rcp_f32_e32 v108, v108
	v_rcp_f32_e32 v109, v109
	v_cvt_pk_f16_f32 v140, v106, v107
	v_cvt_pk_f16_f32 v141, v108, v109
	ds_write_b64 v130, v[140:141] offset:96
	v_mul_f32_e32 v126, 0xbfb8aa3b, v126
	v_mul_f32_e32 v127, 0xbfb8aa3b, v127
	v_mul_f32_e32 v128, 0xbfb8aa3b, v128
	v_mul_f32_e32 v129, 0xbfb8aa3b, v129
	v_exp_f32_e32 v126, v126
	v_exp_f32_e32 v127, v127
	v_exp_f32_e32 v128, v128
	v_exp_f32_e32 v129, v129
	v_add_f32_e32 v126, 1.0, v126
	v_add_f32_e32 v127, 1.0, v127
	v_add_f32_e32 v128, 1.0, v128
	v_add_f32_e32 v129, 1.0, v129
	v_rcp_f32_e32 v126, v126
	v_rcp_f32_e32 v127, v127
	v_rcp_f32_e32 v128, v128
	v_rcp_f32_e32 v129, v129
	v_cvt_pk_f16_f32 v142, v126, v127
	v_cvt_pk_f16_f32 v143, v128, v129
	ds_write_b64 v130, v[142:143] offset:48
	v_mul_f32_e32 v110, 0xbfb8aa3b, v110
	v_mul_f32_e32 v111, 0xbfb8aa3b, v111
	v_mul_f32_e32 v112, 0xbfb8aa3b, v112
	v_mul_f32_e32 v113, 0xbfb8aa3b, v113
	v_exp_f32_e32 v110, v110
	v_exp_f32_e32 v111, v111
	v_exp_f32_e32 v112, v112
	v_exp_f32_e32 v113, v113
	v_add_f32_e32 v110, 1.0, v110
	v_add_f32_e32 v111, 1.0, v111
	v_add_f32_e32 v112, 1.0, v112
	v_add_f32_e32 v113, 1.0, v113
	v_rcp_f32_e32 v110, v110
	v_rcp_f32_e32 v111, v111
	v_rcp_f32_e32 v112, v112
	v_rcp_f32_e32 v113, v113
	v_cvt_pk_f16_f32 v144, v110, v111
	v_cvt_pk_f16_f32 v145, v112, v113
	ds_write_b64 v130, v[144:145] offset:112
	v_mul_f32_e32 v82, 0xbfb8aa3b, v82
	v_mul_f32_e32 v83, 0xbfb8aa3b, v83
	v_mul_f32_e32 v84, 0xbfb8aa3b, v84
	v_mul_f32_e32 v85, 0xbfb8aa3b, v85
	v_exp_f32_e32 v82, v82
	v_exp_f32_e32 v83, v83
	v_exp_f32_e32 v84, v84
	v_exp_f32_e32 v85, v85
	v_add_f32_e32 v82, 1.0, v82
	v_add_f32_e32 v83, 1.0, v83
	v_add_f32_e32 v84, 1.0, v84
	v_add_f32_e32 v85, 1.0, v85
	v_rcp_f32_e32 v82, v82
	v_rcp_f32_e32 v83, v83
	v_rcp_f32_e32 v84, v84
	v_rcp_f32_e32 v85, v85
	v_cvt_pk_f16_f32 v138, v82, v83
	v_cvt_pk_f16_f32 v139, v84, v85
	ds_write_b64 v130, v[138:139] offset:4608
	v_mul_f32_e32 v66, 0xbfb8aa3b, v66
	v_mul_f32_e32 v67, 0xbfb8aa3b, v67
	v_mul_f32_e32 v68, 0xbfb8aa3b, v68
	v_mul_f32_e32 v69, 0xbfb8aa3b, v69
	v_exp_f32_e32 v66, v66
	v_exp_f32_e32 v67, v67
	v_exp_f32_e32 v68, v68
	v_exp_f32_e32 v69, v69
	v_add_f32_e32 v66, 1.0, v66
	v_add_f32_e32 v67, 1.0, v67
	v_add_f32_e32 v68, 1.0, v68
	v_add_f32_e32 v69, 1.0, v69
	v_rcp_f32_e32 v66, v66
	v_rcp_f32_e32 v67, v67
	v_rcp_f32_e32 v68, v68
	v_rcp_f32_e32 v69, v69
	v_cvt_pk_f16_f32 v140, v66, v67
	v_cvt_pk_f16_f32 v141, v68, v69
	ds_write_b64 v130, v[140:141] offset:4672
	v_mul_f32_e32 v86, 0xbfb8aa3b, v86
	v_mul_f32_e32 v87, 0xbfb8aa3b, v87
	v_mul_f32_e32 v88, 0xbfb8aa3b, v88
	v_mul_f32_e32 v89, 0xbfb8aa3b, v89
	v_exp_f32_e32 v86, v86
	v_exp_f32_e32 v87, v87
	v_exp_f32_e32 v88, v88
	v_exp_f32_e32 v89, v89
	v_add_f32_e32 v86, 1.0, v86
	v_add_f32_e32 v87, 1.0, v87
	v_add_f32_e32 v88, 1.0, v88
	v_add_f32_e32 v89, 1.0, v89
	v_rcp_f32_e32 v86, v86
	v_rcp_f32_e32 v87, v87
	v_rcp_f32_e32 v88, v88
	v_rcp_f32_e32 v89, v89
	v_cvt_pk_f16_f32 v142, v86, v87
	v_cvt_pk_f16_f32 v143, v88, v89
	ds_write_b64 v130, v[142:143] offset:4624
	v_mul_f32_e32 v70, 0xbfb8aa3b, v70
	v_mul_f32_e32 v71, 0xbfb8aa3b, v71
	v_mul_f32_e32 v72, 0xbfb8aa3b, v72
	v_mul_f32_e32 v73, 0xbfb8aa3b, v73
	v_exp_f32_e32 v70, v70
	v_exp_f32_e32 v71, v71
	v_exp_f32_e32 v72, v72
	v_exp_f32_e32 v73, v73
	v_add_f32_e32 v70, 1.0, v70
	v_add_f32_e32 v71, 1.0, v71
	v_add_f32_e32 v72, 1.0, v72
	v_add_f32_e32 v73, 1.0, v73
	v_rcp_f32_e32 v70, v70
	v_rcp_f32_e32 v71, v71
	v_rcp_f32_e32 v72, v72
	v_rcp_f32_e32 v73, v73
	v_cvt_pk_f16_f32 v144, v70, v71
	v_cvt_pk_f16_f32 v145, v72, v73
	ds_write_b64 v130, v[144:145] offset:4688
	v_mul_f32_e32 v90, 0xbfb8aa3b, v90
	v_mul_f32_e32 v91, 0xbfb8aa3b, v91
	v_mul_f32_e32 v92, 0xbfb8aa3b, v92
	v_mul_f32_e32 v93, 0xbfb8aa3b, v93
	v_exp_f32_e32 v90, v90
	v_exp_f32_e32 v91, v91
	v_exp_f32_e32 v92, v92
	v_exp_f32_e32 v93, v93
	v_add_f32_e32 v90, 1.0, v90
; DI int otid512() { int t = threadIdx.x; asm volatile("" : "+v"(t)); return t; }
; DI float sigmoid_(float x) { return 1.f / (1.f + __expf(-x)); }
; template <class Epi>
; DI void gemm256_epilogue(f16v (&acc)[4][2], int m0, int n0, Epi epi) {
;   const int tid = otid512(), lane = tid & 63, wv = tid >> 6, wm = wv >> 2, wn = wv & 3, h = lane >> 5;
; #pragma unroll
;   for (int i = 0; i < 4; ++i) {
;     const int m = m0 + wm * 128 + i * 32 + (lane & 31);
; #pragma unroll
;     for (int g = 0; g < 4; ++g) {
;       const int n = n0 + wn * 64 + 8 * g + 4 * h;
;       f4v v0 = {acc[i][0][4 * g], acc[i][0][4 * g + 1], acc[i][0][4 * g + 2], acc[i][0][4 * g + 3]};
;       f4v v1 = {acc[i][1][4 * g], acc[i][1][4 * g + 1], acc[i][1][4 * g + 2], acc[i][1][4 * g + 3]};
;       epi(m, n, v0, v1);
;     }
;   }
; }
; DI void phase_gates(const Params& p, int bid, int nb, h16* lds) {
;     ...
;     gemm256_epilogue(acc, m0, n0, [&](int m, int n, f4v v0, f4v v1) {
;       f4v a, b;
; #pragma unroll
;       for (int i = 0; i < 4; ++i) { a[i] = sigmoid_(v0[i]); b[i] = sigmoid_(v1[i]); }
;       st_h4(&G[(size_t)m * 4096 + n], a); st_h4(&G[(size_t)m * 4096 + n + 32], b);
	v_add_f32_e32 v91, 1.0, v91
	v_add_f32_e32 v92, 1.0, v92
	v_add_f32_e32 v93, 1.0, v93
	v_rcp_f32_e32 v90, v90
	v_rcp_f32_e32 v91, v91
	v_rcp_f32_e32 v92, v92
	v_rcp_f32_e32 v93, v93
	v_cvt_pk_f16_f32 v138, v90, v91
	v_cvt_pk_f16_f32 v139, v92, v93
	ds_write_b64 v130, v[138:139] offset:4640
	v_mul_f32_e32 v74, 0xbfb8aa3b, v74
	v_mul_f32_e32 v75, 0xbfb8aa3b, v75
	v_mul_f32_e32 v76, 0xbfb8aa3b, v76
	v_mul_f32_e32 v77, 0xbfb8aa3b, v77
	v_exp_f32_e32 v74, v74
	v_exp_f32_e32 v75, v75
	v_exp_f32_e32 v76, v76
	v_exp_f32_e32 v77, v77
	v_add_f32_e32 v74, 1.0, v74
	v_add_f32_e32 v75, 1.0, v75
	v_add_f32_e32 v76, 1.0, v76
	v_add_f32_e32 v77, 1.0, v77
	v_rcp_f32_e32 v74, v74
	v_rcp_f32_e32 v75, v75
	v_rcp_f32_e32 v76, v76
	v_rcp_f32_e32 v77, v77
	v_cvt_pk_f16_f32 v140, v74, v75
	v_cvt_pk_f16_f32 v141, v76, v77
	ds_write_b64 v130, v[140:141] offset:4704
	v_mul_f32_e32 v94, 0xbfb8aa3b, v94
	v_mul_f32_e32 v95, 0xbfb8aa3b, v95
	v_mul_f32_e32 v96, 0xbfb8aa3b, v96
	v_mul_f32_e32 v97, 0xbfb8aa3b, v97
	v_exp_f32_e32 v94, v94
	v_exp_f32_e32 v95, v95
	v_exp_f32_e32 v96, v96
	v_exp_f32_e32 v97, v97
	v_add_f32_e32 v94, 1.0, v94
	v_add_f32_e32 v95, 1.0, v95
	v_add_f32_e32 v96, 1.0, v96
	v_add_f32_e32 v97, 1.0, v97
	v_rcp_f32_e32 v94, v94
	v_rcp_f32_e32 v95, v95
	v_rcp_f32_e32 v96, v96
	v_rcp_f32_e32 v97, v97
	v_cvt_pk_f16_f32 v142, v94, v95
	v_cvt_pk_f16_f32 v143, v96, v97
	ds_write_b64 v130, v[142:143] offset:4656
	v_mul_f32_e32 v78, 0xbfb8aa3b, v78
	v_mul_f32_e32 v79, 0xbfb8aa3b, v79
	v_mul_f32_e32 v80, 0xbfb8aa3b, v80
	v_mul_f32_e32 v81, 0xbfb8aa3b, v81
	v_exp_f32_e32 v78, v78
	v_exp_f32_e32 v79, v79
	v_exp_f32_e32 v80, v80
	v_exp_f32_e32 v81, v81
	v_add_f32_e32 v78, 1.0, v78
	v_add_f32_e32 v79, 1.0, v79
	v_add_f32_e32 v80, 1.0, v80
	v_add_f32_e32 v81, 1.0, v81
	v_rcp_f32_e32 v78, v78
	v_rcp_f32_e32 v79, v79
	v_rcp_f32_e32 v80, v80
	v_rcp_f32_e32 v81, v81
	v_cvt_pk_f16_f32 v144, v78, v79
	v_cvt_pk_f16_f32 v145, v80, v81
	ds_write_b64 v130, v[144:145] offset:4720
	v_mul_f32_e32 v50, 0xbfb8aa3b, v50
	v_mul_f32_e32 v51, 0xbfb8aa3b, v51
	v_mul_f32_e32 v52, 0xbfb8aa3b, v52
	v_mul_f32_e32 v53, 0xbfb8aa3b, v53
	v_exp_f32_e32 v50, v50
	v_exp_f32_e32 v51, v51
	v_exp_f32_e32 v52, v52
	v_exp_f32_e32 v53, v53
	v_add_f32_e32 v50, 1.0, v50
	v_add_f32_e32 v51, 1.0, v51
	v_add_f32_e32 v52, 1.0, v52
	v_add_f32_e32 v53, 1.0, v53
	v_rcp_f32_e32 v50, v50
	v_rcp_f32_e32 v51, v51
	v_rcp_f32_e32 v52, v52
	v_rcp_f32_e32 v53, v53
	v_cvt_pk_f16_f32 v138, v50, v51
	v_cvt_pk_f16_f32 v139, v52, v53
	ds_write_b64 v130, v[138:139] offset:9216
	v_mul_f32_e32 v34, 0xbfb8aa3b, v34
	v_mul_f32_e32 v35, 0xbfb8aa3b, v35
	v_mul_f32_e32 v36, 0xbfb8aa3b, v36
	v_mul_f32_e32 v37, 0xbfb8aa3b, v37
	v_exp_f32_e32 v34, v34
	v_exp_f32_e32 v35, v35
	v_exp_f32_e32 v36, v36
	v_exp_f32_e32 v37, v37
	v_add_f32_e32 v34, 1.0, v34
	v_add_f32_e32 v35, 1.0, v35
	v_add_f32_e32 v36, 1.0, v36
	v_add_f32_e32 v37, 1.0, v37
	v_rcp_f32_e32 v34, v34
	v_rcp_f32_e32 v35, v35
	v_rcp_f32_e32 v36, v36
	v_rcp_f32_e32 v37, v37
	v_cvt_pk_f16_f32 v140, v34, v35
	v_cvt_pk_f16_f32 v141, v36, v37
	ds_write_b64 v130, v[140:141] offset:9280
	v_mul_f32_e32 v54, 0xbfb8aa3b, v54
	v_mul_f32_e32 v55, 0xbfb8aa3b, v55
	v_mul_f32_e32 v56, 0xbfb8aa3b, v56
	v_mul_f32_e32 v57, 0xbfb8aa3b, v57
	v_exp_f32_e32 v54, v54
	v_exp_f32_e32 v55, v55
	v_exp_f32_e32 v56, v56
	v_exp_f32_e32 v57, v57
	v_add_f32_e32 v54, 1.0, v54
	v_add_f32_e32 v55, 1.0, v55
	v_add_f32_e32 v56, 1.0, v56
	v_add_f32_e32 v57, 1.0, v57
	v_rcp_f32_e32 v54, v54
	v_rcp_f32_e32 v55, v55
	v_rcp_f32_e32 v56, v56
	v_rcp_f32_e32 v57, v57
	v_cvt_pk_f16_f32 v142, v54, v55
	v_cvt_pk_f16_f32 v143, v56, v57
	ds_write_b64 v130, v[142:143] offset:9232
	v_mul_f32_e32 v38, 0xbfb8aa3b, v38
	v_mul_f32_e32 v39, 0xbfb8aa3b, v39
	v_mul_f32_e32 v40, 0xbfb8aa3b, v40
	v_mul_f32_e32 v41, 0xbfb8aa3b, v41
	v_exp_f32_e32 v38, v38
	v_exp_f32_e32 v39, v39
	v_exp_f32_e32 v40, v40
	v_exp_f32_e32 v41, v41
	v_add_f32_e32 v38, 1.0, v38
	v_add_f32_e32 v39, 1.0, v39
	v_add_f32_e32 v40, 1.0, v40
	v_add_f32_e32 v41, 1.0, v41
	v_rcp_f32_e32 v38, v38
	v_rcp_f32_e32 v39, v39
	v_rcp_f32_e32 v40, v40
	v_rcp_f32_e32 v41, v41
	v_cvt_pk_f16_f32 v144, v38, v39
	v_cvt_pk_f16_f32 v145, v40, v41
	ds_write_b64 v130, v[144:145] offset:9296
	v_mul_f32_e32 v58, 0xbfb8aa3b, v58
	v_mul_f32_e32 v59, 0xbfb8aa3b, v59
	v_mul_f32_e32 v60, 0xbfb8aa3b, v60
	v_mul_f32_e32 v61, 0xbfb8aa3b, v61
	v_exp_f32_e32 v58, v58
	v_exp_f32_e32 v59, v59
	v_exp_f32_e32 v60, v60
	v_exp_f32_e32 v61, v61
	v_add_f32_e32 v58, 1.0, v58
	v_add_f32_e32 v59, 1.0, v59
	v_add_f32_e32 v60, 1.0, v60
	v_add_f32_e32 v61, 1.0, v61
	v_rcp_f32_e32 v58, v58
	v_rcp_f32_e32 v59, v59
	v_rcp_f32_e32 v60, v60
	v_rcp_f32_e32 v61, v61
	v_cvt_pk_f16_f32 v138, v58, v59
	v_cvt_pk_f16_f32 v139, v60, v61
	ds_write_b64 v130, v[138:139] offset:9248
	v_mul_f32_e32 v42, 0xbfb8aa3b, v42
	v_mul_f32_e32 v43, 0xbfb8aa3b, v43
	v_mul_f32_e32 v44, 0xbfb8aa3b, v44
	v_mul_f32_e32 v45, 0xbfb8aa3b, v45
	v_exp_f32_e32 v42, v42
	v_exp_f32_e32 v43, v43
	v_exp_f32_e32 v44, v44
	v_exp_f32_e32 v45, v45
	v_add_f32_e32 v42, 1.0, v42
	v_add_f32_e32 v43, 1.0, v43
	v_add_f32_e32 v44, 1.0, v44
	v_add_f32_e32 v45, 1.0, v45
	v_rcp_f32_e32 v42, v42
	v_rcp_f32_e32 v43, v43
	v_rcp_f32_e32 v44, v44
	v_rcp_f32_e32 v45, v45
	v_cvt_pk_f16_f32 v140, v42, v43
	v_cvt_pk_f16_f32 v141, v44, v45
	ds_write_b64 v130, v[140:141] offset:9312
	v_mul_f32_e32 v62, 0xbfb8aa3b, v62
	v_mul_f32_e32 v63, 0xbfb8aa3b, v63
	v_mul_f32_e32 v64, 0xbfb8aa3b, v64
	v_mul_f32_e32 v65, 0xbfb8aa3b, v65
	v_exp_f32_e32 v62, v62
	v_exp_f32_e32 v63, v63
	v_exp_f32_e32 v64, v64
	v_exp_f32_e32 v65, v65
	v_add_f32_e32 v62, 1.0, v62
	v_add_f32_e32 v63, 1.0, v63
; DI int otid512() { int t = threadIdx.x; asm volatile("" : "+v"(t)); return t; }
; DI float sigmoid_(float x) { return 1.f / (1.f + __expf(-x)); }
; template <class Epi>
; DI void gemm256_epilogue(f16v (&acc)[4][2], int m0, int n0, Epi epi) {
;   const int tid = otid512(), lane = tid & 63, wv = tid >> 6, wm = wv >> 2, wn = wv & 3, h = lane >> 5;
; #pragma unroll
;   for (int i = 0; i < 4; ++i) {
;     const int m = m0 + wm * 128 + i * 32 + (lane & 31);
; #pragma unroll
;     for (int g = 0; g < 4; ++g) {
;       const int n = n0 + wn * 64 + 8 * g + 4 * h;
;       f4v v0 = {acc[i][0][4 * g], acc[i][0][4 * g + 1], acc[i][0][4 * g + 2], acc[i][0][4 * g + 3]};
;       f4v v1 = {acc[i][1][4 * g], acc[i][1][4 * g + 1], acc[i][1][4 * g + 2], acc[i][1][4 * g + 3]};
;       epi(m, n, v0, v1);
;     }
;   }
; }
; DI void phase_gates(const Params& p, int bid, int nb, h16* lds) {
;     ...
;     gemm256_epilogue(acc, m0, n0, [&](int m, int n, f4v v0, f4v v1) {
;       f4v a, b;
; #pragma unroll
;       for (int i = 0; i < 4; ++i) { a[i] = sigmoid_(v0[i]); b[i] = sigmoid_(v1[i]); }
;       st_h4(&G[(size_t)m * 4096 + n], a); st_h4(&G[(size_t)m * 4096 + n + 32], b);
	v_add_f32_e32 v64, 1.0, v64
	v_add_f32_e32 v65, 1.0, v65
	v_rcp_f32_e32 v62, v62
	v_rcp_f32_e32 v63, v63
	v_rcp_f32_e32 v64, v64
	v_rcp_f32_e32 v65, v65
	v_cvt_pk_f16_f32 v142, v62, v63
	v_cvt_pk_f16_f32 v143, v64, v65
	ds_write_b64 v130, v[142:143] offset:9264
	v_mul_f32_e32 v46, 0xbfb8aa3b, v46
	v_mul_f32_e32 v47, 0xbfb8aa3b, v47
	v_mul_f32_e32 v48, 0xbfb8aa3b, v48
	v_mul_f32_e32 v49, 0xbfb8aa3b, v49
	v_exp_f32_e32 v46, v46
	v_exp_f32_e32 v47, v47
	v_exp_f32_e32 v48, v48
	v_exp_f32_e32 v49, v49
	v_add_f32_e32 v46, 1.0, v46
	v_add_f32_e32 v47, 1.0, v47
	v_add_f32_e32 v48, 1.0, v48
	v_add_f32_e32 v49, 1.0, v49
	v_rcp_f32_e32 v46, v46
	v_rcp_f32_e32 v47, v47
	v_rcp_f32_e32 v48, v48
	v_rcp_f32_e32 v49, v49
	v_cvt_pk_f16_f32 v144, v46, v47
	v_cvt_pk_f16_f32 v145, v48, v49
	ds_write_b64 v130, v[144:145] offset:9328
	v_mul_f32_e32 v18, 0xbfb8aa3b, v18
	v_mul_f32_e32 v19, 0xbfb8aa3b, v19
	v_mul_f32_e32 v20, 0xbfb8aa3b, v20
	v_mul_f32_e32 v21, 0xbfb8aa3b, v21
	v_exp_f32_e32 v18, v18
	v_exp_f32_e32 v19, v19
	v_exp_f32_e32 v20, v20
	v_exp_f32_e32 v21, v21
	v_add_f32_e32 v18, 1.0, v18
	v_add_f32_e32 v19, 1.0, v19
	v_add_f32_e32 v20, 1.0, v20
	v_add_f32_e32 v21, 1.0, v21
	v_rcp_f32_e32 v18, v18
	v_rcp_f32_e32 v19, v19
	v_rcp_f32_e32 v20, v20
	v_rcp_f32_e32 v21, v21
	v_cvt_pk_f16_f32 v138, v18, v19
	v_cvt_pk_f16_f32 v139, v20, v21
	ds_write_b64 v130, v[138:139] offset:13824
	v_mul_f32_e32 v2, 0xbfb8aa3b, v2
	v_mul_f32_e32 v3, 0xbfb8aa3b, v3
	v_mul_f32_e32 v4, 0xbfb8aa3b, v4
	v_mul_f32_e32 v5, 0xbfb8aa3b, v5
	v_exp_f32_e32 v2, v2
	v_exp_f32_e32 v3, v3
	v_exp_f32_e32 v4, v4
	v_exp_f32_e32 v5, v5
	v_add_f32_e32 v2, 1.0, v2
	v_add_f32_e32 v3, 1.0, v3
	v_add_f32_e32 v4, 1.0, v4
	v_add_f32_e32 v5, 1.0, v5
	v_rcp_f32_e32 v2, v2
	v_rcp_f32_e32 v3, v3
	v_rcp_f32_e32 v4, v4
	v_rcp_f32_e32 v5, v5
	v_cvt_pk_f16_f32 v140, v2, v3
	v_cvt_pk_f16_f32 v141, v4, v5
	ds_write_b64 v130, v[140:141] offset:13888
	v_mul_f32_e32 v22, 0xbfb8aa3b, v22
	v_mul_f32_e32 v23, 0xbfb8aa3b, v23
	v_mul_f32_e32 v24, 0xbfb8aa3b, v24
	v_mul_f32_e32 v25, 0xbfb8aa3b, v25
	v_exp_f32_e32 v22, v22
	v_exp_f32_e32 v23, v23
	v_exp_f32_e32 v24, v24
	v_exp_f32_e32 v25, v25
	v_add_f32_e32 v22, 1.0, v22
	v_add_f32_e32 v23, 1.0, v23
	v_add_f32_e32 v24, 1.0, v24
	v_add_f32_e32 v25, 1.0, v25
	v_rcp_f32_e32 v22, v22
	v_rcp_f32_e32 v23, v23
	v_rcp_f32_e32 v24, v24
	v_rcp_f32_e32 v25, v25
	v_cvt_pk_f16_f32 v142, v22, v23
	v_cvt_pk_f16_f32 v143, v24, v25
	ds_write_b64 v130, v[142:143] offset:13840
	v_mul_f32_e32 v6, 0xbfb8aa3b, v6
	v_mul_f32_e32 v7, 0xbfb8aa3b, v7
	v_mul_f32_e32 v8, 0xbfb8aa3b, v8
	v_mul_f32_e32 v9, 0xbfb8aa3b, v9
	v_exp_f32_e32 v6, v6
	v_exp_f32_e32 v7, v7
	v_exp_f32_e32 v8, v8
	v_exp_f32_e32 v9, v9
	v_add_f32_e32 v6, 1.0, v6
	v_add_f32_e32 v7, 1.0, v7
	v_add_f32_e32 v8, 1.0, v8
	v_add_f32_e32 v9, 1.0, v9
	v_rcp_f32_e32 v6, v6
	v_rcp_f32_e32 v7, v7
	v_rcp_f32_e32 v8, v8
	v_rcp_f32_e32 v9, v9
	v_cvt_pk_f16_f32 v144, v6, v7
	v_cvt_pk_f16_f32 v145, v8, v9
	ds_write_b64 v130, v[144:145] offset:13904
	v_mul_f32_e32 v26, 0xbfb8aa3b, v26
	v_mul_f32_e32 v27, 0xbfb8aa3b, v27
	v_mul_f32_e32 v28, 0xbfb8aa3b, v28
	v_mul_f32_e32 v29, 0xbfb8aa3b, v29
	v_exp_f32_e32 v26, v26
	v_exp_f32_e32 v27, v27
	v_exp_f32_e32 v28, v28
	v_exp_f32_e32 v29, v29
	v_add_f32_e32 v26, 1.0, v26
	v_add_f32_e32 v27, 1.0, v27
	v_add_f32_e32 v28, 1.0, v28
	v_add_f32_e32 v29, 1.0, v29
	v_rcp_f32_e32 v26, v26
	v_rcp_f32_e32 v27, v27
	v_rcp_f32_e32 v28, v28
	v_rcp_f32_e32 v29, v29
	v_cvt_pk_f16_f32 v138, v26, v27
	v_cvt_pk_f16_f32 v139, v28, v29
	ds_write_b64 v130, v[138:139] offset:13856
	v_mul_f32_e32 v10, 0xbfb8aa3b, v10
	v_mul_f32_e32 v11, 0xbfb8aa3b, v11
	v_mul_f32_e32 v12, 0xbfb8aa3b, v12
	v_mul_f32_e32 v13, 0xbfb8aa3b, v13
	v_exp_f32_e32 v10, v10
	v_exp_f32_e32 v11, v11
	v_exp_f32_e32 v12, v12
	v_exp_f32_e32 v13, v13
	v_add_f32_e32 v10, 1.0, v10
	v_add_f32_e32 v11, 1.0, v11
	v_add_f32_e32 v12, 1.0, v12
	v_add_f32_e32 v13, 1.0, v13
	v_rcp_f32_e32 v10, v10
	v_rcp_f32_e32 v11, v11
	v_rcp_f32_e32 v12, v12
	v_rcp_f32_e32 v13, v13
	v_cvt_pk_f16_f32 v140, v10, v11
	v_cvt_pk_f16_f32 v141, v12, v13
	ds_write_b64 v130, v[140:141] offset:13920
	v_mul_f32_e32 v30, 0xbfb8aa3b, v30
	v_mul_f32_e32 v31, 0xbfb8aa3b, v31
	v_mul_f32_e32 v32, 0xbfb8aa3b, v32
	v_mul_f32_e32 v33, 0xbfb8aa3b, v33
	v_exp_f32_e32 v30, v30
	v_exp_f32_e32 v31, v31
	v_exp_f32_e32 v32, v32
	v_exp_f32_e32 v33, v33
	v_add_f32_e32 v30, 1.0, v30
	v_add_f32_e32 v31, 1.0, v31
	v_add_f32_e32 v32, 1.0, v32
	v_add_f32_e32 v33, 1.0, v33
	v_rcp_f32_e32 v30, v30
	v_rcp_f32_e32 v31, v31
	v_rcp_f32_e32 v32, v32
	v_rcp_f32_e32 v33, v33
	v_cvt_pk_f16_f32 v142, v30, v31
	v_cvt_pk_f16_f32 v143, v32, v33
	ds_write_b64 v130, v[142:143] offset:13872
	v_mul_f32_e32 v14, 0xbfb8aa3b, v14
	v_mul_f32_e32 v15, 0xbfb8aa3b, v15
	v_mul_f32_e32 v16, 0xbfb8aa3b, v16
	v_mul_f32_e32 v17, 0xbfb8aa3b, v17
	v_exp_f32_e32 v14, v14
	v_exp_f32_e32 v15, v15
	v_exp_f32_e32 v16, v16
	v_exp_f32_e32 v17, v17
	v_add_f32_e32 v14, 1.0, v14
	v_add_f32_e32 v15, 1.0, v15
	v_add_f32_e32 v16, 1.0, v16
	v_add_f32_e32 v17, 1.0, v17
	v_rcp_f32_e32 v14, v14
	v_rcp_f32_e32 v15, v15
	v_rcp_f32_e32 v16, v16
	v_rcp_f32_e32 v17, v17
	v_cvt_pk_f16_f32 v144, v14, v15
	v_cvt_pk_f16_f32 v145, v16, v17
	ds_write_b64 v130, v[144:145] offset:13936
	ds_read_b128 v[150:153], v131 offset:0
	ds_read_b128 v[154:157], v131 offset:1152
	ds_read_b128 v[158:161], v131 offset:2304
	ds_read_b128 v[162:165], v131 offset:3456
	ds_read_b128 v[216:219], v131 offset:4608
	ds_read_b128 v[220:223], v131 offset:5760
	ds_read_b128 v[224:227], v131 offset:6912
	ds_read_b128 v[228:231], v131 offset:8064
	s_waitcnt lgkmcnt(7)
; DI float sigmoid_(float x) { return 1.f / (1.f + __expf(-x)); }
; DI void phase_gates(const Params& p, int bid, int nb, h16* lds) {
;     ...
;   for (int u = bid; u < 64 * 16; u += nb) {
;     const int m0 = (u >> 4) * 256, n0 = (u & 15) * 256;
;     f16v acc[4][2]; acc256_zero(acc);
;     gemm256_main<false>(x16, DM, nullptr, m0, wg, 1024, n0, 1024, lds, acc);
;     gemm256_epilogue(acc, m0, n0, [&](int m, int n, f4v v0, f4v v1) {
;       f4v a, b;
; #pragma unroll
;       for (int i = 0; i < 4; ++i) { a[i] = sigmoid_(v0[i]); b[i] = sigmoid_(v1[i]); }
;       st_h4(&G[(size_t)m * 4096 + n], a); st_h4(&G[(size_t)m * 4096 + n + 32], b);
;     });
;   }
	global_store_dwordx4 v[132:133], v[150:153], off
	v_lshl_add_u64 v[132:133], v[132:133], 0, s[76:77]
	s_waitcnt lgkmcnt(6)
	global_store_dwordx4 v[132:133], v[154:157], off
	v_lshl_add_u64 v[132:133], v[132:133], 0, s[76:77]
	s_waitcnt lgkmcnt(5)
	global_store_dwordx4 v[132:133], v[158:161], off
	v_lshl_add_u64 v[132:133], v[132:133], 0, s[76:77]
	s_waitcnt lgkmcnt(4)
	global_store_dwordx4 v[132:133], v[162:165], off
	v_lshl_add_u64 v[132:133], v[132:133], 0, s[76:77]
	s_waitcnt lgkmcnt(3)
	global_store_dwordx4 v[132:133], v[216:219], off
	v_lshl_add_u64 v[132:133], v[132:133], 0, s[76:77]
	s_waitcnt lgkmcnt(2)
	global_store_dwordx4 v[132:133], v[220:223], off
	v_lshl_add_u64 v[132:133], v[132:133], 0, s[76:77]
	s_waitcnt lgkmcnt(1)
	global_store_dwordx4 v[132:133], v[224:227], off
	v_lshl_add_u64 v[132:133], v[132:133], 0, s[76:77]
	s_waitcnt lgkmcnt(0)
	global_store_dwordx4 v[132:133], v[228:231], off
	v_lshl_add_u64 v[132:133], v[132:133], 0, s[76:77]
	s_nop 1
	ds_read_b128 v[150:153], v131 offset:9216
	ds_read_b128 v[154:157], v131 offset:10368
	ds_read_b128 v[158:161], v131 offset:11520
	ds_read_b128 v[162:165], v131 offset:12672
	ds_read_b128 v[216:219], v131 offset:13824
	ds_read_b128 v[220:223], v131 offset:14976
	ds_read_b128 v[224:227], v131 offset:16128
	ds_read_b128 v[228:231], v131 offset:17280
	s_waitcnt lgkmcnt(7)
	global_store_dwordx4 v[132:133], v[150:153], off
	v_lshl_add_u64 v[132:133], v[132:133], 0, s[76:77]
	s_waitcnt lgkmcnt(6)
	global_store_dwordx4 v[132:133], v[154:157], off
	v_lshl_add_u64 v[132:133], v[132:133], 0, s[76:77]
	s_waitcnt lgkmcnt(5)
	global_store_dwordx4 v[132:133], v[158:161], off
	v_lshl_add_u64 v[132:133], v[132:133], 0, s[76:77]
	s_waitcnt lgkmcnt(4)
	global_store_dwordx4 v[132:133], v[162:165], off
	v_lshl_add_u64 v[132:133], v[132:133], 0, s[76:77]
	s_waitcnt lgkmcnt(3)
	global_store_dwordx4 v[132:133], v[216:219], off
	v_lshl_add_u64 v[132:133], v[132:133], 0, s[76:77]
	s_waitcnt lgkmcnt(2)
	global_store_dwordx4 v[132:133], v[220:223], off
	v_lshl_add_u64 v[132:133], v[132:133], 0, s[76:77]
	s_waitcnt lgkmcnt(1)
	global_store_dwordx4 v[132:133], v[224:227], off
	v_lshl_add_u64 v[132:133], v[132:133], 0, s[76:77]
	s_waitcnt lgkmcnt(0)
	global_store_dwordx4 v[132:133], v[228:231], off
	v_lshl_add_u64 v[132:133], v[132:133], 0, s[76:77]
	s_cmp_eq_u32 s60, 1
	s_cbranch_scc1 .LBB0_1246

; DI int otid512() { int t = threadIdx.x; asm volatile("" : "+v"(t)); return t; }
; template <bool GATHER>
; DI void gemm256_main(const h16* __restrict__ A, int lda, const int* __restrict__ idx, int m0,
;                      const h16* __restrict__ B, int ldb, int n0, int K, h16* lds, f16v (&acc)[4][2]) {
;   const int tid = otid512(), lane = tid & 63, wv = tid >> 6, wm = wv >> 2, wn = wv & 3;
;   const int lr = tid >> 1, lc = (tid & 1) * 32;
;   unsigned ao = (unsigned)(GATHER ? idx[m0 + lr] : (m0 + lr)) * (unsigned)lda + lc;
;   unsigned bo = (unsigned)(n0 + lr) * (unsigned)ldb + lc;
;   const h16* ap = A; const h16* bp = B;
;     ...
;   u4v ra[4], rb[4];
;   const int nk = K >> 6;
;   __syncthreads();
; #pragma unroll
;   for (int i = 0; i < 4; ++i) { ra[i] = *(const u4v*)(AP_ + 8 * i); rb[i] = *(const u4v*)(BP_ + 8 * i); }
;   ao += 64; bo += 64;
; #pragma unroll
;   for (int i = 0; i < 4; ++i) { *(u4v*)&lds[lr * LDH + lc + 8 * i] = ra[i]; *(u4v*)&lds[(256 + lr) * LDH + lc + 8 * i] = rb[i]; }
; #pragma unroll
;   for (int i = 0; i < 4; ++i) { ra[i] = *(const u4v*)(AP_ + 8 * i); rb[i] = *(const u4v*)(BP_ + 8 * i); }
;   ao += 64; bo += 64;
;   __syncthreads();
; DI void phase_resid_gemm(const Params& p, const h16* A, int lda, const h16* W, int K, const float* xres, int bid, int nb, h16* lds) {
;     ...
;   for (int u = bid; u < 64 * 4; u += nb) {
;     const int m0 = (u >> 2) * 256, n0 = (u & 3) * 256;
;     f16v acc[4][2]; acc256_zero(acc);
;     gemm256_main<false>(A, lda, nullptr, m0, W, K, n0, K, lds, acc);
.LBB0_1354:
	s_lshl_b32 s5, s4, 6
	v_mov_b32_e32 v1, v180
	s_and_b32 s6, s5, 0xffffff00
	s_lshl_b32 s5, s4, 8
	s_and_b32 s5, s5, 0x300
	v_ashrrev_i32_e32 v58, 1, v1
	v_lshlrev_b32_e32 v2, 5, v1
	v_and_b32_e32 v60, 32, v2
	v_add_u32_e32 v2, s6, v58
	v_lshl_or_b32 v54, v2, 10, v60
	v_add_u32_e32 v2, s5, v58
	v_readlane_b32 s16, v254, 46
	v_lshl_or_b32 v56, v2, 10, v60
	v_mov_b32_e32 v55, v0
	v_mov_b32_e32 v57, v0
	v_readlane_b32 s17, v254, 47
	v_lshl_add_u64 v[2:3], v[54:55], 1, s[30:31]
	v_and_b32_e32 v55, 31, v1
	v_lshl_add_u64 v[4:5], v[56:57], 1, s[16:17]
	v_lshrrev_b32_e32 v57, 2, v1
	v_mul_lo_u32 v62, v58, s33
	v_mov_b32_e32 v59, v0
	v_and_or_b32 v55, v58, s56, v55
	v_and_b32_e32 v174, 8, v57
	v_add_u32_e32 v57, 16, v62
	v_or_b32_e32 v58, 64, v54
	v_mov_b32_e32 v61, v0
	v_mul_lo_u32 v171, v55, s33
	v_lshl_add_u32 v176, v60, 1, v57
	v_or_b32_e32 v60, 64, v56
	v_or_b32_e32 v164, 0x80, v54
	v_lshl_add_u64 v[54:55], v[58:59], 1, s[30:31]
	s_barrier
	v_readlane_b32 s16, v252, 3
	v_readlane_b32 s18, v252, 5
	v_readlane_b32 s19, v252, 6
	v_readlane_b32 s22, v252, 9
	v_readlane_b32 s17, v252, 4
	v_readlane_b32 s20, v252, 7
	v_readlane_b32 s21, v252, 8
	v_readlane_b32 s23, v252, 10
	s_nop 1
	s_add_i32 s4, s4, s22
	s_cmpk_gt_i32 s4, 0xff
	v_mov_b32_e32 v162, v2
	v_mov_b32_e32 v163, v3
	v_mov_b32_e32 v178, v4
	v_mov_b32_e32 v179, v5
	s_cselect_b32 s98, 1, 0
	v_readfirstlane_b32 s99, v180
	s_nop 1
	s_cmp_lt_u32 s99, 0x100
	s_cbranch_scc1 .Lprio_skip_3
	s_setprio 1
.Lprio_skip_3:
	s_cmp_eq_u32 s98, 1
	v_lshrrev_b32_e32 v199, 1, v180
	v_and_b32_e32 v244, 1, v180
	v_mul_u32_u24_e32 v199, 0x90, v199
	v_lshl_add_u32 v165, v244, 6, v199
	v_add_u32_e32 v165, 16, v165
	v_add_u32_e32 v175, 0x12000, v165
	v_lshrrev_b32_e32 v199, 8, v180
	v_and_b32_e32 v245, 31, v180
	v_lshl_or_b32 v199, v199, 7, v245
	v_mul_u32_u24_e32 v199, 0x90, v199
	v_bfe_u32 v244, v180, 5, 1
	v_lshl_add_u32 v199, v244, 4, v199
	v_add_u32_e32 v177, 16, v199
	v_add_u32_e32 v192, 0x12000, v177
	v_bfe_u32 v199, v180, 6, 2
	v_lshl_or_b32 v199, v199, 6, v245
	v_mul_u32_u24_e32 v199, 0x90, v199
	v_lshl_add_u32 v199, v244, 4, v199
	v_add_u32_e32 v193, 0x9010, v199
	v_add_u32_e32 v194, 0x12000, v193
	global_load_dwordx4 v[130:133], v[162:163], off offset:0
	global_load_dwordx4 v[134:137], v[162:163], off offset:16
	global_load_dwordx4 v[138:141], v[162:163], off offset:32
	global_load_dwordx4 v[142:145], v[162:163], off offset:48
	global_load_dwordx4 v[146:149], v[178:179], off offset:0
	global_load_dwordx4 v[150:153], v[178:179], off offset:16
	global_load_dwordx4 v[154:157], v[178:179], off offset:32
	global_load_dwordx4 v[158:161], v[178:179], off offset:48
	s_waitcnt vmcnt(0)
	ds_write_b128 v165, v[130:133]
	ds_write_b128 v165, v[134:137] offset:16
	ds_write_b128 v165, v[138:141] offset:32
	ds_write_b128 v165, v[142:145] offset:48
	ds_write_b128 v165, v[146:149] offset:36864
	ds_write_b128 v165, v[150:153] offset:36880
	ds_write_b128 v165, v[154:157] offset:36896
	ds_write_b128 v165, v[158:161] offset:36912
	global_load_dwordx4 v[130:133], v[162:163], off offset:128
	global_load_dwordx4 v[134:137], v[162:163], off offset:144
	global_load_dwordx4 v[138:141], v[162:163], off offset:160
	global_load_dwordx4 v[142:145], v[162:163], off offset:176
	global_load_dwordx4 v[146:149], v[178:179], off offset:128
	global_load_dwordx4 v[150:153], v[178:179], off offset:144
	global_load_dwordx4 v[154:157], v[178:179], off offset:160
	global_load_dwordx4 v[158:161], v[178:179], off offset:176
	s_waitcnt lgkmcnt(0)
	s_barrier
	ds_read_b128 v[228:231], v193
	ds_read_b128 v[188:191], v177
	ds_read_b128 v[232:235], v193 offset:4608
	ds_read_b128 v[200:203], v177 offset:4608
	ds_read_b128 v[204:207], v177 offset:9216
	ds_read_b128 v[208:211], v177 offset:13824
	ds_read_b128 v[236:239], v193 offset:32
	ds_read_b128 v[212:215], v177 offset:32
	ds_read_b128 v[240:243], v193 offset:4640
	ds_read_b128 v[216:219], v177 offset:4640
	ds_read_b128 v[220:223], v177 offset:9248
	ds_read_b128 v[224:227], v177 offset:13856
	s_waitcnt vmcnt(4)
	ds_write_b128 v175, v[130:133]
	ds_write_b128 v175, v[134:137] offset:16
	ds_write_b128 v175, v[138:141] offset:32
	ds_write_b128 v175, v[142:145] offset:48
	global_load_dwordx4 v[130:133], v[162:163], off offset:256
	global_load_dwordx4 v[134:137], v[162:163], off offset:272
	global_load_dwordx4 v[138:141], v[162:163], off offset:288
	global_load_dwordx4 v[142:145], v[162:163], off offset:304
	s_waitcnt lgkmcnt(14)
	v_mfma_f32_32x32x16_f16 v[114:129], v[228:231], v[188:191], 0
	s_waitcnt lgkmcnt(13)
	v_mfma_f32_32x32x16_f16 v[98:113], v[232:235], v[188:191], 0
	s_waitcnt lgkmcnt(12)
	v_mfma_f32_32x32x16_f16 v[82:97], v[228:231], v[200:203], 0
	v_mfma_f32_32x32x16_f16 v[66:81], v[232:235], v[200:203], 0
	s_waitcnt lgkmcnt(11)
	v_mfma_f32_32x32x16_f16 v[50:65], v[228:231], v[204:207], 0
	v_mfma_f32_32x32x16_f16 v[34:49], v[232:235], v[204:207], 0
	s_waitcnt lgkmcnt(10)
	v_mfma_f32_32x32x16_f16 v[18:33], v[228:231], v[208:211], 0
	v_mfma_f32_32x32x16_f16 v[2:17], v[232:235], v[208:211], 0
	ds_read_b128 v[228:231], v193 offset:64
	ds_read_b128 v[188:191], v177 offset:64
	ds_read_b128 v[232:235], v193 offset:4672
	ds_read_b128 v[200:203], v177 offset:4672
	ds_read_b128 v[204:207], v177 offset:9280
	ds_read_b128 v[208:211], v177 offset:13888
	s_waitcnt vmcnt(4)
	ds_write_b128 v175, v[146:149] offset:36864
	ds_write_b128 v175, v[150:153] offset:36880
	ds_write_b128 v175, v[154:157] offset:36896
	ds_write_b128 v175, v[158:161] offset:36912
	global_load_dwordx4 v[146:149], v[178:179], off offset:256
	global_load_dwordx4 v[150:153], v[178:179], off offset:272
	global_load_dwordx4 v[154:157], v[178:179], off offset:288
	global_load_dwordx4 v[158:161], v[178:179], off offset:304
	s_waitcnt lgkmcnt(15)
; DI f16v mfma32(h8v a, h8v b, f16v c) { return __builtin_amdgcn_mfma_f32_32x32x16_f16(a, b, c, 0, 0, 0); }
; template <bool GATHER>
; DI void gemm256_main(const h16* __restrict__ A, int lda, const int* __restrict__ idx, int m0,
;                      const h16* __restrict__ B, int ldb, int n0, int K, h16* lds, f16v (&acc)[4][2]) {
;     ...
;   for (int kt = 0; kt < nk; ++kt) {
;     const h16* As = lds + (kt & 1) * (512 * LDH);
;     const h16* Bs = As + 256 * LDH;
;     h16* Wn = lds + ((kt & 1) ^ 1) * (512 * LDH);
;     if (kt + 1 < nk) {
; #pragma unroll
;       for (int i = 0; i < 4; ++i) { *(u4v*)&Wn[lr * LDH + lc + 8 * i] = ra[i]; *(u4v*)&Wn[(256 + lr) * LDH + lc + 8 * i] = rb[i]; }
;     }
;     if (kt + 2 < nk) {
; #pragma unroll
;       for (int i = 0; i < 4; ++i) { ra[i] = *(const u4v*)(AP_ + 8 * i); rb[i] = *(const u4v*)(BP_ + 8 * i); }
;       ao += 64; bo += 64;
;     }
; #pragma unroll
;     for (int ks = 0; ks < 4; ++ks) {
;       h8v af[4], bf[2];
; #pragma unroll
;       for (int i = 0; i < 4; ++i) af[i] = *(const h8v*)&As[(wm * 128 + i * 32 + (lane & 31)) * LDH + ks * 16 + 8 * (lane >> 5)];
; #pragma unroll
;       for (int j = 0; j < 2; ++j) bf[j] = *(const h8v*)&Bs[(wn * 64 + j * 32 + (lane & 31)) * LDH + ks * 16 + 8 * (lane >> 5)];
; #pragma unroll
;       for (int i = 0; i < 4; ++i)
; #pragma unroll
;         for (int j = 0; j < 2; ++j) acc[i][j] = mfma32(bf[j], af[i], acc[i][j]);
;     }
;     __syncthreads();
;   }
	v_mfma_f32_32x32x16_f16 v[114:129], v[236:239], v[212:215], v[114:129]
	s_waitcnt lgkmcnt(15)
	v_mfma_f32_32x32x16_f16 v[98:113], v[240:243], v[212:215], v[98:113]
	s_waitcnt lgkmcnt(15)
	v_mfma_f32_32x32x16_f16 v[82:97], v[236:239], v[216:219], v[82:97]
	v_mfma_f32_32x32x16_f16 v[66:81], v[240:243], v[216:219], v[66:81]
	s_waitcnt lgkmcnt(15)
	v_mfma_f32_32x32x16_f16 v[50:65], v[236:239], v[220:223], v[50:65]
	v_mfma_f32_32x32x16_f16 v[34:49], v[240:243], v[220:223], v[34:49]
	s_waitcnt lgkmcnt(14)
	v_mfma_f32_32x32x16_f16 v[18:33], v[236:239], v[224:227], v[18:33]
	v_mfma_f32_32x32x16_f16 v[2:17], v[240:243], v[224:227], v[2:17]
	ds_read_b128 v[236:239], v193 offset:96
	ds_read_b128 v[212:215], v177 offset:96
	ds_read_b128 v[240:243], v193 offset:4704
	ds_read_b128 v[216:219], v177 offset:4704
	ds_read_b128 v[220:223], v177 offset:9312
	ds_read_b128 v[224:227], v177 offset:13920
	s_waitcnt lgkmcnt(14)
	v_mfma_f32_32x32x16_f16 v[114:129], v[228:231], v[188:191], v[114:129]
	s_waitcnt lgkmcnt(13)
	v_mfma_f32_32x32x16_f16 v[98:113], v[232:235], v[188:191], v[98:113]
	s_waitcnt lgkmcnt(12)
	v_mfma_f32_32x32x16_f16 v[82:97], v[228:231], v[200:203], v[82:97]
	v_mfma_f32_32x32x16_f16 v[66:81], v[232:235], v[200:203], v[66:81]
	s_waitcnt lgkmcnt(11)
	v_mfma_f32_32x32x16_f16 v[50:65], v[228:231], v[204:207], v[50:65]
	v_mfma_f32_32x32x16_f16 v[34:49], v[232:235], v[204:207], v[34:49]
	s_waitcnt lgkmcnt(10)
	v_mfma_f32_32x32x16_f16 v[18:33], v[228:231], v[208:211], v[18:33]
	v_mfma_f32_32x32x16_f16 v[2:17], v[232:235], v[208:211], v[2:17]
	s_waitcnt lgkmcnt(0)
	s_barrier
	ds_read_b128 v[228:231], v194
	ds_read_b128 v[188:191], v192
	ds_read_b128 v[232:235], v194 offset:4608
	ds_read_b128 v[200:203], v192 offset:4608
	ds_read_b128 v[204:207], v192 offset:9216
	ds_read_b128 v[208:211], v192 offset:13824
	v_mfma_f32_32x32x16_f16 v[114:129], v[236:239], v[212:215], v[114:129]
	v_mfma_f32_32x32x16_f16 v[98:113], v[240:243], v[212:215], v[98:113]
	v_mfma_f32_32x32x16_f16 v[82:97], v[236:239], v[216:219], v[82:97]
	v_mfma_f32_32x32x16_f16 v[66:81], v[240:243], v[216:219], v[66:81]
	v_mfma_f32_32x32x16_f16 v[50:65], v[236:239], v[220:223], v[50:65]
	v_mfma_f32_32x32x16_f16 v[34:49], v[240:243], v[220:223], v[34:49]
	v_mfma_f32_32x32x16_f16 v[18:33], v[236:239], v[224:227], v[18:33]
	v_mfma_f32_32x32x16_f16 v[2:17], v[240:243], v[224:227], v[2:17]
	ds_read_b128 v[236:239], v194 offset:32
	ds_read_b128 v[212:215], v192 offset:32
	ds_read_b128 v[240:243], v194 offset:4640
	ds_read_b128 v[216:219], v192 offset:4640
	ds_read_b128 v[220:223], v192 offset:9248
	ds_read_b128 v[224:227], v192 offset:13856
	s_waitcnt vmcnt(4)
	ds_write_b128 v165, v[130:133]
	ds_write_b128 v165, v[134:137] offset:16
	ds_write_b128 v165, v[138:141] offset:32
	ds_write_b128 v165, v[142:145] offset:48
	global_load_dwordx4 v[130:133], v[162:163], off offset:384
	global_load_dwordx4 v[134:137], v[162:163], off offset:400
	global_load_dwordx4 v[138:141], v[162:163], off offset:416
	global_load_dwordx4 v[142:145], v[162:163], off offset:432
	s_waitcnt lgkmcnt(14)
	v_mfma_f32_32x32x16_f16 v[114:129], v[228:231], v[188:191], v[114:129]
	s_waitcnt lgkmcnt(13)
	v_mfma_f32_32x32x16_f16 v[98:113], v[232:235], v[188:191], v[98:113]
	s_waitcnt lgkmcnt(12)
	v_mfma_f32_32x32x16_f16 v[82:97], v[228:231], v[200:203], v[82:97]
	v_mfma_f32_32x32x16_f16 v[66:81], v[232:235], v[200:203], v[66:81]
	s_waitcnt lgkmcnt(11)
	v_mfma_f32_32x32x16_f16 v[50:65], v[228:231], v[204:207], v[50:65]
	v_mfma_f32_32x32x16_f16 v[34:49], v[232:235], v[204:207], v[34:49]
	s_waitcnt lgkmcnt(10)
	v_mfma_f32_32x32x16_f16 v[18:33], v[228:231], v[208:211], v[18:33]
	v_mfma_f32_32x32x16_f16 v[2:17], v[232:235], v[208:211], v[2:17]
	ds_read_b128 v[228:231], v194 offset:64
	ds_read_b128 v[188:191], v192 offset:64
	ds_read_b128 v[232:235], v194 offset:4672
	ds_read_b128 v[200:203], v192 offset:4672
	ds_read_b128 v[204:207], v192 offset:9280
	ds_read_b128 v[208:211], v192 offset:13888
	s_waitcnt vmcnt(4)
	ds_write_b128 v165, v[146:149] offset:36864
	ds_write_b128 v165, v[150:153] offset:36880
	ds_write_b128 v165, v[154:157] offset:36896
	ds_write_b128 v165, v[158:161] offset:36912
	global_load_dwordx4 v[146:149], v[178:179], off offset:384
	global_load_dwordx4 v[150:153], v[178:179], off offset:400
	global_load_dwordx4 v[154:157], v[178:179], off offset:416
	global_load_dwordx4 v[158:161], v[178:179], off offset:432
	s_waitcnt lgkmcnt(15)
	v_mfma_f32_32x32x16_f16 v[114:129], v[236:239], v[212:215], v[114:129]
	s_waitcnt lgkmcnt(15)
	v_mfma_f32_32x32x16_f16 v[98:113], v[240:243], v[212:215], v[98:113]
	s_waitcnt lgkmcnt(15)
	v_mfma_f32_32x32x16_f16 v[82:97], v[236:239], v[216:219], v[82:97]
	v_mfma_f32_32x32x16_f16 v[66:81], v[240:243], v[216:219], v[66:81]
	s_waitcnt lgkmcnt(15)
	v_mfma_f32_32x32x16_f16 v[50:65], v[236:239], v[220:223], v[50:65]
	v_mfma_f32_32x32x16_f16 v[34:49], v[240:243], v[220:223], v[34:49]
	s_waitcnt lgkmcnt(14)
	v_mfma_f32_32x32x16_f16 v[18:33], v[236:239], v[224:227], v[18:33]
	v_mfma_f32_32x32x16_f16 v[2:17], v[240:243], v[224:227], v[2:17]
	ds_read_b128 v[236:239], v194 offset:96
	ds_read_b128 v[212:215], v192 offset:96
	ds_read_b128 v[240:243], v194 offset:4704
	ds_read_b128 v[216:219], v192 offset:4704
	ds_read_b128 v[220:223], v192 offset:9312
	ds_read_b128 v[224:227], v192 offset:13920
	s_waitcnt lgkmcnt(14)
	v_mfma_f32_32x32x16_f16 v[114:129], v[228:231], v[188:191], v[114:129]
	s_waitcnt lgkmcnt(13)
	v_mfma_f32_32x32x16_f16 v[98:113], v[232:235], v[188:191], v[98:113]
	s_waitcnt lgkmcnt(12)
	v_mfma_f32_32x32x16_f16 v[82:97], v[228:231], v[200:203], v[82:97]
	v_mfma_f32_32x32x16_f16 v[66:81], v[232:235], v[200:203], v[66:81]
	s_waitcnt lgkmcnt(11)
	v_mfma_f32_32x32x16_f16 v[50:65], v[228:231], v[204:207], v[50:65]
	v_mfma_f32_32x32x16_f16 v[34:49], v[232:235], v[204:207], v[34:49]
	s_waitcnt lgkmcnt(10)
	v_mfma_f32_32x32x16_f16 v[18:33], v[228:231], v[208:211], v[18:33]
	v_mfma_f32_32x32x16_f16 v[2:17], v[232:235], v[208:211], v[2:17]
	s_waitcnt lgkmcnt(0)
	s_barrier
; DI f16v mfma32(h8v a, h8v b, f16v c) { return __builtin_amdgcn_mfma_f32_32x32x16_f16(a, b, c, 0, 0, 0); }
; template <bool GATHER>
; DI void gemm256_main(const h16* __restrict__ A, int lda, const int* __restrict__ idx, int m0,
;                      const h16* __restrict__ B, int ldb, int n0, int K, h16* lds, f16v (&acc)[4][2]) {
;     ...
;   for (int kt = 0; kt < nk; ++kt) {
;     const h16* As = lds + (kt & 1) * (512 * LDH);
;     const h16* Bs = As + 256 * LDH;
;     h16* Wn = lds + ((kt & 1) ^ 1) * (512 * LDH);
;     if (kt + 1 < nk) {
; #pragma unroll
;       for (int i = 0; i < 4; ++i) { *(u4v*)&Wn[lr * LDH + lc + 8 * i] = ra[i]; *(u4v*)&Wn[(256 + lr) * LDH + lc + 8 * i] = rb[i]; }
;     }
;     if (kt + 2 < nk) {
; #pragma unroll
;       for (int i = 0; i < 4; ++i) { ra[i] = *(const u4v*)(AP_ + 8 * i); rb[i] = *(const u4v*)(BP_ + 8 * i); }
;       ao += 64; bo += 64;
;     }
; #pragma unroll
;     for (int ks = 0; ks < 4; ++ks) {
;       h8v af[4], bf[2];
; #pragma unroll
;       for (int i = 0; i < 4; ++i) af[i] = *(const h8v*)&As[(wm * 128 + i * 32 + (lane & 31)) * LDH + ks * 16 + 8 * (lane >> 5)];
; #pragma unroll
;       for (int j = 0; j < 2; ++j) bf[j] = *(const h8v*)&Bs[(wn * 64 + j * 32 + (lane & 31)) * LDH + ks * 16 + 8 * (lane >> 5)];
; #pragma unroll
;       for (int i = 0; i < 4; ++i)
; #pragma unroll
;         for (int j = 0; j < 2; ++j) acc[i][j] = mfma32(bf[j], af[i], acc[i][j]);
;     }
;     __syncthreads();
;   }
	ds_read_b128 v[228:231], v193
	ds_read_b128 v[188:191], v177
	ds_read_b128 v[232:235], v193 offset:4608
	ds_read_b128 v[200:203], v177 offset:4608
	ds_read_b128 v[204:207], v177 offset:9216
	ds_read_b128 v[208:211], v177 offset:13824
	v_mfma_f32_32x32x16_f16 v[114:129], v[236:239], v[212:215], v[114:129]
	v_mfma_f32_32x32x16_f16 v[98:113], v[240:243], v[212:215], v[98:113]
	v_mfma_f32_32x32x16_f16 v[82:97], v[236:239], v[216:219], v[82:97]
	v_mfma_f32_32x32x16_f16 v[66:81], v[240:243], v[216:219], v[66:81]
	v_mfma_f32_32x32x16_f16 v[50:65], v[236:239], v[220:223], v[50:65]
	v_mfma_f32_32x32x16_f16 v[34:49], v[240:243], v[220:223], v[34:49]
	v_mfma_f32_32x32x16_f16 v[18:33], v[236:239], v[224:227], v[18:33]
	v_mfma_f32_32x32x16_f16 v[2:17], v[240:243], v[224:227], v[2:17]
	ds_read_b128 v[236:239], v193 offset:32
	ds_read_b128 v[212:215], v177 offset:32
	ds_read_b128 v[240:243], v193 offset:4640
	ds_read_b128 v[216:219], v177 offset:4640
	ds_read_b128 v[220:223], v177 offset:9248
	ds_read_b128 v[224:227], v177 offset:13856
	s_waitcnt vmcnt(4)
	ds_write_b128 v175, v[130:133]
	ds_write_b128 v175, v[134:137] offset:16
	ds_write_b128 v175, v[138:141] offset:32
	ds_write_b128 v175, v[142:145] offset:48
	global_load_dwordx4 v[130:133], v[162:163], off offset:512
	global_load_dwordx4 v[134:137], v[162:163], off offset:528
	global_load_dwordx4 v[138:141], v[162:163], off offset:544
	global_load_dwordx4 v[142:145], v[162:163], off offset:560
	s_waitcnt lgkmcnt(14)
	v_mfma_f32_32x32x16_f16 v[114:129], v[228:231], v[188:191], v[114:129]
	s_waitcnt lgkmcnt(13)
	v_mfma_f32_32x32x16_f16 v[98:113], v[232:235], v[188:191], v[98:113]
	s_waitcnt lgkmcnt(12)
	v_mfma_f32_32x32x16_f16 v[82:97], v[228:231], v[200:203], v[82:97]
	v_mfma_f32_32x32x16_f16 v[66:81], v[232:235], v[200:203], v[66:81]
	s_waitcnt lgkmcnt(11)
	v_mfma_f32_32x32x16_f16 v[50:65], v[228:231], v[204:207], v[50:65]
	v_mfma_f32_32x32x16_f16 v[34:49], v[232:235], v[204:207], v[34:49]
	s_waitcnt lgkmcnt(10)
	v_mfma_f32_32x32x16_f16 v[18:33], v[228:231], v[208:211], v[18:33]
	v_mfma_f32_32x32x16_f16 v[2:17], v[232:235], v[208:211], v[2:17]
	ds_read_b128 v[228:231], v193 offset:64
	ds_read_b128 v[188:191], v177 offset:64
	ds_read_b128 v[232:235], v193 offset:4672
	ds_read_b128 v[200:203], v177 offset:4672
	ds_read_b128 v[204:207], v177 offset:9280
	ds_read_b128 v[208:211], v177 offset:13888
	s_waitcnt vmcnt(4)
	ds_write_b128 v175, v[146:149] offset:36864
	ds_write_b128 v175, v[150:153] offset:36880
	ds_write_b128 v175, v[154:157] offset:36896
	ds_write_b128 v175, v[158:161] offset:36912
	global_load_dwordx4 v[146:149], v[178:179], off offset:512
	global_load_dwordx4 v[150:153], v[178:179], off offset:528
	global_load_dwordx4 v[154:157], v[178:179], off offset:544
	global_load_dwordx4 v[158:161], v[178:179], off offset:560
	s_waitcnt lgkmcnt(15)
	v_mfma_f32_32x32x16_f16 v[114:129], v[236:239], v[212:215], v[114:129]
	s_waitcnt lgkmcnt(15)
	v_mfma_f32_32x32x16_f16 v[98:113], v[240:243], v[212:215], v[98:113]
	s_waitcnt lgkmcnt(15)
	v_mfma_f32_32x32x16_f16 v[82:97], v[236:239], v[216:219], v[82:97]
	v_mfma_f32_32x32x16_f16 v[66:81], v[240:243], v[216:219], v[66:81]
	s_waitcnt lgkmcnt(15)
	v_mfma_f32_32x32x16_f16 v[50:65], v[236:239], v[220:223], v[50:65]
	v_mfma_f32_32x32x16_f16 v[34:49], v[240:243], v[220:223], v[34:49]
	s_waitcnt lgkmcnt(14)
	v_mfma_f32_32x32x16_f16 v[18:33], v[236:239], v[224:227], v[18:33]
	v_mfma_f32_32x32x16_f16 v[2:17], v[240:243], v[224:227], v[2:17]
	ds_read_b128 v[236:239], v193 offset:96
	ds_read_b128 v[212:215], v177 offset:96
	ds_read_b128 v[240:243], v193 offset:4704
	ds_read_b128 v[216:219], v177 offset:4704
	ds_read_b128 v[220:223], v177 offset:9312
	ds_read_b128 v[224:227], v177 offset:13920
	s_waitcnt lgkmcnt(14)
	v_mfma_f32_32x32x16_f16 v[114:129], v[228:231], v[188:191], v[114:129]
	s_waitcnt lgkmcnt(13)
	v_mfma_f32_32x32x16_f16 v[98:113], v[232:235], v[188:191], v[98:113]
	s_waitcnt lgkmcnt(12)
	v_mfma_f32_32x32x16_f16 v[82:97], v[228:231], v[200:203], v[82:97]
	v_mfma_f32_32x32x16_f16 v[66:81], v[232:235], v[200:203], v[66:81]
	s_waitcnt lgkmcnt(11)
	v_mfma_f32_32x32x16_f16 v[50:65], v[228:231], v[204:207], v[50:65]
	v_mfma_f32_32x32x16_f16 v[34:49], v[232:235], v[204:207], v[34:49]
	s_waitcnt lgkmcnt(10)
	v_mfma_f32_32x32x16_f16 v[18:33], v[228:231], v[208:211], v[18:33]
	v_mfma_f32_32x32x16_f16 v[2:17], v[232:235], v[208:211], v[2:17]
	s_waitcnt lgkmcnt(0)
	s_barrier
; DI f16v mfma32(h8v a, h8v b, f16v c) { return __builtin_amdgcn_mfma_f32_32x32x16_f16(a, b, c, 0, 0, 0); }
; template <bool GATHER>
; DI void gemm256_main(const h16* __restrict__ A, int lda, const int* __restrict__ idx, int m0,
;                      const h16* __restrict__ B, int ldb, int n0, int K, h16* lds, f16v (&acc)[4][2]) {
;     ...
;   for (int kt = 0; kt < nk; ++kt) {
;     const h16* As = lds + (kt & 1) * (512 * LDH);
;     const h16* Bs = As + 256 * LDH;
;     h16* Wn = lds + ((kt & 1) ^ 1) * (512 * LDH);
;     if (kt + 1 < nk) {
; #pragma unroll
;       for (int i = 0; i < 4; ++i) { *(u4v*)&Wn[lr * LDH + lc + 8 * i] = ra[i]; *(u4v*)&Wn[(256 + lr) * LDH + lc + 8 * i] = rb[i]; }
;     }
;     if (kt + 2 < nk) {
; #pragma unroll
;       for (int i = 0; i < 4; ++i) { ra[i] = *(const u4v*)(AP_ + 8 * i); rb[i] = *(const u4v*)(BP_ + 8 * i); }
;       ao += 64; bo += 64;
;     }
; #pragma unroll
;     for (int ks = 0; ks < 4; ++ks) {
;       h8v af[4], bf[2];
; #pragma unroll
;       for (int i = 0; i < 4; ++i) af[i] = *(const h8v*)&As[(wm * 128 + i * 32 + (lane & 31)) * LDH + ks * 16 + 8 * (lane >> 5)];
; #pragma unroll
;       for (int j = 0; j < 2; ++j) bf[j] = *(const h8v*)&Bs[(wn * 64 + j * 32 + (lane & 31)) * LDH + ks * 16 + 8 * (lane >> 5)];
; #pragma unroll
;       for (int i = 0; i < 4; ++i)
; #pragma unroll
;         for (int j = 0; j < 2; ++j) acc[i][j] = mfma32(bf[j], af[i], acc[i][j]);
;     }
;     __syncthreads();
;   }
	ds_read_b128 v[228:231], v194
	ds_read_b128 v[188:191], v192
	ds_read_b128 v[232:235], v194 offset:4608
	ds_read_b128 v[200:203], v192 offset:4608
	ds_read_b128 v[204:207], v192 offset:9216
	ds_read_b128 v[208:211], v192 offset:13824
	v_mfma_f32_32x32x16_f16 v[114:129], v[236:239], v[212:215], v[114:129]
	v_mfma_f32_32x32x16_f16 v[98:113], v[240:243], v[212:215], v[98:113]
	v_mfma_f32_32x32x16_f16 v[82:97], v[236:239], v[216:219], v[82:97]
	v_mfma_f32_32x32x16_f16 v[66:81], v[240:243], v[216:219], v[66:81]
	v_mfma_f32_32x32x16_f16 v[50:65], v[236:239], v[220:223], v[50:65]
	v_mfma_f32_32x32x16_f16 v[34:49], v[240:243], v[220:223], v[34:49]
	v_mfma_f32_32x32x16_f16 v[18:33], v[236:239], v[224:227], v[18:33]
	v_mfma_f32_32x32x16_f16 v[2:17], v[240:243], v[224:227], v[2:17]
	ds_read_b128 v[236:239], v194 offset:32
	ds_read_b128 v[212:215], v192 offset:32
	ds_read_b128 v[240:243], v194 offset:4640
	ds_read_b128 v[216:219], v192 offset:4640
	ds_read_b128 v[220:223], v192 offset:9248
	ds_read_b128 v[224:227], v192 offset:13856
	s_waitcnt vmcnt(4)
	ds_write_b128 v165, v[130:133]
	ds_write_b128 v165, v[134:137] offset:16
	ds_write_b128 v165, v[138:141] offset:32
	ds_write_b128 v165, v[142:145] offset:48
	global_load_dwordx4 v[130:133], v[162:163], off offset:640
	global_load_dwordx4 v[134:137], v[162:163], off offset:656
	global_load_dwordx4 v[138:141], v[162:163], off offset:672
	global_load_dwordx4 v[142:145], v[162:163], off offset:688
	s_waitcnt lgkmcnt(14)
	v_mfma_f32_32x32x16_f16 v[114:129], v[228:231], v[188:191], v[114:129]
	s_waitcnt lgkmcnt(13)
	v_mfma_f32_32x32x16_f16 v[98:113], v[232:235], v[188:191], v[98:113]
	s_waitcnt lgkmcnt(12)
	v_mfma_f32_32x32x16_f16 v[82:97], v[228:231], v[200:203], v[82:97]
	v_mfma_f32_32x32x16_f16 v[66:81], v[232:235], v[200:203], v[66:81]
	s_waitcnt lgkmcnt(11)
	v_mfma_f32_32x32x16_f16 v[50:65], v[228:231], v[204:207], v[50:65]
	v_mfma_f32_32x32x16_f16 v[34:49], v[232:235], v[204:207], v[34:49]
	s_waitcnt lgkmcnt(10)
	v_mfma_f32_32x32x16_f16 v[18:33], v[228:231], v[208:211], v[18:33]
	v_mfma_f32_32x32x16_f16 v[2:17], v[232:235], v[208:211], v[2:17]
	ds_read_b128 v[228:231], v194 offset:64
	ds_read_b128 v[188:191], v192 offset:64
	ds_read_b128 v[232:235], v194 offset:4672
	ds_read_b128 v[200:203], v192 offset:4672
	ds_read_b128 v[204:207], v192 offset:9280
	ds_read_b128 v[208:211], v192 offset:13888
	s_waitcnt vmcnt(4)
	ds_write_b128 v165, v[146:149] offset:36864
	ds_write_b128 v165, v[150:153] offset:36880
	ds_write_b128 v165, v[154:157] offset:36896
	ds_write_b128 v165, v[158:161] offset:36912
	global_load_dwordx4 v[146:149], v[178:179], off offset:640
	global_load_dwordx4 v[150:153], v[178:179], off offset:656
	global_load_dwordx4 v[154:157], v[178:179], off offset:672
	global_load_dwordx4 v[158:161], v[178:179], off offset:688
	s_waitcnt lgkmcnt(15)
	v_mfma_f32_32x32x16_f16 v[114:129], v[236:239], v[212:215], v[114:129]
	s_waitcnt lgkmcnt(15)
	v_mfma_f32_32x32x16_f16 v[98:113], v[240:243], v[212:215], v[98:113]
	s_waitcnt lgkmcnt(15)
	v_mfma_f32_32x32x16_f16 v[82:97], v[236:239], v[216:219], v[82:97]
	v_mfma_f32_32x32x16_f16 v[66:81], v[240:243], v[216:219], v[66:81]
	s_waitcnt lgkmcnt(15)
	v_mfma_f32_32x32x16_f16 v[50:65], v[236:239], v[220:223], v[50:65]
	v_mfma_f32_32x32x16_f16 v[34:49], v[240:243], v[220:223], v[34:49]
	s_waitcnt lgkmcnt(14)
	v_mfma_f32_32x32x16_f16 v[18:33], v[236:239], v[224:227], v[18:33]
	v_mfma_f32_32x32x16_f16 v[2:17], v[240:243], v[224:227], v[2:17]
	ds_read_b128 v[236:239], v194 offset:96
	ds_read_b128 v[212:215], v192 offset:96
	ds_read_b128 v[240:243], v194 offset:4704
	ds_read_b128 v[216:219], v192 offset:4704
	ds_read_b128 v[220:223], v192 offset:9312
	ds_read_b128 v[224:227], v192 offset:13920
	s_waitcnt lgkmcnt(14)
	v_mfma_f32_32x32x16_f16 v[114:129], v[228:231], v[188:191], v[114:129]
	s_waitcnt lgkmcnt(13)
	v_mfma_f32_32x32x16_f16 v[98:113], v[232:235], v[188:191], v[98:113]
	s_waitcnt lgkmcnt(12)
	v_mfma_f32_32x32x16_f16 v[82:97], v[228:231], v[200:203], v[82:97]
	v_mfma_f32_32x32x16_f16 v[66:81], v[232:235], v[200:203], v[66:81]
	s_waitcnt lgkmcnt(11)
	v_mfma_f32_32x32x16_f16 v[50:65], v[228:231], v[204:207], v[50:65]
	v_mfma_f32_32x32x16_f16 v[34:49], v[232:235], v[204:207], v[34:49]
	s_waitcnt lgkmcnt(10)
	v_mfma_f32_32x32x16_f16 v[18:33], v[228:231], v[208:211], v[18:33]
	v_mfma_f32_32x32x16_f16 v[2:17], v[232:235], v[208:211], v[2:17]
	s_waitcnt lgkmcnt(0)
	s_barrier
; DI f16v mfma32(h8v a, h8v b, f16v c) { return __builtin_amdgcn_mfma_f32_32x32x16_f16(a, b, c, 0, 0, 0); }
; template <bool GATHER>
; DI void gemm256_main(const h16* __restrict__ A, int lda, const int* __restrict__ idx, int m0,
;                      const h16* __restrict__ B, int ldb, int n0, int K, h16* lds, f16v (&acc)[4][2]) {
;     ...
;   for (int kt = 0; kt < nk; ++kt) {
;     const h16* As = lds + (kt & 1) * (512 * LDH);
;     const h16* Bs = As + 256 * LDH;
;     h16* Wn = lds + ((kt & 1) ^ 1) * (512 * LDH);
;     if (kt + 1 < nk) {
; #pragma unroll
;       for (int i = 0; i < 4; ++i) { *(u4v*)&Wn[lr * LDH + lc + 8 * i] = ra[i]; *(u4v*)&Wn[(256 + lr) * LDH + lc + 8 * i] = rb[i]; }
;     }
;     if (kt + 2 < nk) {
; #pragma unroll
;       for (int i = 0; i < 4; ++i) { ra[i] = *(const u4v*)(AP_ + 8 * i); rb[i] = *(const u4v*)(BP_ + 8 * i); }
;       ao += 64; bo += 64;
;     }
; #pragma unroll
;     for (int ks = 0; ks < 4; ++ks) {
;       h8v af[4], bf[2];
; #pragma unroll
;       for (int i = 0; i < 4; ++i) af[i] = *(const h8v*)&As[(wm * 128 + i * 32 + (lane & 31)) * LDH + ks * 16 + 8 * (lane >> 5)];
; #pragma unroll
;       for (int j = 0; j < 2; ++j) bf[j] = *(const h8v*)&Bs[(wn * 64 + j * 32 + (lane & 31)) * LDH + ks * 16 + 8 * (lane >> 5)];
; #pragma unroll
;       for (int i = 0; i < 4; ++i)
; #pragma unroll
;         for (int j = 0; j < 2; ++j) acc[i][j] = mfma32(bf[j], af[i], acc[i][j]);
;     }
;     __syncthreads();
;   }
	ds_read_b128 v[228:231], v193
	ds_read_b128 v[188:191], v177
	ds_read_b128 v[232:235], v193 offset:4608
	ds_read_b128 v[200:203], v177 offset:4608
	ds_read_b128 v[204:207], v177 offset:9216
	ds_read_b128 v[208:211], v177 offset:13824
	v_mfma_f32_32x32x16_f16 v[114:129], v[236:239], v[212:215], v[114:129]
	v_mfma_f32_32x32x16_f16 v[98:113], v[240:243], v[212:215], v[98:113]
	v_mfma_f32_32x32x16_f16 v[82:97], v[236:239], v[216:219], v[82:97]
	v_mfma_f32_32x32x16_f16 v[66:81], v[240:243], v[216:219], v[66:81]
	v_mfma_f32_32x32x16_f16 v[50:65], v[236:239], v[220:223], v[50:65]
	v_mfma_f32_32x32x16_f16 v[34:49], v[240:243], v[220:223], v[34:49]
	v_mfma_f32_32x32x16_f16 v[18:33], v[236:239], v[224:227], v[18:33]
	v_mfma_f32_32x32x16_f16 v[2:17], v[240:243], v[224:227], v[2:17]
	ds_read_b128 v[236:239], v193 offset:32
	ds_read_b128 v[212:215], v177 offset:32
	ds_read_b128 v[240:243], v193 offset:4640
	ds_read_b128 v[216:219], v177 offset:4640
	ds_read_b128 v[220:223], v177 offset:9248
	ds_read_b128 v[224:227], v177 offset:13856
	s_waitcnt vmcnt(4)
	ds_write_b128 v175, v[130:133]
	ds_write_b128 v175, v[134:137] offset:16
	ds_write_b128 v175, v[138:141] offset:32
	ds_write_b128 v175, v[142:145] offset:48
	global_load_dwordx4 v[130:133], v[162:163], off offset:768
	global_load_dwordx4 v[134:137], v[162:163], off offset:784
	global_load_dwordx4 v[138:141], v[162:163], off offset:800
	global_load_dwordx4 v[142:145], v[162:163], off offset:816
	s_waitcnt lgkmcnt(14)
	v_mfma_f32_32x32x16_f16 v[114:129], v[228:231], v[188:191], v[114:129]
	s_waitcnt lgkmcnt(13)
	v_mfma_f32_32x32x16_f16 v[98:113], v[232:235], v[188:191], v[98:113]
	s_waitcnt lgkmcnt(12)
	v_mfma_f32_32x32x16_f16 v[82:97], v[228:231], v[200:203], v[82:97]
	v_mfma_f32_32x32x16_f16 v[66:81], v[232:235], v[200:203], v[66:81]
	s_waitcnt lgkmcnt(11)
	v_mfma_f32_32x32x16_f16 v[50:65], v[228:231], v[204:207], v[50:65]
	v_mfma_f32_32x32x16_f16 v[34:49], v[232:235], v[204:207], v[34:49]
	s_waitcnt lgkmcnt(10)
	v_mfma_f32_32x32x16_f16 v[18:33], v[228:231], v[208:211], v[18:33]
	v_mfma_f32_32x32x16_f16 v[2:17], v[232:235], v[208:211], v[2:17]
	ds_read_b128 v[228:231], v193 offset:64
	ds_read_b128 v[188:191], v177 offset:64
	ds_read_b128 v[232:235], v193 offset:4672
	ds_read_b128 v[200:203], v177 offset:4672
	ds_read_b128 v[204:207], v177 offset:9280
	ds_read_b128 v[208:211], v177 offset:13888
	s_waitcnt vmcnt(4)
	ds_write_b128 v175, v[146:149] offset:36864
	ds_write_b128 v175, v[150:153] offset:36880
	ds_write_b128 v175, v[154:157] offset:36896
	ds_write_b128 v175, v[158:161] offset:36912
	global_load_dwordx4 v[146:149], v[178:179], off offset:768
	global_load_dwordx4 v[150:153], v[178:179], off offset:784
	global_load_dwordx4 v[154:157], v[178:179], off offset:800
	global_load_dwordx4 v[158:161], v[178:179], off offset:816
	s_waitcnt lgkmcnt(15)
	v_mfma_f32_32x32x16_f16 v[114:129], v[236:239], v[212:215], v[114:129]
	s_waitcnt lgkmcnt(15)
	v_mfma_f32_32x32x16_f16 v[98:113], v[240:243], v[212:215], v[98:113]
	s_waitcnt lgkmcnt(15)
	v_mfma_f32_32x32x16_f16 v[82:97], v[236:239], v[216:219], v[82:97]
	v_mfma_f32_32x32x16_f16 v[66:81], v[240:243], v[216:219], v[66:81]
	s_waitcnt lgkmcnt(15)
	v_mfma_f32_32x32x16_f16 v[50:65], v[236:239], v[220:223], v[50:65]
	v_mfma_f32_32x32x16_f16 v[34:49], v[240:243], v[220:223], v[34:49]
	s_waitcnt lgkmcnt(14)
	v_mfma_f32_32x32x16_f16 v[18:33], v[236:239], v[224:227], v[18:33]
	v_mfma_f32_32x32x16_f16 v[2:17], v[240:243], v[224:227], v[2:17]
	ds_read_b128 v[236:239], v193 offset:96
	ds_read_b128 v[212:215], v177 offset:96
	ds_read_b128 v[240:243], v193 offset:4704
	ds_read_b128 v[216:219], v177 offset:4704
	ds_read_b128 v[220:223], v177 offset:9312
	ds_read_b128 v[224:227], v177 offset:13920
	s_waitcnt lgkmcnt(14)
	v_mfma_f32_32x32x16_f16 v[114:129], v[228:231], v[188:191], v[114:129]
	s_waitcnt lgkmcnt(13)
	v_mfma_f32_32x32x16_f16 v[98:113], v[232:235], v[188:191], v[98:113]
	s_waitcnt lgkmcnt(12)
	v_mfma_f32_32x32x16_f16 v[82:97], v[228:231], v[200:203], v[82:97]
	v_mfma_f32_32x32x16_f16 v[66:81], v[232:235], v[200:203], v[66:81]
	s_waitcnt lgkmcnt(11)
	v_mfma_f32_32x32x16_f16 v[50:65], v[228:231], v[204:207], v[50:65]
	v_mfma_f32_32x32x16_f16 v[34:49], v[232:235], v[204:207], v[34:49]
	s_waitcnt lgkmcnt(10)
	v_mfma_f32_32x32x16_f16 v[18:33], v[228:231], v[208:211], v[18:33]
	v_mfma_f32_32x32x16_f16 v[2:17], v[232:235], v[208:211], v[2:17]
	s_waitcnt lgkmcnt(0)
	s_barrier
; DI f16v mfma32(h8v a, h8v b, f16v c) { return __builtin_amdgcn_mfma_f32_32x32x16_f16(a, b, c, 0, 0, 0); }
; template <bool GATHER>
; DI void gemm256_main(const h16* __restrict__ A, int lda, const int* __restrict__ idx, int m0,
;                      const h16* __restrict__ B, int ldb, int n0, int K, h16* lds, f16v (&acc)[4][2]) {
;     ...
;   for (int kt = 0; kt < nk; ++kt) {
;     const h16* As = lds + (kt & 1) * (512 * LDH);
;     const h16* Bs = As + 256 * LDH;
;     h16* Wn = lds + ((kt & 1) ^ 1) * (512 * LDH);
;     if (kt + 1 < nk) {
; #pragma unroll
;       for (int i = 0; i < 4; ++i) { *(u4v*)&Wn[lr * LDH + lc + 8 * i] = ra[i]; *(u4v*)&Wn[(256 + lr) * LDH + lc + 8 * i] = rb[i]; }
;     }
;     if (kt + 2 < nk) {
; #pragma unroll
;       for (int i = 0; i < 4; ++i) { ra[i] = *(const u4v*)(AP_ + 8 * i); rb[i] = *(const u4v*)(BP_ + 8 * i); }
;       ao += 64; bo += 64;
;     }
; #pragma unroll
;     for (int ks = 0; ks < 4; ++ks) {
;       h8v af[4], bf[2];
; #pragma unroll
;       for (int i = 0; i < 4; ++i) af[i] = *(const h8v*)&As[(wm * 128 + i * 32 + (lane & 31)) * LDH + ks * 16 + 8 * (lane >> 5)];
; #pragma unroll
;       for (int j = 0; j < 2; ++j) bf[j] = *(const h8v*)&Bs[(wn * 64 + j * 32 + (lane & 31)) * LDH + ks * 16 + 8 * (lane >> 5)];
; #pragma unroll
;       for (int i = 0; i < 4; ++i)
; #pragma unroll
;         for (int j = 0; j < 2; ++j) acc[i][j] = mfma32(bf[j], af[i], acc[i][j]);
;     }
;     __syncthreads();
;   }
	ds_read_b128 v[228:231], v194
	ds_read_b128 v[188:191], v192
	ds_read_b128 v[232:235], v194 offset:4608
	ds_read_b128 v[200:203], v192 offset:4608
	ds_read_b128 v[204:207], v192 offset:9216
	ds_read_b128 v[208:211], v192 offset:13824
	v_mfma_f32_32x32x16_f16 v[114:129], v[236:239], v[212:215], v[114:129]
	v_mfma_f32_32x32x16_f16 v[98:113], v[240:243], v[212:215], v[98:113]
	v_mfma_f32_32x32x16_f16 v[82:97], v[236:239], v[216:219], v[82:97]
	v_mfma_f32_32x32x16_f16 v[66:81], v[240:243], v[216:219], v[66:81]
	v_mfma_f32_32x32x16_f16 v[50:65], v[236:239], v[220:223], v[50:65]
	v_mfma_f32_32x32x16_f16 v[34:49], v[240:243], v[220:223], v[34:49]
	v_mfma_f32_32x32x16_f16 v[18:33], v[236:239], v[224:227], v[18:33]
	v_mfma_f32_32x32x16_f16 v[2:17], v[240:243], v[224:227], v[2:17]
	ds_read_b128 v[236:239], v194 offset:32
	ds_read_b128 v[212:215], v192 offset:32
	ds_read_b128 v[240:243], v194 offset:4640
	ds_read_b128 v[216:219], v192 offset:4640
	ds_read_b128 v[220:223], v192 offset:9248
	ds_read_b128 v[224:227], v192 offset:13856
	s_waitcnt vmcnt(4)
	ds_write_b128 v165, v[130:133]
	ds_write_b128 v165, v[134:137] offset:16
	ds_write_b128 v165, v[138:141] offset:32
	ds_write_b128 v165, v[142:145] offset:48
	global_load_dwordx4 v[130:133], v[162:163], off offset:896
	global_load_dwordx4 v[134:137], v[162:163], off offset:912
	global_load_dwordx4 v[138:141], v[162:163], off offset:928
	global_load_dwordx4 v[142:145], v[162:163], off offset:944
	s_waitcnt lgkmcnt(14)
	v_mfma_f32_32x32x16_f16 v[114:129], v[228:231], v[188:191], v[114:129]
	s_waitcnt lgkmcnt(13)
	v_mfma_f32_32x32x16_f16 v[98:113], v[232:235], v[188:191], v[98:113]
	s_waitcnt lgkmcnt(12)
	v_mfma_f32_32x32x16_f16 v[82:97], v[228:231], v[200:203], v[82:97]
	v_mfma_f32_32x32x16_f16 v[66:81], v[232:235], v[200:203], v[66:81]
	s_waitcnt lgkmcnt(11)
	v_mfma_f32_32x32x16_f16 v[50:65], v[228:231], v[204:207], v[50:65]
	v_mfma_f32_32x32x16_f16 v[34:49], v[232:235], v[204:207], v[34:49]
	s_waitcnt lgkmcnt(10)
	v_mfma_f32_32x32x16_f16 v[18:33], v[228:231], v[208:211], v[18:33]
	v_mfma_f32_32x32x16_f16 v[2:17], v[232:235], v[208:211], v[2:17]
	ds_read_b128 v[228:231], v194 offset:64
	ds_read_b128 v[188:191], v192 offset:64
	ds_read_b128 v[232:235], v194 offset:4672
	ds_read_b128 v[200:203], v192 offset:4672
	ds_read_b128 v[204:207], v192 offset:9280
	ds_read_b128 v[208:211], v192 offset:13888
	s_waitcnt vmcnt(4)
	ds_write_b128 v165, v[146:149] offset:36864
	ds_write_b128 v165, v[150:153] offset:36880
	ds_write_b128 v165, v[154:157] offset:36896
	ds_write_b128 v165, v[158:161] offset:36912
	global_load_dwordx4 v[146:149], v[178:179], off offset:896
	global_load_dwordx4 v[150:153], v[178:179], off offset:912
	global_load_dwordx4 v[154:157], v[178:179], off offset:928
	global_load_dwordx4 v[158:161], v[178:179], off offset:944
	s_waitcnt lgkmcnt(15)
	v_mfma_f32_32x32x16_f16 v[114:129], v[236:239], v[212:215], v[114:129]
	s_waitcnt lgkmcnt(15)
	v_mfma_f32_32x32x16_f16 v[98:113], v[240:243], v[212:215], v[98:113]
	s_waitcnt lgkmcnt(15)
	v_mfma_f32_32x32x16_f16 v[82:97], v[236:239], v[216:219], v[82:97]
	v_mfma_f32_32x32x16_f16 v[66:81], v[240:243], v[216:219], v[66:81]
	s_waitcnt lgkmcnt(15)
	v_mfma_f32_32x32x16_f16 v[50:65], v[236:239], v[220:223], v[50:65]
	v_mfma_f32_32x32x16_f16 v[34:49], v[240:243], v[220:223], v[34:49]
	s_waitcnt lgkmcnt(14)
	v_mfma_f32_32x32x16_f16 v[18:33], v[236:239], v[224:227], v[18:33]
	v_mfma_f32_32x32x16_f16 v[2:17], v[240:243], v[224:227], v[2:17]
	ds_read_b128 v[236:239], v194 offset:96
	ds_read_b128 v[212:215], v192 offset:96
	ds_read_b128 v[240:243], v194 offset:4704
	ds_read_b128 v[216:219], v192 offset:4704
	ds_read_b128 v[220:223], v192 offset:9312
	ds_read_b128 v[224:227], v192 offset:13920
	s_waitcnt lgkmcnt(14)
	v_mfma_f32_32x32x16_f16 v[114:129], v[228:231], v[188:191], v[114:129]
	s_waitcnt lgkmcnt(13)
	v_mfma_f32_32x32x16_f16 v[98:113], v[232:235], v[188:191], v[98:113]
	s_waitcnt lgkmcnt(12)
	v_mfma_f32_32x32x16_f16 v[82:97], v[228:231], v[200:203], v[82:97]
	v_mfma_f32_32x32x16_f16 v[66:81], v[232:235], v[200:203], v[66:81]
	s_waitcnt lgkmcnt(11)
	v_mfma_f32_32x32x16_f16 v[50:65], v[228:231], v[204:207], v[50:65]
	v_mfma_f32_32x32x16_f16 v[34:49], v[232:235], v[204:207], v[34:49]
	s_waitcnt lgkmcnt(10)
	v_mfma_f32_32x32x16_f16 v[18:33], v[228:231], v[208:211], v[18:33]
	v_mfma_f32_32x32x16_f16 v[2:17], v[232:235], v[208:211], v[2:17]
	s_waitcnt lgkmcnt(0)
	s_barrier
; DI f16v mfma32(h8v a, h8v b, f16v c) { return __builtin_amdgcn_mfma_f32_32x32x16_f16(a, b, c, 0, 0, 0); }
; template <bool GATHER>
; DI void gemm256_main(const h16* __restrict__ A, int lda, const int* __restrict__ idx, int m0,
;                      const h16* __restrict__ B, int ldb, int n0, int K, h16* lds, f16v (&acc)[4][2]) {
;     ...
;   for (int kt = 0; kt < nk; ++kt) {
;     const h16* As = lds + (kt & 1) * (512 * LDH);
;     const h16* Bs = As + 256 * LDH;
;     h16* Wn = lds + ((kt & 1) ^ 1) * (512 * LDH);
;     if (kt + 1 < nk) {
; #pragma unroll
;       for (int i = 0; i < 4; ++i) { *(u4v*)&Wn[lr * LDH + lc + 8 * i] = ra[i]; *(u4v*)&Wn[(256 + lr) * LDH + lc + 8 * i] = rb[i]; }
;     }
;     if (kt + 2 < nk) {
; #pragma unroll
;       for (int i = 0; i < 4; ++i) { ra[i] = *(const u4v*)(AP_ + 8 * i); rb[i] = *(const u4v*)(BP_ + 8 * i); }
;       ao += 64; bo += 64;
;     }
; #pragma unroll
;     for (int ks = 0; ks < 4; ++ks) {
;       h8v af[4], bf[2];
; #pragma unroll
;       for (int i = 0; i < 4; ++i) af[i] = *(const h8v*)&As[(wm * 128 + i * 32 + (lane & 31)) * LDH + ks * 16 + 8 * (lane >> 5)];
; #pragma unroll
;       for (int j = 0; j < 2; ++j) bf[j] = *(const h8v*)&Bs[(wn * 64 + j * 32 + (lane & 31)) * LDH + ks * 16 + 8 * (lane >> 5)];
; #pragma unroll
;       for (int i = 0; i < 4; ++i)
; #pragma unroll
;         for (int j = 0; j < 2; ++j) acc[i][j] = mfma32(bf[j], af[i], acc[i][j]);
;     }
;     __syncthreads();
;   }
	ds_read_b128 v[228:231], v193
	ds_read_b128 v[188:191], v177
	ds_read_b128 v[232:235], v193 offset:4608
	ds_read_b128 v[200:203], v177 offset:4608
	ds_read_b128 v[204:207], v177 offset:9216
	ds_read_b128 v[208:211], v177 offset:13824
	v_mfma_f32_32x32x16_f16 v[114:129], v[236:239], v[212:215], v[114:129]
	v_mfma_f32_32x32x16_f16 v[98:113], v[240:243], v[212:215], v[98:113]
	v_mfma_f32_32x32x16_f16 v[82:97], v[236:239], v[216:219], v[82:97]
	v_mfma_f32_32x32x16_f16 v[66:81], v[240:243], v[216:219], v[66:81]
	v_mfma_f32_32x32x16_f16 v[50:65], v[236:239], v[220:223], v[50:65]
	v_mfma_f32_32x32x16_f16 v[34:49], v[240:243], v[220:223], v[34:49]
	v_mfma_f32_32x32x16_f16 v[18:33], v[236:239], v[224:227], v[18:33]
	v_mfma_f32_32x32x16_f16 v[2:17], v[240:243], v[224:227], v[2:17]
	ds_read_b128 v[236:239], v193 offset:32
	ds_read_b128 v[212:215], v177 offset:32
	ds_read_b128 v[240:243], v193 offset:4640
	ds_read_b128 v[216:219], v177 offset:4640
	ds_read_b128 v[220:223], v177 offset:9248
	ds_read_b128 v[224:227], v177 offset:13856
	s_waitcnt vmcnt(4)
	ds_write_b128 v175, v[130:133]
	ds_write_b128 v175, v[134:137] offset:16
	ds_write_b128 v175, v[138:141] offset:32
	ds_write_b128 v175, v[142:145] offset:48
	global_load_dwordx4 v[130:133], v[162:163], off offset:1024
	global_load_dwordx4 v[134:137], v[162:163], off offset:1040
	global_load_dwordx4 v[138:141], v[162:163], off offset:1056
	global_load_dwordx4 v[142:145], v[162:163], off offset:1072
	s_waitcnt lgkmcnt(14)
	v_mfma_f32_32x32x16_f16 v[114:129], v[228:231], v[188:191], v[114:129]
	s_waitcnt lgkmcnt(13)
	v_mfma_f32_32x32x16_f16 v[98:113], v[232:235], v[188:191], v[98:113]
	s_waitcnt lgkmcnt(12)
	v_mfma_f32_32x32x16_f16 v[82:97], v[228:231], v[200:203], v[82:97]
	v_mfma_f32_32x32x16_f16 v[66:81], v[232:235], v[200:203], v[66:81]
	s_waitcnt lgkmcnt(11)
	v_mfma_f32_32x32x16_f16 v[50:65], v[228:231], v[204:207], v[50:65]
	v_mfma_f32_32x32x16_f16 v[34:49], v[232:235], v[204:207], v[34:49]
	s_waitcnt lgkmcnt(10)
	v_mfma_f32_32x32x16_f16 v[18:33], v[228:231], v[208:211], v[18:33]
	v_mfma_f32_32x32x16_f16 v[2:17], v[232:235], v[208:211], v[2:17]
	ds_read_b128 v[228:231], v193 offset:64
	ds_read_b128 v[188:191], v177 offset:64
	ds_read_b128 v[232:235], v193 offset:4672
	ds_read_b128 v[200:203], v177 offset:4672
	ds_read_b128 v[204:207], v177 offset:9280
	ds_read_b128 v[208:211], v177 offset:13888
	s_waitcnt vmcnt(4)
	ds_write_b128 v175, v[146:149] offset:36864
	ds_write_b128 v175, v[150:153] offset:36880
	ds_write_b128 v175, v[154:157] offset:36896
	ds_write_b128 v175, v[158:161] offset:36912
	global_load_dwordx4 v[146:149], v[178:179], off offset:1024
	global_load_dwordx4 v[150:153], v[178:179], off offset:1040
	global_load_dwordx4 v[154:157], v[178:179], off offset:1056
	global_load_dwordx4 v[158:161], v[178:179], off offset:1072
	s_waitcnt lgkmcnt(15)
	v_mfma_f32_32x32x16_f16 v[114:129], v[236:239], v[212:215], v[114:129]
	s_waitcnt lgkmcnt(15)
	v_mfma_f32_32x32x16_f16 v[98:113], v[240:243], v[212:215], v[98:113]
	s_waitcnt lgkmcnt(15)
	v_mfma_f32_32x32x16_f16 v[82:97], v[236:239], v[216:219], v[82:97]
	v_mfma_f32_32x32x16_f16 v[66:81], v[240:243], v[216:219], v[66:81]
	s_waitcnt lgkmcnt(15)
	v_mfma_f32_32x32x16_f16 v[50:65], v[236:239], v[220:223], v[50:65]
	v_mfma_f32_32x32x16_f16 v[34:49], v[240:243], v[220:223], v[34:49]
	s_waitcnt lgkmcnt(14)
	v_mfma_f32_32x32x16_f16 v[18:33], v[236:239], v[224:227], v[18:33]
	v_mfma_f32_32x32x16_f16 v[2:17], v[240:243], v[224:227], v[2:17]
	ds_read_b128 v[236:239], v193 offset:96
	ds_read_b128 v[212:215], v177 offset:96
	ds_read_b128 v[240:243], v193 offset:4704
	ds_read_b128 v[216:219], v177 offset:4704
	ds_read_b128 v[220:223], v177 offset:9312
	ds_read_b128 v[224:227], v177 offset:13920
	s_waitcnt lgkmcnt(14)
	v_mfma_f32_32x32x16_f16 v[114:129], v[228:231], v[188:191], v[114:129]
	s_waitcnt lgkmcnt(13)
	v_mfma_f32_32x32x16_f16 v[98:113], v[232:235], v[188:191], v[98:113]
	s_waitcnt lgkmcnt(12)
	v_mfma_f32_32x32x16_f16 v[82:97], v[228:231], v[200:203], v[82:97]
	v_mfma_f32_32x32x16_f16 v[66:81], v[232:235], v[200:203], v[66:81]
	s_waitcnt lgkmcnt(11)
	v_mfma_f32_32x32x16_f16 v[50:65], v[228:231], v[204:207], v[50:65]
	v_mfma_f32_32x32x16_f16 v[34:49], v[232:235], v[204:207], v[34:49]
	s_waitcnt lgkmcnt(10)
	v_mfma_f32_32x32x16_f16 v[18:33], v[228:231], v[208:211], v[18:33]
	v_mfma_f32_32x32x16_f16 v[2:17], v[232:235], v[208:211], v[2:17]
	s_waitcnt lgkmcnt(0)
	s_barrier
; DI f16v mfma32(h8v a, h8v b, f16v c) { return __builtin_amdgcn_mfma_f32_32x32x16_f16(a, b, c, 0, 0, 0); }
; template <bool GATHER>
; DI void gemm256_main(const h16* __restrict__ A, int lda, const int* __restrict__ idx, int m0,
;                      const h16* __restrict__ B, int ldb, int n0, int K, h16* lds, f16v (&acc)[4][2]) {
;     ...
;   for (int kt = 0; kt < nk; ++kt) {
;     const h16* As = lds + (kt & 1) * (512 * LDH);
;     const h16* Bs = As + 256 * LDH;
;     h16* Wn = lds + ((kt & 1) ^ 1) * (512 * LDH);
;     if (kt + 1 < nk) {
; #pragma unroll
;       for (int i = 0; i < 4; ++i) { *(u4v*)&Wn[lr * LDH + lc + 8 * i] = ra[i]; *(u4v*)&Wn[(256 + lr) * LDH + lc + 8 * i] = rb[i]; }
;     }
;     if (kt + 2 < nk) {
; #pragma unroll
;       for (int i = 0; i < 4; ++i) { ra[i] = *(const u4v*)(AP_ + 8 * i); rb[i] = *(const u4v*)(BP_ + 8 * i); }
;       ao += 64; bo += 64;
;     }
; #pragma unroll
;     for (int ks = 0; ks < 4; ++ks) {
;       h8v af[4], bf[2];
; #pragma unroll
;       for (int i = 0; i < 4; ++i) af[i] = *(const h8v*)&As[(wm * 128 + i * 32 + (lane & 31)) * LDH + ks * 16 + 8 * (lane >> 5)];
; #pragma unroll
;       for (int j = 0; j < 2; ++j) bf[j] = *(const h8v*)&Bs[(wn * 64 + j * 32 + (lane & 31)) * LDH + ks * 16 + 8 * (lane >> 5)];
; #pragma unroll
;       for (int i = 0; i < 4; ++i)
; #pragma unroll
;         for (int j = 0; j < 2; ++j) acc[i][j] = mfma32(bf[j], af[i], acc[i][j]);
;     }
;     __syncthreads();
;   }
	ds_read_b128 v[228:231], v194
	ds_read_b128 v[188:191], v192
	ds_read_b128 v[232:235], v194 offset:4608
	ds_read_b128 v[200:203], v192 offset:4608
	ds_read_b128 v[204:207], v192 offset:9216
	ds_read_b128 v[208:211], v192 offset:13824
	v_mfma_f32_32x32x16_f16 v[114:129], v[236:239], v[212:215], v[114:129]
	v_mfma_f32_32x32x16_f16 v[98:113], v[240:243], v[212:215], v[98:113]
	v_mfma_f32_32x32x16_f16 v[82:97], v[236:239], v[216:219], v[82:97]
	v_mfma_f32_32x32x16_f16 v[66:81], v[240:243], v[216:219], v[66:81]
	v_mfma_f32_32x32x16_f16 v[50:65], v[236:239], v[220:223], v[50:65]
	v_mfma_f32_32x32x16_f16 v[34:49], v[240:243], v[220:223], v[34:49]
	v_mfma_f32_32x32x16_f16 v[18:33], v[236:239], v[224:227], v[18:33]
	v_mfma_f32_32x32x16_f16 v[2:17], v[240:243], v[224:227], v[2:17]
	ds_read_b128 v[236:239], v194 offset:32
	ds_read_b128 v[212:215], v192 offset:32
	ds_read_b128 v[240:243], v194 offset:4640
	ds_read_b128 v[216:219], v192 offset:4640
	ds_read_b128 v[220:223], v192 offset:9248
	ds_read_b128 v[224:227], v192 offset:13856
	s_waitcnt vmcnt(4)
	ds_write_b128 v165, v[130:133]
	ds_write_b128 v165, v[134:137] offset:16
	ds_write_b128 v165, v[138:141] offset:32
	ds_write_b128 v165, v[142:145] offset:48
	global_load_dwordx4 v[130:133], v[162:163], off offset:1152
	global_load_dwordx4 v[134:137], v[162:163], off offset:1168
	global_load_dwordx4 v[138:141], v[162:163], off offset:1184
	global_load_dwordx4 v[142:145], v[162:163], off offset:1200
	s_waitcnt lgkmcnt(14)
	v_mfma_f32_32x32x16_f16 v[114:129], v[228:231], v[188:191], v[114:129]
	s_waitcnt lgkmcnt(13)
	v_mfma_f32_32x32x16_f16 v[98:113], v[232:235], v[188:191], v[98:113]
	s_waitcnt lgkmcnt(12)
	v_mfma_f32_32x32x16_f16 v[82:97], v[228:231], v[200:203], v[82:97]
	v_mfma_f32_32x32x16_f16 v[66:81], v[232:235], v[200:203], v[66:81]
	s_waitcnt lgkmcnt(11)
	v_mfma_f32_32x32x16_f16 v[50:65], v[228:231], v[204:207], v[50:65]
	v_mfma_f32_32x32x16_f16 v[34:49], v[232:235], v[204:207], v[34:49]
	s_waitcnt lgkmcnt(10)
	v_mfma_f32_32x32x16_f16 v[18:33], v[228:231], v[208:211], v[18:33]
	v_mfma_f32_32x32x16_f16 v[2:17], v[232:235], v[208:211], v[2:17]
	ds_read_b128 v[228:231], v194 offset:64
	ds_read_b128 v[188:191], v192 offset:64
	ds_read_b128 v[232:235], v194 offset:4672
	ds_read_b128 v[200:203], v192 offset:4672
	ds_read_b128 v[204:207], v192 offset:9280
	ds_read_b128 v[208:211], v192 offset:13888
	s_waitcnt vmcnt(4)
	ds_write_b128 v165, v[146:149] offset:36864
	ds_write_b128 v165, v[150:153] offset:36880
	ds_write_b128 v165, v[154:157] offset:36896
	ds_write_b128 v165, v[158:161] offset:36912
	global_load_dwordx4 v[146:149], v[178:179], off offset:1152
	global_load_dwordx4 v[150:153], v[178:179], off offset:1168
	global_load_dwordx4 v[154:157], v[178:179], off offset:1184
	global_load_dwordx4 v[158:161], v[178:179], off offset:1200
	s_waitcnt lgkmcnt(15)
	v_mfma_f32_32x32x16_f16 v[114:129], v[236:239], v[212:215], v[114:129]
	s_waitcnt lgkmcnt(15)
	v_mfma_f32_32x32x16_f16 v[98:113], v[240:243], v[212:215], v[98:113]
	s_waitcnt lgkmcnt(15)
	v_mfma_f32_32x32x16_f16 v[82:97], v[236:239], v[216:219], v[82:97]
	v_mfma_f32_32x32x16_f16 v[66:81], v[240:243], v[216:219], v[66:81]
	s_waitcnt lgkmcnt(15)
	v_mfma_f32_32x32x16_f16 v[50:65], v[236:239], v[220:223], v[50:65]
	v_mfma_f32_32x32x16_f16 v[34:49], v[240:243], v[220:223], v[34:49]
	s_waitcnt lgkmcnt(14)
	v_mfma_f32_32x32x16_f16 v[18:33], v[236:239], v[224:227], v[18:33]
	v_mfma_f32_32x32x16_f16 v[2:17], v[240:243], v[224:227], v[2:17]
	ds_read_b128 v[236:239], v194 offset:96
	ds_read_b128 v[212:215], v192 offset:96
	ds_read_b128 v[240:243], v194 offset:4704
	ds_read_b128 v[216:219], v192 offset:4704
	ds_read_b128 v[220:223], v192 offset:9312
	ds_read_b128 v[224:227], v192 offset:13920
	s_waitcnt lgkmcnt(14)
	v_mfma_f32_32x32x16_f16 v[114:129], v[228:231], v[188:191], v[114:129]
	s_waitcnt lgkmcnt(13)
	v_mfma_f32_32x32x16_f16 v[98:113], v[232:235], v[188:191], v[98:113]
	s_waitcnt lgkmcnt(12)
	v_mfma_f32_32x32x16_f16 v[82:97], v[228:231], v[200:203], v[82:97]
	v_mfma_f32_32x32x16_f16 v[66:81], v[232:235], v[200:203], v[66:81]
	s_waitcnt lgkmcnt(11)
	v_mfma_f32_32x32x16_f16 v[50:65], v[228:231], v[204:207], v[50:65]
	v_mfma_f32_32x32x16_f16 v[34:49], v[232:235], v[204:207], v[34:49]
	s_waitcnt lgkmcnt(10)
	v_mfma_f32_32x32x16_f16 v[18:33], v[228:231], v[208:211], v[18:33]
	v_mfma_f32_32x32x16_f16 v[2:17], v[232:235], v[208:211], v[2:17]
	s_waitcnt lgkmcnt(0)
	s_barrier
; DI f16v mfma32(h8v a, h8v b, f16v c) { return __builtin_amdgcn_mfma_f32_32x32x16_f16(a, b, c, 0, 0, 0); }
; template <bool GATHER>
; DI void gemm256_main(const h16* __restrict__ A, int lda, const int* __restrict__ idx, int m0,
;                      const h16* __restrict__ B, int ldb, int n0, int K, h16* lds, f16v (&acc)[4][2]) {
;     ...
;   for (int kt = 0; kt < nk; ++kt) {
;     const h16* As = lds + (kt & 1) * (512 * LDH);
;     const h16* Bs = As + 256 * LDH;
;     h16* Wn = lds + ((kt & 1) ^ 1) * (512 * LDH);
;     if (kt + 1 < nk) {
; #pragma unroll
;       for (int i = 0; i < 4; ++i) { *(u4v*)&Wn[lr * LDH + lc + 8 * i] = ra[i]; *(u4v*)&Wn[(256 + lr) * LDH + lc + 8 * i] = rb[i]; }
;     }
;     if (kt + 2 < nk) {
; #pragma unroll
;       for (int i = 0; i < 4; ++i) { ra[i] = *(const u4v*)(AP_ + 8 * i); rb[i] = *(const u4v*)(BP_ + 8 * i); }
;       ao += 64; bo += 64;
;     }
; #pragma unroll
;     for (int ks = 0; ks < 4; ++ks) {
;       h8v af[4], bf[2];
; #pragma unroll
;       for (int i = 0; i < 4; ++i) af[i] = *(const h8v*)&As[(wm * 128 + i * 32 + (lane & 31)) * LDH + ks * 16 + 8 * (lane >> 5)];
; #pragma unroll
;       for (int j = 0; j < 2; ++j) bf[j] = *(const h8v*)&Bs[(wn * 64 + j * 32 + (lane & 31)) * LDH + ks * 16 + 8 * (lane >> 5)];
; #pragma unroll
;       for (int i = 0; i < 4; ++i)
; #pragma unroll
;         for (int j = 0; j < 2; ++j) acc[i][j] = mfma32(bf[j], af[i], acc[i][j]);
;     }
;     __syncthreads();
;   }
	ds_read_b128 v[228:231], v193
	ds_read_b128 v[188:191], v177
	ds_read_b128 v[232:235], v193 offset:4608
	ds_read_b128 v[200:203], v177 offset:4608
	ds_read_b128 v[204:207], v177 offset:9216
	ds_read_b128 v[208:211], v177 offset:13824
	v_mfma_f32_32x32x16_f16 v[114:129], v[236:239], v[212:215], v[114:129]
	v_mfma_f32_32x32x16_f16 v[98:113], v[240:243], v[212:215], v[98:113]
	v_mfma_f32_32x32x16_f16 v[82:97], v[236:239], v[216:219], v[82:97]
	v_mfma_f32_32x32x16_f16 v[66:81], v[240:243], v[216:219], v[66:81]
	v_mfma_f32_32x32x16_f16 v[50:65], v[236:239], v[220:223], v[50:65]
	v_mfma_f32_32x32x16_f16 v[34:49], v[240:243], v[220:223], v[34:49]
	v_mfma_f32_32x32x16_f16 v[18:33], v[236:239], v[224:227], v[18:33]
	v_mfma_f32_32x32x16_f16 v[2:17], v[240:243], v[224:227], v[2:17]
	ds_read_b128 v[236:239], v193 offset:32
	ds_read_b128 v[212:215], v177 offset:32
	ds_read_b128 v[240:243], v193 offset:4640
	ds_read_b128 v[216:219], v177 offset:4640
	ds_read_b128 v[220:223], v177 offset:9248
	ds_read_b128 v[224:227], v177 offset:13856
	s_waitcnt vmcnt(4)
	ds_write_b128 v175, v[130:133]
	ds_write_b128 v175, v[134:137] offset:16
	ds_write_b128 v175, v[138:141] offset:32
	ds_write_b128 v175, v[142:145] offset:48
	global_load_dwordx4 v[130:133], v[162:163], off offset:1280
	global_load_dwordx4 v[134:137], v[162:163], off offset:1296
	global_load_dwordx4 v[138:141], v[162:163], off offset:1312
	global_load_dwordx4 v[142:145], v[162:163], off offset:1328
	s_waitcnt lgkmcnt(14)
	v_mfma_f32_32x32x16_f16 v[114:129], v[228:231], v[188:191], v[114:129]
	s_waitcnt lgkmcnt(13)
	v_mfma_f32_32x32x16_f16 v[98:113], v[232:235], v[188:191], v[98:113]
	s_waitcnt lgkmcnt(12)
	v_mfma_f32_32x32x16_f16 v[82:97], v[228:231], v[200:203], v[82:97]
	v_mfma_f32_32x32x16_f16 v[66:81], v[232:235], v[200:203], v[66:81]
	s_waitcnt lgkmcnt(11)
	v_mfma_f32_32x32x16_f16 v[50:65], v[228:231], v[204:207], v[50:65]
	v_mfma_f32_32x32x16_f16 v[34:49], v[232:235], v[204:207], v[34:49]
	s_waitcnt lgkmcnt(10)
	v_mfma_f32_32x32x16_f16 v[18:33], v[228:231], v[208:211], v[18:33]
	v_mfma_f32_32x32x16_f16 v[2:17], v[232:235], v[208:211], v[2:17]
	ds_read_b128 v[228:231], v193 offset:64
	ds_read_b128 v[188:191], v177 offset:64
	ds_read_b128 v[232:235], v193 offset:4672
	ds_read_b128 v[200:203], v177 offset:4672
	ds_read_b128 v[204:207], v177 offset:9280
	ds_read_b128 v[208:211], v177 offset:13888
	s_waitcnt vmcnt(4)
	ds_write_b128 v175, v[146:149] offset:36864
	ds_write_b128 v175, v[150:153] offset:36880
	ds_write_b128 v175, v[154:157] offset:36896
	ds_write_b128 v175, v[158:161] offset:36912
	global_load_dwordx4 v[146:149], v[178:179], off offset:1280
	global_load_dwordx4 v[150:153], v[178:179], off offset:1296
	global_load_dwordx4 v[154:157], v[178:179], off offset:1312
	global_load_dwordx4 v[158:161], v[178:179], off offset:1328
	s_waitcnt lgkmcnt(15)
	v_mfma_f32_32x32x16_f16 v[114:129], v[236:239], v[212:215], v[114:129]
	s_waitcnt lgkmcnt(15)
	v_mfma_f32_32x32x16_f16 v[98:113], v[240:243], v[212:215], v[98:113]
	s_waitcnt lgkmcnt(15)
	v_mfma_f32_32x32x16_f16 v[82:97], v[236:239], v[216:219], v[82:97]
	v_mfma_f32_32x32x16_f16 v[66:81], v[240:243], v[216:219], v[66:81]
	s_waitcnt lgkmcnt(15)
	v_mfma_f32_32x32x16_f16 v[50:65], v[236:239], v[220:223], v[50:65]
	v_mfma_f32_32x32x16_f16 v[34:49], v[240:243], v[220:223], v[34:49]
	s_waitcnt lgkmcnt(14)
	v_mfma_f32_32x32x16_f16 v[18:33], v[236:239], v[224:227], v[18:33]
	v_mfma_f32_32x32x16_f16 v[2:17], v[240:243], v[224:227], v[2:17]
	ds_read_b128 v[236:239], v193 offset:96
	ds_read_b128 v[212:215], v177 offset:96
	ds_read_b128 v[240:243], v193 offset:4704
	ds_read_b128 v[216:219], v177 offset:4704
	ds_read_b128 v[220:223], v177 offset:9312
	ds_read_b128 v[224:227], v177 offset:13920
	s_waitcnt lgkmcnt(14)
	v_mfma_f32_32x32x16_f16 v[114:129], v[228:231], v[188:191], v[114:129]
	s_waitcnt lgkmcnt(13)
	v_mfma_f32_32x32x16_f16 v[98:113], v[232:235], v[188:191], v[98:113]
	s_waitcnt lgkmcnt(12)
	v_mfma_f32_32x32x16_f16 v[82:97], v[228:231], v[200:203], v[82:97]
	v_mfma_f32_32x32x16_f16 v[66:81], v[232:235], v[200:203], v[66:81]
	s_waitcnt lgkmcnt(11)
	v_mfma_f32_32x32x16_f16 v[50:65], v[228:231], v[204:207], v[50:65]
	v_mfma_f32_32x32x16_f16 v[34:49], v[232:235], v[204:207], v[34:49]
	s_waitcnt lgkmcnt(10)
	v_mfma_f32_32x32x16_f16 v[18:33], v[228:231], v[208:211], v[18:33]
	v_mfma_f32_32x32x16_f16 v[2:17], v[232:235], v[208:211], v[2:17]
	s_waitcnt lgkmcnt(0)
	s_barrier
; DI f16v mfma32(h8v a, h8v b, f16v c) { return __builtin_amdgcn_mfma_f32_32x32x16_f16(a, b, c, 0, 0, 0); }
; template <bool GATHER>
; DI void gemm256_main(const h16* __restrict__ A, int lda, const int* __restrict__ idx, int m0,
;                      const h16* __restrict__ B, int ldb, int n0, int K, h16* lds, f16v (&acc)[4][2]) {
;     ...
;   for (int kt = 0; kt < nk; ++kt) {
;     const h16* As = lds + (kt & 1) * (512 * LDH);
;     const h16* Bs = As + 256 * LDH;
;     h16* Wn = lds + ((kt & 1) ^ 1) * (512 * LDH);
;     if (kt + 1 < nk) {
; #pragma unroll
;       for (int i = 0; i < 4; ++i) { *(u4v*)&Wn[lr * LDH + lc + 8 * i] = ra[i]; *(u4v*)&Wn[(256 + lr) * LDH + lc + 8 * i] = rb[i]; }
;     }
;     if (kt + 2 < nk) {
; #pragma unroll
;       for (int i = 0; i < 4; ++i) { ra[i] = *(const u4v*)(AP_ + 8 * i); rb[i] = *(const u4v*)(BP_ + 8 * i); }
;       ao += 64; bo += 64;
;     }
; #pragma unroll
;     for (int ks = 0; ks < 4; ++ks) {
;       h8v af[4], bf[2];
; #pragma unroll
;       for (int i = 0; i < 4; ++i) af[i] = *(const h8v*)&As[(wm * 128 + i * 32 + (lane & 31)) * LDH + ks * 16 + 8 * (lane >> 5)];
; #pragma unroll
;       for (int j = 0; j < 2; ++j) bf[j] = *(const h8v*)&Bs[(wn * 64 + j * 32 + (lane & 31)) * LDH + ks * 16 + 8 * (lane >> 5)];
; #pragma unroll
;       for (int i = 0; i < 4; ++i)
; #pragma unroll
;         for (int j = 0; j < 2; ++j) acc[i][j] = mfma32(bf[j], af[i], acc[i][j]);
;     }
;     __syncthreads();
;   }
	ds_read_b128 v[228:231], v194
	ds_read_b128 v[188:191], v192
	ds_read_b128 v[232:235], v194 offset:4608
	ds_read_b128 v[200:203], v192 offset:4608
	ds_read_b128 v[204:207], v192 offset:9216
	ds_read_b128 v[208:211], v192 offset:13824
	v_mfma_f32_32x32x16_f16 v[114:129], v[236:239], v[212:215], v[114:129]
	v_mfma_f32_32x32x16_f16 v[98:113], v[240:243], v[212:215], v[98:113]
	v_mfma_f32_32x32x16_f16 v[82:97], v[236:239], v[216:219], v[82:97]
	v_mfma_f32_32x32x16_f16 v[66:81], v[240:243], v[216:219], v[66:81]
	v_mfma_f32_32x32x16_f16 v[50:65], v[236:239], v[220:223], v[50:65]
	v_mfma_f32_32x32x16_f16 v[34:49], v[240:243], v[220:223], v[34:49]
	v_mfma_f32_32x32x16_f16 v[18:33], v[236:239], v[224:227], v[18:33]
	v_mfma_f32_32x32x16_f16 v[2:17], v[240:243], v[224:227], v[2:17]
	ds_read_b128 v[236:239], v194 offset:32
	ds_read_b128 v[212:215], v192 offset:32
	ds_read_b128 v[240:243], v194 offset:4640
	ds_read_b128 v[216:219], v192 offset:4640
	ds_read_b128 v[220:223], v192 offset:9248
	ds_read_b128 v[224:227], v192 offset:13856
	s_waitcnt vmcnt(4)
	ds_write_b128 v165, v[130:133]
	ds_write_b128 v165, v[134:137] offset:16
	ds_write_b128 v165, v[138:141] offset:32
	ds_write_b128 v165, v[142:145] offset:48
	global_load_dwordx4 v[130:133], v[162:163], off offset:1408
	global_load_dwordx4 v[134:137], v[162:163], off offset:1424
	global_load_dwordx4 v[138:141], v[162:163], off offset:1440
	global_load_dwordx4 v[142:145], v[162:163], off offset:1456
	s_waitcnt lgkmcnt(14)
	v_mfma_f32_32x32x16_f16 v[114:129], v[228:231], v[188:191], v[114:129]
	s_waitcnt lgkmcnt(13)
	v_mfma_f32_32x32x16_f16 v[98:113], v[232:235], v[188:191], v[98:113]
	s_waitcnt lgkmcnt(12)
	v_mfma_f32_32x32x16_f16 v[82:97], v[228:231], v[200:203], v[82:97]
	v_mfma_f32_32x32x16_f16 v[66:81], v[232:235], v[200:203], v[66:81]
	s_waitcnt lgkmcnt(11)
	v_mfma_f32_32x32x16_f16 v[50:65], v[228:231], v[204:207], v[50:65]
	v_mfma_f32_32x32x16_f16 v[34:49], v[232:235], v[204:207], v[34:49]
	s_waitcnt lgkmcnt(10)
	v_mfma_f32_32x32x16_f16 v[18:33], v[228:231], v[208:211], v[18:33]
	v_mfma_f32_32x32x16_f16 v[2:17], v[232:235], v[208:211], v[2:17]
	ds_read_b128 v[228:231], v194 offset:64
	ds_read_b128 v[188:191], v192 offset:64
	ds_read_b128 v[232:235], v194 offset:4672
	ds_read_b128 v[200:203], v192 offset:4672
	ds_read_b128 v[204:207], v192 offset:9280
	ds_read_b128 v[208:211], v192 offset:13888
	s_waitcnt vmcnt(4)
	ds_write_b128 v165, v[146:149] offset:36864
	ds_write_b128 v165, v[150:153] offset:36880
	ds_write_b128 v165, v[154:157] offset:36896
	ds_write_b128 v165, v[158:161] offset:36912
	global_load_dwordx4 v[146:149], v[178:179], off offset:1408
	global_load_dwordx4 v[150:153], v[178:179], off offset:1424
	global_load_dwordx4 v[154:157], v[178:179], off offset:1440
	global_load_dwordx4 v[158:161], v[178:179], off offset:1456
	s_waitcnt lgkmcnt(15)
	v_mfma_f32_32x32x16_f16 v[114:129], v[236:239], v[212:215], v[114:129]
	s_waitcnt lgkmcnt(15)
	v_mfma_f32_32x32x16_f16 v[98:113], v[240:243], v[212:215], v[98:113]
	s_waitcnt lgkmcnt(15)
	v_mfma_f32_32x32x16_f16 v[82:97], v[236:239], v[216:219], v[82:97]
	v_mfma_f32_32x32x16_f16 v[66:81], v[240:243], v[216:219], v[66:81]
	s_waitcnt lgkmcnt(15)
	v_mfma_f32_32x32x16_f16 v[50:65], v[236:239], v[220:223], v[50:65]
	v_mfma_f32_32x32x16_f16 v[34:49], v[240:243], v[220:223], v[34:49]
	s_waitcnt lgkmcnt(14)
	v_mfma_f32_32x32x16_f16 v[18:33], v[236:239], v[224:227], v[18:33]
	v_mfma_f32_32x32x16_f16 v[2:17], v[240:243], v[224:227], v[2:17]
	ds_read_b128 v[236:239], v194 offset:96
	ds_read_b128 v[212:215], v192 offset:96
	ds_read_b128 v[240:243], v194 offset:4704
	ds_read_b128 v[216:219], v192 offset:4704
	ds_read_b128 v[220:223], v192 offset:9312
	ds_read_b128 v[224:227], v192 offset:13920
	s_waitcnt lgkmcnt(14)
	v_mfma_f32_32x32x16_f16 v[114:129], v[228:231], v[188:191], v[114:129]
	s_waitcnt lgkmcnt(13)
	v_mfma_f32_32x32x16_f16 v[98:113], v[232:235], v[188:191], v[98:113]
	s_waitcnt lgkmcnt(12)
	v_mfma_f32_32x32x16_f16 v[82:97], v[228:231], v[200:203], v[82:97]
	v_mfma_f32_32x32x16_f16 v[66:81], v[232:235], v[200:203], v[66:81]
	s_waitcnt lgkmcnt(11)
	v_mfma_f32_32x32x16_f16 v[50:65], v[228:231], v[204:207], v[50:65]
	v_mfma_f32_32x32x16_f16 v[34:49], v[232:235], v[204:207], v[34:49]
	s_waitcnt lgkmcnt(10)
	v_mfma_f32_32x32x16_f16 v[18:33], v[228:231], v[208:211], v[18:33]
	v_mfma_f32_32x32x16_f16 v[2:17], v[232:235], v[208:211], v[2:17]
	s_waitcnt lgkmcnt(0)
	s_barrier
; DI f16v mfma32(h8v a, h8v b, f16v c) { return __builtin_amdgcn_mfma_f32_32x32x16_f16(a, b, c, 0, 0, 0); }
; template <bool GATHER>
; DI void gemm256_main(const h16* __restrict__ A, int lda, const int* __restrict__ idx, int m0,
;                      const h16* __restrict__ B, int ldb, int n0, int K, h16* lds, f16v (&acc)[4][2]) {
;     ...
;   for (int kt = 0; kt < nk; ++kt) {
;     const h16* As = lds + (kt & 1) * (512 * LDH);
;     const h16* Bs = As + 256 * LDH;
;     h16* Wn = lds + ((kt & 1) ^ 1) * (512 * LDH);
;     if (kt + 1 < nk) {
; #pragma unroll
;       for (int i = 0; i < 4; ++i) { *(u4v*)&Wn[lr * LDH + lc + 8 * i] = ra[i]; *(u4v*)&Wn[(256 + lr) * LDH + lc + 8 * i] = rb[i]; }
;     }
;     if (kt + 2 < nk) {
; #pragma unroll
;       for (int i = 0; i < 4; ++i) { ra[i] = *(const u4v*)(AP_ + 8 * i); rb[i] = *(const u4v*)(BP_ + 8 * i); }
;       ao += 64; bo += 64;
;     }
; #pragma unroll
;     for (int ks = 0; ks < 4; ++ks) {
;       h8v af[4], bf[2];
; #pragma unroll
;       for (int i = 0; i < 4; ++i) af[i] = *(const h8v*)&As[(wm * 128 + i * 32 + (lane & 31)) * LDH + ks * 16 + 8 * (lane >> 5)];
; #pragma unroll
;       for (int j = 0; j < 2; ++j) bf[j] = *(const h8v*)&Bs[(wn * 64 + j * 32 + (lane & 31)) * LDH + ks * 16 + 8 * (lane >> 5)];
; #pragma unroll
;       for (int i = 0; i < 4; ++i)
; #pragma unroll
;         for (int j = 0; j < 2; ++j) acc[i][j] = mfma32(bf[j], af[i], acc[i][j]);
;     }
;     __syncthreads();
;   }
	ds_read_b128 v[228:231], v193
	ds_read_b128 v[188:191], v177
	ds_read_b128 v[232:235], v193 offset:4608
	ds_read_b128 v[200:203], v177 offset:4608
	ds_read_b128 v[204:207], v177 offset:9216
	ds_read_b128 v[208:211], v177 offset:13824
	v_mfma_f32_32x32x16_f16 v[114:129], v[236:239], v[212:215], v[114:129]
	v_mfma_f32_32x32x16_f16 v[98:113], v[240:243], v[212:215], v[98:113]
	v_mfma_f32_32x32x16_f16 v[82:97], v[236:239], v[216:219], v[82:97]
	v_mfma_f32_32x32x16_f16 v[66:81], v[240:243], v[216:219], v[66:81]
	v_mfma_f32_32x32x16_f16 v[50:65], v[236:239], v[220:223], v[50:65]
	v_mfma_f32_32x32x16_f16 v[34:49], v[240:243], v[220:223], v[34:49]
	v_mfma_f32_32x32x16_f16 v[18:33], v[236:239], v[224:227], v[18:33]
	v_mfma_f32_32x32x16_f16 v[2:17], v[240:243], v[224:227], v[2:17]
	ds_read_b128 v[236:239], v193 offset:32
	ds_read_b128 v[212:215], v177 offset:32
	ds_read_b128 v[240:243], v193 offset:4640
	ds_read_b128 v[216:219], v177 offset:4640
	ds_read_b128 v[220:223], v177 offset:9248
	ds_read_b128 v[224:227], v177 offset:13856
	s_waitcnt vmcnt(4)
	ds_write_b128 v175, v[130:133]
	ds_write_b128 v175, v[134:137] offset:16
	ds_write_b128 v175, v[138:141] offset:32
	ds_write_b128 v175, v[142:145] offset:48
	global_load_dwordx4 v[130:133], v[162:163], off offset:1536
	global_load_dwordx4 v[134:137], v[162:163], off offset:1552
	global_load_dwordx4 v[138:141], v[162:163], off offset:1568
	global_load_dwordx4 v[142:145], v[162:163], off offset:1584
	s_waitcnt lgkmcnt(14)
	v_mfma_f32_32x32x16_f16 v[114:129], v[228:231], v[188:191], v[114:129]
	s_waitcnt lgkmcnt(13)
	v_mfma_f32_32x32x16_f16 v[98:113], v[232:235], v[188:191], v[98:113]
	s_waitcnt lgkmcnt(12)
	v_mfma_f32_32x32x16_f16 v[82:97], v[228:231], v[200:203], v[82:97]
	v_mfma_f32_32x32x16_f16 v[66:81], v[232:235], v[200:203], v[66:81]
	s_waitcnt lgkmcnt(11)
	v_mfma_f32_32x32x16_f16 v[50:65], v[228:231], v[204:207], v[50:65]
	v_mfma_f32_32x32x16_f16 v[34:49], v[232:235], v[204:207], v[34:49]
	s_waitcnt lgkmcnt(10)
	v_mfma_f32_32x32x16_f16 v[18:33], v[228:231], v[208:211], v[18:33]
	v_mfma_f32_32x32x16_f16 v[2:17], v[232:235], v[208:211], v[2:17]
	ds_read_b128 v[228:231], v193 offset:64
	ds_read_b128 v[188:191], v177 offset:64
	ds_read_b128 v[232:235], v193 offset:4672
	ds_read_b128 v[200:203], v177 offset:4672
	ds_read_b128 v[204:207], v177 offset:9280
	ds_read_b128 v[208:211], v177 offset:13888
	s_waitcnt vmcnt(4)
	ds_write_b128 v175, v[146:149] offset:36864
	ds_write_b128 v175, v[150:153] offset:36880
	ds_write_b128 v175, v[154:157] offset:36896
	ds_write_b128 v175, v[158:161] offset:36912
	global_load_dwordx4 v[146:149], v[178:179], off offset:1536
	global_load_dwordx4 v[150:153], v[178:179], off offset:1552
	global_load_dwordx4 v[154:157], v[178:179], off offset:1568
	global_load_dwordx4 v[158:161], v[178:179], off offset:1584
	s_waitcnt lgkmcnt(15)
	v_mfma_f32_32x32x16_f16 v[114:129], v[236:239], v[212:215], v[114:129]
	s_waitcnt lgkmcnt(15)
	v_mfma_f32_32x32x16_f16 v[98:113], v[240:243], v[212:215], v[98:113]
	s_waitcnt lgkmcnt(15)
	v_mfma_f32_32x32x16_f16 v[82:97], v[236:239], v[216:219], v[82:97]
	v_mfma_f32_32x32x16_f16 v[66:81], v[240:243], v[216:219], v[66:81]
	s_waitcnt lgkmcnt(15)
	v_mfma_f32_32x32x16_f16 v[50:65], v[236:239], v[220:223], v[50:65]
	v_mfma_f32_32x32x16_f16 v[34:49], v[240:243], v[220:223], v[34:49]
	s_waitcnt lgkmcnt(14)
	v_mfma_f32_32x32x16_f16 v[18:33], v[236:239], v[224:227], v[18:33]
	v_mfma_f32_32x32x16_f16 v[2:17], v[240:243], v[224:227], v[2:17]
	ds_read_b128 v[236:239], v193 offset:96
	ds_read_b128 v[212:215], v177 offset:96
	ds_read_b128 v[240:243], v193 offset:4704
	ds_read_b128 v[216:219], v177 offset:4704
	ds_read_b128 v[220:223], v177 offset:9312
	ds_read_b128 v[224:227], v177 offset:13920
	s_waitcnt lgkmcnt(14)
	v_mfma_f32_32x32x16_f16 v[114:129], v[228:231], v[188:191], v[114:129]
	s_waitcnt lgkmcnt(13)
	v_mfma_f32_32x32x16_f16 v[98:113], v[232:235], v[188:191], v[98:113]
	s_waitcnt lgkmcnt(12)
	v_mfma_f32_32x32x16_f16 v[82:97], v[228:231], v[200:203], v[82:97]
	v_mfma_f32_32x32x16_f16 v[66:81], v[232:235], v[200:203], v[66:81]
	s_waitcnt lgkmcnt(11)
	v_mfma_f32_32x32x16_f16 v[50:65], v[228:231], v[204:207], v[50:65]
	v_mfma_f32_32x32x16_f16 v[34:49], v[232:235], v[204:207], v[34:49]
	s_waitcnt lgkmcnt(10)
	v_mfma_f32_32x32x16_f16 v[18:33], v[228:231], v[208:211], v[18:33]
	v_mfma_f32_32x32x16_f16 v[2:17], v[232:235], v[208:211], v[2:17]
	s_waitcnt lgkmcnt(0)
	s_barrier
; DI f16v mfma32(h8v a, h8v b, f16v c) { return __builtin_amdgcn_mfma_f32_32x32x16_f16(a, b, c, 0, 0, 0); }
; template <bool GATHER>
; DI void gemm256_main(const h16* __restrict__ A, int lda, const int* __restrict__ idx, int m0,
;                      const h16* __restrict__ B, int ldb, int n0, int K, h16* lds, f16v (&acc)[4][2]) {
;     ...
;   for (int kt = 0; kt < nk; ++kt) {
;     const h16* As = lds + (kt & 1) * (512 * LDH);
;     const h16* Bs = As + 256 * LDH;
;     h16* Wn = lds + ((kt & 1) ^ 1) * (512 * LDH);
;     if (kt + 1 < nk) {
; #pragma unroll
;       for (int i = 0; i < 4; ++i) { *(u4v*)&Wn[lr * LDH + lc + 8 * i] = ra[i]; *(u4v*)&Wn[(256 + lr) * LDH + lc + 8 * i] = rb[i]; }
;     }
;     if (kt + 2 < nk) {
; #pragma unroll
;       for (int i = 0; i < 4; ++i) { ra[i] = *(const u4v*)(AP_ + 8 * i); rb[i] = *(const u4v*)(BP_ + 8 * i); }
;       ao += 64; bo += 64;
;     }
; #pragma unroll
;     for (int ks = 0; ks < 4; ++ks) {
;       h8v af[4], bf[2];
; #pragma unroll
;       for (int i = 0; i < 4; ++i) af[i] = *(const h8v*)&As[(wm * 128 + i * 32 + (lane & 31)) * LDH + ks * 16 + 8 * (lane >> 5)];
; #pragma unroll
;       for (int j = 0; j < 2; ++j) bf[j] = *(const h8v*)&Bs[(wn * 64 + j * 32 + (lane & 31)) * LDH + ks * 16 + 8 * (lane >> 5)];
; #pragma unroll
;       for (int i = 0; i < 4; ++i)
; #pragma unroll
;         for (int j = 0; j < 2; ++j) acc[i][j] = mfma32(bf[j], af[i], acc[i][j]);
;     }
;     __syncthreads();
;   }
	ds_read_b128 v[228:231], v194
	ds_read_b128 v[188:191], v192
	ds_read_b128 v[232:235], v194 offset:4608
	ds_read_b128 v[200:203], v192 offset:4608
	ds_read_b128 v[204:207], v192 offset:9216
	ds_read_b128 v[208:211], v192 offset:13824
	v_mfma_f32_32x32x16_f16 v[114:129], v[236:239], v[212:215], v[114:129]
	v_mfma_f32_32x32x16_f16 v[98:113], v[240:243], v[212:215], v[98:113]
	v_mfma_f32_32x32x16_f16 v[82:97], v[236:239], v[216:219], v[82:97]
	v_mfma_f32_32x32x16_f16 v[66:81], v[240:243], v[216:219], v[66:81]
	v_mfma_f32_32x32x16_f16 v[50:65], v[236:239], v[220:223], v[50:65]
	v_mfma_f32_32x32x16_f16 v[34:49], v[240:243], v[220:223], v[34:49]
	v_mfma_f32_32x32x16_f16 v[18:33], v[236:239], v[224:227], v[18:33]
	v_mfma_f32_32x32x16_f16 v[2:17], v[240:243], v[224:227], v[2:17]
	ds_read_b128 v[236:239], v194 offset:32
	ds_read_b128 v[212:215], v192 offset:32
	ds_read_b128 v[240:243], v194 offset:4640
	ds_read_b128 v[216:219], v192 offset:4640
	ds_read_b128 v[220:223], v192 offset:9248
	ds_read_b128 v[224:227], v192 offset:13856
	s_waitcnt vmcnt(4)
	ds_write_b128 v165, v[130:133]
	ds_write_b128 v165, v[134:137] offset:16
	ds_write_b128 v165, v[138:141] offset:32
	ds_write_b128 v165, v[142:145] offset:48
	global_load_dwordx4 v[130:133], v[162:163], off offset:1664
	global_load_dwordx4 v[134:137], v[162:163], off offset:1680
	global_load_dwordx4 v[138:141], v[162:163], off offset:1696
	global_load_dwordx4 v[142:145], v[162:163], off offset:1712
	s_waitcnt lgkmcnt(14)
	v_mfma_f32_32x32x16_f16 v[114:129], v[228:231], v[188:191], v[114:129]
	s_waitcnt lgkmcnt(13)
	v_mfma_f32_32x32x16_f16 v[98:113], v[232:235], v[188:191], v[98:113]
	s_waitcnt lgkmcnt(12)
	v_mfma_f32_32x32x16_f16 v[82:97], v[228:231], v[200:203], v[82:97]
	v_mfma_f32_32x32x16_f16 v[66:81], v[232:235], v[200:203], v[66:81]
	s_waitcnt lgkmcnt(11)
	v_mfma_f32_32x32x16_f16 v[50:65], v[228:231], v[204:207], v[50:65]
	v_mfma_f32_32x32x16_f16 v[34:49], v[232:235], v[204:207], v[34:49]
	s_waitcnt lgkmcnt(10)
	v_mfma_f32_32x32x16_f16 v[18:33], v[228:231], v[208:211], v[18:33]
	v_mfma_f32_32x32x16_f16 v[2:17], v[232:235], v[208:211], v[2:17]
	ds_read_b128 v[228:231], v194 offset:64
	ds_read_b128 v[188:191], v192 offset:64
	ds_read_b128 v[232:235], v194 offset:4672
	ds_read_b128 v[200:203], v192 offset:4672
	ds_read_b128 v[204:207], v192 offset:9280
	ds_read_b128 v[208:211], v192 offset:13888
	s_waitcnt vmcnt(4)
	ds_write_b128 v165, v[146:149] offset:36864
	ds_write_b128 v165, v[150:153] offset:36880
	ds_write_b128 v165, v[154:157] offset:36896
	ds_write_b128 v165, v[158:161] offset:36912
	global_load_dwordx4 v[146:149], v[178:179], off offset:1664
	global_load_dwordx4 v[150:153], v[178:179], off offset:1680
	global_load_dwordx4 v[154:157], v[178:179], off offset:1696
	global_load_dwordx4 v[158:161], v[178:179], off offset:1712
	s_waitcnt lgkmcnt(15)
	v_mfma_f32_32x32x16_f16 v[114:129], v[236:239], v[212:215], v[114:129]
	s_waitcnt lgkmcnt(15)
	v_mfma_f32_32x32x16_f16 v[98:113], v[240:243], v[212:215], v[98:113]
	s_waitcnt lgkmcnt(15)
	v_mfma_f32_32x32x16_f16 v[82:97], v[236:239], v[216:219], v[82:97]
	v_mfma_f32_32x32x16_f16 v[66:81], v[240:243], v[216:219], v[66:81]
	s_waitcnt lgkmcnt(15)
	v_mfma_f32_32x32x16_f16 v[50:65], v[236:239], v[220:223], v[50:65]
	v_mfma_f32_32x32x16_f16 v[34:49], v[240:243], v[220:223], v[34:49]
	s_waitcnt lgkmcnt(14)
	v_mfma_f32_32x32x16_f16 v[18:33], v[236:239], v[224:227], v[18:33]
	v_mfma_f32_32x32x16_f16 v[2:17], v[240:243], v[224:227], v[2:17]
	ds_read_b128 v[236:239], v194 offset:96
	ds_read_b128 v[212:215], v192 offset:96
	ds_read_b128 v[240:243], v194 offset:4704
	ds_read_b128 v[216:219], v192 offset:4704
	ds_read_b128 v[220:223], v192 offset:9312
	ds_read_b128 v[224:227], v192 offset:13920
	s_waitcnt lgkmcnt(14)
	v_mfma_f32_32x32x16_f16 v[114:129], v[228:231], v[188:191], v[114:129]
	s_waitcnt lgkmcnt(13)
	v_mfma_f32_32x32x16_f16 v[98:113], v[232:235], v[188:191], v[98:113]
	s_waitcnt lgkmcnt(12)
	v_mfma_f32_32x32x16_f16 v[82:97], v[228:231], v[200:203], v[82:97]
	v_mfma_f32_32x32x16_f16 v[66:81], v[232:235], v[200:203], v[66:81]
	s_waitcnt lgkmcnt(11)
	v_mfma_f32_32x32x16_f16 v[50:65], v[228:231], v[204:207], v[50:65]
	v_mfma_f32_32x32x16_f16 v[34:49], v[232:235], v[204:207], v[34:49]
	s_waitcnt lgkmcnt(10)
	v_mfma_f32_32x32x16_f16 v[18:33], v[228:231], v[208:211], v[18:33]
	v_mfma_f32_32x32x16_f16 v[2:17], v[232:235], v[208:211], v[2:17]
	s_waitcnt lgkmcnt(0)
	s_barrier
; DI f16v mfma32(h8v a, h8v b, f16v c) { return __builtin_amdgcn_mfma_f32_32x32x16_f16(a, b, c, 0, 0, 0); }
; template <bool GATHER>
; DI void gemm256_main(const h16* __restrict__ A, int lda, const int* __restrict__ idx, int m0,
;                      const h16* __restrict__ B, int ldb, int n0, int K, h16* lds, f16v (&acc)[4][2]) {
;     ...
;   for (int kt = 0; kt < nk; ++kt) {
;     const h16* As = lds + (kt & 1) * (512 * LDH);
;     const h16* Bs = As + 256 * LDH;
;     h16* Wn = lds + ((kt & 1) ^ 1) * (512 * LDH);
;     if (kt + 1 < nk) {
; #pragma unroll
;       for (int i = 0; i < 4; ++i) { *(u4v*)&Wn[lr * LDH + lc + 8 * i] = ra[i]; *(u4v*)&Wn[(256 + lr) * LDH + lc + 8 * i] = rb[i]; }
;     }
;     if (kt + 2 < nk) {
; #pragma unroll
;       for (int i = 0; i < 4; ++i) { ra[i] = *(const u4v*)(AP_ + 8 * i); rb[i] = *(const u4v*)(BP_ + 8 * i); }
;       ao += 64; bo += 64;
;     }
; #pragma unroll
;     for (int ks = 0; ks < 4; ++ks) {
;       h8v af[4], bf[2];
; #pragma unroll
;       for (int i = 0; i < 4; ++i) af[i] = *(const h8v*)&As[(wm * 128 + i * 32 + (lane & 31)) * LDH + ks * 16 + 8 * (lane >> 5)];
; #pragma unroll
;       for (int j = 0; j < 2; ++j) bf[j] = *(const h8v*)&Bs[(wn * 64 + j * 32 + (lane & 31)) * LDH + ks * 16 + 8 * (lane >> 5)];
; #pragma unroll
;       for (int i = 0; i < 4; ++i)
; #pragma unroll
;         for (int j = 0; j < 2; ++j) acc[i][j] = mfma32(bf[j], af[i], acc[i][j]);
;     }
;     __syncthreads();
;   }
	ds_read_b128 v[228:231], v193
	ds_read_b128 v[188:191], v177
	ds_read_b128 v[232:235], v193 offset:4608
	ds_read_b128 v[200:203], v177 offset:4608
	ds_read_b128 v[204:207], v177 offset:9216
	ds_read_b128 v[208:211], v177 offset:13824
	v_mfma_f32_32x32x16_f16 v[114:129], v[236:239], v[212:215], v[114:129]
	v_mfma_f32_32x32x16_f16 v[98:113], v[240:243], v[212:215], v[98:113]
	v_mfma_f32_32x32x16_f16 v[82:97], v[236:239], v[216:219], v[82:97]
	v_mfma_f32_32x32x16_f16 v[66:81], v[240:243], v[216:219], v[66:81]
	v_mfma_f32_32x32x16_f16 v[50:65], v[236:239], v[220:223], v[50:65]
	v_mfma_f32_32x32x16_f16 v[34:49], v[240:243], v[220:223], v[34:49]
	v_mfma_f32_32x32x16_f16 v[18:33], v[236:239], v[224:227], v[18:33]
	v_mfma_f32_32x32x16_f16 v[2:17], v[240:243], v[224:227], v[2:17]
	ds_read_b128 v[236:239], v193 offset:32
	ds_read_b128 v[212:215], v177 offset:32
	ds_read_b128 v[240:243], v193 offset:4640
	ds_read_b128 v[216:219], v177 offset:4640
	ds_read_b128 v[220:223], v177 offset:9248
	ds_read_b128 v[224:227], v177 offset:13856
	s_waitcnt vmcnt(4)
	ds_write_b128 v175, v[130:133]
	ds_write_b128 v175, v[134:137] offset:16
	ds_write_b128 v175, v[138:141] offset:32
	ds_write_b128 v175, v[142:145] offset:48
	global_load_dwordx4 v[130:133], v[162:163], off offset:1792
	global_load_dwordx4 v[134:137], v[162:163], off offset:1808
	global_load_dwordx4 v[138:141], v[162:163], off offset:1824
	global_load_dwordx4 v[142:145], v[162:163], off offset:1840
	s_waitcnt lgkmcnt(14)
	v_mfma_f32_32x32x16_f16 v[114:129], v[228:231], v[188:191], v[114:129]
	s_waitcnt lgkmcnt(13)
	v_mfma_f32_32x32x16_f16 v[98:113], v[232:235], v[188:191], v[98:113]
	s_waitcnt lgkmcnt(12)
	v_mfma_f32_32x32x16_f16 v[82:97], v[228:231], v[200:203], v[82:97]
	v_mfma_f32_32x32x16_f16 v[66:81], v[232:235], v[200:203], v[66:81]
	s_waitcnt lgkmcnt(11)
	v_mfma_f32_32x32x16_f16 v[50:65], v[228:231], v[204:207], v[50:65]
	v_mfma_f32_32x32x16_f16 v[34:49], v[232:235], v[204:207], v[34:49]
	s_waitcnt lgkmcnt(10)
	v_mfma_f32_32x32x16_f16 v[18:33], v[228:231], v[208:211], v[18:33]
	v_mfma_f32_32x32x16_f16 v[2:17], v[232:235], v[208:211], v[2:17]
	ds_read_b128 v[228:231], v193 offset:64
	ds_read_b128 v[188:191], v177 offset:64
	ds_read_b128 v[232:235], v193 offset:4672
	ds_read_b128 v[200:203], v177 offset:4672
	ds_read_b128 v[204:207], v177 offset:9280
	ds_read_b128 v[208:211], v177 offset:13888
	s_waitcnt vmcnt(4)
	ds_write_b128 v175, v[146:149] offset:36864
	ds_write_b128 v175, v[150:153] offset:36880
	ds_write_b128 v175, v[154:157] offset:36896
	ds_write_b128 v175, v[158:161] offset:36912
	global_load_dwordx4 v[146:149], v[178:179], off offset:1792
	global_load_dwordx4 v[150:153], v[178:179], off offset:1808
	global_load_dwordx4 v[154:157], v[178:179], off offset:1824
	global_load_dwordx4 v[158:161], v[178:179], off offset:1840
	s_waitcnt lgkmcnt(15)
	v_mfma_f32_32x32x16_f16 v[114:129], v[236:239], v[212:215], v[114:129]
	s_waitcnt lgkmcnt(15)
	v_mfma_f32_32x32x16_f16 v[98:113], v[240:243], v[212:215], v[98:113]
	s_waitcnt lgkmcnt(15)
	v_mfma_f32_32x32x16_f16 v[82:97], v[236:239], v[216:219], v[82:97]
	v_mfma_f32_32x32x16_f16 v[66:81], v[240:243], v[216:219], v[66:81]
	s_waitcnt lgkmcnt(15)
	v_mfma_f32_32x32x16_f16 v[50:65], v[236:239], v[220:223], v[50:65]
	v_mfma_f32_32x32x16_f16 v[34:49], v[240:243], v[220:223], v[34:49]
	s_waitcnt lgkmcnt(14)
	v_mfma_f32_32x32x16_f16 v[18:33], v[236:239], v[224:227], v[18:33]
	v_mfma_f32_32x32x16_f16 v[2:17], v[240:243], v[224:227], v[2:17]
	ds_read_b128 v[236:239], v193 offset:96
	ds_read_b128 v[212:215], v177 offset:96
	ds_read_b128 v[240:243], v193 offset:4704
	ds_read_b128 v[216:219], v177 offset:4704
	ds_read_b128 v[220:223], v177 offset:9312
	ds_read_b128 v[224:227], v177 offset:13920
	s_waitcnt lgkmcnt(14)
	v_mfma_f32_32x32x16_f16 v[114:129], v[228:231], v[188:191], v[114:129]
	s_waitcnt lgkmcnt(13)
	v_mfma_f32_32x32x16_f16 v[98:113], v[232:235], v[188:191], v[98:113]
	s_waitcnt lgkmcnt(12)
	v_mfma_f32_32x32x16_f16 v[82:97], v[228:231], v[200:203], v[82:97]
	v_mfma_f32_32x32x16_f16 v[66:81], v[232:235], v[200:203], v[66:81]
	s_waitcnt lgkmcnt(11)
	v_mfma_f32_32x32x16_f16 v[50:65], v[228:231], v[204:207], v[50:65]
	v_mfma_f32_32x32x16_f16 v[34:49], v[232:235], v[204:207], v[34:49]
	s_waitcnt lgkmcnt(10)
	v_mfma_f32_32x32x16_f16 v[18:33], v[228:231], v[208:211], v[18:33]
	v_mfma_f32_32x32x16_f16 v[2:17], v[232:235], v[208:211], v[2:17]
	s_waitcnt lgkmcnt(0)
	s_barrier
; DI f16v mfma32(h8v a, h8v b, f16v c) { return __builtin_amdgcn_mfma_f32_32x32x16_f16(a, b, c, 0, 0, 0); }
; template <bool GATHER>
; DI void gemm256_main(const h16* __restrict__ A, int lda, const int* __restrict__ idx, int m0,
;                      const h16* __restrict__ B, int ldb, int n0, int K, h16* lds, f16v (&acc)[4][2]) {
;     ...
;   for (int kt = 0; kt < nk; ++kt) {
;     const h16* As = lds + (kt & 1) * (512 * LDH);
;     const h16* Bs = As + 256 * LDH;
;     h16* Wn = lds + ((kt & 1) ^ 1) * (512 * LDH);
;     if (kt + 1 < nk) {
; #pragma unroll
;       for (int i = 0; i < 4; ++i) { *(u4v*)&Wn[lr * LDH + lc + 8 * i] = ra[i]; *(u4v*)&Wn[(256 + lr) * LDH + lc + 8 * i] = rb[i]; }
;     }
;     if (kt + 2 < nk) {
; #pragma unroll
;       for (int i = 0; i < 4; ++i) { ra[i] = *(const u4v*)(AP_ + 8 * i); rb[i] = *(const u4v*)(BP_ + 8 * i); }
;       ao += 64; bo += 64;
;     }
; #pragma unroll
;     for (int ks = 0; ks < 4; ++ks) {
;       h8v af[4], bf[2];
; #pragma unroll
;       for (int i = 0; i < 4; ++i) af[i] = *(const h8v*)&As[(wm * 128 + i * 32 + (lane & 31)) * LDH + ks * 16 + 8 * (lane >> 5)];
; #pragma unroll
;       for (int j = 0; j < 2; ++j) bf[j] = *(const h8v*)&Bs[(wn * 64 + j * 32 + (lane & 31)) * LDH + ks * 16 + 8 * (lane >> 5)];
; #pragma unroll
;       for (int i = 0; i < 4; ++i)
; #pragma unroll
;         for (int j = 0; j < 2; ++j) acc[i][j] = mfma32(bf[j], af[i], acc[i][j]);
;     }
;     __syncthreads();
;   }
	ds_read_b128 v[228:231], v194
	ds_read_b128 v[188:191], v192
	ds_read_b128 v[232:235], v194 offset:4608
	ds_read_b128 v[200:203], v192 offset:4608
	ds_read_b128 v[204:207], v192 offset:9216
	ds_read_b128 v[208:211], v192 offset:13824
	v_mfma_f32_32x32x16_f16 v[114:129], v[236:239], v[212:215], v[114:129]
	v_mfma_f32_32x32x16_f16 v[98:113], v[240:243], v[212:215], v[98:113]
	v_mfma_f32_32x32x16_f16 v[82:97], v[236:239], v[216:219], v[82:97]
	v_mfma_f32_32x32x16_f16 v[66:81], v[240:243], v[216:219], v[66:81]
	v_mfma_f32_32x32x16_f16 v[50:65], v[236:239], v[220:223], v[50:65]
	v_mfma_f32_32x32x16_f16 v[34:49], v[240:243], v[220:223], v[34:49]
	v_mfma_f32_32x32x16_f16 v[18:33], v[236:239], v[224:227], v[18:33]
	v_mfma_f32_32x32x16_f16 v[2:17], v[240:243], v[224:227], v[2:17]
	ds_read_b128 v[236:239], v194 offset:32
	ds_read_b128 v[212:215], v192 offset:32
	ds_read_b128 v[240:243], v194 offset:4640
	ds_read_b128 v[216:219], v192 offset:4640
	ds_read_b128 v[220:223], v192 offset:9248
	ds_read_b128 v[224:227], v192 offset:13856
	s_waitcnt vmcnt(4)
	ds_write_b128 v165, v[130:133]
	ds_write_b128 v165, v[134:137] offset:16
	ds_write_b128 v165, v[138:141] offset:32
	ds_write_b128 v165, v[142:145] offset:48
	global_load_dwordx4 v[130:133], v[162:163], off offset:1920
	global_load_dwordx4 v[134:137], v[162:163], off offset:1936
	global_load_dwordx4 v[138:141], v[162:163], off offset:1952
	global_load_dwordx4 v[142:145], v[162:163], off offset:1968
	s_waitcnt lgkmcnt(14)
	v_mfma_f32_32x32x16_f16 v[114:129], v[228:231], v[188:191], v[114:129]
	s_waitcnt lgkmcnt(13)
	v_mfma_f32_32x32x16_f16 v[98:113], v[232:235], v[188:191], v[98:113]
	s_waitcnt lgkmcnt(12)
	v_mfma_f32_32x32x16_f16 v[82:97], v[228:231], v[200:203], v[82:97]
	v_mfma_f32_32x32x16_f16 v[66:81], v[232:235], v[200:203], v[66:81]
	s_waitcnt lgkmcnt(11)
	v_mfma_f32_32x32x16_f16 v[50:65], v[228:231], v[204:207], v[50:65]
	v_mfma_f32_32x32x16_f16 v[34:49], v[232:235], v[204:207], v[34:49]
	s_waitcnt lgkmcnt(10)
	v_mfma_f32_32x32x16_f16 v[18:33], v[228:231], v[208:211], v[18:33]
	v_mfma_f32_32x32x16_f16 v[2:17], v[232:235], v[208:211], v[2:17]
	ds_read_b128 v[228:231], v194 offset:64
	ds_read_b128 v[188:191], v192 offset:64
	ds_read_b128 v[232:235], v194 offset:4672
	ds_read_b128 v[200:203], v192 offset:4672
	ds_read_b128 v[204:207], v192 offset:9280
	ds_read_b128 v[208:211], v192 offset:13888
	s_waitcnt vmcnt(4)
	ds_write_b128 v165, v[146:149] offset:36864
	ds_write_b128 v165, v[150:153] offset:36880
	ds_write_b128 v165, v[154:157] offset:36896
	ds_write_b128 v165, v[158:161] offset:36912
	global_load_dwordx4 v[146:149], v[178:179], off offset:1920
	global_load_dwordx4 v[150:153], v[178:179], off offset:1936
	global_load_dwordx4 v[154:157], v[178:179], off offset:1952
	global_load_dwordx4 v[158:161], v[178:179], off offset:1968
	s_waitcnt lgkmcnt(15)
	v_mfma_f32_32x32x16_f16 v[114:129], v[236:239], v[212:215], v[114:129]
	s_waitcnt lgkmcnt(15)
	v_mfma_f32_32x32x16_f16 v[98:113], v[240:243], v[212:215], v[98:113]
	s_waitcnt lgkmcnt(15)
	v_mfma_f32_32x32x16_f16 v[82:97], v[236:239], v[216:219], v[82:97]
	v_mfma_f32_32x32x16_f16 v[66:81], v[240:243], v[216:219], v[66:81]
	s_waitcnt lgkmcnt(15)
	v_mfma_f32_32x32x16_f16 v[50:65], v[236:239], v[220:223], v[50:65]
	v_mfma_f32_32x32x16_f16 v[34:49], v[240:243], v[220:223], v[34:49]
	s_waitcnt lgkmcnt(14)
	v_mfma_f32_32x32x16_f16 v[18:33], v[236:239], v[224:227], v[18:33]
	v_mfma_f32_32x32x16_f16 v[2:17], v[240:243], v[224:227], v[2:17]
	ds_read_b128 v[236:239], v194 offset:96
	ds_read_b128 v[212:215], v192 offset:96
	ds_read_b128 v[240:243], v194 offset:4704
	ds_read_b128 v[216:219], v192 offset:4704
	ds_read_b128 v[220:223], v192 offset:9312
	ds_read_b128 v[224:227], v192 offset:13920
	s_waitcnt lgkmcnt(14)
	v_mfma_f32_32x32x16_f16 v[114:129], v[228:231], v[188:191], v[114:129]
	s_waitcnt lgkmcnt(13)
	v_mfma_f32_32x32x16_f16 v[98:113], v[232:235], v[188:191], v[98:113]
	s_waitcnt lgkmcnt(12)
	v_mfma_f32_32x32x16_f16 v[82:97], v[228:231], v[200:203], v[82:97]
	v_mfma_f32_32x32x16_f16 v[66:81], v[232:235], v[200:203], v[66:81]
	s_waitcnt lgkmcnt(11)
	v_mfma_f32_32x32x16_f16 v[50:65], v[228:231], v[204:207], v[50:65]
	v_mfma_f32_32x32x16_f16 v[34:49], v[232:235], v[204:207], v[34:49]
	s_waitcnt lgkmcnt(10)
	v_mfma_f32_32x32x16_f16 v[18:33], v[228:231], v[208:211], v[18:33]
	v_mfma_f32_32x32x16_f16 v[2:17], v[232:235], v[208:211], v[2:17]
	s_waitcnt lgkmcnt(0)
	s_barrier
; DI f16v mfma32(h8v a, h8v b, f16v c) { return __builtin_amdgcn_mfma_f32_32x32x16_f16(a, b, c, 0, 0, 0); }
; template <bool GATHER>
; DI void gemm256_main(const h16* __restrict__ A, int lda, const int* __restrict__ idx, int m0,
;                      const h16* __restrict__ B, int ldb, int n0, int K, h16* lds, f16v (&acc)[4][2]) {
;     ...
;   for (int kt = 0; kt < nk; ++kt) {
;     const h16* As = lds + (kt & 1) * (512 * LDH);
;     const h16* Bs = As + 256 * LDH;
;     h16* Wn = lds + ((kt & 1) ^ 1) * (512 * LDH);
;     if (kt + 1 < nk) {
; #pragma unroll
;       for (int i = 0; i < 4; ++i) { *(u4v*)&Wn[lr * LDH + lc + 8 * i] = ra[i]; *(u4v*)&Wn[(256 + lr) * LDH + lc + 8 * i] = rb[i]; }
;     }
;     if (kt + 2 < nk) {
; #pragma unroll
;       for (int i = 0; i < 4; ++i) { ra[i] = *(const u4v*)(AP_ + 8 * i); rb[i] = *(const u4v*)(BP_ + 8 * i); }
;       ao += 64; bo += 64;
;     }
; #pragma unroll
;     for (int ks = 0; ks < 4; ++ks) {
;       h8v af[4], bf[2];
; #pragma unroll
;       for (int i = 0; i < 4; ++i) af[i] = *(const h8v*)&As[(wm * 128 + i * 32 + (lane & 31)) * LDH + ks * 16 + 8 * (lane >> 5)];
; #pragma unroll
;       for (int j = 0; j < 2; ++j) bf[j] = *(const h8v*)&Bs[(wn * 64 + j * 32 + (lane & 31)) * LDH + ks * 16 + 8 * (lane >> 5)];
; #pragma unroll
;       for (int i = 0; i < 4; ++i)
; #pragma unroll
;         for (int j = 0; j < 2; ++j) acc[i][j] = mfma32(bf[j], af[i], acc[i][j]);
;     }
;     __syncthreads();
;   }
	ds_read_b128 v[228:231], v193
	ds_read_b128 v[188:191], v177
	ds_read_b128 v[232:235], v193 offset:4608
	ds_read_b128 v[200:203], v177 offset:4608
	ds_read_b128 v[204:207], v177 offset:9216
	ds_read_b128 v[208:211], v177 offset:13824
	v_mfma_f32_32x32x16_f16 v[114:129], v[236:239], v[212:215], v[114:129]
	v_mfma_f32_32x32x16_f16 v[98:113], v[240:243], v[212:215], v[98:113]
	v_mfma_f32_32x32x16_f16 v[82:97], v[236:239], v[216:219], v[82:97]
	v_mfma_f32_32x32x16_f16 v[66:81], v[240:243], v[216:219], v[66:81]
	v_mfma_f32_32x32x16_f16 v[50:65], v[236:239], v[220:223], v[50:65]
	v_mfma_f32_32x32x16_f16 v[34:49], v[240:243], v[220:223], v[34:49]
	v_mfma_f32_32x32x16_f16 v[18:33], v[236:239], v[224:227], v[18:33]
	v_mfma_f32_32x32x16_f16 v[2:17], v[240:243], v[224:227], v[2:17]
	ds_read_b128 v[236:239], v193 offset:32
	ds_read_b128 v[212:215], v177 offset:32
	ds_read_b128 v[240:243], v193 offset:4640
	ds_read_b128 v[216:219], v177 offset:4640
	ds_read_b128 v[220:223], v177 offset:9248
	ds_read_b128 v[224:227], v177 offset:13856
	s_waitcnt vmcnt(4)
	ds_write_b128 v175, v[130:133]
	ds_write_b128 v175, v[134:137] offset:16
	ds_write_b128 v175, v[138:141] offset:32
	ds_write_b128 v175, v[142:145] offset:48
	s_waitcnt lgkmcnt(14)
	v_mfma_f32_32x32x16_f16 v[114:129], v[228:231], v[188:191], v[114:129]
	s_waitcnt lgkmcnt(13)
	v_mfma_f32_32x32x16_f16 v[98:113], v[232:235], v[188:191], v[98:113]
	s_waitcnt lgkmcnt(12)
	v_mfma_f32_32x32x16_f16 v[82:97], v[228:231], v[200:203], v[82:97]
	v_mfma_f32_32x32x16_f16 v[66:81], v[232:235], v[200:203], v[66:81]
	s_waitcnt lgkmcnt(11)
	v_mfma_f32_32x32x16_f16 v[50:65], v[228:231], v[204:207], v[50:65]
	v_mfma_f32_32x32x16_f16 v[34:49], v[232:235], v[204:207], v[34:49]
	s_waitcnt lgkmcnt(10)
	v_mfma_f32_32x32x16_f16 v[18:33], v[228:231], v[208:211], v[18:33]
	v_mfma_f32_32x32x16_f16 v[2:17], v[232:235], v[208:211], v[2:17]
	ds_read_b128 v[228:231], v193 offset:64
	ds_read_b128 v[188:191], v177 offset:64
	ds_read_b128 v[232:235], v193 offset:4672
	ds_read_b128 v[200:203], v177 offset:4672
	ds_read_b128 v[204:207], v177 offset:9280
	ds_read_b128 v[208:211], v177 offset:13888
	s_waitcnt vmcnt(0)
	ds_write_b128 v175, v[146:149] offset:36864
	ds_write_b128 v175, v[150:153] offset:36880
	ds_write_b128 v175, v[154:157] offset:36896
	ds_write_b128 v175, v[158:161] offset:36912
	s_waitcnt lgkmcnt(15)
	v_mfma_f32_32x32x16_f16 v[114:129], v[236:239], v[212:215], v[114:129]
	s_waitcnt lgkmcnt(15)
	v_mfma_f32_32x32x16_f16 v[98:113], v[240:243], v[212:215], v[98:113]
	s_waitcnt lgkmcnt(15)
	v_mfma_f32_32x32x16_f16 v[82:97], v[236:239], v[216:219], v[82:97]
	v_mfma_f32_32x32x16_f16 v[66:81], v[240:243], v[216:219], v[66:81]
	s_waitcnt lgkmcnt(15)
	v_mfma_f32_32x32x16_f16 v[50:65], v[236:239], v[220:223], v[50:65]
	v_mfma_f32_32x32x16_f16 v[34:49], v[240:243], v[220:223], v[34:49]
	s_waitcnt lgkmcnt(14)
	v_mfma_f32_32x32x16_f16 v[18:33], v[236:239], v[224:227], v[18:33]
	v_mfma_f32_32x32x16_f16 v[2:17], v[240:243], v[224:227], v[2:17]
	ds_read_b128 v[236:239], v193 offset:96
	ds_read_b128 v[212:215], v177 offset:96
	ds_read_b128 v[240:243], v193 offset:4704
	ds_read_b128 v[216:219], v177 offset:4704
	ds_read_b128 v[220:223], v177 offset:9312
	ds_read_b128 v[224:227], v177 offset:13920
	s_waitcnt lgkmcnt(14)
	v_mfma_f32_32x32x16_f16 v[114:129], v[228:231], v[188:191], v[114:129]
	s_waitcnt lgkmcnt(13)
	v_mfma_f32_32x32x16_f16 v[98:113], v[232:235], v[188:191], v[98:113]
	s_waitcnt lgkmcnt(12)
	v_mfma_f32_32x32x16_f16 v[82:97], v[228:231], v[200:203], v[82:97]
	v_mfma_f32_32x32x16_f16 v[66:81], v[232:235], v[200:203], v[66:81]
	s_waitcnt lgkmcnt(11)
	v_mfma_f32_32x32x16_f16 v[50:65], v[228:231], v[204:207], v[50:65]
	v_mfma_f32_32x32x16_f16 v[34:49], v[232:235], v[204:207], v[34:49]
	s_waitcnt lgkmcnt(10)
	v_mfma_f32_32x32x16_f16 v[18:33], v[228:231], v[208:211], v[18:33]
	v_mfma_f32_32x32x16_f16 v[2:17], v[232:235], v[208:211], v[2:17]
	s_waitcnt lgkmcnt(0)
	s_barrier
	ds_read_b128 v[228:231], v194
	ds_read_b128 v[188:191], v192
	ds_read_b128 v[232:235], v194 offset:4608
	ds_read_b128 v[200:203], v192 offset:4608
	ds_read_b128 v[204:207], v192 offset:9216
	ds_read_b128 v[208:211], v192 offset:13824
	v_mfma_f32_32x32x16_f16 v[114:129], v[236:239], v[212:215], v[114:129]
	v_mfma_f32_32x32x16_f16 v[98:113], v[240:243], v[212:215], v[98:113]
	v_mfma_f32_32x32x16_f16 v[82:97], v[236:239], v[216:219], v[82:97]
	v_mfma_f32_32x32x16_f16 v[66:81], v[240:243], v[216:219], v[66:81]
	v_mfma_f32_32x32x16_f16 v[50:65], v[236:239], v[220:223], v[50:65]
	v_mfma_f32_32x32x16_f16 v[34:49], v[240:243], v[220:223], v[34:49]
	v_mfma_f32_32x32x16_f16 v[18:33], v[236:239], v[224:227], v[18:33]
	v_mfma_f32_32x32x16_f16 v[2:17], v[240:243], v[224:227], v[2:17]
	ds_read_b128 v[236:239], v194 offset:32
	ds_read_b128 v[212:215], v192 offset:32
	ds_read_b128 v[240:243], v194 offset:4640
	ds_read_b128 v[216:219], v192 offset:4640
	ds_read_b128 v[220:223], v192 offset:9248
	ds_read_b128 v[224:227], v192 offset:13856
	s_waitcnt lgkmcnt(10)
	v_mfma_f32_32x32x16_f16 v[114:129], v[228:231], v[188:191], v[114:129]
	s_waitcnt lgkmcnt(9)
	v_mfma_f32_32x32x16_f16 v[98:113], v[232:235], v[188:191], v[98:113]
	s_waitcnt lgkmcnt(8)
	v_mfma_f32_32x32x16_f16 v[82:97], v[228:231], v[200:203], v[82:97]
	v_mfma_f32_32x32x16_f16 v[66:81], v[232:235], v[200:203], v[66:81]
	s_waitcnt lgkmcnt(7)
	v_mfma_f32_32x32x16_f16 v[50:65], v[228:231], v[204:207], v[50:65]
	v_mfma_f32_32x32x16_f16 v[34:49], v[232:235], v[204:207], v[34:49]
	s_waitcnt lgkmcnt(6)
; DI f16v mfma32(h8v a, h8v b, f16v c) { return __builtin_amdgcn_mfma_f32_32x32x16_f16(a, b, c, 0, 0, 0); }
; template <bool GATHER>
; DI void gemm256_main(const h16* __restrict__ A, int lda, const int* __restrict__ idx, int m0,
;                      const h16* __restrict__ B, int ldb, int n0, int K, h16* lds, f16v (&acc)[4][2]) {
;     ...
; #pragma unroll
;     for (int ks = 0; ks < 4; ++ks) {
;       h8v af[4], bf[2];
; #pragma unroll
;       for (int i = 0; i < 4; ++i) af[i] = *(const h8v*)&As[(wm * 128 + i * 32 + (lane & 31)) * LDH + ks * 16 + 8 * (lane >> 5)];
; #pragma unroll
;       for (int j = 0; j < 2; ++j) bf[j] = *(const h8v*)&Bs[(wn * 64 + j * 32 + (lane & 31)) * LDH + ks * 16 + 8 * (lane >> 5)];
; #pragma unroll
;       for (int i = 0; i < 4; ++i)
; #pragma unroll
;         for (int j = 0; j < 2; ++j) acc[i][j] = mfma32(bf[j], af[i], acc[i][j]);
;     }
; DI void phase_resid_gemm(const Params& p, const h16* A, int lda, const h16* W, int K, const float* xres, int bid, int nb, h16* lds) {
;     ...
;   for (int u = bid; u < 64 * 4; u += nb) {
;     const int m0 = (u >> 2) * 256, n0 = (u & 3) * 256;
;     f16v acc[4][2]; acc256_zero(acc);
;     gemm256_main<false>(A, lda, nullptr, m0, W, K, n0, K, lds, acc);
;     gemm256_epilogue(acc, m0, n0, [&](int m, int n, f4v v0, f4v v1) {
;       const f4v x0 = *(const f4v*)&xres[(size_t)m * DM + n], x1 = *(const f4v*)&xres[(size_t)m * DM + n + 32];
;       *(f4v*)&out[(size_t)m * DM + n] = ALPHA * x0 + v0;
;       *(f4v*)&out[(size_t)m * DM + n + 32] = ALPHA * x1 + v1;
;     });
	v_mfma_f32_32x32x16_f16 v[18:33], v[228:231], v[208:211], v[18:33]
	v_mfma_f32_32x32x16_f16 v[2:17], v[232:235], v[208:211], v[2:17]
	ds_read_b128 v[228:231], v194 offset:64
	ds_read_b128 v[188:191], v192 offset:64
	ds_read_b128 v[232:235], v194 offset:4672
	ds_read_b128 v[200:203], v192 offset:4672
	ds_read_b128 v[204:207], v192 offset:9280
	ds_read_b128 v[208:211], v192 offset:13888
	s_waitcnt lgkmcnt(10)
	v_mfma_f32_32x32x16_f16 v[114:129], v[236:239], v[212:215], v[114:129]
	s_waitcnt lgkmcnt(9)
	v_mfma_f32_32x32x16_f16 v[98:113], v[240:243], v[212:215], v[98:113]
	s_waitcnt lgkmcnt(8)
	v_mfma_f32_32x32x16_f16 v[82:97], v[236:239], v[216:219], v[82:97]
	v_mfma_f32_32x32x16_f16 v[66:81], v[240:243], v[216:219], v[66:81]
	s_waitcnt lgkmcnt(7)
	v_mfma_f32_32x32x16_f16 v[50:65], v[236:239], v[220:223], v[50:65]
	v_mfma_f32_32x32x16_f16 v[34:49], v[240:243], v[220:223], v[34:49]
	s_waitcnt lgkmcnt(6)
	v_mfma_f32_32x32x16_f16 v[18:33], v[236:239], v[224:227], v[18:33]
	v_mfma_f32_32x32x16_f16 v[2:17], v[240:243], v[224:227], v[2:17]
	ds_read_b128 v[236:239], v194 offset:96
	ds_read_b128 v[212:215], v192 offset:96
	ds_read_b128 v[240:243], v194 offset:4704
	ds_read_b128 v[216:219], v192 offset:4704
	ds_read_b128 v[220:223], v192 offset:9312
	ds_read_b128 v[224:227], v192 offset:13920
	s_waitcnt lgkmcnt(10)
	v_mfma_f32_32x32x16_f16 v[114:129], v[228:231], v[188:191], v[114:129]
	s_waitcnt lgkmcnt(9)
	v_mfma_f32_32x32x16_f16 v[98:113], v[232:235], v[188:191], v[98:113]
	s_waitcnt lgkmcnt(8)
	v_mfma_f32_32x32x16_f16 v[82:97], v[228:231], v[200:203], v[82:97]
	v_mfma_f32_32x32x16_f16 v[66:81], v[232:235], v[200:203], v[66:81]
	s_waitcnt lgkmcnt(7)
	v_mfma_f32_32x32x16_f16 v[50:65], v[228:231], v[204:207], v[50:65]
	v_mfma_f32_32x32x16_f16 v[34:49], v[232:235], v[204:207], v[34:49]
	s_waitcnt lgkmcnt(6)
	v_mfma_f32_32x32x16_f16 v[18:33], v[228:231], v[208:211], v[18:33]
	v_mfma_f32_32x32x16_f16 v[2:17], v[232:235], v[208:211], v[2:17]
	s_waitcnt lgkmcnt(0)
	v_mfma_f32_32x32x16_f16 v[114:129], v[236:239], v[212:215], v[114:129]
	v_mfma_f32_32x32x16_f16 v[98:113], v[240:243], v[212:215], v[98:113]
	v_mfma_f32_32x32x16_f16 v[82:97], v[236:239], v[216:219], v[82:97]
	v_mfma_f32_32x32x16_f16 v[66:81], v[240:243], v[216:219], v[66:81]
	v_mfma_f32_32x32x16_f16 v[50:65], v[236:239], v[220:223], v[50:65]
	v_mfma_f32_32x32x16_f16 v[34:49], v[240:243], v[220:223], v[34:49]
	v_mfma_f32_32x32x16_f16 v[18:33], v[236:239], v[224:227], v[18:33]
	v_mfma_f32_32x32x16_f16 v[2:17], v[240:243], v[224:227], v[2:17]
	s_nop 15
	v_mov_b32_e32 v188, 0x358637bd
	v_mov_b32_e32 v189, 0x3727c5ac
	v_mov_b32_e32 v190, 0x2100
	v_mov_b32_e32 v191, 0x1400
	v_mov_b32_e32 v192, 0x7f800000
	v_mov_b32_e32 v193, 0x7fc00000
	v_mov_b32_e32 v194, 0xff800000
	v_mov_b32_e32 v199, 0xf149f2ca
	v_mov_b32_e32 v204, 0x7fffec00
	v_mov_b32_e32 v205, 0xff7fc99e
	v_mov_b32_e32 v206, 0x840000
	v_mov_b32_e32 v207, 0xb00000
	v_mov_b32_e32 v208, 0xdc0000
	v_mov_b32_e32 v209, 0x1080000
	v_mov_b32_e32 v210, 0x1340000
	v_mov_b32_e32 v211, 0x420000
	v_mov_b32_e32 v212, 0x580000
	v_mov_b32_e32 v213, 0x6e0000
	v_mov_b32_e32 v214, 0x9a0000
	s_setprio 0
	v_mov_b32_e32 v1, v180
	s_nop 15
	s_cselect_b32 s60, 1, 0
	s_barrier
	v_readfirstlane_b32 s66, v180
	s_mov_b32 s69, s5
	s_mov_b32 s65, s6
	s_lshr_b32 s66, s66, 6
	s_and_b32 s67, s66, 3
	s_lshr_b32 s68, s66, 2
	s_lshl_b32 s70, s67, 6
	s_add_i32 s70, s70, s69
	s_lshl_b32 s71, s68, 7
	s_add_i32 s71, s71, s65
	s_mul_i32 s72, s66, 0x4400
	s_add_i32 s72, s72, 16
	v_and_b32_e32 v136, 63, v180
	v_and_b32_e32 v137, 31, v136
	v_lshrrev_b32_e32 v138, 5, v136
	v_mul_u32_u24_e32 v130, 0x110, v137
	v_lshl_add_u32 v130, v138, 4, v130
	v_add_u32_e32 v130, s72, v130
	v_lshrrev_b32_e32 v137, 4, v136
	v_and_b32_e32 v138, 15, v136
	v_mul_u32_u24_e32 v131, 0x110, v137
	v_lshl_add_u32 v131, v138, 4, v131
	v_add_u32_e32 v131, s72, v131
	v_add_u32_e32 v137, s71, v137
	v_lshl_add_u32 v138, v138, 2, s70
	v_lshlrev_b32_e32 v138, 2, v138
	v_mov_b32_e32 v139, v0
	s_mov_b32 s73, 0x1000
	v_mov_b64_e32 v[132:133], s[2:3]
	v_mad_u64_u32 v[132:133], s[74:75], v137, s73, v[132:133]
	v_lshl_add_u64 v[132:133], v[132:133], 0, v[138:139]
	v_mov_b64_e32 v[134:135], s[18:19]
	v_mad_u64_u32 v[134:135], s[74:75], v137, s73, v[134:135]
	v_lshl_add_u64 v[134:135], v[134:135], 0, v[138:139]
	s_mov_b32 s76, 0x4000
	s_mov_b32 s77, 0
	ds_write_b128 v130, v[114:117]
	ds_write_b128 v130, v[118:121] offset:32
	ds_write_b128 v130, v[122:125] offset:64
	ds_write_b128 v130, v[126:129] offset:96
	ds_write_b128 v130, v[98:101] offset:128
	ds_write_b128 v130, v[102:105] offset:160
	ds_write_b128 v130, v[106:109] offset:192
	ds_write_b128 v130, v[110:113] offset:224
	ds_write_b128 v130, v[82:85] offset:8704
	ds_write_b128 v130, v[86:89] offset:8736
	ds_write_b128 v130, v[90:93] offset:8768
	ds_write_b128 v130, v[94:97] offset:8800
	ds_write_b128 v130, v[66:69] offset:8832
	ds_write_b128 v130, v[70:73] offset:8864
	ds_write_b128 v130, v[74:77] offset:8896
	ds_write_b128 v130, v[78:81] offset:8928
	global_load_dwordx4 v[224:227], v[132:133], off
	v_lshl_add_u64 v[132:133], v[132:133], 0, s[76:77]
	global_load_dwordx4 v[228:231], v[132:133], off
	v_lshl_add_u64 v[132:133], v[132:133], 0, s[76:77]
	global_load_dwordx4 v[232:235], v[132:133], off
	v_lshl_add_u64 v[132:133], v[132:133], 0, s[76:77]
	global_load_dwordx4 v[236:239], v[132:133], off
	v_lshl_add_u64 v[132:133], v[132:133], 0, s[76:77]
	global_load_dwordx4 v[240:243], v[132:133], off
	v_lshl_add_u64 v[132:133], v[132:133], 0, s[76:77]
	global_load_dwordx4 v[244:247], v[132:133], off
	v_lshl_add_u64 v[132:133], v[132:133], 0, s[76:77]
	global_load_dwordx4 v[176:179], v[132:133], off
	v_lshl_add_u64 v[132:133], v[132:133], 0, s[76:77]
	global_load_dwordx4 v[200:203], v[132:133], off
	v_lshl_add_u64 v[132:133], v[132:133], 0, s[76:77]
	ds_read_b128 v[140:143], v131
	ds_read_b128 v[144:147], v131 offset:1088
	ds_read_b128 v[148:151], v131 offset:2176
	ds_read_b128 v[152:155], v131 offset:3264
	ds_read_b128 v[156:159], v131 offset:4352
	ds_read_b128 v[160:163], v131 offset:5440
	ds_read_b128 v[216:219], v131 offset:6528
	ds_read_b128 v[220:223], v131 offset:7616
	s_waitcnt vmcnt(7) lgkmcnt(7)
; DI void phase_resid_gemm(const Params& p, const h16* A, int lda, const h16* W, int K, const float* xres, int bid, int nb, h16* lds) {
;     ...
;     gemm256_epilogue(acc, m0, n0, [&](int m, int n, f4v v0, f4v v1) {
;       const f4v x0 = *(const f4v*)&xres[(size_t)m * DM + n], x1 = *(const f4v*)&xres[(size_t)m * DM + n + 32];
;       *(f4v*)&out[(size_t)m * DM + n] = ALPHA * x0 + v0;
;       *(f4v*)&out[(size_t)m * DM + n + 32] = ALPHA * x1 + v1;
;     });
	v_pk_fma_f32 v[140:141], v[224:225], s[10:11], v[140:141] op_sel_hi:[1,0,1]
	v_pk_fma_f32 v[142:143], v[226:227], s[10:11], v[142:143] op_sel_hi:[1,0,1]
	global_store_dwordx4 v[134:135], v[140:143], off
	v_lshl_add_u64 v[134:135], v[134:135], 0, s[76:77]
	s_waitcnt vmcnt(7) lgkmcnt(6)
	v_pk_fma_f32 v[144:145], v[228:229], s[10:11], v[144:145] op_sel_hi:[1,0,1]
	v_pk_fma_f32 v[146:147], v[230:231], s[10:11], v[146:147] op_sel_hi:[1,0,1]
	global_store_dwordx4 v[134:135], v[144:147], off
	v_lshl_add_u64 v[134:135], v[134:135], 0, s[76:77]
	s_waitcnt vmcnt(7) lgkmcnt(5)
	v_pk_fma_f32 v[148:149], v[232:233], s[10:11], v[148:149] op_sel_hi:[1,0,1]
	v_pk_fma_f32 v[150:151], v[234:235], s[10:11], v[150:151] op_sel_hi:[1,0,1]
	global_store_dwordx4 v[134:135], v[148:151], off
	v_lshl_add_u64 v[134:135], v[134:135], 0, s[76:77]
	s_waitcnt vmcnt(7) lgkmcnt(4)
	v_pk_fma_f32 v[152:153], v[236:237], s[10:11], v[152:153] op_sel_hi:[1,0,1]
	v_pk_fma_f32 v[154:155], v[238:239], s[10:11], v[154:155] op_sel_hi:[1,0,1]
	global_store_dwordx4 v[134:135], v[152:155], off
	v_lshl_add_u64 v[134:135], v[134:135], 0, s[76:77]
	s_waitcnt vmcnt(7) lgkmcnt(3)
	v_pk_fma_f32 v[156:157], v[240:241], s[10:11], v[156:157] op_sel_hi:[1,0,1]
	v_pk_fma_f32 v[158:159], v[242:243], s[10:11], v[158:159] op_sel_hi:[1,0,1]
	global_store_dwordx4 v[134:135], v[156:159], off
	v_lshl_add_u64 v[134:135], v[134:135], 0, s[76:77]
	s_waitcnt vmcnt(7) lgkmcnt(2)
	v_pk_fma_f32 v[160:161], v[244:245], s[10:11], v[160:161] op_sel_hi:[1,0,1]
	v_pk_fma_f32 v[162:163], v[246:247], s[10:11], v[162:163] op_sel_hi:[1,0,1]
	global_store_dwordx4 v[134:135], v[160:163], off
	v_lshl_add_u64 v[134:135], v[134:135], 0, s[76:77]
	s_waitcnt vmcnt(7) lgkmcnt(1)
	v_pk_fma_f32 v[216:217], v[176:177], s[10:11], v[216:217] op_sel_hi:[1,0,1]
	v_pk_fma_f32 v[218:219], v[178:179], s[10:11], v[218:219] op_sel_hi:[1,0,1]
	global_store_dwordx4 v[134:135], v[216:219], off
	v_lshl_add_u64 v[134:135], v[134:135], 0, s[76:77]
	s_waitcnt vmcnt(7) lgkmcnt(0)
	v_pk_fma_f32 v[220:221], v[200:201], s[10:11], v[220:221] op_sel_hi:[1,0,1]
	v_pk_fma_f32 v[222:223], v[202:203], s[10:11], v[222:223] op_sel_hi:[1,0,1]
	global_store_dwordx4 v[134:135], v[220:223], off
	v_lshl_add_u64 v[134:135], v[134:135], 0, s[76:77]
	s_nop 1
	global_load_dwordx4 v[224:227], v[132:133], off
	v_lshl_add_u64 v[132:133], v[132:133], 0, s[76:77]
	global_load_dwordx4 v[228:231], v[132:133], off
	v_lshl_add_u64 v[132:133], v[132:133], 0, s[76:77]
	global_load_dwordx4 v[232:235], v[132:133], off
	v_lshl_add_u64 v[132:133], v[132:133], 0, s[76:77]
	global_load_dwordx4 v[236:239], v[132:133], off
	v_lshl_add_u64 v[132:133], v[132:133], 0, s[76:77]
	global_load_dwordx4 v[240:243], v[132:133], off
	v_lshl_add_u64 v[132:133], v[132:133], 0, s[76:77]
	global_load_dwordx4 v[244:247], v[132:133], off
	v_lshl_add_u64 v[132:133], v[132:133], 0, s[76:77]
	global_load_dwordx4 v[176:179], v[132:133], off
	v_lshl_add_u64 v[132:133], v[132:133], 0, s[76:77]
	global_load_dwordx4 v[200:203], v[132:133], off
	v_lshl_add_u64 v[132:133], v[132:133], 0, s[76:77]
	ds_read_b128 v[140:143], v131 offset:8704
	ds_read_b128 v[144:147], v131 offset:9792
	ds_read_b128 v[148:151], v131 offset:10880
	ds_read_b128 v[152:155], v131 offset:11968
	ds_read_b128 v[156:159], v131 offset:13056
	ds_read_b128 v[160:163], v131 offset:14144
	ds_read_b128 v[216:219], v131 offset:15232
	ds_read_b128 v[220:223], v131 offset:16320
	s_waitcnt vmcnt(7) lgkmcnt(7)
	v_pk_fma_f32 v[140:141], v[224:225], s[10:11], v[140:141] op_sel_hi:[1,0,1]
	v_pk_fma_f32 v[142:143], v[226:227], s[10:11], v[142:143] op_sel_hi:[1,0,1]
	global_store_dwordx4 v[134:135], v[140:143], off
	v_lshl_add_u64 v[134:135], v[134:135], 0, s[76:77]
	s_waitcnt vmcnt(7) lgkmcnt(6)
	v_pk_fma_f32 v[144:145], v[228:229], s[10:11], v[144:145] op_sel_hi:[1,0,1]
	v_pk_fma_f32 v[146:147], v[230:231], s[10:11], v[146:147] op_sel_hi:[1,0,1]
	global_store_dwordx4 v[134:135], v[144:147], off
	v_lshl_add_u64 v[134:135], v[134:135], 0, s[76:77]
	s_waitcnt vmcnt(7) lgkmcnt(5)
	v_pk_fma_f32 v[148:149], v[232:233], s[10:11], v[148:149] op_sel_hi:[1,0,1]
	v_pk_fma_f32 v[150:151], v[234:235], s[10:11], v[150:151] op_sel_hi:[1,0,1]
	global_store_dwordx4 v[134:135], v[148:151], off
	v_lshl_add_u64 v[134:135], v[134:135], 0, s[76:77]
	s_waitcnt vmcnt(7) lgkmcnt(4)
	v_pk_fma_f32 v[152:153], v[236:237], s[10:11], v[152:153] op_sel_hi:[1,0,1]
	v_pk_fma_f32 v[154:155], v[238:239], s[10:11], v[154:155] op_sel_hi:[1,0,1]
	global_store_dwordx4 v[134:135], v[152:155], off
	v_lshl_add_u64 v[134:135], v[134:135], 0, s[76:77]
	s_waitcnt vmcnt(7) lgkmcnt(3)
	v_pk_fma_f32 v[156:157], v[240:241], s[10:11], v[156:157] op_sel_hi:[1,0,1]
	v_pk_fma_f32 v[158:159], v[242:243], s[10:11], v[158:159] op_sel_hi:[1,0,1]
	global_store_dwordx4 v[134:135], v[156:159], off
	v_lshl_add_u64 v[134:135], v[134:135], 0, s[76:77]
	s_waitcnt vmcnt(7) lgkmcnt(2)
	v_pk_fma_f32 v[160:161], v[244:245], s[10:11], v[160:161] op_sel_hi:[1,0,1]
	v_pk_fma_f32 v[162:163], v[246:247], s[10:11], v[162:163] op_sel_hi:[1,0,1]
	global_store_dwordx4 v[134:135], v[160:163], off
	v_lshl_add_u64 v[134:135], v[134:135], 0, s[76:77]
	s_waitcnt vmcnt(7) lgkmcnt(1)
	v_pk_fma_f32 v[216:217], v[176:177], s[10:11], v[216:217] op_sel_hi:[1,0,1]
	v_pk_fma_f32 v[218:219], v[178:179], s[10:11], v[218:219] op_sel_hi:[1,0,1]
	global_store_dwordx4 v[134:135], v[216:219], off
	v_lshl_add_u64 v[134:135], v[134:135], 0, s[76:77]
	s_waitcnt vmcnt(7) lgkmcnt(0)
; DI void phase_resid_gemm(const Params& p, const h16* A, int lda, const h16* W, int K, const float* xres, int bid, int nb, h16* lds) {
;     ...
;   for (int u = bid; u < 64 * 4; u += nb) {
;     const int m0 = (u >> 2) * 256, n0 = (u & 3) * 256;
;     f16v acc[4][2]; acc256_zero(acc);
;     gemm256_main<false>(A, lda, nullptr, m0, W, K, n0, K, lds, acc);
;     gemm256_epilogue(acc, m0, n0, [&](int m, int n, f4v v0, f4v v1) {
;       const f4v x0 = *(const f4v*)&xres[(size_t)m * DM + n], x1 = *(const f4v*)&xres[(size_t)m * DM + n + 32];
;       *(f4v*)&out[(size_t)m * DM + n] = ALPHA * x0 + v0;
;       *(f4v*)&out[(size_t)m * DM + n + 32] = ALPHA * x1 + v1;
;     });
	v_pk_fma_f32 v[220:221], v[200:201], s[10:11], v[220:221] op_sel_hi:[1,0,1]
	v_pk_fma_f32 v[222:223], v[202:203], s[10:11], v[222:223] op_sel_hi:[1,0,1]
	global_store_dwordx4 v[134:135], v[220:223], off
	v_lshl_add_u64 v[134:135], v[134:135], 0, s[76:77]
	s_nop 1
	ds_write_b128 v130, v[50:53]
	ds_write_b128 v130, v[54:57] offset:32
	ds_write_b128 v130, v[58:61] offset:64
	ds_write_b128 v130, v[62:65] offset:96
	ds_write_b128 v130, v[34:37] offset:128
	ds_write_b128 v130, v[38:41] offset:160
	ds_write_b128 v130, v[42:45] offset:192
	ds_write_b128 v130, v[46:49] offset:224
	ds_write_b128 v130, v[18:21] offset:8704
	ds_write_b128 v130, v[22:25] offset:8736
	ds_write_b128 v130, v[26:29] offset:8768
	ds_write_b128 v130, v[30:33] offset:8800
	ds_write_b128 v130, v[2:5] offset:8832
	ds_write_b128 v130, v[6:9] offset:8864
	ds_write_b128 v130, v[10:13] offset:8896
	ds_write_b128 v130, v[14:17] offset:8928
	global_load_dwordx4 v[224:227], v[132:133], off
	v_lshl_add_u64 v[132:133], v[132:133], 0, s[76:77]
	global_load_dwordx4 v[228:231], v[132:133], off
	v_lshl_add_u64 v[132:133], v[132:133], 0, s[76:77]
	global_load_dwordx4 v[232:235], v[132:133], off
	v_lshl_add_u64 v[132:133], v[132:133], 0, s[76:77]
	global_load_dwordx4 v[236:239], v[132:133], off
	v_lshl_add_u64 v[132:133], v[132:133], 0, s[76:77]
	global_load_dwordx4 v[240:243], v[132:133], off
	v_lshl_add_u64 v[132:133], v[132:133], 0, s[76:77]
	global_load_dwordx4 v[244:247], v[132:133], off
	v_lshl_add_u64 v[132:133], v[132:133], 0, s[76:77]
	global_load_dwordx4 v[176:179], v[132:133], off
	v_lshl_add_u64 v[132:133], v[132:133], 0, s[76:77]
	global_load_dwordx4 v[200:203], v[132:133], off
	v_lshl_add_u64 v[132:133], v[132:133], 0, s[76:77]
	ds_read_b128 v[140:143], v131
	ds_read_b128 v[144:147], v131 offset:1088
	ds_read_b128 v[148:151], v131 offset:2176
	ds_read_b128 v[152:155], v131 offset:3264
	ds_read_b128 v[156:159], v131 offset:4352
	ds_read_b128 v[160:163], v131 offset:5440
	ds_read_b128 v[216:219], v131 offset:6528
	ds_read_b128 v[220:223], v131 offset:7616
	s_waitcnt vmcnt(7) lgkmcnt(7)
	v_pk_fma_f32 v[140:141], v[224:225], s[10:11], v[140:141] op_sel_hi:[1,0,1]
	v_pk_fma_f32 v[142:143], v[226:227], s[10:11], v[142:143] op_sel_hi:[1,0,1]
	global_store_dwordx4 v[134:135], v[140:143], off
	v_lshl_add_u64 v[134:135], v[134:135], 0, s[76:77]
	s_waitcnt vmcnt(7) lgkmcnt(6)
	v_pk_fma_f32 v[144:145], v[228:229], s[10:11], v[144:145] op_sel_hi:[1,0,1]
	v_pk_fma_f32 v[146:147], v[230:231], s[10:11], v[146:147] op_sel_hi:[1,0,1]
	global_store_dwordx4 v[134:135], v[144:147], off
	v_lshl_add_u64 v[134:135], v[134:135], 0, s[76:77]
	s_waitcnt vmcnt(7) lgkmcnt(5)
	v_pk_fma_f32 v[148:149], v[232:233], s[10:11], v[148:149] op_sel_hi:[1,0,1]
	v_pk_fma_f32 v[150:151], v[234:235], s[10:11], v[150:151] op_sel_hi:[1,0,1]
	global_store_dwordx4 v[134:135], v[148:151], off
	v_lshl_add_u64 v[134:135], v[134:135], 0, s[76:77]
	s_waitcnt vmcnt(7) lgkmcnt(4)
	v_pk_fma_f32 v[152:153], v[236:237], s[10:11], v[152:153] op_sel_hi:[1,0,1]
	v_pk_fma_f32 v[154:155], v[238:239], s[10:11], v[154:155] op_sel_hi:[1,0,1]
	global_store_dwordx4 v[134:135], v[152:155], off
	v_lshl_add_u64 v[134:135], v[134:135], 0, s[76:77]
	s_waitcnt vmcnt(7) lgkmcnt(3)
	v_pk_fma_f32 v[156:157], v[240:241], s[10:11], v[156:157] op_sel_hi:[1,0,1]
	v_pk_fma_f32 v[158:159], v[242:243], s[10:11], v[158:159] op_sel_hi:[1,0,1]
	global_store_dwordx4 v[134:135], v[156:159], off
	v_lshl_add_u64 v[134:135], v[134:135], 0, s[76:77]
	s_waitcnt vmcnt(7) lgkmcnt(2)
	v_pk_fma_f32 v[160:161], v[244:245], s[10:11], v[160:161] op_sel_hi:[1,0,1]
	v_pk_fma_f32 v[162:163], v[246:247], s[10:11], v[162:163] op_sel_hi:[1,0,1]
	global_store_dwordx4 v[134:135], v[160:163], off
	v_lshl_add_u64 v[134:135], v[134:135], 0, s[76:77]
	s_waitcnt vmcnt(7) lgkmcnt(1)
; DI void phase_resid_gemm(const Params& p, const h16* A, int lda, const h16* W, int K, const float* xres, int bid, int nb, h16* lds) {
;     ...
;   for (int u = bid; u < 64 * 4; u += nb) {
;     const int m0 = (u >> 2) * 256, n0 = (u & 3) * 256;
;     f16v acc[4][2]; acc256_zero(acc);
;     gemm256_main<false>(A, lda, nullptr, m0, W, K, n0, K, lds, acc);
;     gemm256_epilogue(acc, m0, n0, [&](int m, int n, f4v v0, f4v v1) {
;       const f4v x0 = *(const f4v*)&xres[(size_t)m * DM + n], x1 = *(const f4v*)&xres[(size_t)m * DM + n + 32];
;       *(f4v*)&out[(size_t)m * DM + n] = ALPHA * x0 + v0;
;       *(f4v*)&out[(size_t)m * DM + n + 32] = ALPHA * x1 + v1;
;     });
	v_pk_fma_f32 v[216:217], v[176:177], s[10:11], v[216:217] op_sel_hi:[1,0,1]
	v_pk_fma_f32 v[218:219], v[178:179], s[10:11], v[218:219] op_sel_hi:[1,0,1]
	global_store_dwordx4 v[134:135], v[216:219], off
	v_lshl_add_u64 v[134:135], v[134:135], 0, s[76:77]
	s_waitcnt vmcnt(7) lgkmcnt(0)
	v_pk_fma_f32 v[220:221], v[200:201], s[10:11], v[220:221] op_sel_hi:[1,0,1]
	v_pk_fma_f32 v[222:223], v[202:203], s[10:11], v[222:223] op_sel_hi:[1,0,1]
	global_store_dwordx4 v[134:135], v[220:223], off
	v_lshl_add_u64 v[134:135], v[134:135], 0, s[76:77]
	s_nop 1
	global_load_dwordx4 v[224:227], v[132:133], off
	v_lshl_add_u64 v[132:133], v[132:133], 0, s[76:77]
	global_load_dwordx4 v[228:231], v[132:133], off
	v_lshl_add_u64 v[132:133], v[132:133], 0, s[76:77]
	global_load_dwordx4 v[232:235], v[132:133], off
	v_lshl_add_u64 v[132:133], v[132:133], 0, s[76:77]
	global_load_dwordx4 v[236:239], v[132:133], off
	v_lshl_add_u64 v[132:133], v[132:133], 0, s[76:77]
	global_load_dwordx4 v[240:243], v[132:133], off
	v_lshl_add_u64 v[132:133], v[132:133], 0, s[76:77]
	global_load_dwordx4 v[244:247], v[132:133], off
	v_lshl_add_u64 v[132:133], v[132:133], 0, s[76:77]
	global_load_dwordx4 v[176:179], v[132:133], off
	v_lshl_add_u64 v[132:133], v[132:133], 0, s[76:77]
	global_load_dwordx4 v[200:203], v[132:133], off
	v_lshl_add_u64 v[132:133], v[132:133], 0, s[76:77]
	ds_read_b128 v[140:143], v131 offset:8704
	ds_read_b128 v[144:147], v131 offset:9792
	ds_read_b128 v[148:151], v131 offset:10880
	ds_read_b128 v[152:155], v131 offset:11968
	ds_read_b128 v[156:159], v131 offset:13056
	ds_read_b128 v[160:163], v131 offset:14144
	ds_read_b128 v[216:219], v131 offset:15232
	ds_read_b128 v[220:223], v131 offset:16320
	s_waitcnt vmcnt(7) lgkmcnt(7)
	v_pk_fma_f32 v[140:141], v[224:225], s[10:11], v[140:141] op_sel_hi:[1,0,1]
	v_pk_fma_f32 v[142:143], v[226:227], s[10:11], v[142:143] op_sel_hi:[1,0,1]
	global_store_dwordx4 v[134:135], v[140:143], off
	v_lshl_add_u64 v[134:135], v[134:135], 0, s[76:77]
	s_waitcnt vmcnt(7) lgkmcnt(6)
	v_pk_fma_f32 v[144:145], v[228:229], s[10:11], v[144:145] op_sel_hi:[1,0,1]
	v_pk_fma_f32 v[146:147], v[230:231], s[10:11], v[146:147] op_sel_hi:[1,0,1]
	global_store_dwordx4 v[134:135], v[144:147], off
	v_lshl_add_u64 v[134:135], v[134:135], 0, s[76:77]
	s_waitcnt vmcnt(7) lgkmcnt(5)
	v_pk_fma_f32 v[148:149], v[232:233], s[10:11], v[148:149] op_sel_hi:[1,0,1]
	v_pk_fma_f32 v[150:151], v[234:235], s[10:11], v[150:151] op_sel_hi:[1,0,1]
	global_store_dwordx4 v[134:135], v[148:151], off
	v_lshl_add_u64 v[134:135], v[134:135], 0, s[76:77]
	s_waitcnt vmcnt(7) lgkmcnt(4)
	v_pk_fma_f32 v[152:153], v[236:237], s[10:11], v[152:153] op_sel_hi:[1,0,1]
	v_pk_fma_f32 v[154:155], v[238:239], s[10:11], v[154:155] op_sel_hi:[1,0,1]
	global_store_dwordx4 v[134:135], v[152:155], off
	v_lshl_add_u64 v[134:135], v[134:135], 0, s[76:77]
	s_waitcnt vmcnt(7) lgkmcnt(3)
	v_pk_fma_f32 v[156:157], v[240:241], s[10:11], v[156:157] op_sel_hi:[1,0,1]
	v_pk_fma_f32 v[158:159], v[242:243], s[10:11], v[158:159] op_sel_hi:[1,0,1]
	global_store_dwordx4 v[134:135], v[156:159], off
	v_lshl_add_u64 v[134:135], v[134:135], 0, s[76:77]
	s_waitcnt vmcnt(7) lgkmcnt(2)
	v_pk_fma_f32 v[160:161], v[244:245], s[10:11], v[160:161] op_sel_hi:[1,0,1]
	v_pk_fma_f32 v[162:163], v[246:247], s[10:11], v[162:163] op_sel_hi:[1,0,1]
	global_store_dwordx4 v[134:135], v[160:163], off
	v_lshl_add_u64 v[134:135], v[134:135], 0, s[76:77]
	s_waitcnt vmcnt(7) lgkmcnt(1)
	v_pk_fma_f32 v[216:217], v[176:177], s[10:11], v[216:217] op_sel_hi:[1,0,1]
	v_pk_fma_f32 v[218:219], v[178:179], s[10:11], v[218:219] op_sel_hi:[1,0,1]
	global_store_dwordx4 v[134:135], v[216:219], off
	v_lshl_add_u64 v[134:135], v[134:135], 0, s[76:77]
	s_waitcnt vmcnt(7) lgkmcnt(0)
	v_pk_fma_f32 v[220:221], v[200:201], s[10:11], v[220:221] op_sel_hi:[1,0,1]
	v_pk_fma_f32 v[222:223], v[202:203], s[10:11], v[222:223] op_sel_hi:[1,0,1]
	global_store_dwordx4 v[134:135], v[220:223], off
	v_lshl_add_u64 v[134:135], v[134:135], 0, s[76:77]
	s_nop 1
	s_cmp_eq_u32 s60, 1
	s_cbranch_scc0 .LBB0_1354

; DI int otid512() { int t = threadIdx.x; asm volatile("" : "+v"(t)); return t; }
; template <bool GATHER>
; DI void gemm256_main(const h16* __restrict__ A, int lda, const int* __restrict__ idx, int m0,
;                      const h16* __restrict__ B, int ldb, int n0, int K, h16* lds, f16v (&acc)[4][2]) {
;   const int tid = otid512(), lane = tid & 63, wv = tid >> 6, wm = wv >> 2, wn = wv & 3;
;   const int lr = tid >> 1, lc = (tid & 1) * 32;
;   unsigned ao = (unsigned)(GATHER ? idx[m0 + lr] : (m0 + lr)) * (unsigned)lda + lc;
;   unsigned bo = (unsigned)(n0 + lr) * (unsigned)ldb + lc;
;   const h16* ap = A; const h16* bp = B;
;     ...
;   u4v ra[4], rb[4];
;   const int nk = K >> 6;
;   __syncthreads();
; #pragma unroll
;   for (int i = 0; i < 4; ++i) { ra[i] = *(const u4v*)(AP_ + 8 * i); rb[i] = *(const u4v*)(BP_ + 8 * i); }
;   ao += 64; bo += 64;
; #pragma unroll
;   for (int i = 0; i < 4; ++i) { *(u4v*)&lds[lr * LDH + lc + 8 * i] = ra[i]; *(u4v*)&lds[(256 + lr) * LDH + lc + 8 * i] = rb[i]; }
; #pragma unroll
;   for (int i = 0; i < 4; ++i) { ra[i] = *(const u4v*)(AP_ + 8 * i); rb[i] = *(const u4v*)(BP_ + 8 * i); }
;   ao += 64; bo += 64;
;   __syncthreads();
; DI void phase_ffn1_moe(const Params& p, int bid, int nb, h16* lds) {
;     ...
;   for (int u = bid; u < ntl; u += nb) {
;     const int mt = u / 11, m0 = mt * 256, n0 = (u % 11) * 256;
;     int e = 0;
; #pragma unroll
;     for (int i = 1; i < 8; ++i) if (m0 >= ps[i]) e = i;
;     f16v acc[4][2]; acc256_zero(acc);
;     gemm256_main<true>(x16, DM, st, m0, w13 + (size_t)e * 2816 * 1024, 1024, n0, 1024, lds, acc);
.LBB0_1520:
	s_mul_hi_i32 s6, s5, 0x2e8ba2e9
	s_lshr_b32 s7, s6, 31
	s_ashr_i32 s6, s6, 1
	s_add_i32 s7, s6, s7
	v_mov_b32_e32 v34, v180
	s_lshl_b32 s6, s7, 8
	s_cmp_lt_i32 s6, s2
	v_ashrrev_i32_e32 v35, 1, v34
	v_lshlrev_b32_e32 v4, 5, v34
	v_and_b32_e32 v36, 32, v4
	v_add_u32_e32 v4, s6, v35
	v_ashrrev_i32_e32 v5, 31, v4
	v_lshl_add_u64 v[4:5], v[4:5], 2, s[16:17]
	global_load_dword v4, v[4:5], off
	s_cselect_b32 s8, 0, 0x2c0000
	s_cmp_lt_i32 s6, s3
	s_cselect_b32 s8, s8, 0x580000
	v_cmp_lt_i32_e32 vcc, s6, v1
	v_mov_b32_e32 v2, s8
	s_mulk_i32 s7, 0xb00
	v_cndmask_b32_e32 v2, v206, v2, vcc
	v_cmp_lt_i32_e32 vcc, s6, v171
	v_subrev_u32_e32 v5, s7, v35
	v_mov_b32_e32 v3, v0
	v_cndmask_b32_e32 v2, v207, v2, vcc
	v_cmp_lt_i32_e32 vcc, s6, v178
	v_add_u32_e32 v5, s4, v5
	v_lshl_or_b32 v6, v5, 10, v36
	v_cndmask_b32_e32 v2, v208, v2, vcc
	v_cmp_lt_i32_e32 vcc, s6, v179
	v_mov_b32_e32 v5, v0
	v_mov_b32_e32 v7, v0
	v_cndmask_b32_e32 v2, v209, v2, vcc
	v_cmp_lt_i32_e32 vcc, s6, v215
	s_barrier
	s_nop 0
	v_cndmask_b32_e32 v2, v210, v2, vcc
	v_lshlrev_b64 v[2:3], 1, v[2:3]
	v_lshl_add_u64 v[2:3], s[18:19], 0, v[2:3]
	v_lshl_add_u64 v[176:177], v[6:7], 1, v[2:3]
	v_mul_lo_u32 v37, v35, s33
	s_add_i32 s8, 16, 0x12000
	s_add_i32 s9, 16, 0x1b000
	s_add_i32 s5, s5, s22
	s_waitcnt vmcnt(0)
	v_lshl_or_b32 v4, v4, 10, v36
	v_lshl_add_u64 v[174:175], v[4:5], 1, s[20:21]
	v_mov_b32_e32 v130, v174
	v_mov_b32_e32 v131, v175
	v_mov_b32_e32 v200, v176
	v_mov_b32_e32 v201, v177
	s_cselect_b32 s98, 1, 0
	v_readfirstlane_b32 s99, v180
	s_nop 1
	s_cmp_lt_u32 s99, 0x100
	s_cbranch_scc1 .Lprio_skip_4
	s_setprio 1
.Lprio_skip_4:
	s_cmp_eq_u32 s98, 1
	v_lshrrev_b32_e32 v192, 1, v180
	v_and_b32_e32 v193, 1, v180
	v_mul_u32_u24_e32 v192, 0x90, v192
	v_lshl_add_u32 v132, v193, 6, v192
	v_add_u32_e32 v132, 16, v132
	v_add_u32_e32 v133, 0x12000, v132
	v_lshrrev_b32_e32 v192, 8, v180
	v_and_b32_e32 v194, 31, v180
	v_lshl_or_b32 v192, v192, 7, v194
	v_mul_u32_u24_e32 v192, 0x90, v192
	v_bfe_u32 v193, v180, 5, 1
	v_lshl_add_u32 v192, v193, 4, v192
	v_add_u32_e32 v217, 16, v192
	v_add_u32_e32 v212, 0x12000, v217
	v_bfe_u32 v192, v180, 6, 2
	v_lshl_or_b32 v192, v192, 6, v194
	v_mul_u32_u24_e32 v192, 0x90, v192
	v_lshl_add_u32 v192, v193, 4, v192
	v_add_u32_e32 v213, 0x9010, v192
	v_add_u32_e32 v214, 0x12000, v213
	global_load_dwordx4 v[134:137], v[130:131], off offset:0
	global_load_dwordx4 v[138:141], v[130:131], off offset:16
	global_load_dwordx4 v[142:145], v[130:131], off offset:32
	global_load_dwordx4 v[146:149], v[130:131], off offset:48
	global_load_dwordx4 v[150:153], v[200:201], off offset:0
	global_load_dwordx4 v[154:157], v[200:201], off offset:16
	global_load_dwordx4 v[158:161], v[200:201], off offset:32
	global_load_dwordx4 v[162:165], v[200:201], off offset:48
	s_waitcnt vmcnt(0)
	ds_write_b128 v132, v[134:137]
	ds_write_b128 v132, v[138:141] offset:16
	ds_write_b128 v132, v[142:145] offset:32
	ds_write_b128 v132, v[146:149] offset:48
	ds_write_b128 v132, v[150:153] offset:36864
	ds_write_b128 v132, v[154:157] offset:36880
	ds_write_b128 v132, v[158:161] offset:36896
	ds_write_b128 v132, v[162:165] offset:36912
	global_load_dwordx4 v[134:137], v[130:131], off offset:128
	global_load_dwordx4 v[138:141], v[130:131], off offset:144
	global_load_dwordx4 v[142:145], v[130:131], off offset:160
	global_load_dwordx4 v[146:149], v[130:131], off offset:176
	global_load_dwordx4 v[150:153], v[200:201], off offset:128
	global_load_dwordx4 v[154:157], v[200:201], off offset:144
	global_load_dwordx4 v[158:161], v[200:201], off offset:160
	global_load_dwordx4 v[162:165], v[200:201], off offset:176
	s_waitcnt lgkmcnt(0)
	s_barrier
	ds_read_b128 v[234:237], v213
	ds_read_b128 v[218:221], v217
	ds_read_b128 v[238:241], v213 offset:4608
	ds_read_b128 v[222:225], v217 offset:4608
	ds_read_b128 v[226:229], v217 offset:9216
	ds_read_b128 v[230:233], v217 offset:13824
	ds_read_b128 v[188:191], v213 offset:32
	ds_read_b128 v[242:245], v217 offset:32
	ds_read_b128 v[174:177], v213 offset:4640
	ds_read_b128 v[246:249], v217 offset:4640
	ds_read_b128 v[204:207], v217 offset:9248
	ds_read_b128 v[208:211], v217 offset:13856
	s_waitcnt vmcnt(4)
	ds_write_b128 v133, v[134:137]
	ds_write_b128 v133, v[138:141] offset:16
	ds_write_b128 v133, v[142:145] offset:32
	ds_write_b128 v133, v[146:149] offset:48
	global_load_dwordx4 v[134:137], v[130:131], off offset:256
	global_load_dwordx4 v[138:141], v[130:131], off offset:272
	global_load_dwordx4 v[142:145], v[130:131], off offset:288
	global_load_dwordx4 v[146:149], v[130:131], off offset:304
	s_waitcnt lgkmcnt(14)
	v_mfma_f32_32x32x16_f16 v[98:113], v[234:237], v[218:221], 0
	s_waitcnt lgkmcnt(13)
	v_mfma_f32_32x32x16_f16 v[114:129], v[238:241], v[218:221], 0
	s_waitcnt lgkmcnt(12)
	v_mfma_f32_32x32x16_f16 v[66:81], v[234:237], v[222:225], 0
	v_mfma_f32_32x32x16_f16 v[82:97], v[238:241], v[222:225], 0
	s_waitcnt lgkmcnt(11)
	v_mfma_f32_32x32x16_f16 v[34:49], v[234:237], v[226:229], 0
	v_mfma_f32_32x32x16_f16 v[50:65], v[238:241], v[226:229], 0
	s_waitcnt lgkmcnt(10)
	v_mfma_f32_32x32x16_f16 v[2:17], v[234:237], v[230:233], 0
	v_mfma_f32_32x32x16_f16 v[18:33], v[238:241], v[230:233], 0
	ds_read_b128 v[234:237], v213 offset:64
	ds_read_b128 v[218:221], v217 offset:64
	ds_read_b128 v[238:241], v213 offset:4672
	ds_read_b128 v[222:225], v217 offset:4672
	ds_read_b128 v[226:229], v217 offset:9280
	ds_read_b128 v[230:233], v217 offset:13888
	s_waitcnt vmcnt(4)
; DI f16v mfma32(h8v a, h8v b, f16v c) { return __builtin_amdgcn_mfma_f32_32x32x16_f16(a, b, c, 0, 0, 0); }
; template <bool GATHER>
; DI void gemm256_main(const h16* __restrict__ A, int lda, const int* __restrict__ idx, int m0,
;                      const h16* __restrict__ B, int ldb, int n0, int K, h16* lds, f16v (&acc)[4][2]) {
;     ...
;   for (int kt = 0; kt < nk; ++kt) {
;     const h16* As = lds + (kt & 1) * (512 * LDH);
;     const h16* Bs = As + 256 * LDH;
;     h16* Wn = lds + ((kt & 1) ^ 1) * (512 * LDH);
;     if (kt + 1 < nk) {
; #pragma unroll
;       for (int i = 0; i < 4; ++i) { *(u4v*)&Wn[lr * LDH + lc + 8 * i] = ra[i]; *(u4v*)&Wn[(256 + lr) * LDH + lc + 8 * i] = rb[i]; }
;     }
;     if (kt + 2 < nk) {
; #pragma unroll
;       for (int i = 0; i < 4; ++i) { ra[i] = *(const u4v*)(AP_ + 8 * i); rb[i] = *(const u4v*)(BP_ + 8 * i); }
;       ao += 64; bo += 64;
;     }
; #pragma unroll
;     for (int ks = 0; ks < 4; ++ks) {
;       h8v af[4], bf[2];
; #pragma unroll
;       for (int i = 0; i < 4; ++i) af[i] = *(const h8v*)&As[(wm * 128 + i * 32 + (lane & 31)) * LDH + ks * 16 + 8 * (lane >> 5)];
; #pragma unroll
;       for (int j = 0; j < 2; ++j) bf[j] = *(const h8v*)&Bs[(wn * 64 + j * 32 + (lane & 31)) * LDH + ks * 16 + 8 * (lane >> 5)];
; #pragma unroll
;       for (int i = 0; i < 4; ++i)
; #pragma unroll
;         for (int j = 0; j < 2; ++j) acc[i][j] = mfma32(bf[j], af[i], acc[i][j]);
;     }
;     __syncthreads();
;   }
	ds_write_b128 v133, v[150:153] offset:36864
	ds_write_b128 v133, v[154:157] offset:36880
	ds_write_b128 v133, v[158:161] offset:36896
	ds_write_b128 v133, v[162:165] offset:36912
	global_load_dwordx4 v[150:153], v[200:201], off offset:256
	global_load_dwordx4 v[154:157], v[200:201], off offset:272
	global_load_dwordx4 v[158:161], v[200:201], off offset:288
	global_load_dwordx4 v[162:165], v[200:201], off offset:304
	s_waitcnt lgkmcnt(15)
	v_mfma_f32_32x32x16_f16 v[98:113], v[188:191], v[242:245], v[98:113]
	s_waitcnt lgkmcnt(15)
	v_mfma_f32_32x32x16_f16 v[114:129], v[174:177], v[242:245], v[114:129]
	s_waitcnt lgkmcnt(15)
	v_mfma_f32_32x32x16_f16 v[66:81], v[188:191], v[246:249], v[66:81]
	v_mfma_f32_32x32x16_f16 v[82:97], v[174:177], v[246:249], v[82:97]
	s_waitcnt lgkmcnt(15)
	v_mfma_f32_32x32x16_f16 v[34:49], v[188:191], v[204:207], v[34:49]
	v_mfma_f32_32x32x16_f16 v[50:65], v[174:177], v[204:207], v[50:65]
	s_waitcnt lgkmcnt(14)
	v_mfma_f32_32x32x16_f16 v[2:17], v[188:191], v[208:211], v[2:17]
	v_mfma_f32_32x32x16_f16 v[18:33], v[174:177], v[208:211], v[18:33]
	ds_read_b128 v[188:191], v213 offset:96
	ds_read_b128 v[242:245], v217 offset:96
	ds_read_b128 v[174:177], v213 offset:4704
	ds_read_b128 v[246:249], v217 offset:4704
	ds_read_b128 v[204:207], v217 offset:9312
	ds_read_b128 v[208:211], v217 offset:13920
	s_waitcnt lgkmcnt(14)
	v_mfma_f32_32x32x16_f16 v[98:113], v[234:237], v[218:221], v[98:113]
	s_waitcnt lgkmcnt(13)
	v_mfma_f32_32x32x16_f16 v[114:129], v[238:241], v[218:221], v[114:129]
	s_waitcnt lgkmcnt(12)
	v_mfma_f32_32x32x16_f16 v[66:81], v[234:237], v[222:225], v[66:81]
	v_mfma_f32_32x32x16_f16 v[82:97], v[238:241], v[222:225], v[82:97]
	s_waitcnt lgkmcnt(11)
	v_mfma_f32_32x32x16_f16 v[34:49], v[234:237], v[226:229], v[34:49]
	v_mfma_f32_32x32x16_f16 v[50:65], v[238:241], v[226:229], v[50:65]
	s_waitcnt lgkmcnt(10)
	v_mfma_f32_32x32x16_f16 v[2:17], v[234:237], v[230:233], v[2:17]
	v_mfma_f32_32x32x16_f16 v[18:33], v[238:241], v[230:233], v[18:33]
	s_waitcnt lgkmcnt(0)
	s_barrier
	ds_read_b128 v[234:237], v214
	ds_read_b128 v[218:221], v212
	ds_read_b128 v[238:241], v214 offset:4608
	ds_read_b128 v[222:225], v212 offset:4608
	ds_read_b128 v[226:229], v212 offset:9216
	ds_read_b128 v[230:233], v212 offset:13824
	v_mfma_f32_32x32x16_f16 v[98:113], v[188:191], v[242:245], v[98:113]
	v_mfma_f32_32x32x16_f16 v[114:129], v[174:177], v[242:245], v[114:129]
	v_mfma_f32_32x32x16_f16 v[66:81], v[188:191], v[246:249], v[66:81]
	v_mfma_f32_32x32x16_f16 v[82:97], v[174:177], v[246:249], v[82:97]
	v_mfma_f32_32x32x16_f16 v[34:49], v[188:191], v[204:207], v[34:49]
	v_mfma_f32_32x32x16_f16 v[50:65], v[174:177], v[204:207], v[50:65]
	v_mfma_f32_32x32x16_f16 v[2:17], v[188:191], v[208:211], v[2:17]
	v_mfma_f32_32x32x16_f16 v[18:33], v[174:177], v[208:211], v[18:33]
	ds_read_b128 v[188:191], v214 offset:32
	ds_read_b128 v[242:245], v212 offset:32
	ds_read_b128 v[174:177], v214 offset:4640
	ds_read_b128 v[246:249], v212 offset:4640
	ds_read_b128 v[204:207], v212 offset:9248
	ds_read_b128 v[208:211], v212 offset:13856
	s_waitcnt vmcnt(4)
	ds_write_b128 v132, v[134:137]
	ds_write_b128 v132, v[138:141] offset:16
	ds_write_b128 v132, v[142:145] offset:32
	ds_write_b128 v132, v[146:149] offset:48
	global_load_dwordx4 v[134:137], v[130:131], off offset:384
	global_load_dwordx4 v[138:141], v[130:131], off offset:400
	global_load_dwordx4 v[142:145], v[130:131], off offset:416
	global_load_dwordx4 v[146:149], v[130:131], off offset:432
	s_waitcnt lgkmcnt(14)
	v_mfma_f32_32x32x16_f16 v[98:113], v[234:237], v[218:221], v[98:113]
	s_waitcnt lgkmcnt(13)
	v_mfma_f32_32x32x16_f16 v[114:129], v[238:241], v[218:221], v[114:129]
	s_waitcnt lgkmcnt(12)
	v_mfma_f32_32x32x16_f16 v[66:81], v[234:237], v[222:225], v[66:81]
	v_mfma_f32_32x32x16_f16 v[82:97], v[238:241], v[222:225], v[82:97]
	s_waitcnt lgkmcnt(11)
	v_mfma_f32_32x32x16_f16 v[34:49], v[234:237], v[226:229], v[34:49]
	v_mfma_f32_32x32x16_f16 v[50:65], v[238:241], v[226:229], v[50:65]
	s_waitcnt lgkmcnt(10)
	v_mfma_f32_32x32x16_f16 v[2:17], v[234:237], v[230:233], v[2:17]
	v_mfma_f32_32x32x16_f16 v[18:33], v[238:241], v[230:233], v[18:33]
	ds_read_b128 v[234:237], v214 offset:64
	ds_read_b128 v[218:221], v212 offset:64
	ds_read_b128 v[238:241], v214 offset:4672
	ds_read_b128 v[222:225], v212 offset:4672
	ds_read_b128 v[226:229], v212 offset:9280
	ds_read_b128 v[230:233], v212 offset:13888
	s_waitcnt vmcnt(4)
	ds_write_b128 v132, v[150:153] offset:36864
	ds_write_b128 v132, v[154:157] offset:36880
	ds_write_b128 v132, v[158:161] offset:36896
	ds_write_b128 v132, v[162:165] offset:36912
	global_load_dwordx4 v[150:153], v[200:201], off offset:384
	global_load_dwordx4 v[154:157], v[200:201], off offset:400
	global_load_dwordx4 v[158:161], v[200:201], off offset:416
	global_load_dwordx4 v[162:165], v[200:201], off offset:432
	s_waitcnt lgkmcnt(15)
	v_mfma_f32_32x32x16_f16 v[98:113], v[188:191], v[242:245], v[98:113]
	s_waitcnt lgkmcnt(15)
	v_mfma_f32_32x32x16_f16 v[114:129], v[174:177], v[242:245], v[114:129]
	s_waitcnt lgkmcnt(15)
	v_mfma_f32_32x32x16_f16 v[66:81], v[188:191], v[246:249], v[66:81]
	v_mfma_f32_32x32x16_f16 v[82:97], v[174:177], v[246:249], v[82:97]
	s_waitcnt lgkmcnt(15)
	v_mfma_f32_32x32x16_f16 v[34:49], v[188:191], v[204:207], v[34:49]
	v_mfma_f32_32x32x16_f16 v[50:65], v[174:177], v[204:207], v[50:65]
	s_waitcnt lgkmcnt(14)
	v_mfma_f32_32x32x16_f16 v[2:17], v[188:191], v[208:211], v[2:17]
	v_mfma_f32_32x32x16_f16 v[18:33], v[174:177], v[208:211], v[18:33]
	ds_read_b128 v[188:191], v214 offset:96
	ds_read_b128 v[242:245], v212 offset:96
	ds_read_b128 v[174:177], v214 offset:4704
	ds_read_b128 v[246:249], v212 offset:4704
	ds_read_b128 v[204:207], v212 offset:9312
	ds_read_b128 v[208:211], v212 offset:13920
	s_waitcnt lgkmcnt(14)
	v_mfma_f32_32x32x16_f16 v[98:113], v[234:237], v[218:221], v[98:113]
	s_waitcnt lgkmcnt(13)
	v_mfma_f32_32x32x16_f16 v[114:129], v[238:241], v[218:221], v[114:129]
	s_waitcnt lgkmcnt(12)
	v_mfma_f32_32x32x16_f16 v[66:81], v[234:237], v[222:225], v[66:81]
	v_mfma_f32_32x32x16_f16 v[82:97], v[238:241], v[222:225], v[82:97]
	s_waitcnt lgkmcnt(11)
	v_mfma_f32_32x32x16_f16 v[34:49], v[234:237], v[226:229], v[34:49]
	v_mfma_f32_32x32x16_f16 v[50:65], v[238:241], v[226:229], v[50:65]
	s_waitcnt lgkmcnt(10)
	v_mfma_f32_32x32x16_f16 v[2:17], v[234:237], v[230:233], v[2:17]
	v_mfma_f32_32x32x16_f16 v[18:33], v[238:241], v[230:233], v[18:33]
	s_waitcnt lgkmcnt(0)
	s_barrier
; DI f16v mfma32(h8v a, h8v b, f16v c) { return __builtin_amdgcn_mfma_f32_32x32x16_f16(a, b, c, 0, 0, 0); }
; template <bool GATHER>
; DI void gemm256_main(const h16* __restrict__ A, int lda, const int* __restrict__ idx, int m0,
;                      const h16* __restrict__ B, int ldb, int n0, int K, h16* lds, f16v (&acc)[4][2]) {
;     ...
;   for (int kt = 0; kt < nk; ++kt) {
;     const h16* As = lds + (kt & 1) * (512 * LDH);
;     const h16* Bs = As + 256 * LDH;
;     h16* Wn = lds + ((kt & 1) ^ 1) * (512 * LDH);
;     if (kt + 1 < nk) {
; #pragma unroll
;       for (int i = 0; i < 4; ++i) { *(u4v*)&Wn[lr * LDH + lc + 8 * i] = ra[i]; *(u4v*)&Wn[(256 + lr) * LDH + lc + 8 * i] = rb[i]; }
;     }
;     if (kt + 2 < nk) {
; #pragma unroll
;       for (int i = 0; i < 4; ++i) { ra[i] = *(const u4v*)(AP_ + 8 * i); rb[i] = *(const u4v*)(BP_ + 8 * i); }
;       ao += 64; bo += 64;
;     }
; #pragma unroll
;     for (int ks = 0; ks < 4; ++ks) {
;       h8v af[4], bf[2];
; #pragma unroll
;       for (int i = 0; i < 4; ++i) af[i] = *(const h8v*)&As[(wm * 128 + i * 32 + (lane & 31)) * LDH + ks * 16 + 8 * (lane >> 5)];
; #pragma unroll
;       for (int j = 0; j < 2; ++j) bf[j] = *(const h8v*)&Bs[(wn * 64 + j * 32 + (lane & 31)) * LDH + ks * 16 + 8 * (lane >> 5)];
; #pragma unroll
;       for (int i = 0; i < 4; ++i)
; #pragma unroll
;         for (int j = 0; j < 2; ++j) acc[i][j] = mfma32(bf[j], af[i], acc[i][j]);
;     }
;     __syncthreads();
;   }
	ds_read_b128 v[234:237], v213
	ds_read_b128 v[218:221], v217
	ds_read_b128 v[238:241], v213 offset:4608
	ds_read_b128 v[222:225], v217 offset:4608
	ds_read_b128 v[226:229], v217 offset:9216
	ds_read_b128 v[230:233], v217 offset:13824
	v_mfma_f32_32x32x16_f16 v[98:113], v[188:191], v[242:245], v[98:113]
	v_mfma_f32_32x32x16_f16 v[114:129], v[174:177], v[242:245], v[114:129]
	v_mfma_f32_32x32x16_f16 v[66:81], v[188:191], v[246:249], v[66:81]
	v_mfma_f32_32x32x16_f16 v[82:97], v[174:177], v[246:249], v[82:97]
	v_mfma_f32_32x32x16_f16 v[34:49], v[188:191], v[204:207], v[34:49]
	v_mfma_f32_32x32x16_f16 v[50:65], v[174:177], v[204:207], v[50:65]
	v_mfma_f32_32x32x16_f16 v[2:17], v[188:191], v[208:211], v[2:17]
	v_mfma_f32_32x32x16_f16 v[18:33], v[174:177], v[208:211], v[18:33]
	ds_read_b128 v[188:191], v213 offset:32
	ds_read_b128 v[242:245], v217 offset:32
	ds_read_b128 v[174:177], v213 offset:4640
	ds_read_b128 v[246:249], v217 offset:4640
	ds_read_b128 v[204:207], v217 offset:9248
	ds_read_b128 v[208:211], v217 offset:13856
	s_waitcnt vmcnt(4)
	ds_write_b128 v133, v[134:137]
	ds_write_b128 v133, v[138:141] offset:16
	ds_write_b128 v133, v[142:145] offset:32
	ds_write_b128 v133, v[146:149] offset:48
	global_load_dwordx4 v[134:137], v[130:131], off offset:512
	global_load_dwordx4 v[138:141], v[130:131], off offset:528
	global_load_dwordx4 v[142:145], v[130:131], off offset:544
	global_load_dwordx4 v[146:149], v[130:131], off offset:560
	s_waitcnt lgkmcnt(14)
	v_mfma_f32_32x32x16_f16 v[98:113], v[234:237], v[218:221], v[98:113]
	s_waitcnt lgkmcnt(13)
	v_mfma_f32_32x32x16_f16 v[114:129], v[238:241], v[218:221], v[114:129]
	s_waitcnt lgkmcnt(12)
	v_mfma_f32_32x32x16_f16 v[66:81], v[234:237], v[222:225], v[66:81]
	v_mfma_f32_32x32x16_f16 v[82:97], v[238:241], v[222:225], v[82:97]
	s_waitcnt lgkmcnt(11)
	v_mfma_f32_32x32x16_f16 v[34:49], v[234:237], v[226:229], v[34:49]
	v_mfma_f32_32x32x16_f16 v[50:65], v[238:241], v[226:229], v[50:65]
	s_waitcnt lgkmcnt(10)
	v_mfma_f32_32x32x16_f16 v[2:17], v[234:237], v[230:233], v[2:17]
	v_mfma_f32_32x32x16_f16 v[18:33], v[238:241], v[230:233], v[18:33]
	ds_read_b128 v[234:237], v213 offset:64
	ds_read_b128 v[218:221], v217 offset:64
	ds_read_b128 v[238:241], v213 offset:4672
	ds_read_b128 v[222:225], v217 offset:4672
	ds_read_b128 v[226:229], v217 offset:9280
	ds_read_b128 v[230:233], v217 offset:13888
	s_waitcnt vmcnt(4)
	ds_write_b128 v133, v[150:153] offset:36864
	ds_write_b128 v133, v[154:157] offset:36880
	ds_write_b128 v133, v[158:161] offset:36896
	ds_write_b128 v133, v[162:165] offset:36912
	global_load_dwordx4 v[150:153], v[200:201], off offset:512
	global_load_dwordx4 v[154:157], v[200:201], off offset:528
	global_load_dwordx4 v[158:161], v[200:201], off offset:544
	global_load_dwordx4 v[162:165], v[200:201], off offset:560
	s_waitcnt lgkmcnt(15)
	v_mfma_f32_32x32x16_f16 v[98:113], v[188:191], v[242:245], v[98:113]
	s_waitcnt lgkmcnt(15)
	v_mfma_f32_32x32x16_f16 v[114:129], v[174:177], v[242:245], v[114:129]
	s_waitcnt lgkmcnt(15)
	v_mfma_f32_32x32x16_f16 v[66:81], v[188:191], v[246:249], v[66:81]
	v_mfma_f32_32x32x16_f16 v[82:97], v[174:177], v[246:249], v[82:97]
	s_waitcnt lgkmcnt(15)
	v_mfma_f32_32x32x16_f16 v[34:49], v[188:191], v[204:207], v[34:49]
	v_mfma_f32_32x32x16_f16 v[50:65], v[174:177], v[204:207], v[50:65]
	s_waitcnt lgkmcnt(14)
	v_mfma_f32_32x32x16_f16 v[2:17], v[188:191], v[208:211], v[2:17]
	v_mfma_f32_32x32x16_f16 v[18:33], v[174:177], v[208:211], v[18:33]
	ds_read_b128 v[188:191], v213 offset:96
	ds_read_b128 v[242:245], v217 offset:96
	ds_read_b128 v[174:177], v213 offset:4704
	ds_read_b128 v[246:249], v217 offset:4704
	ds_read_b128 v[204:207], v217 offset:9312
	ds_read_b128 v[208:211], v217 offset:13920
	s_waitcnt lgkmcnt(14)
	v_mfma_f32_32x32x16_f16 v[98:113], v[234:237], v[218:221], v[98:113]
	s_waitcnt lgkmcnt(13)
	v_mfma_f32_32x32x16_f16 v[114:129], v[238:241], v[218:221], v[114:129]
	s_waitcnt lgkmcnt(12)
	v_mfma_f32_32x32x16_f16 v[66:81], v[234:237], v[222:225], v[66:81]
	v_mfma_f32_32x32x16_f16 v[82:97], v[238:241], v[222:225], v[82:97]
	s_waitcnt lgkmcnt(11)
	v_mfma_f32_32x32x16_f16 v[34:49], v[234:237], v[226:229], v[34:49]
	v_mfma_f32_32x32x16_f16 v[50:65], v[238:241], v[226:229], v[50:65]
	s_waitcnt lgkmcnt(10)
	v_mfma_f32_32x32x16_f16 v[2:17], v[234:237], v[230:233], v[2:17]
	v_mfma_f32_32x32x16_f16 v[18:33], v[238:241], v[230:233], v[18:33]
	s_waitcnt lgkmcnt(0)
	s_barrier
; DI f16v mfma32(h8v a, h8v b, f16v c) { return __builtin_amdgcn_mfma_f32_32x32x16_f16(a, b, c, 0, 0, 0); }
; template <bool GATHER>
; DI void gemm256_main(const h16* __restrict__ A, int lda, const int* __restrict__ idx, int m0,
;                      const h16* __restrict__ B, int ldb, int n0, int K, h16* lds, f16v (&acc)[4][2]) {
;     ...
;   for (int kt = 0; kt < nk; ++kt) {
;     const h16* As = lds + (kt & 1) * (512 * LDH);
;     const h16* Bs = As + 256 * LDH;
;     h16* Wn = lds + ((kt & 1) ^ 1) * (512 * LDH);
;     if (kt + 1 < nk) {
; #pragma unroll
;       for (int i = 0; i < 4; ++i) { *(u4v*)&Wn[lr * LDH + lc + 8 * i] = ra[i]; *(u4v*)&Wn[(256 + lr) * LDH + lc + 8 * i] = rb[i]; }
;     }
;     if (kt + 2 < nk) {
; #pragma unroll
;       for (int i = 0; i < 4; ++i) { ra[i] = *(const u4v*)(AP_ + 8 * i); rb[i] = *(const u4v*)(BP_ + 8 * i); }
;       ao += 64; bo += 64;
;     }
; #pragma unroll
;     for (int ks = 0; ks < 4; ++ks) {
;       h8v af[4], bf[2];
; #pragma unroll
;       for (int i = 0; i < 4; ++i) af[i] = *(const h8v*)&As[(wm * 128 + i * 32 + (lane & 31)) * LDH + ks * 16 + 8 * (lane >> 5)];
; #pragma unroll
;       for (int j = 0; j < 2; ++j) bf[j] = *(const h8v*)&Bs[(wn * 64 + j * 32 + (lane & 31)) * LDH + ks * 16 + 8 * (lane >> 5)];
; #pragma unroll
;       for (int i = 0; i < 4; ++i)
; #pragma unroll
;         for (int j = 0; j < 2; ++j) acc[i][j] = mfma32(bf[j], af[i], acc[i][j]);
;     }
;     __syncthreads();
;   }
	ds_read_b128 v[234:237], v214
	ds_read_b128 v[218:221], v212
	ds_read_b128 v[238:241], v214 offset:4608
	ds_read_b128 v[222:225], v212 offset:4608
	ds_read_b128 v[226:229], v212 offset:9216
	ds_read_b128 v[230:233], v212 offset:13824
	v_mfma_f32_32x32x16_f16 v[98:113], v[188:191], v[242:245], v[98:113]
	v_mfma_f32_32x32x16_f16 v[114:129], v[174:177], v[242:245], v[114:129]
	v_mfma_f32_32x32x16_f16 v[66:81], v[188:191], v[246:249], v[66:81]
	v_mfma_f32_32x32x16_f16 v[82:97], v[174:177], v[246:249], v[82:97]
	v_mfma_f32_32x32x16_f16 v[34:49], v[188:191], v[204:207], v[34:49]
	v_mfma_f32_32x32x16_f16 v[50:65], v[174:177], v[204:207], v[50:65]
	v_mfma_f32_32x32x16_f16 v[2:17], v[188:191], v[208:211], v[2:17]
	v_mfma_f32_32x32x16_f16 v[18:33], v[174:177], v[208:211], v[18:33]
	ds_read_b128 v[188:191], v214 offset:32
	ds_read_b128 v[242:245], v212 offset:32
	ds_read_b128 v[174:177], v214 offset:4640
	ds_read_b128 v[246:249], v212 offset:4640
	ds_read_b128 v[204:207], v212 offset:9248
	ds_read_b128 v[208:211], v212 offset:13856
	s_waitcnt vmcnt(4)
	ds_write_b128 v132, v[134:137]
	ds_write_b128 v132, v[138:141] offset:16
	ds_write_b128 v132, v[142:145] offset:32
	ds_write_b128 v132, v[146:149] offset:48
	global_load_dwordx4 v[134:137], v[130:131], off offset:640
	global_load_dwordx4 v[138:141], v[130:131], off offset:656
	global_load_dwordx4 v[142:145], v[130:131], off offset:672
	global_load_dwordx4 v[146:149], v[130:131], off offset:688
	s_waitcnt lgkmcnt(14)
	v_mfma_f32_32x32x16_f16 v[98:113], v[234:237], v[218:221], v[98:113]
	s_waitcnt lgkmcnt(13)
	v_mfma_f32_32x32x16_f16 v[114:129], v[238:241], v[218:221], v[114:129]
	s_waitcnt lgkmcnt(12)
	v_mfma_f32_32x32x16_f16 v[66:81], v[234:237], v[222:225], v[66:81]
	v_mfma_f32_32x32x16_f16 v[82:97], v[238:241], v[222:225], v[82:97]
	s_waitcnt lgkmcnt(11)
	v_mfma_f32_32x32x16_f16 v[34:49], v[234:237], v[226:229], v[34:49]
	v_mfma_f32_32x32x16_f16 v[50:65], v[238:241], v[226:229], v[50:65]
	s_waitcnt lgkmcnt(10)
	v_mfma_f32_32x32x16_f16 v[2:17], v[234:237], v[230:233], v[2:17]
	v_mfma_f32_32x32x16_f16 v[18:33], v[238:241], v[230:233], v[18:33]
	ds_read_b128 v[234:237], v214 offset:64
	ds_read_b128 v[218:221], v212 offset:64
	ds_read_b128 v[238:241], v214 offset:4672
	ds_read_b128 v[222:225], v212 offset:4672
	ds_read_b128 v[226:229], v212 offset:9280
	ds_read_b128 v[230:233], v212 offset:13888
	s_waitcnt vmcnt(4)
	ds_write_b128 v132, v[150:153] offset:36864
	ds_write_b128 v132, v[154:157] offset:36880
	ds_write_b128 v132, v[158:161] offset:36896
	ds_write_b128 v132, v[162:165] offset:36912
	global_load_dwordx4 v[150:153], v[200:201], off offset:640
	global_load_dwordx4 v[154:157], v[200:201], off offset:656
	global_load_dwordx4 v[158:161], v[200:201], off offset:672
	global_load_dwordx4 v[162:165], v[200:201], off offset:688
	s_waitcnt lgkmcnt(15)
	v_mfma_f32_32x32x16_f16 v[98:113], v[188:191], v[242:245], v[98:113]
	s_waitcnt lgkmcnt(15)
	v_mfma_f32_32x32x16_f16 v[114:129], v[174:177], v[242:245], v[114:129]
	s_waitcnt lgkmcnt(15)
	v_mfma_f32_32x32x16_f16 v[66:81], v[188:191], v[246:249], v[66:81]
	v_mfma_f32_32x32x16_f16 v[82:97], v[174:177], v[246:249], v[82:97]
	s_waitcnt lgkmcnt(15)
	v_mfma_f32_32x32x16_f16 v[34:49], v[188:191], v[204:207], v[34:49]
	v_mfma_f32_32x32x16_f16 v[50:65], v[174:177], v[204:207], v[50:65]
	s_waitcnt lgkmcnt(14)
	v_mfma_f32_32x32x16_f16 v[2:17], v[188:191], v[208:211], v[2:17]
	v_mfma_f32_32x32x16_f16 v[18:33], v[174:177], v[208:211], v[18:33]
	ds_read_b128 v[188:191], v214 offset:96
	ds_read_b128 v[242:245], v212 offset:96
	ds_read_b128 v[174:177], v214 offset:4704
	ds_read_b128 v[246:249], v212 offset:4704
	ds_read_b128 v[204:207], v212 offset:9312
	ds_read_b128 v[208:211], v212 offset:13920
	s_waitcnt lgkmcnt(14)
	v_mfma_f32_32x32x16_f16 v[98:113], v[234:237], v[218:221], v[98:113]
	s_waitcnt lgkmcnt(13)
	v_mfma_f32_32x32x16_f16 v[114:129], v[238:241], v[218:221], v[114:129]
	s_waitcnt lgkmcnt(12)
	v_mfma_f32_32x32x16_f16 v[66:81], v[234:237], v[222:225], v[66:81]
	v_mfma_f32_32x32x16_f16 v[82:97], v[238:241], v[222:225], v[82:97]
	s_waitcnt lgkmcnt(11)
	v_mfma_f32_32x32x16_f16 v[34:49], v[234:237], v[226:229], v[34:49]
	v_mfma_f32_32x32x16_f16 v[50:65], v[238:241], v[226:229], v[50:65]
	s_waitcnt lgkmcnt(10)
	v_mfma_f32_32x32x16_f16 v[2:17], v[234:237], v[230:233], v[2:17]
	v_mfma_f32_32x32x16_f16 v[18:33], v[238:241], v[230:233], v[18:33]
	s_waitcnt lgkmcnt(0)
	s_barrier
; DI f16v mfma32(h8v a, h8v b, f16v c) { return __builtin_amdgcn_mfma_f32_32x32x16_f16(a, b, c, 0, 0, 0); }
; template <bool GATHER>
; DI void gemm256_main(const h16* __restrict__ A, int lda, const int* __restrict__ idx, int m0,
;                      const h16* __restrict__ B, int ldb, int n0, int K, h16* lds, f16v (&acc)[4][2]) {
;     ...
;   for (int kt = 0; kt < nk; ++kt) {
;     const h16* As = lds + (kt & 1) * (512 * LDH);
;     const h16* Bs = As + 256 * LDH;
;     h16* Wn = lds + ((kt & 1) ^ 1) * (512 * LDH);
;     if (kt + 1 < nk) {
; #pragma unroll
;       for (int i = 0; i < 4; ++i) { *(u4v*)&Wn[lr * LDH + lc + 8 * i] = ra[i]; *(u4v*)&Wn[(256 + lr) * LDH + lc + 8 * i] = rb[i]; }
;     }
;     if (kt + 2 < nk) {
; #pragma unroll
;       for (int i = 0; i < 4; ++i) { ra[i] = *(const u4v*)(AP_ + 8 * i); rb[i] = *(const u4v*)(BP_ + 8 * i); }
;       ao += 64; bo += 64;
;     }
; #pragma unroll
;     for (int ks = 0; ks < 4; ++ks) {
;       h8v af[4], bf[2];
; #pragma unroll
;       for (int i = 0; i < 4; ++i) af[i] = *(const h8v*)&As[(wm * 128 + i * 32 + (lane & 31)) * LDH + ks * 16 + 8 * (lane >> 5)];
; #pragma unroll
;       for (int j = 0; j < 2; ++j) bf[j] = *(const h8v*)&Bs[(wn * 64 + j * 32 + (lane & 31)) * LDH + ks * 16 + 8 * (lane >> 5)];
; #pragma unroll
;       for (int i = 0; i < 4; ++i)
; #pragma unroll
;         for (int j = 0; j < 2; ++j) acc[i][j] = mfma32(bf[j], af[i], acc[i][j]);
;     }
;     __syncthreads();
;   }
	ds_read_b128 v[234:237], v213
	ds_read_b128 v[218:221], v217
	ds_read_b128 v[238:241], v213 offset:4608
	ds_read_b128 v[222:225], v217 offset:4608
	ds_read_b128 v[226:229], v217 offset:9216
	ds_read_b128 v[230:233], v217 offset:13824
	v_mfma_f32_32x32x16_f16 v[98:113], v[188:191], v[242:245], v[98:113]
	v_mfma_f32_32x32x16_f16 v[114:129], v[174:177], v[242:245], v[114:129]
	v_mfma_f32_32x32x16_f16 v[66:81], v[188:191], v[246:249], v[66:81]
	v_mfma_f32_32x32x16_f16 v[82:97], v[174:177], v[246:249], v[82:97]
	v_mfma_f32_32x32x16_f16 v[34:49], v[188:191], v[204:207], v[34:49]
	v_mfma_f32_32x32x16_f16 v[50:65], v[174:177], v[204:207], v[50:65]
	v_mfma_f32_32x32x16_f16 v[2:17], v[188:191], v[208:211], v[2:17]
	v_mfma_f32_32x32x16_f16 v[18:33], v[174:177], v[208:211], v[18:33]
	ds_read_b128 v[188:191], v213 offset:32
	ds_read_b128 v[242:245], v217 offset:32
	ds_read_b128 v[174:177], v213 offset:4640
	ds_read_b128 v[246:249], v217 offset:4640
	ds_read_b128 v[204:207], v217 offset:9248
	ds_read_b128 v[208:211], v217 offset:13856
	s_waitcnt vmcnt(4)
	ds_write_b128 v133, v[134:137]
	ds_write_b128 v133, v[138:141] offset:16
	ds_write_b128 v133, v[142:145] offset:32
	ds_write_b128 v133, v[146:149] offset:48
	global_load_dwordx4 v[134:137], v[130:131], off offset:768
	global_load_dwordx4 v[138:141], v[130:131], off offset:784
	global_load_dwordx4 v[142:145], v[130:131], off offset:800
	global_load_dwordx4 v[146:149], v[130:131], off offset:816
	s_waitcnt lgkmcnt(14)
	v_mfma_f32_32x32x16_f16 v[98:113], v[234:237], v[218:221], v[98:113]
	s_waitcnt lgkmcnt(13)
	v_mfma_f32_32x32x16_f16 v[114:129], v[238:241], v[218:221], v[114:129]
	s_waitcnt lgkmcnt(12)
	v_mfma_f32_32x32x16_f16 v[66:81], v[234:237], v[222:225], v[66:81]
	v_mfma_f32_32x32x16_f16 v[82:97], v[238:241], v[222:225], v[82:97]
	s_waitcnt lgkmcnt(11)
	v_mfma_f32_32x32x16_f16 v[34:49], v[234:237], v[226:229], v[34:49]
	v_mfma_f32_32x32x16_f16 v[50:65], v[238:241], v[226:229], v[50:65]
	s_waitcnt lgkmcnt(10)
	v_mfma_f32_32x32x16_f16 v[2:17], v[234:237], v[230:233], v[2:17]
	v_mfma_f32_32x32x16_f16 v[18:33], v[238:241], v[230:233], v[18:33]
	ds_read_b128 v[234:237], v213 offset:64
	ds_read_b128 v[218:221], v217 offset:64
	ds_read_b128 v[238:241], v213 offset:4672
	ds_read_b128 v[222:225], v217 offset:4672
	ds_read_b128 v[226:229], v217 offset:9280
	ds_read_b128 v[230:233], v217 offset:13888
	s_waitcnt vmcnt(4)
	ds_write_b128 v133, v[150:153] offset:36864
	ds_write_b128 v133, v[154:157] offset:36880
	ds_write_b128 v133, v[158:161] offset:36896
	ds_write_b128 v133, v[162:165] offset:36912
	global_load_dwordx4 v[150:153], v[200:201], off offset:768
	global_load_dwordx4 v[154:157], v[200:201], off offset:784
	global_load_dwordx4 v[158:161], v[200:201], off offset:800
	global_load_dwordx4 v[162:165], v[200:201], off offset:816
	s_waitcnt lgkmcnt(15)
	v_mfma_f32_32x32x16_f16 v[98:113], v[188:191], v[242:245], v[98:113]
	s_waitcnt lgkmcnt(15)
	v_mfma_f32_32x32x16_f16 v[114:129], v[174:177], v[242:245], v[114:129]
	s_waitcnt lgkmcnt(15)
	v_mfma_f32_32x32x16_f16 v[66:81], v[188:191], v[246:249], v[66:81]
	v_mfma_f32_32x32x16_f16 v[82:97], v[174:177], v[246:249], v[82:97]
	s_waitcnt lgkmcnt(15)
	v_mfma_f32_32x32x16_f16 v[34:49], v[188:191], v[204:207], v[34:49]
	v_mfma_f32_32x32x16_f16 v[50:65], v[174:177], v[204:207], v[50:65]
	s_waitcnt lgkmcnt(14)
	v_mfma_f32_32x32x16_f16 v[2:17], v[188:191], v[208:211], v[2:17]
	v_mfma_f32_32x32x16_f16 v[18:33], v[174:177], v[208:211], v[18:33]
	ds_read_b128 v[188:191], v213 offset:96
	ds_read_b128 v[242:245], v217 offset:96
	ds_read_b128 v[174:177], v213 offset:4704
	ds_read_b128 v[246:249], v217 offset:4704
	ds_read_b128 v[204:207], v217 offset:9312
	ds_read_b128 v[208:211], v217 offset:13920
	s_waitcnt lgkmcnt(14)
	v_mfma_f32_32x32x16_f16 v[98:113], v[234:237], v[218:221], v[98:113]
	s_waitcnt lgkmcnt(13)
	v_mfma_f32_32x32x16_f16 v[114:129], v[238:241], v[218:221], v[114:129]
	s_waitcnt lgkmcnt(12)
	v_mfma_f32_32x32x16_f16 v[66:81], v[234:237], v[222:225], v[66:81]
	v_mfma_f32_32x32x16_f16 v[82:97], v[238:241], v[222:225], v[82:97]
	s_waitcnt lgkmcnt(11)
	v_mfma_f32_32x32x16_f16 v[34:49], v[234:237], v[226:229], v[34:49]
	v_mfma_f32_32x32x16_f16 v[50:65], v[238:241], v[226:229], v[50:65]
	s_waitcnt lgkmcnt(10)
	v_mfma_f32_32x32x16_f16 v[2:17], v[234:237], v[230:233], v[2:17]
	v_mfma_f32_32x32x16_f16 v[18:33], v[238:241], v[230:233], v[18:33]
	s_waitcnt lgkmcnt(0)
	s_barrier
; DI f16v mfma32(h8v a, h8v b, f16v c) { return __builtin_amdgcn_mfma_f32_32x32x16_f16(a, b, c, 0, 0, 0); }
; template <bool GATHER>
; DI void gemm256_main(const h16* __restrict__ A, int lda, const int* __restrict__ idx, int m0,
;                      const h16* __restrict__ B, int ldb, int n0, int K, h16* lds, f16v (&acc)[4][2]) {
;     ...
;   for (int kt = 0; kt < nk; ++kt) {
;     const h16* As = lds + (kt & 1) * (512 * LDH);
;     const h16* Bs = As + 256 * LDH;
;     h16* Wn = lds + ((kt & 1) ^ 1) * (512 * LDH);
;     if (kt + 1 < nk) {
; #pragma unroll
;       for (int i = 0; i < 4; ++i) { *(u4v*)&Wn[lr * LDH + lc + 8 * i] = ra[i]; *(u4v*)&Wn[(256 + lr) * LDH + lc + 8 * i] = rb[i]; }
;     }
;     if (kt + 2 < nk) {
; #pragma unroll
;       for (int i = 0; i < 4; ++i) { ra[i] = *(const u4v*)(AP_ + 8 * i); rb[i] = *(const u4v*)(BP_ + 8 * i); }
;       ao += 64; bo += 64;
;     }
; #pragma unroll
;     for (int ks = 0; ks < 4; ++ks) {
;       h8v af[4], bf[2];
; #pragma unroll
;       for (int i = 0; i < 4; ++i) af[i] = *(const h8v*)&As[(wm * 128 + i * 32 + (lane & 31)) * LDH + ks * 16 + 8 * (lane >> 5)];
; #pragma unroll
;       for (int j = 0; j < 2; ++j) bf[j] = *(const h8v*)&Bs[(wn * 64 + j * 32 + (lane & 31)) * LDH + ks * 16 + 8 * (lane >> 5)];
; #pragma unroll
;       for (int i = 0; i < 4; ++i)
; #pragma unroll
;         for (int j = 0; j < 2; ++j) acc[i][j] = mfma32(bf[j], af[i], acc[i][j]);
;     }
;     __syncthreads();
;   }
	ds_read_b128 v[234:237], v214
	ds_read_b128 v[218:221], v212
	ds_read_b128 v[238:241], v214 offset:4608
	ds_read_b128 v[222:225], v212 offset:4608
	ds_read_b128 v[226:229], v212 offset:9216
	ds_read_b128 v[230:233], v212 offset:13824
	v_mfma_f32_32x32x16_f16 v[98:113], v[188:191], v[242:245], v[98:113]
	v_mfma_f32_32x32x16_f16 v[114:129], v[174:177], v[242:245], v[114:129]
	v_mfma_f32_32x32x16_f16 v[66:81], v[188:191], v[246:249], v[66:81]
	v_mfma_f32_32x32x16_f16 v[82:97], v[174:177], v[246:249], v[82:97]
	v_mfma_f32_32x32x16_f16 v[34:49], v[188:191], v[204:207], v[34:49]
	v_mfma_f32_32x32x16_f16 v[50:65], v[174:177], v[204:207], v[50:65]
	v_mfma_f32_32x32x16_f16 v[2:17], v[188:191], v[208:211], v[2:17]
	v_mfma_f32_32x32x16_f16 v[18:33], v[174:177], v[208:211], v[18:33]
	ds_read_b128 v[188:191], v214 offset:32
	ds_read_b128 v[242:245], v212 offset:32
	ds_read_b128 v[174:177], v214 offset:4640
	ds_read_b128 v[246:249], v212 offset:4640
	ds_read_b128 v[204:207], v212 offset:9248
	ds_read_b128 v[208:211], v212 offset:13856
	s_waitcnt vmcnt(4)
	ds_write_b128 v132, v[134:137]
	ds_write_b128 v132, v[138:141] offset:16
	ds_write_b128 v132, v[142:145] offset:32
	ds_write_b128 v132, v[146:149] offset:48
	global_load_dwordx4 v[134:137], v[130:131], off offset:896
	global_load_dwordx4 v[138:141], v[130:131], off offset:912
	global_load_dwordx4 v[142:145], v[130:131], off offset:928
	global_load_dwordx4 v[146:149], v[130:131], off offset:944
	s_waitcnt lgkmcnt(14)
	v_mfma_f32_32x32x16_f16 v[98:113], v[234:237], v[218:221], v[98:113]
	s_waitcnt lgkmcnt(13)
	v_mfma_f32_32x32x16_f16 v[114:129], v[238:241], v[218:221], v[114:129]
	s_waitcnt lgkmcnt(12)
	v_mfma_f32_32x32x16_f16 v[66:81], v[234:237], v[222:225], v[66:81]
	v_mfma_f32_32x32x16_f16 v[82:97], v[238:241], v[222:225], v[82:97]
	s_waitcnt lgkmcnt(11)
	v_mfma_f32_32x32x16_f16 v[34:49], v[234:237], v[226:229], v[34:49]
	v_mfma_f32_32x32x16_f16 v[50:65], v[238:241], v[226:229], v[50:65]
	s_waitcnt lgkmcnt(10)
	v_mfma_f32_32x32x16_f16 v[2:17], v[234:237], v[230:233], v[2:17]
	v_mfma_f32_32x32x16_f16 v[18:33], v[238:241], v[230:233], v[18:33]
	ds_read_b128 v[234:237], v214 offset:64
	ds_read_b128 v[218:221], v212 offset:64
	ds_read_b128 v[238:241], v214 offset:4672
	ds_read_b128 v[222:225], v212 offset:4672
	ds_read_b128 v[226:229], v212 offset:9280
	ds_read_b128 v[230:233], v212 offset:13888
	s_waitcnt vmcnt(4)
	ds_write_b128 v132, v[150:153] offset:36864
	ds_write_b128 v132, v[154:157] offset:36880
	ds_write_b128 v132, v[158:161] offset:36896
	ds_write_b128 v132, v[162:165] offset:36912
	global_load_dwordx4 v[150:153], v[200:201], off offset:896
	global_load_dwordx4 v[154:157], v[200:201], off offset:912
	global_load_dwordx4 v[158:161], v[200:201], off offset:928
	global_load_dwordx4 v[162:165], v[200:201], off offset:944
	s_waitcnt lgkmcnt(15)
	v_mfma_f32_32x32x16_f16 v[98:113], v[188:191], v[242:245], v[98:113]
	s_waitcnt lgkmcnt(15)
	v_mfma_f32_32x32x16_f16 v[114:129], v[174:177], v[242:245], v[114:129]
	s_waitcnt lgkmcnt(15)
	v_mfma_f32_32x32x16_f16 v[66:81], v[188:191], v[246:249], v[66:81]
	v_mfma_f32_32x32x16_f16 v[82:97], v[174:177], v[246:249], v[82:97]
	s_waitcnt lgkmcnt(15)
	v_mfma_f32_32x32x16_f16 v[34:49], v[188:191], v[204:207], v[34:49]
	v_mfma_f32_32x32x16_f16 v[50:65], v[174:177], v[204:207], v[50:65]
	s_waitcnt lgkmcnt(14)
	v_mfma_f32_32x32x16_f16 v[2:17], v[188:191], v[208:211], v[2:17]
	v_mfma_f32_32x32x16_f16 v[18:33], v[174:177], v[208:211], v[18:33]
	ds_read_b128 v[188:191], v214 offset:96
	ds_read_b128 v[242:245], v212 offset:96
	ds_read_b128 v[174:177], v214 offset:4704
	ds_read_b128 v[246:249], v212 offset:4704
	ds_read_b128 v[204:207], v212 offset:9312
	ds_read_b128 v[208:211], v212 offset:13920
	s_waitcnt lgkmcnt(14)
	v_mfma_f32_32x32x16_f16 v[98:113], v[234:237], v[218:221], v[98:113]
	s_waitcnt lgkmcnt(13)
	v_mfma_f32_32x32x16_f16 v[114:129], v[238:241], v[218:221], v[114:129]
	s_waitcnt lgkmcnt(12)
	v_mfma_f32_32x32x16_f16 v[66:81], v[234:237], v[222:225], v[66:81]
	v_mfma_f32_32x32x16_f16 v[82:97], v[238:241], v[222:225], v[82:97]
	s_waitcnt lgkmcnt(11)
	v_mfma_f32_32x32x16_f16 v[34:49], v[234:237], v[226:229], v[34:49]
	v_mfma_f32_32x32x16_f16 v[50:65], v[238:241], v[226:229], v[50:65]
	s_waitcnt lgkmcnt(10)
	v_mfma_f32_32x32x16_f16 v[2:17], v[234:237], v[230:233], v[2:17]
	v_mfma_f32_32x32x16_f16 v[18:33], v[238:241], v[230:233], v[18:33]
	s_waitcnt lgkmcnt(0)
	s_barrier
; DI f16v mfma32(h8v a, h8v b, f16v c) { return __builtin_amdgcn_mfma_f32_32x32x16_f16(a, b, c, 0, 0, 0); }
; template <bool GATHER>
; DI void gemm256_main(const h16* __restrict__ A, int lda, const int* __restrict__ idx, int m0,
;                      const h16* __restrict__ B, int ldb, int n0, int K, h16* lds, f16v (&acc)[4][2]) {
;     ...
;   for (int kt = 0; kt < nk; ++kt) {
;     const h16* As = lds + (kt & 1) * (512 * LDH);
;     const h16* Bs = As + 256 * LDH;
;     h16* Wn = lds + ((kt & 1) ^ 1) * (512 * LDH);
;     if (kt + 1 < nk) {
; #pragma unroll
;       for (int i = 0; i < 4; ++i) { *(u4v*)&Wn[lr * LDH + lc + 8 * i] = ra[i]; *(u4v*)&Wn[(256 + lr) * LDH + lc + 8 * i] = rb[i]; }
;     }
;     if (kt + 2 < nk) {
; #pragma unroll
;       for (int i = 0; i < 4; ++i) { ra[i] = *(const u4v*)(AP_ + 8 * i); rb[i] = *(const u4v*)(BP_ + 8 * i); }
;       ao += 64; bo += 64;
;     }
; #pragma unroll
;     for (int ks = 0; ks < 4; ++ks) {
;       h8v af[4], bf[2];
; #pragma unroll
;       for (int i = 0; i < 4; ++i) af[i] = *(const h8v*)&As[(wm * 128 + i * 32 + (lane & 31)) * LDH + ks * 16 + 8 * (lane >> 5)];
; #pragma unroll
;       for (int j = 0; j < 2; ++j) bf[j] = *(const h8v*)&Bs[(wn * 64 + j * 32 + (lane & 31)) * LDH + ks * 16 + 8 * (lane >> 5)];
; #pragma unroll
;       for (int i = 0; i < 4; ++i)
; #pragma unroll
;         for (int j = 0; j < 2; ++j) acc[i][j] = mfma32(bf[j], af[i], acc[i][j]);
;     }
;     __syncthreads();
;   }
	ds_read_b128 v[234:237], v213
	ds_read_b128 v[218:221], v217
	ds_read_b128 v[238:241], v213 offset:4608
	ds_read_b128 v[222:225], v217 offset:4608
	ds_read_b128 v[226:229], v217 offset:9216
	ds_read_b128 v[230:233], v217 offset:13824
	v_mfma_f32_32x32x16_f16 v[98:113], v[188:191], v[242:245], v[98:113]
	v_mfma_f32_32x32x16_f16 v[114:129], v[174:177], v[242:245], v[114:129]
	v_mfma_f32_32x32x16_f16 v[66:81], v[188:191], v[246:249], v[66:81]
	v_mfma_f32_32x32x16_f16 v[82:97], v[174:177], v[246:249], v[82:97]
	v_mfma_f32_32x32x16_f16 v[34:49], v[188:191], v[204:207], v[34:49]
	v_mfma_f32_32x32x16_f16 v[50:65], v[174:177], v[204:207], v[50:65]
	v_mfma_f32_32x32x16_f16 v[2:17], v[188:191], v[208:211], v[2:17]
	v_mfma_f32_32x32x16_f16 v[18:33], v[174:177], v[208:211], v[18:33]
	ds_read_b128 v[188:191], v213 offset:32
	ds_read_b128 v[242:245], v217 offset:32
	ds_read_b128 v[174:177], v213 offset:4640
	ds_read_b128 v[246:249], v217 offset:4640
	ds_read_b128 v[204:207], v217 offset:9248
	ds_read_b128 v[208:211], v217 offset:13856
	s_waitcnt vmcnt(4)
	ds_write_b128 v133, v[134:137]
	ds_write_b128 v133, v[138:141] offset:16
	ds_write_b128 v133, v[142:145] offset:32
	ds_write_b128 v133, v[146:149] offset:48
	global_load_dwordx4 v[134:137], v[130:131], off offset:1024
	global_load_dwordx4 v[138:141], v[130:131], off offset:1040
	global_load_dwordx4 v[142:145], v[130:131], off offset:1056
	global_load_dwordx4 v[146:149], v[130:131], off offset:1072
	s_waitcnt lgkmcnt(14)
	v_mfma_f32_32x32x16_f16 v[98:113], v[234:237], v[218:221], v[98:113]
	s_waitcnt lgkmcnt(13)
	v_mfma_f32_32x32x16_f16 v[114:129], v[238:241], v[218:221], v[114:129]
	s_waitcnt lgkmcnt(12)
	v_mfma_f32_32x32x16_f16 v[66:81], v[234:237], v[222:225], v[66:81]
	v_mfma_f32_32x32x16_f16 v[82:97], v[238:241], v[222:225], v[82:97]
	s_waitcnt lgkmcnt(11)
	v_mfma_f32_32x32x16_f16 v[34:49], v[234:237], v[226:229], v[34:49]
	v_mfma_f32_32x32x16_f16 v[50:65], v[238:241], v[226:229], v[50:65]
	s_waitcnt lgkmcnt(10)
	v_mfma_f32_32x32x16_f16 v[2:17], v[234:237], v[230:233], v[2:17]
	v_mfma_f32_32x32x16_f16 v[18:33], v[238:241], v[230:233], v[18:33]
	ds_read_b128 v[234:237], v213 offset:64
	ds_read_b128 v[218:221], v217 offset:64
	ds_read_b128 v[238:241], v213 offset:4672
	ds_read_b128 v[222:225], v217 offset:4672
	ds_read_b128 v[226:229], v217 offset:9280
	ds_read_b128 v[230:233], v217 offset:13888
	s_waitcnt vmcnt(4)
	ds_write_b128 v133, v[150:153] offset:36864
	ds_write_b128 v133, v[154:157] offset:36880
	ds_write_b128 v133, v[158:161] offset:36896
	ds_write_b128 v133, v[162:165] offset:36912
	global_load_dwordx4 v[150:153], v[200:201], off offset:1024
	global_load_dwordx4 v[154:157], v[200:201], off offset:1040
	global_load_dwordx4 v[158:161], v[200:201], off offset:1056
	global_load_dwordx4 v[162:165], v[200:201], off offset:1072
	s_waitcnt lgkmcnt(15)
	v_mfma_f32_32x32x16_f16 v[98:113], v[188:191], v[242:245], v[98:113]
	s_waitcnt lgkmcnt(15)
	v_mfma_f32_32x32x16_f16 v[114:129], v[174:177], v[242:245], v[114:129]
	s_waitcnt lgkmcnt(15)
	v_mfma_f32_32x32x16_f16 v[66:81], v[188:191], v[246:249], v[66:81]
	v_mfma_f32_32x32x16_f16 v[82:97], v[174:177], v[246:249], v[82:97]
	s_waitcnt lgkmcnt(15)
	v_mfma_f32_32x32x16_f16 v[34:49], v[188:191], v[204:207], v[34:49]
	v_mfma_f32_32x32x16_f16 v[50:65], v[174:177], v[204:207], v[50:65]
	s_waitcnt lgkmcnt(14)
	v_mfma_f32_32x32x16_f16 v[2:17], v[188:191], v[208:211], v[2:17]
	v_mfma_f32_32x32x16_f16 v[18:33], v[174:177], v[208:211], v[18:33]
	ds_read_b128 v[188:191], v213 offset:96
	ds_read_b128 v[242:245], v217 offset:96
	ds_read_b128 v[174:177], v213 offset:4704
	ds_read_b128 v[246:249], v217 offset:4704
	ds_read_b128 v[204:207], v217 offset:9312
	ds_read_b128 v[208:211], v217 offset:13920
	s_waitcnt lgkmcnt(14)
	v_mfma_f32_32x32x16_f16 v[98:113], v[234:237], v[218:221], v[98:113]
	s_waitcnt lgkmcnt(13)
	v_mfma_f32_32x32x16_f16 v[114:129], v[238:241], v[218:221], v[114:129]
	s_waitcnt lgkmcnt(12)
	v_mfma_f32_32x32x16_f16 v[66:81], v[234:237], v[222:225], v[66:81]
	v_mfma_f32_32x32x16_f16 v[82:97], v[238:241], v[222:225], v[82:97]
	s_waitcnt lgkmcnt(11)
	v_mfma_f32_32x32x16_f16 v[34:49], v[234:237], v[226:229], v[34:49]
	v_mfma_f32_32x32x16_f16 v[50:65], v[238:241], v[226:229], v[50:65]
	s_waitcnt lgkmcnt(10)
	v_mfma_f32_32x32x16_f16 v[2:17], v[234:237], v[230:233], v[2:17]
	v_mfma_f32_32x32x16_f16 v[18:33], v[238:241], v[230:233], v[18:33]
	s_waitcnt lgkmcnt(0)
	s_barrier
; DI f16v mfma32(h8v a, h8v b, f16v c) { return __builtin_amdgcn_mfma_f32_32x32x16_f16(a, b, c, 0, 0, 0); }
; template <bool GATHER>
; DI void gemm256_main(const h16* __restrict__ A, int lda, const int* __restrict__ idx, int m0,
;                      const h16* __restrict__ B, int ldb, int n0, int K, h16* lds, f16v (&acc)[4][2]) {
;     ...
;   for (int kt = 0; kt < nk; ++kt) {
;     const h16* As = lds + (kt & 1) * (512 * LDH);
;     const h16* Bs = As + 256 * LDH;
;     h16* Wn = lds + ((kt & 1) ^ 1) * (512 * LDH);
;     if (kt + 1 < nk) {
; #pragma unroll
;       for (int i = 0; i < 4; ++i) { *(u4v*)&Wn[lr * LDH + lc + 8 * i] = ra[i]; *(u4v*)&Wn[(256 + lr) * LDH + lc + 8 * i] = rb[i]; }
;     }
;     if (kt + 2 < nk) {
; #pragma unroll
;       for (int i = 0; i < 4; ++i) { ra[i] = *(const u4v*)(AP_ + 8 * i); rb[i] = *(const u4v*)(BP_ + 8 * i); }
;       ao += 64; bo += 64;
;     }
; #pragma unroll
;     for (int ks = 0; ks < 4; ++ks) {
;       h8v af[4], bf[2];
; #pragma unroll
;       for (int i = 0; i < 4; ++i) af[i] = *(const h8v*)&As[(wm * 128 + i * 32 + (lane & 31)) * LDH + ks * 16 + 8 * (lane >> 5)];
; #pragma unroll
;       for (int j = 0; j < 2; ++j) bf[j] = *(const h8v*)&Bs[(wn * 64 + j * 32 + (lane & 31)) * LDH + ks * 16 + 8 * (lane >> 5)];
; #pragma unroll
;       for (int i = 0; i < 4; ++i)
; #pragma unroll
;         for (int j = 0; j < 2; ++j) acc[i][j] = mfma32(bf[j], af[i], acc[i][j]);
;     }
;     __syncthreads();
;   }
	ds_read_b128 v[234:237], v214
	ds_read_b128 v[218:221], v212
	ds_read_b128 v[238:241], v214 offset:4608
	ds_read_b128 v[222:225], v212 offset:4608
	ds_read_b128 v[226:229], v212 offset:9216
	ds_read_b128 v[230:233], v212 offset:13824
	v_mfma_f32_32x32x16_f16 v[98:113], v[188:191], v[242:245], v[98:113]
	v_mfma_f32_32x32x16_f16 v[114:129], v[174:177], v[242:245], v[114:129]
	v_mfma_f32_32x32x16_f16 v[66:81], v[188:191], v[246:249], v[66:81]
	v_mfma_f32_32x32x16_f16 v[82:97], v[174:177], v[246:249], v[82:97]
	v_mfma_f32_32x32x16_f16 v[34:49], v[188:191], v[204:207], v[34:49]
	v_mfma_f32_32x32x16_f16 v[50:65], v[174:177], v[204:207], v[50:65]
	v_mfma_f32_32x32x16_f16 v[2:17], v[188:191], v[208:211], v[2:17]
	v_mfma_f32_32x32x16_f16 v[18:33], v[174:177], v[208:211], v[18:33]
	ds_read_b128 v[188:191], v214 offset:32
	ds_read_b128 v[242:245], v212 offset:32
	ds_read_b128 v[174:177], v214 offset:4640
	ds_read_b128 v[246:249], v212 offset:4640
	ds_read_b128 v[204:207], v212 offset:9248
	ds_read_b128 v[208:211], v212 offset:13856
	s_waitcnt vmcnt(4)
	ds_write_b128 v132, v[134:137]
	ds_write_b128 v132, v[138:141] offset:16
	ds_write_b128 v132, v[142:145] offset:32
	ds_write_b128 v132, v[146:149] offset:48
	global_load_dwordx4 v[134:137], v[130:131], off offset:1152
	global_load_dwordx4 v[138:141], v[130:131], off offset:1168
	global_load_dwordx4 v[142:145], v[130:131], off offset:1184
	global_load_dwordx4 v[146:149], v[130:131], off offset:1200
	s_waitcnt lgkmcnt(14)
	v_mfma_f32_32x32x16_f16 v[98:113], v[234:237], v[218:221], v[98:113]
	s_waitcnt lgkmcnt(13)
	v_mfma_f32_32x32x16_f16 v[114:129], v[238:241], v[218:221], v[114:129]
	s_waitcnt lgkmcnt(12)
	v_mfma_f32_32x32x16_f16 v[66:81], v[234:237], v[222:225], v[66:81]
	v_mfma_f32_32x32x16_f16 v[82:97], v[238:241], v[222:225], v[82:97]
	s_waitcnt lgkmcnt(11)
	v_mfma_f32_32x32x16_f16 v[34:49], v[234:237], v[226:229], v[34:49]
	v_mfma_f32_32x32x16_f16 v[50:65], v[238:241], v[226:229], v[50:65]
	s_waitcnt lgkmcnt(10)
	v_mfma_f32_32x32x16_f16 v[2:17], v[234:237], v[230:233], v[2:17]
	v_mfma_f32_32x32x16_f16 v[18:33], v[238:241], v[230:233], v[18:33]
	ds_read_b128 v[234:237], v214 offset:64
	ds_read_b128 v[218:221], v212 offset:64
	ds_read_b128 v[238:241], v214 offset:4672
	ds_read_b128 v[222:225], v212 offset:4672
	ds_read_b128 v[226:229], v212 offset:9280
	ds_read_b128 v[230:233], v212 offset:13888
	s_waitcnt vmcnt(4)
	ds_write_b128 v132, v[150:153] offset:36864
	ds_write_b128 v132, v[154:157] offset:36880
	ds_write_b128 v132, v[158:161] offset:36896
	ds_write_b128 v132, v[162:165] offset:36912
	global_load_dwordx4 v[150:153], v[200:201], off offset:1152
	global_load_dwordx4 v[154:157], v[200:201], off offset:1168
	global_load_dwordx4 v[158:161], v[200:201], off offset:1184
	global_load_dwordx4 v[162:165], v[200:201], off offset:1200
	s_waitcnt lgkmcnt(15)
	v_mfma_f32_32x32x16_f16 v[98:113], v[188:191], v[242:245], v[98:113]
	s_waitcnt lgkmcnt(15)
	v_mfma_f32_32x32x16_f16 v[114:129], v[174:177], v[242:245], v[114:129]
	s_waitcnt lgkmcnt(15)
	v_mfma_f32_32x32x16_f16 v[66:81], v[188:191], v[246:249], v[66:81]
	v_mfma_f32_32x32x16_f16 v[82:97], v[174:177], v[246:249], v[82:97]
	s_waitcnt lgkmcnt(15)
	v_mfma_f32_32x32x16_f16 v[34:49], v[188:191], v[204:207], v[34:49]
	v_mfma_f32_32x32x16_f16 v[50:65], v[174:177], v[204:207], v[50:65]
	s_waitcnt lgkmcnt(14)
	v_mfma_f32_32x32x16_f16 v[2:17], v[188:191], v[208:211], v[2:17]
	v_mfma_f32_32x32x16_f16 v[18:33], v[174:177], v[208:211], v[18:33]
	ds_read_b128 v[188:191], v214 offset:96
	ds_read_b128 v[242:245], v212 offset:96
	ds_read_b128 v[174:177], v214 offset:4704
	ds_read_b128 v[246:249], v212 offset:4704
	ds_read_b128 v[204:207], v212 offset:9312
	ds_read_b128 v[208:211], v212 offset:13920
	s_waitcnt lgkmcnt(14)
	v_mfma_f32_32x32x16_f16 v[98:113], v[234:237], v[218:221], v[98:113]
	s_waitcnt lgkmcnt(13)
	v_mfma_f32_32x32x16_f16 v[114:129], v[238:241], v[218:221], v[114:129]
	s_waitcnt lgkmcnt(12)
	v_mfma_f32_32x32x16_f16 v[66:81], v[234:237], v[222:225], v[66:81]
	v_mfma_f32_32x32x16_f16 v[82:97], v[238:241], v[222:225], v[82:97]
	s_waitcnt lgkmcnt(11)
	v_mfma_f32_32x32x16_f16 v[34:49], v[234:237], v[226:229], v[34:49]
	v_mfma_f32_32x32x16_f16 v[50:65], v[238:241], v[226:229], v[50:65]
	s_waitcnt lgkmcnt(10)
	v_mfma_f32_32x32x16_f16 v[2:17], v[234:237], v[230:233], v[2:17]
	v_mfma_f32_32x32x16_f16 v[18:33], v[238:241], v[230:233], v[18:33]
	s_waitcnt lgkmcnt(0)
	s_barrier
; DI f16v mfma32(h8v a, h8v b, f16v c) { return __builtin_amdgcn_mfma_f32_32x32x16_f16(a, b, c, 0, 0, 0); }
; template <bool GATHER>
; DI void gemm256_main(const h16* __restrict__ A, int lda, const int* __restrict__ idx, int m0,
;                      const h16* __restrict__ B, int ldb, int n0, int K, h16* lds, f16v (&acc)[4][2]) {
;     ...
;   for (int kt = 0; kt < nk; ++kt) {
;     const h16* As = lds + (kt & 1) * (512 * LDH);
;     const h16* Bs = As + 256 * LDH;
;     h16* Wn = lds + ((kt & 1) ^ 1) * (512 * LDH);
;     if (kt + 1 < nk) {
; #pragma unroll
;       for (int i = 0; i < 4; ++i) { *(u4v*)&Wn[lr * LDH + lc + 8 * i] = ra[i]; *(u4v*)&Wn[(256 + lr) * LDH + lc + 8 * i] = rb[i]; }
;     }
;     if (kt + 2 < nk) {
; #pragma unroll
;       for (int i = 0; i < 4; ++i) { ra[i] = *(const u4v*)(AP_ + 8 * i); rb[i] = *(const u4v*)(BP_ + 8 * i); }
;       ao += 64; bo += 64;
;     }
; #pragma unroll
;     for (int ks = 0; ks < 4; ++ks) {
;       h8v af[4], bf[2];
; #pragma unroll
;       for (int i = 0; i < 4; ++i) af[i] = *(const h8v*)&As[(wm * 128 + i * 32 + (lane & 31)) * LDH + ks * 16 + 8 * (lane >> 5)];
; #pragma unroll
;       for (int j = 0; j < 2; ++j) bf[j] = *(const h8v*)&Bs[(wn * 64 + j * 32 + (lane & 31)) * LDH + ks * 16 + 8 * (lane >> 5)];
; #pragma unroll
;       for (int i = 0; i < 4; ++i)
; #pragma unroll
;         for (int j = 0; j < 2; ++j) acc[i][j] = mfma32(bf[j], af[i], acc[i][j]);
;     }
;     __syncthreads();
;   }
	ds_read_b128 v[234:237], v213
	ds_read_b128 v[218:221], v217
	ds_read_b128 v[238:241], v213 offset:4608
	ds_read_b128 v[222:225], v217 offset:4608
	ds_read_b128 v[226:229], v217 offset:9216
	ds_read_b128 v[230:233], v217 offset:13824
	v_mfma_f32_32x32x16_f16 v[98:113], v[188:191], v[242:245], v[98:113]
	v_mfma_f32_32x32x16_f16 v[114:129], v[174:177], v[242:245], v[114:129]
	v_mfma_f32_32x32x16_f16 v[66:81], v[188:191], v[246:249], v[66:81]
	v_mfma_f32_32x32x16_f16 v[82:97], v[174:177], v[246:249], v[82:97]
	v_mfma_f32_32x32x16_f16 v[34:49], v[188:191], v[204:207], v[34:49]
	v_mfma_f32_32x32x16_f16 v[50:65], v[174:177], v[204:207], v[50:65]
	v_mfma_f32_32x32x16_f16 v[2:17], v[188:191], v[208:211], v[2:17]
	v_mfma_f32_32x32x16_f16 v[18:33], v[174:177], v[208:211], v[18:33]
	ds_read_b128 v[188:191], v213 offset:32
	ds_read_b128 v[242:245], v217 offset:32
	ds_read_b128 v[174:177], v213 offset:4640
	ds_read_b128 v[246:249], v217 offset:4640
	ds_read_b128 v[204:207], v217 offset:9248
	ds_read_b128 v[208:211], v217 offset:13856
	s_waitcnt vmcnt(4)
	ds_write_b128 v133, v[134:137]
	ds_write_b128 v133, v[138:141] offset:16
	ds_write_b128 v133, v[142:145] offset:32
	ds_write_b128 v133, v[146:149] offset:48
	global_load_dwordx4 v[134:137], v[130:131], off offset:1280
	global_load_dwordx4 v[138:141], v[130:131], off offset:1296
	global_load_dwordx4 v[142:145], v[130:131], off offset:1312
	global_load_dwordx4 v[146:149], v[130:131], off offset:1328
	s_waitcnt lgkmcnt(14)
	v_mfma_f32_32x32x16_f16 v[98:113], v[234:237], v[218:221], v[98:113]
	s_waitcnt lgkmcnt(13)
	v_mfma_f32_32x32x16_f16 v[114:129], v[238:241], v[218:221], v[114:129]
	s_waitcnt lgkmcnt(12)
	v_mfma_f32_32x32x16_f16 v[66:81], v[234:237], v[222:225], v[66:81]
	v_mfma_f32_32x32x16_f16 v[82:97], v[238:241], v[222:225], v[82:97]
	s_waitcnt lgkmcnt(11)
	v_mfma_f32_32x32x16_f16 v[34:49], v[234:237], v[226:229], v[34:49]
	v_mfma_f32_32x32x16_f16 v[50:65], v[238:241], v[226:229], v[50:65]
	s_waitcnt lgkmcnt(10)
	v_mfma_f32_32x32x16_f16 v[2:17], v[234:237], v[230:233], v[2:17]
	v_mfma_f32_32x32x16_f16 v[18:33], v[238:241], v[230:233], v[18:33]
	ds_read_b128 v[234:237], v213 offset:64
	ds_read_b128 v[218:221], v217 offset:64
	ds_read_b128 v[238:241], v213 offset:4672
	ds_read_b128 v[222:225], v217 offset:4672
	ds_read_b128 v[226:229], v217 offset:9280
	ds_read_b128 v[230:233], v217 offset:13888
	s_waitcnt vmcnt(4)
	ds_write_b128 v133, v[150:153] offset:36864
	ds_write_b128 v133, v[154:157] offset:36880
	ds_write_b128 v133, v[158:161] offset:36896
	ds_write_b128 v133, v[162:165] offset:36912
	global_load_dwordx4 v[150:153], v[200:201], off offset:1280
	global_load_dwordx4 v[154:157], v[200:201], off offset:1296
	global_load_dwordx4 v[158:161], v[200:201], off offset:1312
	global_load_dwordx4 v[162:165], v[200:201], off offset:1328
	s_waitcnt lgkmcnt(15)
	v_mfma_f32_32x32x16_f16 v[98:113], v[188:191], v[242:245], v[98:113]
	s_waitcnt lgkmcnt(15)
	v_mfma_f32_32x32x16_f16 v[114:129], v[174:177], v[242:245], v[114:129]
	s_waitcnt lgkmcnt(15)
	v_mfma_f32_32x32x16_f16 v[66:81], v[188:191], v[246:249], v[66:81]
	v_mfma_f32_32x32x16_f16 v[82:97], v[174:177], v[246:249], v[82:97]
	s_waitcnt lgkmcnt(15)
	v_mfma_f32_32x32x16_f16 v[34:49], v[188:191], v[204:207], v[34:49]
	v_mfma_f32_32x32x16_f16 v[50:65], v[174:177], v[204:207], v[50:65]
	s_waitcnt lgkmcnt(14)
	v_mfma_f32_32x32x16_f16 v[2:17], v[188:191], v[208:211], v[2:17]
	v_mfma_f32_32x32x16_f16 v[18:33], v[174:177], v[208:211], v[18:33]
	ds_read_b128 v[188:191], v213 offset:96
	ds_read_b128 v[242:245], v217 offset:96
	ds_read_b128 v[174:177], v213 offset:4704
	ds_read_b128 v[246:249], v217 offset:4704
	ds_read_b128 v[204:207], v217 offset:9312
	ds_read_b128 v[208:211], v217 offset:13920
	s_waitcnt lgkmcnt(14)
	v_mfma_f32_32x32x16_f16 v[98:113], v[234:237], v[218:221], v[98:113]
	s_waitcnt lgkmcnt(13)
	v_mfma_f32_32x32x16_f16 v[114:129], v[238:241], v[218:221], v[114:129]
	s_waitcnt lgkmcnt(12)
	v_mfma_f32_32x32x16_f16 v[66:81], v[234:237], v[222:225], v[66:81]
	v_mfma_f32_32x32x16_f16 v[82:97], v[238:241], v[222:225], v[82:97]
	s_waitcnt lgkmcnt(11)
	v_mfma_f32_32x32x16_f16 v[34:49], v[234:237], v[226:229], v[34:49]
	v_mfma_f32_32x32x16_f16 v[50:65], v[238:241], v[226:229], v[50:65]
	s_waitcnt lgkmcnt(10)
	v_mfma_f32_32x32x16_f16 v[2:17], v[234:237], v[230:233], v[2:17]
	v_mfma_f32_32x32x16_f16 v[18:33], v[238:241], v[230:233], v[18:33]
	s_waitcnt lgkmcnt(0)
	s_barrier
; DI f16v mfma32(h8v a, h8v b, f16v c) { return __builtin_amdgcn_mfma_f32_32x32x16_f16(a, b, c, 0, 0, 0); }
; template <bool GATHER>
; DI void gemm256_main(const h16* __restrict__ A, int lda, const int* __restrict__ idx, int m0,
;                      const h16* __restrict__ B, int ldb, int n0, int K, h16* lds, f16v (&acc)[4][2]) {
;     ...
;   for (int kt = 0; kt < nk; ++kt) {
;     const h16* As = lds + (kt & 1) * (512 * LDH);
;     const h16* Bs = As + 256 * LDH;
;     h16* Wn = lds + ((kt & 1) ^ 1) * (512 * LDH);
;     if (kt + 1 < nk) {
; #pragma unroll
;       for (int i = 0; i < 4; ++i) { *(u4v*)&Wn[lr * LDH + lc + 8 * i] = ra[i]; *(u4v*)&Wn[(256 + lr) * LDH + lc + 8 * i] = rb[i]; }
;     }
;     if (kt + 2 < nk) {
; #pragma unroll
;       for (int i = 0; i < 4; ++i) { ra[i] = *(const u4v*)(AP_ + 8 * i); rb[i] = *(const u4v*)(BP_ + 8 * i); }
;       ao += 64; bo += 64;
;     }
; #pragma unroll
;     for (int ks = 0; ks < 4; ++ks) {
;       h8v af[4], bf[2];
; #pragma unroll
;       for (int i = 0; i < 4; ++i) af[i] = *(const h8v*)&As[(wm * 128 + i * 32 + (lane & 31)) * LDH + ks * 16 + 8 * (lane >> 5)];
; #pragma unroll
;       for (int j = 0; j < 2; ++j) bf[j] = *(const h8v*)&Bs[(wn * 64 + j * 32 + (lane & 31)) * LDH + ks * 16 + 8 * (lane >> 5)];
; #pragma unroll
;       for (int i = 0; i < 4; ++i)
; #pragma unroll
;         for (int j = 0; j < 2; ++j) acc[i][j] = mfma32(bf[j], af[i], acc[i][j]);
;     }
;     __syncthreads();
;   }
	ds_read_b128 v[234:237], v214
	ds_read_b128 v[218:221], v212
	ds_read_b128 v[238:241], v214 offset:4608
	ds_read_b128 v[222:225], v212 offset:4608
	ds_read_b128 v[226:229], v212 offset:9216
	ds_read_b128 v[230:233], v212 offset:13824
	v_mfma_f32_32x32x16_f16 v[98:113], v[188:191], v[242:245], v[98:113]
	v_mfma_f32_32x32x16_f16 v[114:129], v[174:177], v[242:245], v[114:129]
	v_mfma_f32_32x32x16_f16 v[66:81], v[188:191], v[246:249], v[66:81]
	v_mfma_f32_32x32x16_f16 v[82:97], v[174:177], v[246:249], v[82:97]
	v_mfma_f32_32x32x16_f16 v[34:49], v[188:191], v[204:207], v[34:49]
	v_mfma_f32_32x32x16_f16 v[50:65], v[174:177], v[204:207], v[50:65]
	v_mfma_f32_32x32x16_f16 v[2:17], v[188:191], v[208:211], v[2:17]
	v_mfma_f32_32x32x16_f16 v[18:33], v[174:177], v[208:211], v[18:33]
	ds_read_b128 v[188:191], v214 offset:32
	ds_read_b128 v[242:245], v212 offset:32
	ds_read_b128 v[174:177], v214 offset:4640
	ds_read_b128 v[246:249], v212 offset:4640
	ds_read_b128 v[204:207], v212 offset:9248
	ds_read_b128 v[208:211], v212 offset:13856
	s_waitcnt vmcnt(4)
	ds_write_b128 v132, v[134:137]
	ds_write_b128 v132, v[138:141] offset:16
	ds_write_b128 v132, v[142:145] offset:32
	ds_write_b128 v132, v[146:149] offset:48
	global_load_dwordx4 v[134:137], v[130:131], off offset:1408
	global_load_dwordx4 v[138:141], v[130:131], off offset:1424
	global_load_dwordx4 v[142:145], v[130:131], off offset:1440
	global_load_dwordx4 v[146:149], v[130:131], off offset:1456
	s_waitcnt lgkmcnt(14)
	v_mfma_f32_32x32x16_f16 v[98:113], v[234:237], v[218:221], v[98:113]
	s_waitcnt lgkmcnt(13)
	v_mfma_f32_32x32x16_f16 v[114:129], v[238:241], v[218:221], v[114:129]
	s_waitcnt lgkmcnt(12)
	v_mfma_f32_32x32x16_f16 v[66:81], v[234:237], v[222:225], v[66:81]
	v_mfma_f32_32x32x16_f16 v[82:97], v[238:241], v[222:225], v[82:97]
	s_waitcnt lgkmcnt(11)
	v_mfma_f32_32x32x16_f16 v[34:49], v[234:237], v[226:229], v[34:49]
	v_mfma_f32_32x32x16_f16 v[50:65], v[238:241], v[226:229], v[50:65]
	s_waitcnt lgkmcnt(10)
	v_mfma_f32_32x32x16_f16 v[2:17], v[234:237], v[230:233], v[2:17]
	v_mfma_f32_32x32x16_f16 v[18:33], v[238:241], v[230:233], v[18:33]
	ds_read_b128 v[234:237], v214 offset:64
	ds_read_b128 v[218:221], v212 offset:64
	ds_read_b128 v[238:241], v214 offset:4672
	ds_read_b128 v[222:225], v212 offset:4672
	ds_read_b128 v[226:229], v212 offset:9280
	ds_read_b128 v[230:233], v212 offset:13888
	s_waitcnt vmcnt(4)
	ds_write_b128 v132, v[150:153] offset:36864
	ds_write_b128 v132, v[154:157] offset:36880
	ds_write_b128 v132, v[158:161] offset:36896
	ds_write_b128 v132, v[162:165] offset:36912
	global_load_dwordx4 v[150:153], v[200:201], off offset:1408
	global_load_dwordx4 v[154:157], v[200:201], off offset:1424
	global_load_dwordx4 v[158:161], v[200:201], off offset:1440
	global_load_dwordx4 v[162:165], v[200:201], off offset:1456
	s_waitcnt lgkmcnt(15)
	v_mfma_f32_32x32x16_f16 v[98:113], v[188:191], v[242:245], v[98:113]
	s_waitcnt lgkmcnt(15)
	v_mfma_f32_32x32x16_f16 v[114:129], v[174:177], v[242:245], v[114:129]
	s_waitcnt lgkmcnt(15)
	v_mfma_f32_32x32x16_f16 v[66:81], v[188:191], v[246:249], v[66:81]
	v_mfma_f32_32x32x16_f16 v[82:97], v[174:177], v[246:249], v[82:97]
	s_waitcnt lgkmcnt(15)
	v_mfma_f32_32x32x16_f16 v[34:49], v[188:191], v[204:207], v[34:49]
	v_mfma_f32_32x32x16_f16 v[50:65], v[174:177], v[204:207], v[50:65]
	s_waitcnt lgkmcnt(14)
	v_mfma_f32_32x32x16_f16 v[2:17], v[188:191], v[208:211], v[2:17]
	v_mfma_f32_32x32x16_f16 v[18:33], v[174:177], v[208:211], v[18:33]
	ds_read_b128 v[188:191], v214 offset:96
	ds_read_b128 v[242:245], v212 offset:96
	ds_read_b128 v[174:177], v214 offset:4704
	ds_read_b128 v[246:249], v212 offset:4704
	ds_read_b128 v[204:207], v212 offset:9312
	ds_read_b128 v[208:211], v212 offset:13920
	s_waitcnt lgkmcnt(14)
	v_mfma_f32_32x32x16_f16 v[98:113], v[234:237], v[218:221], v[98:113]
	s_waitcnt lgkmcnt(13)
	v_mfma_f32_32x32x16_f16 v[114:129], v[238:241], v[218:221], v[114:129]
	s_waitcnt lgkmcnt(12)
	v_mfma_f32_32x32x16_f16 v[66:81], v[234:237], v[222:225], v[66:81]
	v_mfma_f32_32x32x16_f16 v[82:97], v[238:241], v[222:225], v[82:97]
	s_waitcnt lgkmcnt(11)
	v_mfma_f32_32x32x16_f16 v[34:49], v[234:237], v[226:229], v[34:49]
	v_mfma_f32_32x32x16_f16 v[50:65], v[238:241], v[226:229], v[50:65]
	s_waitcnt lgkmcnt(10)
	v_mfma_f32_32x32x16_f16 v[2:17], v[234:237], v[230:233], v[2:17]
	v_mfma_f32_32x32x16_f16 v[18:33], v[238:241], v[230:233], v[18:33]
	s_waitcnt lgkmcnt(0)
	s_barrier
; DI f16v mfma32(h8v a, h8v b, f16v c) { return __builtin_amdgcn_mfma_f32_32x32x16_f16(a, b, c, 0, 0, 0); }
; template <bool GATHER>
; DI void gemm256_main(const h16* __restrict__ A, int lda, const int* __restrict__ idx, int m0,
;                      const h16* __restrict__ B, int ldb, int n0, int K, h16* lds, f16v (&acc)[4][2]) {
;     ...
;   for (int kt = 0; kt < nk; ++kt) {
;     const h16* As = lds + (kt & 1) * (512 * LDH);
;     const h16* Bs = As + 256 * LDH;
;     h16* Wn = lds + ((kt & 1) ^ 1) * (512 * LDH);
;     if (kt + 1 < nk) {
; #pragma unroll
;       for (int i = 0; i < 4; ++i) { *(u4v*)&Wn[lr * LDH + lc + 8 * i] = ra[i]; *(u4v*)&Wn[(256 + lr) * LDH + lc + 8 * i] = rb[i]; }
;     }
;     if (kt + 2 < nk) {
; #pragma unroll
;       for (int i = 0; i < 4; ++i) { ra[i] = *(const u4v*)(AP_ + 8 * i); rb[i] = *(const u4v*)(BP_ + 8 * i); }
;       ao += 64; bo += 64;
;     }
; #pragma unroll
;     for (int ks = 0; ks < 4; ++ks) {
;       h8v af[4], bf[2];
; #pragma unroll
;       for (int i = 0; i < 4; ++i) af[i] = *(const h8v*)&As[(wm * 128 + i * 32 + (lane & 31)) * LDH + ks * 16 + 8 * (lane >> 5)];
; #pragma unroll
;       for (int j = 0; j < 2; ++j) bf[j] = *(const h8v*)&Bs[(wn * 64 + j * 32 + (lane & 31)) * LDH + ks * 16 + 8 * (lane >> 5)];
; #pragma unroll
;       for (int i = 0; i < 4; ++i)
; #pragma unroll
;         for (int j = 0; j < 2; ++j) acc[i][j] = mfma32(bf[j], af[i], acc[i][j]);
;     }
;     __syncthreads();
;   }
	ds_read_b128 v[234:237], v213
	ds_read_b128 v[218:221], v217
	ds_read_b128 v[238:241], v213 offset:4608
	ds_read_b128 v[222:225], v217 offset:4608
	ds_read_b128 v[226:229], v217 offset:9216
	ds_read_b128 v[230:233], v217 offset:13824
	v_mfma_f32_32x32x16_f16 v[98:113], v[188:191], v[242:245], v[98:113]
	v_mfma_f32_32x32x16_f16 v[114:129], v[174:177], v[242:245], v[114:129]
	v_mfma_f32_32x32x16_f16 v[66:81], v[188:191], v[246:249], v[66:81]
	v_mfma_f32_32x32x16_f16 v[82:97], v[174:177], v[246:249], v[82:97]
	v_mfma_f32_32x32x16_f16 v[34:49], v[188:191], v[204:207], v[34:49]
	v_mfma_f32_32x32x16_f16 v[50:65], v[174:177], v[204:207], v[50:65]
	v_mfma_f32_32x32x16_f16 v[2:17], v[188:191], v[208:211], v[2:17]
	v_mfma_f32_32x32x16_f16 v[18:33], v[174:177], v[208:211], v[18:33]
	ds_read_b128 v[188:191], v213 offset:32
	ds_read_b128 v[242:245], v217 offset:32
	ds_read_b128 v[174:177], v213 offset:4640
	ds_read_b128 v[246:249], v217 offset:4640
	ds_read_b128 v[204:207], v217 offset:9248
	ds_read_b128 v[208:211], v217 offset:13856
	s_waitcnt vmcnt(4)
	ds_write_b128 v133, v[134:137]
	ds_write_b128 v133, v[138:141] offset:16
	ds_write_b128 v133, v[142:145] offset:32
	ds_write_b128 v133, v[146:149] offset:48
	global_load_dwordx4 v[134:137], v[130:131], off offset:1536
	global_load_dwordx4 v[138:141], v[130:131], off offset:1552
	global_load_dwordx4 v[142:145], v[130:131], off offset:1568
	global_load_dwordx4 v[146:149], v[130:131], off offset:1584
	s_waitcnt lgkmcnt(14)
	v_mfma_f32_32x32x16_f16 v[98:113], v[234:237], v[218:221], v[98:113]
	s_waitcnt lgkmcnt(13)
	v_mfma_f32_32x32x16_f16 v[114:129], v[238:241], v[218:221], v[114:129]
	s_waitcnt lgkmcnt(12)
	v_mfma_f32_32x32x16_f16 v[66:81], v[234:237], v[222:225], v[66:81]
	v_mfma_f32_32x32x16_f16 v[82:97], v[238:241], v[222:225], v[82:97]
	s_waitcnt lgkmcnt(11)
	v_mfma_f32_32x32x16_f16 v[34:49], v[234:237], v[226:229], v[34:49]
	v_mfma_f32_32x32x16_f16 v[50:65], v[238:241], v[226:229], v[50:65]
	s_waitcnt lgkmcnt(10)
	v_mfma_f32_32x32x16_f16 v[2:17], v[234:237], v[230:233], v[2:17]
	v_mfma_f32_32x32x16_f16 v[18:33], v[238:241], v[230:233], v[18:33]
	ds_read_b128 v[234:237], v213 offset:64
	ds_read_b128 v[218:221], v217 offset:64
	ds_read_b128 v[238:241], v213 offset:4672
	ds_read_b128 v[222:225], v217 offset:4672
	ds_read_b128 v[226:229], v217 offset:9280
	ds_read_b128 v[230:233], v217 offset:13888
	s_waitcnt vmcnt(4)
	ds_write_b128 v133, v[150:153] offset:36864
	ds_write_b128 v133, v[154:157] offset:36880
	ds_write_b128 v133, v[158:161] offset:36896
	ds_write_b128 v133, v[162:165] offset:36912
	global_load_dwordx4 v[150:153], v[200:201], off offset:1536
	global_load_dwordx4 v[154:157], v[200:201], off offset:1552
	global_load_dwordx4 v[158:161], v[200:201], off offset:1568
	global_load_dwordx4 v[162:165], v[200:201], off offset:1584
	s_waitcnt lgkmcnt(15)
	v_mfma_f32_32x32x16_f16 v[98:113], v[188:191], v[242:245], v[98:113]
	s_waitcnt lgkmcnt(15)
	v_mfma_f32_32x32x16_f16 v[114:129], v[174:177], v[242:245], v[114:129]
	s_waitcnt lgkmcnt(15)
	v_mfma_f32_32x32x16_f16 v[66:81], v[188:191], v[246:249], v[66:81]
	v_mfma_f32_32x32x16_f16 v[82:97], v[174:177], v[246:249], v[82:97]
	s_waitcnt lgkmcnt(15)
	v_mfma_f32_32x32x16_f16 v[34:49], v[188:191], v[204:207], v[34:49]
	v_mfma_f32_32x32x16_f16 v[50:65], v[174:177], v[204:207], v[50:65]
	s_waitcnt lgkmcnt(14)
	v_mfma_f32_32x32x16_f16 v[2:17], v[188:191], v[208:211], v[2:17]
	v_mfma_f32_32x32x16_f16 v[18:33], v[174:177], v[208:211], v[18:33]
	ds_read_b128 v[188:191], v213 offset:96
	ds_read_b128 v[242:245], v217 offset:96
	ds_read_b128 v[174:177], v213 offset:4704
	ds_read_b128 v[246:249], v217 offset:4704
	ds_read_b128 v[204:207], v217 offset:9312
	ds_read_b128 v[208:211], v217 offset:13920
	s_waitcnt lgkmcnt(14)
	v_mfma_f32_32x32x16_f16 v[98:113], v[234:237], v[218:221], v[98:113]
	s_waitcnt lgkmcnt(13)
	v_mfma_f32_32x32x16_f16 v[114:129], v[238:241], v[218:221], v[114:129]
	s_waitcnt lgkmcnt(12)
	v_mfma_f32_32x32x16_f16 v[66:81], v[234:237], v[222:225], v[66:81]
	v_mfma_f32_32x32x16_f16 v[82:97], v[238:241], v[222:225], v[82:97]
	s_waitcnt lgkmcnt(11)
	v_mfma_f32_32x32x16_f16 v[34:49], v[234:237], v[226:229], v[34:49]
	v_mfma_f32_32x32x16_f16 v[50:65], v[238:241], v[226:229], v[50:65]
	s_waitcnt lgkmcnt(10)
	v_mfma_f32_32x32x16_f16 v[2:17], v[234:237], v[230:233], v[2:17]
	v_mfma_f32_32x32x16_f16 v[18:33], v[238:241], v[230:233], v[18:33]
	s_waitcnt lgkmcnt(0)
	s_barrier
; DI f16v mfma32(h8v a, h8v b, f16v c) { return __builtin_amdgcn_mfma_f32_32x32x16_f16(a, b, c, 0, 0, 0); }
; template <bool GATHER>
; DI void gemm256_main(const h16* __restrict__ A, int lda, const int* __restrict__ idx, int m0,
;                      const h16* __restrict__ B, int ldb, int n0, int K, h16* lds, f16v (&acc)[4][2]) {
;     ...
;   for (int kt = 0; kt < nk; ++kt) {
;     const h16* As = lds + (kt & 1) * (512 * LDH);
;     const h16* Bs = As + 256 * LDH;
;     h16* Wn = lds + ((kt & 1) ^ 1) * (512 * LDH);
;     if (kt + 1 < nk) {
; #pragma unroll
;       for (int i = 0; i < 4; ++i) { *(u4v*)&Wn[lr * LDH + lc + 8 * i] = ra[i]; *(u4v*)&Wn[(256 + lr) * LDH + lc + 8 * i] = rb[i]; }
;     }
;     if (kt + 2 < nk) {
; #pragma unroll
;       for (int i = 0; i < 4; ++i) { ra[i] = *(const u4v*)(AP_ + 8 * i); rb[i] = *(const u4v*)(BP_ + 8 * i); }
;       ao += 64; bo += 64;
;     }
; #pragma unroll
;     for (int ks = 0; ks < 4; ++ks) {
;       h8v af[4], bf[2];
; #pragma unroll
;       for (int i = 0; i < 4; ++i) af[i] = *(const h8v*)&As[(wm * 128 + i * 32 + (lane & 31)) * LDH + ks * 16 + 8 * (lane >> 5)];
; #pragma unroll
;       for (int j = 0; j < 2; ++j) bf[j] = *(const h8v*)&Bs[(wn * 64 + j * 32 + (lane & 31)) * LDH + ks * 16 + 8 * (lane >> 5)];
; #pragma unroll
;       for (int i = 0; i < 4; ++i)
; #pragma unroll
;         for (int j = 0; j < 2; ++j) acc[i][j] = mfma32(bf[j], af[i], acc[i][j]);
;     }
;     __syncthreads();
;   }
	ds_read_b128 v[234:237], v214
	ds_read_b128 v[218:221], v212
	ds_read_b128 v[238:241], v214 offset:4608
	ds_read_b128 v[222:225], v212 offset:4608
	ds_read_b128 v[226:229], v212 offset:9216
	ds_read_b128 v[230:233], v212 offset:13824
	v_mfma_f32_32x32x16_f16 v[98:113], v[188:191], v[242:245], v[98:113]
	v_mfma_f32_32x32x16_f16 v[114:129], v[174:177], v[242:245], v[114:129]
	v_mfma_f32_32x32x16_f16 v[66:81], v[188:191], v[246:249], v[66:81]
	v_mfma_f32_32x32x16_f16 v[82:97], v[174:177], v[246:249], v[82:97]
	v_mfma_f32_32x32x16_f16 v[34:49], v[188:191], v[204:207], v[34:49]
	v_mfma_f32_32x32x16_f16 v[50:65], v[174:177], v[204:207], v[50:65]
	v_mfma_f32_32x32x16_f16 v[2:17], v[188:191], v[208:211], v[2:17]
	v_mfma_f32_32x32x16_f16 v[18:33], v[174:177], v[208:211], v[18:33]
	ds_read_b128 v[188:191], v214 offset:32
	ds_read_b128 v[242:245], v212 offset:32
	ds_read_b128 v[174:177], v214 offset:4640
	ds_read_b128 v[246:249], v212 offset:4640
	ds_read_b128 v[204:207], v212 offset:9248
	ds_read_b128 v[208:211], v212 offset:13856
	s_waitcnt vmcnt(4)
	ds_write_b128 v132, v[134:137]
	ds_write_b128 v132, v[138:141] offset:16
	ds_write_b128 v132, v[142:145] offset:32
	ds_write_b128 v132, v[146:149] offset:48
	global_load_dwordx4 v[134:137], v[130:131], off offset:1664
	global_load_dwordx4 v[138:141], v[130:131], off offset:1680
	global_load_dwordx4 v[142:145], v[130:131], off offset:1696
	global_load_dwordx4 v[146:149], v[130:131], off offset:1712
	s_waitcnt lgkmcnt(14)
	v_mfma_f32_32x32x16_f16 v[98:113], v[234:237], v[218:221], v[98:113]
	s_waitcnt lgkmcnt(13)
	v_mfma_f32_32x32x16_f16 v[114:129], v[238:241], v[218:221], v[114:129]
	s_waitcnt lgkmcnt(12)
	v_mfma_f32_32x32x16_f16 v[66:81], v[234:237], v[222:225], v[66:81]
	v_mfma_f32_32x32x16_f16 v[82:97], v[238:241], v[222:225], v[82:97]
	s_waitcnt lgkmcnt(11)
	v_mfma_f32_32x32x16_f16 v[34:49], v[234:237], v[226:229], v[34:49]
	v_mfma_f32_32x32x16_f16 v[50:65], v[238:241], v[226:229], v[50:65]
	s_waitcnt lgkmcnt(10)
	v_mfma_f32_32x32x16_f16 v[2:17], v[234:237], v[230:233], v[2:17]
	v_mfma_f32_32x32x16_f16 v[18:33], v[238:241], v[230:233], v[18:33]
	ds_read_b128 v[234:237], v214 offset:64
	ds_read_b128 v[218:221], v212 offset:64
	ds_read_b128 v[238:241], v214 offset:4672
	ds_read_b128 v[222:225], v212 offset:4672
	ds_read_b128 v[226:229], v212 offset:9280
	ds_read_b128 v[230:233], v212 offset:13888
	s_waitcnt vmcnt(4)
	ds_write_b128 v132, v[150:153] offset:36864
	ds_write_b128 v132, v[154:157] offset:36880
	ds_write_b128 v132, v[158:161] offset:36896
	ds_write_b128 v132, v[162:165] offset:36912
	global_load_dwordx4 v[150:153], v[200:201], off offset:1664
	global_load_dwordx4 v[154:157], v[200:201], off offset:1680
	global_load_dwordx4 v[158:161], v[200:201], off offset:1696
	global_load_dwordx4 v[162:165], v[200:201], off offset:1712
	s_waitcnt lgkmcnt(15)
	v_mfma_f32_32x32x16_f16 v[98:113], v[188:191], v[242:245], v[98:113]
	s_waitcnt lgkmcnt(15)
	v_mfma_f32_32x32x16_f16 v[114:129], v[174:177], v[242:245], v[114:129]
	s_waitcnt lgkmcnt(15)
	v_mfma_f32_32x32x16_f16 v[66:81], v[188:191], v[246:249], v[66:81]
	v_mfma_f32_32x32x16_f16 v[82:97], v[174:177], v[246:249], v[82:97]
	s_waitcnt lgkmcnt(15)
	v_mfma_f32_32x32x16_f16 v[34:49], v[188:191], v[204:207], v[34:49]
	v_mfma_f32_32x32x16_f16 v[50:65], v[174:177], v[204:207], v[50:65]
	s_waitcnt lgkmcnt(14)
	v_mfma_f32_32x32x16_f16 v[2:17], v[188:191], v[208:211], v[2:17]
	v_mfma_f32_32x32x16_f16 v[18:33], v[174:177], v[208:211], v[18:33]
	ds_read_b128 v[188:191], v214 offset:96
	ds_read_b128 v[242:245], v212 offset:96
	ds_read_b128 v[174:177], v214 offset:4704
	ds_read_b128 v[246:249], v212 offset:4704
	ds_read_b128 v[204:207], v212 offset:9312
	ds_read_b128 v[208:211], v212 offset:13920
	s_waitcnt lgkmcnt(14)
	v_mfma_f32_32x32x16_f16 v[98:113], v[234:237], v[218:221], v[98:113]
	s_waitcnt lgkmcnt(13)
	v_mfma_f32_32x32x16_f16 v[114:129], v[238:241], v[218:221], v[114:129]
	s_waitcnt lgkmcnt(12)
	v_mfma_f32_32x32x16_f16 v[66:81], v[234:237], v[222:225], v[66:81]
	v_mfma_f32_32x32x16_f16 v[82:97], v[238:241], v[222:225], v[82:97]
	s_waitcnt lgkmcnt(11)
	v_mfma_f32_32x32x16_f16 v[34:49], v[234:237], v[226:229], v[34:49]
	v_mfma_f32_32x32x16_f16 v[50:65], v[238:241], v[226:229], v[50:65]
	s_waitcnt lgkmcnt(10)
	v_mfma_f32_32x32x16_f16 v[2:17], v[234:237], v[230:233], v[2:17]
	v_mfma_f32_32x32x16_f16 v[18:33], v[238:241], v[230:233], v[18:33]
	s_waitcnt lgkmcnt(0)
	s_barrier
; DI f16v mfma32(h8v a, h8v b, f16v c) { return __builtin_amdgcn_mfma_f32_32x32x16_f16(a, b, c, 0, 0, 0); }
; template <bool GATHER>
; DI void gemm256_main(const h16* __restrict__ A, int lda, const int* __restrict__ idx, int m0,
;                      const h16* __restrict__ B, int ldb, int n0, int K, h16* lds, f16v (&acc)[4][2]) {
;     ...
;   for (int kt = 0; kt < nk; ++kt) {
;     const h16* As = lds + (kt & 1) * (512 * LDH);
;     const h16* Bs = As + 256 * LDH;
;     h16* Wn = lds + ((kt & 1) ^ 1) * (512 * LDH);
;     if (kt + 1 < nk) {
; #pragma unroll
;       for (int i = 0; i < 4; ++i) { *(u4v*)&Wn[lr * LDH + lc + 8 * i] = ra[i]; *(u4v*)&Wn[(256 + lr) * LDH + lc + 8 * i] = rb[i]; }
;     }
;     if (kt + 2 < nk) {
; #pragma unroll
;       for (int i = 0; i < 4; ++i) { ra[i] = *(const u4v*)(AP_ + 8 * i); rb[i] = *(const u4v*)(BP_ + 8 * i); }
;       ao += 64; bo += 64;
;     }
; #pragma unroll
;     for (int ks = 0; ks < 4; ++ks) {
;       h8v af[4], bf[2];
; #pragma unroll
;       for (int i = 0; i < 4; ++i) af[i] = *(const h8v*)&As[(wm * 128 + i * 32 + (lane & 31)) * LDH + ks * 16 + 8 * (lane >> 5)];
; #pragma unroll
;       for (int j = 0; j < 2; ++j) bf[j] = *(const h8v*)&Bs[(wn * 64 + j * 32 + (lane & 31)) * LDH + ks * 16 + 8 * (lane >> 5)];
; #pragma unroll
;       for (int i = 0; i < 4; ++i)
; #pragma unroll
;         for (int j = 0; j < 2; ++j) acc[i][j] = mfma32(bf[j], af[i], acc[i][j]);
;     }
;     __syncthreads();
;   }
	ds_read_b128 v[234:237], v213
	ds_read_b128 v[218:221], v217
	ds_read_b128 v[238:241], v213 offset:4608
	ds_read_b128 v[222:225], v217 offset:4608
	ds_read_b128 v[226:229], v217 offset:9216
	ds_read_b128 v[230:233], v217 offset:13824
	v_mfma_f32_32x32x16_f16 v[98:113], v[188:191], v[242:245], v[98:113]
	v_mfma_f32_32x32x16_f16 v[114:129], v[174:177], v[242:245], v[114:129]
	v_mfma_f32_32x32x16_f16 v[66:81], v[188:191], v[246:249], v[66:81]
	v_mfma_f32_32x32x16_f16 v[82:97], v[174:177], v[246:249], v[82:97]
	v_mfma_f32_32x32x16_f16 v[34:49], v[188:191], v[204:207], v[34:49]
	v_mfma_f32_32x32x16_f16 v[50:65], v[174:177], v[204:207], v[50:65]
	v_mfma_f32_32x32x16_f16 v[2:17], v[188:191], v[208:211], v[2:17]
	v_mfma_f32_32x32x16_f16 v[18:33], v[174:177], v[208:211], v[18:33]
	ds_read_b128 v[188:191], v213 offset:32
	ds_read_b128 v[242:245], v217 offset:32
	ds_read_b128 v[174:177], v213 offset:4640
	ds_read_b128 v[246:249], v217 offset:4640
	ds_read_b128 v[204:207], v217 offset:9248
	ds_read_b128 v[208:211], v217 offset:13856
	s_waitcnt vmcnt(4)
	ds_write_b128 v133, v[134:137]
	ds_write_b128 v133, v[138:141] offset:16
	ds_write_b128 v133, v[142:145] offset:32
	ds_write_b128 v133, v[146:149] offset:48
	global_load_dwordx4 v[134:137], v[130:131], off offset:1792
	global_load_dwordx4 v[138:141], v[130:131], off offset:1808
	global_load_dwordx4 v[142:145], v[130:131], off offset:1824
	global_load_dwordx4 v[146:149], v[130:131], off offset:1840
	s_waitcnt lgkmcnt(14)
	v_mfma_f32_32x32x16_f16 v[98:113], v[234:237], v[218:221], v[98:113]
	s_waitcnt lgkmcnt(13)
	v_mfma_f32_32x32x16_f16 v[114:129], v[238:241], v[218:221], v[114:129]
	s_waitcnt lgkmcnt(12)
	v_mfma_f32_32x32x16_f16 v[66:81], v[234:237], v[222:225], v[66:81]
	v_mfma_f32_32x32x16_f16 v[82:97], v[238:241], v[222:225], v[82:97]
	s_waitcnt lgkmcnt(11)
	v_mfma_f32_32x32x16_f16 v[34:49], v[234:237], v[226:229], v[34:49]
	v_mfma_f32_32x32x16_f16 v[50:65], v[238:241], v[226:229], v[50:65]
	s_waitcnt lgkmcnt(10)
	v_mfma_f32_32x32x16_f16 v[2:17], v[234:237], v[230:233], v[2:17]
	v_mfma_f32_32x32x16_f16 v[18:33], v[238:241], v[230:233], v[18:33]
	ds_read_b128 v[234:237], v213 offset:64
	ds_read_b128 v[218:221], v217 offset:64
	ds_read_b128 v[238:241], v213 offset:4672
	ds_read_b128 v[222:225], v217 offset:4672
	ds_read_b128 v[226:229], v217 offset:9280
	ds_read_b128 v[230:233], v217 offset:13888
	s_waitcnt vmcnt(4)
	ds_write_b128 v133, v[150:153] offset:36864
	ds_write_b128 v133, v[154:157] offset:36880
	ds_write_b128 v133, v[158:161] offset:36896
	ds_write_b128 v133, v[162:165] offset:36912
	global_load_dwordx4 v[150:153], v[200:201], off offset:1792
	global_load_dwordx4 v[154:157], v[200:201], off offset:1808
	global_load_dwordx4 v[158:161], v[200:201], off offset:1824
	global_load_dwordx4 v[162:165], v[200:201], off offset:1840
	s_waitcnt lgkmcnt(15)
	v_mfma_f32_32x32x16_f16 v[98:113], v[188:191], v[242:245], v[98:113]
	s_waitcnt lgkmcnt(15)
	v_mfma_f32_32x32x16_f16 v[114:129], v[174:177], v[242:245], v[114:129]
	s_waitcnt lgkmcnt(15)
	v_mfma_f32_32x32x16_f16 v[66:81], v[188:191], v[246:249], v[66:81]
	v_mfma_f32_32x32x16_f16 v[82:97], v[174:177], v[246:249], v[82:97]
	s_waitcnt lgkmcnt(15)
	v_mfma_f32_32x32x16_f16 v[34:49], v[188:191], v[204:207], v[34:49]
	v_mfma_f32_32x32x16_f16 v[50:65], v[174:177], v[204:207], v[50:65]
	s_waitcnt lgkmcnt(14)
	v_mfma_f32_32x32x16_f16 v[2:17], v[188:191], v[208:211], v[2:17]
	v_mfma_f32_32x32x16_f16 v[18:33], v[174:177], v[208:211], v[18:33]
	ds_read_b128 v[188:191], v213 offset:96
	ds_read_b128 v[242:245], v217 offset:96
	ds_read_b128 v[174:177], v213 offset:4704
	ds_read_b128 v[246:249], v217 offset:4704
	ds_read_b128 v[204:207], v217 offset:9312
	ds_read_b128 v[208:211], v217 offset:13920
	s_waitcnt lgkmcnt(14)
	v_mfma_f32_32x32x16_f16 v[98:113], v[234:237], v[218:221], v[98:113]
	s_waitcnt lgkmcnt(13)
	v_mfma_f32_32x32x16_f16 v[114:129], v[238:241], v[218:221], v[114:129]
	s_waitcnt lgkmcnt(12)
	v_mfma_f32_32x32x16_f16 v[66:81], v[234:237], v[222:225], v[66:81]
	v_mfma_f32_32x32x16_f16 v[82:97], v[238:241], v[222:225], v[82:97]
	s_waitcnt lgkmcnt(11)
	v_mfma_f32_32x32x16_f16 v[34:49], v[234:237], v[226:229], v[34:49]
	v_mfma_f32_32x32x16_f16 v[50:65], v[238:241], v[226:229], v[50:65]
	s_waitcnt lgkmcnt(10)
	v_mfma_f32_32x32x16_f16 v[2:17], v[234:237], v[230:233], v[2:17]
	v_mfma_f32_32x32x16_f16 v[18:33], v[238:241], v[230:233], v[18:33]
	s_waitcnt lgkmcnt(0)
	s_barrier
; DI f16v mfma32(h8v a, h8v b, f16v c) { return __builtin_amdgcn_mfma_f32_32x32x16_f16(a, b, c, 0, 0, 0); }
; template <bool GATHER>
; DI void gemm256_main(const h16* __restrict__ A, int lda, const int* __restrict__ idx, int m0,
;                      const h16* __restrict__ B, int ldb, int n0, int K, h16* lds, f16v (&acc)[4][2]) {
;     ...
;   for (int kt = 0; kt < nk; ++kt) {
;     const h16* As = lds + (kt & 1) * (512 * LDH);
;     const h16* Bs = As + 256 * LDH;
;     h16* Wn = lds + ((kt & 1) ^ 1) * (512 * LDH);
;     if (kt + 1 < nk) {
; #pragma unroll
;       for (int i = 0; i < 4; ++i) { *(u4v*)&Wn[lr * LDH + lc + 8 * i] = ra[i]; *(u4v*)&Wn[(256 + lr) * LDH + lc + 8 * i] = rb[i]; }
;     }
;     if (kt + 2 < nk) {
; #pragma unroll
;       for (int i = 0; i < 4; ++i) { ra[i] = *(const u4v*)(AP_ + 8 * i); rb[i] = *(const u4v*)(BP_ + 8 * i); }
;       ao += 64; bo += 64;
;     }
; #pragma unroll
;     for (int ks = 0; ks < 4; ++ks) {
;       h8v af[4], bf[2];
; #pragma unroll
;       for (int i = 0; i < 4; ++i) af[i] = *(const h8v*)&As[(wm * 128 + i * 32 + (lane & 31)) * LDH + ks * 16 + 8 * (lane >> 5)];
; #pragma unroll
;       for (int j = 0; j < 2; ++j) bf[j] = *(const h8v*)&Bs[(wn * 64 + j * 32 + (lane & 31)) * LDH + ks * 16 + 8 * (lane >> 5)];
; #pragma unroll
;       for (int i = 0; i < 4; ++i)
; #pragma unroll
;         for (int j = 0; j < 2; ++j) acc[i][j] = mfma32(bf[j], af[i], acc[i][j]);
;     }
;     __syncthreads();
;   }
	ds_read_b128 v[234:237], v214
	ds_read_b128 v[218:221], v212
	ds_read_b128 v[238:241], v214 offset:4608
	ds_read_b128 v[222:225], v212 offset:4608
	ds_read_b128 v[226:229], v212 offset:9216
	ds_read_b128 v[230:233], v212 offset:13824
	v_mfma_f32_32x32x16_f16 v[98:113], v[188:191], v[242:245], v[98:113]
	v_mfma_f32_32x32x16_f16 v[114:129], v[174:177], v[242:245], v[114:129]
	v_mfma_f32_32x32x16_f16 v[66:81], v[188:191], v[246:249], v[66:81]
	v_mfma_f32_32x32x16_f16 v[82:97], v[174:177], v[246:249], v[82:97]
	v_mfma_f32_32x32x16_f16 v[34:49], v[188:191], v[204:207], v[34:49]
	v_mfma_f32_32x32x16_f16 v[50:65], v[174:177], v[204:207], v[50:65]
	v_mfma_f32_32x32x16_f16 v[2:17], v[188:191], v[208:211], v[2:17]
	v_mfma_f32_32x32x16_f16 v[18:33], v[174:177], v[208:211], v[18:33]
	ds_read_b128 v[188:191], v214 offset:32
	ds_read_b128 v[242:245], v212 offset:32
	ds_read_b128 v[174:177], v214 offset:4640
	ds_read_b128 v[246:249], v212 offset:4640
	ds_read_b128 v[204:207], v212 offset:9248
	ds_read_b128 v[208:211], v212 offset:13856
	s_waitcnt vmcnt(4)
	ds_write_b128 v132, v[134:137]
	ds_write_b128 v132, v[138:141] offset:16
	ds_write_b128 v132, v[142:145] offset:32
	ds_write_b128 v132, v[146:149] offset:48
	global_load_dwordx4 v[134:137], v[130:131], off offset:1920
	global_load_dwordx4 v[138:141], v[130:131], off offset:1936
	global_load_dwordx4 v[142:145], v[130:131], off offset:1952
	global_load_dwordx4 v[146:149], v[130:131], off offset:1968
	s_waitcnt lgkmcnt(14)
	v_mfma_f32_32x32x16_f16 v[98:113], v[234:237], v[218:221], v[98:113]
	s_waitcnt lgkmcnt(13)
	v_mfma_f32_32x32x16_f16 v[114:129], v[238:241], v[218:221], v[114:129]
	s_waitcnt lgkmcnt(12)
	v_mfma_f32_32x32x16_f16 v[66:81], v[234:237], v[222:225], v[66:81]
	v_mfma_f32_32x32x16_f16 v[82:97], v[238:241], v[222:225], v[82:97]
	s_waitcnt lgkmcnt(11)
	v_mfma_f32_32x32x16_f16 v[34:49], v[234:237], v[226:229], v[34:49]
	v_mfma_f32_32x32x16_f16 v[50:65], v[238:241], v[226:229], v[50:65]
	s_waitcnt lgkmcnt(10)
	v_mfma_f32_32x32x16_f16 v[2:17], v[234:237], v[230:233], v[2:17]
	v_mfma_f32_32x32x16_f16 v[18:33], v[238:241], v[230:233], v[18:33]
	ds_read_b128 v[234:237], v214 offset:64
	ds_read_b128 v[218:221], v212 offset:64
	ds_read_b128 v[238:241], v214 offset:4672
	ds_read_b128 v[222:225], v212 offset:4672
	ds_read_b128 v[226:229], v212 offset:9280
	ds_read_b128 v[230:233], v212 offset:13888
	s_waitcnt vmcnt(4)
	ds_write_b128 v132, v[150:153] offset:36864
	ds_write_b128 v132, v[154:157] offset:36880
	ds_write_b128 v132, v[158:161] offset:36896
	ds_write_b128 v132, v[162:165] offset:36912
	global_load_dwordx4 v[150:153], v[200:201], off offset:1920
	global_load_dwordx4 v[154:157], v[200:201], off offset:1936
	global_load_dwordx4 v[158:161], v[200:201], off offset:1952
	global_load_dwordx4 v[162:165], v[200:201], off offset:1968
	s_waitcnt lgkmcnt(15)
	v_mfma_f32_32x32x16_f16 v[98:113], v[188:191], v[242:245], v[98:113]
	s_waitcnt lgkmcnt(15)
	v_mfma_f32_32x32x16_f16 v[114:129], v[174:177], v[242:245], v[114:129]
	s_waitcnt lgkmcnt(15)
	v_mfma_f32_32x32x16_f16 v[66:81], v[188:191], v[246:249], v[66:81]
	v_mfma_f32_32x32x16_f16 v[82:97], v[174:177], v[246:249], v[82:97]
	s_waitcnt lgkmcnt(15)
	v_mfma_f32_32x32x16_f16 v[34:49], v[188:191], v[204:207], v[34:49]
	v_mfma_f32_32x32x16_f16 v[50:65], v[174:177], v[204:207], v[50:65]
	s_waitcnt lgkmcnt(14)
	v_mfma_f32_32x32x16_f16 v[2:17], v[188:191], v[208:211], v[2:17]
	v_mfma_f32_32x32x16_f16 v[18:33], v[174:177], v[208:211], v[18:33]
	ds_read_b128 v[188:191], v214 offset:96
	ds_read_b128 v[242:245], v212 offset:96
	ds_read_b128 v[174:177], v214 offset:4704
	ds_read_b128 v[246:249], v212 offset:4704
	ds_read_b128 v[204:207], v212 offset:9312
	ds_read_b128 v[208:211], v212 offset:13920
	s_waitcnt lgkmcnt(14)
	v_mfma_f32_32x32x16_f16 v[98:113], v[234:237], v[218:221], v[98:113]
	s_waitcnt lgkmcnt(13)
	v_mfma_f32_32x32x16_f16 v[114:129], v[238:241], v[218:221], v[114:129]
	s_waitcnt lgkmcnt(12)
	v_mfma_f32_32x32x16_f16 v[66:81], v[234:237], v[222:225], v[66:81]
	v_mfma_f32_32x32x16_f16 v[82:97], v[238:241], v[222:225], v[82:97]
	s_waitcnt lgkmcnt(11)
	v_mfma_f32_32x32x16_f16 v[34:49], v[234:237], v[226:229], v[34:49]
	v_mfma_f32_32x32x16_f16 v[50:65], v[238:241], v[226:229], v[50:65]
	s_waitcnt lgkmcnt(10)
	v_mfma_f32_32x32x16_f16 v[2:17], v[234:237], v[230:233], v[2:17]
	v_mfma_f32_32x32x16_f16 v[18:33], v[238:241], v[230:233], v[18:33]
	s_waitcnt lgkmcnt(0)
	s_barrier
; DI f16v mfma32(h8v a, h8v b, f16v c) { return __builtin_amdgcn_mfma_f32_32x32x16_f16(a, b, c, 0, 0, 0); }
; template <bool GATHER>
; DI void gemm256_main(const h16* __restrict__ A, int lda, const int* __restrict__ idx, int m0,
;                      const h16* __restrict__ B, int ldb, int n0, int K, h16* lds, f16v (&acc)[4][2]) {
;     ...
;   for (int kt = 0; kt < nk; ++kt) {
;     const h16* As = lds + (kt & 1) * (512 * LDH);
;     const h16* Bs = As + 256 * LDH;
;     h16* Wn = lds + ((kt & 1) ^ 1) * (512 * LDH);
;     if (kt + 1 < nk) {
; #pragma unroll
;       for (int i = 0; i < 4; ++i) { *(u4v*)&Wn[lr * LDH + lc + 8 * i] = ra[i]; *(u4v*)&Wn[(256 + lr) * LDH + lc + 8 * i] = rb[i]; }
;     }
;     if (kt + 2 < nk) {
; #pragma unroll
;       for (int i = 0; i < 4; ++i) { ra[i] = *(const u4v*)(AP_ + 8 * i); rb[i] = *(const u4v*)(BP_ + 8 * i); }
;       ao += 64; bo += 64;
;     }
; #pragma unroll
;     for (int ks = 0; ks < 4; ++ks) {
;       h8v af[4], bf[2];
; #pragma unroll
;       for (int i = 0; i < 4; ++i) af[i] = *(const h8v*)&As[(wm * 128 + i * 32 + (lane & 31)) * LDH + ks * 16 + 8 * (lane >> 5)];
; #pragma unroll
;       for (int j = 0; j < 2; ++j) bf[j] = *(const h8v*)&Bs[(wn * 64 + j * 32 + (lane & 31)) * LDH + ks * 16 + 8 * (lane >> 5)];
; #pragma unroll
;       for (int i = 0; i < 4; ++i)
; #pragma unroll
;         for (int j = 0; j < 2; ++j) acc[i][j] = mfma32(bf[j], af[i], acc[i][j]);
;     }
;     __syncthreads();
;   }
	ds_read_b128 v[234:237], v213
	ds_read_b128 v[218:221], v217
	ds_read_b128 v[238:241], v213 offset:4608
	ds_read_b128 v[222:225], v217 offset:4608
	ds_read_b128 v[226:229], v217 offset:9216
	ds_read_b128 v[230:233], v217 offset:13824
	v_mfma_f32_32x32x16_f16 v[98:113], v[188:191], v[242:245], v[98:113]
	v_mfma_f32_32x32x16_f16 v[114:129], v[174:177], v[242:245], v[114:129]
	v_mfma_f32_32x32x16_f16 v[66:81], v[188:191], v[246:249], v[66:81]
	v_mfma_f32_32x32x16_f16 v[82:97], v[174:177], v[246:249], v[82:97]
	v_mfma_f32_32x32x16_f16 v[34:49], v[188:191], v[204:207], v[34:49]
	v_mfma_f32_32x32x16_f16 v[50:65], v[174:177], v[204:207], v[50:65]
	v_mfma_f32_32x32x16_f16 v[2:17], v[188:191], v[208:211], v[2:17]
	v_mfma_f32_32x32x16_f16 v[18:33], v[174:177], v[208:211], v[18:33]
	ds_read_b128 v[188:191], v213 offset:32
	ds_read_b128 v[242:245], v217 offset:32
	ds_read_b128 v[174:177], v213 offset:4640
	ds_read_b128 v[246:249], v217 offset:4640
	ds_read_b128 v[204:207], v217 offset:9248
	ds_read_b128 v[208:211], v217 offset:13856
	s_waitcnt vmcnt(4)
	ds_write_b128 v133, v[134:137]
	ds_write_b128 v133, v[138:141] offset:16
	ds_write_b128 v133, v[142:145] offset:32
	ds_write_b128 v133, v[146:149] offset:48
	s_waitcnt lgkmcnt(14)
	v_mfma_f32_32x32x16_f16 v[98:113], v[234:237], v[218:221], v[98:113]
	s_waitcnt lgkmcnt(13)
	v_mfma_f32_32x32x16_f16 v[114:129], v[238:241], v[218:221], v[114:129]
	s_waitcnt lgkmcnt(12)
	v_mfma_f32_32x32x16_f16 v[66:81], v[234:237], v[222:225], v[66:81]
	v_mfma_f32_32x32x16_f16 v[82:97], v[238:241], v[222:225], v[82:97]
	s_waitcnt lgkmcnt(11)
	v_mfma_f32_32x32x16_f16 v[34:49], v[234:237], v[226:229], v[34:49]
	v_mfma_f32_32x32x16_f16 v[50:65], v[238:241], v[226:229], v[50:65]
	s_waitcnt lgkmcnt(10)
	v_mfma_f32_32x32x16_f16 v[2:17], v[234:237], v[230:233], v[2:17]
	v_mfma_f32_32x32x16_f16 v[18:33], v[238:241], v[230:233], v[18:33]
	ds_read_b128 v[234:237], v213 offset:64
	ds_read_b128 v[218:221], v217 offset:64
	ds_read_b128 v[238:241], v213 offset:4672
	ds_read_b128 v[222:225], v217 offset:4672
	ds_read_b128 v[226:229], v217 offset:9280
	ds_read_b128 v[230:233], v217 offset:13888
	s_waitcnt vmcnt(0)
	ds_write_b128 v133, v[150:153] offset:36864
	ds_write_b128 v133, v[154:157] offset:36880
	ds_write_b128 v133, v[158:161] offset:36896
	ds_write_b128 v133, v[162:165] offset:36912
	s_waitcnt lgkmcnt(15)
	v_mfma_f32_32x32x16_f16 v[98:113], v[188:191], v[242:245], v[98:113]
	s_waitcnt lgkmcnt(15)
	v_mfma_f32_32x32x16_f16 v[114:129], v[174:177], v[242:245], v[114:129]
	s_waitcnt lgkmcnt(15)
	v_mfma_f32_32x32x16_f16 v[66:81], v[188:191], v[246:249], v[66:81]
	v_mfma_f32_32x32x16_f16 v[82:97], v[174:177], v[246:249], v[82:97]
	s_waitcnt lgkmcnt(15)
	v_mfma_f32_32x32x16_f16 v[34:49], v[188:191], v[204:207], v[34:49]
	v_mfma_f32_32x32x16_f16 v[50:65], v[174:177], v[204:207], v[50:65]
	s_waitcnt lgkmcnt(14)
	v_mfma_f32_32x32x16_f16 v[2:17], v[188:191], v[208:211], v[2:17]
	v_mfma_f32_32x32x16_f16 v[18:33], v[174:177], v[208:211], v[18:33]
	ds_read_b128 v[188:191], v213 offset:96
	ds_read_b128 v[242:245], v217 offset:96
	ds_read_b128 v[174:177], v213 offset:4704
	ds_read_b128 v[246:249], v217 offset:4704
	ds_read_b128 v[204:207], v217 offset:9312
	ds_read_b128 v[208:211], v217 offset:13920
	s_waitcnt lgkmcnt(14)
	v_mfma_f32_32x32x16_f16 v[98:113], v[234:237], v[218:221], v[98:113]
	s_waitcnt lgkmcnt(13)
	v_mfma_f32_32x32x16_f16 v[114:129], v[238:241], v[218:221], v[114:129]
	s_waitcnt lgkmcnt(12)
	v_mfma_f32_32x32x16_f16 v[66:81], v[234:237], v[222:225], v[66:81]
	v_mfma_f32_32x32x16_f16 v[82:97], v[238:241], v[222:225], v[82:97]
	s_waitcnt lgkmcnt(11)
	v_mfma_f32_32x32x16_f16 v[34:49], v[234:237], v[226:229], v[34:49]
	v_mfma_f32_32x32x16_f16 v[50:65], v[238:241], v[226:229], v[50:65]
	s_waitcnt lgkmcnt(10)
	v_mfma_f32_32x32x16_f16 v[2:17], v[234:237], v[230:233], v[2:17]
	v_mfma_f32_32x32x16_f16 v[18:33], v[238:241], v[230:233], v[18:33]
	s_waitcnt lgkmcnt(0)
	s_barrier
	ds_read_b128 v[234:237], v214
	ds_read_b128 v[218:221], v212
	ds_read_b128 v[238:241], v214 offset:4608
	ds_read_b128 v[222:225], v212 offset:4608
	ds_read_b128 v[226:229], v212 offset:9216
	ds_read_b128 v[230:233], v212 offset:13824
	v_mfma_f32_32x32x16_f16 v[98:113], v[188:191], v[242:245], v[98:113]
	v_mfma_f32_32x32x16_f16 v[114:129], v[174:177], v[242:245], v[114:129]
	v_mfma_f32_32x32x16_f16 v[66:81], v[188:191], v[246:249], v[66:81]
	v_mfma_f32_32x32x16_f16 v[82:97], v[174:177], v[246:249], v[82:97]
	v_mfma_f32_32x32x16_f16 v[34:49], v[188:191], v[204:207], v[34:49]
	v_mfma_f32_32x32x16_f16 v[50:65], v[174:177], v[204:207], v[50:65]
	v_mfma_f32_32x32x16_f16 v[2:17], v[188:191], v[208:211], v[2:17]
	v_mfma_f32_32x32x16_f16 v[18:33], v[174:177], v[208:211], v[18:33]
	ds_read_b128 v[188:191], v214 offset:32
	ds_read_b128 v[242:245], v212 offset:32
	ds_read_b128 v[174:177], v214 offset:4640
	ds_read_b128 v[246:249], v212 offset:4640
	ds_read_b128 v[204:207], v212 offset:9248
	ds_read_b128 v[208:211], v212 offset:13856
	s_waitcnt lgkmcnt(10)
	v_mfma_f32_32x32x16_f16 v[98:113], v[234:237], v[218:221], v[98:113]
	s_waitcnt lgkmcnt(9)
	v_mfma_f32_32x32x16_f16 v[114:129], v[238:241], v[218:221], v[114:129]
	s_waitcnt lgkmcnt(8)
	v_mfma_f32_32x32x16_f16 v[66:81], v[234:237], v[222:225], v[66:81]
	v_mfma_f32_32x32x16_f16 v[82:97], v[238:241], v[222:225], v[82:97]
	s_waitcnt lgkmcnt(7)
	v_mfma_f32_32x32x16_f16 v[34:49], v[234:237], v[226:229], v[34:49]
	v_mfma_f32_32x32x16_f16 v[50:65], v[238:241], v[226:229], v[50:65]
	s_waitcnt lgkmcnt(6)
; DI float silu_(float x) { return x / (1.f + __expf(-x)); }
; DI f16v mfma32(h8v a, h8v b, f16v c) { return __builtin_amdgcn_mfma_f32_32x32x16_f16(a, b, c, 0, 0, 0); }
; template <bool GATHER>
; DI void gemm256_main(const h16* __restrict__ A, int lda, const int* __restrict__ idx, int m0,
;                      const h16* __restrict__ B, int ldb, int n0, int K, h16* lds, f16v (&acc)[4][2]) {
;     ...
; #pragma unroll
;     for (int ks = 0; ks < 4; ++ks) {
;       h8v af[4], bf[2];
; #pragma unroll
;       for (int i = 0; i < 4; ++i) af[i] = *(const h8v*)&As[(wm * 128 + i * 32 + (lane & 31)) * LDH + ks * 16 + 8 * (lane >> 5)];
; #pragma unroll
;       for (int j = 0; j < 2; ++j) bf[j] = *(const h8v*)&Bs[(wn * 64 + j * 32 + (lane & 31)) * LDH + ks * 16 + 8 * (lane >> 5)];
; #pragma unroll
;       for (int i = 0; i < 4; ++i)
; #pragma unroll
;         for (int j = 0; j < 2; ++j) acc[i][j] = mfma32(bf[j], af[i], acc[i][j]);
; DI void phase_ffn1_moe(const Params& p, int bid, int nb, h16* lds) {
;     ...
;     gemm256_epilogue(acc, m0, n0, [&](int m, int n, f4v v0, f4v v1) {
;       f4v hq;
; #pragma unroll
;       for (int i = 0; i < 4; ++i) hq[i] = silu_(v0[i]) * v1[i];
;       st_h4(&H[(size_t)m * 1408 + (n >> 6) * 32 + (n & 31)], hq);
;     });
	v_mfma_f32_32x32x16_f16 v[2:17], v[234:237], v[230:233], v[2:17]
	v_mfma_f32_32x32x16_f16 v[18:33], v[238:241], v[230:233], v[18:33]
	ds_read_b128 v[234:237], v214 offset:64
	ds_read_b128 v[218:221], v212 offset:64
	ds_read_b128 v[238:241], v214 offset:4672
	ds_read_b128 v[222:225], v212 offset:4672
	ds_read_b128 v[226:229], v212 offset:9280
	ds_read_b128 v[230:233], v212 offset:13888
	s_waitcnt lgkmcnt(10)
	v_mfma_f32_32x32x16_f16 v[98:113], v[188:191], v[242:245], v[98:113]
	s_waitcnt lgkmcnt(9)
	v_mfma_f32_32x32x16_f16 v[114:129], v[174:177], v[242:245], v[114:129]
	s_waitcnt lgkmcnt(8)
	v_mfma_f32_32x32x16_f16 v[66:81], v[188:191], v[246:249], v[66:81]
	v_mfma_f32_32x32x16_f16 v[82:97], v[174:177], v[246:249], v[82:97]
	s_waitcnt lgkmcnt(7)
	v_mfma_f32_32x32x16_f16 v[34:49], v[188:191], v[204:207], v[34:49]
	v_mfma_f32_32x32x16_f16 v[50:65], v[174:177], v[204:207], v[50:65]
	s_waitcnt lgkmcnt(6)
	v_mfma_f32_32x32x16_f16 v[2:17], v[188:191], v[208:211], v[2:17]
	v_mfma_f32_32x32x16_f16 v[18:33], v[174:177], v[208:211], v[18:33]
	ds_read_b128 v[188:191], v214 offset:96
	ds_read_b128 v[242:245], v212 offset:96
	ds_read_b128 v[174:177], v214 offset:4704
	ds_read_b128 v[246:249], v212 offset:4704
	ds_read_b128 v[204:207], v212 offset:9312
	ds_read_b128 v[208:211], v212 offset:13920
	s_waitcnt lgkmcnt(10)
	v_mfma_f32_32x32x16_f16 v[98:113], v[234:237], v[218:221], v[98:113]
	s_waitcnt lgkmcnt(9)
	v_mfma_f32_32x32x16_f16 v[114:129], v[238:241], v[218:221], v[114:129]
	s_waitcnt lgkmcnt(8)
	v_mfma_f32_32x32x16_f16 v[66:81], v[234:237], v[222:225], v[66:81]
	v_mfma_f32_32x32x16_f16 v[82:97], v[238:241], v[222:225], v[82:97]
	s_waitcnt lgkmcnt(7)
	v_mfma_f32_32x32x16_f16 v[34:49], v[234:237], v[226:229], v[34:49]
	v_mfma_f32_32x32x16_f16 v[50:65], v[238:241], v[226:229], v[50:65]
	s_waitcnt lgkmcnt(6)
	v_mfma_f32_32x32x16_f16 v[2:17], v[234:237], v[230:233], v[2:17]
	v_mfma_f32_32x32x16_f16 v[18:33], v[238:241], v[230:233], v[18:33]
	s_waitcnt lgkmcnt(0)
	v_mfma_f32_32x32x16_f16 v[98:113], v[188:191], v[242:245], v[98:113]
	v_mfma_f32_32x32x16_f16 v[114:129], v[174:177], v[242:245], v[114:129]
	v_mfma_f32_32x32x16_f16 v[66:81], v[188:191], v[246:249], v[66:81]
	v_mfma_f32_32x32x16_f16 v[82:97], v[174:177], v[246:249], v[82:97]
	v_mfma_f32_32x32x16_f16 v[34:49], v[188:191], v[204:207], v[34:49]
	v_mfma_f32_32x32x16_f16 v[50:65], v[174:177], v[204:207], v[50:65]
	v_mfma_f32_32x32x16_f16 v[2:17], v[188:191], v[208:211], v[2:17]
	v_mfma_f32_32x32x16_f16 v[18:33], v[174:177], v[208:211], v[18:33]
	s_nop 15
	v_mov_b32_e32 v188, 0x358637bd
	v_mov_b32_e32 v189, 0x3727c5ac
	v_mov_b32_e32 v190, 0x2100
	v_mov_b32_e32 v191, 0x1400
	v_mov_b32_e32 v192, 0x7f800000
	v_mov_b32_e32 v193, 0x7fc00000
	v_mov_b32_e32 v194, 0xff800000
	v_mov_b32_e32 v204, 0x7fffec00
	v_mov_b32_e32 v205, 0xff7fc99e
	v_mov_b32_e32 v206, 0x840000
	v_mov_b32_e32 v207, 0xb00000
	v_mov_b32_e32 v208, 0xdc0000
	v_mov_b32_e32 v209, 0x1080000
	v_mov_b32_e32 v210, 0x1340000
	v_mov_b32_e32 v211, 0x420000
	v_mov_b32_e32 v212, 0x580000
	v_mov_b32_e32 v213, 0x6e0000
	v_mov_b32_e32 v214, 0x9a0000
	s_setprio 0
	s_barrier
	v_readfirstlane_b32 s66, v180
	s_sub_i32 s69, s4, s7
	s_mov_b32 s65, s6
	s_lshr_b32 s66, s66, 6
	s_and_b32 s67, s66, 3
	s_lshr_b32 s68, s66, 2
	s_lshr_b32 s70, s69, 1
	s_lshl_b32 s67, s67, 5
	s_add_i32 s70, s70, s67
	s_lshl_b32 s71, s68, 7
	s_add_i32 s71, s71, s65
	s_mul_i32 s72, s66, 0x2800
	s_add_i32 s72, s72, 16
	s_mov_b32 s73, 0xb00
	v_and_b32_e32 v146, 63, v180
	v_and_b32_e32 v148, 31, v146
	v_lshrrev_b32_e32 v147, 5, v146
	v_mul_u32_u24_e32 v130, 0x50, v148
	v_lshl_add_u32 v130, v147, 3, v130
	v_add_u32_e32 v130, s72, v130
	v_lshrrev_b32_e32 v149, 2, v146
	v_and_b32_e32 v138, 3, v146
	v_mul_u32_u24_e32 v131, 0x50, v149
	v_lshl_add_u32 v131, v138, 4, v131
	v_add_u32_e32 v131, s72, v131
	v_add_u32_e32 v140, s71, v149
	v_lshl_add_u32 v138, v138, 3, s70
	v_mov_b64_e32 v[132:133], s[0:1]
	v_mad_u64_u32 v[132:133], s[74:75], v140, s73, v[132:133]
	v_lshlrev_b32_e32 v138, 1, v138
	v_mov_b32_e32 v139, v0
	v_lshl_add_u64 v[132:133], v[132:133], 0, v[138:139]
	s_mov_b32 s76, 0xb000
	s_mov_b32 s77, 0
	v_mul_f32_e32 v234, 0xbfb8aa3b, v98
	v_mul_f32_e32 v235, 0xbfb8aa3b, v99
	v_mul_f32_e32 v236, 0xbfb8aa3b, v100
	v_mul_f32_e32 v237, 0xbfb8aa3b, v101
	v_exp_f32_e32 v234, v234
	v_exp_f32_e32 v235, v235
	v_exp_f32_e32 v236, v236
	v_exp_f32_e32 v237, v237
	v_add_f32_e32 v234, 1.0, v234
	v_add_f32_e32 v235, 1.0, v235
	v_add_f32_e32 v236, 1.0, v236
	v_add_f32_e32 v237, 1.0, v237
	v_rcp_f32_e32 v234, v234
	v_rcp_f32_e32 v235, v235
	v_rcp_f32_e32 v236, v236
	v_rcp_f32_e32 v237, v237
	v_mul_f32_e32 v98, v98, v234
	v_mul_f32_e32 v99, v99, v235
	v_mul_f32_e32 v100, v100, v236
	v_mul_f32_e32 v101, v101, v237
	v_mul_f32_e32 v98, v98, v114
	v_mul_f32_e32 v99, v99, v115
	v_mul_f32_e32 v100, v100, v116
	v_mul_f32_e32 v101, v101, v117
	v_cvt_pk_f16_f32 v138, v98, v99
	v_cvt_pk_f16_f32 v139, v100, v101
	ds_write_b64 v130, v[138:139] offset:0
	v_mul_f32_e32 v234, 0xbfb8aa3b, v102
	v_mul_f32_e32 v235, 0xbfb8aa3b, v103
	v_mul_f32_e32 v236, 0xbfb8aa3b, v104
	v_mul_f32_e32 v237, 0xbfb8aa3b, v105
	v_exp_f32_e32 v234, v234
	v_exp_f32_e32 v235, v235
	v_exp_f32_e32 v236, v236
	v_exp_f32_e32 v237, v237
	v_add_f32_e32 v234, 1.0, v234
	v_add_f32_e32 v235, 1.0, v235
	v_add_f32_e32 v236, 1.0, v236
	v_add_f32_e32 v237, 1.0, v237
	v_rcp_f32_e32 v234, v234
	v_rcp_f32_e32 v235, v235
	v_rcp_f32_e32 v236, v236
	v_rcp_f32_e32 v237, v237
	v_mul_f32_e32 v102, v102, v234
	v_mul_f32_e32 v103, v103, v235
	v_mul_f32_e32 v104, v104, v236
	v_mul_f32_e32 v105, v105, v237
	v_mul_f32_e32 v102, v102, v118
	v_mul_f32_e32 v103, v103, v119
; DI float silu_(float x) { return x / (1.f + __expf(-x)); }
; DI void phase_ffn1_moe(const Params& p, int bid, int nb, h16* lds) {
;     ...
;     gemm256_epilogue(acc, m0, n0, [&](int m, int n, f4v v0, f4v v1) {
;       f4v hq;
; #pragma unroll
;       for (int i = 0; i < 4; ++i) hq[i] = silu_(v0[i]) * v1[i];
;       st_h4(&H[(size_t)m * 1408 + (n >> 6) * 32 + (n & 31)], hq);
;     });
	v_mul_f32_e32 v104, v104, v120
	v_mul_f32_e32 v105, v105, v121
	v_cvt_pk_f16_f32 v140, v102, v103
	v_cvt_pk_f16_f32 v141, v104, v105
	ds_write_b64 v130, v[140:141] offset:16
	v_mul_f32_e32 v234, 0xbfb8aa3b, v106
	v_mul_f32_e32 v235, 0xbfb8aa3b, v107
	v_mul_f32_e32 v236, 0xbfb8aa3b, v108
	v_mul_f32_e32 v237, 0xbfb8aa3b, v109
	v_exp_f32_e32 v234, v234
	v_exp_f32_e32 v235, v235
	v_exp_f32_e32 v236, v236
	v_exp_f32_e32 v237, v237
	v_add_f32_e32 v234, 1.0, v234
	v_add_f32_e32 v235, 1.0, v235
	v_add_f32_e32 v236, 1.0, v236
	v_add_f32_e32 v237, 1.0, v237
	v_rcp_f32_e32 v234, v234
	v_rcp_f32_e32 v235, v235
	v_rcp_f32_e32 v236, v236
	v_rcp_f32_e32 v237, v237
	v_mul_f32_e32 v106, v106, v234
	v_mul_f32_e32 v107, v107, v235
	v_mul_f32_e32 v108, v108, v236
	v_mul_f32_e32 v109, v109, v237
	v_mul_f32_e32 v106, v106, v122
	v_mul_f32_e32 v107, v107, v123
	v_mul_f32_e32 v108, v108, v124
	v_mul_f32_e32 v109, v109, v125
	v_cvt_pk_f16_f32 v142, v106, v107
	v_cvt_pk_f16_f32 v143, v108, v109
	ds_write_b64 v130, v[142:143] offset:32
	v_mul_f32_e32 v234, 0xbfb8aa3b, v110
	v_mul_f32_e32 v235, 0xbfb8aa3b, v111
	v_mul_f32_e32 v236, 0xbfb8aa3b, v112
	v_mul_f32_e32 v237, 0xbfb8aa3b, v113
	v_exp_f32_e32 v234, v234
	v_exp_f32_e32 v235, v235
	v_exp_f32_e32 v236, v236
	v_exp_f32_e32 v237, v237
	v_add_f32_e32 v234, 1.0, v234
	v_add_f32_e32 v235, 1.0, v235
	v_add_f32_e32 v236, 1.0, v236
	v_add_f32_e32 v237, 1.0, v237
	v_rcp_f32_e32 v234, v234
	v_rcp_f32_e32 v235, v235
	v_rcp_f32_e32 v236, v236
	v_rcp_f32_e32 v237, v237
	v_mul_f32_e32 v110, v110, v234
	v_mul_f32_e32 v111, v111, v235
	v_mul_f32_e32 v112, v112, v236
	v_mul_f32_e32 v113, v113, v237
	v_mul_f32_e32 v110, v110, v126
	v_mul_f32_e32 v111, v111, v127
	v_mul_f32_e32 v112, v112, v128
	v_mul_f32_e32 v113, v113, v129
	v_cvt_pk_f16_f32 v144, v110, v111
	v_cvt_pk_f16_f32 v145, v112, v113
	ds_write_b64 v130, v[144:145] offset:48
	v_mul_f32_e32 v234, 0xbfb8aa3b, v66
	v_mul_f32_e32 v235, 0xbfb8aa3b, v67
	v_mul_f32_e32 v236, 0xbfb8aa3b, v68
	v_mul_f32_e32 v237, 0xbfb8aa3b, v69
	v_exp_f32_e32 v234, v234
	v_exp_f32_e32 v235, v235
	v_exp_f32_e32 v236, v236
	v_exp_f32_e32 v237, v237
	v_add_f32_e32 v234, 1.0, v234
	v_add_f32_e32 v235, 1.0, v235
	v_add_f32_e32 v236, 1.0, v236
	v_add_f32_e32 v237, 1.0, v237
	v_rcp_f32_e32 v234, v234
	v_rcp_f32_e32 v235, v235
	v_rcp_f32_e32 v236, v236
	v_rcp_f32_e32 v237, v237
	v_mul_f32_e32 v66, v66, v234
	v_mul_f32_e32 v67, v67, v235
	v_mul_f32_e32 v68, v68, v236
	v_mul_f32_e32 v69, v69, v237
	v_mul_f32_e32 v66, v66, v82
	v_mul_f32_e32 v67, v67, v83
	v_mul_f32_e32 v68, v68, v84
	v_mul_f32_e32 v69, v69, v85
	v_cvt_pk_f16_f32 v138, v66, v67
	v_cvt_pk_f16_f32 v139, v68, v69
	ds_write_b64 v130, v[138:139] offset:2560
	v_mul_f32_e32 v234, 0xbfb8aa3b, v70
	v_mul_f32_e32 v235, 0xbfb8aa3b, v71
	v_mul_f32_e32 v236, 0xbfb8aa3b, v72
	v_mul_f32_e32 v237, 0xbfb8aa3b, v73
	v_exp_f32_e32 v234, v234
	v_exp_f32_e32 v235, v235
	v_exp_f32_e32 v236, v236
	v_exp_f32_e32 v237, v237
	v_add_f32_e32 v234, 1.0, v234
	v_add_f32_e32 v235, 1.0, v235
	v_add_f32_e32 v236, 1.0, v236
	v_add_f32_e32 v237, 1.0, v237
	v_rcp_f32_e32 v234, v234
	v_rcp_f32_e32 v235, v235
	v_rcp_f32_e32 v236, v236
	v_rcp_f32_e32 v237, v237
	v_mul_f32_e32 v70, v70, v234
	v_mul_f32_e32 v71, v71, v235
	v_mul_f32_e32 v72, v72, v236
	v_mul_f32_e32 v73, v73, v237
	v_mul_f32_e32 v70, v70, v86
	v_mul_f32_e32 v71, v71, v87
	v_mul_f32_e32 v72, v72, v88
	v_mul_f32_e32 v73, v73, v89
	v_cvt_pk_f16_f32 v140, v70, v71
	v_cvt_pk_f16_f32 v141, v72, v73
	ds_write_b64 v130, v[140:141] offset:2576
	v_mul_f32_e32 v234, 0xbfb8aa3b, v74
	v_mul_f32_e32 v235, 0xbfb8aa3b, v75
	v_mul_f32_e32 v236, 0xbfb8aa3b, v76
	v_mul_f32_e32 v237, 0xbfb8aa3b, v77
	v_exp_f32_e32 v234, v234
	v_exp_f32_e32 v235, v235
	v_exp_f32_e32 v236, v236
	v_exp_f32_e32 v237, v237
	v_add_f32_e32 v234, 1.0, v234
	v_add_f32_e32 v235, 1.0, v235
	v_add_f32_e32 v236, 1.0, v236
	v_add_f32_e32 v237, 1.0, v237
	v_rcp_f32_e32 v234, v234
	v_rcp_f32_e32 v235, v235
	v_rcp_f32_e32 v236, v236
	v_rcp_f32_e32 v237, v237
	v_mul_f32_e32 v74, v74, v234
	v_mul_f32_e32 v75, v75, v235
	v_mul_f32_e32 v76, v76, v236
	v_mul_f32_e32 v77, v77, v237
	v_mul_f32_e32 v74, v74, v90
	v_mul_f32_e32 v75, v75, v91
	v_mul_f32_e32 v76, v76, v92
	v_mul_f32_e32 v77, v77, v93
	v_cvt_pk_f16_f32 v142, v74, v75
	v_cvt_pk_f16_f32 v143, v76, v77
	ds_write_b64 v130, v[142:143] offset:2592
	v_mul_f32_e32 v234, 0xbfb8aa3b, v78
	v_mul_f32_e32 v235, 0xbfb8aa3b, v79
	v_mul_f32_e32 v236, 0xbfb8aa3b, v80
	v_mul_f32_e32 v237, 0xbfb8aa3b, v81
	v_exp_f32_e32 v234, v234
	v_exp_f32_e32 v235, v235
	v_exp_f32_e32 v236, v236
	v_exp_f32_e32 v237, v237
	v_add_f32_e32 v234, 1.0, v234
	v_add_f32_e32 v235, 1.0, v235
	v_add_f32_e32 v236, 1.0, v236
	v_add_f32_e32 v237, 1.0, v237
	v_rcp_f32_e32 v234, v234
	v_rcp_f32_e32 v235, v235
	v_rcp_f32_e32 v236, v236
	v_rcp_f32_e32 v237, v237
	v_mul_f32_e32 v78, v78, v234
	v_mul_f32_e32 v79, v79, v235
	v_mul_f32_e32 v80, v80, v236
	v_mul_f32_e32 v81, v81, v237
	v_mul_f32_e32 v78, v78, v94
	v_mul_f32_e32 v79, v79, v95
	v_mul_f32_e32 v80, v80, v96
	v_mul_f32_e32 v81, v81, v97
	v_cvt_pk_f16_f32 v144, v78, v79
	v_cvt_pk_f16_f32 v145, v80, v81
	ds_write_b64 v130, v[144:145] offset:2608
	v_mul_f32_e32 v234, 0xbfb8aa3b, v34
	v_mul_f32_e32 v235, 0xbfb8aa3b, v35
	v_mul_f32_e32 v236, 0xbfb8aa3b, v36
	v_mul_f32_e32 v237, 0xbfb8aa3b, v37
	v_exp_f32_e32 v234, v234
	v_exp_f32_e32 v235, v235
	v_exp_f32_e32 v236, v236
	v_exp_f32_e32 v237, v237
	v_add_f32_e32 v234, 1.0, v234
	v_add_f32_e32 v235, 1.0, v235
	v_add_f32_e32 v236, 1.0, v236
	v_add_f32_e32 v237, 1.0, v237
	v_rcp_f32_e32 v234, v234
	v_rcp_f32_e32 v235, v235
	v_rcp_f32_e32 v236, v236
; DI float silu_(float x) { return x / (1.f + __expf(-x)); }
; DI void phase_ffn1_moe(const Params& p, int bid, int nb, h16* lds) {
;     ...
;     gemm256_epilogue(acc, m0, n0, [&](int m, int n, f4v v0, f4v v1) {
;       f4v hq;
; #pragma unroll
;       for (int i = 0; i < 4; ++i) hq[i] = silu_(v0[i]) * v1[i];
;       st_h4(&H[(size_t)m * 1408 + (n >> 6) * 32 + (n & 31)], hq);
;     });
	v_rcp_f32_e32 v237, v237
	v_mul_f32_e32 v34, v34, v234
	v_mul_f32_e32 v35, v35, v235
	v_mul_f32_e32 v36, v36, v236
	v_mul_f32_e32 v37, v37, v237
	v_mul_f32_e32 v34, v34, v50
	v_mul_f32_e32 v35, v35, v51
	v_mul_f32_e32 v36, v36, v52
	v_mul_f32_e32 v37, v37, v53
	v_cvt_pk_f16_f32 v138, v34, v35
	v_cvt_pk_f16_f32 v139, v36, v37
	ds_write_b64 v130, v[138:139] offset:5120
	v_mul_f32_e32 v234, 0xbfb8aa3b, v38
	v_mul_f32_e32 v235, 0xbfb8aa3b, v39
	v_mul_f32_e32 v236, 0xbfb8aa3b, v40
	v_mul_f32_e32 v237, 0xbfb8aa3b, v41
	v_exp_f32_e32 v234, v234
	v_exp_f32_e32 v235, v235
	v_exp_f32_e32 v236, v236
	v_exp_f32_e32 v237, v237
	v_add_f32_e32 v234, 1.0, v234
	v_add_f32_e32 v235, 1.0, v235
	v_add_f32_e32 v236, 1.0, v236
	v_add_f32_e32 v237, 1.0, v237
	v_rcp_f32_e32 v234, v234
	v_rcp_f32_e32 v235, v235
	v_rcp_f32_e32 v236, v236
	v_rcp_f32_e32 v237, v237
	v_mul_f32_e32 v38, v38, v234
	v_mul_f32_e32 v39, v39, v235
	v_mul_f32_e32 v40, v40, v236
	v_mul_f32_e32 v41, v41, v237
	v_mul_f32_e32 v38, v38, v54
	v_mul_f32_e32 v39, v39, v55
	v_mul_f32_e32 v40, v40, v56
	v_mul_f32_e32 v41, v41, v57
	v_cvt_pk_f16_f32 v140, v38, v39
	v_cvt_pk_f16_f32 v141, v40, v41
	ds_write_b64 v130, v[140:141] offset:5136
	v_mul_f32_e32 v234, 0xbfb8aa3b, v42
	v_mul_f32_e32 v235, 0xbfb8aa3b, v43
	v_mul_f32_e32 v236, 0xbfb8aa3b, v44
	v_mul_f32_e32 v237, 0xbfb8aa3b, v45
	v_exp_f32_e32 v234, v234
	v_exp_f32_e32 v235, v235
	v_exp_f32_e32 v236, v236
	v_exp_f32_e32 v237, v237
	v_add_f32_e32 v234, 1.0, v234
	v_add_f32_e32 v235, 1.0, v235
	v_add_f32_e32 v236, 1.0, v236
	v_add_f32_e32 v237, 1.0, v237
	v_rcp_f32_e32 v234, v234
	v_rcp_f32_e32 v235, v235
	v_rcp_f32_e32 v236, v236
	v_rcp_f32_e32 v237, v237
	v_mul_f32_e32 v42, v42, v234
	v_mul_f32_e32 v43, v43, v235
	v_mul_f32_e32 v44, v44, v236
	v_mul_f32_e32 v45, v45, v237
	v_mul_f32_e32 v42, v42, v58
	v_mul_f32_e32 v43, v43, v59
	v_mul_f32_e32 v44, v44, v60
	v_mul_f32_e32 v45, v45, v61
	v_cvt_pk_f16_f32 v142, v42, v43
	v_cvt_pk_f16_f32 v143, v44, v45
	ds_write_b64 v130, v[142:143] offset:5152
	v_mul_f32_e32 v234, 0xbfb8aa3b, v46
	v_mul_f32_e32 v235, 0xbfb8aa3b, v47
	v_mul_f32_e32 v236, 0xbfb8aa3b, v48
	v_mul_f32_e32 v237, 0xbfb8aa3b, v49
	v_exp_f32_e32 v234, v234
	v_exp_f32_e32 v235, v235
	v_exp_f32_e32 v236, v236
	v_exp_f32_e32 v237, v237
	v_add_f32_e32 v234, 1.0, v234
	v_add_f32_e32 v235, 1.0, v235
	v_add_f32_e32 v236, 1.0, v236
	v_add_f32_e32 v237, 1.0, v237
	v_rcp_f32_e32 v234, v234
	v_rcp_f32_e32 v235, v235
	v_rcp_f32_e32 v236, v236
	v_rcp_f32_e32 v237, v237
	v_mul_f32_e32 v46, v46, v234
	v_mul_f32_e32 v47, v47, v235
	v_mul_f32_e32 v48, v48, v236
	v_mul_f32_e32 v49, v49, v237
	v_mul_f32_e32 v46, v46, v62
	v_mul_f32_e32 v47, v47, v63
	v_mul_f32_e32 v48, v48, v64
	v_mul_f32_e32 v49, v49, v65
	v_cvt_pk_f16_f32 v144, v46, v47
	v_cvt_pk_f16_f32 v145, v48, v49
	ds_write_b64 v130, v[144:145] offset:5168
	v_mul_f32_e32 v234, 0xbfb8aa3b, v2
	v_mul_f32_e32 v235, 0xbfb8aa3b, v3
	v_mul_f32_e32 v236, 0xbfb8aa3b, v4
	v_mul_f32_e32 v237, 0xbfb8aa3b, v5
	v_exp_f32_e32 v234, v234
	v_exp_f32_e32 v235, v235
	v_exp_f32_e32 v236, v236
	v_exp_f32_e32 v237, v237
	v_add_f32_e32 v234, 1.0, v234
	v_add_f32_e32 v235, 1.0, v235
	v_add_f32_e32 v236, 1.0, v236
	v_add_f32_e32 v237, 1.0, v237
	v_rcp_f32_e32 v234, v234
	v_rcp_f32_e32 v235, v235
	v_rcp_f32_e32 v236, v236
	v_rcp_f32_e32 v237, v237
	v_mul_f32_e32 v2, v2, v234
	v_mul_f32_e32 v3, v3, v235
	v_mul_f32_e32 v4, v4, v236
	v_mul_f32_e32 v5, v5, v237
	v_mul_f32_e32 v2, v2, v18
	v_mul_f32_e32 v3, v3, v19
	v_mul_f32_e32 v4, v4, v20
	v_mul_f32_e32 v5, v5, v21
	v_cvt_pk_f16_f32 v138, v2, v3
	v_cvt_pk_f16_f32 v139, v4, v5
	ds_write_b64 v130, v[138:139] offset:7680
	v_mul_f32_e32 v234, 0xbfb8aa3b, v6
	v_mul_f32_e32 v235, 0xbfb8aa3b, v7
	v_mul_f32_e32 v236, 0xbfb8aa3b, v8
	v_mul_f32_e32 v237, 0xbfb8aa3b, v9
	v_exp_f32_e32 v234, v234
	v_exp_f32_e32 v235, v235
	v_exp_f32_e32 v236, v236
	v_exp_f32_e32 v237, v237
	v_add_f32_e32 v234, 1.0, v234
	v_add_f32_e32 v235, 1.0, v235
	v_add_f32_e32 v236, 1.0, v236
	v_add_f32_e32 v237, 1.0, v237
	v_rcp_f32_e32 v234, v234
	v_rcp_f32_e32 v235, v235
	v_rcp_f32_e32 v236, v236
	v_rcp_f32_e32 v237, v237
	v_mul_f32_e32 v6, v6, v234
	v_mul_f32_e32 v7, v7, v235
	v_mul_f32_e32 v8, v8, v236
	v_mul_f32_e32 v9, v9, v237
	v_mul_f32_e32 v6, v6, v22
	v_mul_f32_e32 v7, v7, v23
	v_mul_f32_e32 v8, v8, v24
	v_mul_f32_e32 v9, v9, v25
	v_cvt_pk_f16_f32 v140, v6, v7
	v_cvt_pk_f16_f32 v141, v8, v9
	ds_write_b64 v130, v[140:141] offset:7696
	v_mul_f32_e32 v234, 0xbfb8aa3b, v10
	v_mul_f32_e32 v235, 0xbfb8aa3b, v11
	v_mul_f32_e32 v236, 0xbfb8aa3b, v12
	v_mul_f32_e32 v237, 0xbfb8aa3b, v13
	v_exp_f32_e32 v234, v234
	v_exp_f32_e32 v235, v235
	v_exp_f32_e32 v236, v236
	v_exp_f32_e32 v237, v237
	v_add_f32_e32 v234, 1.0, v234
	v_add_f32_e32 v235, 1.0, v235
	v_add_f32_e32 v236, 1.0, v236
	v_add_f32_e32 v237, 1.0, v237
	v_rcp_f32_e32 v234, v234
	v_rcp_f32_e32 v235, v235
	v_rcp_f32_e32 v236, v236
	v_rcp_f32_e32 v237, v237
	v_mul_f32_e32 v10, v10, v234
	v_mul_f32_e32 v11, v11, v235
	v_mul_f32_e32 v12, v12, v236
	v_mul_f32_e32 v13, v13, v237
	v_mul_f32_e32 v10, v10, v26
	v_mul_f32_e32 v11, v11, v27
	v_mul_f32_e32 v12, v12, v28
	v_mul_f32_e32 v13, v13, v29
	v_cvt_pk_f16_f32 v142, v10, v11
	v_cvt_pk_f16_f32 v143, v12, v13
	ds_write_b64 v130, v[142:143] offset:7712
	v_mul_f32_e32 v234, 0xbfb8aa3b, v14
	v_mul_f32_e32 v235, 0xbfb8aa3b, v15
	v_mul_f32_e32 v236, 0xbfb8aa3b, v16
	v_mul_f32_e32 v237, 0xbfb8aa3b, v17
	v_exp_f32_e32 v234, v234
	v_exp_f32_e32 v235, v235
	v_exp_f32_e32 v236, v236
	v_exp_f32_e32 v237, v237
	v_add_f32_e32 v234, 1.0, v234
	v_add_f32_e32 v235, 1.0, v235
	v_add_f32_e32 v236, 1.0, v236
	v_add_f32_e32 v237, 1.0, v237
	v_rcp_f32_e32 v234, v234
	v_rcp_f32_e32 v235, v235
	v_rcp_f32_e32 v236, v236
	v_rcp_f32_e32 v237, v237
	v_mul_f32_e32 v14, v14, v234
	v_mul_f32_e32 v15, v15, v235
	v_mul_f32_e32 v16, v16, v236
	v_mul_f32_e32 v17, v17, v237
	v_mul_f32_e32 v14, v14, v30
	v_mul_f32_e32 v15, v15, v31
	v_mul_f32_e32 v16, v16, v32
	v_mul_f32_e32 v17, v17, v33
	v_cvt_pk_f16_f32 v144, v14, v15
	v_cvt_pk_f16_f32 v145, v16, v17
	ds_write_b64 v130, v[144:145] offset:7728
	ds_read_b128 v[150:153], v131 offset:0
	ds_read_b128 v[154:157], v131 offset:1280
	ds_read_b128 v[158:161], v131 offset:2560
	ds_read_b128 v[162:165], v131 offset:3840
	ds_read_b128 v[218:221], v131 offset:5120
	ds_read_b128 v[222:225], v131 offset:6400
	ds_read_b128 v[226:229], v131 offset:7680
	ds_read_b128 v[230:233], v131 offset:8960
	s_waitcnt lgkmcnt(7)
; DI float silu_(float x) { return x / (1.f + __expf(-x)); }
; DI void phase_ffn1_moe(const Params& p, int bid, int nb, h16* lds) {
;     ...
;   for (int u = bid; u < ntl; u += nb) {
;     const int mt = u / 11, m0 = mt * 256, n0 = (u % 11) * 256;
;     int e = 0;
; #pragma unroll
;     for (int i = 1; i < 8; ++i) if (m0 >= ps[i]) e = i;
;     f16v acc[4][2]; acc256_zero(acc);
;     gemm256_main<true>(x16, DM, st, m0, w13 + (size_t)e * 2816 * 1024, 1024, n0, 1024, lds, acc);
;     gemm256_epilogue(acc, m0, n0, [&](int m, int n, f4v v0, f4v v1) {
;       f4v hq;
; #pragma unroll
;       for (int i = 0; i < 4; ++i) hq[i] = silu_(v0[i]) * v1[i];
;       st_h4(&H[(size_t)m * 1408 + (n >> 6) * 32 + (n & 31)], hq);
;     });
	global_store_dwordx4 v[132:133], v[150:153], off
	v_lshl_add_u64 v[132:133], v[132:133], 0, s[76:77]
	s_waitcnt lgkmcnt(6)
	global_store_dwordx4 v[132:133], v[154:157], off
	v_lshl_add_u64 v[132:133], v[132:133], 0, s[76:77]
	s_waitcnt lgkmcnt(5)
	global_store_dwordx4 v[132:133], v[158:161], off
	v_lshl_add_u64 v[132:133], v[132:133], 0, s[76:77]
	s_waitcnt lgkmcnt(4)
	global_store_dwordx4 v[132:133], v[162:165], off
	v_lshl_add_u64 v[132:133], v[132:133], 0, s[76:77]
	s_waitcnt lgkmcnt(3)
	global_store_dwordx4 v[132:133], v[218:221], off
	v_lshl_add_u64 v[132:133], v[132:133], 0, s[76:77]
	s_waitcnt lgkmcnt(2)
	global_store_dwordx4 v[132:133], v[222:225], off
	v_lshl_add_u64 v[132:133], v[132:133], 0, s[76:77]
	s_waitcnt lgkmcnt(1)
	global_store_dwordx4 v[132:133], v[226:229], off
	v_lshl_add_u64 v[132:133], v[132:133], 0, s[76:77]
	s_waitcnt lgkmcnt(0)
	global_store_dwordx4 v[132:133], v[230:233], off
	v_lshl_add_u64 v[132:133], v[132:133], 0, s[76:77]
	s_add_i32 s4, s4, s23
	v_cmp_lt_i32_e32 vcc, s5, v216
	s_nop 4
	s_cbranch_vccnz .LBB0_1520
	s_mov_b32 s56, 0xfffff80

; DI int otid512() { int t = threadIdx.x; asm volatile("" : "+v"(t)); return t; }
; template <bool GATHER>
; DI void gemm256_main(const h16* __restrict__ A, int lda, const int* __restrict__ idx, int m0,
;                      const h16* __restrict__ B, int ldb, int n0, int K, h16* lds, f16v (&acc)[4][2]) {
;   const int tid = otid512(), lane = tid & 63, wv = tid >> 6, wm = wv >> 2, wn = wv & 3;
;   const int lr = tid >> 1, lc = (tid & 1) * 32;
;   unsigned ao = (unsigned)(GATHER ? idx[m0 + lr] : (m0 + lr)) * (unsigned)lda + lc;
;   unsigned bo = (unsigned)(n0 + lr) * (unsigned)ldb + lc;
;   const h16* ap = A; const h16* bp = B;
;     ...
;   u4v ra[4], rb[4];
;   const int nk = K >> 6;
;   __syncthreads();
; #pragma unroll
;   for (int i = 0; i < 4; ++i) { ra[i] = *(const u4v*)(AP_ + 8 * i); rb[i] = *(const u4v*)(BP_ + 8 * i); }
;   ao += 64; bo += 64;
; #pragma unroll
;   for (int i = 0; i < 4; ++i) { *(u4v*)&lds[lr * LDH + lc + 8 * i] = ra[i]; *(u4v*)&lds[(256 + lr) * LDH + lc + 8 * i] = rb[i]; }
; #pragma unroll
;   for (int i = 0; i < 4; ++i) { ra[i] = *(const u4v*)(AP_ + 8 * i); rb[i] = *(const u4v*)(BP_ + 8 * i); }
;   ao += 64; bo += 64;
;   __syncthreads();
;   for (int kt = 0; kt < nk; ++kt) {
;     const h16* As = lds + (kt & 1) * (512 * LDH);
;     const h16* Bs = As + 256 * LDH;
;     h16* Wn = lds + ((kt & 1) ^ 1) * (512 * LDH);
;     if (kt + 1 < nk) {
; #pragma unroll
;       for (int i = 0; i < 4; ++i) { *(u4v*)&Wn[lr * LDH + lc + 8 * i] = ra[i]; *(u4v*)&Wn[(256 + lr) * LDH + lc + 8 * i] = rb[i]; }
;     }
;     if (kt + 2 < nk) {
; #pragma unroll
;       for (int i = 0; i < 4; ++i) { ra[i] = *(const u4v*)(AP_ + 8 * i); rb[i] = *(const u4v*)(BP_ + 8 * i); }
;       ao += 64; bo += 64;
;     }
; #pragma unroll
;     for (int ks = 0; ks < 4; ++ks) {
;       h8v af[4], bf[2];
; #pragma unroll
;       for (int i = 0; i < 4; ++i) af[i] = *(const h8v*)&As[(wm * 128 + i * 32 + (lane & 31)) * LDH + ks * 16 + 8 * (lane >> 5)];
; #pragma unroll
; DI void phase_ffn2_moe(const Params& p, int bid, int nb, h16* lds) {
;     ...
;   for (int u = bid; u < ntl; u += nb) {
;     const int mt = u >> 2, m0 = mt * 256, n0 = (u & 3) * 256;
;     int e = 0;
; #pragma unroll
;     for (int i = 1; i < 8; ++i) if (m0 >= ps[i]) e = i;
;     f16v acc[4][2]; acc256_zero(acc);
;     gemm256_main<false>(H, 1408, nullptr, m0, w2 + (size_t)e * 1024 * 1408, 1408, n0, 1408, lds, acc);
.LBB0_1571:
	s_lshl_b32 s5, s4, 6
	s_and_b32 s6, s5, 0xffffff00
	s_lshl_b32 s5, s4, 8
	s_and_b32 s5, s5, 0x300
	s_cmp_lt_i32 s6, s2
	s_cselect_b32 s7, 0, 0x160000
	s_cmp_lt_i32 s6, s3
	s_cselect_b32 s7, s7, 0x2c0000
	v_mov_b32_e32 v2, s7
	v_cmp_lt_i32_e32 vcc, s6, v1
	v_mov_b32_e32 v3, v0
	v_readlane_b32 s8, v254, 44
	v_cndmask_b32_e32 v2, v211, v2, vcc
	v_cmp_lt_i32_e32 vcc, s6, v171
	v_readlane_b32 s9, v254, 45
	v_mov_b32_e32 v13, v180
	v_cndmask_b32_e32 v2, v212, v2, vcc
	v_cmp_lt_i32_e32 vcc, s6, v176
	s_movk_i32 s7, 0x580
	v_ashrrev_i32_e32 v52, 1, v13
	v_cndmask_b32_e32 v2, v213, v2, vcc
	v_cmp_lt_i32_e32 vcc, s6, v177
	v_mov_b32_e32 v47, v0
	v_mov_b32_e32 v49, v0
	v_cndmask_b32_e32 v2, v206, v2, vcc
	v_cmp_lt_i32_e32 vcc, s6, v178
	v_mov_b32_e32 v53, v0
	v_mul_lo_u32 v55, v52, s33
	v_cndmask_b32_e32 v2, v214, v2, vcc
	v_lshlrev_b64 v[2:3], 1, v[2:3]
	v_lshl_add_u64 v[162:163], s[8:9], 0, v[2:3]
	v_lshlrev_b32_e32 v2, 5, v13
	v_and_b32_e32 v54, 32, v2
	v_add_u32_e32 v2, s6, v52
	v_mul_lo_u32 v2, v2, s7
	v_or_b32_e32 v46, v2, v54
	v_add_u32_e32 v2, s5, v52
	v_mul_lo_u32 v2, v2, s7
	v_or_b32_e32 v48, v2, v54
	v_lshl_add_u64 v[2:3], v[46:47], 1, s[0:1]
	v_and_b32_e32 v47, 31, v13
	v_and_or_b32 v47, v52, s56, v47
	v_or_b32_e32 v52, 64, v46
	v_lshl_add_u64 v[50:51], v[48:49], 1, v[162:163]
	v_mul_lo_u32 v215, v47, s33
	v_add_u32_e32 v174, 0x80, v46
	v_lshl_add_u64 v[46:47], v[52:53], 1, s[0:1]
	s_barrier
	v_readlane_b32 s16, v252, 3
	v_readlane_b32 s22, v252, 9
	v_readlane_b32 s17, v252, 4
	v_readlane_b32 s18, v252, 5
	v_readlane_b32 s19, v252, 6
	v_readlane_b32 s20, v252, 7
	v_readlane_b32 s21, v252, 8
	v_readlane_b32 s23, v252, 10
	s_nop 1
	s_add_i32 s4, s4, s22
	v_cmp_lt_i32_e32 vcc, s4, v179
	s_and_b64 vcc, exec, vcc
	v_mov_b32_e32 v164, v2
	v_mov_b32_e32 v165, v3
	v_mov_b32_e32 v192, v50
	v_mov_b32_e32 v193, v51
	s_cselect_b32 s98, 1, 0
	v_readfirstlane_b32 s99, v180
	s_nop 1
	s_cmp_lt_u32 s99, 0x100
	s_cbranch_scc1 .Lprio_skip_5
	s_setprio 1
.Lprio_skip_5:
	s_cmp_eq_u32 s98, 1
	v_lshrrev_b32_e32 v214, 1, v180
	v_and_b32_e32 v248, 1, v180
	v_mul_u32_u24_e32 v214, 0x90, v214
	v_lshl_add_u32 v163, v248, 6, v214
	v_add_u32_e32 v163, 16, v163
	v_add_u32_e32 v175, 0x12000, v163
	v_lshrrev_b32_e32 v214, 8, v180
	v_and_b32_e32 v249, 31, v180
	v_lshl_or_b32 v214, v214, 7, v249
	v_mul_u32_u24_e32 v214, 0x90, v214
	v_bfe_u32 v248, v180, 5, 1
	v_lshl_add_u32 v214, v248, 4, v214
	v_add_u32_e32 v194, 16, v214
	v_add_u32_e32 v199, 0x12000, v194
	v_bfe_u32 v214, v180, 6, 2
	v_lshl_or_b32 v214, v214, 6, v249
	v_mul_u32_u24_e32 v214, 0x90, v214
	v_lshl_add_u32 v214, v248, 4, v214
	v_add_u32_e32 v212, 0x9010, v214
	v_add_u32_e32 v213, 0x12000, v212
	global_load_dwordx4 v[130:133], v[164:165], off offset:0
	global_load_dwordx4 v[134:137], v[164:165], off offset:16
	global_load_dwordx4 v[138:141], v[164:165], off offset:32
	global_load_dwordx4 v[142:145], v[164:165], off offset:48
	global_load_dwordx4 v[146:149], v[192:193], off offset:0
	global_load_dwordx4 v[150:153], v[192:193], off offset:16
	global_load_dwordx4 v[154:157], v[192:193], off offset:32
	global_load_dwordx4 v[158:161], v[192:193], off offset:48
	s_waitcnt vmcnt(0)
	ds_write_b128 v163, v[130:133]
	ds_write_b128 v163, v[134:137] offset:16
	ds_write_b128 v163, v[138:141] offset:32
	ds_write_b128 v163, v[142:145] offset:48
	ds_write_b128 v163, v[146:149] offset:36864
	ds_write_b128 v163, v[150:153] offset:36880
	ds_write_b128 v163, v[154:157] offset:36896
	ds_write_b128 v163, v[158:161] offset:36912
	global_load_dwordx4 v[130:133], v[164:165], off offset:128
	global_load_dwordx4 v[134:137], v[164:165], off offset:144
	global_load_dwordx4 v[138:141], v[164:165], off offset:160
	global_load_dwordx4 v[142:145], v[164:165], off offset:176
	global_load_dwordx4 v[146:149], v[192:193], off offset:128
	global_load_dwordx4 v[150:153], v[192:193], off offset:144
	global_load_dwordx4 v[154:157], v[192:193], off offset:160
	global_load_dwordx4 v[158:161], v[192:193], off offset:176
	s_waitcnt lgkmcnt(0)
	s_barrier
	ds_read_b128 v[232:235], v212
	ds_read_b128 v[188:191], v194
	ds_read_b128 v[236:239], v212 offset:4608
	ds_read_b128 v[200:203], v194 offset:4608
	ds_read_b128 v[204:207], v194 offset:9216
	ds_read_b128 v[208:211], v194 offset:13824
	ds_read_b128 v[240:243], v212 offset:32
	ds_read_b128 v[216:219], v194 offset:32
	ds_read_b128 v[244:247], v212 offset:4640
	ds_read_b128 v[220:223], v194 offset:4640
	ds_read_b128 v[224:227], v194 offset:9248
	ds_read_b128 v[228:231], v194 offset:13856
	s_waitcnt vmcnt(4)
	ds_write_b128 v175, v[130:133]
	ds_write_b128 v175, v[134:137] offset:16
	ds_write_b128 v175, v[138:141] offset:32
	ds_write_b128 v175, v[142:145] offset:48
	global_load_dwordx4 v[130:133], v[164:165], off offset:256
	global_load_dwordx4 v[134:137], v[164:165], off offset:272
	global_load_dwordx4 v[138:141], v[164:165], off offset:288
	global_load_dwordx4 v[142:145], v[164:165], off offset:304
	s_waitcnt lgkmcnt(14)
	v_mfma_f32_32x32x16_f16 v[114:129], v[232:235], v[188:191], 0
	s_waitcnt lgkmcnt(13)
	v_mfma_f32_32x32x16_f16 v[98:113], v[236:239], v[188:191], 0
	s_waitcnt lgkmcnt(12)
	v_mfma_f32_32x32x16_f16 v[82:97], v[232:235], v[200:203], 0
	v_mfma_f32_32x32x16_f16 v[66:81], v[236:239], v[200:203], 0
	s_waitcnt lgkmcnt(11)
	v_mfma_f32_32x32x16_f16 v[50:65], v[232:235], v[204:207], 0
	v_mfma_f32_32x32x16_f16 v[34:49], v[236:239], v[204:207], 0
	s_waitcnt lgkmcnt(10)
	v_mfma_f32_32x32x16_f16 v[18:33], v[232:235], v[208:211], 0
	v_mfma_f32_32x32x16_f16 v[2:17], v[236:239], v[208:211], 0
	ds_read_b128 v[232:235], v212 offset:64
	ds_read_b128 v[188:191], v194 offset:64
	ds_read_b128 v[236:239], v212 offset:4672
	ds_read_b128 v[200:203], v194 offset:4672
	ds_read_b128 v[204:207], v194 offset:9280
	ds_read_b128 v[208:211], v194 offset:13888
	s_waitcnt vmcnt(4)
; DI f16v mfma32(h8v a, h8v b, f16v c) { return __builtin_amdgcn_mfma_f32_32x32x16_f16(a, b, c, 0, 0, 0); }
; template <bool GATHER>
; DI void gemm256_main(const h16* __restrict__ A, int lda, const int* __restrict__ idx, int m0,
;                      const h16* __restrict__ B, int ldb, int n0, int K, h16* lds, f16v (&acc)[4][2]) {
;     ...
;   for (int kt = 0; kt < nk; ++kt) {
;     const h16* As = lds + (kt & 1) * (512 * LDH);
;     const h16* Bs = As + 256 * LDH;
;     h16* Wn = lds + ((kt & 1) ^ 1) * (512 * LDH);
;     if (kt + 1 < nk) {
; #pragma unroll
;       for (int i = 0; i < 4; ++i) { *(u4v*)&Wn[lr * LDH + lc + 8 * i] = ra[i]; *(u4v*)&Wn[(256 + lr) * LDH + lc + 8 * i] = rb[i]; }
;     }
;     if (kt + 2 < nk) {
; #pragma unroll
;       for (int i = 0; i < 4; ++i) { ra[i] = *(const u4v*)(AP_ + 8 * i); rb[i] = *(const u4v*)(BP_ + 8 * i); }
;       ao += 64; bo += 64;
;     }
; #pragma unroll
;     for (int ks = 0; ks < 4; ++ks) {
;       h8v af[4], bf[2];
; #pragma unroll
;       for (int i = 0; i < 4; ++i) af[i] = *(const h8v*)&As[(wm * 128 + i * 32 + (lane & 31)) * LDH + ks * 16 + 8 * (lane >> 5)];
; #pragma unroll
;       for (int j = 0; j < 2; ++j) bf[j] = *(const h8v*)&Bs[(wn * 64 + j * 32 + (lane & 31)) * LDH + ks * 16 + 8 * (lane >> 5)];
; #pragma unroll
;       for (int i = 0; i < 4; ++i)
; #pragma unroll
;         for (int j = 0; j < 2; ++j) acc[i][j] = mfma32(bf[j], af[i], acc[i][j]);
;     }
;     __syncthreads();
	ds_write_b128 v175, v[146:149] offset:36864
	ds_write_b128 v175, v[150:153] offset:36880
	ds_write_b128 v175, v[154:157] offset:36896
	ds_write_b128 v175, v[158:161] offset:36912
	global_load_dwordx4 v[146:149], v[192:193], off offset:256
	global_load_dwordx4 v[150:153], v[192:193], off offset:272
	global_load_dwordx4 v[154:157], v[192:193], off offset:288
	global_load_dwordx4 v[158:161], v[192:193], off offset:304
	s_waitcnt lgkmcnt(15)
	v_mfma_f32_32x32x16_f16 v[114:129], v[240:243], v[216:219], v[114:129]
	s_waitcnt lgkmcnt(15)
	v_mfma_f32_32x32x16_f16 v[98:113], v[244:247], v[216:219], v[98:113]
	s_waitcnt lgkmcnt(15)
	v_mfma_f32_32x32x16_f16 v[82:97], v[240:243], v[220:223], v[82:97]
	v_mfma_f32_32x32x16_f16 v[66:81], v[244:247], v[220:223], v[66:81]
	s_waitcnt lgkmcnt(15)
	v_mfma_f32_32x32x16_f16 v[50:65], v[240:243], v[224:227], v[50:65]
	v_mfma_f32_32x32x16_f16 v[34:49], v[244:247], v[224:227], v[34:49]
	s_waitcnt lgkmcnt(14)
	v_mfma_f32_32x32x16_f16 v[18:33], v[240:243], v[228:231], v[18:33]
	v_mfma_f32_32x32x16_f16 v[2:17], v[244:247], v[228:231], v[2:17]
	ds_read_b128 v[240:243], v212 offset:96
	ds_read_b128 v[216:219], v194 offset:96
	ds_read_b128 v[244:247], v212 offset:4704
	ds_read_b128 v[220:223], v194 offset:4704
	ds_read_b128 v[224:227], v194 offset:9312
	ds_read_b128 v[228:231], v194 offset:13920
	s_waitcnt lgkmcnt(14)
	v_mfma_f32_32x32x16_f16 v[114:129], v[232:235], v[188:191], v[114:129]
	s_waitcnt lgkmcnt(13)
	v_mfma_f32_32x32x16_f16 v[98:113], v[236:239], v[188:191], v[98:113]
	s_waitcnt lgkmcnt(12)
	v_mfma_f32_32x32x16_f16 v[82:97], v[232:235], v[200:203], v[82:97]
	v_mfma_f32_32x32x16_f16 v[66:81], v[236:239], v[200:203], v[66:81]
	s_waitcnt lgkmcnt(11)
	v_mfma_f32_32x32x16_f16 v[50:65], v[232:235], v[204:207], v[50:65]
	v_mfma_f32_32x32x16_f16 v[34:49], v[236:239], v[204:207], v[34:49]
	s_waitcnt lgkmcnt(10)
	v_mfma_f32_32x32x16_f16 v[18:33], v[232:235], v[208:211], v[18:33]
	v_mfma_f32_32x32x16_f16 v[2:17], v[236:239], v[208:211], v[2:17]
	s_waitcnt lgkmcnt(0)
	s_barrier
	ds_read_b128 v[232:235], v213
	ds_read_b128 v[188:191], v199
	ds_read_b128 v[236:239], v213 offset:4608
	ds_read_b128 v[200:203], v199 offset:4608
	ds_read_b128 v[204:207], v199 offset:9216
	ds_read_b128 v[208:211], v199 offset:13824
	v_mfma_f32_32x32x16_f16 v[114:129], v[240:243], v[216:219], v[114:129]
	v_mfma_f32_32x32x16_f16 v[98:113], v[244:247], v[216:219], v[98:113]
	v_mfma_f32_32x32x16_f16 v[82:97], v[240:243], v[220:223], v[82:97]
	v_mfma_f32_32x32x16_f16 v[66:81], v[244:247], v[220:223], v[66:81]
	v_mfma_f32_32x32x16_f16 v[50:65], v[240:243], v[224:227], v[50:65]
	v_mfma_f32_32x32x16_f16 v[34:49], v[244:247], v[224:227], v[34:49]
	v_mfma_f32_32x32x16_f16 v[18:33], v[240:243], v[228:231], v[18:33]
	v_mfma_f32_32x32x16_f16 v[2:17], v[244:247], v[228:231], v[2:17]
	ds_read_b128 v[240:243], v213 offset:32
	ds_read_b128 v[216:219], v199 offset:32
	ds_read_b128 v[244:247], v213 offset:4640
	ds_read_b128 v[220:223], v199 offset:4640
	ds_read_b128 v[224:227], v199 offset:9248
	ds_read_b128 v[228:231], v199 offset:13856
	s_waitcnt vmcnt(4)
	ds_write_b128 v163, v[130:133]
	ds_write_b128 v163, v[134:137] offset:16
	ds_write_b128 v163, v[138:141] offset:32
	ds_write_b128 v163, v[142:145] offset:48
	global_load_dwordx4 v[130:133], v[164:165], off offset:384
	global_load_dwordx4 v[134:137], v[164:165], off offset:400
	global_load_dwordx4 v[138:141], v[164:165], off offset:416
	global_load_dwordx4 v[142:145], v[164:165], off offset:432
	s_waitcnt lgkmcnt(14)
	v_mfma_f32_32x32x16_f16 v[114:129], v[232:235], v[188:191], v[114:129]
	s_waitcnt lgkmcnt(13)
	v_mfma_f32_32x32x16_f16 v[98:113], v[236:239], v[188:191], v[98:113]
	s_waitcnt lgkmcnt(12)
	v_mfma_f32_32x32x16_f16 v[82:97], v[232:235], v[200:203], v[82:97]
	v_mfma_f32_32x32x16_f16 v[66:81], v[236:239], v[200:203], v[66:81]
	s_waitcnt lgkmcnt(11)
	v_mfma_f32_32x32x16_f16 v[50:65], v[232:235], v[204:207], v[50:65]
	v_mfma_f32_32x32x16_f16 v[34:49], v[236:239], v[204:207], v[34:49]
	s_waitcnt lgkmcnt(10)
	v_mfma_f32_32x32x16_f16 v[18:33], v[232:235], v[208:211], v[18:33]
	v_mfma_f32_32x32x16_f16 v[2:17], v[236:239], v[208:211], v[2:17]
	ds_read_b128 v[232:235], v213 offset:64
	ds_read_b128 v[188:191], v199 offset:64
	ds_read_b128 v[236:239], v213 offset:4672
	ds_read_b128 v[200:203], v199 offset:4672
	ds_read_b128 v[204:207], v199 offset:9280
	ds_read_b128 v[208:211], v199 offset:13888
	s_waitcnt vmcnt(4)
	ds_write_b128 v163, v[146:149] offset:36864
	ds_write_b128 v163, v[150:153] offset:36880
	ds_write_b128 v163, v[154:157] offset:36896
	ds_write_b128 v163, v[158:161] offset:36912
	global_load_dwordx4 v[146:149], v[192:193], off offset:384
	global_load_dwordx4 v[150:153], v[192:193], off offset:400
	global_load_dwordx4 v[154:157], v[192:193], off offset:416
	global_load_dwordx4 v[158:161], v[192:193], off offset:432
	s_waitcnt lgkmcnt(15)
	v_mfma_f32_32x32x16_f16 v[114:129], v[240:243], v[216:219], v[114:129]
	s_waitcnt lgkmcnt(15)
	v_mfma_f32_32x32x16_f16 v[98:113], v[244:247], v[216:219], v[98:113]
	s_waitcnt lgkmcnt(15)
	v_mfma_f32_32x32x16_f16 v[82:97], v[240:243], v[220:223], v[82:97]
	v_mfma_f32_32x32x16_f16 v[66:81], v[244:247], v[220:223], v[66:81]
	s_waitcnt lgkmcnt(15)
	v_mfma_f32_32x32x16_f16 v[50:65], v[240:243], v[224:227], v[50:65]
	v_mfma_f32_32x32x16_f16 v[34:49], v[244:247], v[224:227], v[34:49]
	s_waitcnt lgkmcnt(14)
	v_mfma_f32_32x32x16_f16 v[18:33], v[240:243], v[228:231], v[18:33]
	v_mfma_f32_32x32x16_f16 v[2:17], v[244:247], v[228:231], v[2:17]
	ds_read_b128 v[240:243], v213 offset:96
	ds_read_b128 v[216:219], v199 offset:96
	ds_read_b128 v[244:247], v213 offset:4704
	ds_read_b128 v[220:223], v199 offset:4704
	ds_read_b128 v[224:227], v199 offset:9312
	ds_read_b128 v[228:231], v199 offset:13920
	s_waitcnt lgkmcnt(14)
	v_mfma_f32_32x32x16_f16 v[114:129], v[232:235], v[188:191], v[114:129]
	s_waitcnt lgkmcnt(13)
	v_mfma_f32_32x32x16_f16 v[98:113], v[236:239], v[188:191], v[98:113]
	s_waitcnt lgkmcnt(12)
	v_mfma_f32_32x32x16_f16 v[82:97], v[232:235], v[200:203], v[82:97]
	v_mfma_f32_32x32x16_f16 v[66:81], v[236:239], v[200:203], v[66:81]
	s_waitcnt lgkmcnt(11)
	v_mfma_f32_32x32x16_f16 v[50:65], v[232:235], v[204:207], v[50:65]
	v_mfma_f32_32x32x16_f16 v[34:49], v[236:239], v[204:207], v[34:49]
	s_waitcnt lgkmcnt(10)
	v_mfma_f32_32x32x16_f16 v[18:33], v[232:235], v[208:211], v[18:33]
	v_mfma_f32_32x32x16_f16 v[2:17], v[236:239], v[208:211], v[2:17]
	s_waitcnt lgkmcnt(0)
	s_barrier
; DI f16v mfma32(h8v a, h8v b, f16v c) { return __builtin_amdgcn_mfma_f32_32x32x16_f16(a, b, c, 0, 0, 0); }
; template <bool GATHER>
; DI void gemm256_main(const h16* __restrict__ A, int lda, const int* __restrict__ idx, int m0,
;                      const h16* __restrict__ B, int ldb, int n0, int K, h16* lds, f16v (&acc)[4][2]) {
;     ...
;   for (int kt = 0; kt < nk; ++kt) {
;     const h16* As = lds + (kt & 1) * (512 * LDH);
;     const h16* Bs = As + 256 * LDH;
;     h16* Wn = lds + ((kt & 1) ^ 1) * (512 * LDH);
;     if (kt + 1 < nk) {
; #pragma unroll
;       for (int i = 0; i < 4; ++i) { *(u4v*)&Wn[lr * LDH + lc + 8 * i] = ra[i]; *(u4v*)&Wn[(256 + lr) * LDH + lc + 8 * i] = rb[i]; }
;     }
;     if (kt + 2 < nk) {
; #pragma unroll
;       for (int i = 0; i < 4; ++i) { ra[i] = *(const u4v*)(AP_ + 8 * i); rb[i] = *(const u4v*)(BP_ + 8 * i); }
;       ao += 64; bo += 64;
;     }
; #pragma unroll
;     for (int ks = 0; ks < 4; ++ks) {
;       h8v af[4], bf[2];
; #pragma unroll
;       for (int i = 0; i < 4; ++i) af[i] = *(const h8v*)&As[(wm * 128 + i * 32 + (lane & 31)) * LDH + ks * 16 + 8 * (lane >> 5)];
; #pragma unroll
;       for (int j = 0; j < 2; ++j) bf[j] = *(const h8v*)&Bs[(wn * 64 + j * 32 + (lane & 31)) * LDH + ks * 16 + 8 * (lane >> 5)];
; #pragma unroll
;       for (int i = 0; i < 4; ++i)
; #pragma unroll
;         for (int j = 0; j < 2; ++j) acc[i][j] = mfma32(bf[j], af[i], acc[i][j]);
;     }
;     __syncthreads();
	ds_read_b128 v[232:235], v212
	ds_read_b128 v[188:191], v194
	ds_read_b128 v[236:239], v212 offset:4608
	ds_read_b128 v[200:203], v194 offset:4608
	ds_read_b128 v[204:207], v194 offset:9216
	ds_read_b128 v[208:211], v194 offset:13824
	v_mfma_f32_32x32x16_f16 v[114:129], v[240:243], v[216:219], v[114:129]
	v_mfma_f32_32x32x16_f16 v[98:113], v[244:247], v[216:219], v[98:113]
	v_mfma_f32_32x32x16_f16 v[82:97], v[240:243], v[220:223], v[82:97]
	v_mfma_f32_32x32x16_f16 v[66:81], v[244:247], v[220:223], v[66:81]
	v_mfma_f32_32x32x16_f16 v[50:65], v[240:243], v[224:227], v[50:65]
	v_mfma_f32_32x32x16_f16 v[34:49], v[244:247], v[224:227], v[34:49]
	v_mfma_f32_32x32x16_f16 v[18:33], v[240:243], v[228:231], v[18:33]
	v_mfma_f32_32x32x16_f16 v[2:17], v[244:247], v[228:231], v[2:17]
	ds_read_b128 v[240:243], v212 offset:32
	ds_read_b128 v[216:219], v194 offset:32
	ds_read_b128 v[244:247], v212 offset:4640
	ds_read_b128 v[220:223], v194 offset:4640
	ds_read_b128 v[224:227], v194 offset:9248
	ds_read_b128 v[228:231], v194 offset:13856
	s_waitcnt vmcnt(4)
	ds_write_b128 v175, v[130:133]
	ds_write_b128 v175, v[134:137] offset:16
	ds_write_b128 v175, v[138:141] offset:32
	ds_write_b128 v175, v[142:145] offset:48
	global_load_dwordx4 v[130:133], v[164:165], off offset:512
	global_load_dwordx4 v[134:137], v[164:165], off offset:528
	global_load_dwordx4 v[138:141], v[164:165], off offset:544
	global_load_dwordx4 v[142:145], v[164:165], off offset:560
	s_waitcnt lgkmcnt(14)
	v_mfma_f32_32x32x16_f16 v[114:129], v[232:235], v[188:191], v[114:129]
	s_waitcnt lgkmcnt(13)
	v_mfma_f32_32x32x16_f16 v[98:113], v[236:239], v[188:191], v[98:113]
	s_waitcnt lgkmcnt(12)
	v_mfma_f32_32x32x16_f16 v[82:97], v[232:235], v[200:203], v[82:97]
	v_mfma_f32_32x32x16_f16 v[66:81], v[236:239], v[200:203], v[66:81]
	s_waitcnt lgkmcnt(11)
	v_mfma_f32_32x32x16_f16 v[50:65], v[232:235], v[204:207], v[50:65]
	v_mfma_f32_32x32x16_f16 v[34:49], v[236:239], v[204:207], v[34:49]
	s_waitcnt lgkmcnt(10)
	v_mfma_f32_32x32x16_f16 v[18:33], v[232:235], v[208:211], v[18:33]
	v_mfma_f32_32x32x16_f16 v[2:17], v[236:239], v[208:211], v[2:17]
	ds_read_b128 v[232:235], v212 offset:64
	ds_read_b128 v[188:191], v194 offset:64
	ds_read_b128 v[236:239], v212 offset:4672
	ds_read_b128 v[200:203], v194 offset:4672
	ds_read_b128 v[204:207], v194 offset:9280
	ds_read_b128 v[208:211], v194 offset:13888
	s_waitcnt vmcnt(4)
	ds_write_b128 v175, v[146:149] offset:36864
	ds_write_b128 v175, v[150:153] offset:36880
	ds_write_b128 v175, v[154:157] offset:36896
	ds_write_b128 v175, v[158:161] offset:36912
	global_load_dwordx4 v[146:149], v[192:193], off offset:512
	global_load_dwordx4 v[150:153], v[192:193], off offset:528
	global_load_dwordx4 v[154:157], v[192:193], off offset:544
	global_load_dwordx4 v[158:161], v[192:193], off offset:560
	s_waitcnt lgkmcnt(15)
	v_mfma_f32_32x32x16_f16 v[114:129], v[240:243], v[216:219], v[114:129]
	s_waitcnt lgkmcnt(15)
	v_mfma_f32_32x32x16_f16 v[98:113], v[244:247], v[216:219], v[98:113]
	s_waitcnt lgkmcnt(15)
	v_mfma_f32_32x32x16_f16 v[82:97], v[240:243], v[220:223], v[82:97]
	v_mfma_f32_32x32x16_f16 v[66:81], v[244:247], v[220:223], v[66:81]
	s_waitcnt lgkmcnt(15)
	v_mfma_f32_32x32x16_f16 v[50:65], v[240:243], v[224:227], v[50:65]
	v_mfma_f32_32x32x16_f16 v[34:49], v[244:247], v[224:227], v[34:49]
	s_waitcnt lgkmcnt(14)
	v_mfma_f32_32x32x16_f16 v[18:33], v[240:243], v[228:231], v[18:33]
	v_mfma_f32_32x32x16_f16 v[2:17], v[244:247], v[228:231], v[2:17]
	ds_read_b128 v[240:243], v212 offset:96
	ds_read_b128 v[216:219], v194 offset:96
	ds_read_b128 v[244:247], v212 offset:4704
	ds_read_b128 v[220:223], v194 offset:4704
	ds_read_b128 v[224:227], v194 offset:9312
	ds_read_b128 v[228:231], v194 offset:13920
	s_waitcnt lgkmcnt(14)
	v_mfma_f32_32x32x16_f16 v[114:129], v[232:235], v[188:191], v[114:129]
	s_waitcnt lgkmcnt(13)
	v_mfma_f32_32x32x16_f16 v[98:113], v[236:239], v[188:191], v[98:113]
	s_waitcnt lgkmcnt(12)
	v_mfma_f32_32x32x16_f16 v[82:97], v[232:235], v[200:203], v[82:97]
	v_mfma_f32_32x32x16_f16 v[66:81], v[236:239], v[200:203], v[66:81]
	s_waitcnt lgkmcnt(11)
	v_mfma_f32_32x32x16_f16 v[50:65], v[232:235], v[204:207], v[50:65]
	v_mfma_f32_32x32x16_f16 v[34:49], v[236:239], v[204:207], v[34:49]
	s_waitcnt lgkmcnt(10)
	v_mfma_f32_32x32x16_f16 v[18:33], v[232:235], v[208:211], v[18:33]
	v_mfma_f32_32x32x16_f16 v[2:17], v[236:239], v[208:211], v[2:17]
	s_waitcnt lgkmcnt(0)
	s_barrier
; DI f16v mfma32(h8v a, h8v b, f16v c) { return __builtin_amdgcn_mfma_f32_32x32x16_f16(a, b, c, 0, 0, 0); }
; template <bool GATHER>
; DI void gemm256_main(const h16* __restrict__ A, int lda, const int* __restrict__ idx, int m0,
;                      const h16* __restrict__ B, int ldb, int n0, int K, h16* lds, f16v (&acc)[4][2]) {
;     ...
;   for (int kt = 0; kt < nk; ++kt) {
;     const h16* As = lds + (kt & 1) * (512 * LDH);
;     const h16* Bs = As + 256 * LDH;
;     h16* Wn = lds + ((kt & 1) ^ 1) * (512 * LDH);
;     if (kt + 1 < nk) {
; #pragma unroll
;       for (int i = 0; i < 4; ++i) { *(u4v*)&Wn[lr * LDH + lc + 8 * i] = ra[i]; *(u4v*)&Wn[(256 + lr) * LDH + lc + 8 * i] = rb[i]; }
;     }
;     if (kt + 2 < nk) {
; #pragma unroll
;       for (int i = 0; i < 4; ++i) { ra[i] = *(const u4v*)(AP_ + 8 * i); rb[i] = *(const u4v*)(BP_ + 8 * i); }
;       ao += 64; bo += 64;
;     }
; #pragma unroll
;     for (int ks = 0; ks < 4; ++ks) {
;       h8v af[4], bf[2];
; #pragma unroll
;       for (int i = 0; i < 4; ++i) af[i] = *(const h8v*)&As[(wm * 128 + i * 32 + (lane & 31)) * LDH + ks * 16 + 8 * (lane >> 5)];
; #pragma unroll
;       for (int j = 0; j < 2; ++j) bf[j] = *(const h8v*)&Bs[(wn * 64 + j * 32 + (lane & 31)) * LDH + ks * 16 + 8 * (lane >> 5)];
; #pragma unroll
;       for (int i = 0; i < 4; ++i)
; #pragma unroll
;         for (int j = 0; j < 2; ++j) acc[i][j] = mfma32(bf[j], af[i], acc[i][j]);
;     }
;     __syncthreads();
	ds_read_b128 v[232:235], v213
	ds_read_b128 v[188:191], v199
	ds_read_b128 v[236:239], v213 offset:4608
	ds_read_b128 v[200:203], v199 offset:4608
	ds_read_b128 v[204:207], v199 offset:9216
	ds_read_b128 v[208:211], v199 offset:13824
	v_mfma_f32_32x32x16_f16 v[114:129], v[240:243], v[216:219], v[114:129]
	v_mfma_f32_32x32x16_f16 v[98:113], v[244:247], v[216:219], v[98:113]
	v_mfma_f32_32x32x16_f16 v[82:97], v[240:243], v[220:223], v[82:97]
	v_mfma_f32_32x32x16_f16 v[66:81], v[244:247], v[220:223], v[66:81]
	v_mfma_f32_32x32x16_f16 v[50:65], v[240:243], v[224:227], v[50:65]
	v_mfma_f32_32x32x16_f16 v[34:49], v[244:247], v[224:227], v[34:49]
	v_mfma_f32_32x32x16_f16 v[18:33], v[240:243], v[228:231], v[18:33]
	v_mfma_f32_32x32x16_f16 v[2:17], v[244:247], v[228:231], v[2:17]
	ds_read_b128 v[240:243], v213 offset:32
	ds_read_b128 v[216:219], v199 offset:32
	ds_read_b128 v[244:247], v213 offset:4640
	ds_read_b128 v[220:223], v199 offset:4640
	ds_read_b128 v[224:227], v199 offset:9248
	ds_read_b128 v[228:231], v199 offset:13856
	s_waitcnt vmcnt(4)
	ds_write_b128 v163, v[130:133]
	ds_write_b128 v163, v[134:137] offset:16
	ds_write_b128 v163, v[138:141] offset:32
	ds_write_b128 v163, v[142:145] offset:48
	global_load_dwordx4 v[130:133], v[164:165], off offset:640
	global_load_dwordx4 v[134:137], v[164:165], off offset:656
	global_load_dwordx4 v[138:141], v[164:165], off offset:672
	global_load_dwordx4 v[142:145], v[164:165], off offset:688
	s_waitcnt lgkmcnt(14)
	v_mfma_f32_32x32x16_f16 v[114:129], v[232:235], v[188:191], v[114:129]
	s_waitcnt lgkmcnt(13)
	v_mfma_f32_32x32x16_f16 v[98:113], v[236:239], v[188:191], v[98:113]
	s_waitcnt lgkmcnt(12)
	v_mfma_f32_32x32x16_f16 v[82:97], v[232:235], v[200:203], v[82:97]
	v_mfma_f32_32x32x16_f16 v[66:81], v[236:239], v[200:203], v[66:81]
	s_waitcnt lgkmcnt(11)
	v_mfma_f32_32x32x16_f16 v[50:65], v[232:235], v[204:207], v[50:65]
	v_mfma_f32_32x32x16_f16 v[34:49], v[236:239], v[204:207], v[34:49]
	s_waitcnt lgkmcnt(10)
	v_mfma_f32_32x32x16_f16 v[18:33], v[232:235], v[208:211], v[18:33]
	v_mfma_f32_32x32x16_f16 v[2:17], v[236:239], v[208:211], v[2:17]
	ds_read_b128 v[232:235], v213 offset:64
	ds_read_b128 v[188:191], v199 offset:64
	ds_read_b128 v[236:239], v213 offset:4672
	ds_read_b128 v[200:203], v199 offset:4672
	ds_read_b128 v[204:207], v199 offset:9280
	ds_read_b128 v[208:211], v199 offset:13888
	s_waitcnt vmcnt(4)
	ds_write_b128 v163, v[146:149] offset:36864
	ds_write_b128 v163, v[150:153] offset:36880
	ds_write_b128 v163, v[154:157] offset:36896
	ds_write_b128 v163, v[158:161] offset:36912
	global_load_dwordx4 v[146:149], v[192:193], off offset:640
	global_load_dwordx4 v[150:153], v[192:193], off offset:656
	global_load_dwordx4 v[154:157], v[192:193], off offset:672
	global_load_dwordx4 v[158:161], v[192:193], off offset:688
	s_waitcnt lgkmcnt(15)
	v_mfma_f32_32x32x16_f16 v[114:129], v[240:243], v[216:219], v[114:129]
	s_waitcnt lgkmcnt(15)
	v_mfma_f32_32x32x16_f16 v[98:113], v[244:247], v[216:219], v[98:113]
	s_waitcnt lgkmcnt(15)
	v_mfma_f32_32x32x16_f16 v[82:97], v[240:243], v[220:223], v[82:97]
	v_mfma_f32_32x32x16_f16 v[66:81], v[244:247], v[220:223], v[66:81]
	s_waitcnt lgkmcnt(15)
	v_mfma_f32_32x32x16_f16 v[50:65], v[240:243], v[224:227], v[50:65]
	v_mfma_f32_32x32x16_f16 v[34:49], v[244:247], v[224:227], v[34:49]
	s_waitcnt lgkmcnt(14)
	v_mfma_f32_32x32x16_f16 v[18:33], v[240:243], v[228:231], v[18:33]
	v_mfma_f32_32x32x16_f16 v[2:17], v[244:247], v[228:231], v[2:17]
	ds_read_b128 v[240:243], v213 offset:96
	ds_read_b128 v[216:219], v199 offset:96
	ds_read_b128 v[244:247], v213 offset:4704
	ds_read_b128 v[220:223], v199 offset:4704
	ds_read_b128 v[224:227], v199 offset:9312
	ds_read_b128 v[228:231], v199 offset:13920
	s_waitcnt lgkmcnt(14)
	v_mfma_f32_32x32x16_f16 v[114:129], v[232:235], v[188:191], v[114:129]
	s_waitcnt lgkmcnt(13)
	v_mfma_f32_32x32x16_f16 v[98:113], v[236:239], v[188:191], v[98:113]
	s_waitcnt lgkmcnt(12)
	v_mfma_f32_32x32x16_f16 v[82:97], v[232:235], v[200:203], v[82:97]
	v_mfma_f32_32x32x16_f16 v[66:81], v[236:239], v[200:203], v[66:81]
	s_waitcnt lgkmcnt(11)
	v_mfma_f32_32x32x16_f16 v[50:65], v[232:235], v[204:207], v[50:65]
	v_mfma_f32_32x32x16_f16 v[34:49], v[236:239], v[204:207], v[34:49]
	s_waitcnt lgkmcnt(10)
	v_mfma_f32_32x32x16_f16 v[18:33], v[232:235], v[208:211], v[18:33]
	v_mfma_f32_32x32x16_f16 v[2:17], v[236:239], v[208:211], v[2:17]
	s_waitcnt lgkmcnt(0)
	s_barrier
; DI f16v mfma32(h8v a, h8v b, f16v c) { return __builtin_amdgcn_mfma_f32_32x32x16_f16(a, b, c, 0, 0, 0); }
; template <bool GATHER>
; DI void gemm256_main(const h16* __restrict__ A, int lda, const int* __restrict__ idx, int m0,
;                      const h16* __restrict__ B, int ldb, int n0, int K, h16* lds, f16v (&acc)[4][2]) {
;     ...
;   for (int kt = 0; kt < nk; ++kt) {
;     const h16* As = lds + (kt & 1) * (512 * LDH);
;     const h16* Bs = As + 256 * LDH;
;     h16* Wn = lds + ((kt & 1) ^ 1) * (512 * LDH);
;     if (kt + 1 < nk) {
; #pragma unroll
;       for (int i = 0; i < 4; ++i) { *(u4v*)&Wn[lr * LDH + lc + 8 * i] = ra[i]; *(u4v*)&Wn[(256 + lr) * LDH + lc + 8 * i] = rb[i]; }
;     }
;     if (kt + 2 < nk) {
; #pragma unroll
;       for (int i = 0; i < 4; ++i) { ra[i] = *(const u4v*)(AP_ + 8 * i); rb[i] = *(const u4v*)(BP_ + 8 * i); }
;       ao += 64; bo += 64;
;     }
; #pragma unroll
;     for (int ks = 0; ks < 4; ++ks) {
;       h8v af[4], bf[2];
; #pragma unroll
;       for (int i = 0; i < 4; ++i) af[i] = *(const h8v*)&As[(wm * 128 + i * 32 + (lane & 31)) * LDH + ks * 16 + 8 * (lane >> 5)];
; #pragma unroll
;       for (int j = 0; j < 2; ++j) bf[j] = *(const h8v*)&Bs[(wn * 64 + j * 32 + (lane & 31)) * LDH + ks * 16 + 8 * (lane >> 5)];
; #pragma unroll
;       for (int i = 0; i < 4; ++i)
; #pragma unroll
;         for (int j = 0; j < 2; ++j) acc[i][j] = mfma32(bf[j], af[i], acc[i][j]);
;     }
;     __syncthreads();
	ds_read_b128 v[232:235], v212
	ds_read_b128 v[188:191], v194
	ds_read_b128 v[236:239], v212 offset:4608
	ds_read_b128 v[200:203], v194 offset:4608
	ds_read_b128 v[204:207], v194 offset:9216
	ds_read_b128 v[208:211], v194 offset:13824
	v_mfma_f32_32x32x16_f16 v[114:129], v[240:243], v[216:219], v[114:129]
	v_mfma_f32_32x32x16_f16 v[98:113], v[244:247], v[216:219], v[98:113]
	v_mfma_f32_32x32x16_f16 v[82:97], v[240:243], v[220:223], v[82:97]
	v_mfma_f32_32x32x16_f16 v[66:81], v[244:247], v[220:223], v[66:81]
	v_mfma_f32_32x32x16_f16 v[50:65], v[240:243], v[224:227], v[50:65]
	v_mfma_f32_32x32x16_f16 v[34:49], v[244:247], v[224:227], v[34:49]
	v_mfma_f32_32x32x16_f16 v[18:33], v[240:243], v[228:231], v[18:33]
	v_mfma_f32_32x32x16_f16 v[2:17], v[244:247], v[228:231], v[2:17]
	ds_read_b128 v[240:243], v212 offset:32
	ds_read_b128 v[216:219], v194 offset:32
	ds_read_b128 v[244:247], v212 offset:4640
	ds_read_b128 v[220:223], v194 offset:4640
	ds_read_b128 v[224:227], v194 offset:9248
	ds_read_b128 v[228:231], v194 offset:13856
	s_waitcnt vmcnt(4)
	ds_write_b128 v175, v[130:133]
	ds_write_b128 v175, v[134:137] offset:16
	ds_write_b128 v175, v[138:141] offset:32
	ds_write_b128 v175, v[142:145] offset:48
	global_load_dwordx4 v[130:133], v[164:165], off offset:768
	global_load_dwordx4 v[134:137], v[164:165], off offset:784
	global_load_dwordx4 v[138:141], v[164:165], off offset:800
	global_load_dwordx4 v[142:145], v[164:165], off offset:816
	s_waitcnt lgkmcnt(14)
	v_mfma_f32_32x32x16_f16 v[114:129], v[232:235], v[188:191], v[114:129]
	s_waitcnt lgkmcnt(13)
	v_mfma_f32_32x32x16_f16 v[98:113], v[236:239], v[188:191], v[98:113]
	s_waitcnt lgkmcnt(12)
	v_mfma_f32_32x32x16_f16 v[82:97], v[232:235], v[200:203], v[82:97]
	v_mfma_f32_32x32x16_f16 v[66:81], v[236:239], v[200:203], v[66:81]
	s_waitcnt lgkmcnt(11)
	v_mfma_f32_32x32x16_f16 v[50:65], v[232:235], v[204:207], v[50:65]
	v_mfma_f32_32x32x16_f16 v[34:49], v[236:239], v[204:207], v[34:49]
	s_waitcnt lgkmcnt(10)
	v_mfma_f32_32x32x16_f16 v[18:33], v[232:235], v[208:211], v[18:33]
	v_mfma_f32_32x32x16_f16 v[2:17], v[236:239], v[208:211], v[2:17]
	ds_read_b128 v[232:235], v212 offset:64
	ds_read_b128 v[188:191], v194 offset:64
	ds_read_b128 v[236:239], v212 offset:4672
	ds_read_b128 v[200:203], v194 offset:4672
	ds_read_b128 v[204:207], v194 offset:9280
	ds_read_b128 v[208:211], v194 offset:13888
	s_waitcnt vmcnt(4)
	ds_write_b128 v175, v[146:149] offset:36864
	ds_write_b128 v175, v[150:153] offset:36880
	ds_write_b128 v175, v[154:157] offset:36896
	ds_write_b128 v175, v[158:161] offset:36912
	global_load_dwordx4 v[146:149], v[192:193], off offset:768
	global_load_dwordx4 v[150:153], v[192:193], off offset:784
	global_load_dwordx4 v[154:157], v[192:193], off offset:800
	global_load_dwordx4 v[158:161], v[192:193], off offset:816
	s_waitcnt lgkmcnt(15)
	v_mfma_f32_32x32x16_f16 v[114:129], v[240:243], v[216:219], v[114:129]
	s_waitcnt lgkmcnt(15)
	v_mfma_f32_32x32x16_f16 v[98:113], v[244:247], v[216:219], v[98:113]
	s_waitcnt lgkmcnt(15)
	v_mfma_f32_32x32x16_f16 v[82:97], v[240:243], v[220:223], v[82:97]
	v_mfma_f32_32x32x16_f16 v[66:81], v[244:247], v[220:223], v[66:81]
	s_waitcnt lgkmcnt(15)
	v_mfma_f32_32x32x16_f16 v[50:65], v[240:243], v[224:227], v[50:65]
	v_mfma_f32_32x32x16_f16 v[34:49], v[244:247], v[224:227], v[34:49]
	s_waitcnt lgkmcnt(14)
	v_mfma_f32_32x32x16_f16 v[18:33], v[240:243], v[228:231], v[18:33]
	v_mfma_f32_32x32x16_f16 v[2:17], v[244:247], v[228:231], v[2:17]
	ds_read_b128 v[240:243], v212 offset:96
	ds_read_b128 v[216:219], v194 offset:96
	ds_read_b128 v[244:247], v212 offset:4704
	ds_read_b128 v[220:223], v194 offset:4704
	ds_read_b128 v[224:227], v194 offset:9312
	ds_read_b128 v[228:231], v194 offset:13920
	s_waitcnt lgkmcnt(14)
	v_mfma_f32_32x32x16_f16 v[114:129], v[232:235], v[188:191], v[114:129]
	s_waitcnt lgkmcnt(13)
	v_mfma_f32_32x32x16_f16 v[98:113], v[236:239], v[188:191], v[98:113]
	s_waitcnt lgkmcnt(12)
	v_mfma_f32_32x32x16_f16 v[82:97], v[232:235], v[200:203], v[82:97]
	v_mfma_f32_32x32x16_f16 v[66:81], v[236:239], v[200:203], v[66:81]
	s_waitcnt lgkmcnt(11)
	v_mfma_f32_32x32x16_f16 v[50:65], v[232:235], v[204:207], v[50:65]
	v_mfma_f32_32x32x16_f16 v[34:49], v[236:239], v[204:207], v[34:49]
	s_waitcnt lgkmcnt(10)
	v_mfma_f32_32x32x16_f16 v[18:33], v[232:235], v[208:211], v[18:33]
	v_mfma_f32_32x32x16_f16 v[2:17], v[236:239], v[208:211], v[2:17]
	s_waitcnt lgkmcnt(0)
	s_barrier
; DI f16v mfma32(h8v a, h8v b, f16v c) { return __builtin_amdgcn_mfma_f32_32x32x16_f16(a, b, c, 0, 0, 0); }
; template <bool GATHER>
; DI void gemm256_main(const h16* __restrict__ A, int lda, const int* __restrict__ idx, int m0,
;                      const h16* __restrict__ B, int ldb, int n0, int K, h16* lds, f16v (&acc)[4][2]) {
;     ...
;   for (int kt = 0; kt < nk; ++kt) {
;     const h16* As = lds + (kt & 1) * (512 * LDH);
;     const h16* Bs = As + 256 * LDH;
;     h16* Wn = lds + ((kt & 1) ^ 1) * (512 * LDH);
;     if (kt + 1 < nk) {
; #pragma unroll
;       for (int i = 0; i < 4; ++i) { *(u4v*)&Wn[lr * LDH + lc + 8 * i] = ra[i]; *(u4v*)&Wn[(256 + lr) * LDH + lc + 8 * i] = rb[i]; }
;     }
;     if (kt + 2 < nk) {
; #pragma unroll
;       for (int i = 0; i < 4; ++i) { ra[i] = *(const u4v*)(AP_ + 8 * i); rb[i] = *(const u4v*)(BP_ + 8 * i); }
;       ao += 64; bo += 64;
;     }
; #pragma unroll
;     for (int ks = 0; ks < 4; ++ks) {
;       h8v af[4], bf[2];
; #pragma unroll
;       for (int i = 0; i < 4; ++i) af[i] = *(const h8v*)&As[(wm * 128 + i * 32 + (lane & 31)) * LDH + ks * 16 + 8 * (lane >> 5)];
; #pragma unroll
;       for (int j = 0; j < 2; ++j) bf[j] = *(const h8v*)&Bs[(wn * 64 + j * 32 + (lane & 31)) * LDH + ks * 16 + 8 * (lane >> 5)];
; #pragma unroll
;       for (int i = 0; i < 4; ++i)
; #pragma unroll
;         for (int j = 0; j < 2; ++j) acc[i][j] = mfma32(bf[j], af[i], acc[i][j]);
;     }
;     __syncthreads();
	ds_read_b128 v[232:235], v213
	ds_read_b128 v[188:191], v199
	ds_read_b128 v[236:239], v213 offset:4608
	ds_read_b128 v[200:203], v199 offset:4608
	ds_read_b128 v[204:207], v199 offset:9216
	ds_read_b128 v[208:211], v199 offset:13824
	v_mfma_f32_32x32x16_f16 v[114:129], v[240:243], v[216:219], v[114:129]
	v_mfma_f32_32x32x16_f16 v[98:113], v[244:247], v[216:219], v[98:113]
	v_mfma_f32_32x32x16_f16 v[82:97], v[240:243], v[220:223], v[82:97]
	v_mfma_f32_32x32x16_f16 v[66:81], v[244:247], v[220:223], v[66:81]
	v_mfma_f32_32x32x16_f16 v[50:65], v[240:243], v[224:227], v[50:65]
	v_mfma_f32_32x32x16_f16 v[34:49], v[244:247], v[224:227], v[34:49]
	v_mfma_f32_32x32x16_f16 v[18:33], v[240:243], v[228:231], v[18:33]
	v_mfma_f32_32x32x16_f16 v[2:17], v[244:247], v[228:231], v[2:17]
	ds_read_b128 v[240:243], v213 offset:32
	ds_read_b128 v[216:219], v199 offset:32
	ds_read_b128 v[244:247], v213 offset:4640
	ds_read_b128 v[220:223], v199 offset:4640
	ds_read_b128 v[224:227], v199 offset:9248
	ds_read_b128 v[228:231], v199 offset:13856
	s_waitcnt vmcnt(4)
	ds_write_b128 v163, v[130:133]
	ds_write_b128 v163, v[134:137] offset:16
	ds_write_b128 v163, v[138:141] offset:32
	ds_write_b128 v163, v[142:145] offset:48
	global_load_dwordx4 v[130:133], v[164:165], off offset:896
	global_load_dwordx4 v[134:137], v[164:165], off offset:912
	global_load_dwordx4 v[138:141], v[164:165], off offset:928
	global_load_dwordx4 v[142:145], v[164:165], off offset:944
	s_waitcnt lgkmcnt(14)
	v_mfma_f32_32x32x16_f16 v[114:129], v[232:235], v[188:191], v[114:129]
	s_waitcnt lgkmcnt(13)
	v_mfma_f32_32x32x16_f16 v[98:113], v[236:239], v[188:191], v[98:113]
	s_waitcnt lgkmcnt(12)
	v_mfma_f32_32x32x16_f16 v[82:97], v[232:235], v[200:203], v[82:97]
	v_mfma_f32_32x32x16_f16 v[66:81], v[236:239], v[200:203], v[66:81]
	s_waitcnt lgkmcnt(11)
	v_mfma_f32_32x32x16_f16 v[50:65], v[232:235], v[204:207], v[50:65]
	v_mfma_f32_32x32x16_f16 v[34:49], v[236:239], v[204:207], v[34:49]
	s_waitcnt lgkmcnt(10)
	v_mfma_f32_32x32x16_f16 v[18:33], v[232:235], v[208:211], v[18:33]
	v_mfma_f32_32x32x16_f16 v[2:17], v[236:239], v[208:211], v[2:17]
	ds_read_b128 v[232:235], v213 offset:64
	ds_read_b128 v[188:191], v199 offset:64
	ds_read_b128 v[236:239], v213 offset:4672
	ds_read_b128 v[200:203], v199 offset:4672
	ds_read_b128 v[204:207], v199 offset:9280
	ds_read_b128 v[208:211], v199 offset:13888
	s_waitcnt vmcnt(4)
	ds_write_b128 v163, v[146:149] offset:36864
	ds_write_b128 v163, v[150:153] offset:36880
	ds_write_b128 v163, v[154:157] offset:36896
	ds_write_b128 v163, v[158:161] offset:36912
	global_load_dwordx4 v[146:149], v[192:193], off offset:896
	global_load_dwordx4 v[150:153], v[192:193], off offset:912
	global_load_dwordx4 v[154:157], v[192:193], off offset:928
	global_load_dwordx4 v[158:161], v[192:193], off offset:944
	s_waitcnt lgkmcnt(15)
	v_mfma_f32_32x32x16_f16 v[114:129], v[240:243], v[216:219], v[114:129]
	s_waitcnt lgkmcnt(15)
	v_mfma_f32_32x32x16_f16 v[98:113], v[244:247], v[216:219], v[98:113]
	s_waitcnt lgkmcnt(15)
	v_mfma_f32_32x32x16_f16 v[82:97], v[240:243], v[220:223], v[82:97]
	v_mfma_f32_32x32x16_f16 v[66:81], v[244:247], v[220:223], v[66:81]
	s_waitcnt lgkmcnt(15)
	v_mfma_f32_32x32x16_f16 v[50:65], v[240:243], v[224:227], v[50:65]
	v_mfma_f32_32x32x16_f16 v[34:49], v[244:247], v[224:227], v[34:49]
	s_waitcnt lgkmcnt(14)
	v_mfma_f32_32x32x16_f16 v[18:33], v[240:243], v[228:231], v[18:33]
	v_mfma_f32_32x32x16_f16 v[2:17], v[244:247], v[228:231], v[2:17]
	ds_read_b128 v[240:243], v213 offset:96
	ds_read_b128 v[216:219], v199 offset:96
	ds_read_b128 v[244:247], v213 offset:4704
	ds_read_b128 v[220:223], v199 offset:4704
	ds_read_b128 v[224:227], v199 offset:9312
	ds_read_b128 v[228:231], v199 offset:13920
	s_waitcnt lgkmcnt(14)
	v_mfma_f32_32x32x16_f16 v[114:129], v[232:235], v[188:191], v[114:129]
	s_waitcnt lgkmcnt(13)
	v_mfma_f32_32x32x16_f16 v[98:113], v[236:239], v[188:191], v[98:113]
	s_waitcnt lgkmcnt(12)
	v_mfma_f32_32x32x16_f16 v[82:97], v[232:235], v[200:203], v[82:97]
	v_mfma_f32_32x32x16_f16 v[66:81], v[236:239], v[200:203], v[66:81]
	s_waitcnt lgkmcnt(11)
	v_mfma_f32_32x32x16_f16 v[50:65], v[232:235], v[204:207], v[50:65]
	v_mfma_f32_32x32x16_f16 v[34:49], v[236:239], v[204:207], v[34:49]
	s_waitcnt lgkmcnt(10)
	v_mfma_f32_32x32x16_f16 v[18:33], v[232:235], v[208:211], v[18:33]
	v_mfma_f32_32x32x16_f16 v[2:17], v[236:239], v[208:211], v[2:17]
	s_waitcnt lgkmcnt(0)
	s_barrier
; DI f16v mfma32(h8v a, h8v b, f16v c) { return __builtin_amdgcn_mfma_f32_32x32x16_f16(a, b, c, 0, 0, 0); }
; template <bool GATHER>
; DI void gemm256_main(const h16* __restrict__ A, int lda, const int* __restrict__ idx, int m0,
;                      const h16* __restrict__ B, int ldb, int n0, int K, h16* lds, f16v (&acc)[4][2]) {
;     ...
;   for (int kt = 0; kt < nk; ++kt) {
;     const h16* As = lds + (kt & 1) * (512 * LDH);
;     const h16* Bs = As + 256 * LDH;
;     h16* Wn = lds + ((kt & 1) ^ 1) * (512 * LDH);
;     if (kt + 1 < nk) {
; #pragma unroll
;       for (int i = 0; i < 4; ++i) { *(u4v*)&Wn[lr * LDH + lc + 8 * i] = ra[i]; *(u4v*)&Wn[(256 + lr) * LDH + lc + 8 * i] = rb[i]; }
;     }
;     if (kt + 2 < nk) {
; #pragma unroll
;       for (int i = 0; i < 4; ++i) { ra[i] = *(const u4v*)(AP_ + 8 * i); rb[i] = *(const u4v*)(BP_ + 8 * i); }
;       ao += 64; bo += 64;
;     }
; #pragma unroll
;     for (int ks = 0; ks < 4; ++ks) {
;       h8v af[4], bf[2];
; #pragma unroll
;       for (int i = 0; i < 4; ++i) af[i] = *(const h8v*)&As[(wm * 128 + i * 32 + (lane & 31)) * LDH + ks * 16 + 8 * (lane >> 5)];
; #pragma unroll
;       for (int j = 0; j < 2; ++j) bf[j] = *(const h8v*)&Bs[(wn * 64 + j * 32 + (lane & 31)) * LDH + ks * 16 + 8 * (lane >> 5)];
; #pragma unroll
;       for (int i = 0; i < 4; ++i)
; #pragma unroll
;         for (int j = 0; j < 2; ++j) acc[i][j] = mfma32(bf[j], af[i], acc[i][j]);
;     }
;     __syncthreads();
	ds_read_b128 v[232:235], v212
	ds_read_b128 v[188:191], v194
	ds_read_b128 v[236:239], v212 offset:4608
	ds_read_b128 v[200:203], v194 offset:4608
	ds_read_b128 v[204:207], v194 offset:9216
	ds_read_b128 v[208:211], v194 offset:13824
	v_mfma_f32_32x32x16_f16 v[114:129], v[240:243], v[216:219], v[114:129]
	v_mfma_f32_32x32x16_f16 v[98:113], v[244:247], v[216:219], v[98:113]
	v_mfma_f32_32x32x16_f16 v[82:97], v[240:243], v[220:223], v[82:97]
	v_mfma_f32_32x32x16_f16 v[66:81], v[244:247], v[220:223], v[66:81]
	v_mfma_f32_32x32x16_f16 v[50:65], v[240:243], v[224:227], v[50:65]
	v_mfma_f32_32x32x16_f16 v[34:49], v[244:247], v[224:227], v[34:49]
	v_mfma_f32_32x32x16_f16 v[18:33], v[240:243], v[228:231], v[18:33]
	v_mfma_f32_32x32x16_f16 v[2:17], v[244:247], v[228:231], v[2:17]
	ds_read_b128 v[240:243], v212 offset:32
	ds_read_b128 v[216:219], v194 offset:32
	ds_read_b128 v[244:247], v212 offset:4640
	ds_read_b128 v[220:223], v194 offset:4640
	ds_read_b128 v[224:227], v194 offset:9248
	ds_read_b128 v[228:231], v194 offset:13856
	s_waitcnt vmcnt(4)
	ds_write_b128 v175, v[130:133]
	ds_write_b128 v175, v[134:137] offset:16
	ds_write_b128 v175, v[138:141] offset:32
	ds_write_b128 v175, v[142:145] offset:48
	global_load_dwordx4 v[130:133], v[164:165], off offset:1024
	global_load_dwordx4 v[134:137], v[164:165], off offset:1040
	global_load_dwordx4 v[138:141], v[164:165], off offset:1056
	global_load_dwordx4 v[142:145], v[164:165], off offset:1072
	s_waitcnt lgkmcnt(14)
	v_mfma_f32_32x32x16_f16 v[114:129], v[232:235], v[188:191], v[114:129]
	s_waitcnt lgkmcnt(13)
	v_mfma_f32_32x32x16_f16 v[98:113], v[236:239], v[188:191], v[98:113]
	s_waitcnt lgkmcnt(12)
	v_mfma_f32_32x32x16_f16 v[82:97], v[232:235], v[200:203], v[82:97]
	v_mfma_f32_32x32x16_f16 v[66:81], v[236:239], v[200:203], v[66:81]
	s_waitcnt lgkmcnt(11)
	v_mfma_f32_32x32x16_f16 v[50:65], v[232:235], v[204:207], v[50:65]
	v_mfma_f32_32x32x16_f16 v[34:49], v[236:239], v[204:207], v[34:49]
	s_waitcnt lgkmcnt(10)
	v_mfma_f32_32x32x16_f16 v[18:33], v[232:235], v[208:211], v[18:33]
	v_mfma_f32_32x32x16_f16 v[2:17], v[236:239], v[208:211], v[2:17]
	ds_read_b128 v[232:235], v212 offset:64
	ds_read_b128 v[188:191], v194 offset:64
	ds_read_b128 v[236:239], v212 offset:4672
	ds_read_b128 v[200:203], v194 offset:4672
	ds_read_b128 v[204:207], v194 offset:9280
	ds_read_b128 v[208:211], v194 offset:13888
	s_waitcnt vmcnt(4)
	ds_write_b128 v175, v[146:149] offset:36864
	ds_write_b128 v175, v[150:153] offset:36880
	ds_write_b128 v175, v[154:157] offset:36896
	ds_write_b128 v175, v[158:161] offset:36912
	global_load_dwordx4 v[146:149], v[192:193], off offset:1024
	global_load_dwordx4 v[150:153], v[192:193], off offset:1040
	global_load_dwordx4 v[154:157], v[192:193], off offset:1056
	global_load_dwordx4 v[158:161], v[192:193], off offset:1072
	s_waitcnt lgkmcnt(15)
	v_mfma_f32_32x32x16_f16 v[114:129], v[240:243], v[216:219], v[114:129]
	s_waitcnt lgkmcnt(15)
	v_mfma_f32_32x32x16_f16 v[98:113], v[244:247], v[216:219], v[98:113]
	s_waitcnt lgkmcnt(15)
	v_mfma_f32_32x32x16_f16 v[82:97], v[240:243], v[220:223], v[82:97]
	v_mfma_f32_32x32x16_f16 v[66:81], v[244:247], v[220:223], v[66:81]
	s_waitcnt lgkmcnt(15)
	v_mfma_f32_32x32x16_f16 v[50:65], v[240:243], v[224:227], v[50:65]
	v_mfma_f32_32x32x16_f16 v[34:49], v[244:247], v[224:227], v[34:49]
	s_waitcnt lgkmcnt(14)
	v_mfma_f32_32x32x16_f16 v[18:33], v[240:243], v[228:231], v[18:33]
	v_mfma_f32_32x32x16_f16 v[2:17], v[244:247], v[228:231], v[2:17]
	ds_read_b128 v[240:243], v212 offset:96
	ds_read_b128 v[216:219], v194 offset:96
	ds_read_b128 v[244:247], v212 offset:4704
	ds_read_b128 v[220:223], v194 offset:4704
	ds_read_b128 v[224:227], v194 offset:9312
	ds_read_b128 v[228:231], v194 offset:13920
	s_waitcnt lgkmcnt(14)
	v_mfma_f32_32x32x16_f16 v[114:129], v[232:235], v[188:191], v[114:129]
	s_waitcnt lgkmcnt(13)
	v_mfma_f32_32x32x16_f16 v[98:113], v[236:239], v[188:191], v[98:113]
	s_waitcnt lgkmcnt(12)
	v_mfma_f32_32x32x16_f16 v[82:97], v[232:235], v[200:203], v[82:97]
	v_mfma_f32_32x32x16_f16 v[66:81], v[236:239], v[200:203], v[66:81]
	s_waitcnt lgkmcnt(11)
	v_mfma_f32_32x32x16_f16 v[50:65], v[232:235], v[204:207], v[50:65]
	v_mfma_f32_32x32x16_f16 v[34:49], v[236:239], v[204:207], v[34:49]
	s_waitcnt lgkmcnt(10)
	v_mfma_f32_32x32x16_f16 v[18:33], v[232:235], v[208:211], v[18:33]
	v_mfma_f32_32x32x16_f16 v[2:17], v[236:239], v[208:211], v[2:17]
	s_waitcnt lgkmcnt(0)
	s_barrier
; DI f16v mfma32(h8v a, h8v b, f16v c) { return __builtin_amdgcn_mfma_f32_32x32x16_f16(a, b, c, 0, 0, 0); }
; template <bool GATHER>
; DI void gemm256_main(const h16* __restrict__ A, int lda, const int* __restrict__ idx, int m0,
;                      const h16* __restrict__ B, int ldb, int n0, int K, h16* lds, f16v (&acc)[4][2]) {
;     ...
;   for (int kt = 0; kt < nk; ++kt) {
;     const h16* As = lds + (kt & 1) * (512 * LDH);
;     const h16* Bs = As + 256 * LDH;
;     h16* Wn = lds + ((kt & 1) ^ 1) * (512 * LDH);
;     if (kt + 1 < nk) {
; #pragma unroll
;       for (int i = 0; i < 4; ++i) { *(u4v*)&Wn[lr * LDH + lc + 8 * i] = ra[i]; *(u4v*)&Wn[(256 + lr) * LDH + lc + 8 * i] = rb[i]; }
;     }
;     if (kt + 2 < nk) {
; #pragma unroll
;       for (int i = 0; i < 4; ++i) { ra[i] = *(const u4v*)(AP_ + 8 * i); rb[i] = *(const u4v*)(BP_ + 8 * i); }
;       ao += 64; bo += 64;
;     }
; #pragma unroll
;     for (int ks = 0; ks < 4; ++ks) {
;       h8v af[4], bf[2];
; #pragma unroll
;       for (int i = 0; i < 4; ++i) af[i] = *(const h8v*)&As[(wm * 128 + i * 32 + (lane & 31)) * LDH + ks * 16 + 8 * (lane >> 5)];
; #pragma unroll
;       for (int j = 0; j < 2; ++j) bf[j] = *(const h8v*)&Bs[(wn * 64 + j * 32 + (lane & 31)) * LDH + ks * 16 + 8 * (lane >> 5)];
; #pragma unroll
;       for (int i = 0; i < 4; ++i)
; #pragma unroll
;         for (int j = 0; j < 2; ++j) acc[i][j] = mfma32(bf[j], af[i], acc[i][j]);
;     }
;     __syncthreads();
	ds_read_b128 v[232:235], v213
	ds_read_b128 v[188:191], v199
	ds_read_b128 v[236:239], v213 offset:4608
	ds_read_b128 v[200:203], v199 offset:4608
	ds_read_b128 v[204:207], v199 offset:9216
	ds_read_b128 v[208:211], v199 offset:13824
	v_mfma_f32_32x32x16_f16 v[114:129], v[240:243], v[216:219], v[114:129]
	v_mfma_f32_32x32x16_f16 v[98:113], v[244:247], v[216:219], v[98:113]
	v_mfma_f32_32x32x16_f16 v[82:97], v[240:243], v[220:223], v[82:97]
	v_mfma_f32_32x32x16_f16 v[66:81], v[244:247], v[220:223], v[66:81]
	v_mfma_f32_32x32x16_f16 v[50:65], v[240:243], v[224:227], v[50:65]
	v_mfma_f32_32x32x16_f16 v[34:49], v[244:247], v[224:227], v[34:49]
	v_mfma_f32_32x32x16_f16 v[18:33], v[240:243], v[228:231], v[18:33]
	v_mfma_f32_32x32x16_f16 v[2:17], v[244:247], v[228:231], v[2:17]
	ds_read_b128 v[240:243], v213 offset:32
	ds_read_b128 v[216:219], v199 offset:32
	ds_read_b128 v[244:247], v213 offset:4640
	ds_read_b128 v[220:223], v199 offset:4640
	ds_read_b128 v[224:227], v199 offset:9248
	ds_read_b128 v[228:231], v199 offset:13856
	s_waitcnt vmcnt(4)
	ds_write_b128 v163, v[130:133]
	ds_write_b128 v163, v[134:137] offset:16
	ds_write_b128 v163, v[138:141] offset:32
	ds_write_b128 v163, v[142:145] offset:48
	global_load_dwordx4 v[130:133], v[164:165], off offset:1152
	global_load_dwordx4 v[134:137], v[164:165], off offset:1168
	global_load_dwordx4 v[138:141], v[164:165], off offset:1184
	global_load_dwordx4 v[142:145], v[164:165], off offset:1200
	s_waitcnt lgkmcnt(14)
	v_mfma_f32_32x32x16_f16 v[114:129], v[232:235], v[188:191], v[114:129]
	s_waitcnt lgkmcnt(13)
	v_mfma_f32_32x32x16_f16 v[98:113], v[236:239], v[188:191], v[98:113]
	s_waitcnt lgkmcnt(12)
	v_mfma_f32_32x32x16_f16 v[82:97], v[232:235], v[200:203], v[82:97]
	v_mfma_f32_32x32x16_f16 v[66:81], v[236:239], v[200:203], v[66:81]
	s_waitcnt lgkmcnt(11)
	v_mfma_f32_32x32x16_f16 v[50:65], v[232:235], v[204:207], v[50:65]
	v_mfma_f32_32x32x16_f16 v[34:49], v[236:239], v[204:207], v[34:49]
	s_waitcnt lgkmcnt(10)
	v_mfma_f32_32x32x16_f16 v[18:33], v[232:235], v[208:211], v[18:33]
	v_mfma_f32_32x32x16_f16 v[2:17], v[236:239], v[208:211], v[2:17]
	ds_read_b128 v[232:235], v213 offset:64
	ds_read_b128 v[188:191], v199 offset:64
	ds_read_b128 v[236:239], v213 offset:4672
	ds_read_b128 v[200:203], v199 offset:4672
	ds_read_b128 v[204:207], v199 offset:9280
	ds_read_b128 v[208:211], v199 offset:13888
	s_waitcnt vmcnt(4)
	ds_write_b128 v163, v[146:149] offset:36864
	ds_write_b128 v163, v[150:153] offset:36880
	ds_write_b128 v163, v[154:157] offset:36896
	ds_write_b128 v163, v[158:161] offset:36912
	global_load_dwordx4 v[146:149], v[192:193], off offset:1152
	global_load_dwordx4 v[150:153], v[192:193], off offset:1168
	global_load_dwordx4 v[154:157], v[192:193], off offset:1184
	global_load_dwordx4 v[158:161], v[192:193], off offset:1200
	s_waitcnt lgkmcnt(15)
	v_mfma_f32_32x32x16_f16 v[114:129], v[240:243], v[216:219], v[114:129]
	s_waitcnt lgkmcnt(15)
	v_mfma_f32_32x32x16_f16 v[98:113], v[244:247], v[216:219], v[98:113]
	s_waitcnt lgkmcnt(15)
	v_mfma_f32_32x32x16_f16 v[82:97], v[240:243], v[220:223], v[82:97]
	v_mfma_f32_32x32x16_f16 v[66:81], v[244:247], v[220:223], v[66:81]
	s_waitcnt lgkmcnt(15)
	v_mfma_f32_32x32x16_f16 v[50:65], v[240:243], v[224:227], v[50:65]
	v_mfma_f32_32x32x16_f16 v[34:49], v[244:247], v[224:227], v[34:49]
	s_waitcnt lgkmcnt(14)
	v_mfma_f32_32x32x16_f16 v[18:33], v[240:243], v[228:231], v[18:33]
	v_mfma_f32_32x32x16_f16 v[2:17], v[244:247], v[228:231], v[2:17]
	ds_read_b128 v[240:243], v213 offset:96
	ds_read_b128 v[216:219], v199 offset:96
	ds_read_b128 v[244:247], v213 offset:4704
	ds_read_b128 v[220:223], v199 offset:4704
	ds_read_b128 v[224:227], v199 offset:9312
	ds_read_b128 v[228:231], v199 offset:13920
	s_waitcnt lgkmcnt(14)
	v_mfma_f32_32x32x16_f16 v[114:129], v[232:235], v[188:191], v[114:129]
	s_waitcnt lgkmcnt(13)
	v_mfma_f32_32x32x16_f16 v[98:113], v[236:239], v[188:191], v[98:113]
	s_waitcnt lgkmcnt(12)
	v_mfma_f32_32x32x16_f16 v[82:97], v[232:235], v[200:203], v[82:97]
	v_mfma_f32_32x32x16_f16 v[66:81], v[236:239], v[200:203], v[66:81]
	s_waitcnt lgkmcnt(11)
	v_mfma_f32_32x32x16_f16 v[50:65], v[232:235], v[204:207], v[50:65]
	v_mfma_f32_32x32x16_f16 v[34:49], v[236:239], v[204:207], v[34:49]
	s_waitcnt lgkmcnt(10)
	v_mfma_f32_32x32x16_f16 v[18:33], v[232:235], v[208:211], v[18:33]
	v_mfma_f32_32x32x16_f16 v[2:17], v[236:239], v[208:211], v[2:17]
	s_waitcnt lgkmcnt(0)
	s_barrier
; DI f16v mfma32(h8v a, h8v b, f16v c) { return __builtin_amdgcn_mfma_f32_32x32x16_f16(a, b, c, 0, 0, 0); }
; template <bool GATHER>
; DI void gemm256_main(const h16* __restrict__ A, int lda, const int* __restrict__ idx, int m0,
;                      const h16* __restrict__ B, int ldb, int n0, int K, h16* lds, f16v (&acc)[4][2]) {
;     ...
;   for (int kt = 0; kt < nk; ++kt) {
;     const h16* As = lds + (kt & 1) * (512 * LDH);
;     const h16* Bs = As + 256 * LDH;
;     h16* Wn = lds + ((kt & 1) ^ 1) * (512 * LDH);
;     if (kt + 1 < nk) {
; #pragma unroll
;       for (int i = 0; i < 4; ++i) { *(u4v*)&Wn[lr * LDH + lc + 8 * i] = ra[i]; *(u4v*)&Wn[(256 + lr) * LDH + lc + 8 * i] = rb[i]; }
;     }
;     if (kt + 2 < nk) {
; #pragma unroll
;       for (int i = 0; i < 4; ++i) { ra[i] = *(const u4v*)(AP_ + 8 * i); rb[i] = *(const u4v*)(BP_ + 8 * i); }
;       ao += 64; bo += 64;
;     }
; #pragma unroll
;     for (int ks = 0; ks < 4; ++ks) {
;       h8v af[4], bf[2];
; #pragma unroll
;       for (int i = 0; i < 4; ++i) af[i] = *(const h8v*)&As[(wm * 128 + i * 32 + (lane & 31)) * LDH + ks * 16 + 8 * (lane >> 5)];
; #pragma unroll
;       for (int j = 0; j < 2; ++j) bf[j] = *(const h8v*)&Bs[(wn * 64 + j * 32 + (lane & 31)) * LDH + ks * 16 + 8 * (lane >> 5)];
; #pragma unroll
;       for (int i = 0; i < 4; ++i)
; #pragma unroll
;         for (int j = 0; j < 2; ++j) acc[i][j] = mfma32(bf[j], af[i], acc[i][j]);
;     }
;     __syncthreads();
	ds_read_b128 v[232:235], v212
	ds_read_b128 v[188:191], v194
	ds_read_b128 v[236:239], v212 offset:4608
	ds_read_b128 v[200:203], v194 offset:4608
	ds_read_b128 v[204:207], v194 offset:9216
	ds_read_b128 v[208:211], v194 offset:13824
	v_mfma_f32_32x32x16_f16 v[114:129], v[240:243], v[216:219], v[114:129]
	v_mfma_f32_32x32x16_f16 v[98:113], v[244:247], v[216:219], v[98:113]
	v_mfma_f32_32x32x16_f16 v[82:97], v[240:243], v[220:223], v[82:97]
	v_mfma_f32_32x32x16_f16 v[66:81], v[244:247], v[220:223], v[66:81]
	v_mfma_f32_32x32x16_f16 v[50:65], v[240:243], v[224:227], v[50:65]
	v_mfma_f32_32x32x16_f16 v[34:49], v[244:247], v[224:227], v[34:49]
	v_mfma_f32_32x32x16_f16 v[18:33], v[240:243], v[228:231], v[18:33]
	v_mfma_f32_32x32x16_f16 v[2:17], v[244:247], v[228:231], v[2:17]
	ds_read_b128 v[240:243], v212 offset:32
	ds_read_b128 v[216:219], v194 offset:32
	ds_read_b128 v[244:247], v212 offset:4640
	ds_read_b128 v[220:223], v194 offset:4640
	ds_read_b128 v[224:227], v194 offset:9248
	ds_read_b128 v[228:231], v194 offset:13856
	s_waitcnt vmcnt(4)
	ds_write_b128 v175, v[130:133]
	ds_write_b128 v175, v[134:137] offset:16
	ds_write_b128 v175, v[138:141] offset:32
	ds_write_b128 v175, v[142:145] offset:48
	global_load_dwordx4 v[130:133], v[164:165], off offset:1280
	global_load_dwordx4 v[134:137], v[164:165], off offset:1296
	global_load_dwordx4 v[138:141], v[164:165], off offset:1312
	global_load_dwordx4 v[142:145], v[164:165], off offset:1328
	s_waitcnt lgkmcnt(14)
	v_mfma_f32_32x32x16_f16 v[114:129], v[232:235], v[188:191], v[114:129]
	s_waitcnt lgkmcnt(13)
	v_mfma_f32_32x32x16_f16 v[98:113], v[236:239], v[188:191], v[98:113]
	s_waitcnt lgkmcnt(12)
	v_mfma_f32_32x32x16_f16 v[82:97], v[232:235], v[200:203], v[82:97]
	v_mfma_f32_32x32x16_f16 v[66:81], v[236:239], v[200:203], v[66:81]
	s_waitcnt lgkmcnt(11)
	v_mfma_f32_32x32x16_f16 v[50:65], v[232:235], v[204:207], v[50:65]
	v_mfma_f32_32x32x16_f16 v[34:49], v[236:239], v[204:207], v[34:49]
	s_waitcnt lgkmcnt(10)
	v_mfma_f32_32x32x16_f16 v[18:33], v[232:235], v[208:211], v[18:33]
	v_mfma_f32_32x32x16_f16 v[2:17], v[236:239], v[208:211], v[2:17]
	ds_read_b128 v[232:235], v212 offset:64
	ds_read_b128 v[188:191], v194 offset:64
	ds_read_b128 v[236:239], v212 offset:4672
	ds_read_b128 v[200:203], v194 offset:4672
	ds_read_b128 v[204:207], v194 offset:9280
	ds_read_b128 v[208:211], v194 offset:13888
	s_waitcnt vmcnt(4)
	ds_write_b128 v175, v[146:149] offset:36864
	ds_write_b128 v175, v[150:153] offset:36880
	ds_write_b128 v175, v[154:157] offset:36896
	ds_write_b128 v175, v[158:161] offset:36912
	global_load_dwordx4 v[146:149], v[192:193], off offset:1280
	global_load_dwordx4 v[150:153], v[192:193], off offset:1296
	global_load_dwordx4 v[154:157], v[192:193], off offset:1312
	global_load_dwordx4 v[158:161], v[192:193], off offset:1328
	s_waitcnt lgkmcnt(15)
	v_mfma_f32_32x32x16_f16 v[114:129], v[240:243], v[216:219], v[114:129]
	s_waitcnt lgkmcnt(15)
	v_mfma_f32_32x32x16_f16 v[98:113], v[244:247], v[216:219], v[98:113]
	s_waitcnt lgkmcnt(15)
	v_mfma_f32_32x32x16_f16 v[82:97], v[240:243], v[220:223], v[82:97]
	v_mfma_f32_32x32x16_f16 v[66:81], v[244:247], v[220:223], v[66:81]
	s_waitcnt lgkmcnt(15)
	v_mfma_f32_32x32x16_f16 v[50:65], v[240:243], v[224:227], v[50:65]
	v_mfma_f32_32x32x16_f16 v[34:49], v[244:247], v[224:227], v[34:49]
	s_waitcnt lgkmcnt(14)
	v_mfma_f32_32x32x16_f16 v[18:33], v[240:243], v[228:231], v[18:33]
	v_mfma_f32_32x32x16_f16 v[2:17], v[244:247], v[228:231], v[2:17]
	ds_read_b128 v[240:243], v212 offset:96
	ds_read_b128 v[216:219], v194 offset:96
	ds_read_b128 v[244:247], v212 offset:4704
	ds_read_b128 v[220:223], v194 offset:4704
	ds_read_b128 v[224:227], v194 offset:9312
	ds_read_b128 v[228:231], v194 offset:13920
	s_waitcnt lgkmcnt(14)
	v_mfma_f32_32x32x16_f16 v[114:129], v[232:235], v[188:191], v[114:129]
	s_waitcnt lgkmcnt(13)
	v_mfma_f32_32x32x16_f16 v[98:113], v[236:239], v[188:191], v[98:113]
	s_waitcnt lgkmcnt(12)
	v_mfma_f32_32x32x16_f16 v[82:97], v[232:235], v[200:203], v[82:97]
	v_mfma_f32_32x32x16_f16 v[66:81], v[236:239], v[200:203], v[66:81]
	s_waitcnt lgkmcnt(11)
	v_mfma_f32_32x32x16_f16 v[50:65], v[232:235], v[204:207], v[50:65]
	v_mfma_f32_32x32x16_f16 v[34:49], v[236:239], v[204:207], v[34:49]
	s_waitcnt lgkmcnt(10)
	v_mfma_f32_32x32x16_f16 v[18:33], v[232:235], v[208:211], v[18:33]
	v_mfma_f32_32x32x16_f16 v[2:17], v[236:239], v[208:211], v[2:17]
	s_waitcnt lgkmcnt(0)
	s_barrier
; DI f16v mfma32(h8v a, h8v b, f16v c) { return __builtin_amdgcn_mfma_f32_32x32x16_f16(a, b, c, 0, 0, 0); }
; template <bool GATHER>
; DI void gemm256_main(const h16* __restrict__ A, int lda, const int* __restrict__ idx, int m0,
;                      const h16* __restrict__ B, int ldb, int n0, int K, h16* lds, f16v (&acc)[4][2]) {
;     ...
;   for (int kt = 0; kt < nk; ++kt) {
;     const h16* As = lds + (kt & 1) * (512 * LDH);
;     const h16* Bs = As + 256 * LDH;
;     h16* Wn = lds + ((kt & 1) ^ 1) * (512 * LDH);
;     if (kt + 1 < nk) {
; #pragma unroll
;       for (int i = 0; i < 4; ++i) { *(u4v*)&Wn[lr * LDH + lc + 8 * i] = ra[i]; *(u4v*)&Wn[(256 + lr) * LDH + lc + 8 * i] = rb[i]; }
;     }
;     if (kt + 2 < nk) {
; #pragma unroll
;       for (int i = 0; i < 4; ++i) { ra[i] = *(const u4v*)(AP_ + 8 * i); rb[i] = *(const u4v*)(BP_ + 8 * i); }
;       ao += 64; bo += 64;
;     }
; #pragma unroll
;     for (int ks = 0; ks < 4; ++ks) {
;       h8v af[4], bf[2];
; #pragma unroll
;       for (int i = 0; i < 4; ++i) af[i] = *(const h8v*)&As[(wm * 128 + i * 32 + (lane & 31)) * LDH + ks * 16 + 8 * (lane >> 5)];
; #pragma unroll
;       for (int j = 0; j < 2; ++j) bf[j] = *(const h8v*)&Bs[(wn * 64 + j * 32 + (lane & 31)) * LDH + ks * 16 + 8 * (lane >> 5)];
; #pragma unroll
;       for (int i = 0; i < 4; ++i)
; #pragma unroll
;         for (int j = 0; j < 2; ++j) acc[i][j] = mfma32(bf[j], af[i], acc[i][j]);
;     }
;     __syncthreads();
	ds_read_b128 v[232:235], v213
	ds_read_b128 v[188:191], v199
	ds_read_b128 v[236:239], v213 offset:4608
	ds_read_b128 v[200:203], v199 offset:4608
	ds_read_b128 v[204:207], v199 offset:9216
	ds_read_b128 v[208:211], v199 offset:13824
	v_mfma_f32_32x32x16_f16 v[114:129], v[240:243], v[216:219], v[114:129]
	v_mfma_f32_32x32x16_f16 v[98:113], v[244:247], v[216:219], v[98:113]
	v_mfma_f32_32x32x16_f16 v[82:97], v[240:243], v[220:223], v[82:97]
	v_mfma_f32_32x32x16_f16 v[66:81], v[244:247], v[220:223], v[66:81]
	v_mfma_f32_32x32x16_f16 v[50:65], v[240:243], v[224:227], v[50:65]
	v_mfma_f32_32x32x16_f16 v[34:49], v[244:247], v[224:227], v[34:49]
	v_mfma_f32_32x32x16_f16 v[18:33], v[240:243], v[228:231], v[18:33]
	v_mfma_f32_32x32x16_f16 v[2:17], v[244:247], v[228:231], v[2:17]
	ds_read_b128 v[240:243], v213 offset:32
	ds_read_b128 v[216:219], v199 offset:32
	ds_read_b128 v[244:247], v213 offset:4640
	ds_read_b128 v[220:223], v199 offset:4640
	ds_read_b128 v[224:227], v199 offset:9248
	ds_read_b128 v[228:231], v199 offset:13856
	s_waitcnt vmcnt(4)
	ds_write_b128 v163, v[130:133]
	ds_write_b128 v163, v[134:137] offset:16
	ds_write_b128 v163, v[138:141] offset:32
	ds_write_b128 v163, v[142:145] offset:48
	global_load_dwordx4 v[130:133], v[164:165], off offset:1408
	global_load_dwordx4 v[134:137], v[164:165], off offset:1424
	global_load_dwordx4 v[138:141], v[164:165], off offset:1440
	global_load_dwordx4 v[142:145], v[164:165], off offset:1456
	s_waitcnt lgkmcnt(14)
	v_mfma_f32_32x32x16_f16 v[114:129], v[232:235], v[188:191], v[114:129]
	s_waitcnt lgkmcnt(13)
	v_mfma_f32_32x32x16_f16 v[98:113], v[236:239], v[188:191], v[98:113]
	s_waitcnt lgkmcnt(12)
	v_mfma_f32_32x32x16_f16 v[82:97], v[232:235], v[200:203], v[82:97]
	v_mfma_f32_32x32x16_f16 v[66:81], v[236:239], v[200:203], v[66:81]
	s_waitcnt lgkmcnt(11)
	v_mfma_f32_32x32x16_f16 v[50:65], v[232:235], v[204:207], v[50:65]
	v_mfma_f32_32x32x16_f16 v[34:49], v[236:239], v[204:207], v[34:49]
	s_waitcnt lgkmcnt(10)
	v_mfma_f32_32x32x16_f16 v[18:33], v[232:235], v[208:211], v[18:33]
	v_mfma_f32_32x32x16_f16 v[2:17], v[236:239], v[208:211], v[2:17]
	ds_read_b128 v[232:235], v213 offset:64
	ds_read_b128 v[188:191], v199 offset:64
	ds_read_b128 v[236:239], v213 offset:4672
	ds_read_b128 v[200:203], v199 offset:4672
	ds_read_b128 v[204:207], v199 offset:9280
	ds_read_b128 v[208:211], v199 offset:13888
	s_waitcnt vmcnt(4)
	ds_write_b128 v163, v[146:149] offset:36864
	ds_write_b128 v163, v[150:153] offset:36880
	ds_write_b128 v163, v[154:157] offset:36896
	ds_write_b128 v163, v[158:161] offset:36912
	global_load_dwordx4 v[146:149], v[192:193], off offset:1408
	global_load_dwordx4 v[150:153], v[192:193], off offset:1424
	global_load_dwordx4 v[154:157], v[192:193], off offset:1440
	global_load_dwordx4 v[158:161], v[192:193], off offset:1456
	s_waitcnt lgkmcnt(15)
	v_mfma_f32_32x32x16_f16 v[114:129], v[240:243], v[216:219], v[114:129]
	s_waitcnt lgkmcnt(15)
	v_mfma_f32_32x32x16_f16 v[98:113], v[244:247], v[216:219], v[98:113]
	s_waitcnt lgkmcnt(15)
	v_mfma_f32_32x32x16_f16 v[82:97], v[240:243], v[220:223], v[82:97]
	v_mfma_f32_32x32x16_f16 v[66:81], v[244:247], v[220:223], v[66:81]
	s_waitcnt lgkmcnt(15)
	v_mfma_f32_32x32x16_f16 v[50:65], v[240:243], v[224:227], v[50:65]
	v_mfma_f32_32x32x16_f16 v[34:49], v[244:247], v[224:227], v[34:49]
	s_waitcnt lgkmcnt(14)
	v_mfma_f32_32x32x16_f16 v[18:33], v[240:243], v[228:231], v[18:33]
	v_mfma_f32_32x32x16_f16 v[2:17], v[244:247], v[228:231], v[2:17]
	ds_read_b128 v[240:243], v213 offset:96
	ds_read_b128 v[216:219], v199 offset:96
	ds_read_b128 v[244:247], v213 offset:4704
	ds_read_b128 v[220:223], v199 offset:4704
	ds_read_b128 v[224:227], v199 offset:9312
	ds_read_b128 v[228:231], v199 offset:13920
	s_waitcnt lgkmcnt(14)
	v_mfma_f32_32x32x16_f16 v[114:129], v[232:235], v[188:191], v[114:129]
	s_waitcnt lgkmcnt(13)
	v_mfma_f32_32x32x16_f16 v[98:113], v[236:239], v[188:191], v[98:113]
	s_waitcnt lgkmcnt(12)
	v_mfma_f32_32x32x16_f16 v[82:97], v[232:235], v[200:203], v[82:97]
	v_mfma_f32_32x32x16_f16 v[66:81], v[236:239], v[200:203], v[66:81]
	s_waitcnt lgkmcnt(11)
	v_mfma_f32_32x32x16_f16 v[50:65], v[232:235], v[204:207], v[50:65]
	v_mfma_f32_32x32x16_f16 v[34:49], v[236:239], v[204:207], v[34:49]
	s_waitcnt lgkmcnt(10)
	v_mfma_f32_32x32x16_f16 v[18:33], v[232:235], v[208:211], v[18:33]
	v_mfma_f32_32x32x16_f16 v[2:17], v[236:239], v[208:211], v[2:17]
	s_waitcnt lgkmcnt(0)
	s_barrier
; DI f16v mfma32(h8v a, h8v b, f16v c) { return __builtin_amdgcn_mfma_f32_32x32x16_f16(a, b, c, 0, 0, 0); }
; template <bool GATHER>
; DI void gemm256_main(const h16* __restrict__ A, int lda, const int* __restrict__ idx, int m0,
;                      const h16* __restrict__ B, int ldb, int n0, int K, h16* lds, f16v (&acc)[4][2]) {
;     ...
;   for (int kt = 0; kt < nk; ++kt) {
;     const h16* As = lds + (kt & 1) * (512 * LDH);
;     const h16* Bs = As + 256 * LDH;
;     h16* Wn = lds + ((kt & 1) ^ 1) * (512 * LDH);
;     if (kt + 1 < nk) {
; #pragma unroll
;       for (int i = 0; i < 4; ++i) { *(u4v*)&Wn[lr * LDH + lc + 8 * i] = ra[i]; *(u4v*)&Wn[(256 + lr) * LDH + lc + 8 * i] = rb[i]; }
;     }
;     if (kt + 2 < nk) {
; #pragma unroll
;       for (int i = 0; i < 4; ++i) { ra[i] = *(const u4v*)(AP_ + 8 * i); rb[i] = *(const u4v*)(BP_ + 8 * i); }
;       ao += 64; bo += 64;
;     }
; #pragma unroll
;     for (int ks = 0; ks < 4; ++ks) {
;       h8v af[4], bf[2];
; #pragma unroll
;       for (int i = 0; i < 4; ++i) af[i] = *(const h8v*)&As[(wm * 128 + i * 32 + (lane & 31)) * LDH + ks * 16 + 8 * (lane >> 5)];
; #pragma unroll
;       for (int j = 0; j < 2; ++j) bf[j] = *(const h8v*)&Bs[(wn * 64 + j * 32 + (lane & 31)) * LDH + ks * 16 + 8 * (lane >> 5)];
; #pragma unroll
;       for (int i = 0; i < 4; ++i)
; #pragma unroll
;         for (int j = 0; j < 2; ++j) acc[i][j] = mfma32(bf[j], af[i], acc[i][j]);
;     }
;     __syncthreads();
	ds_read_b128 v[232:235], v212
	ds_read_b128 v[188:191], v194
	ds_read_b128 v[236:239], v212 offset:4608
	ds_read_b128 v[200:203], v194 offset:4608
	ds_read_b128 v[204:207], v194 offset:9216
	ds_read_b128 v[208:211], v194 offset:13824
	v_mfma_f32_32x32x16_f16 v[114:129], v[240:243], v[216:219], v[114:129]
	v_mfma_f32_32x32x16_f16 v[98:113], v[244:247], v[216:219], v[98:113]
	v_mfma_f32_32x32x16_f16 v[82:97], v[240:243], v[220:223], v[82:97]
	v_mfma_f32_32x32x16_f16 v[66:81], v[244:247], v[220:223], v[66:81]
	v_mfma_f32_32x32x16_f16 v[50:65], v[240:243], v[224:227], v[50:65]
	v_mfma_f32_32x32x16_f16 v[34:49], v[244:247], v[224:227], v[34:49]
	v_mfma_f32_32x32x16_f16 v[18:33], v[240:243], v[228:231], v[18:33]
	v_mfma_f32_32x32x16_f16 v[2:17], v[244:247], v[228:231], v[2:17]
	ds_read_b128 v[240:243], v212 offset:32
	ds_read_b128 v[216:219], v194 offset:32
	ds_read_b128 v[244:247], v212 offset:4640
	ds_read_b128 v[220:223], v194 offset:4640
	ds_read_b128 v[224:227], v194 offset:9248
	ds_read_b128 v[228:231], v194 offset:13856
	s_waitcnt vmcnt(4)
	ds_write_b128 v175, v[130:133]
	ds_write_b128 v175, v[134:137] offset:16
	ds_write_b128 v175, v[138:141] offset:32
	ds_write_b128 v175, v[142:145] offset:48
	global_load_dwordx4 v[130:133], v[164:165], off offset:1536
	global_load_dwordx4 v[134:137], v[164:165], off offset:1552
	global_load_dwordx4 v[138:141], v[164:165], off offset:1568
	global_load_dwordx4 v[142:145], v[164:165], off offset:1584
	s_waitcnt lgkmcnt(14)
	v_mfma_f32_32x32x16_f16 v[114:129], v[232:235], v[188:191], v[114:129]
	s_waitcnt lgkmcnt(13)
	v_mfma_f32_32x32x16_f16 v[98:113], v[236:239], v[188:191], v[98:113]
	s_waitcnt lgkmcnt(12)
	v_mfma_f32_32x32x16_f16 v[82:97], v[232:235], v[200:203], v[82:97]
	v_mfma_f32_32x32x16_f16 v[66:81], v[236:239], v[200:203], v[66:81]
	s_waitcnt lgkmcnt(11)
	v_mfma_f32_32x32x16_f16 v[50:65], v[232:235], v[204:207], v[50:65]
	v_mfma_f32_32x32x16_f16 v[34:49], v[236:239], v[204:207], v[34:49]
	s_waitcnt lgkmcnt(10)
	v_mfma_f32_32x32x16_f16 v[18:33], v[232:235], v[208:211], v[18:33]
	v_mfma_f32_32x32x16_f16 v[2:17], v[236:239], v[208:211], v[2:17]
	ds_read_b128 v[232:235], v212 offset:64
	ds_read_b128 v[188:191], v194 offset:64
	ds_read_b128 v[236:239], v212 offset:4672
	ds_read_b128 v[200:203], v194 offset:4672
	ds_read_b128 v[204:207], v194 offset:9280
	ds_read_b128 v[208:211], v194 offset:13888
	s_waitcnt vmcnt(4)
	ds_write_b128 v175, v[146:149] offset:36864
	ds_write_b128 v175, v[150:153] offset:36880
	ds_write_b128 v175, v[154:157] offset:36896
	ds_write_b128 v175, v[158:161] offset:36912
	global_load_dwordx4 v[146:149], v[192:193], off offset:1536
	global_load_dwordx4 v[150:153], v[192:193], off offset:1552
	global_load_dwordx4 v[154:157], v[192:193], off offset:1568
	global_load_dwordx4 v[158:161], v[192:193], off offset:1584
	s_waitcnt lgkmcnt(15)
	v_mfma_f32_32x32x16_f16 v[114:129], v[240:243], v[216:219], v[114:129]
	s_waitcnt lgkmcnt(15)
	v_mfma_f32_32x32x16_f16 v[98:113], v[244:247], v[216:219], v[98:113]
	s_waitcnt lgkmcnt(15)
	v_mfma_f32_32x32x16_f16 v[82:97], v[240:243], v[220:223], v[82:97]
	v_mfma_f32_32x32x16_f16 v[66:81], v[244:247], v[220:223], v[66:81]
	s_waitcnt lgkmcnt(15)
	v_mfma_f32_32x32x16_f16 v[50:65], v[240:243], v[224:227], v[50:65]
	v_mfma_f32_32x32x16_f16 v[34:49], v[244:247], v[224:227], v[34:49]
	s_waitcnt lgkmcnt(14)
	v_mfma_f32_32x32x16_f16 v[18:33], v[240:243], v[228:231], v[18:33]
	v_mfma_f32_32x32x16_f16 v[2:17], v[244:247], v[228:231], v[2:17]
	ds_read_b128 v[240:243], v212 offset:96
	ds_read_b128 v[216:219], v194 offset:96
	ds_read_b128 v[244:247], v212 offset:4704
	ds_read_b128 v[220:223], v194 offset:4704
	ds_read_b128 v[224:227], v194 offset:9312
	ds_read_b128 v[228:231], v194 offset:13920
	s_waitcnt lgkmcnt(14)
	v_mfma_f32_32x32x16_f16 v[114:129], v[232:235], v[188:191], v[114:129]
	s_waitcnt lgkmcnt(13)
	v_mfma_f32_32x32x16_f16 v[98:113], v[236:239], v[188:191], v[98:113]
	s_waitcnt lgkmcnt(12)
	v_mfma_f32_32x32x16_f16 v[82:97], v[232:235], v[200:203], v[82:97]
	v_mfma_f32_32x32x16_f16 v[66:81], v[236:239], v[200:203], v[66:81]
	s_waitcnt lgkmcnt(11)
	v_mfma_f32_32x32x16_f16 v[50:65], v[232:235], v[204:207], v[50:65]
	v_mfma_f32_32x32x16_f16 v[34:49], v[236:239], v[204:207], v[34:49]
	s_waitcnt lgkmcnt(10)
	v_mfma_f32_32x32x16_f16 v[18:33], v[232:235], v[208:211], v[18:33]
	v_mfma_f32_32x32x16_f16 v[2:17], v[236:239], v[208:211], v[2:17]
	s_waitcnt lgkmcnt(0)
	s_barrier
; DI f16v mfma32(h8v a, h8v b, f16v c) { return __builtin_amdgcn_mfma_f32_32x32x16_f16(a, b, c, 0, 0, 0); }
; template <bool GATHER>
; DI void gemm256_main(const h16* __restrict__ A, int lda, const int* __restrict__ idx, int m0,
;                      const h16* __restrict__ B, int ldb, int n0, int K, h16* lds, f16v (&acc)[4][2]) {
;     ...
;   for (int kt = 0; kt < nk; ++kt) {
;     const h16* As = lds + (kt & 1) * (512 * LDH);
;     const h16* Bs = As + 256 * LDH;
;     h16* Wn = lds + ((kt & 1) ^ 1) * (512 * LDH);
;     if (kt + 1 < nk) {
; #pragma unroll
;       for (int i = 0; i < 4; ++i) { *(u4v*)&Wn[lr * LDH + lc + 8 * i] = ra[i]; *(u4v*)&Wn[(256 + lr) * LDH + lc + 8 * i] = rb[i]; }
;     }
;     if (kt + 2 < nk) {
; #pragma unroll
;       for (int i = 0; i < 4; ++i) { ra[i] = *(const u4v*)(AP_ + 8 * i); rb[i] = *(const u4v*)(BP_ + 8 * i); }
;       ao += 64; bo += 64;
;     }
; #pragma unroll
;     for (int ks = 0; ks < 4; ++ks) {
;       h8v af[4], bf[2];
; #pragma unroll
;       for (int i = 0; i < 4; ++i) af[i] = *(const h8v*)&As[(wm * 128 + i * 32 + (lane & 31)) * LDH + ks * 16 + 8 * (lane >> 5)];
; #pragma unroll
;       for (int j = 0; j < 2; ++j) bf[j] = *(const h8v*)&Bs[(wn * 64 + j * 32 + (lane & 31)) * LDH + ks * 16 + 8 * (lane >> 5)];
; #pragma unroll
;       for (int i = 0; i < 4; ++i)
; #pragma unroll
;         for (int j = 0; j < 2; ++j) acc[i][j] = mfma32(bf[j], af[i], acc[i][j]);
;     }
;     __syncthreads();
	ds_read_b128 v[232:235], v213
	ds_read_b128 v[188:191], v199
	ds_read_b128 v[236:239], v213 offset:4608
	ds_read_b128 v[200:203], v199 offset:4608
	ds_read_b128 v[204:207], v199 offset:9216
	ds_read_b128 v[208:211], v199 offset:13824
	v_mfma_f32_32x32x16_f16 v[114:129], v[240:243], v[216:219], v[114:129]
	v_mfma_f32_32x32x16_f16 v[98:113], v[244:247], v[216:219], v[98:113]
	v_mfma_f32_32x32x16_f16 v[82:97], v[240:243], v[220:223], v[82:97]
	v_mfma_f32_32x32x16_f16 v[66:81], v[244:247], v[220:223], v[66:81]
	v_mfma_f32_32x32x16_f16 v[50:65], v[240:243], v[224:227], v[50:65]
	v_mfma_f32_32x32x16_f16 v[34:49], v[244:247], v[224:227], v[34:49]
	v_mfma_f32_32x32x16_f16 v[18:33], v[240:243], v[228:231], v[18:33]
	v_mfma_f32_32x32x16_f16 v[2:17], v[244:247], v[228:231], v[2:17]
	ds_read_b128 v[240:243], v213 offset:32
	ds_read_b128 v[216:219], v199 offset:32
	ds_read_b128 v[244:247], v213 offset:4640
	ds_read_b128 v[220:223], v199 offset:4640
	ds_read_b128 v[224:227], v199 offset:9248
	ds_read_b128 v[228:231], v199 offset:13856
	s_waitcnt vmcnt(4)
	ds_write_b128 v163, v[130:133]
	ds_write_b128 v163, v[134:137] offset:16
	ds_write_b128 v163, v[138:141] offset:32
	ds_write_b128 v163, v[142:145] offset:48
	global_load_dwordx4 v[130:133], v[164:165], off offset:1664
	global_load_dwordx4 v[134:137], v[164:165], off offset:1680
	global_load_dwordx4 v[138:141], v[164:165], off offset:1696
	global_load_dwordx4 v[142:145], v[164:165], off offset:1712
	s_waitcnt lgkmcnt(14)
	v_mfma_f32_32x32x16_f16 v[114:129], v[232:235], v[188:191], v[114:129]
	s_waitcnt lgkmcnt(13)
	v_mfma_f32_32x32x16_f16 v[98:113], v[236:239], v[188:191], v[98:113]
	s_waitcnt lgkmcnt(12)
	v_mfma_f32_32x32x16_f16 v[82:97], v[232:235], v[200:203], v[82:97]
	v_mfma_f32_32x32x16_f16 v[66:81], v[236:239], v[200:203], v[66:81]
	s_waitcnt lgkmcnt(11)
	v_mfma_f32_32x32x16_f16 v[50:65], v[232:235], v[204:207], v[50:65]
	v_mfma_f32_32x32x16_f16 v[34:49], v[236:239], v[204:207], v[34:49]
	s_waitcnt lgkmcnt(10)
	v_mfma_f32_32x32x16_f16 v[18:33], v[232:235], v[208:211], v[18:33]
	v_mfma_f32_32x32x16_f16 v[2:17], v[236:239], v[208:211], v[2:17]
	ds_read_b128 v[232:235], v213 offset:64
	ds_read_b128 v[188:191], v199 offset:64
	ds_read_b128 v[236:239], v213 offset:4672
	ds_read_b128 v[200:203], v199 offset:4672
	ds_read_b128 v[204:207], v199 offset:9280
	ds_read_b128 v[208:211], v199 offset:13888
	s_waitcnt vmcnt(4)
	ds_write_b128 v163, v[146:149] offset:36864
	ds_write_b128 v163, v[150:153] offset:36880
	ds_write_b128 v163, v[154:157] offset:36896
	ds_write_b128 v163, v[158:161] offset:36912
	global_load_dwordx4 v[146:149], v[192:193], off offset:1664
	global_load_dwordx4 v[150:153], v[192:193], off offset:1680
	global_load_dwordx4 v[154:157], v[192:193], off offset:1696
	global_load_dwordx4 v[158:161], v[192:193], off offset:1712
	s_waitcnt lgkmcnt(15)
	v_mfma_f32_32x32x16_f16 v[114:129], v[240:243], v[216:219], v[114:129]
	s_waitcnt lgkmcnt(15)
	v_mfma_f32_32x32x16_f16 v[98:113], v[244:247], v[216:219], v[98:113]
	s_waitcnt lgkmcnt(15)
	v_mfma_f32_32x32x16_f16 v[82:97], v[240:243], v[220:223], v[82:97]
	v_mfma_f32_32x32x16_f16 v[66:81], v[244:247], v[220:223], v[66:81]
	s_waitcnt lgkmcnt(15)
	v_mfma_f32_32x32x16_f16 v[50:65], v[240:243], v[224:227], v[50:65]
	v_mfma_f32_32x32x16_f16 v[34:49], v[244:247], v[224:227], v[34:49]
	s_waitcnt lgkmcnt(14)
	v_mfma_f32_32x32x16_f16 v[18:33], v[240:243], v[228:231], v[18:33]
	v_mfma_f32_32x32x16_f16 v[2:17], v[244:247], v[228:231], v[2:17]
	ds_read_b128 v[240:243], v213 offset:96
	ds_read_b128 v[216:219], v199 offset:96
	ds_read_b128 v[244:247], v213 offset:4704
	ds_read_b128 v[220:223], v199 offset:4704
	ds_read_b128 v[224:227], v199 offset:9312
	ds_read_b128 v[228:231], v199 offset:13920
	s_waitcnt lgkmcnt(14)
	v_mfma_f32_32x32x16_f16 v[114:129], v[232:235], v[188:191], v[114:129]
	s_waitcnt lgkmcnt(13)
	v_mfma_f32_32x32x16_f16 v[98:113], v[236:239], v[188:191], v[98:113]
	s_waitcnt lgkmcnt(12)
	v_mfma_f32_32x32x16_f16 v[82:97], v[232:235], v[200:203], v[82:97]
	v_mfma_f32_32x32x16_f16 v[66:81], v[236:239], v[200:203], v[66:81]
	s_waitcnt lgkmcnt(11)
	v_mfma_f32_32x32x16_f16 v[50:65], v[232:235], v[204:207], v[50:65]
	v_mfma_f32_32x32x16_f16 v[34:49], v[236:239], v[204:207], v[34:49]
	s_waitcnt lgkmcnt(10)
	v_mfma_f32_32x32x16_f16 v[18:33], v[232:235], v[208:211], v[18:33]
	v_mfma_f32_32x32x16_f16 v[2:17], v[236:239], v[208:211], v[2:17]
	s_waitcnt lgkmcnt(0)
	s_barrier
; DI f16v mfma32(h8v a, h8v b, f16v c) { return __builtin_amdgcn_mfma_f32_32x32x16_f16(a, b, c, 0, 0, 0); }
; template <bool GATHER>
; DI void gemm256_main(const h16* __restrict__ A, int lda, const int* __restrict__ idx, int m0,
;                      const h16* __restrict__ B, int ldb, int n0, int K, h16* lds, f16v (&acc)[4][2]) {
;     ...
;   for (int kt = 0; kt < nk; ++kt) {
;     const h16* As = lds + (kt & 1) * (512 * LDH);
;     const h16* Bs = As + 256 * LDH;
;     h16* Wn = lds + ((kt & 1) ^ 1) * (512 * LDH);
;     if (kt + 1 < nk) {
; #pragma unroll
;       for (int i = 0; i < 4; ++i) { *(u4v*)&Wn[lr * LDH + lc + 8 * i] = ra[i]; *(u4v*)&Wn[(256 + lr) * LDH + lc + 8 * i] = rb[i]; }
;     }
;     if (kt + 2 < nk) {
; #pragma unroll
;       for (int i = 0; i < 4; ++i) { ra[i] = *(const u4v*)(AP_ + 8 * i); rb[i] = *(const u4v*)(BP_ + 8 * i); }
;       ao += 64; bo += 64;
;     }
; #pragma unroll
;     for (int ks = 0; ks < 4; ++ks) {
;       h8v af[4], bf[2];
; #pragma unroll
;       for (int i = 0; i < 4; ++i) af[i] = *(const h8v*)&As[(wm * 128 + i * 32 + (lane & 31)) * LDH + ks * 16 + 8 * (lane >> 5)];
; #pragma unroll
;       for (int j = 0; j < 2; ++j) bf[j] = *(const h8v*)&Bs[(wn * 64 + j * 32 + (lane & 31)) * LDH + ks * 16 + 8 * (lane >> 5)];
; #pragma unroll
;       for (int i = 0; i < 4; ++i)
; #pragma unroll
;         for (int j = 0; j < 2; ++j) acc[i][j] = mfma32(bf[j], af[i], acc[i][j]);
;     }
;     __syncthreads();
	ds_read_b128 v[232:235], v212
	ds_read_b128 v[188:191], v194
	ds_read_b128 v[236:239], v212 offset:4608
	ds_read_b128 v[200:203], v194 offset:4608
	ds_read_b128 v[204:207], v194 offset:9216
	ds_read_b128 v[208:211], v194 offset:13824
	v_mfma_f32_32x32x16_f16 v[114:129], v[240:243], v[216:219], v[114:129]
	v_mfma_f32_32x32x16_f16 v[98:113], v[244:247], v[216:219], v[98:113]
	v_mfma_f32_32x32x16_f16 v[82:97], v[240:243], v[220:223], v[82:97]
	v_mfma_f32_32x32x16_f16 v[66:81], v[244:247], v[220:223], v[66:81]
	v_mfma_f32_32x32x16_f16 v[50:65], v[240:243], v[224:227], v[50:65]
	v_mfma_f32_32x32x16_f16 v[34:49], v[244:247], v[224:227], v[34:49]
	v_mfma_f32_32x32x16_f16 v[18:33], v[240:243], v[228:231], v[18:33]
	v_mfma_f32_32x32x16_f16 v[2:17], v[244:247], v[228:231], v[2:17]
	ds_read_b128 v[240:243], v212 offset:32
	ds_read_b128 v[216:219], v194 offset:32
	ds_read_b128 v[244:247], v212 offset:4640
	ds_read_b128 v[220:223], v194 offset:4640
	ds_read_b128 v[224:227], v194 offset:9248
	ds_read_b128 v[228:231], v194 offset:13856
	s_waitcnt vmcnt(4)
	ds_write_b128 v175, v[130:133]
	ds_write_b128 v175, v[134:137] offset:16
	ds_write_b128 v175, v[138:141] offset:32
	ds_write_b128 v175, v[142:145] offset:48
	global_load_dwordx4 v[130:133], v[164:165], off offset:1792
	global_load_dwordx4 v[134:137], v[164:165], off offset:1808
	global_load_dwordx4 v[138:141], v[164:165], off offset:1824
	global_load_dwordx4 v[142:145], v[164:165], off offset:1840
	s_waitcnt lgkmcnt(14)
	v_mfma_f32_32x32x16_f16 v[114:129], v[232:235], v[188:191], v[114:129]
	s_waitcnt lgkmcnt(13)
	v_mfma_f32_32x32x16_f16 v[98:113], v[236:239], v[188:191], v[98:113]
	s_waitcnt lgkmcnt(12)
	v_mfma_f32_32x32x16_f16 v[82:97], v[232:235], v[200:203], v[82:97]
	v_mfma_f32_32x32x16_f16 v[66:81], v[236:239], v[200:203], v[66:81]
	s_waitcnt lgkmcnt(11)
	v_mfma_f32_32x32x16_f16 v[50:65], v[232:235], v[204:207], v[50:65]
	v_mfma_f32_32x32x16_f16 v[34:49], v[236:239], v[204:207], v[34:49]
	s_waitcnt lgkmcnt(10)
	v_mfma_f32_32x32x16_f16 v[18:33], v[232:235], v[208:211], v[18:33]
	v_mfma_f32_32x32x16_f16 v[2:17], v[236:239], v[208:211], v[2:17]
	ds_read_b128 v[232:235], v212 offset:64
	ds_read_b128 v[188:191], v194 offset:64
	ds_read_b128 v[236:239], v212 offset:4672
	ds_read_b128 v[200:203], v194 offset:4672
	ds_read_b128 v[204:207], v194 offset:9280
	ds_read_b128 v[208:211], v194 offset:13888
	s_waitcnt vmcnt(4)
	ds_write_b128 v175, v[146:149] offset:36864
	ds_write_b128 v175, v[150:153] offset:36880
	ds_write_b128 v175, v[154:157] offset:36896
	ds_write_b128 v175, v[158:161] offset:36912
	global_load_dwordx4 v[146:149], v[192:193], off offset:1792
	global_load_dwordx4 v[150:153], v[192:193], off offset:1808
	global_load_dwordx4 v[154:157], v[192:193], off offset:1824
	global_load_dwordx4 v[158:161], v[192:193], off offset:1840
	s_waitcnt lgkmcnt(15)
	v_mfma_f32_32x32x16_f16 v[114:129], v[240:243], v[216:219], v[114:129]
	s_waitcnt lgkmcnt(15)
	v_mfma_f32_32x32x16_f16 v[98:113], v[244:247], v[216:219], v[98:113]
	s_waitcnt lgkmcnt(15)
	v_mfma_f32_32x32x16_f16 v[82:97], v[240:243], v[220:223], v[82:97]
	v_mfma_f32_32x32x16_f16 v[66:81], v[244:247], v[220:223], v[66:81]
	s_waitcnt lgkmcnt(15)
	v_mfma_f32_32x32x16_f16 v[50:65], v[240:243], v[224:227], v[50:65]
	v_mfma_f32_32x32x16_f16 v[34:49], v[244:247], v[224:227], v[34:49]
	s_waitcnt lgkmcnt(14)
	v_mfma_f32_32x32x16_f16 v[18:33], v[240:243], v[228:231], v[18:33]
	v_mfma_f32_32x32x16_f16 v[2:17], v[244:247], v[228:231], v[2:17]
	ds_read_b128 v[240:243], v212 offset:96
	ds_read_b128 v[216:219], v194 offset:96
	ds_read_b128 v[244:247], v212 offset:4704
	ds_read_b128 v[220:223], v194 offset:4704
	ds_read_b128 v[224:227], v194 offset:9312
	ds_read_b128 v[228:231], v194 offset:13920
	s_waitcnt lgkmcnt(14)
	v_mfma_f32_32x32x16_f16 v[114:129], v[232:235], v[188:191], v[114:129]
	s_waitcnt lgkmcnt(13)
	v_mfma_f32_32x32x16_f16 v[98:113], v[236:239], v[188:191], v[98:113]
	s_waitcnt lgkmcnt(12)
	v_mfma_f32_32x32x16_f16 v[82:97], v[232:235], v[200:203], v[82:97]
	v_mfma_f32_32x32x16_f16 v[66:81], v[236:239], v[200:203], v[66:81]
	s_waitcnt lgkmcnt(11)
	v_mfma_f32_32x32x16_f16 v[50:65], v[232:235], v[204:207], v[50:65]
	v_mfma_f32_32x32x16_f16 v[34:49], v[236:239], v[204:207], v[34:49]
	s_waitcnt lgkmcnt(10)
	v_mfma_f32_32x32x16_f16 v[18:33], v[232:235], v[208:211], v[18:33]
	v_mfma_f32_32x32x16_f16 v[2:17], v[236:239], v[208:211], v[2:17]
	s_waitcnt lgkmcnt(0)
	s_barrier
; DI f16v mfma32(h8v a, h8v b, f16v c) { return __builtin_amdgcn_mfma_f32_32x32x16_f16(a, b, c, 0, 0, 0); }
; template <bool GATHER>
; DI void gemm256_main(const h16* __restrict__ A, int lda, const int* __restrict__ idx, int m0,
;                      const h16* __restrict__ B, int ldb, int n0, int K, h16* lds, f16v (&acc)[4][2]) {
;     ...
;   for (int kt = 0; kt < nk; ++kt) {
;     const h16* As = lds + (kt & 1) * (512 * LDH);
;     const h16* Bs = As + 256 * LDH;
;     h16* Wn = lds + ((kt & 1) ^ 1) * (512 * LDH);
;     if (kt + 1 < nk) {
; #pragma unroll
;       for (int i = 0; i < 4; ++i) { *(u4v*)&Wn[lr * LDH + lc + 8 * i] = ra[i]; *(u4v*)&Wn[(256 + lr) * LDH + lc + 8 * i] = rb[i]; }
;     }
;     if (kt + 2 < nk) {
; #pragma unroll
;       for (int i = 0; i < 4; ++i) { ra[i] = *(const u4v*)(AP_ + 8 * i); rb[i] = *(const u4v*)(BP_ + 8 * i); }
;       ao += 64; bo += 64;
;     }
; #pragma unroll
;     for (int ks = 0; ks < 4; ++ks) {
;       h8v af[4], bf[2];
; #pragma unroll
;       for (int i = 0; i < 4; ++i) af[i] = *(const h8v*)&As[(wm * 128 + i * 32 + (lane & 31)) * LDH + ks * 16 + 8 * (lane >> 5)];
; #pragma unroll
;       for (int j = 0; j < 2; ++j) bf[j] = *(const h8v*)&Bs[(wn * 64 + j * 32 + (lane & 31)) * LDH + ks * 16 + 8 * (lane >> 5)];
; #pragma unroll
;       for (int i = 0; i < 4; ++i)
; #pragma unroll
;         for (int j = 0; j < 2; ++j) acc[i][j] = mfma32(bf[j], af[i], acc[i][j]);
;     }
;     __syncthreads();
	ds_read_b128 v[232:235], v213
	ds_read_b128 v[188:191], v199
	ds_read_b128 v[236:239], v213 offset:4608
	ds_read_b128 v[200:203], v199 offset:4608
	ds_read_b128 v[204:207], v199 offset:9216
	ds_read_b128 v[208:211], v199 offset:13824
	v_mfma_f32_32x32x16_f16 v[114:129], v[240:243], v[216:219], v[114:129]
	v_mfma_f32_32x32x16_f16 v[98:113], v[244:247], v[216:219], v[98:113]
	v_mfma_f32_32x32x16_f16 v[82:97], v[240:243], v[220:223], v[82:97]
	v_mfma_f32_32x32x16_f16 v[66:81], v[244:247], v[220:223], v[66:81]
	v_mfma_f32_32x32x16_f16 v[50:65], v[240:243], v[224:227], v[50:65]
	v_mfma_f32_32x32x16_f16 v[34:49], v[244:247], v[224:227], v[34:49]
	v_mfma_f32_32x32x16_f16 v[18:33], v[240:243], v[228:231], v[18:33]
	v_mfma_f32_32x32x16_f16 v[2:17], v[244:247], v[228:231], v[2:17]
	ds_read_b128 v[240:243], v213 offset:32
	ds_read_b128 v[216:219], v199 offset:32
	ds_read_b128 v[244:247], v213 offset:4640
	ds_read_b128 v[220:223], v199 offset:4640
	ds_read_b128 v[224:227], v199 offset:9248
	ds_read_b128 v[228:231], v199 offset:13856
	s_waitcnt vmcnt(4)
	ds_write_b128 v163, v[130:133]
	ds_write_b128 v163, v[134:137] offset:16
	ds_write_b128 v163, v[138:141] offset:32
	ds_write_b128 v163, v[142:145] offset:48
	global_load_dwordx4 v[130:133], v[164:165], off offset:1920
	global_load_dwordx4 v[134:137], v[164:165], off offset:1936
	global_load_dwordx4 v[138:141], v[164:165], off offset:1952
	global_load_dwordx4 v[142:145], v[164:165], off offset:1968
	s_waitcnt lgkmcnt(14)
	v_mfma_f32_32x32x16_f16 v[114:129], v[232:235], v[188:191], v[114:129]
	s_waitcnt lgkmcnt(13)
	v_mfma_f32_32x32x16_f16 v[98:113], v[236:239], v[188:191], v[98:113]
	s_waitcnt lgkmcnt(12)
	v_mfma_f32_32x32x16_f16 v[82:97], v[232:235], v[200:203], v[82:97]
	v_mfma_f32_32x32x16_f16 v[66:81], v[236:239], v[200:203], v[66:81]
	s_waitcnt lgkmcnt(11)
	v_mfma_f32_32x32x16_f16 v[50:65], v[232:235], v[204:207], v[50:65]
	v_mfma_f32_32x32x16_f16 v[34:49], v[236:239], v[204:207], v[34:49]
	s_waitcnt lgkmcnt(10)
	v_mfma_f32_32x32x16_f16 v[18:33], v[232:235], v[208:211], v[18:33]
	v_mfma_f32_32x32x16_f16 v[2:17], v[236:239], v[208:211], v[2:17]
	ds_read_b128 v[232:235], v213 offset:64
	ds_read_b128 v[188:191], v199 offset:64
	ds_read_b128 v[236:239], v213 offset:4672
	ds_read_b128 v[200:203], v199 offset:4672
	ds_read_b128 v[204:207], v199 offset:9280
	ds_read_b128 v[208:211], v199 offset:13888
	s_waitcnt vmcnt(4)
	ds_write_b128 v163, v[146:149] offset:36864
	ds_write_b128 v163, v[150:153] offset:36880
	ds_write_b128 v163, v[154:157] offset:36896
	ds_write_b128 v163, v[158:161] offset:36912
	global_load_dwordx4 v[146:149], v[192:193], off offset:1920
	global_load_dwordx4 v[150:153], v[192:193], off offset:1936
	global_load_dwordx4 v[154:157], v[192:193], off offset:1952
	global_load_dwordx4 v[158:161], v[192:193], off offset:1968
	s_waitcnt lgkmcnt(15)
	v_mfma_f32_32x32x16_f16 v[114:129], v[240:243], v[216:219], v[114:129]
	s_waitcnt lgkmcnt(15)
	v_mfma_f32_32x32x16_f16 v[98:113], v[244:247], v[216:219], v[98:113]
	s_waitcnt lgkmcnt(15)
	v_mfma_f32_32x32x16_f16 v[82:97], v[240:243], v[220:223], v[82:97]
	v_mfma_f32_32x32x16_f16 v[66:81], v[244:247], v[220:223], v[66:81]
	s_waitcnt lgkmcnt(15)
	v_mfma_f32_32x32x16_f16 v[50:65], v[240:243], v[224:227], v[50:65]
	v_mfma_f32_32x32x16_f16 v[34:49], v[244:247], v[224:227], v[34:49]
	s_waitcnt lgkmcnt(14)
	v_mfma_f32_32x32x16_f16 v[18:33], v[240:243], v[228:231], v[18:33]
	v_mfma_f32_32x32x16_f16 v[2:17], v[244:247], v[228:231], v[2:17]
	ds_read_b128 v[240:243], v213 offset:96
	ds_read_b128 v[216:219], v199 offset:96
	ds_read_b128 v[244:247], v213 offset:4704
	ds_read_b128 v[220:223], v199 offset:4704
	ds_read_b128 v[224:227], v199 offset:9312
	ds_read_b128 v[228:231], v199 offset:13920
	s_waitcnt lgkmcnt(14)
	v_mfma_f32_32x32x16_f16 v[114:129], v[232:235], v[188:191], v[114:129]
	s_waitcnt lgkmcnt(13)
	v_mfma_f32_32x32x16_f16 v[98:113], v[236:239], v[188:191], v[98:113]
	s_waitcnt lgkmcnt(12)
	v_mfma_f32_32x32x16_f16 v[82:97], v[232:235], v[200:203], v[82:97]
	v_mfma_f32_32x32x16_f16 v[66:81], v[236:239], v[200:203], v[66:81]
	s_waitcnt lgkmcnt(11)
	v_mfma_f32_32x32x16_f16 v[50:65], v[232:235], v[204:207], v[50:65]
	v_mfma_f32_32x32x16_f16 v[34:49], v[236:239], v[204:207], v[34:49]
	s_waitcnt lgkmcnt(10)
	v_mfma_f32_32x32x16_f16 v[18:33], v[232:235], v[208:211], v[18:33]
	v_mfma_f32_32x32x16_f16 v[2:17], v[236:239], v[208:211], v[2:17]
	s_waitcnt lgkmcnt(0)
	s_barrier
; DI f16v mfma32(h8v a, h8v b, f16v c) { return __builtin_amdgcn_mfma_f32_32x32x16_f16(a, b, c, 0, 0, 0); }
; template <bool GATHER>
; DI void gemm256_main(const h16* __restrict__ A, int lda, const int* __restrict__ idx, int m0,
;                      const h16* __restrict__ B, int ldb, int n0, int K, h16* lds, f16v (&acc)[4][2]) {
;     ...
;   for (int kt = 0; kt < nk; ++kt) {
;     const h16* As = lds + (kt & 1) * (512 * LDH);
;     const h16* Bs = As + 256 * LDH;
;     h16* Wn = lds + ((kt & 1) ^ 1) * (512 * LDH);
;     if (kt + 1 < nk) {
; #pragma unroll
;       for (int i = 0; i < 4; ++i) { *(u4v*)&Wn[lr * LDH + lc + 8 * i] = ra[i]; *(u4v*)&Wn[(256 + lr) * LDH + lc + 8 * i] = rb[i]; }
;     }
;     if (kt + 2 < nk) {
; #pragma unroll
;       for (int i = 0; i < 4; ++i) { ra[i] = *(const u4v*)(AP_ + 8 * i); rb[i] = *(const u4v*)(BP_ + 8 * i); }
;       ao += 64; bo += 64;
;     }
; #pragma unroll
;     for (int ks = 0; ks < 4; ++ks) {
;       h8v af[4], bf[2];
; #pragma unroll
;       for (int i = 0; i < 4; ++i) af[i] = *(const h8v*)&As[(wm * 128 + i * 32 + (lane & 31)) * LDH + ks * 16 + 8 * (lane >> 5)];
; #pragma unroll
;       for (int j = 0; j < 2; ++j) bf[j] = *(const h8v*)&Bs[(wn * 64 + j * 32 + (lane & 31)) * LDH + ks * 16 + 8 * (lane >> 5)];
; #pragma unroll
;       for (int i = 0; i < 4; ++i)
; #pragma unroll
;         for (int j = 0; j < 2; ++j) acc[i][j] = mfma32(bf[j], af[i], acc[i][j]);
;     }
;     __syncthreads();
	ds_read_b128 v[232:235], v212
	ds_read_b128 v[188:191], v194
	ds_read_b128 v[236:239], v212 offset:4608
	ds_read_b128 v[200:203], v194 offset:4608
	ds_read_b128 v[204:207], v194 offset:9216
	ds_read_b128 v[208:211], v194 offset:13824
	v_mfma_f32_32x32x16_f16 v[114:129], v[240:243], v[216:219], v[114:129]
	v_mfma_f32_32x32x16_f16 v[98:113], v[244:247], v[216:219], v[98:113]
	v_mfma_f32_32x32x16_f16 v[82:97], v[240:243], v[220:223], v[82:97]
	v_mfma_f32_32x32x16_f16 v[66:81], v[244:247], v[220:223], v[66:81]
	v_mfma_f32_32x32x16_f16 v[50:65], v[240:243], v[224:227], v[50:65]
	v_mfma_f32_32x32x16_f16 v[34:49], v[244:247], v[224:227], v[34:49]
	v_mfma_f32_32x32x16_f16 v[18:33], v[240:243], v[228:231], v[18:33]
	v_mfma_f32_32x32x16_f16 v[2:17], v[244:247], v[228:231], v[2:17]
	ds_read_b128 v[240:243], v212 offset:32
	ds_read_b128 v[216:219], v194 offset:32
	ds_read_b128 v[244:247], v212 offset:4640
	ds_read_b128 v[220:223], v194 offset:4640
	ds_read_b128 v[224:227], v194 offset:9248
	ds_read_b128 v[228:231], v194 offset:13856
	s_waitcnt vmcnt(4)
	ds_write_b128 v175, v[130:133]
	ds_write_b128 v175, v[134:137] offset:16
	ds_write_b128 v175, v[138:141] offset:32
	ds_write_b128 v175, v[142:145] offset:48
	global_load_dwordx4 v[130:133], v[164:165], off offset:2048
	global_load_dwordx4 v[134:137], v[164:165], off offset:2064
	global_load_dwordx4 v[138:141], v[164:165], off offset:2080
	global_load_dwordx4 v[142:145], v[164:165], off offset:2096
	s_waitcnt lgkmcnt(14)
	v_mfma_f32_32x32x16_f16 v[114:129], v[232:235], v[188:191], v[114:129]
	s_waitcnt lgkmcnt(13)
	v_mfma_f32_32x32x16_f16 v[98:113], v[236:239], v[188:191], v[98:113]
	s_waitcnt lgkmcnt(12)
	v_mfma_f32_32x32x16_f16 v[82:97], v[232:235], v[200:203], v[82:97]
	v_mfma_f32_32x32x16_f16 v[66:81], v[236:239], v[200:203], v[66:81]
	s_waitcnt lgkmcnt(11)
	v_mfma_f32_32x32x16_f16 v[50:65], v[232:235], v[204:207], v[50:65]
	v_mfma_f32_32x32x16_f16 v[34:49], v[236:239], v[204:207], v[34:49]
	s_waitcnt lgkmcnt(10)
	v_mfma_f32_32x32x16_f16 v[18:33], v[232:235], v[208:211], v[18:33]
	v_mfma_f32_32x32x16_f16 v[2:17], v[236:239], v[208:211], v[2:17]
	ds_read_b128 v[232:235], v212 offset:64
	ds_read_b128 v[188:191], v194 offset:64
	ds_read_b128 v[236:239], v212 offset:4672
	ds_read_b128 v[200:203], v194 offset:4672
	ds_read_b128 v[204:207], v194 offset:9280
	ds_read_b128 v[208:211], v194 offset:13888
	s_waitcnt vmcnt(4)
	ds_write_b128 v175, v[146:149] offset:36864
	ds_write_b128 v175, v[150:153] offset:36880
	ds_write_b128 v175, v[154:157] offset:36896
	ds_write_b128 v175, v[158:161] offset:36912
	global_load_dwordx4 v[146:149], v[192:193], off offset:2048
	global_load_dwordx4 v[150:153], v[192:193], off offset:2064
	global_load_dwordx4 v[154:157], v[192:193], off offset:2080
	global_load_dwordx4 v[158:161], v[192:193], off offset:2096
	s_waitcnt lgkmcnt(15)
	v_mfma_f32_32x32x16_f16 v[114:129], v[240:243], v[216:219], v[114:129]
	s_waitcnt lgkmcnt(15)
	v_mfma_f32_32x32x16_f16 v[98:113], v[244:247], v[216:219], v[98:113]
	s_waitcnt lgkmcnt(15)
	v_mfma_f32_32x32x16_f16 v[82:97], v[240:243], v[220:223], v[82:97]
	v_mfma_f32_32x32x16_f16 v[66:81], v[244:247], v[220:223], v[66:81]
	s_waitcnt lgkmcnt(15)
	v_mfma_f32_32x32x16_f16 v[50:65], v[240:243], v[224:227], v[50:65]
	v_mfma_f32_32x32x16_f16 v[34:49], v[244:247], v[224:227], v[34:49]
	s_waitcnt lgkmcnt(14)
	v_mfma_f32_32x32x16_f16 v[18:33], v[240:243], v[228:231], v[18:33]
	v_mfma_f32_32x32x16_f16 v[2:17], v[244:247], v[228:231], v[2:17]
	ds_read_b128 v[240:243], v212 offset:96
	ds_read_b128 v[216:219], v194 offset:96
	ds_read_b128 v[244:247], v212 offset:4704
	ds_read_b128 v[220:223], v194 offset:4704
	ds_read_b128 v[224:227], v194 offset:9312
	ds_read_b128 v[228:231], v194 offset:13920
	s_waitcnt lgkmcnt(14)
	v_mfma_f32_32x32x16_f16 v[114:129], v[232:235], v[188:191], v[114:129]
	s_waitcnt lgkmcnt(13)
	v_mfma_f32_32x32x16_f16 v[98:113], v[236:239], v[188:191], v[98:113]
	s_waitcnt lgkmcnt(12)
	v_mfma_f32_32x32x16_f16 v[82:97], v[232:235], v[200:203], v[82:97]
	v_mfma_f32_32x32x16_f16 v[66:81], v[236:239], v[200:203], v[66:81]
	s_waitcnt lgkmcnt(11)
	v_mfma_f32_32x32x16_f16 v[50:65], v[232:235], v[204:207], v[50:65]
	v_mfma_f32_32x32x16_f16 v[34:49], v[236:239], v[204:207], v[34:49]
	s_waitcnt lgkmcnt(10)
	v_mfma_f32_32x32x16_f16 v[18:33], v[232:235], v[208:211], v[18:33]
	v_mfma_f32_32x32x16_f16 v[2:17], v[236:239], v[208:211], v[2:17]
	s_waitcnt lgkmcnt(0)
	s_barrier
; DI f16v mfma32(h8v a, h8v b, f16v c) { return __builtin_amdgcn_mfma_f32_32x32x16_f16(a, b, c, 0, 0, 0); }
; template <bool GATHER>
; DI void gemm256_main(const h16* __restrict__ A, int lda, const int* __restrict__ idx, int m0,
;                      const h16* __restrict__ B, int ldb, int n0, int K, h16* lds, f16v (&acc)[4][2]) {
;     ...
;   for (int kt = 0; kt < nk; ++kt) {
;     const h16* As = lds + (kt & 1) * (512 * LDH);
;     const h16* Bs = As + 256 * LDH;
;     h16* Wn = lds + ((kt & 1) ^ 1) * (512 * LDH);
;     if (kt + 1 < nk) {
; #pragma unroll
;       for (int i = 0; i < 4; ++i) { *(u4v*)&Wn[lr * LDH + lc + 8 * i] = ra[i]; *(u4v*)&Wn[(256 + lr) * LDH + lc + 8 * i] = rb[i]; }
;     }
;     if (kt + 2 < nk) {
; #pragma unroll
;       for (int i = 0; i < 4; ++i) { ra[i] = *(const u4v*)(AP_ + 8 * i); rb[i] = *(const u4v*)(BP_ + 8 * i); }
;       ao += 64; bo += 64;
;     }
; #pragma unroll
;     for (int ks = 0; ks < 4; ++ks) {
;       h8v af[4], bf[2];
; #pragma unroll
;       for (int i = 0; i < 4; ++i) af[i] = *(const h8v*)&As[(wm * 128 + i * 32 + (lane & 31)) * LDH + ks * 16 + 8 * (lane >> 5)];
; #pragma unroll
;       for (int j = 0; j < 2; ++j) bf[j] = *(const h8v*)&Bs[(wn * 64 + j * 32 + (lane & 31)) * LDH + ks * 16 + 8 * (lane >> 5)];
; #pragma unroll
;       for (int i = 0; i < 4; ++i)
; #pragma unroll
;         for (int j = 0; j < 2; ++j) acc[i][j] = mfma32(bf[j], af[i], acc[i][j]);
;     }
;     __syncthreads();
	ds_read_b128 v[232:235], v213
	ds_read_b128 v[188:191], v199
	ds_read_b128 v[236:239], v213 offset:4608
	ds_read_b128 v[200:203], v199 offset:4608
	ds_read_b128 v[204:207], v199 offset:9216
	ds_read_b128 v[208:211], v199 offset:13824
	v_mfma_f32_32x32x16_f16 v[114:129], v[240:243], v[216:219], v[114:129]
	v_mfma_f32_32x32x16_f16 v[98:113], v[244:247], v[216:219], v[98:113]
	v_mfma_f32_32x32x16_f16 v[82:97], v[240:243], v[220:223], v[82:97]
	v_mfma_f32_32x32x16_f16 v[66:81], v[244:247], v[220:223], v[66:81]
	v_mfma_f32_32x32x16_f16 v[50:65], v[240:243], v[224:227], v[50:65]
	v_mfma_f32_32x32x16_f16 v[34:49], v[244:247], v[224:227], v[34:49]
	v_mfma_f32_32x32x16_f16 v[18:33], v[240:243], v[228:231], v[18:33]
	v_mfma_f32_32x32x16_f16 v[2:17], v[244:247], v[228:231], v[2:17]
	ds_read_b128 v[240:243], v213 offset:32
	ds_read_b128 v[216:219], v199 offset:32
	ds_read_b128 v[244:247], v213 offset:4640
	ds_read_b128 v[220:223], v199 offset:4640
	ds_read_b128 v[224:227], v199 offset:9248
	ds_read_b128 v[228:231], v199 offset:13856
	s_waitcnt vmcnt(4)
	ds_write_b128 v163, v[130:133]
	ds_write_b128 v163, v[134:137] offset:16
	ds_write_b128 v163, v[138:141] offset:32
	ds_write_b128 v163, v[142:145] offset:48
	global_load_dwordx4 v[130:133], v[164:165], off offset:2176
	global_load_dwordx4 v[134:137], v[164:165], off offset:2192
	global_load_dwordx4 v[138:141], v[164:165], off offset:2208
	global_load_dwordx4 v[142:145], v[164:165], off offset:2224
	s_waitcnt lgkmcnt(14)
	v_mfma_f32_32x32x16_f16 v[114:129], v[232:235], v[188:191], v[114:129]
	s_waitcnt lgkmcnt(13)
	v_mfma_f32_32x32x16_f16 v[98:113], v[236:239], v[188:191], v[98:113]
	s_waitcnt lgkmcnt(12)
	v_mfma_f32_32x32x16_f16 v[82:97], v[232:235], v[200:203], v[82:97]
	v_mfma_f32_32x32x16_f16 v[66:81], v[236:239], v[200:203], v[66:81]
	s_waitcnt lgkmcnt(11)
	v_mfma_f32_32x32x16_f16 v[50:65], v[232:235], v[204:207], v[50:65]
	v_mfma_f32_32x32x16_f16 v[34:49], v[236:239], v[204:207], v[34:49]
	s_waitcnt lgkmcnt(10)
	v_mfma_f32_32x32x16_f16 v[18:33], v[232:235], v[208:211], v[18:33]
	v_mfma_f32_32x32x16_f16 v[2:17], v[236:239], v[208:211], v[2:17]
	ds_read_b128 v[232:235], v213 offset:64
	ds_read_b128 v[188:191], v199 offset:64
	ds_read_b128 v[236:239], v213 offset:4672
	ds_read_b128 v[200:203], v199 offset:4672
	ds_read_b128 v[204:207], v199 offset:9280
	ds_read_b128 v[208:211], v199 offset:13888
	s_waitcnt vmcnt(4)
	ds_write_b128 v163, v[146:149] offset:36864
	ds_write_b128 v163, v[150:153] offset:36880
	ds_write_b128 v163, v[154:157] offset:36896
	ds_write_b128 v163, v[158:161] offset:36912
	global_load_dwordx4 v[146:149], v[192:193], off offset:2176
	global_load_dwordx4 v[150:153], v[192:193], off offset:2192
	global_load_dwordx4 v[154:157], v[192:193], off offset:2208
	global_load_dwordx4 v[158:161], v[192:193], off offset:2224
	s_waitcnt lgkmcnt(15)
	v_mfma_f32_32x32x16_f16 v[114:129], v[240:243], v[216:219], v[114:129]
	s_waitcnt lgkmcnt(15)
	v_mfma_f32_32x32x16_f16 v[98:113], v[244:247], v[216:219], v[98:113]
	s_waitcnt lgkmcnt(15)
	v_mfma_f32_32x32x16_f16 v[82:97], v[240:243], v[220:223], v[82:97]
	v_mfma_f32_32x32x16_f16 v[66:81], v[244:247], v[220:223], v[66:81]
	s_waitcnt lgkmcnt(15)
	v_mfma_f32_32x32x16_f16 v[50:65], v[240:243], v[224:227], v[50:65]
	v_mfma_f32_32x32x16_f16 v[34:49], v[244:247], v[224:227], v[34:49]
	s_waitcnt lgkmcnt(14)
	v_mfma_f32_32x32x16_f16 v[18:33], v[240:243], v[228:231], v[18:33]
	v_mfma_f32_32x32x16_f16 v[2:17], v[244:247], v[228:231], v[2:17]
	ds_read_b128 v[240:243], v213 offset:96
	ds_read_b128 v[216:219], v199 offset:96
	ds_read_b128 v[244:247], v213 offset:4704
	ds_read_b128 v[220:223], v199 offset:4704
	ds_read_b128 v[224:227], v199 offset:9312
	ds_read_b128 v[228:231], v199 offset:13920
	s_waitcnt lgkmcnt(14)
	v_mfma_f32_32x32x16_f16 v[114:129], v[232:235], v[188:191], v[114:129]
	s_waitcnt lgkmcnt(13)
	v_mfma_f32_32x32x16_f16 v[98:113], v[236:239], v[188:191], v[98:113]
	s_waitcnt lgkmcnt(12)
	v_mfma_f32_32x32x16_f16 v[82:97], v[232:235], v[200:203], v[82:97]
	v_mfma_f32_32x32x16_f16 v[66:81], v[236:239], v[200:203], v[66:81]
	s_waitcnt lgkmcnt(11)
	v_mfma_f32_32x32x16_f16 v[50:65], v[232:235], v[204:207], v[50:65]
	v_mfma_f32_32x32x16_f16 v[34:49], v[236:239], v[204:207], v[34:49]
	s_waitcnt lgkmcnt(10)
	v_mfma_f32_32x32x16_f16 v[18:33], v[232:235], v[208:211], v[18:33]
	v_mfma_f32_32x32x16_f16 v[2:17], v[236:239], v[208:211], v[2:17]
	s_waitcnt lgkmcnt(0)
	s_barrier
; DI f16v mfma32(h8v a, h8v b, f16v c) { return __builtin_amdgcn_mfma_f32_32x32x16_f16(a, b, c, 0, 0, 0); }
; template <bool GATHER>
; DI void gemm256_main(const h16* __restrict__ A, int lda, const int* __restrict__ idx, int m0,
;                      const h16* __restrict__ B, int ldb, int n0, int K, h16* lds, f16v (&acc)[4][2]) {
;     ...
;   for (int kt = 0; kt < nk; ++kt) {
;     const h16* As = lds + (kt & 1) * (512 * LDH);
;     const h16* Bs = As + 256 * LDH;
;     h16* Wn = lds + ((kt & 1) ^ 1) * (512 * LDH);
;     if (kt + 1 < nk) {
; #pragma unroll
;       for (int i = 0; i < 4; ++i) { *(u4v*)&Wn[lr * LDH + lc + 8 * i] = ra[i]; *(u4v*)&Wn[(256 + lr) * LDH + lc + 8 * i] = rb[i]; }
;     }
;     if (kt + 2 < nk) {
; #pragma unroll
;       for (int i = 0; i < 4; ++i) { ra[i] = *(const u4v*)(AP_ + 8 * i); rb[i] = *(const u4v*)(BP_ + 8 * i); }
;       ao += 64; bo += 64;
;     }
; #pragma unroll
;     for (int ks = 0; ks < 4; ++ks) {
;       h8v af[4], bf[2];
; #pragma unroll
;       for (int i = 0; i < 4; ++i) af[i] = *(const h8v*)&As[(wm * 128 + i * 32 + (lane & 31)) * LDH + ks * 16 + 8 * (lane >> 5)];
; #pragma unroll
;       for (int j = 0; j < 2; ++j) bf[j] = *(const h8v*)&Bs[(wn * 64 + j * 32 + (lane & 31)) * LDH + ks * 16 + 8 * (lane >> 5)];
; #pragma unroll
;       for (int i = 0; i < 4; ++i)
; #pragma unroll
;         for (int j = 0; j < 2; ++j) acc[i][j] = mfma32(bf[j], af[i], acc[i][j]);
;     }
;     __syncthreads();
	ds_read_b128 v[232:235], v212
	ds_read_b128 v[188:191], v194
	ds_read_b128 v[236:239], v212 offset:4608
	ds_read_b128 v[200:203], v194 offset:4608
	ds_read_b128 v[204:207], v194 offset:9216
	ds_read_b128 v[208:211], v194 offset:13824
	v_mfma_f32_32x32x16_f16 v[114:129], v[240:243], v[216:219], v[114:129]
	v_mfma_f32_32x32x16_f16 v[98:113], v[244:247], v[216:219], v[98:113]
	v_mfma_f32_32x32x16_f16 v[82:97], v[240:243], v[220:223], v[82:97]
	v_mfma_f32_32x32x16_f16 v[66:81], v[244:247], v[220:223], v[66:81]
	v_mfma_f32_32x32x16_f16 v[50:65], v[240:243], v[224:227], v[50:65]
	v_mfma_f32_32x32x16_f16 v[34:49], v[244:247], v[224:227], v[34:49]
	v_mfma_f32_32x32x16_f16 v[18:33], v[240:243], v[228:231], v[18:33]
	v_mfma_f32_32x32x16_f16 v[2:17], v[244:247], v[228:231], v[2:17]
	ds_read_b128 v[240:243], v212 offset:32
	ds_read_b128 v[216:219], v194 offset:32
	ds_read_b128 v[244:247], v212 offset:4640
	ds_read_b128 v[220:223], v194 offset:4640
	ds_read_b128 v[224:227], v194 offset:9248
	ds_read_b128 v[228:231], v194 offset:13856
	s_waitcnt vmcnt(4)
	ds_write_b128 v175, v[130:133]
	ds_write_b128 v175, v[134:137] offset:16
	ds_write_b128 v175, v[138:141] offset:32
	ds_write_b128 v175, v[142:145] offset:48
	global_load_dwordx4 v[130:133], v[164:165], off offset:2304
	global_load_dwordx4 v[134:137], v[164:165], off offset:2320
	global_load_dwordx4 v[138:141], v[164:165], off offset:2336
	global_load_dwordx4 v[142:145], v[164:165], off offset:2352
	s_waitcnt lgkmcnt(14)
	v_mfma_f32_32x32x16_f16 v[114:129], v[232:235], v[188:191], v[114:129]
	s_waitcnt lgkmcnt(13)
	v_mfma_f32_32x32x16_f16 v[98:113], v[236:239], v[188:191], v[98:113]
	s_waitcnt lgkmcnt(12)
	v_mfma_f32_32x32x16_f16 v[82:97], v[232:235], v[200:203], v[82:97]
	v_mfma_f32_32x32x16_f16 v[66:81], v[236:239], v[200:203], v[66:81]
	s_waitcnt lgkmcnt(11)
	v_mfma_f32_32x32x16_f16 v[50:65], v[232:235], v[204:207], v[50:65]
	v_mfma_f32_32x32x16_f16 v[34:49], v[236:239], v[204:207], v[34:49]
	s_waitcnt lgkmcnt(10)
	v_mfma_f32_32x32x16_f16 v[18:33], v[232:235], v[208:211], v[18:33]
	v_mfma_f32_32x32x16_f16 v[2:17], v[236:239], v[208:211], v[2:17]
	ds_read_b128 v[232:235], v212 offset:64
	ds_read_b128 v[188:191], v194 offset:64
	ds_read_b128 v[236:239], v212 offset:4672
	ds_read_b128 v[200:203], v194 offset:4672
	ds_read_b128 v[204:207], v194 offset:9280
	ds_read_b128 v[208:211], v194 offset:13888
	s_waitcnt vmcnt(4)
	ds_write_b128 v175, v[146:149] offset:36864
	ds_write_b128 v175, v[150:153] offset:36880
	ds_write_b128 v175, v[154:157] offset:36896
	ds_write_b128 v175, v[158:161] offset:36912
	global_load_dwordx4 v[146:149], v[192:193], off offset:2304
	global_load_dwordx4 v[150:153], v[192:193], off offset:2320
	global_load_dwordx4 v[154:157], v[192:193], off offset:2336
	global_load_dwordx4 v[158:161], v[192:193], off offset:2352
	s_waitcnt lgkmcnt(15)
	v_mfma_f32_32x32x16_f16 v[114:129], v[240:243], v[216:219], v[114:129]
	s_waitcnt lgkmcnt(15)
	v_mfma_f32_32x32x16_f16 v[98:113], v[244:247], v[216:219], v[98:113]
	s_waitcnt lgkmcnt(15)
	v_mfma_f32_32x32x16_f16 v[82:97], v[240:243], v[220:223], v[82:97]
	v_mfma_f32_32x32x16_f16 v[66:81], v[244:247], v[220:223], v[66:81]
	s_waitcnt lgkmcnt(15)
	v_mfma_f32_32x32x16_f16 v[50:65], v[240:243], v[224:227], v[50:65]
	v_mfma_f32_32x32x16_f16 v[34:49], v[244:247], v[224:227], v[34:49]
	s_waitcnt lgkmcnt(14)
	v_mfma_f32_32x32x16_f16 v[18:33], v[240:243], v[228:231], v[18:33]
	v_mfma_f32_32x32x16_f16 v[2:17], v[244:247], v[228:231], v[2:17]
	ds_read_b128 v[240:243], v212 offset:96
	ds_read_b128 v[216:219], v194 offset:96
	ds_read_b128 v[244:247], v212 offset:4704
	ds_read_b128 v[220:223], v194 offset:4704
	ds_read_b128 v[224:227], v194 offset:9312
	ds_read_b128 v[228:231], v194 offset:13920
	s_waitcnt lgkmcnt(14)
	v_mfma_f32_32x32x16_f16 v[114:129], v[232:235], v[188:191], v[114:129]
	s_waitcnt lgkmcnt(13)
	v_mfma_f32_32x32x16_f16 v[98:113], v[236:239], v[188:191], v[98:113]
	s_waitcnt lgkmcnt(12)
	v_mfma_f32_32x32x16_f16 v[82:97], v[232:235], v[200:203], v[82:97]
	v_mfma_f32_32x32x16_f16 v[66:81], v[236:239], v[200:203], v[66:81]
	s_waitcnt lgkmcnt(11)
	v_mfma_f32_32x32x16_f16 v[50:65], v[232:235], v[204:207], v[50:65]
	v_mfma_f32_32x32x16_f16 v[34:49], v[236:239], v[204:207], v[34:49]
	s_waitcnt lgkmcnt(10)
	v_mfma_f32_32x32x16_f16 v[18:33], v[232:235], v[208:211], v[18:33]
	v_mfma_f32_32x32x16_f16 v[2:17], v[236:239], v[208:211], v[2:17]
	s_waitcnt lgkmcnt(0)
	s_barrier
; DI f16v mfma32(h8v a, h8v b, f16v c) { return __builtin_amdgcn_mfma_f32_32x32x16_f16(a, b, c, 0, 0, 0); }
; template <bool GATHER>
; DI void gemm256_main(const h16* __restrict__ A, int lda, const int* __restrict__ idx, int m0,
;                      const h16* __restrict__ B, int ldb, int n0, int K, h16* lds, f16v (&acc)[4][2]) {
;     ...
;   for (int kt = 0; kt < nk; ++kt) {
;     const h16* As = lds + (kt & 1) * (512 * LDH);
;     const h16* Bs = As + 256 * LDH;
;     h16* Wn = lds + ((kt & 1) ^ 1) * (512 * LDH);
;     if (kt + 1 < nk) {
; #pragma unroll
;       for (int i = 0; i < 4; ++i) { *(u4v*)&Wn[lr * LDH + lc + 8 * i] = ra[i]; *(u4v*)&Wn[(256 + lr) * LDH + lc + 8 * i] = rb[i]; }
;     }
;     if (kt + 2 < nk) {
; #pragma unroll
;       for (int i = 0; i < 4; ++i) { ra[i] = *(const u4v*)(AP_ + 8 * i); rb[i] = *(const u4v*)(BP_ + 8 * i); }
;       ao += 64; bo += 64;
;     }
; #pragma unroll
;     for (int ks = 0; ks < 4; ++ks) {
;       h8v af[4], bf[2];
; #pragma unroll
;       for (int i = 0; i < 4; ++i) af[i] = *(const h8v*)&As[(wm * 128 + i * 32 + (lane & 31)) * LDH + ks * 16 + 8 * (lane >> 5)];
; #pragma unroll
;       for (int j = 0; j < 2; ++j) bf[j] = *(const h8v*)&Bs[(wn * 64 + j * 32 + (lane & 31)) * LDH + ks * 16 + 8 * (lane >> 5)];
; #pragma unroll
;       for (int i = 0; i < 4; ++i)
; #pragma unroll
;         for (int j = 0; j < 2; ++j) acc[i][j] = mfma32(bf[j], af[i], acc[i][j]);
;     }
;     __syncthreads();
	ds_read_b128 v[232:235], v213
	ds_read_b128 v[188:191], v199
	ds_read_b128 v[236:239], v213 offset:4608
	ds_read_b128 v[200:203], v199 offset:4608
	ds_read_b128 v[204:207], v199 offset:9216
	ds_read_b128 v[208:211], v199 offset:13824
	v_mfma_f32_32x32x16_f16 v[114:129], v[240:243], v[216:219], v[114:129]
	v_mfma_f32_32x32x16_f16 v[98:113], v[244:247], v[216:219], v[98:113]
	v_mfma_f32_32x32x16_f16 v[82:97], v[240:243], v[220:223], v[82:97]
	v_mfma_f32_32x32x16_f16 v[66:81], v[244:247], v[220:223], v[66:81]
	v_mfma_f32_32x32x16_f16 v[50:65], v[240:243], v[224:227], v[50:65]
	v_mfma_f32_32x32x16_f16 v[34:49], v[244:247], v[224:227], v[34:49]
	v_mfma_f32_32x32x16_f16 v[18:33], v[240:243], v[228:231], v[18:33]
	v_mfma_f32_32x32x16_f16 v[2:17], v[244:247], v[228:231], v[2:17]
	ds_read_b128 v[240:243], v213 offset:32
	ds_read_b128 v[216:219], v199 offset:32
	ds_read_b128 v[244:247], v213 offset:4640
	ds_read_b128 v[220:223], v199 offset:4640
	ds_read_b128 v[224:227], v199 offset:9248
	ds_read_b128 v[228:231], v199 offset:13856
	s_waitcnt vmcnt(4)
	ds_write_b128 v163, v[130:133]
	ds_write_b128 v163, v[134:137] offset:16
	ds_write_b128 v163, v[138:141] offset:32
	ds_write_b128 v163, v[142:145] offset:48
	global_load_dwordx4 v[130:133], v[164:165], off offset:2432
	global_load_dwordx4 v[134:137], v[164:165], off offset:2448
	global_load_dwordx4 v[138:141], v[164:165], off offset:2464
	global_load_dwordx4 v[142:145], v[164:165], off offset:2480
	s_waitcnt lgkmcnt(14)
	v_mfma_f32_32x32x16_f16 v[114:129], v[232:235], v[188:191], v[114:129]
	s_waitcnt lgkmcnt(13)
	v_mfma_f32_32x32x16_f16 v[98:113], v[236:239], v[188:191], v[98:113]
	s_waitcnt lgkmcnt(12)
	v_mfma_f32_32x32x16_f16 v[82:97], v[232:235], v[200:203], v[82:97]
	v_mfma_f32_32x32x16_f16 v[66:81], v[236:239], v[200:203], v[66:81]
	s_waitcnt lgkmcnt(11)
	v_mfma_f32_32x32x16_f16 v[50:65], v[232:235], v[204:207], v[50:65]
	v_mfma_f32_32x32x16_f16 v[34:49], v[236:239], v[204:207], v[34:49]
	s_waitcnt lgkmcnt(10)
	v_mfma_f32_32x32x16_f16 v[18:33], v[232:235], v[208:211], v[18:33]
	v_mfma_f32_32x32x16_f16 v[2:17], v[236:239], v[208:211], v[2:17]
	ds_read_b128 v[232:235], v213 offset:64
	ds_read_b128 v[188:191], v199 offset:64
	ds_read_b128 v[236:239], v213 offset:4672
	ds_read_b128 v[200:203], v199 offset:4672
	ds_read_b128 v[204:207], v199 offset:9280
	ds_read_b128 v[208:211], v199 offset:13888
	s_waitcnt vmcnt(4)
	ds_write_b128 v163, v[146:149] offset:36864
	ds_write_b128 v163, v[150:153] offset:36880
	ds_write_b128 v163, v[154:157] offset:36896
	ds_write_b128 v163, v[158:161] offset:36912
	global_load_dwordx4 v[146:149], v[192:193], off offset:2432
	global_load_dwordx4 v[150:153], v[192:193], off offset:2448
	global_load_dwordx4 v[154:157], v[192:193], off offset:2464
	global_load_dwordx4 v[158:161], v[192:193], off offset:2480
	s_waitcnt lgkmcnt(15)
	v_mfma_f32_32x32x16_f16 v[114:129], v[240:243], v[216:219], v[114:129]
	s_waitcnt lgkmcnt(15)
	v_mfma_f32_32x32x16_f16 v[98:113], v[244:247], v[216:219], v[98:113]
	s_waitcnt lgkmcnt(15)
	v_mfma_f32_32x32x16_f16 v[82:97], v[240:243], v[220:223], v[82:97]
	v_mfma_f32_32x32x16_f16 v[66:81], v[244:247], v[220:223], v[66:81]
	s_waitcnt lgkmcnt(15)
	v_mfma_f32_32x32x16_f16 v[50:65], v[240:243], v[224:227], v[50:65]
	v_mfma_f32_32x32x16_f16 v[34:49], v[244:247], v[224:227], v[34:49]
	s_waitcnt lgkmcnt(14)
	v_mfma_f32_32x32x16_f16 v[18:33], v[240:243], v[228:231], v[18:33]
	v_mfma_f32_32x32x16_f16 v[2:17], v[244:247], v[228:231], v[2:17]
	ds_read_b128 v[240:243], v213 offset:96
	ds_read_b128 v[216:219], v199 offset:96
	ds_read_b128 v[244:247], v213 offset:4704
	ds_read_b128 v[220:223], v199 offset:4704
	ds_read_b128 v[224:227], v199 offset:9312
	ds_read_b128 v[228:231], v199 offset:13920
	s_waitcnt lgkmcnt(14)
	v_mfma_f32_32x32x16_f16 v[114:129], v[232:235], v[188:191], v[114:129]
	s_waitcnt lgkmcnt(13)
	v_mfma_f32_32x32x16_f16 v[98:113], v[236:239], v[188:191], v[98:113]
	s_waitcnt lgkmcnt(12)
	v_mfma_f32_32x32x16_f16 v[82:97], v[232:235], v[200:203], v[82:97]
	v_mfma_f32_32x32x16_f16 v[66:81], v[236:239], v[200:203], v[66:81]
	s_waitcnt lgkmcnt(11)
	v_mfma_f32_32x32x16_f16 v[50:65], v[232:235], v[204:207], v[50:65]
	v_mfma_f32_32x32x16_f16 v[34:49], v[236:239], v[204:207], v[34:49]
	s_waitcnt lgkmcnt(10)
	v_mfma_f32_32x32x16_f16 v[18:33], v[232:235], v[208:211], v[18:33]
	v_mfma_f32_32x32x16_f16 v[2:17], v[236:239], v[208:211], v[2:17]
	s_waitcnt lgkmcnt(0)
	s_barrier
; DI f16v mfma32(h8v a, h8v b, f16v c) { return __builtin_amdgcn_mfma_f32_32x32x16_f16(a, b, c, 0, 0, 0); }
; template <bool GATHER>
; DI void gemm256_main(const h16* __restrict__ A, int lda, const int* __restrict__ idx, int m0,
;                      const h16* __restrict__ B, int ldb, int n0, int K, h16* lds, f16v (&acc)[4][2]) {
;     ...
;   for (int kt = 0; kt < nk; ++kt) {
;     const h16* As = lds + (kt & 1) * (512 * LDH);
;     const h16* Bs = As + 256 * LDH;
;     h16* Wn = lds + ((kt & 1) ^ 1) * (512 * LDH);
;     if (kt + 1 < nk) {
; #pragma unroll
;       for (int i = 0; i < 4; ++i) { *(u4v*)&Wn[lr * LDH + lc + 8 * i] = ra[i]; *(u4v*)&Wn[(256 + lr) * LDH + lc + 8 * i] = rb[i]; }
;     }
;     if (kt + 2 < nk) {
; #pragma unroll
;       for (int i = 0; i < 4; ++i) { ra[i] = *(const u4v*)(AP_ + 8 * i); rb[i] = *(const u4v*)(BP_ + 8 * i); }
;       ao += 64; bo += 64;
;     }
; #pragma unroll
;     for (int ks = 0; ks < 4; ++ks) {
;       h8v af[4], bf[2];
; #pragma unroll
;       for (int i = 0; i < 4; ++i) af[i] = *(const h8v*)&As[(wm * 128 + i * 32 + (lane & 31)) * LDH + ks * 16 + 8 * (lane >> 5)];
; #pragma unroll
;       for (int j = 0; j < 2; ++j) bf[j] = *(const h8v*)&Bs[(wn * 64 + j * 32 + (lane & 31)) * LDH + ks * 16 + 8 * (lane >> 5)];
; #pragma unroll
;       for (int i = 0; i < 4; ++i)
; #pragma unroll
;         for (int j = 0; j < 2; ++j) acc[i][j] = mfma32(bf[j], af[i], acc[i][j]);
;     }
;     __syncthreads();
	ds_read_b128 v[232:235], v212
	ds_read_b128 v[188:191], v194
	ds_read_b128 v[236:239], v212 offset:4608
	ds_read_b128 v[200:203], v194 offset:4608
	ds_read_b128 v[204:207], v194 offset:9216
	ds_read_b128 v[208:211], v194 offset:13824
	v_mfma_f32_32x32x16_f16 v[114:129], v[240:243], v[216:219], v[114:129]
	v_mfma_f32_32x32x16_f16 v[98:113], v[244:247], v[216:219], v[98:113]
	v_mfma_f32_32x32x16_f16 v[82:97], v[240:243], v[220:223], v[82:97]
	v_mfma_f32_32x32x16_f16 v[66:81], v[244:247], v[220:223], v[66:81]
	v_mfma_f32_32x32x16_f16 v[50:65], v[240:243], v[224:227], v[50:65]
	v_mfma_f32_32x32x16_f16 v[34:49], v[244:247], v[224:227], v[34:49]
	v_mfma_f32_32x32x16_f16 v[18:33], v[240:243], v[228:231], v[18:33]
	v_mfma_f32_32x32x16_f16 v[2:17], v[244:247], v[228:231], v[2:17]
	ds_read_b128 v[240:243], v212 offset:32
	ds_read_b128 v[216:219], v194 offset:32
	ds_read_b128 v[244:247], v212 offset:4640
	ds_read_b128 v[220:223], v194 offset:4640
	ds_read_b128 v[224:227], v194 offset:9248
	ds_read_b128 v[228:231], v194 offset:13856
	s_waitcnt vmcnt(4)
	ds_write_b128 v175, v[130:133]
	ds_write_b128 v175, v[134:137] offset:16
	ds_write_b128 v175, v[138:141] offset:32
	ds_write_b128 v175, v[142:145] offset:48
	global_load_dwordx4 v[130:133], v[164:165], off offset:2560
	global_load_dwordx4 v[134:137], v[164:165], off offset:2576
	global_load_dwordx4 v[138:141], v[164:165], off offset:2592
	global_load_dwordx4 v[142:145], v[164:165], off offset:2608
	s_waitcnt lgkmcnt(14)
	v_mfma_f32_32x32x16_f16 v[114:129], v[232:235], v[188:191], v[114:129]
	s_waitcnt lgkmcnt(13)
	v_mfma_f32_32x32x16_f16 v[98:113], v[236:239], v[188:191], v[98:113]
	s_waitcnt lgkmcnt(12)
	v_mfma_f32_32x32x16_f16 v[82:97], v[232:235], v[200:203], v[82:97]
	v_mfma_f32_32x32x16_f16 v[66:81], v[236:239], v[200:203], v[66:81]
	s_waitcnt lgkmcnt(11)
	v_mfma_f32_32x32x16_f16 v[50:65], v[232:235], v[204:207], v[50:65]
	v_mfma_f32_32x32x16_f16 v[34:49], v[236:239], v[204:207], v[34:49]
	s_waitcnt lgkmcnt(10)
	v_mfma_f32_32x32x16_f16 v[18:33], v[232:235], v[208:211], v[18:33]
	v_mfma_f32_32x32x16_f16 v[2:17], v[236:239], v[208:211], v[2:17]
	ds_read_b128 v[232:235], v212 offset:64
	ds_read_b128 v[188:191], v194 offset:64
	ds_read_b128 v[236:239], v212 offset:4672
	ds_read_b128 v[200:203], v194 offset:4672
	ds_read_b128 v[204:207], v194 offset:9280
	ds_read_b128 v[208:211], v194 offset:13888
	s_waitcnt vmcnt(4)
	ds_write_b128 v175, v[146:149] offset:36864
	ds_write_b128 v175, v[150:153] offset:36880
	ds_write_b128 v175, v[154:157] offset:36896
	ds_write_b128 v175, v[158:161] offset:36912
	global_load_dwordx4 v[146:149], v[192:193], off offset:2560
	global_load_dwordx4 v[150:153], v[192:193], off offset:2576
	global_load_dwordx4 v[154:157], v[192:193], off offset:2592
	global_load_dwordx4 v[158:161], v[192:193], off offset:2608
	s_waitcnt lgkmcnt(15)
	v_mfma_f32_32x32x16_f16 v[114:129], v[240:243], v[216:219], v[114:129]
	s_waitcnt lgkmcnt(15)
	v_mfma_f32_32x32x16_f16 v[98:113], v[244:247], v[216:219], v[98:113]
	s_waitcnt lgkmcnt(15)
	v_mfma_f32_32x32x16_f16 v[82:97], v[240:243], v[220:223], v[82:97]
	v_mfma_f32_32x32x16_f16 v[66:81], v[244:247], v[220:223], v[66:81]
	s_waitcnt lgkmcnt(15)
	v_mfma_f32_32x32x16_f16 v[50:65], v[240:243], v[224:227], v[50:65]
	v_mfma_f32_32x32x16_f16 v[34:49], v[244:247], v[224:227], v[34:49]
	s_waitcnt lgkmcnt(14)
	v_mfma_f32_32x32x16_f16 v[18:33], v[240:243], v[228:231], v[18:33]
	v_mfma_f32_32x32x16_f16 v[2:17], v[244:247], v[228:231], v[2:17]
	ds_read_b128 v[240:243], v212 offset:96
	ds_read_b128 v[216:219], v194 offset:96
	ds_read_b128 v[244:247], v212 offset:4704
	ds_read_b128 v[220:223], v194 offset:4704
	ds_read_b128 v[224:227], v194 offset:9312
	ds_read_b128 v[228:231], v194 offset:13920
	s_waitcnt lgkmcnt(14)
	v_mfma_f32_32x32x16_f16 v[114:129], v[232:235], v[188:191], v[114:129]
	s_waitcnt lgkmcnt(13)
	v_mfma_f32_32x32x16_f16 v[98:113], v[236:239], v[188:191], v[98:113]
	s_waitcnt lgkmcnt(12)
	v_mfma_f32_32x32x16_f16 v[82:97], v[232:235], v[200:203], v[82:97]
	v_mfma_f32_32x32x16_f16 v[66:81], v[236:239], v[200:203], v[66:81]
	s_waitcnt lgkmcnt(11)
	v_mfma_f32_32x32x16_f16 v[50:65], v[232:235], v[204:207], v[50:65]
	v_mfma_f32_32x32x16_f16 v[34:49], v[236:239], v[204:207], v[34:49]
	s_waitcnt lgkmcnt(10)
	v_mfma_f32_32x32x16_f16 v[18:33], v[232:235], v[208:211], v[18:33]
	v_mfma_f32_32x32x16_f16 v[2:17], v[236:239], v[208:211], v[2:17]
	s_waitcnt lgkmcnt(0)
	s_barrier
; DI f16v mfma32(h8v a, h8v b, f16v c) { return __builtin_amdgcn_mfma_f32_32x32x16_f16(a, b, c, 0, 0, 0); }
; template <bool GATHER>
; DI void gemm256_main(const h16* __restrict__ A, int lda, const int* __restrict__ idx, int m0,
;                      const h16* __restrict__ B, int ldb, int n0, int K, h16* lds, f16v (&acc)[4][2]) {
;     ...
;   for (int kt = 0; kt < nk; ++kt) {
;     const h16* As = lds + (kt & 1) * (512 * LDH);
;     const h16* Bs = As + 256 * LDH;
;     h16* Wn = lds + ((kt & 1) ^ 1) * (512 * LDH);
;     if (kt + 1 < nk) {
; #pragma unroll
;       for (int i = 0; i < 4; ++i) { *(u4v*)&Wn[lr * LDH + lc + 8 * i] = ra[i]; *(u4v*)&Wn[(256 + lr) * LDH + lc + 8 * i] = rb[i]; }
;     }
;     if (kt + 2 < nk) {
; #pragma unroll
;       for (int i = 0; i < 4; ++i) { ra[i] = *(const u4v*)(AP_ + 8 * i); rb[i] = *(const u4v*)(BP_ + 8 * i); }
;       ao += 64; bo += 64;
;     }
; #pragma unroll
;     for (int ks = 0; ks < 4; ++ks) {
;       h8v af[4], bf[2];
; #pragma unroll
;       for (int i = 0; i < 4; ++i) af[i] = *(const h8v*)&As[(wm * 128 + i * 32 + (lane & 31)) * LDH + ks * 16 + 8 * (lane >> 5)];
; #pragma unroll
;       for (int j = 0; j < 2; ++j) bf[j] = *(const h8v*)&Bs[(wn * 64 + j * 32 + (lane & 31)) * LDH + ks * 16 + 8 * (lane >> 5)];
; #pragma unroll
;       for (int i = 0; i < 4; ++i)
; #pragma unroll
;         for (int j = 0; j < 2; ++j) acc[i][j] = mfma32(bf[j], af[i], acc[i][j]);
;     }
;     __syncthreads();
	ds_read_b128 v[232:235], v213
	ds_read_b128 v[188:191], v199
	ds_read_b128 v[236:239], v213 offset:4608
	ds_read_b128 v[200:203], v199 offset:4608
	ds_read_b128 v[204:207], v199 offset:9216
	ds_read_b128 v[208:211], v199 offset:13824
	v_mfma_f32_32x32x16_f16 v[114:129], v[240:243], v[216:219], v[114:129]
	v_mfma_f32_32x32x16_f16 v[98:113], v[244:247], v[216:219], v[98:113]
	v_mfma_f32_32x32x16_f16 v[82:97], v[240:243], v[220:223], v[82:97]
	v_mfma_f32_32x32x16_f16 v[66:81], v[244:247], v[220:223], v[66:81]
	v_mfma_f32_32x32x16_f16 v[50:65], v[240:243], v[224:227], v[50:65]
	v_mfma_f32_32x32x16_f16 v[34:49], v[244:247], v[224:227], v[34:49]
	v_mfma_f32_32x32x16_f16 v[18:33], v[240:243], v[228:231], v[18:33]
	v_mfma_f32_32x32x16_f16 v[2:17], v[244:247], v[228:231], v[2:17]
	ds_read_b128 v[240:243], v213 offset:32
	ds_read_b128 v[216:219], v199 offset:32
	ds_read_b128 v[244:247], v213 offset:4640
	ds_read_b128 v[220:223], v199 offset:4640
	ds_read_b128 v[224:227], v199 offset:9248
	ds_read_b128 v[228:231], v199 offset:13856
	s_waitcnt vmcnt(4)
	ds_write_b128 v163, v[130:133]
	ds_write_b128 v163, v[134:137] offset:16
	ds_write_b128 v163, v[138:141] offset:32
	ds_write_b128 v163, v[142:145] offset:48
	global_load_dwordx4 v[130:133], v[164:165], off offset:2688
	global_load_dwordx4 v[134:137], v[164:165], off offset:2704
	global_load_dwordx4 v[138:141], v[164:165], off offset:2720
	global_load_dwordx4 v[142:145], v[164:165], off offset:2736
	s_waitcnt lgkmcnt(14)
	v_mfma_f32_32x32x16_f16 v[114:129], v[232:235], v[188:191], v[114:129]
	s_waitcnt lgkmcnt(13)
	v_mfma_f32_32x32x16_f16 v[98:113], v[236:239], v[188:191], v[98:113]
	s_waitcnt lgkmcnt(12)
	v_mfma_f32_32x32x16_f16 v[82:97], v[232:235], v[200:203], v[82:97]
	v_mfma_f32_32x32x16_f16 v[66:81], v[236:239], v[200:203], v[66:81]
	s_waitcnt lgkmcnt(11)
	v_mfma_f32_32x32x16_f16 v[50:65], v[232:235], v[204:207], v[50:65]
	v_mfma_f32_32x32x16_f16 v[34:49], v[236:239], v[204:207], v[34:49]
	s_waitcnt lgkmcnt(10)
	v_mfma_f32_32x32x16_f16 v[18:33], v[232:235], v[208:211], v[18:33]
	v_mfma_f32_32x32x16_f16 v[2:17], v[236:239], v[208:211], v[2:17]
	ds_read_b128 v[232:235], v213 offset:64
	ds_read_b128 v[188:191], v199 offset:64
	ds_read_b128 v[236:239], v213 offset:4672
	ds_read_b128 v[200:203], v199 offset:4672
	ds_read_b128 v[204:207], v199 offset:9280
	ds_read_b128 v[208:211], v199 offset:13888
	s_waitcnt vmcnt(4)
	ds_write_b128 v163, v[146:149] offset:36864
	ds_write_b128 v163, v[150:153] offset:36880
	ds_write_b128 v163, v[154:157] offset:36896
	ds_write_b128 v163, v[158:161] offset:36912
	global_load_dwordx4 v[146:149], v[192:193], off offset:2688
	global_load_dwordx4 v[150:153], v[192:193], off offset:2704
	global_load_dwordx4 v[154:157], v[192:193], off offset:2720
	global_load_dwordx4 v[158:161], v[192:193], off offset:2736
	s_waitcnt lgkmcnt(15)
	v_mfma_f32_32x32x16_f16 v[114:129], v[240:243], v[216:219], v[114:129]
	s_waitcnt lgkmcnt(15)
	v_mfma_f32_32x32x16_f16 v[98:113], v[244:247], v[216:219], v[98:113]
	s_waitcnt lgkmcnt(15)
	v_mfma_f32_32x32x16_f16 v[82:97], v[240:243], v[220:223], v[82:97]
	v_mfma_f32_32x32x16_f16 v[66:81], v[244:247], v[220:223], v[66:81]
	s_waitcnt lgkmcnt(15)
	v_mfma_f32_32x32x16_f16 v[50:65], v[240:243], v[224:227], v[50:65]
	v_mfma_f32_32x32x16_f16 v[34:49], v[244:247], v[224:227], v[34:49]
	s_waitcnt lgkmcnt(14)
	v_mfma_f32_32x32x16_f16 v[18:33], v[240:243], v[228:231], v[18:33]
	v_mfma_f32_32x32x16_f16 v[2:17], v[244:247], v[228:231], v[2:17]
	ds_read_b128 v[240:243], v213 offset:96
	ds_read_b128 v[216:219], v199 offset:96
	ds_read_b128 v[244:247], v213 offset:4704
	ds_read_b128 v[220:223], v199 offset:4704
	ds_read_b128 v[224:227], v199 offset:9312
	ds_read_b128 v[228:231], v199 offset:13920
	s_waitcnt lgkmcnt(14)
	v_mfma_f32_32x32x16_f16 v[114:129], v[232:235], v[188:191], v[114:129]
	s_waitcnt lgkmcnt(13)
	v_mfma_f32_32x32x16_f16 v[98:113], v[236:239], v[188:191], v[98:113]
	s_waitcnt lgkmcnt(12)
	v_mfma_f32_32x32x16_f16 v[82:97], v[232:235], v[200:203], v[82:97]
	v_mfma_f32_32x32x16_f16 v[66:81], v[236:239], v[200:203], v[66:81]
	s_waitcnt lgkmcnt(11)
	v_mfma_f32_32x32x16_f16 v[50:65], v[232:235], v[204:207], v[50:65]
	v_mfma_f32_32x32x16_f16 v[34:49], v[236:239], v[204:207], v[34:49]
	s_waitcnt lgkmcnt(10)
	v_mfma_f32_32x32x16_f16 v[18:33], v[232:235], v[208:211], v[18:33]
	v_mfma_f32_32x32x16_f16 v[2:17], v[236:239], v[208:211], v[2:17]
	s_waitcnt lgkmcnt(0)
	s_barrier
; DI f16v mfma32(h8v a, h8v b, f16v c) { return __builtin_amdgcn_mfma_f32_32x32x16_f16(a, b, c, 0, 0, 0); }
; template <bool GATHER>
; DI void gemm256_main(const h16* __restrict__ A, int lda, const int* __restrict__ idx, int m0,
;                      const h16* __restrict__ B, int ldb, int n0, int K, h16* lds, f16v (&acc)[4][2]) {
;     ...
;   for (int kt = 0; kt < nk; ++kt) {
;     const h16* As = lds + (kt & 1) * (512 * LDH);
;     const h16* Bs = As + 256 * LDH;
;     h16* Wn = lds + ((kt & 1) ^ 1) * (512 * LDH);
;     if (kt + 1 < nk) {
; #pragma unroll
;       for (int i = 0; i < 4; ++i) { *(u4v*)&Wn[lr * LDH + lc + 8 * i] = ra[i]; *(u4v*)&Wn[(256 + lr) * LDH + lc + 8 * i] = rb[i]; }
;     }
;     if (kt + 2 < nk) {
; #pragma unroll
;       for (int i = 0; i < 4; ++i) { ra[i] = *(const u4v*)(AP_ + 8 * i); rb[i] = *(const u4v*)(BP_ + 8 * i); }
;       ao += 64; bo += 64;
;     }
; #pragma unroll
;     for (int ks = 0; ks < 4; ++ks) {
;       h8v af[4], bf[2];
; #pragma unroll
;       for (int i = 0; i < 4; ++i) af[i] = *(const h8v*)&As[(wm * 128 + i * 32 + (lane & 31)) * LDH + ks * 16 + 8 * (lane >> 5)];
; #pragma unroll
;       for (int j = 0; j < 2; ++j) bf[j] = *(const h8v*)&Bs[(wn * 64 + j * 32 + (lane & 31)) * LDH + ks * 16 + 8 * (lane >> 5)];
; #pragma unroll
;       for (int i = 0; i < 4; ++i)
; #pragma unroll
;         for (int j = 0; j < 2; ++j) acc[i][j] = mfma32(bf[j], af[i], acc[i][j]);
;     }
;     __syncthreads();
	ds_read_b128 v[232:235], v212
	ds_read_b128 v[188:191], v194
	ds_read_b128 v[236:239], v212 offset:4608
	ds_read_b128 v[200:203], v194 offset:4608
	ds_read_b128 v[204:207], v194 offset:9216
	ds_read_b128 v[208:211], v194 offset:13824
	v_mfma_f32_32x32x16_f16 v[114:129], v[240:243], v[216:219], v[114:129]
	v_mfma_f32_32x32x16_f16 v[98:113], v[244:247], v[216:219], v[98:113]
	v_mfma_f32_32x32x16_f16 v[82:97], v[240:243], v[220:223], v[82:97]
	v_mfma_f32_32x32x16_f16 v[66:81], v[244:247], v[220:223], v[66:81]
	v_mfma_f32_32x32x16_f16 v[50:65], v[240:243], v[224:227], v[50:65]
	v_mfma_f32_32x32x16_f16 v[34:49], v[244:247], v[224:227], v[34:49]
	v_mfma_f32_32x32x16_f16 v[18:33], v[240:243], v[228:231], v[18:33]
	v_mfma_f32_32x32x16_f16 v[2:17], v[244:247], v[228:231], v[2:17]
	ds_read_b128 v[240:243], v212 offset:32
	ds_read_b128 v[216:219], v194 offset:32
	ds_read_b128 v[244:247], v212 offset:4640
	ds_read_b128 v[220:223], v194 offset:4640
	ds_read_b128 v[224:227], v194 offset:9248
	ds_read_b128 v[228:231], v194 offset:13856
	s_waitcnt vmcnt(4)
	ds_write_b128 v175, v[130:133]
	ds_write_b128 v175, v[134:137] offset:16
	ds_write_b128 v175, v[138:141] offset:32
	ds_write_b128 v175, v[142:145] offset:48
	s_waitcnt lgkmcnt(14)
	v_mfma_f32_32x32x16_f16 v[114:129], v[232:235], v[188:191], v[114:129]
	s_waitcnt lgkmcnt(13)
	v_mfma_f32_32x32x16_f16 v[98:113], v[236:239], v[188:191], v[98:113]
	s_waitcnt lgkmcnt(12)
	v_mfma_f32_32x32x16_f16 v[82:97], v[232:235], v[200:203], v[82:97]
	v_mfma_f32_32x32x16_f16 v[66:81], v[236:239], v[200:203], v[66:81]
	s_waitcnt lgkmcnt(11)
	v_mfma_f32_32x32x16_f16 v[50:65], v[232:235], v[204:207], v[50:65]
	v_mfma_f32_32x32x16_f16 v[34:49], v[236:239], v[204:207], v[34:49]
	s_waitcnt lgkmcnt(10)
	v_mfma_f32_32x32x16_f16 v[18:33], v[232:235], v[208:211], v[18:33]
	v_mfma_f32_32x32x16_f16 v[2:17], v[236:239], v[208:211], v[2:17]
	ds_read_b128 v[232:235], v212 offset:64
	ds_read_b128 v[188:191], v194 offset:64
	ds_read_b128 v[236:239], v212 offset:4672
	ds_read_b128 v[200:203], v194 offset:4672
	ds_read_b128 v[204:207], v194 offset:9280
	ds_read_b128 v[208:211], v194 offset:13888
	s_waitcnt vmcnt(0)
	ds_write_b128 v175, v[146:149] offset:36864
	ds_write_b128 v175, v[150:153] offset:36880
	ds_write_b128 v175, v[154:157] offset:36896
	ds_write_b128 v175, v[158:161] offset:36912
	s_waitcnt lgkmcnt(15)
	v_mfma_f32_32x32x16_f16 v[114:129], v[240:243], v[216:219], v[114:129]
	s_waitcnt lgkmcnt(15)
	v_mfma_f32_32x32x16_f16 v[98:113], v[244:247], v[216:219], v[98:113]
	s_waitcnt lgkmcnt(15)
	v_mfma_f32_32x32x16_f16 v[82:97], v[240:243], v[220:223], v[82:97]
	v_mfma_f32_32x32x16_f16 v[66:81], v[244:247], v[220:223], v[66:81]
	s_waitcnt lgkmcnt(15)
	v_mfma_f32_32x32x16_f16 v[50:65], v[240:243], v[224:227], v[50:65]
	v_mfma_f32_32x32x16_f16 v[34:49], v[244:247], v[224:227], v[34:49]
	s_waitcnt lgkmcnt(14)
	v_mfma_f32_32x32x16_f16 v[18:33], v[240:243], v[228:231], v[18:33]
	v_mfma_f32_32x32x16_f16 v[2:17], v[244:247], v[228:231], v[2:17]
	ds_read_b128 v[240:243], v212 offset:96
	ds_read_b128 v[216:219], v194 offset:96
	ds_read_b128 v[244:247], v212 offset:4704
	ds_read_b128 v[220:223], v194 offset:4704
	ds_read_b128 v[224:227], v194 offset:9312
	ds_read_b128 v[228:231], v194 offset:13920
	s_waitcnt lgkmcnt(14)
	v_mfma_f32_32x32x16_f16 v[114:129], v[232:235], v[188:191], v[114:129]
	s_waitcnt lgkmcnt(13)
	v_mfma_f32_32x32x16_f16 v[98:113], v[236:239], v[188:191], v[98:113]
	s_waitcnt lgkmcnt(12)
	v_mfma_f32_32x32x16_f16 v[82:97], v[232:235], v[200:203], v[82:97]
	v_mfma_f32_32x32x16_f16 v[66:81], v[236:239], v[200:203], v[66:81]
	s_waitcnt lgkmcnt(11)
	v_mfma_f32_32x32x16_f16 v[50:65], v[232:235], v[204:207], v[50:65]
	v_mfma_f32_32x32x16_f16 v[34:49], v[236:239], v[204:207], v[34:49]
	s_waitcnt lgkmcnt(10)
	v_mfma_f32_32x32x16_f16 v[18:33], v[232:235], v[208:211], v[18:33]
	v_mfma_f32_32x32x16_f16 v[2:17], v[236:239], v[208:211], v[2:17]
	s_waitcnt lgkmcnt(0)
	s_barrier
	ds_read_b128 v[232:235], v213
	ds_read_b128 v[188:191], v199
	ds_read_b128 v[236:239], v213 offset:4608
	ds_read_b128 v[200:203], v199 offset:4608
	ds_read_b128 v[204:207], v199 offset:9216
	ds_read_b128 v[208:211], v199 offset:13824
	v_mfma_f32_32x32x16_f16 v[114:129], v[240:243], v[216:219], v[114:129]
	v_mfma_f32_32x32x16_f16 v[98:113], v[244:247], v[216:219], v[98:113]
	v_mfma_f32_32x32x16_f16 v[82:97], v[240:243], v[220:223], v[82:97]
	v_mfma_f32_32x32x16_f16 v[66:81], v[244:247], v[220:223], v[66:81]
	v_mfma_f32_32x32x16_f16 v[50:65], v[240:243], v[224:227], v[50:65]
	v_mfma_f32_32x32x16_f16 v[34:49], v[244:247], v[224:227], v[34:49]
	v_mfma_f32_32x32x16_f16 v[18:33], v[240:243], v[228:231], v[18:33]
	v_mfma_f32_32x32x16_f16 v[2:17], v[244:247], v[228:231], v[2:17]
	ds_read_b128 v[240:243], v213 offset:32
	ds_read_b128 v[216:219], v199 offset:32
	ds_read_b128 v[244:247], v213 offset:4640
	ds_read_b128 v[220:223], v199 offset:4640
	ds_read_b128 v[224:227], v199 offset:9248
	ds_read_b128 v[228:231], v199 offset:13856
	s_waitcnt lgkmcnt(10)
	v_mfma_f32_32x32x16_f16 v[114:129], v[232:235], v[188:191], v[114:129]
	s_waitcnt lgkmcnt(9)
	v_mfma_f32_32x32x16_f16 v[98:113], v[236:239], v[188:191], v[98:113]
	s_waitcnt lgkmcnt(8)
	v_mfma_f32_32x32x16_f16 v[82:97], v[232:235], v[200:203], v[82:97]
	v_mfma_f32_32x32x16_f16 v[66:81], v[236:239], v[200:203], v[66:81]
	s_waitcnt lgkmcnt(7)
	v_mfma_f32_32x32x16_f16 v[50:65], v[232:235], v[204:207], v[50:65]
	v_mfma_f32_32x32x16_f16 v[34:49], v[236:239], v[204:207], v[34:49]
	s_waitcnt lgkmcnt(6)
; DI int otid512() { int t = threadIdx.x; asm volatile("" : "+v"(t)); return t; }
; template <class Epi>
; DI void gemm256_epilogue(f16v (&acc)[4][2], int m0, int n0, Epi epi) {
;   const int tid = otid512(), lane = tid & 63, wv = tid >> 6, wm = wv >> 2, wn = wv & 3, h = lane >> 5;
; #pragma unroll
;   for (int i = 0; i < 4; ++i) {
;     const int m = m0 + wm * 128 + i * 32 + (lane & 31);
; #pragma unroll
;     for (int g = 0; g < 4; ++g) {
;       const int n = n0 + wn * 64 + 8 * g + 4 * h;
;       f4v v0 = {acc[i][0][4 * g], acc[i][0][4 * g + 1], acc[i][0][4 * g + 2], acc[i][0][4 * g + 3]};
;       f4v v1 = {acc[i][1][4 * g], acc[i][1][4 * g + 1], acc[i][1][4 * g + 2], acc[i][1][4 * g + 3]};
;       epi(m, n, v0, v1);
;     }
;   }
; }
; DI void phase_ffn2_moe(const Params& p, int bid, int nb, h16* lds) {
;     ...
;     gemm256_epilogue(acc, m0, n0, [&](int m, int n, f4v v0, f4v v1) {
;       const float g = sg[m];
;       st_h4(&YB[(size_t)m * DM + n], g * v0); st_h4(&YB[(size_t)m * DM + n + 32], g * v1);
;     });
	v_mfma_f32_32x32x16_f16 v[18:33], v[232:235], v[208:211], v[18:33]
	v_mfma_f32_32x32x16_f16 v[2:17], v[236:239], v[208:211], v[2:17]
	ds_read_b128 v[232:235], v213 offset:64
	ds_read_b128 v[188:191], v199 offset:64
	ds_read_b128 v[236:239], v213 offset:4672
	ds_read_b128 v[200:203], v199 offset:4672
	ds_read_b128 v[204:207], v199 offset:9280
	ds_read_b128 v[208:211], v199 offset:13888
	s_waitcnt lgkmcnt(10)
	v_mfma_f32_32x32x16_f16 v[114:129], v[240:243], v[216:219], v[114:129]
	s_waitcnt lgkmcnt(9)
	v_mfma_f32_32x32x16_f16 v[98:113], v[244:247], v[216:219], v[98:113]
	s_waitcnt lgkmcnt(8)
	v_mfma_f32_32x32x16_f16 v[82:97], v[240:243], v[220:223], v[82:97]
	v_mfma_f32_32x32x16_f16 v[66:81], v[244:247], v[220:223], v[66:81]
	s_waitcnt lgkmcnt(7)
	v_mfma_f32_32x32x16_f16 v[50:65], v[240:243], v[224:227], v[50:65]
	v_mfma_f32_32x32x16_f16 v[34:49], v[244:247], v[224:227], v[34:49]
	s_waitcnt lgkmcnt(6)
	v_mfma_f32_32x32x16_f16 v[18:33], v[240:243], v[228:231], v[18:33]
	v_mfma_f32_32x32x16_f16 v[2:17], v[244:247], v[228:231], v[2:17]
	ds_read_b128 v[240:243], v213 offset:96
	ds_read_b128 v[216:219], v199 offset:96
	ds_read_b128 v[244:247], v213 offset:4704
	ds_read_b128 v[220:223], v199 offset:4704
	ds_read_b128 v[224:227], v199 offset:9312
	ds_read_b128 v[228:231], v199 offset:13920
	s_waitcnt lgkmcnt(10)
	v_mfma_f32_32x32x16_f16 v[114:129], v[232:235], v[188:191], v[114:129]
	s_waitcnt lgkmcnt(9)
	v_mfma_f32_32x32x16_f16 v[98:113], v[236:239], v[188:191], v[98:113]
	s_waitcnt lgkmcnt(8)
	v_mfma_f32_32x32x16_f16 v[82:97], v[232:235], v[200:203], v[82:97]
	v_mfma_f32_32x32x16_f16 v[66:81], v[236:239], v[200:203], v[66:81]
	s_waitcnt lgkmcnt(7)
	v_mfma_f32_32x32x16_f16 v[50:65], v[232:235], v[204:207], v[50:65]
	v_mfma_f32_32x32x16_f16 v[34:49], v[236:239], v[204:207], v[34:49]
	s_waitcnt lgkmcnt(6)
	v_mfma_f32_32x32x16_f16 v[18:33], v[232:235], v[208:211], v[18:33]
	v_mfma_f32_32x32x16_f16 v[2:17], v[236:239], v[208:211], v[2:17]
	s_waitcnt lgkmcnt(0)
	v_mfma_f32_32x32x16_f16 v[114:129], v[240:243], v[216:219], v[114:129]
	v_mfma_f32_32x32x16_f16 v[98:113], v[244:247], v[216:219], v[98:113]
	v_mfma_f32_32x32x16_f16 v[82:97], v[240:243], v[220:223], v[82:97]
	v_mfma_f32_32x32x16_f16 v[66:81], v[244:247], v[220:223], v[66:81]
	v_mfma_f32_32x32x16_f16 v[50:65], v[240:243], v[224:227], v[50:65]
	v_mfma_f32_32x32x16_f16 v[34:49], v[244:247], v[224:227], v[34:49]
	v_mfma_f32_32x32x16_f16 v[18:33], v[240:243], v[228:231], v[18:33]
	v_mfma_f32_32x32x16_f16 v[2:17], v[244:247], v[228:231], v[2:17]
	s_nop 15
	v_mov_b32_e32 v188, 0x358637bd
	v_mov_b32_e32 v189, 0x3727c5ac
	v_mov_b32_e32 v190, 0x2100
	v_mov_b32_e32 v191, 0x1400
	v_mov_b32_e32 v192, 0x7f800000
	v_mov_b32_e32 v193, 0x7fc00000
	v_mov_b32_e32 v194, 0xff800000
	v_mov_b32_e32 v199, 0xf149f2ca
	v_mov_b32_e32 v204, 0x7fffec00
	v_mov_b32_e32 v205, 0xff7fc99e
	v_mov_b32_e32 v206, 0x840000
	v_mov_b32_e32 v207, 0xb00000
	v_mov_b32_e32 v208, 0xdc0000
	v_mov_b32_e32 v209, 0x1080000
	v_mov_b32_e32 v210, 0x1340000
	v_mov_b32_e32 v211, 0x420000
	v_mov_b32_e32 v212, 0x580000
	v_mov_b32_e32 v213, 0x6e0000
	v_mov_b32_e32 v214, 0x9a0000
	s_setprio 0
	v_mov_b32_e32 v162, v180
	s_nop 0
	v_ashrrev_i32_e32 v163, 1, v162
	v_and_b32_e32 v163, 0xffffff80, v163
	v_and_or_b32 v164, v162, 31, s6
	v_add_u32_e32 v164, v164, v163
	v_readlane_b32 s6, v255, 4
	v_ashrrev_i32_e32 v165, 31, v164
	v_readlane_b32 s7, v255, 5
	v_and_b32_e32 v163, 0xc0, v162
	v_lshl_add_u64 v[174:175], v[164:165], 2, s[6:7]
	v_lshrrev_b32_e32 v162, 3, v162
	v_and_b32_e32 v162, 4, v162
	v_or3_b32 v215, v163, v162, s5
	v_lshlrev_b64 v[162:163], 11, v[164:165]
	global_load_dword v228, v[174:175], off
	v_lshl_add_u64 v[230:231], s[28:29], 0, v[162:163]
	v_lshlrev_b32_e32 v162, 1, v215
	v_mov_b32_e32 v163, v0
	v_lshl_add_u64 v[230:231], v[230:231], 0, v[162:163]
	s_waitcnt vmcnt(0)
	s_nop 9
	v_mul_f32_e64 v116, v116, v228
	v_mul_f32_e64 v117, v117, v228
	v_mul_f32_e64 v114, v114, v228
	v_mul_f32_e64 v115, v115, v228
	v_pk_mul_f32 v[100:101], v[100:101], v[228:229] op_sel_hi:[1,0]
	v_pk_mul_f32 v[98:99], v[98:99], v[228:229] op_sel_hi:[1,0]
	v_cvt_pk_f16_f32 v117, v116, v117
	v_cvt_pk_f16_f32 v116, v114, v115
	v_cvt_pk_f16_f32 v101, v100, v101
	v_cvt_pk_f16_f32 v100, v98, v99
	global_store_dwordx2 v[230:231], v[116:117], off
	global_store_dwordx2 v[230:231], v[100:101], off offset:64
	global_load_dword v98, v[174:175], off
	s_waitcnt vmcnt(0)
	v_mul_f32_e64 v100, v120, v98
	v_mul_f32_e64 v101, v121, v98
	v_mul_f32_e64 v114, v118, v98
	v_mul_f32_e64 v115, v119, v98
	v_cvt_pk_f16_f32 v101, v100, v101
	v_cvt_pk_f16_f32 v100, v114, v115
	global_store_dwordx2 v[230:231], v[100:101], off offset:16
	v_pk_mul_f32 v[100:101], v[104:105], v[98:99] op_sel_hi:[1,0]
	v_pk_mul_f32 v[98:99], v[102:103], v[98:99] op_sel_hi:[1,0]
	v_cvt_pk_f16_f32 v101, v100, v101
	v_cvt_pk_f16_f32 v100, v98, v99
	global_store_dwordx2 v[230:231], v[100:101], off offset:80
	global_load_dword v98, v[174:175], off
	s_waitcnt vmcnt(0)
	v_mul_f32_e64 v100, v124, v98
	v_mul_f32_e64 v101, v125, v98
	v_mul_f32_e64 v102, v122, v98
	v_mul_f32_e64 v103, v123, v98
	v_cvt_pk_f16_f32 v101, v100, v101
	v_cvt_pk_f16_f32 v100, v102, v103
	global_store_dwordx2 v[230:231], v[100:101], off offset:32
	v_pk_mul_f32 v[100:101], v[108:109], v[98:99] op_sel_hi:[1,0]
	v_pk_mul_f32 v[98:99], v[106:107], v[98:99] op_sel_hi:[1,0]
	v_cvt_pk_f16_f32 v101, v100, v101
	v_cvt_pk_f16_f32 v100, v98, v99
	global_store_dwordx2 v[230:231], v[100:101], off offset:96
	global_load_dword v98, v[174:175], off
	s_waitcnt vmcnt(0)
; DI int otid512() { int t = threadIdx.x; asm volatile("" : "+v"(t)); return t; }
; template <class Epi>
; DI void gemm256_epilogue(f16v (&acc)[4][2], int m0, int n0, Epi epi) {
;   const int tid = otid512(), lane = tid & 63, wv = tid >> 6, wm = wv >> 2, wn = wv & 3, h = lane >> 5;
; #pragma unroll
;   for (int i = 0; i < 4; ++i) {
;     const int m = m0 + wm * 128 + i * 32 + (lane & 31);
; #pragma unroll
;     for (int g = 0; g < 4; ++g) {
;       const int n = n0 + wn * 64 + 8 * g + 4 * h;
;       f4v v0 = {acc[i][0][4 * g], acc[i][0][4 * g + 1], acc[i][0][4 * g + 2], acc[i][0][4 * g + 3]};
;       f4v v1 = {acc[i][1][4 * g], acc[i][1][4 * g + 1], acc[i][1][4 * g + 2], acc[i][1][4 * g + 3]};
;       epi(m, n, v0, v1);
;     }
;   }
; }
; DI void phase_ffn2_moe(const Params& p, int bid, int nb, h16* lds) {
;     ...
;     gemm256_epilogue(acc, m0, n0, [&](int m, int n, f4v v0, f4v v1) {
;       const float g = sg[m];
;       st_h4(&YB[(size_t)m * DM + n], g * v0); st_h4(&YB[(size_t)m * DM + n + 32], g * v1);
;     });
	v_mul_f32_e64 v100, v128, v98
	v_mul_f32_e64 v101, v129, v98
	v_mul_f32_e64 v102, v126, v98
	v_mul_f32_e64 v103, v127, v98
	v_cvt_pk_f16_f32 v101, v100, v101
	v_cvt_pk_f16_f32 v100, v102, v103
	global_store_dwordx2 v[230:231], v[100:101], off offset:48
	v_pk_mul_f32 v[100:101], v[112:113], v[98:99] op_sel_hi:[1,0]
	v_pk_mul_f32 v[98:99], v[110:111], v[98:99] op_sel_hi:[1,0]
	v_cvt_pk_f16_f32 v101, v100, v101
	v_cvt_pk_f16_f32 v100, v98, v99
	v_or_b32_e32 v98, 32, v164
	v_ashrrev_i32_e32 v99, 31, v98
	global_store_dwordx2 v[230:231], v[100:101], off offset:112
	v_lshl_add_u64 v[100:101], v[98:99], 2, s[6:7]
	global_load_dword v102, v[100:101], off
	v_lshlrev_b64 v[98:99], 11, v[98:99]
	v_lshl_add_u64 v[98:99], s[28:29], 0, v[98:99]
	v_lshl_add_u64 v[98:99], v[98:99], 0, v[162:163]
	s_waitcnt vmcnt(0)
	s_nop 9
	v_mul_f32_e64 v84, v84, v102
	v_mul_f32_e64 v85, v85, v102
	v_mul_f32_e64 v82, v82, v102
	v_mul_f32_e64 v83, v83, v102
	v_pk_mul_f32 v[68:69], v[68:69], v[102:103] op_sel_hi:[1,0]
	v_pk_mul_f32 v[66:67], v[66:67], v[102:103] op_sel_hi:[1,0]
	v_cvt_pk_f16_f32 v85, v84, v85
	v_cvt_pk_f16_f32 v84, v82, v83
	v_cvt_pk_f16_f32 v69, v68, v69
	v_cvt_pk_f16_f32 v68, v66, v67
	global_store_dwordx2 v[98:99], v[84:85], off
	global_store_dwordx2 v[98:99], v[68:69], off offset:64
	global_load_dword v66, v[100:101], off
	s_waitcnt vmcnt(0)
	v_mul_f32_e64 v68, v88, v66
	v_mul_f32_e64 v69, v89, v66
	v_mul_f32_e64 v82, v86, v66
	v_mul_f32_e64 v83, v87, v66
	v_pk_mul_f32 v[72:73], v[72:73], v[66:67] op_sel_hi:[1,0]
	v_pk_mul_f32 v[66:67], v[70:71], v[66:67] op_sel_hi:[1,0]
	v_cvt_pk_f16_f32 v69, v68, v69
	v_cvt_pk_f16_f32 v68, v82, v83
	v_cvt_pk_f16_f32 v71, v72, v73
	v_cvt_pk_f16_f32 v70, v66, v67
	global_store_dwordx2 v[98:99], v[68:69], off offset:16
	global_store_dwordx2 v[98:99], v[70:71], off offset:80
	global_load_dword v66, v[100:101], off
	s_waitcnt vmcnt(0)
	v_mul_f32_e64 v68, v92, v66
	v_mul_f32_e64 v69, v93, v66
	v_mul_f32_e64 v70, v90, v66
	v_mul_f32_e64 v71, v91, v66
	v_pk_mul_f32 v[72:73], v[76:77], v[66:67] op_sel_hi:[1,0]
	v_pk_mul_f32 v[66:67], v[74:75], v[66:67] op_sel_hi:[1,0]
	v_cvt_pk_f16_f32 v69, v68, v69
	v_cvt_pk_f16_f32 v68, v70, v71
	v_cvt_pk_f16_f32 v71, v72, v73
	v_cvt_pk_f16_f32 v70, v66, v67
	global_store_dwordx2 v[98:99], v[68:69], off offset:32
	global_store_dwordx2 v[98:99], v[70:71], off offset:96
	global_load_dword v66, v[100:101], off
	v_or_b32_e32 v68, 64, v164
	v_ashrrev_i32_e32 v69, 31, v68
	v_lshl_add_u64 v[70:71], v[68:69], 2, s[6:7]
	v_lshlrev_b64 v[68:69], 11, v[68:69]
	v_lshl_add_u64 v[68:69], s[28:29], 0, v[68:69]
	v_lshl_add_u64 v[68:69], v[68:69], 0, v[162:163]
	s_waitcnt vmcnt(0)
	v_mul_f32_e64 v72, v96, v66
	v_mul_f32_e64 v73, v97, v66
	v_pk_mul_f32 v[74:75], v[94:95], v[66:67] op_sel_hi:[1,0]
	v_pk_mul_f32 v[76:77], v[80:81], v[66:67] op_sel_hi:[1,0]
	v_pk_mul_f32 v[66:67], v[78:79], v[66:67] op_sel_hi:[1,0]
	v_cvt_pk_f16_f32 v73, v72, v73
	v_cvt_pk_f16_f32 v72, v74, v75
	v_cvt_pk_f16_f32 v75, v76, v77
	v_cvt_pk_f16_f32 v74, v66, v67
	global_store_dwordx2 v[98:99], v[72:73], off offset:48
	global_store_dwordx2 v[98:99], v[74:75], off offset:112
	global_load_dword v66, v[70:71], off
	s_waitcnt vmcnt(0)
	s_nop 9
	v_mul_f32_e64 v52, v52, v66
	v_mul_f32_e64 v53, v53, v66
	v_mul_f32_e64 v50, v50, v66
	v_mul_f32_e64 v51, v51, v66
	v_pk_mul_f32 v[36:37], v[36:37], v[66:67] op_sel_hi:[1,0]
	v_pk_mul_f32 v[34:35], v[34:35], v[66:67] op_sel_hi:[1,0]
	v_cvt_pk_f16_f32 v53, v52, v53
	v_cvt_pk_f16_f32 v52, v50, v51
	v_cvt_pk_f16_f32 v37, v36, v37
	v_cvt_pk_f16_f32 v36, v34, v35
	global_store_dwordx2 v[68:69], v[52:53], off
	global_store_dwordx2 v[68:69], v[36:37], off offset:64
	global_load_dword v34, v[70:71], off
	s_waitcnt vmcnt(0)
; DI void phase_ffn2_moe(const Params& p, int bid, int nb, h16* lds) {
;     ...
;   for (int u = bid; u < ntl; u += nb) {
;     ...
;     gemm256_epilogue(acc, m0, n0, [&](int m, int n, f4v v0, f4v v1) {
;       const float g = sg[m];
;       st_h4(&YB[(size_t)m * DM + n], g * v0); st_h4(&YB[(size_t)m * DM + n + 32], g * v1);
;     });
	v_mul_f32_e64 v36, v56, v34
	v_mul_f32_e64 v37, v57, v34
	v_mul_f32_e64 v50, v54, v34
	v_mul_f32_e64 v51, v55, v34
	v_pk_mul_f32 v[40:41], v[40:41], v[34:35] op_sel_hi:[1,0]
	v_pk_mul_f32 v[34:35], v[38:39], v[34:35] op_sel_hi:[1,0]
	v_cvt_pk_f16_f32 v37, v36, v37
	v_cvt_pk_f16_f32 v36, v50, v51
	v_cvt_pk_f16_f32 v39, v40, v41
	v_cvt_pk_f16_f32 v38, v34, v35
	global_store_dwordx2 v[68:69], v[36:37], off offset:16
	global_store_dwordx2 v[68:69], v[38:39], off offset:80
	global_load_dword v34, v[70:71], off
	s_waitcnt vmcnt(0)
	v_mul_f32_e64 v36, v60, v34
	v_mul_f32_e64 v37, v61, v34
	v_mul_f32_e64 v38, v58, v34
	v_mul_f32_e64 v39, v59, v34
	v_pk_mul_f32 v[40:41], v[44:45], v[34:35] op_sel_hi:[1,0]
	v_pk_mul_f32 v[34:35], v[42:43], v[34:35] op_sel_hi:[1,0]
	v_cvt_pk_f16_f32 v37, v36, v37
	v_cvt_pk_f16_f32 v36, v38, v39
	v_cvt_pk_f16_f32 v39, v40, v41
	v_cvt_pk_f16_f32 v38, v34, v35
	global_store_dwordx2 v[68:69], v[36:37], off offset:32
	global_store_dwordx2 v[68:69], v[38:39], off offset:96
	global_load_dword v34, v[70:71], off
	v_or_b32_e32 v36, 0x60, v164
	v_ashrrev_i32_e32 v37, 31, v36
	v_lshl_add_u64 v[38:39], v[36:37], 2, s[6:7]
	v_lshlrev_b64 v[36:37], 11, v[36:37]
	v_lshl_add_u64 v[36:37], s[28:29], 0, v[36:37]
	v_lshl_add_u64 v[36:37], v[36:37], 0, v[162:163]
	s_waitcnt vmcnt(0)
	v_mul_f32_e64 v40, v64, v34
	v_mul_f32_e64 v41, v65, v34
	v_pk_mul_f32 v[42:43], v[62:63], v[34:35] op_sel_hi:[1,0]
	v_pk_mul_f32 v[44:45], v[48:49], v[34:35] op_sel_hi:[1,0]
	v_pk_mul_f32 v[34:35], v[46:47], v[34:35] op_sel_hi:[1,0]
	v_cvt_pk_f16_f32 v41, v40, v41
	v_cvt_pk_f16_f32 v40, v42, v43
	v_cvt_pk_f16_f32 v43, v44, v45
	v_cvt_pk_f16_f32 v42, v34, v35
	global_store_dwordx2 v[68:69], v[40:41], off offset:48
	global_store_dwordx2 v[68:69], v[42:43], off offset:112
	global_load_dword v34, v[38:39], off
	s_waitcnt vmcnt(0)
	s_nop 9
	v_mul_f32_e64 v20, v20, v34
	v_mul_f32_e64 v21, v21, v34
	v_mul_f32_e64 v18, v18, v34
	v_mul_f32_e64 v19, v19, v34
	v_pk_mul_f32 v[4:5], v[4:5], v[34:35] op_sel_hi:[1,0]
	v_pk_mul_f32 v[2:3], v[2:3], v[34:35] op_sel_hi:[1,0]
	v_cvt_pk_f16_f32 v21, v20, v21
	v_cvt_pk_f16_f32 v20, v18, v19
	v_cvt_pk_f16_f32 v5, v4, v5
	v_cvt_pk_f16_f32 v4, v2, v3
	global_store_dwordx2 v[36:37], v[20:21], off
	global_store_dwordx2 v[36:37], v[4:5], off offset:64
	global_load_dword v2, v[38:39], off
	s_waitcnt vmcnt(0)
	v_pk_mul_f32 v[4:5], v[24:25], v[2:3] op_sel_hi:[1,0]
	v_pk_mul_f32 v[18:19], v[22:23], v[2:3] op_sel_hi:[1,0]
	v_pk_mul_f32 v[8:9], v[8:9], v[2:3] op_sel_hi:[1,0]
	v_pk_mul_f32 v[2:3], v[6:7], v[2:3] op_sel_hi:[1,0]
	v_cvt_pk_f16_f32 v5, v4, v5
	v_cvt_pk_f16_f32 v4, v18, v19
	v_cvt_pk_f16_f32 v7, v8, v9
	v_cvt_pk_f16_f32 v6, v2, v3
	global_store_dwordx2 v[36:37], v[4:5], off offset:16
	global_store_dwordx2 v[36:37], v[6:7], off offset:80
	global_load_dword v2, v[38:39], off
	s_waitcnt vmcnt(0)
	v_pk_mul_f32 v[4:5], v[28:29], v[2:3] op_sel_hi:[1,0]
	v_pk_mul_f32 v[6:7], v[26:27], v[2:3] op_sel_hi:[1,0]
	v_pk_mul_f32 v[8:9], v[12:13], v[2:3] op_sel_hi:[1,0]
	v_pk_mul_f32 v[2:3], v[10:11], v[2:3] op_sel_hi:[1,0]
	v_cvt_pk_f16_f32 v5, v4, v5
	v_cvt_pk_f16_f32 v4, v6, v7
	v_cvt_pk_f16_f32 v7, v8, v9
	v_cvt_pk_f16_f32 v6, v2, v3
	global_store_dwordx2 v[36:37], v[4:5], off offset:32
	global_store_dwordx2 v[36:37], v[6:7], off offset:96
	global_load_dword v2, v[38:39], off
	s_waitcnt vmcnt(0)
	v_pk_mul_f32 v[4:5], v[32:33], v[2:3] op_sel_hi:[1,0]
	v_pk_mul_f32 v[6:7], v[30:31], v[2:3] op_sel_hi:[1,0]
	v_pk_mul_f32 v[8:9], v[16:17], v[2:3] op_sel_hi:[1,0]
	v_pk_mul_f32 v[2:3], v[14:15], v[2:3] op_sel_hi:[1,0]
	v_cvt_pk_f16_f32 v5, v4, v5
	v_cvt_pk_f16_f32 v4, v6, v7
	v_cvt_pk_f16_f32 v7, v8, v9
	v_cvt_pk_f16_f32 v6, v2, v3
	global_store_dwordx2 v[36:37], v[4:5], off offset:48
	global_store_dwordx2 v[36:37], v[6:7], off offset:112
	s_cbranch_vccnz .LBB0_1571

; template <bool GATHER>
; DI void gemm256_main(const h16* __restrict__ A, int lda, const int* __restrict__ idx, int m0,
;                      const h16* __restrict__ B, int ldb, int n0, int K, h16* lds, f16v (&acc)[4][2]) {
;   const int tid = otid512(), lane = tid & 63, wv = tid >> 6, wm = wv >> 2, wn = wv & 3;
;   const int lr = tid >> 1, lc = (tid & 1) * 32;
;   unsigned ao = (unsigned)(GATHER ? idx[m0 + lr] : (m0 + lr)) * (unsigned)lda + lc;
;   unsigned bo = (unsigned)(n0 + lr) * (unsigned)ldb + lc;
;   const h16* ap = A; const h16* bp = B;
;     ...
;   u4v ra[4], rb[4];
;   const int nk = K >> 6;
;   __syncthreads();
; #pragma unroll
;   for (int i = 0; i < 4; ++i) { ra[i] = *(const u4v*)(AP_ + 8 * i); rb[i] = *(const u4v*)(BP_ + 8 * i); }
;   ao += 64; bo += 64;
; #pragma unroll
;   for (int i = 0; i < 4; ++i) { *(u4v*)&lds[lr * LDH + lc + 8 * i] = ra[i]; *(u4v*)&lds[(256 + lr) * LDH + lc + 8 * i] = rb[i]; }
; #pragma unroll
;   for (int i = 0; i < 4; ++i) { ra[i] = *(const u4v*)(AP_ + 8 * i); rb[i] = *(const u4v*)(BP_ + 8 * i); }
;   ao += 64; bo += 64;
;   __syncthreads();
;   for (int kt = 0; kt < nk; ++kt) {
;     const h16* As = lds + (kt & 1) * (512 * LDH);
;     const h16* Bs = As + 256 * LDH;
;     h16* Wn = lds + ((kt & 1) ^ 1) * (512 * LDH);
;     if (kt + 1 < nk) {
; #pragma unroll
;       for (int i = 0; i < 4; ++i) { *(u4v*)&Wn[lr * LDH + lc + 8 * i] = ra[i]; *(u4v*)&Wn[(256 + lr) * LDH + lc + 8 * i] = rb[i]; }
;     }
;     if (kt + 2 < nk) {
; #pragma unroll
;       for (int i = 0; i < 4; ++i) { ra[i] = *(const u4v*)(AP_ + 8 * i); rb[i] = *(const u4v*)(BP_ + 8 * i); }
;       ao += 64; bo += 64;
;     }
; #pragma unroll
;     for (int ks = 0; ks < 4; ++ks) {
;       h8v af[4], bf[2];
; #pragma unroll
;       for (int i = 0; i < 4; ++i) af[i] = *(const h8v*)&As[(wm * 128 + i * 32 + (lane & 31)) * LDH + ks * 16 + 8 * (lane >> 5)];
; #pragma unroll
;       for (int j = 0; j < 2; ++j) bf[j] = *(const h8v*)&Bs[(wn * 64 + j * 32 + (lane & 31)) * LDH + ks * 16 + 8 * (lane >> 5)];
; #pragma unroll
;       for (int i = 0; i < 4; ++i)
; #pragma unroll
; DI void phase_ffn1_dense(const Params& p, int bid, int nb, h16* lds) {
;     ...
;   for (int u = bid; u < 64 * 22; u += nb) {
;     const int m0 = (u / 22) * 256, n0 = (u % 22) * 256;
;     f16v acc[4][2]; acc256_zero(acc);
;     gemm256_main<false>(x16, DM, nullptr, m0, w13, 1024, n0, 1024, lds, acc);
.LBB0_1626:
	s_mul_hi_i32 s4, s3, 0x2e8ba2e9
	s_lshr_b32 s5, s4, 31
	s_ashr_i32 s4, s4, 2
	s_add_i32 s5, s4, s5
	v_mov_b32_e32 v1, v180
	s_lshl_b32 s4, s5, 8
	s_mulk_i32 s5, 0x1600
	v_ashrrev_i32_e32 v34, 1, v1
	v_lshlrev_b32_e32 v2, 5, v1
	v_subrev_u32_e32 v3, s5, v34
	v_and_b32_e32 v35, 32, v2
	v_add_u32_e32 v2, s4, v34
	v_add_u32_e32 v3, s2, v3
	v_lshl_or_b32 v2, v2, 10, v35
	v_lshl_or_b32 v176, v3, 10, v35
	v_mov_b32_e32 v3, v0
	v_mov_b32_e32 v177, v0
	v_lshl_add_u64 v[174:175], v[2:3], 1, s[20:21]
	v_lshl_add_u64 v[30:31], v[176:177], 1, s[8:9]
	s_barrier
	s_add_i32 s3, s3, s22
	v_mov_b32_e32 v130, v174
	v_mov_b32_e32 v131, v175
	v_mov_b32_e32 v248, v30
	v_mov_b32_e32 v249, v31
	s_cselect_b32 s98, 1, 0
	v_readfirstlane_b32 s99, v180
	s_nop 1
	s_cmp_lt_u32 s99, 0x100
	s_cbranch_scc1 .Lprio_skip_6
	s_setprio 1
.Lprio_skip_6:
	s_cmp_eq_u32 s98, 1
	v_lshrrev_b32_e32 v192, 1, v180
	v_and_b32_e32 v193, 1, v180
	v_mul_u32_u24_e32 v192, 0x90, v192
	v_lshl_add_u32 v178, v193, 6, v192
	v_add_u32_e32 v178, 16, v178
	v_add_u32_e32 v179, 0x12000, v178
	v_lshrrev_b32_e32 v192, 8, v180
	v_and_b32_e32 v194, 31, v180
	v_lshl_or_b32 v192, v192, 7, v194
	v_mul_u32_u24_e32 v192, 0x90, v192
	v_bfe_u32 v193, v180, 5, 1
	v_lshl_add_u32 v192, v193, 4, v192
	v_add_u32_e32 v215, 16, v192
	v_add_u32_e32 v212, 0x12000, v215
	v_bfe_u32 v192, v180, 6, 2
	v_lshl_or_b32 v192, v192, 6, v194
	v_mul_u32_u24_e32 v192, 0x90, v192
	v_lshl_add_u32 v192, v193, 4, v192
	v_add_u32_e32 v213, 0x9010, v192
	v_add_u32_e32 v214, 0x12000, v213
	global_load_dwordx4 v[134:137], v[130:131], off offset:0
	global_load_dwordx4 v[138:141], v[130:131], off offset:16
	global_load_dwordx4 v[142:145], v[130:131], off offset:32
	global_load_dwordx4 v[146:149], v[130:131], off offset:48
	global_load_dwordx4 v[150:153], v[248:249], off offset:0
	global_load_dwordx4 v[154:157], v[248:249], off offset:16
	global_load_dwordx4 v[158:161], v[248:249], off offset:32
	global_load_dwordx4 v[162:165], v[248:249], off offset:48
	s_waitcnt vmcnt(0)
	ds_write_b128 v178, v[134:137]
	ds_write_b128 v178, v[138:141] offset:16
	ds_write_b128 v178, v[142:145] offset:32
	ds_write_b128 v178, v[146:149] offset:48
	ds_write_b128 v178, v[150:153] offset:36864
	ds_write_b128 v178, v[154:157] offset:36880
	ds_write_b128 v178, v[158:161] offset:36896
	ds_write_b128 v178, v[162:165] offset:36912
	global_load_dwordx4 v[134:137], v[130:131], off offset:128
	global_load_dwordx4 v[138:141], v[130:131], off offset:144
	global_load_dwordx4 v[142:145], v[130:131], off offset:160
	global_load_dwordx4 v[146:149], v[130:131], off offset:176
	global_load_dwordx4 v[150:153], v[248:249], off offset:128
	global_load_dwordx4 v[154:157], v[248:249], off offset:144
	global_load_dwordx4 v[158:161], v[248:249], off offset:160
	global_load_dwordx4 v[162:165], v[248:249], off offset:176
	s_waitcnt lgkmcnt(0)
	s_barrier
	ds_read_b128 v[232:235], v213
	ds_read_b128 v[216:219], v215
	ds_read_b128 v[236:239], v213 offset:4608
	ds_read_b128 v[220:223], v215 offset:4608
	ds_read_b128 v[224:227], v215 offset:9216
	ds_read_b128 v[228:231], v215 offset:13824
	ds_read_b128 v[208:211], v213 offset:32
	ds_read_b128 v[240:243], v215 offset:32
	ds_read_b128 v[174:177], v213 offset:4640
	ds_read_b128 v[244:247], v215 offset:4640
	ds_read_b128 v[200:203], v215 offset:9248
	ds_read_b128 v[204:207], v215 offset:13856
	s_waitcnt vmcnt(4)
	ds_write_b128 v179, v[134:137]
	ds_write_b128 v179, v[138:141] offset:16
	ds_write_b128 v179, v[142:145] offset:32
	ds_write_b128 v179, v[146:149] offset:48
	global_load_dwordx4 v[134:137], v[130:131], off offset:256
	global_load_dwordx4 v[138:141], v[130:131], off offset:272
	global_load_dwordx4 v[142:145], v[130:131], off offset:288
	global_load_dwordx4 v[146:149], v[130:131], off offset:304
	s_waitcnt lgkmcnt(14)
	v_mfma_f32_32x32x16_f16 v[98:113], v[232:235], v[216:219], 0
	s_waitcnt lgkmcnt(13)
	v_mfma_f32_32x32x16_f16 v[114:129], v[236:239], v[216:219], 0
	s_waitcnt lgkmcnt(12)
	v_mfma_f32_32x32x16_f16 v[66:81], v[232:235], v[220:223], 0
	v_mfma_f32_32x32x16_f16 v[82:97], v[236:239], v[220:223], 0
	s_waitcnt lgkmcnt(11)
	v_mfma_f32_32x32x16_f16 v[34:49], v[232:235], v[224:227], 0
	v_mfma_f32_32x32x16_f16 v[50:65], v[236:239], v[224:227], 0
	s_waitcnt lgkmcnt(10)
	v_mfma_f32_32x32x16_f16 v[2:17], v[232:235], v[228:231], 0
	v_mfma_f32_32x32x16_f16 v[18:33], v[236:239], v[228:231], 0
	ds_read_b128 v[232:235], v213 offset:64
	ds_read_b128 v[216:219], v215 offset:64
	ds_read_b128 v[236:239], v213 offset:4672
	ds_read_b128 v[220:223], v215 offset:4672
	ds_read_b128 v[224:227], v215 offset:9280
	ds_read_b128 v[228:231], v215 offset:13888
	s_waitcnt vmcnt(4)
	ds_write_b128 v179, v[150:153] offset:36864
	ds_write_b128 v179, v[154:157] offset:36880
	ds_write_b128 v179, v[158:161] offset:36896
	ds_write_b128 v179, v[162:165] offset:36912
	global_load_dwordx4 v[150:153], v[248:249], off offset:256
	global_load_dwordx4 v[154:157], v[248:249], off offset:272
	global_load_dwordx4 v[158:161], v[248:249], off offset:288
	global_load_dwordx4 v[162:165], v[248:249], off offset:304
	s_waitcnt lgkmcnt(15)
	v_mfma_f32_32x32x16_f16 v[98:113], v[208:211], v[240:243], v[98:113]
	s_waitcnt lgkmcnt(15)
	v_mfma_f32_32x32x16_f16 v[114:129], v[174:177], v[240:243], v[114:129]
	s_waitcnt lgkmcnt(15)
	v_mfma_f32_32x32x16_f16 v[66:81], v[208:211], v[244:247], v[66:81]
	v_mfma_f32_32x32x16_f16 v[82:97], v[174:177], v[244:247], v[82:97]
	s_waitcnt lgkmcnt(15)
	v_mfma_f32_32x32x16_f16 v[34:49], v[208:211], v[200:203], v[34:49]
	v_mfma_f32_32x32x16_f16 v[50:65], v[174:177], v[200:203], v[50:65]
	s_waitcnt lgkmcnt(14)
	v_mfma_f32_32x32x16_f16 v[2:17], v[208:211], v[204:207], v[2:17]
	v_mfma_f32_32x32x16_f16 v[18:33], v[174:177], v[204:207], v[18:33]
	ds_read_b128 v[208:211], v213 offset:96
	ds_read_b128 v[240:243], v215 offset:96
	ds_read_b128 v[174:177], v213 offset:4704
	ds_read_b128 v[244:247], v215 offset:4704
	ds_read_b128 v[200:203], v215 offset:9312
	ds_read_b128 v[204:207], v215 offset:13920
	s_waitcnt lgkmcnt(14)
	v_mfma_f32_32x32x16_f16 v[98:113], v[232:235], v[216:219], v[98:113]
	s_waitcnt lgkmcnt(13)
	v_mfma_f32_32x32x16_f16 v[114:129], v[236:239], v[216:219], v[114:129]
	s_waitcnt lgkmcnt(12)
	v_mfma_f32_32x32x16_f16 v[66:81], v[232:235], v[220:223], v[66:81]
	v_mfma_f32_32x32x16_f16 v[82:97], v[236:239], v[220:223], v[82:97]
	s_waitcnt lgkmcnt(11)
	v_mfma_f32_32x32x16_f16 v[34:49], v[232:235], v[224:227], v[34:49]
	v_mfma_f32_32x32x16_f16 v[50:65], v[236:239], v[224:227], v[50:65]
	s_waitcnt lgkmcnt(10)
	v_mfma_f32_32x32x16_f16 v[2:17], v[232:235], v[228:231], v[2:17]
	v_mfma_f32_32x32x16_f16 v[18:33], v[236:239], v[228:231], v[18:33]
	s_waitcnt lgkmcnt(0)
	s_barrier
; DI f16v mfma32(h8v a, h8v b, f16v c) { return __builtin_amdgcn_mfma_f32_32x32x16_f16(a, b, c, 0, 0, 0); }
; template <bool GATHER>
; DI void gemm256_main(const h16* __restrict__ A, int lda, const int* __restrict__ idx, int m0,
;                      const h16* __restrict__ B, int ldb, int n0, int K, h16* lds, f16v (&acc)[4][2]) {
;     ...
;   for (int kt = 0; kt < nk; ++kt) {
;     const h16* As = lds + (kt & 1) * (512 * LDH);
;     const h16* Bs = As + 256 * LDH;
;     h16* Wn = lds + ((kt & 1) ^ 1) * (512 * LDH);
;     if (kt + 1 < nk) {
; #pragma unroll
;       for (int i = 0; i < 4; ++i) { *(u4v*)&Wn[lr * LDH + lc + 8 * i] = ra[i]; *(u4v*)&Wn[(256 + lr) * LDH + lc + 8 * i] = rb[i]; }
;     }
;     if (kt + 2 < nk) {
; #pragma unroll
;       for (int i = 0; i < 4; ++i) { ra[i] = *(const u4v*)(AP_ + 8 * i); rb[i] = *(const u4v*)(BP_ + 8 * i); }
;       ao += 64; bo += 64;
;     }
; #pragma unroll
;     for (int ks = 0; ks < 4; ++ks) {
;       h8v af[4], bf[2];
; #pragma unroll
;       for (int i = 0; i < 4; ++i) af[i] = *(const h8v*)&As[(wm * 128 + i * 32 + (lane & 31)) * LDH + ks * 16 + 8 * (lane >> 5)];
; #pragma unroll
;       for (int j = 0; j < 2; ++j) bf[j] = *(const h8v*)&Bs[(wn * 64 + j * 32 + (lane & 31)) * LDH + ks * 16 + 8 * (lane >> 5)];
; #pragma unroll
;       for (int i = 0; i < 4; ++i)
; #pragma unroll
;         for (int j = 0; j < 2; ++j) acc[i][j] = mfma32(bf[j], af[i], acc[i][j]);
;     }
;     __syncthreads();
	ds_read_b128 v[232:235], v214
	ds_read_b128 v[216:219], v212
	ds_read_b128 v[236:239], v214 offset:4608
	ds_read_b128 v[220:223], v212 offset:4608
	ds_read_b128 v[224:227], v212 offset:9216
	ds_read_b128 v[228:231], v212 offset:13824
	v_mfma_f32_32x32x16_f16 v[98:113], v[208:211], v[240:243], v[98:113]
	v_mfma_f32_32x32x16_f16 v[114:129], v[174:177], v[240:243], v[114:129]
	v_mfma_f32_32x32x16_f16 v[66:81], v[208:211], v[244:247], v[66:81]
	v_mfma_f32_32x32x16_f16 v[82:97], v[174:177], v[244:247], v[82:97]
	v_mfma_f32_32x32x16_f16 v[34:49], v[208:211], v[200:203], v[34:49]
	v_mfma_f32_32x32x16_f16 v[50:65], v[174:177], v[200:203], v[50:65]
	v_mfma_f32_32x32x16_f16 v[2:17], v[208:211], v[204:207], v[2:17]
	v_mfma_f32_32x32x16_f16 v[18:33], v[174:177], v[204:207], v[18:33]
	ds_read_b128 v[208:211], v214 offset:32
	ds_read_b128 v[240:243], v212 offset:32
	ds_read_b128 v[174:177], v214 offset:4640
	ds_read_b128 v[244:247], v212 offset:4640
	ds_read_b128 v[200:203], v212 offset:9248
	ds_read_b128 v[204:207], v212 offset:13856
	s_waitcnt vmcnt(4)
	ds_write_b128 v178, v[134:137]
	ds_write_b128 v178, v[138:141] offset:16
	ds_write_b128 v178, v[142:145] offset:32
	ds_write_b128 v178, v[146:149] offset:48
	global_load_dwordx4 v[134:137], v[130:131], off offset:384
	global_load_dwordx4 v[138:141], v[130:131], off offset:400
	global_load_dwordx4 v[142:145], v[130:131], off offset:416
	global_load_dwordx4 v[146:149], v[130:131], off offset:432
	s_waitcnt lgkmcnt(14)
	v_mfma_f32_32x32x16_f16 v[98:113], v[232:235], v[216:219], v[98:113]
	s_waitcnt lgkmcnt(13)
	v_mfma_f32_32x32x16_f16 v[114:129], v[236:239], v[216:219], v[114:129]
	s_waitcnt lgkmcnt(12)
	v_mfma_f32_32x32x16_f16 v[66:81], v[232:235], v[220:223], v[66:81]
	v_mfma_f32_32x32x16_f16 v[82:97], v[236:239], v[220:223], v[82:97]
	s_waitcnt lgkmcnt(11)
	v_mfma_f32_32x32x16_f16 v[34:49], v[232:235], v[224:227], v[34:49]
	v_mfma_f32_32x32x16_f16 v[50:65], v[236:239], v[224:227], v[50:65]
	s_waitcnt lgkmcnt(10)
	v_mfma_f32_32x32x16_f16 v[2:17], v[232:235], v[228:231], v[2:17]
	v_mfma_f32_32x32x16_f16 v[18:33], v[236:239], v[228:231], v[18:33]
	ds_read_b128 v[232:235], v214 offset:64
	ds_read_b128 v[216:219], v212 offset:64
	ds_read_b128 v[236:239], v214 offset:4672
	ds_read_b128 v[220:223], v212 offset:4672
	ds_read_b128 v[224:227], v212 offset:9280
	ds_read_b128 v[228:231], v212 offset:13888
	s_waitcnt vmcnt(4)
	ds_write_b128 v178, v[150:153] offset:36864
	ds_write_b128 v178, v[154:157] offset:36880
	ds_write_b128 v178, v[158:161] offset:36896
	ds_write_b128 v178, v[162:165] offset:36912
	global_load_dwordx4 v[150:153], v[248:249], off offset:384
	global_load_dwordx4 v[154:157], v[248:249], off offset:400
	global_load_dwordx4 v[158:161], v[248:249], off offset:416
	global_load_dwordx4 v[162:165], v[248:249], off offset:432
	s_waitcnt lgkmcnt(15)
	v_mfma_f32_32x32x16_f16 v[98:113], v[208:211], v[240:243], v[98:113]
	s_waitcnt lgkmcnt(15)
	v_mfma_f32_32x32x16_f16 v[114:129], v[174:177], v[240:243], v[114:129]
	s_waitcnt lgkmcnt(15)
	v_mfma_f32_32x32x16_f16 v[66:81], v[208:211], v[244:247], v[66:81]
	v_mfma_f32_32x32x16_f16 v[82:97], v[174:177], v[244:247], v[82:97]
	s_waitcnt lgkmcnt(15)
	v_mfma_f32_32x32x16_f16 v[34:49], v[208:211], v[200:203], v[34:49]
	v_mfma_f32_32x32x16_f16 v[50:65], v[174:177], v[200:203], v[50:65]
	s_waitcnt lgkmcnt(14)
	v_mfma_f32_32x32x16_f16 v[2:17], v[208:211], v[204:207], v[2:17]
	v_mfma_f32_32x32x16_f16 v[18:33], v[174:177], v[204:207], v[18:33]
	ds_read_b128 v[208:211], v214 offset:96
	ds_read_b128 v[240:243], v212 offset:96
	ds_read_b128 v[174:177], v214 offset:4704
	ds_read_b128 v[244:247], v212 offset:4704
	ds_read_b128 v[200:203], v212 offset:9312
	ds_read_b128 v[204:207], v212 offset:13920
	s_waitcnt lgkmcnt(14)
	v_mfma_f32_32x32x16_f16 v[98:113], v[232:235], v[216:219], v[98:113]
	s_waitcnt lgkmcnt(13)
	v_mfma_f32_32x32x16_f16 v[114:129], v[236:239], v[216:219], v[114:129]
	s_waitcnt lgkmcnt(12)
	v_mfma_f32_32x32x16_f16 v[66:81], v[232:235], v[220:223], v[66:81]
	v_mfma_f32_32x32x16_f16 v[82:97], v[236:239], v[220:223], v[82:97]
	s_waitcnt lgkmcnt(11)
	v_mfma_f32_32x32x16_f16 v[34:49], v[232:235], v[224:227], v[34:49]
	v_mfma_f32_32x32x16_f16 v[50:65], v[236:239], v[224:227], v[50:65]
	s_waitcnt lgkmcnt(10)
	v_mfma_f32_32x32x16_f16 v[2:17], v[232:235], v[228:231], v[2:17]
	v_mfma_f32_32x32x16_f16 v[18:33], v[236:239], v[228:231], v[18:33]
	s_waitcnt lgkmcnt(0)
	s_barrier
; DI f16v mfma32(h8v a, h8v b, f16v c) { return __builtin_amdgcn_mfma_f32_32x32x16_f16(a, b, c, 0, 0, 0); }
; template <bool GATHER>
; DI void gemm256_main(const h16* __restrict__ A, int lda, const int* __restrict__ idx, int m0,
;                      const h16* __restrict__ B, int ldb, int n0, int K, h16* lds, f16v (&acc)[4][2]) {
;     ...
;   for (int kt = 0; kt < nk; ++kt) {
;     const h16* As = lds + (kt & 1) * (512 * LDH);
;     const h16* Bs = As + 256 * LDH;
;     h16* Wn = lds + ((kt & 1) ^ 1) * (512 * LDH);
;     if (kt + 1 < nk) {
; #pragma unroll
;       for (int i = 0; i < 4; ++i) { *(u4v*)&Wn[lr * LDH + lc + 8 * i] = ra[i]; *(u4v*)&Wn[(256 + lr) * LDH + lc + 8 * i] = rb[i]; }
;     }
;     if (kt + 2 < nk) {
; #pragma unroll
;       for (int i = 0; i < 4; ++i) { ra[i] = *(const u4v*)(AP_ + 8 * i); rb[i] = *(const u4v*)(BP_ + 8 * i); }
;       ao += 64; bo += 64;
;     }
; #pragma unroll
;     for (int ks = 0; ks < 4; ++ks) {
;       h8v af[4], bf[2];
; #pragma unroll
;       for (int i = 0; i < 4; ++i) af[i] = *(const h8v*)&As[(wm * 128 + i * 32 + (lane & 31)) * LDH + ks * 16 + 8 * (lane >> 5)];
; #pragma unroll
;       for (int j = 0; j < 2; ++j) bf[j] = *(const h8v*)&Bs[(wn * 64 + j * 32 + (lane & 31)) * LDH + ks * 16 + 8 * (lane >> 5)];
; #pragma unroll
;       for (int i = 0; i < 4; ++i)
; #pragma unroll
;         for (int j = 0; j < 2; ++j) acc[i][j] = mfma32(bf[j], af[i], acc[i][j]);
;     }
;     __syncthreads();
;   }
	ds_read_b128 v[232:235], v213
	ds_read_b128 v[216:219], v215
	ds_read_b128 v[236:239], v213 offset:4608
	ds_read_b128 v[220:223], v215 offset:4608
	ds_read_b128 v[224:227], v215 offset:9216
	ds_read_b128 v[228:231], v215 offset:13824
	v_mfma_f32_32x32x16_f16 v[98:113], v[208:211], v[240:243], v[98:113]
	v_mfma_f32_32x32x16_f16 v[114:129], v[174:177], v[240:243], v[114:129]
	v_mfma_f32_32x32x16_f16 v[66:81], v[208:211], v[244:247], v[66:81]
	v_mfma_f32_32x32x16_f16 v[82:97], v[174:177], v[244:247], v[82:97]
	v_mfma_f32_32x32x16_f16 v[34:49], v[208:211], v[200:203], v[34:49]
	v_mfma_f32_32x32x16_f16 v[50:65], v[174:177], v[200:203], v[50:65]
	v_mfma_f32_32x32x16_f16 v[2:17], v[208:211], v[204:207], v[2:17]
	v_mfma_f32_32x32x16_f16 v[18:33], v[174:177], v[204:207], v[18:33]
	ds_read_b128 v[208:211], v213 offset:32
	ds_read_b128 v[240:243], v215 offset:32
	ds_read_b128 v[174:177], v213 offset:4640
	ds_read_b128 v[244:247], v215 offset:4640
	ds_read_b128 v[200:203], v215 offset:9248
	ds_read_b128 v[204:207], v215 offset:13856
	s_waitcnt vmcnt(4)
	ds_write_b128 v179, v[134:137]
	ds_write_b128 v179, v[138:141] offset:16
	ds_write_b128 v179, v[142:145] offset:32
	ds_write_b128 v179, v[146:149] offset:48
	global_load_dwordx4 v[134:137], v[130:131], off offset:512
	global_load_dwordx4 v[138:141], v[130:131], off offset:528
	global_load_dwordx4 v[142:145], v[130:131], off offset:544
	global_load_dwordx4 v[146:149], v[130:131], off offset:560
	s_waitcnt lgkmcnt(14)
	v_mfma_f32_32x32x16_f16 v[98:113], v[232:235], v[216:219], v[98:113]
	s_waitcnt lgkmcnt(13)
	v_mfma_f32_32x32x16_f16 v[114:129], v[236:239], v[216:219], v[114:129]
	s_waitcnt lgkmcnt(12)
	v_mfma_f32_32x32x16_f16 v[66:81], v[232:235], v[220:223], v[66:81]
	v_mfma_f32_32x32x16_f16 v[82:97], v[236:239], v[220:223], v[82:97]
	s_waitcnt lgkmcnt(11)
	v_mfma_f32_32x32x16_f16 v[34:49], v[232:235], v[224:227], v[34:49]
	v_mfma_f32_32x32x16_f16 v[50:65], v[236:239], v[224:227], v[50:65]
	s_waitcnt lgkmcnt(10)
	v_mfma_f32_32x32x16_f16 v[2:17], v[232:235], v[228:231], v[2:17]
	v_mfma_f32_32x32x16_f16 v[18:33], v[236:239], v[228:231], v[18:33]
	ds_read_b128 v[232:235], v213 offset:64
	ds_read_b128 v[216:219], v215 offset:64
	ds_read_b128 v[236:239], v213 offset:4672
	ds_read_b128 v[220:223], v215 offset:4672
	ds_read_b128 v[224:227], v215 offset:9280
	ds_read_b128 v[228:231], v215 offset:13888
	s_waitcnt vmcnt(4)
	ds_write_b128 v179, v[150:153] offset:36864
	ds_write_b128 v179, v[154:157] offset:36880
	ds_write_b128 v179, v[158:161] offset:36896
	ds_write_b128 v179, v[162:165] offset:36912
	global_load_dwordx4 v[150:153], v[248:249], off offset:512
	global_load_dwordx4 v[154:157], v[248:249], off offset:528
	global_load_dwordx4 v[158:161], v[248:249], off offset:544
	global_load_dwordx4 v[162:165], v[248:249], off offset:560
	s_waitcnt lgkmcnt(15)
	v_mfma_f32_32x32x16_f16 v[98:113], v[208:211], v[240:243], v[98:113]
	s_waitcnt lgkmcnt(15)
	v_mfma_f32_32x32x16_f16 v[114:129], v[174:177], v[240:243], v[114:129]
	s_waitcnt lgkmcnt(15)
	v_mfma_f32_32x32x16_f16 v[66:81], v[208:211], v[244:247], v[66:81]
	v_mfma_f32_32x32x16_f16 v[82:97], v[174:177], v[244:247], v[82:97]
	s_waitcnt lgkmcnt(15)
	v_mfma_f32_32x32x16_f16 v[34:49], v[208:211], v[200:203], v[34:49]
	v_mfma_f32_32x32x16_f16 v[50:65], v[174:177], v[200:203], v[50:65]
	s_waitcnt lgkmcnt(14)
	v_mfma_f32_32x32x16_f16 v[2:17], v[208:211], v[204:207], v[2:17]
	v_mfma_f32_32x32x16_f16 v[18:33], v[174:177], v[204:207], v[18:33]
	ds_read_b128 v[208:211], v213 offset:96
	ds_read_b128 v[240:243], v215 offset:96
	ds_read_b128 v[174:177], v213 offset:4704
	ds_read_b128 v[244:247], v215 offset:4704
	ds_read_b128 v[200:203], v215 offset:9312
	ds_read_b128 v[204:207], v215 offset:13920
	s_waitcnt lgkmcnt(14)
	v_mfma_f32_32x32x16_f16 v[98:113], v[232:235], v[216:219], v[98:113]
	s_waitcnt lgkmcnt(13)
	v_mfma_f32_32x32x16_f16 v[114:129], v[236:239], v[216:219], v[114:129]
	s_waitcnt lgkmcnt(12)
	v_mfma_f32_32x32x16_f16 v[66:81], v[232:235], v[220:223], v[66:81]
	v_mfma_f32_32x32x16_f16 v[82:97], v[236:239], v[220:223], v[82:97]
	s_waitcnt lgkmcnt(11)
	v_mfma_f32_32x32x16_f16 v[34:49], v[232:235], v[224:227], v[34:49]
	v_mfma_f32_32x32x16_f16 v[50:65], v[236:239], v[224:227], v[50:65]
	s_waitcnt lgkmcnt(10)
	v_mfma_f32_32x32x16_f16 v[2:17], v[232:235], v[228:231], v[2:17]
	v_mfma_f32_32x32x16_f16 v[18:33], v[236:239], v[228:231], v[18:33]
	s_waitcnt lgkmcnt(0)
	s_barrier
; DI f16v mfma32(h8v a, h8v b, f16v c) { return __builtin_amdgcn_mfma_f32_32x32x16_f16(a, b, c, 0, 0, 0); }
; template <bool GATHER>
; DI void gemm256_main(const h16* __restrict__ A, int lda, const int* __restrict__ idx, int m0,
;                      const h16* __restrict__ B, int ldb, int n0, int K, h16* lds, f16v (&acc)[4][2]) {
;     ...
;   for (int kt = 0; kt < nk; ++kt) {
;     const h16* As = lds + (kt & 1) * (512 * LDH);
;     const h16* Bs = As + 256 * LDH;
;     h16* Wn = lds + ((kt & 1) ^ 1) * (512 * LDH);
;     if (kt + 1 < nk) {
; #pragma unroll
;       for (int i = 0; i < 4; ++i) { *(u4v*)&Wn[lr * LDH + lc + 8 * i] = ra[i]; *(u4v*)&Wn[(256 + lr) * LDH + lc + 8 * i] = rb[i]; }
;     }
;     if (kt + 2 < nk) {
; #pragma unroll
;       for (int i = 0; i < 4; ++i) { ra[i] = *(const u4v*)(AP_ + 8 * i); rb[i] = *(const u4v*)(BP_ + 8 * i); }
;       ao += 64; bo += 64;
;     }
; #pragma unroll
;     for (int ks = 0; ks < 4; ++ks) {
;       h8v af[4], bf[2];
; #pragma unroll
;       for (int i = 0; i < 4; ++i) af[i] = *(const h8v*)&As[(wm * 128 + i * 32 + (lane & 31)) * LDH + ks * 16 + 8 * (lane >> 5)];
; #pragma unroll
;       for (int j = 0; j < 2; ++j) bf[j] = *(const h8v*)&Bs[(wn * 64 + j * 32 + (lane & 31)) * LDH + ks * 16 + 8 * (lane >> 5)];
; #pragma unroll
;       for (int i = 0; i < 4; ++i)
; #pragma unroll
;         for (int j = 0; j < 2; ++j) acc[i][j] = mfma32(bf[j], af[i], acc[i][j]);
;     }
;     __syncthreads();
;   }
	ds_read_b128 v[232:235], v214
	ds_read_b128 v[216:219], v212
	ds_read_b128 v[236:239], v214 offset:4608
	ds_read_b128 v[220:223], v212 offset:4608
	ds_read_b128 v[224:227], v212 offset:9216
	ds_read_b128 v[228:231], v212 offset:13824
	v_mfma_f32_32x32x16_f16 v[98:113], v[208:211], v[240:243], v[98:113]
	v_mfma_f32_32x32x16_f16 v[114:129], v[174:177], v[240:243], v[114:129]
	v_mfma_f32_32x32x16_f16 v[66:81], v[208:211], v[244:247], v[66:81]
	v_mfma_f32_32x32x16_f16 v[82:97], v[174:177], v[244:247], v[82:97]
	v_mfma_f32_32x32x16_f16 v[34:49], v[208:211], v[200:203], v[34:49]
	v_mfma_f32_32x32x16_f16 v[50:65], v[174:177], v[200:203], v[50:65]
	v_mfma_f32_32x32x16_f16 v[2:17], v[208:211], v[204:207], v[2:17]
	v_mfma_f32_32x32x16_f16 v[18:33], v[174:177], v[204:207], v[18:33]
	ds_read_b128 v[208:211], v214 offset:32
	ds_read_b128 v[240:243], v212 offset:32
	ds_read_b128 v[174:177], v214 offset:4640
	ds_read_b128 v[244:247], v212 offset:4640
	ds_read_b128 v[200:203], v212 offset:9248
	ds_read_b128 v[204:207], v212 offset:13856
	s_waitcnt vmcnt(4)
	ds_write_b128 v178, v[134:137]
	ds_write_b128 v178, v[138:141] offset:16
	ds_write_b128 v178, v[142:145] offset:32
	ds_write_b128 v178, v[146:149] offset:48
	global_load_dwordx4 v[134:137], v[130:131], off offset:640
	global_load_dwordx4 v[138:141], v[130:131], off offset:656
	global_load_dwordx4 v[142:145], v[130:131], off offset:672
	global_load_dwordx4 v[146:149], v[130:131], off offset:688
	s_waitcnt lgkmcnt(14)
	v_mfma_f32_32x32x16_f16 v[98:113], v[232:235], v[216:219], v[98:113]
	s_waitcnt lgkmcnt(13)
	v_mfma_f32_32x32x16_f16 v[114:129], v[236:239], v[216:219], v[114:129]
	s_waitcnt lgkmcnt(12)
	v_mfma_f32_32x32x16_f16 v[66:81], v[232:235], v[220:223], v[66:81]
	v_mfma_f32_32x32x16_f16 v[82:97], v[236:239], v[220:223], v[82:97]
	s_waitcnt lgkmcnt(11)
	v_mfma_f32_32x32x16_f16 v[34:49], v[232:235], v[224:227], v[34:49]
	v_mfma_f32_32x32x16_f16 v[50:65], v[236:239], v[224:227], v[50:65]
	s_waitcnt lgkmcnt(10)
	v_mfma_f32_32x32x16_f16 v[2:17], v[232:235], v[228:231], v[2:17]
	v_mfma_f32_32x32x16_f16 v[18:33], v[236:239], v[228:231], v[18:33]
	ds_read_b128 v[232:235], v214 offset:64
	ds_read_b128 v[216:219], v212 offset:64
	ds_read_b128 v[236:239], v214 offset:4672
	ds_read_b128 v[220:223], v212 offset:4672
	ds_read_b128 v[224:227], v212 offset:9280
	ds_read_b128 v[228:231], v212 offset:13888
	s_waitcnt vmcnt(4)
	ds_write_b128 v178, v[150:153] offset:36864
	ds_write_b128 v178, v[154:157] offset:36880
	ds_write_b128 v178, v[158:161] offset:36896
	ds_write_b128 v178, v[162:165] offset:36912
	global_load_dwordx4 v[150:153], v[248:249], off offset:640
	global_load_dwordx4 v[154:157], v[248:249], off offset:656
	global_load_dwordx4 v[158:161], v[248:249], off offset:672
	global_load_dwordx4 v[162:165], v[248:249], off offset:688
	s_waitcnt lgkmcnt(15)
	v_mfma_f32_32x32x16_f16 v[98:113], v[208:211], v[240:243], v[98:113]
	s_waitcnt lgkmcnt(15)
	v_mfma_f32_32x32x16_f16 v[114:129], v[174:177], v[240:243], v[114:129]
	s_waitcnt lgkmcnt(15)
	v_mfma_f32_32x32x16_f16 v[66:81], v[208:211], v[244:247], v[66:81]
	v_mfma_f32_32x32x16_f16 v[82:97], v[174:177], v[244:247], v[82:97]
	s_waitcnt lgkmcnt(15)
	v_mfma_f32_32x32x16_f16 v[34:49], v[208:211], v[200:203], v[34:49]
	v_mfma_f32_32x32x16_f16 v[50:65], v[174:177], v[200:203], v[50:65]
	s_waitcnt lgkmcnt(14)
	v_mfma_f32_32x32x16_f16 v[2:17], v[208:211], v[204:207], v[2:17]
	v_mfma_f32_32x32x16_f16 v[18:33], v[174:177], v[204:207], v[18:33]
	ds_read_b128 v[208:211], v214 offset:96
	ds_read_b128 v[240:243], v212 offset:96
	ds_read_b128 v[174:177], v214 offset:4704
	ds_read_b128 v[244:247], v212 offset:4704
	ds_read_b128 v[200:203], v212 offset:9312
	ds_read_b128 v[204:207], v212 offset:13920
	s_waitcnt lgkmcnt(14)
	v_mfma_f32_32x32x16_f16 v[98:113], v[232:235], v[216:219], v[98:113]
	s_waitcnt lgkmcnt(13)
	v_mfma_f32_32x32x16_f16 v[114:129], v[236:239], v[216:219], v[114:129]
	s_waitcnt lgkmcnt(12)
	v_mfma_f32_32x32x16_f16 v[66:81], v[232:235], v[220:223], v[66:81]
	v_mfma_f32_32x32x16_f16 v[82:97], v[236:239], v[220:223], v[82:97]
	s_waitcnt lgkmcnt(11)
	v_mfma_f32_32x32x16_f16 v[34:49], v[232:235], v[224:227], v[34:49]
	v_mfma_f32_32x32x16_f16 v[50:65], v[236:239], v[224:227], v[50:65]
	s_waitcnt lgkmcnt(10)
	v_mfma_f32_32x32x16_f16 v[2:17], v[232:235], v[228:231], v[2:17]
	v_mfma_f32_32x32x16_f16 v[18:33], v[236:239], v[228:231], v[18:33]
	s_waitcnt lgkmcnt(0)
	s_barrier
; DI f16v mfma32(h8v a, h8v b, f16v c) { return __builtin_amdgcn_mfma_f32_32x32x16_f16(a, b, c, 0, 0, 0); }
; template <bool GATHER>
; DI void gemm256_main(const h16* __restrict__ A, int lda, const int* __restrict__ idx, int m0,
;                      const h16* __restrict__ B, int ldb, int n0, int K, h16* lds, f16v (&acc)[4][2]) {
;     ...
;   for (int kt = 0; kt < nk; ++kt) {
;     const h16* As = lds + (kt & 1) * (512 * LDH);
;     const h16* Bs = As + 256 * LDH;
;     h16* Wn = lds + ((kt & 1) ^ 1) * (512 * LDH);
;     if (kt + 1 < nk) {
; #pragma unroll
;       for (int i = 0; i < 4; ++i) { *(u4v*)&Wn[lr * LDH + lc + 8 * i] = ra[i]; *(u4v*)&Wn[(256 + lr) * LDH + lc + 8 * i] = rb[i]; }
;     }
;     if (kt + 2 < nk) {
; #pragma unroll
;       for (int i = 0; i < 4; ++i) { ra[i] = *(const u4v*)(AP_ + 8 * i); rb[i] = *(const u4v*)(BP_ + 8 * i); }
;       ao += 64; bo += 64;
;     }
; #pragma unroll
;     for (int ks = 0; ks < 4; ++ks) {
;       h8v af[4], bf[2];
; #pragma unroll
;       for (int i = 0; i < 4; ++i) af[i] = *(const h8v*)&As[(wm * 128 + i * 32 + (lane & 31)) * LDH + ks * 16 + 8 * (lane >> 5)];
; #pragma unroll
;       for (int j = 0; j < 2; ++j) bf[j] = *(const h8v*)&Bs[(wn * 64 + j * 32 + (lane & 31)) * LDH + ks * 16 + 8 * (lane >> 5)];
; #pragma unroll
;       for (int i = 0; i < 4; ++i)
; #pragma unroll
;         for (int j = 0; j < 2; ++j) acc[i][j] = mfma32(bf[j], af[i], acc[i][j]);
;     }
;     __syncthreads();
;   }
	ds_read_b128 v[232:235], v213
	ds_read_b128 v[216:219], v215
	ds_read_b128 v[236:239], v213 offset:4608
	ds_read_b128 v[220:223], v215 offset:4608
	ds_read_b128 v[224:227], v215 offset:9216
	ds_read_b128 v[228:231], v215 offset:13824
	v_mfma_f32_32x32x16_f16 v[98:113], v[208:211], v[240:243], v[98:113]
	v_mfma_f32_32x32x16_f16 v[114:129], v[174:177], v[240:243], v[114:129]
	v_mfma_f32_32x32x16_f16 v[66:81], v[208:211], v[244:247], v[66:81]
	v_mfma_f32_32x32x16_f16 v[82:97], v[174:177], v[244:247], v[82:97]
	v_mfma_f32_32x32x16_f16 v[34:49], v[208:211], v[200:203], v[34:49]
	v_mfma_f32_32x32x16_f16 v[50:65], v[174:177], v[200:203], v[50:65]
	v_mfma_f32_32x32x16_f16 v[2:17], v[208:211], v[204:207], v[2:17]
	v_mfma_f32_32x32x16_f16 v[18:33], v[174:177], v[204:207], v[18:33]
	ds_read_b128 v[208:211], v213 offset:32
	ds_read_b128 v[240:243], v215 offset:32
	ds_read_b128 v[174:177], v213 offset:4640
	ds_read_b128 v[244:247], v215 offset:4640
	ds_read_b128 v[200:203], v215 offset:9248
	ds_read_b128 v[204:207], v215 offset:13856
	s_waitcnt vmcnt(4)
	ds_write_b128 v179, v[134:137]
	ds_write_b128 v179, v[138:141] offset:16
	ds_write_b128 v179, v[142:145] offset:32
	ds_write_b128 v179, v[146:149] offset:48
	global_load_dwordx4 v[134:137], v[130:131], off offset:768
	global_load_dwordx4 v[138:141], v[130:131], off offset:784
	global_load_dwordx4 v[142:145], v[130:131], off offset:800
	global_load_dwordx4 v[146:149], v[130:131], off offset:816
	s_waitcnt lgkmcnt(14)
	v_mfma_f32_32x32x16_f16 v[98:113], v[232:235], v[216:219], v[98:113]
	s_waitcnt lgkmcnt(13)
	v_mfma_f32_32x32x16_f16 v[114:129], v[236:239], v[216:219], v[114:129]
	s_waitcnt lgkmcnt(12)
	v_mfma_f32_32x32x16_f16 v[66:81], v[232:235], v[220:223], v[66:81]
	v_mfma_f32_32x32x16_f16 v[82:97], v[236:239], v[220:223], v[82:97]
	s_waitcnt lgkmcnt(11)
	v_mfma_f32_32x32x16_f16 v[34:49], v[232:235], v[224:227], v[34:49]
	v_mfma_f32_32x32x16_f16 v[50:65], v[236:239], v[224:227], v[50:65]
	s_waitcnt lgkmcnt(10)
	v_mfma_f32_32x32x16_f16 v[2:17], v[232:235], v[228:231], v[2:17]
	v_mfma_f32_32x32x16_f16 v[18:33], v[236:239], v[228:231], v[18:33]
	ds_read_b128 v[232:235], v213 offset:64
	ds_read_b128 v[216:219], v215 offset:64
	ds_read_b128 v[236:239], v213 offset:4672
	ds_read_b128 v[220:223], v215 offset:4672
	ds_read_b128 v[224:227], v215 offset:9280
	ds_read_b128 v[228:231], v215 offset:13888
	s_waitcnt vmcnt(4)
	ds_write_b128 v179, v[150:153] offset:36864
	ds_write_b128 v179, v[154:157] offset:36880
	ds_write_b128 v179, v[158:161] offset:36896
	ds_write_b128 v179, v[162:165] offset:36912
	global_load_dwordx4 v[150:153], v[248:249], off offset:768
	global_load_dwordx4 v[154:157], v[248:249], off offset:784
	global_load_dwordx4 v[158:161], v[248:249], off offset:800
	global_load_dwordx4 v[162:165], v[248:249], off offset:816
	s_waitcnt lgkmcnt(15)
	v_mfma_f32_32x32x16_f16 v[98:113], v[208:211], v[240:243], v[98:113]
	s_waitcnt lgkmcnt(15)
	v_mfma_f32_32x32x16_f16 v[114:129], v[174:177], v[240:243], v[114:129]
	s_waitcnt lgkmcnt(15)
	v_mfma_f32_32x32x16_f16 v[66:81], v[208:211], v[244:247], v[66:81]
	v_mfma_f32_32x32x16_f16 v[82:97], v[174:177], v[244:247], v[82:97]
	s_waitcnt lgkmcnt(15)
	v_mfma_f32_32x32x16_f16 v[34:49], v[208:211], v[200:203], v[34:49]
	v_mfma_f32_32x32x16_f16 v[50:65], v[174:177], v[200:203], v[50:65]
	s_waitcnt lgkmcnt(14)
	v_mfma_f32_32x32x16_f16 v[2:17], v[208:211], v[204:207], v[2:17]
	v_mfma_f32_32x32x16_f16 v[18:33], v[174:177], v[204:207], v[18:33]
	ds_read_b128 v[208:211], v213 offset:96
	ds_read_b128 v[240:243], v215 offset:96
	ds_read_b128 v[174:177], v213 offset:4704
	ds_read_b128 v[244:247], v215 offset:4704
	ds_read_b128 v[200:203], v215 offset:9312
	ds_read_b128 v[204:207], v215 offset:13920
	s_waitcnt lgkmcnt(14)
	v_mfma_f32_32x32x16_f16 v[98:113], v[232:235], v[216:219], v[98:113]
	s_waitcnt lgkmcnt(13)
	v_mfma_f32_32x32x16_f16 v[114:129], v[236:239], v[216:219], v[114:129]
	s_waitcnt lgkmcnt(12)
	v_mfma_f32_32x32x16_f16 v[66:81], v[232:235], v[220:223], v[66:81]
	v_mfma_f32_32x32x16_f16 v[82:97], v[236:239], v[220:223], v[82:97]
	s_waitcnt lgkmcnt(11)
	v_mfma_f32_32x32x16_f16 v[34:49], v[232:235], v[224:227], v[34:49]
	v_mfma_f32_32x32x16_f16 v[50:65], v[236:239], v[224:227], v[50:65]
	s_waitcnt lgkmcnt(10)
	v_mfma_f32_32x32x16_f16 v[2:17], v[232:235], v[228:231], v[2:17]
	v_mfma_f32_32x32x16_f16 v[18:33], v[236:239], v[228:231], v[18:33]
	s_waitcnt lgkmcnt(0)
	s_barrier
; DI f16v mfma32(h8v a, h8v b, f16v c) { return __builtin_amdgcn_mfma_f32_32x32x16_f16(a, b, c, 0, 0, 0); }
; template <bool GATHER>
; DI void gemm256_main(const h16* __restrict__ A, int lda, const int* __restrict__ idx, int m0,
;                      const h16* __restrict__ B, int ldb, int n0, int K, h16* lds, f16v (&acc)[4][2]) {
;     ...
;   for (int kt = 0; kt < nk; ++kt) {
;     const h16* As = lds + (kt & 1) * (512 * LDH);
;     const h16* Bs = As + 256 * LDH;
;     h16* Wn = lds + ((kt & 1) ^ 1) * (512 * LDH);
;     if (kt + 1 < nk) {
; #pragma unroll
;       for (int i = 0; i < 4; ++i) { *(u4v*)&Wn[lr * LDH + lc + 8 * i] = ra[i]; *(u4v*)&Wn[(256 + lr) * LDH + lc + 8 * i] = rb[i]; }
;     }
;     if (kt + 2 < nk) {
; #pragma unroll
;       for (int i = 0; i < 4; ++i) { ra[i] = *(const u4v*)(AP_ + 8 * i); rb[i] = *(const u4v*)(BP_ + 8 * i); }
;       ao += 64; bo += 64;
;     }
; #pragma unroll
;     for (int ks = 0; ks < 4; ++ks) {
;       h8v af[4], bf[2];
; #pragma unroll
;       for (int i = 0; i < 4; ++i) af[i] = *(const h8v*)&As[(wm * 128 + i * 32 + (lane & 31)) * LDH + ks * 16 + 8 * (lane >> 5)];
; #pragma unroll
;       for (int j = 0; j < 2; ++j) bf[j] = *(const h8v*)&Bs[(wn * 64 + j * 32 + (lane & 31)) * LDH + ks * 16 + 8 * (lane >> 5)];
; #pragma unroll
;       for (int i = 0; i < 4; ++i)
; #pragma unroll
;         for (int j = 0; j < 2; ++j) acc[i][j] = mfma32(bf[j], af[i], acc[i][j]);
;     }
;     __syncthreads();
;   }
	ds_read_b128 v[232:235], v214
	ds_read_b128 v[216:219], v212
	ds_read_b128 v[236:239], v214 offset:4608
	ds_read_b128 v[220:223], v212 offset:4608
	ds_read_b128 v[224:227], v212 offset:9216
	ds_read_b128 v[228:231], v212 offset:13824
	v_mfma_f32_32x32x16_f16 v[98:113], v[208:211], v[240:243], v[98:113]
	v_mfma_f32_32x32x16_f16 v[114:129], v[174:177], v[240:243], v[114:129]
	v_mfma_f32_32x32x16_f16 v[66:81], v[208:211], v[244:247], v[66:81]
	v_mfma_f32_32x32x16_f16 v[82:97], v[174:177], v[244:247], v[82:97]
	v_mfma_f32_32x32x16_f16 v[34:49], v[208:211], v[200:203], v[34:49]
	v_mfma_f32_32x32x16_f16 v[50:65], v[174:177], v[200:203], v[50:65]
	v_mfma_f32_32x32x16_f16 v[2:17], v[208:211], v[204:207], v[2:17]
	v_mfma_f32_32x32x16_f16 v[18:33], v[174:177], v[204:207], v[18:33]
	ds_read_b128 v[208:211], v214 offset:32
	ds_read_b128 v[240:243], v212 offset:32
	ds_read_b128 v[174:177], v214 offset:4640
	ds_read_b128 v[244:247], v212 offset:4640
	ds_read_b128 v[200:203], v212 offset:9248
	ds_read_b128 v[204:207], v212 offset:13856
	s_waitcnt vmcnt(4)
	ds_write_b128 v178, v[134:137]
	ds_write_b128 v178, v[138:141] offset:16
	ds_write_b128 v178, v[142:145] offset:32
	ds_write_b128 v178, v[146:149] offset:48
	global_load_dwordx4 v[134:137], v[130:131], off offset:896
	global_load_dwordx4 v[138:141], v[130:131], off offset:912
	global_load_dwordx4 v[142:145], v[130:131], off offset:928
	global_load_dwordx4 v[146:149], v[130:131], off offset:944
	s_waitcnt lgkmcnt(14)
	v_mfma_f32_32x32x16_f16 v[98:113], v[232:235], v[216:219], v[98:113]
	s_waitcnt lgkmcnt(13)
	v_mfma_f32_32x32x16_f16 v[114:129], v[236:239], v[216:219], v[114:129]
	s_waitcnt lgkmcnt(12)
	v_mfma_f32_32x32x16_f16 v[66:81], v[232:235], v[220:223], v[66:81]
	v_mfma_f32_32x32x16_f16 v[82:97], v[236:239], v[220:223], v[82:97]
	s_waitcnt lgkmcnt(11)
	v_mfma_f32_32x32x16_f16 v[34:49], v[232:235], v[224:227], v[34:49]
	v_mfma_f32_32x32x16_f16 v[50:65], v[236:239], v[224:227], v[50:65]
	s_waitcnt lgkmcnt(10)
	v_mfma_f32_32x32x16_f16 v[2:17], v[232:235], v[228:231], v[2:17]
	v_mfma_f32_32x32x16_f16 v[18:33], v[236:239], v[228:231], v[18:33]
	ds_read_b128 v[232:235], v214 offset:64
	ds_read_b128 v[216:219], v212 offset:64
	ds_read_b128 v[236:239], v214 offset:4672
	ds_read_b128 v[220:223], v212 offset:4672
	ds_read_b128 v[224:227], v212 offset:9280
	ds_read_b128 v[228:231], v212 offset:13888
	s_waitcnt vmcnt(4)
	ds_write_b128 v178, v[150:153] offset:36864
	ds_write_b128 v178, v[154:157] offset:36880
	ds_write_b128 v178, v[158:161] offset:36896
	ds_write_b128 v178, v[162:165] offset:36912
	global_load_dwordx4 v[150:153], v[248:249], off offset:896
	global_load_dwordx4 v[154:157], v[248:249], off offset:912
	global_load_dwordx4 v[158:161], v[248:249], off offset:928
	global_load_dwordx4 v[162:165], v[248:249], off offset:944
	s_waitcnt lgkmcnt(15)
	v_mfma_f32_32x32x16_f16 v[98:113], v[208:211], v[240:243], v[98:113]
	s_waitcnt lgkmcnt(15)
	v_mfma_f32_32x32x16_f16 v[114:129], v[174:177], v[240:243], v[114:129]
	s_waitcnt lgkmcnt(15)
	v_mfma_f32_32x32x16_f16 v[66:81], v[208:211], v[244:247], v[66:81]
	v_mfma_f32_32x32x16_f16 v[82:97], v[174:177], v[244:247], v[82:97]
	s_waitcnt lgkmcnt(15)
	v_mfma_f32_32x32x16_f16 v[34:49], v[208:211], v[200:203], v[34:49]
	v_mfma_f32_32x32x16_f16 v[50:65], v[174:177], v[200:203], v[50:65]
	s_waitcnt lgkmcnt(14)
	v_mfma_f32_32x32x16_f16 v[2:17], v[208:211], v[204:207], v[2:17]
	v_mfma_f32_32x32x16_f16 v[18:33], v[174:177], v[204:207], v[18:33]
	ds_read_b128 v[208:211], v214 offset:96
	ds_read_b128 v[240:243], v212 offset:96
	ds_read_b128 v[174:177], v214 offset:4704
	ds_read_b128 v[244:247], v212 offset:4704
	ds_read_b128 v[200:203], v212 offset:9312
	ds_read_b128 v[204:207], v212 offset:13920
	s_waitcnt lgkmcnt(14)
	v_mfma_f32_32x32x16_f16 v[98:113], v[232:235], v[216:219], v[98:113]
	s_waitcnt lgkmcnt(13)
	v_mfma_f32_32x32x16_f16 v[114:129], v[236:239], v[216:219], v[114:129]
	s_waitcnt lgkmcnt(12)
	v_mfma_f32_32x32x16_f16 v[66:81], v[232:235], v[220:223], v[66:81]
	v_mfma_f32_32x32x16_f16 v[82:97], v[236:239], v[220:223], v[82:97]
	s_waitcnt lgkmcnt(11)
	v_mfma_f32_32x32x16_f16 v[34:49], v[232:235], v[224:227], v[34:49]
	v_mfma_f32_32x32x16_f16 v[50:65], v[236:239], v[224:227], v[50:65]
	s_waitcnt lgkmcnt(10)
	v_mfma_f32_32x32x16_f16 v[2:17], v[232:235], v[228:231], v[2:17]
	v_mfma_f32_32x32x16_f16 v[18:33], v[236:239], v[228:231], v[18:33]
	s_waitcnt lgkmcnt(0)
	s_barrier
; DI f16v mfma32(h8v a, h8v b, f16v c) { return __builtin_amdgcn_mfma_f32_32x32x16_f16(a, b, c, 0, 0, 0); }
; template <bool GATHER>
; DI void gemm256_main(const h16* __restrict__ A, int lda, const int* __restrict__ idx, int m0,
;                      const h16* __restrict__ B, int ldb, int n0, int K, h16* lds, f16v (&acc)[4][2]) {
;     ...
;   for (int kt = 0; kt < nk; ++kt) {
;     const h16* As = lds + (kt & 1) * (512 * LDH);
;     const h16* Bs = As + 256 * LDH;
;     h16* Wn = lds + ((kt & 1) ^ 1) * (512 * LDH);
;     if (kt + 1 < nk) {
; #pragma unroll
;       for (int i = 0; i < 4; ++i) { *(u4v*)&Wn[lr * LDH + lc + 8 * i] = ra[i]; *(u4v*)&Wn[(256 + lr) * LDH + lc + 8 * i] = rb[i]; }
;     }
;     if (kt + 2 < nk) {
; #pragma unroll
;       for (int i = 0; i < 4; ++i) { ra[i] = *(const u4v*)(AP_ + 8 * i); rb[i] = *(const u4v*)(BP_ + 8 * i); }
;       ao += 64; bo += 64;
;     }
; #pragma unroll
;     for (int ks = 0; ks < 4; ++ks) {
;       h8v af[4], bf[2];
; #pragma unroll
;       for (int i = 0; i < 4; ++i) af[i] = *(const h8v*)&As[(wm * 128 + i * 32 + (lane & 31)) * LDH + ks * 16 + 8 * (lane >> 5)];
; #pragma unroll
;       for (int j = 0; j < 2; ++j) bf[j] = *(const h8v*)&Bs[(wn * 64 + j * 32 + (lane & 31)) * LDH + ks * 16 + 8 * (lane >> 5)];
; #pragma unroll
;       for (int i = 0; i < 4; ++i)
; #pragma unroll
;         for (int j = 0; j < 2; ++j) acc[i][j] = mfma32(bf[j], af[i], acc[i][j]);
;     }
;     __syncthreads();
;   }
	ds_read_b128 v[232:235], v213
	ds_read_b128 v[216:219], v215
	ds_read_b128 v[236:239], v213 offset:4608
	ds_read_b128 v[220:223], v215 offset:4608
	ds_read_b128 v[224:227], v215 offset:9216
	ds_read_b128 v[228:231], v215 offset:13824
	v_mfma_f32_32x32x16_f16 v[98:113], v[208:211], v[240:243], v[98:113]
	v_mfma_f32_32x32x16_f16 v[114:129], v[174:177], v[240:243], v[114:129]
	v_mfma_f32_32x32x16_f16 v[66:81], v[208:211], v[244:247], v[66:81]
	v_mfma_f32_32x32x16_f16 v[82:97], v[174:177], v[244:247], v[82:97]
	v_mfma_f32_32x32x16_f16 v[34:49], v[208:211], v[200:203], v[34:49]
	v_mfma_f32_32x32x16_f16 v[50:65], v[174:177], v[200:203], v[50:65]
	v_mfma_f32_32x32x16_f16 v[2:17], v[208:211], v[204:207], v[2:17]
	v_mfma_f32_32x32x16_f16 v[18:33], v[174:177], v[204:207], v[18:33]
	ds_read_b128 v[208:211], v213 offset:32
	ds_read_b128 v[240:243], v215 offset:32
	ds_read_b128 v[174:177], v213 offset:4640
	ds_read_b128 v[244:247], v215 offset:4640
	ds_read_b128 v[200:203], v215 offset:9248
	ds_read_b128 v[204:207], v215 offset:13856
	s_waitcnt vmcnt(4)
	ds_write_b128 v179, v[134:137]
	ds_write_b128 v179, v[138:141] offset:16
	ds_write_b128 v179, v[142:145] offset:32
	ds_write_b128 v179, v[146:149] offset:48
	global_load_dwordx4 v[134:137], v[130:131], off offset:1024
	global_load_dwordx4 v[138:141], v[130:131], off offset:1040
	global_load_dwordx4 v[142:145], v[130:131], off offset:1056
	global_load_dwordx4 v[146:149], v[130:131], off offset:1072
	s_waitcnt lgkmcnt(14)
	v_mfma_f32_32x32x16_f16 v[98:113], v[232:235], v[216:219], v[98:113]
	s_waitcnt lgkmcnt(13)
	v_mfma_f32_32x32x16_f16 v[114:129], v[236:239], v[216:219], v[114:129]
	s_waitcnt lgkmcnt(12)
	v_mfma_f32_32x32x16_f16 v[66:81], v[232:235], v[220:223], v[66:81]
	v_mfma_f32_32x32x16_f16 v[82:97], v[236:239], v[220:223], v[82:97]
	s_waitcnt lgkmcnt(11)
	v_mfma_f32_32x32x16_f16 v[34:49], v[232:235], v[224:227], v[34:49]
	v_mfma_f32_32x32x16_f16 v[50:65], v[236:239], v[224:227], v[50:65]
	s_waitcnt lgkmcnt(10)
	v_mfma_f32_32x32x16_f16 v[2:17], v[232:235], v[228:231], v[2:17]
	v_mfma_f32_32x32x16_f16 v[18:33], v[236:239], v[228:231], v[18:33]
	ds_read_b128 v[232:235], v213 offset:64
	ds_read_b128 v[216:219], v215 offset:64
	ds_read_b128 v[236:239], v213 offset:4672
	ds_read_b128 v[220:223], v215 offset:4672
	ds_read_b128 v[224:227], v215 offset:9280
	ds_read_b128 v[228:231], v215 offset:13888
	s_waitcnt vmcnt(4)
	ds_write_b128 v179, v[150:153] offset:36864
	ds_write_b128 v179, v[154:157] offset:36880
	ds_write_b128 v179, v[158:161] offset:36896
	ds_write_b128 v179, v[162:165] offset:36912
	global_load_dwordx4 v[150:153], v[248:249], off offset:1024
	global_load_dwordx4 v[154:157], v[248:249], off offset:1040
	global_load_dwordx4 v[158:161], v[248:249], off offset:1056
	global_load_dwordx4 v[162:165], v[248:249], off offset:1072
	s_waitcnt lgkmcnt(15)
	v_mfma_f32_32x32x16_f16 v[98:113], v[208:211], v[240:243], v[98:113]
	s_waitcnt lgkmcnt(15)
	v_mfma_f32_32x32x16_f16 v[114:129], v[174:177], v[240:243], v[114:129]
	s_waitcnt lgkmcnt(15)
	v_mfma_f32_32x32x16_f16 v[66:81], v[208:211], v[244:247], v[66:81]
	v_mfma_f32_32x32x16_f16 v[82:97], v[174:177], v[244:247], v[82:97]
	s_waitcnt lgkmcnt(15)
	v_mfma_f32_32x32x16_f16 v[34:49], v[208:211], v[200:203], v[34:49]
	v_mfma_f32_32x32x16_f16 v[50:65], v[174:177], v[200:203], v[50:65]
	s_waitcnt lgkmcnt(14)
	v_mfma_f32_32x32x16_f16 v[2:17], v[208:211], v[204:207], v[2:17]
	v_mfma_f32_32x32x16_f16 v[18:33], v[174:177], v[204:207], v[18:33]
	ds_read_b128 v[208:211], v213 offset:96
	ds_read_b128 v[240:243], v215 offset:96
	ds_read_b128 v[174:177], v213 offset:4704
	ds_read_b128 v[244:247], v215 offset:4704
	ds_read_b128 v[200:203], v215 offset:9312
	ds_read_b128 v[204:207], v215 offset:13920
	s_waitcnt lgkmcnt(14)
	v_mfma_f32_32x32x16_f16 v[98:113], v[232:235], v[216:219], v[98:113]
	s_waitcnt lgkmcnt(13)
	v_mfma_f32_32x32x16_f16 v[114:129], v[236:239], v[216:219], v[114:129]
	s_waitcnt lgkmcnt(12)
	v_mfma_f32_32x32x16_f16 v[66:81], v[232:235], v[220:223], v[66:81]
	v_mfma_f32_32x32x16_f16 v[82:97], v[236:239], v[220:223], v[82:97]
	s_waitcnt lgkmcnt(11)
	v_mfma_f32_32x32x16_f16 v[34:49], v[232:235], v[224:227], v[34:49]
	v_mfma_f32_32x32x16_f16 v[50:65], v[236:239], v[224:227], v[50:65]
	s_waitcnt lgkmcnt(10)
	v_mfma_f32_32x32x16_f16 v[2:17], v[232:235], v[228:231], v[2:17]
	v_mfma_f32_32x32x16_f16 v[18:33], v[236:239], v[228:231], v[18:33]
	s_waitcnt lgkmcnt(0)
	s_barrier
; DI f16v mfma32(h8v a, h8v b, f16v c) { return __builtin_amdgcn_mfma_f32_32x32x16_f16(a, b, c, 0, 0, 0); }
; template <bool GATHER>
; DI void gemm256_main(const h16* __restrict__ A, int lda, const int* __restrict__ idx, int m0,
;                      const h16* __restrict__ B, int ldb, int n0, int K, h16* lds, f16v (&acc)[4][2]) {
;     ...
;   for (int kt = 0; kt < nk; ++kt) {
;     const h16* As = lds + (kt & 1) * (512 * LDH);
;     const h16* Bs = As + 256 * LDH;
;     h16* Wn = lds + ((kt & 1) ^ 1) * (512 * LDH);
;     if (kt + 1 < nk) {
; #pragma unroll
;       for (int i = 0; i < 4; ++i) { *(u4v*)&Wn[lr * LDH + lc + 8 * i] = ra[i]; *(u4v*)&Wn[(256 + lr) * LDH + lc + 8 * i] = rb[i]; }
;     }
;     if (kt + 2 < nk) {
; #pragma unroll
;       for (int i = 0; i < 4; ++i) { ra[i] = *(const u4v*)(AP_ + 8 * i); rb[i] = *(const u4v*)(BP_ + 8 * i); }
;       ao += 64; bo += 64;
;     }
; #pragma unroll
;     for (int ks = 0; ks < 4; ++ks) {
;       h8v af[4], bf[2];
; #pragma unroll
;       for (int i = 0; i < 4; ++i) af[i] = *(const h8v*)&As[(wm * 128 + i * 32 + (lane & 31)) * LDH + ks * 16 + 8 * (lane >> 5)];
; #pragma unroll
;       for (int j = 0; j < 2; ++j) bf[j] = *(const h8v*)&Bs[(wn * 64 + j * 32 + (lane & 31)) * LDH + ks * 16 + 8 * (lane >> 5)];
; #pragma unroll
;       for (int i = 0; i < 4; ++i)
; #pragma unroll
;         for (int j = 0; j < 2; ++j) acc[i][j] = mfma32(bf[j], af[i], acc[i][j]);
;     }
;     __syncthreads();
;   }
	ds_read_b128 v[232:235], v214
	ds_read_b128 v[216:219], v212
	ds_read_b128 v[236:239], v214 offset:4608
	ds_read_b128 v[220:223], v212 offset:4608
	ds_read_b128 v[224:227], v212 offset:9216
	ds_read_b128 v[228:231], v212 offset:13824
	v_mfma_f32_32x32x16_f16 v[98:113], v[208:211], v[240:243], v[98:113]
	v_mfma_f32_32x32x16_f16 v[114:129], v[174:177], v[240:243], v[114:129]
	v_mfma_f32_32x32x16_f16 v[66:81], v[208:211], v[244:247], v[66:81]
	v_mfma_f32_32x32x16_f16 v[82:97], v[174:177], v[244:247], v[82:97]
	v_mfma_f32_32x32x16_f16 v[34:49], v[208:211], v[200:203], v[34:49]
	v_mfma_f32_32x32x16_f16 v[50:65], v[174:177], v[200:203], v[50:65]
	v_mfma_f32_32x32x16_f16 v[2:17], v[208:211], v[204:207], v[2:17]
	v_mfma_f32_32x32x16_f16 v[18:33], v[174:177], v[204:207], v[18:33]
	ds_read_b128 v[208:211], v214 offset:32
	ds_read_b128 v[240:243], v212 offset:32
	ds_read_b128 v[174:177], v214 offset:4640
	ds_read_b128 v[244:247], v212 offset:4640
	ds_read_b128 v[200:203], v212 offset:9248
	ds_read_b128 v[204:207], v212 offset:13856
	s_waitcnt vmcnt(4)
	ds_write_b128 v178, v[134:137]
	ds_write_b128 v178, v[138:141] offset:16
	ds_write_b128 v178, v[142:145] offset:32
	ds_write_b128 v178, v[146:149] offset:48
	global_load_dwordx4 v[134:137], v[130:131], off offset:1152
	global_load_dwordx4 v[138:141], v[130:131], off offset:1168
	global_load_dwordx4 v[142:145], v[130:131], off offset:1184
	global_load_dwordx4 v[146:149], v[130:131], off offset:1200
	s_waitcnt lgkmcnt(14)
	v_mfma_f32_32x32x16_f16 v[98:113], v[232:235], v[216:219], v[98:113]
	s_waitcnt lgkmcnt(13)
	v_mfma_f32_32x32x16_f16 v[114:129], v[236:239], v[216:219], v[114:129]
	s_waitcnt lgkmcnt(12)
	v_mfma_f32_32x32x16_f16 v[66:81], v[232:235], v[220:223], v[66:81]
	v_mfma_f32_32x32x16_f16 v[82:97], v[236:239], v[220:223], v[82:97]
	s_waitcnt lgkmcnt(11)
	v_mfma_f32_32x32x16_f16 v[34:49], v[232:235], v[224:227], v[34:49]
	v_mfma_f32_32x32x16_f16 v[50:65], v[236:239], v[224:227], v[50:65]
	s_waitcnt lgkmcnt(10)
	v_mfma_f32_32x32x16_f16 v[2:17], v[232:235], v[228:231], v[2:17]
	v_mfma_f32_32x32x16_f16 v[18:33], v[236:239], v[228:231], v[18:33]
	ds_read_b128 v[232:235], v214 offset:64
	ds_read_b128 v[216:219], v212 offset:64
	ds_read_b128 v[236:239], v214 offset:4672
	ds_read_b128 v[220:223], v212 offset:4672
	ds_read_b128 v[224:227], v212 offset:9280
	ds_read_b128 v[228:231], v212 offset:13888
	s_waitcnt vmcnt(4)
	ds_write_b128 v178, v[150:153] offset:36864
	ds_write_b128 v178, v[154:157] offset:36880
	ds_write_b128 v178, v[158:161] offset:36896
	ds_write_b128 v178, v[162:165] offset:36912
	global_load_dwordx4 v[150:153], v[248:249], off offset:1152
	global_load_dwordx4 v[154:157], v[248:249], off offset:1168
	global_load_dwordx4 v[158:161], v[248:249], off offset:1184
	global_load_dwordx4 v[162:165], v[248:249], off offset:1200
	s_waitcnt lgkmcnt(15)
	v_mfma_f32_32x32x16_f16 v[98:113], v[208:211], v[240:243], v[98:113]
	s_waitcnt lgkmcnt(15)
	v_mfma_f32_32x32x16_f16 v[114:129], v[174:177], v[240:243], v[114:129]
	s_waitcnt lgkmcnt(15)
	v_mfma_f32_32x32x16_f16 v[66:81], v[208:211], v[244:247], v[66:81]
	v_mfma_f32_32x32x16_f16 v[82:97], v[174:177], v[244:247], v[82:97]
	s_waitcnt lgkmcnt(15)
	v_mfma_f32_32x32x16_f16 v[34:49], v[208:211], v[200:203], v[34:49]
	v_mfma_f32_32x32x16_f16 v[50:65], v[174:177], v[200:203], v[50:65]
	s_waitcnt lgkmcnt(14)
	v_mfma_f32_32x32x16_f16 v[2:17], v[208:211], v[204:207], v[2:17]
	v_mfma_f32_32x32x16_f16 v[18:33], v[174:177], v[204:207], v[18:33]
	ds_read_b128 v[208:211], v214 offset:96
	ds_read_b128 v[240:243], v212 offset:96
	ds_read_b128 v[174:177], v214 offset:4704
	ds_read_b128 v[244:247], v212 offset:4704
	ds_read_b128 v[200:203], v212 offset:9312
	ds_read_b128 v[204:207], v212 offset:13920
	s_waitcnt lgkmcnt(14)
	v_mfma_f32_32x32x16_f16 v[98:113], v[232:235], v[216:219], v[98:113]
	s_waitcnt lgkmcnt(13)
	v_mfma_f32_32x32x16_f16 v[114:129], v[236:239], v[216:219], v[114:129]
	s_waitcnt lgkmcnt(12)
	v_mfma_f32_32x32x16_f16 v[66:81], v[232:235], v[220:223], v[66:81]
	v_mfma_f32_32x32x16_f16 v[82:97], v[236:239], v[220:223], v[82:97]
	s_waitcnt lgkmcnt(11)
	v_mfma_f32_32x32x16_f16 v[34:49], v[232:235], v[224:227], v[34:49]
	v_mfma_f32_32x32x16_f16 v[50:65], v[236:239], v[224:227], v[50:65]
	s_waitcnt lgkmcnt(10)
	v_mfma_f32_32x32x16_f16 v[2:17], v[232:235], v[228:231], v[2:17]
	v_mfma_f32_32x32x16_f16 v[18:33], v[236:239], v[228:231], v[18:33]
	s_waitcnt lgkmcnt(0)
	s_barrier
; DI f16v mfma32(h8v a, h8v b, f16v c) { return __builtin_amdgcn_mfma_f32_32x32x16_f16(a, b, c, 0, 0, 0); }
; template <bool GATHER>
; DI void gemm256_main(const h16* __restrict__ A, int lda, const int* __restrict__ idx, int m0,
;                      const h16* __restrict__ B, int ldb, int n0, int K, h16* lds, f16v (&acc)[4][2]) {
;     ...
;   for (int kt = 0; kt < nk; ++kt) {
;     const h16* As = lds + (kt & 1) * (512 * LDH);
;     const h16* Bs = As + 256 * LDH;
;     h16* Wn = lds + ((kt & 1) ^ 1) * (512 * LDH);
;     if (kt + 1 < nk) {
; #pragma unroll
;       for (int i = 0; i < 4; ++i) { *(u4v*)&Wn[lr * LDH + lc + 8 * i] = ra[i]; *(u4v*)&Wn[(256 + lr) * LDH + lc + 8 * i] = rb[i]; }
;     }
;     if (kt + 2 < nk) {
; #pragma unroll
;       for (int i = 0; i < 4; ++i) { ra[i] = *(const u4v*)(AP_ + 8 * i); rb[i] = *(const u4v*)(BP_ + 8 * i); }
;       ao += 64; bo += 64;
;     }
; #pragma unroll
;     for (int ks = 0; ks < 4; ++ks) {
;       h8v af[4], bf[2];
; #pragma unroll
;       for (int i = 0; i < 4; ++i) af[i] = *(const h8v*)&As[(wm * 128 + i * 32 + (lane & 31)) * LDH + ks * 16 + 8 * (lane >> 5)];
; #pragma unroll
;       for (int j = 0; j < 2; ++j) bf[j] = *(const h8v*)&Bs[(wn * 64 + j * 32 + (lane & 31)) * LDH + ks * 16 + 8 * (lane >> 5)];
; #pragma unroll
;       for (int i = 0; i < 4; ++i)
; #pragma unroll
;         for (int j = 0; j < 2; ++j) acc[i][j] = mfma32(bf[j], af[i], acc[i][j]);
;     }
;     __syncthreads();
;   }
	ds_read_b128 v[232:235], v213
	ds_read_b128 v[216:219], v215
	ds_read_b128 v[236:239], v213 offset:4608
	ds_read_b128 v[220:223], v215 offset:4608
	ds_read_b128 v[224:227], v215 offset:9216
	ds_read_b128 v[228:231], v215 offset:13824
	v_mfma_f32_32x32x16_f16 v[98:113], v[208:211], v[240:243], v[98:113]
	v_mfma_f32_32x32x16_f16 v[114:129], v[174:177], v[240:243], v[114:129]
	v_mfma_f32_32x32x16_f16 v[66:81], v[208:211], v[244:247], v[66:81]
	v_mfma_f32_32x32x16_f16 v[82:97], v[174:177], v[244:247], v[82:97]
	v_mfma_f32_32x32x16_f16 v[34:49], v[208:211], v[200:203], v[34:49]
	v_mfma_f32_32x32x16_f16 v[50:65], v[174:177], v[200:203], v[50:65]
	v_mfma_f32_32x32x16_f16 v[2:17], v[208:211], v[204:207], v[2:17]
	v_mfma_f32_32x32x16_f16 v[18:33], v[174:177], v[204:207], v[18:33]
	ds_read_b128 v[208:211], v213 offset:32
	ds_read_b128 v[240:243], v215 offset:32
	ds_read_b128 v[174:177], v213 offset:4640
	ds_read_b128 v[244:247], v215 offset:4640
	ds_read_b128 v[200:203], v215 offset:9248
	ds_read_b128 v[204:207], v215 offset:13856
	s_waitcnt vmcnt(4)
	ds_write_b128 v179, v[134:137]
	ds_write_b128 v179, v[138:141] offset:16
	ds_write_b128 v179, v[142:145] offset:32
	ds_write_b128 v179, v[146:149] offset:48
	global_load_dwordx4 v[134:137], v[130:131], off offset:1280
	global_load_dwordx4 v[138:141], v[130:131], off offset:1296
	global_load_dwordx4 v[142:145], v[130:131], off offset:1312
	global_load_dwordx4 v[146:149], v[130:131], off offset:1328
	s_waitcnt lgkmcnt(14)
	v_mfma_f32_32x32x16_f16 v[98:113], v[232:235], v[216:219], v[98:113]
	s_waitcnt lgkmcnt(13)
	v_mfma_f32_32x32x16_f16 v[114:129], v[236:239], v[216:219], v[114:129]
	s_waitcnt lgkmcnt(12)
	v_mfma_f32_32x32x16_f16 v[66:81], v[232:235], v[220:223], v[66:81]
	v_mfma_f32_32x32x16_f16 v[82:97], v[236:239], v[220:223], v[82:97]
	s_waitcnt lgkmcnt(11)
	v_mfma_f32_32x32x16_f16 v[34:49], v[232:235], v[224:227], v[34:49]
	v_mfma_f32_32x32x16_f16 v[50:65], v[236:239], v[224:227], v[50:65]
	s_waitcnt lgkmcnt(10)
	v_mfma_f32_32x32x16_f16 v[2:17], v[232:235], v[228:231], v[2:17]
	v_mfma_f32_32x32x16_f16 v[18:33], v[236:239], v[228:231], v[18:33]
	ds_read_b128 v[232:235], v213 offset:64
	ds_read_b128 v[216:219], v215 offset:64
	ds_read_b128 v[236:239], v213 offset:4672
	ds_read_b128 v[220:223], v215 offset:4672
	ds_read_b128 v[224:227], v215 offset:9280
	ds_read_b128 v[228:231], v215 offset:13888
	s_waitcnt vmcnt(4)
	ds_write_b128 v179, v[150:153] offset:36864
	ds_write_b128 v179, v[154:157] offset:36880
	ds_write_b128 v179, v[158:161] offset:36896
	ds_write_b128 v179, v[162:165] offset:36912
	global_load_dwordx4 v[150:153], v[248:249], off offset:1280
	global_load_dwordx4 v[154:157], v[248:249], off offset:1296
	global_load_dwordx4 v[158:161], v[248:249], off offset:1312
	global_load_dwordx4 v[162:165], v[248:249], off offset:1328
	s_waitcnt lgkmcnt(15)
	v_mfma_f32_32x32x16_f16 v[98:113], v[208:211], v[240:243], v[98:113]
	s_waitcnt lgkmcnt(15)
	v_mfma_f32_32x32x16_f16 v[114:129], v[174:177], v[240:243], v[114:129]
	s_waitcnt lgkmcnt(15)
	v_mfma_f32_32x32x16_f16 v[66:81], v[208:211], v[244:247], v[66:81]
	v_mfma_f32_32x32x16_f16 v[82:97], v[174:177], v[244:247], v[82:97]
	s_waitcnt lgkmcnt(15)
	v_mfma_f32_32x32x16_f16 v[34:49], v[208:211], v[200:203], v[34:49]
	v_mfma_f32_32x32x16_f16 v[50:65], v[174:177], v[200:203], v[50:65]
	s_waitcnt lgkmcnt(14)
	v_mfma_f32_32x32x16_f16 v[2:17], v[208:211], v[204:207], v[2:17]
	v_mfma_f32_32x32x16_f16 v[18:33], v[174:177], v[204:207], v[18:33]
	ds_read_b128 v[208:211], v213 offset:96
	ds_read_b128 v[240:243], v215 offset:96
	ds_read_b128 v[174:177], v213 offset:4704
	ds_read_b128 v[244:247], v215 offset:4704
	ds_read_b128 v[200:203], v215 offset:9312
	ds_read_b128 v[204:207], v215 offset:13920
	s_waitcnt lgkmcnt(14)
	v_mfma_f32_32x32x16_f16 v[98:113], v[232:235], v[216:219], v[98:113]
	s_waitcnt lgkmcnt(13)
	v_mfma_f32_32x32x16_f16 v[114:129], v[236:239], v[216:219], v[114:129]
	s_waitcnt lgkmcnt(12)
	v_mfma_f32_32x32x16_f16 v[66:81], v[232:235], v[220:223], v[66:81]
	v_mfma_f32_32x32x16_f16 v[82:97], v[236:239], v[220:223], v[82:97]
	s_waitcnt lgkmcnt(11)
	v_mfma_f32_32x32x16_f16 v[34:49], v[232:235], v[224:227], v[34:49]
	v_mfma_f32_32x32x16_f16 v[50:65], v[236:239], v[224:227], v[50:65]
	s_waitcnt lgkmcnt(10)
	v_mfma_f32_32x32x16_f16 v[2:17], v[232:235], v[228:231], v[2:17]
	v_mfma_f32_32x32x16_f16 v[18:33], v[236:239], v[228:231], v[18:33]
	s_waitcnt lgkmcnt(0)
	s_barrier
; DI f16v mfma32(h8v a, h8v b, f16v c) { return __builtin_amdgcn_mfma_f32_32x32x16_f16(a, b, c, 0, 0, 0); }
; template <bool GATHER>
; DI void gemm256_main(const h16* __restrict__ A, int lda, const int* __restrict__ idx, int m0,
;                      const h16* __restrict__ B, int ldb, int n0, int K, h16* lds, f16v (&acc)[4][2]) {
;     ...
;   for (int kt = 0; kt < nk; ++kt) {
;     const h16* As = lds + (kt & 1) * (512 * LDH);
;     const h16* Bs = As + 256 * LDH;
;     h16* Wn = lds + ((kt & 1) ^ 1) * (512 * LDH);
;     if (kt + 1 < nk) {
; #pragma unroll
;       for (int i = 0; i < 4; ++i) { *(u4v*)&Wn[lr * LDH + lc + 8 * i] = ra[i]; *(u4v*)&Wn[(256 + lr) * LDH + lc + 8 * i] = rb[i]; }
;     }
;     if (kt + 2 < nk) {
; #pragma unroll
;       for (int i = 0; i < 4; ++i) { ra[i] = *(const u4v*)(AP_ + 8 * i); rb[i] = *(const u4v*)(BP_ + 8 * i); }
;       ao += 64; bo += 64;
;     }
; #pragma unroll
;     for (int ks = 0; ks < 4; ++ks) {
;       h8v af[4], bf[2];
; #pragma unroll
;       for (int i = 0; i < 4; ++i) af[i] = *(const h8v*)&As[(wm * 128 + i * 32 + (lane & 31)) * LDH + ks * 16 + 8 * (lane >> 5)];
; #pragma unroll
;       for (int j = 0; j < 2; ++j) bf[j] = *(const h8v*)&Bs[(wn * 64 + j * 32 + (lane & 31)) * LDH + ks * 16 + 8 * (lane >> 5)];
; #pragma unroll
;       for (int i = 0; i < 4; ++i)
; #pragma unroll
;         for (int j = 0; j < 2; ++j) acc[i][j] = mfma32(bf[j], af[i], acc[i][j]);
;     }
;     __syncthreads();
;   }
	ds_read_b128 v[232:235], v214
	ds_read_b128 v[216:219], v212
	ds_read_b128 v[236:239], v214 offset:4608
	ds_read_b128 v[220:223], v212 offset:4608
	ds_read_b128 v[224:227], v212 offset:9216
	ds_read_b128 v[228:231], v212 offset:13824
	v_mfma_f32_32x32x16_f16 v[98:113], v[208:211], v[240:243], v[98:113]
	v_mfma_f32_32x32x16_f16 v[114:129], v[174:177], v[240:243], v[114:129]
	v_mfma_f32_32x32x16_f16 v[66:81], v[208:211], v[244:247], v[66:81]
	v_mfma_f32_32x32x16_f16 v[82:97], v[174:177], v[244:247], v[82:97]
	v_mfma_f32_32x32x16_f16 v[34:49], v[208:211], v[200:203], v[34:49]
	v_mfma_f32_32x32x16_f16 v[50:65], v[174:177], v[200:203], v[50:65]
	v_mfma_f32_32x32x16_f16 v[2:17], v[208:211], v[204:207], v[2:17]
	v_mfma_f32_32x32x16_f16 v[18:33], v[174:177], v[204:207], v[18:33]
	ds_read_b128 v[208:211], v214 offset:32
	ds_read_b128 v[240:243], v212 offset:32
	ds_read_b128 v[174:177], v214 offset:4640
	ds_read_b128 v[244:247], v212 offset:4640
	ds_read_b128 v[200:203], v212 offset:9248
	ds_read_b128 v[204:207], v212 offset:13856
	s_waitcnt vmcnt(4)
	ds_write_b128 v178, v[134:137]
	ds_write_b128 v178, v[138:141] offset:16
	ds_write_b128 v178, v[142:145] offset:32
	ds_write_b128 v178, v[146:149] offset:48
	global_load_dwordx4 v[134:137], v[130:131], off offset:1408
	global_load_dwordx4 v[138:141], v[130:131], off offset:1424
	global_load_dwordx4 v[142:145], v[130:131], off offset:1440
	global_load_dwordx4 v[146:149], v[130:131], off offset:1456
	s_waitcnt lgkmcnt(14)
	v_mfma_f32_32x32x16_f16 v[98:113], v[232:235], v[216:219], v[98:113]
	s_waitcnt lgkmcnt(13)
	v_mfma_f32_32x32x16_f16 v[114:129], v[236:239], v[216:219], v[114:129]
	s_waitcnt lgkmcnt(12)
	v_mfma_f32_32x32x16_f16 v[66:81], v[232:235], v[220:223], v[66:81]
	v_mfma_f32_32x32x16_f16 v[82:97], v[236:239], v[220:223], v[82:97]
	s_waitcnt lgkmcnt(11)
	v_mfma_f32_32x32x16_f16 v[34:49], v[232:235], v[224:227], v[34:49]
	v_mfma_f32_32x32x16_f16 v[50:65], v[236:239], v[224:227], v[50:65]
	s_waitcnt lgkmcnt(10)
	v_mfma_f32_32x32x16_f16 v[2:17], v[232:235], v[228:231], v[2:17]
	v_mfma_f32_32x32x16_f16 v[18:33], v[236:239], v[228:231], v[18:33]
	ds_read_b128 v[232:235], v214 offset:64
	ds_read_b128 v[216:219], v212 offset:64
	ds_read_b128 v[236:239], v214 offset:4672
	ds_read_b128 v[220:223], v212 offset:4672
	ds_read_b128 v[224:227], v212 offset:9280
	ds_read_b128 v[228:231], v212 offset:13888
	s_waitcnt vmcnt(4)
	ds_write_b128 v178, v[150:153] offset:36864
	ds_write_b128 v178, v[154:157] offset:36880
	ds_write_b128 v178, v[158:161] offset:36896
	ds_write_b128 v178, v[162:165] offset:36912
	global_load_dwordx4 v[150:153], v[248:249], off offset:1408
	global_load_dwordx4 v[154:157], v[248:249], off offset:1424
	global_load_dwordx4 v[158:161], v[248:249], off offset:1440
	global_load_dwordx4 v[162:165], v[248:249], off offset:1456
	s_waitcnt lgkmcnt(15)
	v_mfma_f32_32x32x16_f16 v[98:113], v[208:211], v[240:243], v[98:113]
	s_waitcnt lgkmcnt(15)
	v_mfma_f32_32x32x16_f16 v[114:129], v[174:177], v[240:243], v[114:129]
	s_waitcnt lgkmcnt(15)
	v_mfma_f32_32x32x16_f16 v[66:81], v[208:211], v[244:247], v[66:81]
	v_mfma_f32_32x32x16_f16 v[82:97], v[174:177], v[244:247], v[82:97]
	s_waitcnt lgkmcnt(15)
	v_mfma_f32_32x32x16_f16 v[34:49], v[208:211], v[200:203], v[34:49]
	v_mfma_f32_32x32x16_f16 v[50:65], v[174:177], v[200:203], v[50:65]
	s_waitcnt lgkmcnt(14)
	v_mfma_f32_32x32x16_f16 v[2:17], v[208:211], v[204:207], v[2:17]
	v_mfma_f32_32x32x16_f16 v[18:33], v[174:177], v[204:207], v[18:33]
	ds_read_b128 v[208:211], v214 offset:96
	ds_read_b128 v[240:243], v212 offset:96
	ds_read_b128 v[174:177], v214 offset:4704
	ds_read_b128 v[244:247], v212 offset:4704
	ds_read_b128 v[200:203], v212 offset:9312
	ds_read_b128 v[204:207], v212 offset:13920
	s_waitcnt lgkmcnt(14)
	v_mfma_f32_32x32x16_f16 v[98:113], v[232:235], v[216:219], v[98:113]
	s_waitcnt lgkmcnt(13)
	v_mfma_f32_32x32x16_f16 v[114:129], v[236:239], v[216:219], v[114:129]
	s_waitcnt lgkmcnt(12)
	v_mfma_f32_32x32x16_f16 v[66:81], v[232:235], v[220:223], v[66:81]
	v_mfma_f32_32x32x16_f16 v[82:97], v[236:239], v[220:223], v[82:97]
	s_waitcnt lgkmcnt(11)
	v_mfma_f32_32x32x16_f16 v[34:49], v[232:235], v[224:227], v[34:49]
	v_mfma_f32_32x32x16_f16 v[50:65], v[236:239], v[224:227], v[50:65]
	s_waitcnt lgkmcnt(10)
	v_mfma_f32_32x32x16_f16 v[2:17], v[232:235], v[228:231], v[2:17]
	v_mfma_f32_32x32x16_f16 v[18:33], v[236:239], v[228:231], v[18:33]
	s_waitcnt lgkmcnt(0)
	s_barrier
; DI f16v mfma32(h8v a, h8v b, f16v c) { return __builtin_amdgcn_mfma_f32_32x32x16_f16(a, b, c, 0, 0, 0); }
; template <bool GATHER>
; DI void gemm256_main(const h16* __restrict__ A, int lda, const int* __restrict__ idx, int m0,
;                      const h16* __restrict__ B, int ldb, int n0, int K, h16* lds, f16v (&acc)[4][2]) {
;     ...
;   for (int kt = 0; kt < nk; ++kt) {
;     const h16* As = lds + (kt & 1) * (512 * LDH);
;     const h16* Bs = As + 256 * LDH;
;     h16* Wn = lds + ((kt & 1) ^ 1) * (512 * LDH);
;     if (kt + 1 < nk) {
; #pragma unroll
;       for (int i = 0; i < 4; ++i) { *(u4v*)&Wn[lr * LDH + lc + 8 * i] = ra[i]; *(u4v*)&Wn[(256 + lr) * LDH + lc + 8 * i] = rb[i]; }
;     }
;     if (kt + 2 < nk) {
; #pragma unroll
;       for (int i = 0; i < 4; ++i) { ra[i] = *(const u4v*)(AP_ + 8 * i); rb[i] = *(const u4v*)(BP_ + 8 * i); }
;       ao += 64; bo += 64;
;     }
; #pragma unroll
;     for (int ks = 0; ks < 4; ++ks) {
;       h8v af[4], bf[2];
; #pragma unroll
;       for (int i = 0; i < 4; ++i) af[i] = *(const h8v*)&As[(wm * 128 + i * 32 + (lane & 31)) * LDH + ks * 16 + 8 * (lane >> 5)];
; #pragma unroll
;       for (int j = 0; j < 2; ++j) bf[j] = *(const h8v*)&Bs[(wn * 64 + j * 32 + (lane & 31)) * LDH + ks * 16 + 8 * (lane >> 5)];
; #pragma unroll
;       for (int i = 0; i < 4; ++i)
; #pragma unroll
;         for (int j = 0; j < 2; ++j) acc[i][j] = mfma32(bf[j], af[i], acc[i][j]);
;     }
;     __syncthreads();
;   }
	ds_read_b128 v[232:235], v213
	ds_read_b128 v[216:219], v215
	ds_read_b128 v[236:239], v213 offset:4608
	ds_read_b128 v[220:223], v215 offset:4608
	ds_read_b128 v[224:227], v215 offset:9216
	ds_read_b128 v[228:231], v215 offset:13824
	v_mfma_f32_32x32x16_f16 v[98:113], v[208:211], v[240:243], v[98:113]
	v_mfma_f32_32x32x16_f16 v[114:129], v[174:177], v[240:243], v[114:129]
	v_mfma_f32_32x32x16_f16 v[66:81], v[208:211], v[244:247], v[66:81]
	v_mfma_f32_32x32x16_f16 v[82:97], v[174:177], v[244:247], v[82:97]
	v_mfma_f32_32x32x16_f16 v[34:49], v[208:211], v[200:203], v[34:49]
	v_mfma_f32_32x32x16_f16 v[50:65], v[174:177], v[200:203], v[50:65]
	v_mfma_f32_32x32x16_f16 v[2:17], v[208:211], v[204:207], v[2:17]
	v_mfma_f32_32x32x16_f16 v[18:33], v[174:177], v[204:207], v[18:33]
	ds_read_b128 v[208:211], v213 offset:32
	ds_read_b128 v[240:243], v215 offset:32
	ds_read_b128 v[174:177], v213 offset:4640
	ds_read_b128 v[244:247], v215 offset:4640
	ds_read_b128 v[200:203], v215 offset:9248
	ds_read_b128 v[204:207], v215 offset:13856
	s_waitcnt vmcnt(4)
	ds_write_b128 v179, v[134:137]
	ds_write_b128 v179, v[138:141] offset:16
	ds_write_b128 v179, v[142:145] offset:32
	ds_write_b128 v179, v[146:149] offset:48
	global_load_dwordx4 v[134:137], v[130:131], off offset:1536
	global_load_dwordx4 v[138:141], v[130:131], off offset:1552
	global_load_dwordx4 v[142:145], v[130:131], off offset:1568
	global_load_dwordx4 v[146:149], v[130:131], off offset:1584
	s_waitcnt lgkmcnt(14)
	v_mfma_f32_32x32x16_f16 v[98:113], v[232:235], v[216:219], v[98:113]
	s_waitcnt lgkmcnt(13)
	v_mfma_f32_32x32x16_f16 v[114:129], v[236:239], v[216:219], v[114:129]
	s_waitcnt lgkmcnt(12)
	v_mfma_f32_32x32x16_f16 v[66:81], v[232:235], v[220:223], v[66:81]
	v_mfma_f32_32x32x16_f16 v[82:97], v[236:239], v[220:223], v[82:97]
	s_waitcnt lgkmcnt(11)
	v_mfma_f32_32x32x16_f16 v[34:49], v[232:235], v[224:227], v[34:49]
	v_mfma_f32_32x32x16_f16 v[50:65], v[236:239], v[224:227], v[50:65]
	s_waitcnt lgkmcnt(10)
	v_mfma_f32_32x32x16_f16 v[2:17], v[232:235], v[228:231], v[2:17]
	v_mfma_f32_32x32x16_f16 v[18:33], v[236:239], v[228:231], v[18:33]
	ds_read_b128 v[232:235], v213 offset:64
	ds_read_b128 v[216:219], v215 offset:64
	ds_read_b128 v[236:239], v213 offset:4672
	ds_read_b128 v[220:223], v215 offset:4672
	ds_read_b128 v[224:227], v215 offset:9280
	ds_read_b128 v[228:231], v215 offset:13888
	s_waitcnt vmcnt(4)
	ds_write_b128 v179, v[150:153] offset:36864
	ds_write_b128 v179, v[154:157] offset:36880
	ds_write_b128 v179, v[158:161] offset:36896
	ds_write_b128 v179, v[162:165] offset:36912
	global_load_dwordx4 v[150:153], v[248:249], off offset:1536
	global_load_dwordx4 v[154:157], v[248:249], off offset:1552
	global_load_dwordx4 v[158:161], v[248:249], off offset:1568
	global_load_dwordx4 v[162:165], v[248:249], off offset:1584
	s_waitcnt lgkmcnt(15)
	v_mfma_f32_32x32x16_f16 v[98:113], v[208:211], v[240:243], v[98:113]
	s_waitcnt lgkmcnt(15)
	v_mfma_f32_32x32x16_f16 v[114:129], v[174:177], v[240:243], v[114:129]
	s_waitcnt lgkmcnt(15)
	v_mfma_f32_32x32x16_f16 v[66:81], v[208:211], v[244:247], v[66:81]
	v_mfma_f32_32x32x16_f16 v[82:97], v[174:177], v[244:247], v[82:97]
	s_waitcnt lgkmcnt(15)
	v_mfma_f32_32x32x16_f16 v[34:49], v[208:211], v[200:203], v[34:49]
	v_mfma_f32_32x32x16_f16 v[50:65], v[174:177], v[200:203], v[50:65]
	s_waitcnt lgkmcnt(14)
	v_mfma_f32_32x32x16_f16 v[2:17], v[208:211], v[204:207], v[2:17]
	v_mfma_f32_32x32x16_f16 v[18:33], v[174:177], v[204:207], v[18:33]
	ds_read_b128 v[208:211], v213 offset:96
	ds_read_b128 v[240:243], v215 offset:96
	ds_read_b128 v[174:177], v213 offset:4704
	ds_read_b128 v[244:247], v215 offset:4704
	ds_read_b128 v[200:203], v215 offset:9312
	ds_read_b128 v[204:207], v215 offset:13920
	s_waitcnt lgkmcnt(14)
	v_mfma_f32_32x32x16_f16 v[98:113], v[232:235], v[216:219], v[98:113]
	s_waitcnt lgkmcnt(13)
	v_mfma_f32_32x32x16_f16 v[114:129], v[236:239], v[216:219], v[114:129]
	s_waitcnt lgkmcnt(12)
	v_mfma_f32_32x32x16_f16 v[66:81], v[232:235], v[220:223], v[66:81]
	v_mfma_f32_32x32x16_f16 v[82:97], v[236:239], v[220:223], v[82:97]
	s_waitcnt lgkmcnt(11)
	v_mfma_f32_32x32x16_f16 v[34:49], v[232:235], v[224:227], v[34:49]
	v_mfma_f32_32x32x16_f16 v[50:65], v[236:239], v[224:227], v[50:65]
	s_waitcnt lgkmcnt(10)
	v_mfma_f32_32x32x16_f16 v[2:17], v[232:235], v[228:231], v[2:17]
	v_mfma_f32_32x32x16_f16 v[18:33], v[236:239], v[228:231], v[18:33]
	s_waitcnt lgkmcnt(0)
	s_barrier
; DI f16v mfma32(h8v a, h8v b, f16v c) { return __builtin_amdgcn_mfma_f32_32x32x16_f16(a, b, c, 0, 0, 0); }
; template <bool GATHER>
; DI void gemm256_main(const h16* __restrict__ A, int lda, const int* __restrict__ idx, int m0,
;                      const h16* __restrict__ B, int ldb, int n0, int K, h16* lds, f16v (&acc)[4][2]) {
;     ...
;   for (int kt = 0; kt < nk; ++kt) {
;     const h16* As = lds + (kt & 1) * (512 * LDH);
;     const h16* Bs = As + 256 * LDH;
;     h16* Wn = lds + ((kt & 1) ^ 1) * (512 * LDH);
;     if (kt + 1 < nk) {
; #pragma unroll
;       for (int i = 0; i < 4; ++i) { *(u4v*)&Wn[lr * LDH + lc + 8 * i] = ra[i]; *(u4v*)&Wn[(256 + lr) * LDH + lc + 8 * i] = rb[i]; }
;     }
;     if (kt + 2 < nk) {
; #pragma unroll
;       for (int i = 0; i < 4; ++i) { ra[i] = *(const u4v*)(AP_ + 8 * i); rb[i] = *(const u4v*)(BP_ + 8 * i); }
;       ao += 64; bo += 64;
;     }
; #pragma unroll
;     for (int ks = 0; ks < 4; ++ks) {
;       h8v af[4], bf[2];
; #pragma unroll
;       for (int i = 0; i < 4; ++i) af[i] = *(const h8v*)&As[(wm * 128 + i * 32 + (lane & 31)) * LDH + ks * 16 + 8 * (lane >> 5)];
; #pragma unroll
;       for (int j = 0; j < 2; ++j) bf[j] = *(const h8v*)&Bs[(wn * 64 + j * 32 + (lane & 31)) * LDH + ks * 16 + 8 * (lane >> 5)];
; #pragma unroll
;       for (int i = 0; i < 4; ++i)
; #pragma unroll
;         for (int j = 0; j < 2; ++j) acc[i][j] = mfma32(bf[j], af[i], acc[i][j]);
;     }
;     __syncthreads();
;   }
	ds_read_b128 v[232:235], v214
	ds_read_b128 v[216:219], v212
	ds_read_b128 v[236:239], v214 offset:4608
	ds_read_b128 v[220:223], v212 offset:4608
	ds_read_b128 v[224:227], v212 offset:9216
	ds_read_b128 v[228:231], v212 offset:13824
	v_mfma_f32_32x32x16_f16 v[98:113], v[208:211], v[240:243], v[98:113]
	v_mfma_f32_32x32x16_f16 v[114:129], v[174:177], v[240:243], v[114:129]
	v_mfma_f32_32x32x16_f16 v[66:81], v[208:211], v[244:247], v[66:81]
	v_mfma_f32_32x32x16_f16 v[82:97], v[174:177], v[244:247], v[82:97]
	v_mfma_f32_32x32x16_f16 v[34:49], v[208:211], v[200:203], v[34:49]
	v_mfma_f32_32x32x16_f16 v[50:65], v[174:177], v[200:203], v[50:65]
	v_mfma_f32_32x32x16_f16 v[2:17], v[208:211], v[204:207], v[2:17]
	v_mfma_f32_32x32x16_f16 v[18:33], v[174:177], v[204:207], v[18:33]
	ds_read_b128 v[208:211], v214 offset:32
	ds_read_b128 v[240:243], v212 offset:32
	ds_read_b128 v[174:177], v214 offset:4640
	ds_read_b128 v[244:247], v212 offset:4640
	ds_read_b128 v[200:203], v212 offset:9248
	ds_read_b128 v[204:207], v212 offset:13856
	s_waitcnt vmcnt(4)
	ds_write_b128 v178, v[134:137]
	ds_write_b128 v178, v[138:141] offset:16
	ds_write_b128 v178, v[142:145] offset:32
	ds_write_b128 v178, v[146:149] offset:48
	global_load_dwordx4 v[134:137], v[130:131], off offset:1664
	global_load_dwordx4 v[138:141], v[130:131], off offset:1680
	global_load_dwordx4 v[142:145], v[130:131], off offset:1696
	global_load_dwordx4 v[146:149], v[130:131], off offset:1712
	s_waitcnt lgkmcnt(14)
	v_mfma_f32_32x32x16_f16 v[98:113], v[232:235], v[216:219], v[98:113]
	s_waitcnt lgkmcnt(13)
	v_mfma_f32_32x32x16_f16 v[114:129], v[236:239], v[216:219], v[114:129]
	s_waitcnt lgkmcnt(12)
	v_mfma_f32_32x32x16_f16 v[66:81], v[232:235], v[220:223], v[66:81]
	v_mfma_f32_32x32x16_f16 v[82:97], v[236:239], v[220:223], v[82:97]
	s_waitcnt lgkmcnt(11)
	v_mfma_f32_32x32x16_f16 v[34:49], v[232:235], v[224:227], v[34:49]
	v_mfma_f32_32x32x16_f16 v[50:65], v[236:239], v[224:227], v[50:65]
	s_waitcnt lgkmcnt(10)
	v_mfma_f32_32x32x16_f16 v[2:17], v[232:235], v[228:231], v[2:17]
	v_mfma_f32_32x32x16_f16 v[18:33], v[236:239], v[228:231], v[18:33]
	ds_read_b128 v[232:235], v214 offset:64
	ds_read_b128 v[216:219], v212 offset:64
	ds_read_b128 v[236:239], v214 offset:4672
	ds_read_b128 v[220:223], v212 offset:4672
	ds_read_b128 v[224:227], v212 offset:9280
	ds_read_b128 v[228:231], v212 offset:13888
	s_waitcnt vmcnt(4)
	ds_write_b128 v178, v[150:153] offset:36864
	ds_write_b128 v178, v[154:157] offset:36880
	ds_write_b128 v178, v[158:161] offset:36896
	ds_write_b128 v178, v[162:165] offset:36912
	global_load_dwordx4 v[150:153], v[248:249], off offset:1664
	global_load_dwordx4 v[154:157], v[248:249], off offset:1680
	global_load_dwordx4 v[158:161], v[248:249], off offset:1696
	global_load_dwordx4 v[162:165], v[248:249], off offset:1712
	s_waitcnt lgkmcnt(15)
	v_mfma_f32_32x32x16_f16 v[98:113], v[208:211], v[240:243], v[98:113]
	s_waitcnt lgkmcnt(15)
	v_mfma_f32_32x32x16_f16 v[114:129], v[174:177], v[240:243], v[114:129]
	s_waitcnt lgkmcnt(15)
	v_mfma_f32_32x32x16_f16 v[66:81], v[208:211], v[244:247], v[66:81]
	v_mfma_f32_32x32x16_f16 v[82:97], v[174:177], v[244:247], v[82:97]
	s_waitcnt lgkmcnt(15)
	v_mfma_f32_32x32x16_f16 v[34:49], v[208:211], v[200:203], v[34:49]
	v_mfma_f32_32x32x16_f16 v[50:65], v[174:177], v[200:203], v[50:65]
	s_waitcnt lgkmcnt(14)
	v_mfma_f32_32x32x16_f16 v[2:17], v[208:211], v[204:207], v[2:17]
	v_mfma_f32_32x32x16_f16 v[18:33], v[174:177], v[204:207], v[18:33]
	ds_read_b128 v[208:211], v214 offset:96
	ds_read_b128 v[240:243], v212 offset:96
	ds_read_b128 v[174:177], v214 offset:4704
	ds_read_b128 v[244:247], v212 offset:4704
	ds_read_b128 v[200:203], v212 offset:9312
	ds_read_b128 v[204:207], v212 offset:13920
	s_waitcnt lgkmcnt(14)
	v_mfma_f32_32x32x16_f16 v[98:113], v[232:235], v[216:219], v[98:113]
	s_waitcnt lgkmcnt(13)
	v_mfma_f32_32x32x16_f16 v[114:129], v[236:239], v[216:219], v[114:129]
	s_waitcnt lgkmcnt(12)
	v_mfma_f32_32x32x16_f16 v[66:81], v[232:235], v[220:223], v[66:81]
	v_mfma_f32_32x32x16_f16 v[82:97], v[236:239], v[220:223], v[82:97]
	s_waitcnt lgkmcnt(11)
	v_mfma_f32_32x32x16_f16 v[34:49], v[232:235], v[224:227], v[34:49]
	v_mfma_f32_32x32x16_f16 v[50:65], v[236:239], v[224:227], v[50:65]
	s_waitcnt lgkmcnt(10)
	v_mfma_f32_32x32x16_f16 v[2:17], v[232:235], v[228:231], v[2:17]
	v_mfma_f32_32x32x16_f16 v[18:33], v[236:239], v[228:231], v[18:33]
	s_waitcnt lgkmcnt(0)
	s_barrier
; DI f16v mfma32(h8v a, h8v b, f16v c) { return __builtin_amdgcn_mfma_f32_32x32x16_f16(a, b, c, 0, 0, 0); }
; template <bool GATHER>
; DI void gemm256_main(const h16* __restrict__ A, int lda, const int* __restrict__ idx, int m0,
;                      const h16* __restrict__ B, int ldb, int n0, int K, h16* lds, f16v (&acc)[4][2]) {
;     ...
;   for (int kt = 0; kt < nk; ++kt) {
;     const h16* As = lds + (kt & 1) * (512 * LDH);
;     const h16* Bs = As + 256 * LDH;
;     h16* Wn = lds + ((kt & 1) ^ 1) * (512 * LDH);
;     if (kt + 1 < nk) {
; #pragma unroll
;       for (int i = 0; i < 4; ++i) { *(u4v*)&Wn[lr * LDH + lc + 8 * i] = ra[i]; *(u4v*)&Wn[(256 + lr) * LDH + lc + 8 * i] = rb[i]; }
;     }
;     if (kt + 2 < nk) {
; #pragma unroll
;       for (int i = 0; i < 4; ++i) { ra[i] = *(const u4v*)(AP_ + 8 * i); rb[i] = *(const u4v*)(BP_ + 8 * i); }
;       ao += 64; bo += 64;
;     }
; #pragma unroll
;     for (int ks = 0; ks < 4; ++ks) {
;       h8v af[4], bf[2];
; #pragma unroll
;       for (int i = 0; i < 4; ++i) af[i] = *(const h8v*)&As[(wm * 128 + i * 32 + (lane & 31)) * LDH + ks * 16 + 8 * (lane >> 5)];
; #pragma unroll
;       for (int j = 0; j < 2; ++j) bf[j] = *(const h8v*)&Bs[(wn * 64 + j * 32 + (lane & 31)) * LDH + ks * 16 + 8 * (lane >> 5)];
; #pragma unroll
;       for (int i = 0; i < 4; ++i)
; #pragma unroll
;         for (int j = 0; j < 2; ++j) acc[i][j] = mfma32(bf[j], af[i], acc[i][j]);
;     }
;     __syncthreads();
;   }
	ds_read_b128 v[232:235], v213
	ds_read_b128 v[216:219], v215
	ds_read_b128 v[236:239], v213 offset:4608
	ds_read_b128 v[220:223], v215 offset:4608
	ds_read_b128 v[224:227], v215 offset:9216
	ds_read_b128 v[228:231], v215 offset:13824
	v_mfma_f32_32x32x16_f16 v[98:113], v[208:211], v[240:243], v[98:113]
	v_mfma_f32_32x32x16_f16 v[114:129], v[174:177], v[240:243], v[114:129]
	v_mfma_f32_32x32x16_f16 v[66:81], v[208:211], v[244:247], v[66:81]
	v_mfma_f32_32x32x16_f16 v[82:97], v[174:177], v[244:247], v[82:97]
	v_mfma_f32_32x32x16_f16 v[34:49], v[208:211], v[200:203], v[34:49]
	v_mfma_f32_32x32x16_f16 v[50:65], v[174:177], v[200:203], v[50:65]
	v_mfma_f32_32x32x16_f16 v[2:17], v[208:211], v[204:207], v[2:17]
	v_mfma_f32_32x32x16_f16 v[18:33], v[174:177], v[204:207], v[18:33]
	ds_read_b128 v[208:211], v213 offset:32
	ds_read_b128 v[240:243], v215 offset:32
	ds_read_b128 v[174:177], v213 offset:4640
	ds_read_b128 v[244:247], v215 offset:4640
	ds_read_b128 v[200:203], v215 offset:9248
	ds_read_b128 v[204:207], v215 offset:13856
	s_waitcnt vmcnt(4)
	ds_write_b128 v179, v[134:137]
	ds_write_b128 v179, v[138:141] offset:16
	ds_write_b128 v179, v[142:145] offset:32
	ds_write_b128 v179, v[146:149] offset:48
	global_load_dwordx4 v[134:137], v[130:131], off offset:1792
	global_load_dwordx4 v[138:141], v[130:131], off offset:1808
	global_load_dwordx4 v[142:145], v[130:131], off offset:1824
	global_load_dwordx4 v[146:149], v[130:131], off offset:1840
	s_waitcnt lgkmcnt(14)
	v_mfma_f32_32x32x16_f16 v[98:113], v[232:235], v[216:219], v[98:113]
	s_waitcnt lgkmcnt(13)
	v_mfma_f32_32x32x16_f16 v[114:129], v[236:239], v[216:219], v[114:129]
	s_waitcnt lgkmcnt(12)
	v_mfma_f32_32x32x16_f16 v[66:81], v[232:235], v[220:223], v[66:81]
	v_mfma_f32_32x32x16_f16 v[82:97], v[236:239], v[220:223], v[82:97]
	s_waitcnt lgkmcnt(11)
	v_mfma_f32_32x32x16_f16 v[34:49], v[232:235], v[224:227], v[34:49]
	v_mfma_f32_32x32x16_f16 v[50:65], v[236:239], v[224:227], v[50:65]
	s_waitcnt lgkmcnt(10)
	v_mfma_f32_32x32x16_f16 v[2:17], v[232:235], v[228:231], v[2:17]
	v_mfma_f32_32x32x16_f16 v[18:33], v[236:239], v[228:231], v[18:33]
	ds_read_b128 v[232:235], v213 offset:64
	ds_read_b128 v[216:219], v215 offset:64
	ds_read_b128 v[236:239], v213 offset:4672
	ds_read_b128 v[220:223], v215 offset:4672
	ds_read_b128 v[224:227], v215 offset:9280
	ds_read_b128 v[228:231], v215 offset:13888
	s_waitcnt vmcnt(4)
	ds_write_b128 v179, v[150:153] offset:36864
	ds_write_b128 v179, v[154:157] offset:36880
	ds_write_b128 v179, v[158:161] offset:36896
	ds_write_b128 v179, v[162:165] offset:36912
	global_load_dwordx4 v[150:153], v[248:249], off offset:1792
	global_load_dwordx4 v[154:157], v[248:249], off offset:1808
	global_load_dwordx4 v[158:161], v[248:249], off offset:1824
	global_load_dwordx4 v[162:165], v[248:249], off offset:1840
	s_waitcnt lgkmcnt(15)
	v_mfma_f32_32x32x16_f16 v[98:113], v[208:211], v[240:243], v[98:113]
	s_waitcnt lgkmcnt(15)
	v_mfma_f32_32x32x16_f16 v[114:129], v[174:177], v[240:243], v[114:129]
	s_waitcnt lgkmcnt(15)
	v_mfma_f32_32x32x16_f16 v[66:81], v[208:211], v[244:247], v[66:81]
	v_mfma_f32_32x32x16_f16 v[82:97], v[174:177], v[244:247], v[82:97]
	s_waitcnt lgkmcnt(15)
	v_mfma_f32_32x32x16_f16 v[34:49], v[208:211], v[200:203], v[34:49]
	v_mfma_f32_32x32x16_f16 v[50:65], v[174:177], v[200:203], v[50:65]
	s_waitcnt lgkmcnt(14)
	v_mfma_f32_32x32x16_f16 v[2:17], v[208:211], v[204:207], v[2:17]
	v_mfma_f32_32x32x16_f16 v[18:33], v[174:177], v[204:207], v[18:33]
	ds_read_b128 v[208:211], v213 offset:96
	ds_read_b128 v[240:243], v215 offset:96
	ds_read_b128 v[174:177], v213 offset:4704
	ds_read_b128 v[244:247], v215 offset:4704
	ds_read_b128 v[200:203], v215 offset:9312
	ds_read_b128 v[204:207], v215 offset:13920
	s_waitcnt lgkmcnt(14)
	v_mfma_f32_32x32x16_f16 v[98:113], v[232:235], v[216:219], v[98:113]
	s_waitcnt lgkmcnt(13)
	v_mfma_f32_32x32x16_f16 v[114:129], v[236:239], v[216:219], v[114:129]
	s_waitcnt lgkmcnt(12)
	v_mfma_f32_32x32x16_f16 v[66:81], v[232:235], v[220:223], v[66:81]
	v_mfma_f32_32x32x16_f16 v[82:97], v[236:239], v[220:223], v[82:97]
	s_waitcnt lgkmcnt(11)
	v_mfma_f32_32x32x16_f16 v[34:49], v[232:235], v[224:227], v[34:49]
	v_mfma_f32_32x32x16_f16 v[50:65], v[236:239], v[224:227], v[50:65]
	s_waitcnt lgkmcnt(10)
	v_mfma_f32_32x32x16_f16 v[2:17], v[232:235], v[228:231], v[2:17]
	v_mfma_f32_32x32x16_f16 v[18:33], v[236:239], v[228:231], v[18:33]
	s_waitcnt lgkmcnt(0)
	s_barrier
; DI f16v mfma32(h8v a, h8v b, f16v c) { return __builtin_amdgcn_mfma_f32_32x32x16_f16(a, b, c, 0, 0, 0); }
; template <bool GATHER>
; DI void gemm256_main(const h16* __restrict__ A, int lda, const int* __restrict__ idx, int m0,
;                      const h16* __restrict__ B, int ldb, int n0, int K, h16* lds, f16v (&acc)[4][2]) {
;     ...
;   for (int kt = 0; kt < nk; ++kt) {
;     const h16* As = lds + (kt & 1) * (512 * LDH);
;     const h16* Bs = As + 256 * LDH;
;     h16* Wn = lds + ((kt & 1) ^ 1) * (512 * LDH);
;     if (kt + 1 < nk) {
; #pragma unroll
;       for (int i = 0; i < 4; ++i) { *(u4v*)&Wn[lr * LDH + lc + 8 * i] = ra[i]; *(u4v*)&Wn[(256 + lr) * LDH + lc + 8 * i] = rb[i]; }
;     }
;     if (kt + 2 < nk) {
; #pragma unroll
;       for (int i = 0; i < 4; ++i) { ra[i] = *(const u4v*)(AP_ + 8 * i); rb[i] = *(const u4v*)(BP_ + 8 * i); }
;       ao += 64; bo += 64;
;     }
; #pragma unroll
;     for (int ks = 0; ks < 4; ++ks) {
;       h8v af[4], bf[2];
; #pragma unroll
;       for (int i = 0; i < 4; ++i) af[i] = *(const h8v*)&As[(wm * 128 + i * 32 + (lane & 31)) * LDH + ks * 16 + 8 * (lane >> 5)];
; #pragma unroll
;       for (int j = 0; j < 2; ++j) bf[j] = *(const h8v*)&Bs[(wn * 64 + j * 32 + (lane & 31)) * LDH + ks * 16 + 8 * (lane >> 5)];
; #pragma unroll
;       for (int i = 0; i < 4; ++i)
; #pragma unroll
;         for (int j = 0; j < 2; ++j) acc[i][j] = mfma32(bf[j], af[i], acc[i][j]);
;     }
;     __syncthreads();
;   }
	ds_read_b128 v[232:235], v214
	ds_read_b128 v[216:219], v212
	ds_read_b128 v[236:239], v214 offset:4608
	ds_read_b128 v[220:223], v212 offset:4608
	ds_read_b128 v[224:227], v212 offset:9216
	ds_read_b128 v[228:231], v212 offset:13824
	v_mfma_f32_32x32x16_f16 v[98:113], v[208:211], v[240:243], v[98:113]
	v_mfma_f32_32x32x16_f16 v[114:129], v[174:177], v[240:243], v[114:129]
	v_mfma_f32_32x32x16_f16 v[66:81], v[208:211], v[244:247], v[66:81]
	v_mfma_f32_32x32x16_f16 v[82:97], v[174:177], v[244:247], v[82:97]
	v_mfma_f32_32x32x16_f16 v[34:49], v[208:211], v[200:203], v[34:49]
	v_mfma_f32_32x32x16_f16 v[50:65], v[174:177], v[200:203], v[50:65]
	v_mfma_f32_32x32x16_f16 v[2:17], v[208:211], v[204:207], v[2:17]
	v_mfma_f32_32x32x16_f16 v[18:33], v[174:177], v[204:207], v[18:33]
	ds_read_b128 v[208:211], v214 offset:32
	ds_read_b128 v[240:243], v212 offset:32
	ds_read_b128 v[174:177], v214 offset:4640
	ds_read_b128 v[244:247], v212 offset:4640
	ds_read_b128 v[200:203], v212 offset:9248
	ds_read_b128 v[204:207], v212 offset:13856
	s_waitcnt vmcnt(4)
	ds_write_b128 v178, v[134:137]
	ds_write_b128 v178, v[138:141] offset:16
	ds_write_b128 v178, v[142:145] offset:32
	ds_write_b128 v178, v[146:149] offset:48
	global_load_dwordx4 v[134:137], v[130:131], off offset:1920
	global_load_dwordx4 v[138:141], v[130:131], off offset:1936
	global_load_dwordx4 v[142:145], v[130:131], off offset:1952
	global_load_dwordx4 v[146:149], v[130:131], off offset:1968
	s_waitcnt lgkmcnt(14)
	v_mfma_f32_32x32x16_f16 v[98:113], v[232:235], v[216:219], v[98:113]
	s_waitcnt lgkmcnt(13)
	v_mfma_f32_32x32x16_f16 v[114:129], v[236:239], v[216:219], v[114:129]
	s_waitcnt lgkmcnt(12)
	v_mfma_f32_32x32x16_f16 v[66:81], v[232:235], v[220:223], v[66:81]
	v_mfma_f32_32x32x16_f16 v[82:97], v[236:239], v[220:223], v[82:97]
	s_waitcnt lgkmcnt(11)
	v_mfma_f32_32x32x16_f16 v[34:49], v[232:235], v[224:227], v[34:49]
	v_mfma_f32_32x32x16_f16 v[50:65], v[236:239], v[224:227], v[50:65]
	s_waitcnt lgkmcnt(10)
	v_mfma_f32_32x32x16_f16 v[2:17], v[232:235], v[228:231], v[2:17]
	v_mfma_f32_32x32x16_f16 v[18:33], v[236:239], v[228:231], v[18:33]
	ds_read_b128 v[232:235], v214 offset:64
	ds_read_b128 v[216:219], v212 offset:64
	ds_read_b128 v[236:239], v214 offset:4672
	ds_read_b128 v[220:223], v212 offset:4672
	ds_read_b128 v[224:227], v212 offset:9280
	ds_read_b128 v[228:231], v212 offset:13888
	s_waitcnt vmcnt(4)
	ds_write_b128 v178, v[150:153] offset:36864
	ds_write_b128 v178, v[154:157] offset:36880
	ds_write_b128 v178, v[158:161] offset:36896
	ds_write_b128 v178, v[162:165] offset:36912
	global_load_dwordx4 v[150:153], v[248:249], off offset:1920
	global_load_dwordx4 v[154:157], v[248:249], off offset:1936
	global_load_dwordx4 v[158:161], v[248:249], off offset:1952
	global_load_dwordx4 v[162:165], v[248:249], off offset:1968
	s_waitcnt lgkmcnt(15)
	v_mfma_f32_32x32x16_f16 v[98:113], v[208:211], v[240:243], v[98:113]
	s_waitcnt lgkmcnt(15)
	v_mfma_f32_32x32x16_f16 v[114:129], v[174:177], v[240:243], v[114:129]
	s_waitcnt lgkmcnt(15)
	v_mfma_f32_32x32x16_f16 v[66:81], v[208:211], v[244:247], v[66:81]
	v_mfma_f32_32x32x16_f16 v[82:97], v[174:177], v[244:247], v[82:97]
	s_waitcnt lgkmcnt(15)
	v_mfma_f32_32x32x16_f16 v[34:49], v[208:211], v[200:203], v[34:49]
	v_mfma_f32_32x32x16_f16 v[50:65], v[174:177], v[200:203], v[50:65]
	s_waitcnt lgkmcnt(14)
	v_mfma_f32_32x32x16_f16 v[2:17], v[208:211], v[204:207], v[2:17]
	v_mfma_f32_32x32x16_f16 v[18:33], v[174:177], v[204:207], v[18:33]
	ds_read_b128 v[208:211], v214 offset:96
	ds_read_b128 v[240:243], v212 offset:96
	ds_read_b128 v[174:177], v214 offset:4704
	ds_read_b128 v[244:247], v212 offset:4704
	ds_read_b128 v[200:203], v212 offset:9312
	ds_read_b128 v[204:207], v212 offset:13920
	s_waitcnt lgkmcnt(14)
	v_mfma_f32_32x32x16_f16 v[98:113], v[232:235], v[216:219], v[98:113]
	s_waitcnt lgkmcnt(13)
	v_mfma_f32_32x32x16_f16 v[114:129], v[236:239], v[216:219], v[114:129]
	s_waitcnt lgkmcnt(12)
	v_mfma_f32_32x32x16_f16 v[66:81], v[232:235], v[220:223], v[66:81]
	v_mfma_f32_32x32x16_f16 v[82:97], v[236:239], v[220:223], v[82:97]
	s_waitcnt lgkmcnt(11)
	v_mfma_f32_32x32x16_f16 v[34:49], v[232:235], v[224:227], v[34:49]
	v_mfma_f32_32x32x16_f16 v[50:65], v[236:239], v[224:227], v[50:65]
	s_waitcnt lgkmcnt(10)
	v_mfma_f32_32x32x16_f16 v[2:17], v[232:235], v[228:231], v[2:17]
	v_mfma_f32_32x32x16_f16 v[18:33], v[236:239], v[228:231], v[18:33]
	s_waitcnt lgkmcnt(0)
	s_barrier
; DI f16v mfma32(h8v a, h8v b, f16v c) { return __builtin_amdgcn_mfma_f32_32x32x16_f16(a, b, c, 0, 0, 0); }
; template <bool GATHER>
; DI void gemm256_main(const h16* __restrict__ A, int lda, const int* __restrict__ idx, int m0,
;                      const h16* __restrict__ B, int ldb, int n0, int K, h16* lds, f16v (&acc)[4][2]) {
;     ...
;   for (int kt = 0; kt < nk; ++kt) {
;     const h16* As = lds + (kt & 1) * (512 * LDH);
;     const h16* Bs = As + 256 * LDH;
;     h16* Wn = lds + ((kt & 1) ^ 1) * (512 * LDH);
;     if (kt + 1 < nk) {
; #pragma unroll
;       for (int i = 0; i < 4; ++i) { *(u4v*)&Wn[lr * LDH + lc + 8 * i] = ra[i]; *(u4v*)&Wn[(256 + lr) * LDH + lc + 8 * i] = rb[i]; }
;     }
;     if (kt + 2 < nk) {
; #pragma unroll
;       for (int i = 0; i < 4; ++i) { ra[i] = *(const u4v*)(AP_ + 8 * i); rb[i] = *(const u4v*)(BP_ + 8 * i); }
;       ao += 64; bo += 64;
;     }
; #pragma unroll
;     for (int ks = 0; ks < 4; ++ks) {
;       h8v af[4], bf[2];
; #pragma unroll
;       for (int i = 0; i < 4; ++i) af[i] = *(const h8v*)&As[(wm * 128 + i * 32 + (lane & 31)) * LDH + ks * 16 + 8 * (lane >> 5)];
; #pragma unroll
;       for (int j = 0; j < 2; ++j) bf[j] = *(const h8v*)&Bs[(wn * 64 + j * 32 + (lane & 31)) * LDH + ks * 16 + 8 * (lane >> 5)];
; #pragma unroll
;       for (int i = 0; i < 4; ++i)
; #pragma unroll
;         for (int j = 0; j < 2; ++j) acc[i][j] = mfma32(bf[j], af[i], acc[i][j]);
;     }
;     __syncthreads();
;   }
	ds_read_b128 v[232:235], v213
	ds_read_b128 v[216:219], v215
	ds_read_b128 v[236:239], v213 offset:4608
	ds_read_b128 v[220:223], v215 offset:4608
	ds_read_b128 v[224:227], v215 offset:9216
	ds_read_b128 v[228:231], v215 offset:13824
	v_mfma_f32_32x32x16_f16 v[98:113], v[208:211], v[240:243], v[98:113]
	v_mfma_f32_32x32x16_f16 v[114:129], v[174:177], v[240:243], v[114:129]
	v_mfma_f32_32x32x16_f16 v[66:81], v[208:211], v[244:247], v[66:81]
	v_mfma_f32_32x32x16_f16 v[82:97], v[174:177], v[244:247], v[82:97]
	v_mfma_f32_32x32x16_f16 v[34:49], v[208:211], v[200:203], v[34:49]
	v_mfma_f32_32x32x16_f16 v[50:65], v[174:177], v[200:203], v[50:65]
	v_mfma_f32_32x32x16_f16 v[2:17], v[208:211], v[204:207], v[2:17]
	v_mfma_f32_32x32x16_f16 v[18:33], v[174:177], v[204:207], v[18:33]
	ds_read_b128 v[208:211], v213 offset:32
	ds_read_b128 v[240:243], v215 offset:32
	ds_read_b128 v[174:177], v213 offset:4640
	ds_read_b128 v[244:247], v215 offset:4640
	ds_read_b128 v[200:203], v215 offset:9248
	ds_read_b128 v[204:207], v215 offset:13856
	s_waitcnt vmcnt(4)
	ds_write_b128 v179, v[134:137]
	ds_write_b128 v179, v[138:141] offset:16
	ds_write_b128 v179, v[142:145] offset:32
	ds_write_b128 v179, v[146:149] offset:48
	s_waitcnt lgkmcnt(14)
	v_mfma_f32_32x32x16_f16 v[98:113], v[232:235], v[216:219], v[98:113]
	s_waitcnt lgkmcnt(13)
	v_mfma_f32_32x32x16_f16 v[114:129], v[236:239], v[216:219], v[114:129]
	s_waitcnt lgkmcnt(12)
	v_mfma_f32_32x32x16_f16 v[66:81], v[232:235], v[220:223], v[66:81]
	v_mfma_f32_32x32x16_f16 v[82:97], v[236:239], v[220:223], v[82:97]
	s_waitcnt lgkmcnt(11)
	v_mfma_f32_32x32x16_f16 v[34:49], v[232:235], v[224:227], v[34:49]
	v_mfma_f32_32x32x16_f16 v[50:65], v[236:239], v[224:227], v[50:65]
	s_waitcnt lgkmcnt(10)
	v_mfma_f32_32x32x16_f16 v[2:17], v[232:235], v[228:231], v[2:17]
	v_mfma_f32_32x32x16_f16 v[18:33], v[236:239], v[228:231], v[18:33]
	ds_read_b128 v[232:235], v213 offset:64
	ds_read_b128 v[216:219], v215 offset:64
	ds_read_b128 v[236:239], v213 offset:4672
	ds_read_b128 v[220:223], v215 offset:4672
	ds_read_b128 v[224:227], v215 offset:9280
	ds_read_b128 v[228:231], v215 offset:13888
	s_waitcnt vmcnt(0)
	ds_write_b128 v179, v[150:153] offset:36864
	ds_write_b128 v179, v[154:157] offset:36880
	ds_write_b128 v179, v[158:161] offset:36896
	ds_write_b128 v179, v[162:165] offset:36912
	s_waitcnt lgkmcnt(15)
	v_mfma_f32_32x32x16_f16 v[98:113], v[208:211], v[240:243], v[98:113]
	s_waitcnt lgkmcnt(15)
	v_mfma_f32_32x32x16_f16 v[114:129], v[174:177], v[240:243], v[114:129]
	s_waitcnt lgkmcnt(15)
	v_mfma_f32_32x32x16_f16 v[66:81], v[208:211], v[244:247], v[66:81]
	v_mfma_f32_32x32x16_f16 v[82:97], v[174:177], v[244:247], v[82:97]
	s_waitcnt lgkmcnt(15)
	v_mfma_f32_32x32x16_f16 v[34:49], v[208:211], v[200:203], v[34:49]
	v_mfma_f32_32x32x16_f16 v[50:65], v[174:177], v[200:203], v[50:65]
	s_waitcnt lgkmcnt(14)
	v_mfma_f32_32x32x16_f16 v[2:17], v[208:211], v[204:207], v[2:17]
	v_mfma_f32_32x32x16_f16 v[18:33], v[174:177], v[204:207], v[18:33]
	ds_read_b128 v[208:211], v213 offset:96
	ds_read_b128 v[240:243], v215 offset:96
	ds_read_b128 v[174:177], v213 offset:4704
	ds_read_b128 v[244:247], v215 offset:4704
	ds_read_b128 v[200:203], v215 offset:9312
	ds_read_b128 v[204:207], v215 offset:13920
	s_waitcnt lgkmcnt(14)
	v_mfma_f32_32x32x16_f16 v[98:113], v[232:235], v[216:219], v[98:113]
	s_waitcnt lgkmcnt(13)
	v_mfma_f32_32x32x16_f16 v[114:129], v[236:239], v[216:219], v[114:129]
	s_waitcnt lgkmcnt(12)
	v_mfma_f32_32x32x16_f16 v[66:81], v[232:235], v[220:223], v[66:81]
	v_mfma_f32_32x32x16_f16 v[82:97], v[236:239], v[220:223], v[82:97]
	s_waitcnt lgkmcnt(11)
	v_mfma_f32_32x32x16_f16 v[34:49], v[232:235], v[224:227], v[34:49]
	v_mfma_f32_32x32x16_f16 v[50:65], v[236:239], v[224:227], v[50:65]
	s_waitcnt lgkmcnt(10)
	v_mfma_f32_32x32x16_f16 v[2:17], v[232:235], v[228:231], v[2:17]
	v_mfma_f32_32x32x16_f16 v[18:33], v[236:239], v[228:231], v[18:33]
	s_waitcnt lgkmcnt(0)
	s_barrier
	ds_read_b128 v[232:235], v214
	ds_read_b128 v[216:219], v212
	ds_read_b128 v[236:239], v214 offset:4608
	ds_read_b128 v[220:223], v212 offset:4608
	ds_read_b128 v[224:227], v212 offset:9216
	ds_read_b128 v[228:231], v212 offset:13824
	v_mfma_f32_32x32x16_f16 v[98:113], v[208:211], v[240:243], v[98:113]
	v_mfma_f32_32x32x16_f16 v[114:129], v[174:177], v[240:243], v[114:129]
	v_mfma_f32_32x32x16_f16 v[66:81], v[208:211], v[244:247], v[66:81]
	v_mfma_f32_32x32x16_f16 v[82:97], v[174:177], v[244:247], v[82:97]
	v_mfma_f32_32x32x16_f16 v[34:49], v[208:211], v[200:203], v[34:49]
	v_mfma_f32_32x32x16_f16 v[50:65], v[174:177], v[200:203], v[50:65]
	v_mfma_f32_32x32x16_f16 v[2:17], v[208:211], v[204:207], v[2:17]
	v_mfma_f32_32x32x16_f16 v[18:33], v[174:177], v[204:207], v[18:33]
	ds_read_b128 v[208:211], v214 offset:32
	ds_read_b128 v[240:243], v212 offset:32
	ds_read_b128 v[174:177], v214 offset:4640
	ds_read_b128 v[244:247], v212 offset:4640
	ds_read_b128 v[200:203], v212 offset:9248
	ds_read_b128 v[204:207], v212 offset:13856
	s_waitcnt lgkmcnt(10)
	v_mfma_f32_32x32x16_f16 v[98:113], v[232:235], v[216:219], v[98:113]
	s_waitcnt lgkmcnt(9)
	v_mfma_f32_32x32x16_f16 v[114:129], v[236:239], v[216:219], v[114:129]
	s_waitcnt lgkmcnt(8)
	v_mfma_f32_32x32x16_f16 v[66:81], v[232:235], v[220:223], v[66:81]
	v_mfma_f32_32x32x16_f16 v[82:97], v[236:239], v[220:223], v[82:97]
	s_waitcnt lgkmcnt(7)
	v_mfma_f32_32x32x16_f16 v[34:49], v[232:235], v[224:227], v[34:49]
	v_mfma_f32_32x32x16_f16 v[50:65], v[236:239], v[224:227], v[50:65]
	s_waitcnt lgkmcnt(6)
; DI float silu_(float x) { return x / (1.f + __expf(-x)); }
; DI f16v mfma32(h8v a, h8v b, f16v c) { return __builtin_amdgcn_mfma_f32_32x32x16_f16(a, b, c, 0, 0, 0); }
; template <bool GATHER>
; DI void gemm256_main(const h16* __restrict__ A, int lda, const int* __restrict__ idx, int m0,
;                      const h16* __restrict__ B, int ldb, int n0, int K, h16* lds, f16v (&acc)[4][2]) {
;     ...
; #pragma unroll
;     for (int ks = 0; ks < 4; ++ks) {
;       h8v af[4], bf[2];
; #pragma unroll
;       for (int i = 0; i < 4; ++i) af[i] = *(const h8v*)&As[(wm * 128 + i * 32 + (lane & 31)) * LDH + ks * 16 + 8 * (lane >> 5)];
; #pragma unroll
;       for (int j = 0; j < 2; ++j) bf[j] = *(const h8v*)&Bs[(wn * 64 + j * 32 + (lane & 31)) * LDH + ks * 16 + 8 * (lane >> 5)];
; #pragma unroll
;       for (int i = 0; i < 4; ++i)
; #pragma unroll
;         for (int j = 0; j < 2; ++j) acc[i][j] = mfma32(bf[j], af[i], acc[i][j]);
;     }
;     __syncthreads();
;   }
; DI void phase_ffn1_dense(const Params& p, int bid, int nb, h16* lds) {
;     ...
;     gemm256_epilogue(acc, m0, n0, [&](int m, int n, f4v v0, f4v v1) {
;       f4v hq;
; #pragma unroll
;       for (int i = 0; i < 4; ++i) hq[i] = silu_(v0[i]) * v1[i];
;       st_h4(&H[(size_t)m * 2816 + (n >> 6) * 32 + (n & 31)], hq);
	v_mfma_f32_32x32x16_f16 v[2:17], v[232:235], v[228:231], v[2:17]
	v_mfma_f32_32x32x16_f16 v[18:33], v[236:239], v[228:231], v[18:33]
	ds_read_b128 v[232:235], v214 offset:64
	ds_read_b128 v[216:219], v212 offset:64
	ds_read_b128 v[236:239], v214 offset:4672
	ds_read_b128 v[220:223], v212 offset:4672
	ds_read_b128 v[224:227], v212 offset:9280
	ds_read_b128 v[228:231], v212 offset:13888
	s_waitcnt lgkmcnt(10)
	v_mfma_f32_32x32x16_f16 v[98:113], v[208:211], v[240:243], v[98:113]
	s_waitcnt lgkmcnt(9)
	v_mfma_f32_32x32x16_f16 v[114:129], v[174:177], v[240:243], v[114:129]
	s_waitcnt lgkmcnt(8)
	v_mfma_f32_32x32x16_f16 v[66:81], v[208:211], v[244:247], v[66:81]
	v_mfma_f32_32x32x16_f16 v[82:97], v[174:177], v[244:247], v[82:97]
	s_waitcnt lgkmcnt(7)
	v_mfma_f32_32x32x16_f16 v[34:49], v[208:211], v[200:203], v[34:49]
	v_mfma_f32_32x32x16_f16 v[50:65], v[174:177], v[200:203], v[50:65]
	s_waitcnt lgkmcnt(6)
	v_mfma_f32_32x32x16_f16 v[2:17], v[208:211], v[204:207], v[2:17]
	v_mfma_f32_32x32x16_f16 v[18:33], v[174:177], v[204:207], v[18:33]
	ds_read_b128 v[208:211], v214 offset:96
	ds_read_b128 v[240:243], v212 offset:96
	ds_read_b128 v[174:177], v214 offset:4704
	ds_read_b128 v[244:247], v212 offset:4704
	ds_read_b128 v[200:203], v212 offset:9312
	ds_read_b128 v[204:207], v212 offset:13920
	s_waitcnt lgkmcnt(10)
	v_mfma_f32_32x32x16_f16 v[98:113], v[232:235], v[216:219], v[98:113]
	s_waitcnt lgkmcnt(9)
	v_mfma_f32_32x32x16_f16 v[114:129], v[236:239], v[216:219], v[114:129]
	s_waitcnt lgkmcnt(8)
	v_mfma_f32_32x32x16_f16 v[66:81], v[232:235], v[220:223], v[66:81]
	v_mfma_f32_32x32x16_f16 v[82:97], v[236:239], v[220:223], v[82:97]
	s_waitcnt lgkmcnt(7)
	v_mfma_f32_32x32x16_f16 v[34:49], v[232:235], v[224:227], v[34:49]
	v_mfma_f32_32x32x16_f16 v[50:65], v[236:239], v[224:227], v[50:65]
	s_waitcnt lgkmcnt(6)
	v_mfma_f32_32x32x16_f16 v[2:17], v[232:235], v[228:231], v[2:17]
	v_mfma_f32_32x32x16_f16 v[18:33], v[236:239], v[228:231], v[18:33]
	s_waitcnt lgkmcnt(0)
	v_mfma_f32_32x32x16_f16 v[98:113], v[208:211], v[240:243], v[98:113]
	v_mfma_f32_32x32x16_f16 v[114:129], v[174:177], v[240:243], v[114:129]
	v_mfma_f32_32x32x16_f16 v[66:81], v[208:211], v[244:247], v[66:81]
	v_mfma_f32_32x32x16_f16 v[82:97], v[174:177], v[244:247], v[82:97]
	v_mfma_f32_32x32x16_f16 v[34:49], v[208:211], v[200:203], v[34:49]
	v_mfma_f32_32x32x16_f16 v[50:65], v[174:177], v[200:203], v[50:65]
	v_mfma_f32_32x32x16_f16 v[2:17], v[208:211], v[204:207], v[2:17]
	v_mfma_f32_32x32x16_f16 v[18:33], v[174:177], v[204:207], v[18:33]
	s_nop 15
	v_mov_b32_e32 v192, 0x7f800000
	v_mov_b32_e32 v193, 0x7fc00000
	v_mov_b32_e32 v194, 0xff800000
	v_mov_b32_e32 v204, 0x7fffec00
	v_mov_b32_e32 v205, 0xff7fc99e
	v_mov_b32_e32 v206, 0x840000
	v_mov_b32_e32 v207, 0xb00000
	v_mov_b32_e32 v208, 0xdc0000
	v_mov_b32_e32 v209, 0x1080000
	v_mov_b32_e32 v210, 0x1340000
	v_mov_b32_e32 v211, 0x420000
	v_mov_b32_e32 v212, 0x580000
	v_mov_b32_e32 v213, 0x6e0000
	v_mov_b32_e32 v214, 0x9a0000
	s_setprio 0
	s_barrier
	v_readfirstlane_b32 s66, v180
	s_sub_i32 s69, s2, s5
	s_mov_b32 s65, s4
	s_lshr_b32 s66, s66, 6
	s_and_b32 s67, s66, 3
	s_lshr_b32 s68, s66, 2
	s_lshr_b32 s70, s69, 1
	s_lshl_b32 s67, s67, 5
	s_add_i32 s70, s70, s67
	s_lshl_b32 s71, s68, 7
	s_add_i32 s71, s71, s65
	s_mul_i32 s72, s66, 0x2800
	s_add_i32 s72, s72, 16
	s_mov_b32 s73, 0x1600
	v_and_b32_e32 v146, 63, v180
	v_and_b32_e32 v148, 31, v146
	v_lshrrev_b32_e32 v147, 5, v146
	v_mul_u32_u24_e32 v130, 0x50, v148
	v_lshl_add_u32 v130, v147, 3, v130
	v_add_u32_e32 v130, s72, v130
	v_lshrrev_b32_e32 v149, 2, v146
	v_and_b32_e32 v138, 3, v146
	v_mul_u32_u24_e32 v131, 0x50, v149
	v_lshl_add_u32 v131, v138, 4, v131
	v_add_u32_e32 v131, s72, v131
	v_add_u32_e32 v140, s71, v149
	v_lshl_add_u32 v138, v138, 3, s70
	v_mov_b64_e32 v[132:133], s[0:1]
	v_mad_u64_u32 v[132:133], s[74:75], v140, s73, v[132:133]
	v_lshlrev_b32_e32 v138, 1, v138
	v_mov_b32_e32 v139, v0
	v_lshl_add_u64 v[132:133], v[132:133], 0, v[138:139]
	s_mov_b32 s76, 0x16000
	s_mov_b32 s77, 0
	v_mul_f32_e32 v232, 0xbfb8aa3b, v98
	v_mul_f32_e32 v233, 0xbfb8aa3b, v99
	v_mul_f32_e32 v234, 0xbfb8aa3b, v100
	v_mul_f32_e32 v235, 0xbfb8aa3b, v101
	v_exp_f32_e32 v232, v232
	v_exp_f32_e32 v233, v233
	v_exp_f32_e32 v234, v234
	v_exp_f32_e32 v235, v235
	v_add_f32_e32 v232, 1.0, v232
	v_add_f32_e32 v233, 1.0, v233
	v_add_f32_e32 v234, 1.0, v234
	v_add_f32_e32 v235, 1.0, v235
	v_rcp_f32_e32 v232, v232
	v_rcp_f32_e32 v233, v233
	v_rcp_f32_e32 v234, v234
	v_rcp_f32_e32 v235, v235
	v_mul_f32_e32 v98, v98, v232
	v_mul_f32_e32 v99, v99, v233
	v_mul_f32_e32 v100, v100, v234
	v_mul_f32_e32 v101, v101, v235
	v_mul_f32_e32 v98, v98, v114
	v_mul_f32_e32 v99, v99, v115
	v_mul_f32_e32 v100, v100, v116
	v_mul_f32_e32 v101, v101, v117
	v_cvt_pk_f16_f32 v138, v98, v99
	v_cvt_pk_f16_f32 v139, v100, v101
	ds_write_b64 v130, v[138:139] offset:0
	v_mul_f32_e32 v232, 0xbfb8aa3b, v102
	v_mul_f32_e32 v233, 0xbfb8aa3b, v103
	v_mul_f32_e32 v234, 0xbfb8aa3b, v104
	v_mul_f32_e32 v235, 0xbfb8aa3b, v105
	v_exp_f32_e32 v232, v232
	v_exp_f32_e32 v233, v233
	v_exp_f32_e32 v234, v234
	v_exp_f32_e32 v235, v235
	v_add_f32_e32 v232, 1.0, v232
	v_add_f32_e32 v233, 1.0, v233
	v_add_f32_e32 v234, 1.0, v234
	v_add_f32_e32 v235, 1.0, v235
	v_rcp_f32_e32 v232, v232
	v_rcp_f32_e32 v233, v233
	v_rcp_f32_e32 v234, v234
	v_rcp_f32_e32 v235, v235
	v_mul_f32_e32 v102, v102, v232
	v_mul_f32_e32 v103, v103, v233
	v_mul_f32_e32 v104, v104, v234
	v_mul_f32_e32 v105, v105, v235
	v_mul_f32_e32 v102, v102, v118
	v_mul_f32_e32 v103, v103, v119
	v_mul_f32_e32 v104, v104, v120
	v_mul_f32_e32 v105, v105, v121
	v_cvt_pk_f16_f32 v140, v102, v103
; DI int otid512() { int t = threadIdx.x; asm volatile("" : "+v"(t)); return t; }
; DI float silu_(float x) { return x / (1.f + __expf(-x)); }
; template <class Epi>
; DI void gemm256_epilogue(f16v (&acc)[4][2], int m0, int n0, Epi epi) {
;   const int tid = otid512(), lane = tid & 63, wv = tid >> 6, wm = wv >> 2, wn = wv & 3, h = lane >> 5;
; #pragma unroll
;   for (int i = 0; i < 4; ++i) {
;     const int m = m0 + wm * 128 + i * 32 + (lane & 31);
; #pragma unroll
;     for (int g = 0; g < 4; ++g) {
;       const int n = n0 + wn * 64 + 8 * g + 4 * h;
;       f4v v0 = {acc[i][0][4 * g], acc[i][0][4 * g + 1], acc[i][0][4 * g + 2], acc[i][0][4 * g + 3]};
;       f4v v1 = {acc[i][1][4 * g], acc[i][1][4 * g + 1], acc[i][1][4 * g + 2], acc[i][1][4 * g + 3]};
;       epi(m, n, v0, v1);
; DI void phase_ffn1_dense(const Params& p, int bid, int nb, h16* lds) {
;     ...
;     gemm256_epilogue(acc, m0, n0, [&](int m, int n, f4v v0, f4v v1) {
;       f4v hq;
; #pragma unroll
;       for (int i = 0; i < 4; ++i) hq[i] = silu_(v0[i]) * v1[i];
;       st_h4(&H[(size_t)m * 2816 + (n >> 6) * 32 + (n & 31)], hq);
	v_cvt_pk_f16_f32 v141, v104, v105
	ds_write_b64 v130, v[140:141] offset:16
	v_mul_f32_e32 v232, 0xbfb8aa3b, v106
	v_mul_f32_e32 v233, 0xbfb8aa3b, v107
	v_mul_f32_e32 v234, 0xbfb8aa3b, v108
	v_mul_f32_e32 v235, 0xbfb8aa3b, v109
	v_exp_f32_e32 v232, v232
	v_exp_f32_e32 v233, v233
	v_exp_f32_e32 v234, v234
	v_exp_f32_e32 v235, v235
	v_add_f32_e32 v232, 1.0, v232
	v_add_f32_e32 v233, 1.0, v233
	v_add_f32_e32 v234, 1.0, v234
	v_add_f32_e32 v235, 1.0, v235
	v_rcp_f32_e32 v232, v232
	v_rcp_f32_e32 v233, v233
	v_rcp_f32_e32 v234, v234
	v_rcp_f32_e32 v235, v235
	v_mul_f32_e32 v106, v106, v232
	v_mul_f32_e32 v107, v107, v233
	v_mul_f32_e32 v108, v108, v234
	v_mul_f32_e32 v109, v109, v235
	v_mul_f32_e32 v106, v106, v122
	v_mul_f32_e32 v107, v107, v123
	v_mul_f32_e32 v108, v108, v124
	v_mul_f32_e32 v109, v109, v125
	v_cvt_pk_f16_f32 v142, v106, v107
	v_cvt_pk_f16_f32 v143, v108, v109
	ds_write_b64 v130, v[142:143] offset:32
	v_mul_f32_e32 v232, 0xbfb8aa3b, v110
	v_mul_f32_e32 v233, 0xbfb8aa3b, v111
	v_mul_f32_e32 v234, 0xbfb8aa3b, v112
	v_mul_f32_e32 v235, 0xbfb8aa3b, v113
	v_exp_f32_e32 v232, v232
	v_exp_f32_e32 v233, v233
	v_exp_f32_e32 v234, v234
	v_exp_f32_e32 v235, v235
	v_add_f32_e32 v232, 1.0, v232
	v_add_f32_e32 v233, 1.0, v233
	v_add_f32_e32 v234, 1.0, v234
	v_add_f32_e32 v235, 1.0, v235
	v_rcp_f32_e32 v232, v232
	v_rcp_f32_e32 v233, v233
	v_rcp_f32_e32 v234, v234
	v_rcp_f32_e32 v235, v235
	v_mul_f32_e32 v110, v110, v232
	v_mul_f32_e32 v111, v111, v233
	v_mul_f32_e32 v112, v112, v234
	v_mul_f32_e32 v113, v113, v235
	v_mul_f32_e32 v110, v110, v126
	v_mul_f32_e32 v111, v111, v127
	v_mul_f32_e32 v112, v112, v128
	v_mul_f32_e32 v113, v113, v129
	v_cvt_pk_f16_f32 v144, v110, v111
	v_cvt_pk_f16_f32 v145, v112, v113
	ds_write_b64 v130, v[144:145] offset:48
	v_mul_f32_e32 v232, 0xbfb8aa3b, v66
	v_mul_f32_e32 v233, 0xbfb8aa3b, v67
	v_mul_f32_e32 v234, 0xbfb8aa3b, v68
	v_mul_f32_e32 v235, 0xbfb8aa3b, v69
	v_exp_f32_e32 v232, v232
	v_exp_f32_e32 v233, v233
	v_exp_f32_e32 v234, v234
	v_exp_f32_e32 v235, v235
	v_add_f32_e32 v232, 1.0, v232
	v_add_f32_e32 v233, 1.0, v233
	v_add_f32_e32 v234, 1.0, v234
	v_add_f32_e32 v235, 1.0, v235
	v_rcp_f32_e32 v232, v232
	v_rcp_f32_e32 v233, v233
	v_rcp_f32_e32 v234, v234
	v_rcp_f32_e32 v235, v235
	v_mul_f32_e32 v66, v66, v232
	v_mul_f32_e32 v67, v67, v233
	v_mul_f32_e32 v68, v68, v234
	v_mul_f32_e32 v69, v69, v235
	v_mul_f32_e32 v66, v66, v82
	v_mul_f32_e32 v67, v67, v83
	v_mul_f32_e32 v68, v68, v84
	v_mul_f32_e32 v69, v69, v85
	v_cvt_pk_f16_f32 v138, v66, v67
	v_cvt_pk_f16_f32 v139, v68, v69
	ds_write_b64 v130, v[138:139] offset:2560
	v_mul_f32_e32 v232, 0xbfb8aa3b, v70
	v_mul_f32_e32 v233, 0xbfb8aa3b, v71
	v_mul_f32_e32 v234, 0xbfb8aa3b, v72
	v_mul_f32_e32 v235, 0xbfb8aa3b, v73
	v_exp_f32_e32 v232, v232
	v_exp_f32_e32 v233, v233
	v_exp_f32_e32 v234, v234
	v_exp_f32_e32 v235, v235
	v_add_f32_e32 v232, 1.0, v232
	v_add_f32_e32 v233, 1.0, v233
	v_add_f32_e32 v234, 1.0, v234
	v_add_f32_e32 v235, 1.0, v235
	v_rcp_f32_e32 v232, v232
	v_rcp_f32_e32 v233, v233
	v_rcp_f32_e32 v234, v234
	v_rcp_f32_e32 v235, v235
	v_mul_f32_e32 v70, v70, v232
	v_mul_f32_e32 v71, v71, v233
	v_mul_f32_e32 v72, v72, v234
	v_mul_f32_e32 v73, v73, v235
	v_mul_f32_e32 v70, v70, v86
	v_mul_f32_e32 v71, v71, v87
	v_mul_f32_e32 v72, v72, v88
	v_mul_f32_e32 v73, v73, v89
	v_cvt_pk_f16_f32 v140, v70, v71
	v_cvt_pk_f16_f32 v141, v72, v73
	ds_write_b64 v130, v[140:141] offset:2576
	v_mul_f32_e32 v232, 0xbfb8aa3b, v74
	v_mul_f32_e32 v233, 0xbfb8aa3b, v75
	v_mul_f32_e32 v234, 0xbfb8aa3b, v76
	v_mul_f32_e32 v235, 0xbfb8aa3b, v77
	v_exp_f32_e32 v232, v232
	v_exp_f32_e32 v233, v233
	v_exp_f32_e32 v234, v234
	v_exp_f32_e32 v235, v235
	v_add_f32_e32 v232, 1.0, v232
	v_add_f32_e32 v233, 1.0, v233
	v_add_f32_e32 v234, 1.0, v234
	v_add_f32_e32 v235, 1.0, v235
	v_rcp_f32_e32 v232, v232
	v_rcp_f32_e32 v233, v233
	v_rcp_f32_e32 v234, v234
	v_rcp_f32_e32 v235, v235
	v_mul_f32_e32 v74, v74, v232
	v_mul_f32_e32 v75, v75, v233
	v_mul_f32_e32 v76, v76, v234
	v_mul_f32_e32 v77, v77, v235
	v_mul_f32_e32 v74, v74, v90
	v_mul_f32_e32 v75, v75, v91
	v_mul_f32_e32 v76, v76, v92
	v_mul_f32_e32 v77, v77, v93
	v_cvt_pk_f16_f32 v142, v74, v75
	v_cvt_pk_f16_f32 v143, v76, v77
	ds_write_b64 v130, v[142:143] offset:2592
	v_mul_f32_e32 v232, 0xbfb8aa3b, v78
	v_mul_f32_e32 v233, 0xbfb8aa3b, v79
	v_mul_f32_e32 v234, 0xbfb8aa3b, v80
	v_mul_f32_e32 v235, 0xbfb8aa3b, v81
	v_exp_f32_e32 v232, v232
	v_exp_f32_e32 v233, v233
	v_exp_f32_e32 v234, v234
	v_exp_f32_e32 v235, v235
	v_add_f32_e32 v232, 1.0, v232
	v_add_f32_e32 v233, 1.0, v233
	v_add_f32_e32 v234, 1.0, v234
	v_add_f32_e32 v235, 1.0, v235
	v_rcp_f32_e32 v232, v232
	v_rcp_f32_e32 v233, v233
	v_rcp_f32_e32 v234, v234
	v_rcp_f32_e32 v235, v235
	v_mul_f32_e32 v78, v78, v232
	v_mul_f32_e32 v79, v79, v233
	v_mul_f32_e32 v80, v80, v234
	v_mul_f32_e32 v81, v81, v235
	v_mul_f32_e32 v78, v78, v94
	v_mul_f32_e32 v79, v79, v95
	v_mul_f32_e32 v80, v80, v96
	v_mul_f32_e32 v81, v81, v97
	v_cvt_pk_f16_f32 v144, v78, v79
	v_cvt_pk_f16_f32 v145, v80, v81
	ds_write_b64 v130, v[144:145] offset:2608
	v_mul_f32_e32 v232, 0xbfb8aa3b, v34
	v_mul_f32_e32 v233, 0xbfb8aa3b, v35
	v_mul_f32_e32 v234, 0xbfb8aa3b, v36
	v_mul_f32_e32 v235, 0xbfb8aa3b, v37
	v_exp_f32_e32 v232, v232
	v_exp_f32_e32 v233, v233
	v_exp_f32_e32 v234, v234
	v_exp_f32_e32 v235, v235
	v_add_f32_e32 v232, 1.0, v232
	v_add_f32_e32 v233, 1.0, v233
	v_add_f32_e32 v234, 1.0, v234
	v_add_f32_e32 v235, 1.0, v235
	v_rcp_f32_e32 v232, v232
	v_rcp_f32_e32 v233, v233
	v_rcp_f32_e32 v234, v234
	v_rcp_f32_e32 v235, v235
	v_mul_f32_e32 v34, v34, v232
	v_mul_f32_e32 v35, v35, v233
	v_mul_f32_e32 v36, v36, v234
; DI int otid512() { int t = threadIdx.x; asm volatile("" : "+v"(t)); return t; }
; DI float silu_(float x) { return x / (1.f + __expf(-x)); }
; template <class Epi>
; DI void gemm256_epilogue(f16v (&acc)[4][2], int m0, int n0, Epi epi) {
;   const int tid = otid512(), lane = tid & 63, wv = tid >> 6, wm = wv >> 2, wn = wv & 3, h = lane >> 5;
; #pragma unroll
;   for (int i = 0; i < 4; ++i) {
;     const int m = m0 + wm * 128 + i * 32 + (lane & 31);
; #pragma unroll
;     for (int g = 0; g < 4; ++g) {
;       const int n = n0 + wn * 64 + 8 * g + 4 * h;
;       f4v v0 = {acc[i][0][4 * g], acc[i][0][4 * g + 1], acc[i][0][4 * g + 2], acc[i][0][4 * g + 3]};
;       f4v v1 = {acc[i][1][4 * g], acc[i][1][4 * g + 1], acc[i][1][4 * g + 2], acc[i][1][4 * g + 3]};
;       epi(m, n, v0, v1);
; DI void phase_ffn1_dense(const Params& p, int bid, int nb, h16* lds) {
;     ...
;     gemm256_epilogue(acc, m0, n0, [&](int m, int n, f4v v0, f4v v1) {
;       f4v hq;
; #pragma unroll
;       for (int i = 0; i < 4; ++i) hq[i] = silu_(v0[i]) * v1[i];
;       st_h4(&H[(size_t)m * 2816 + (n >> 6) * 32 + (n & 31)], hq);
	v_mul_f32_e32 v37, v37, v235
	v_mul_f32_e32 v34, v34, v50
	v_mul_f32_e32 v35, v35, v51
	v_mul_f32_e32 v36, v36, v52
	v_mul_f32_e32 v37, v37, v53
	v_cvt_pk_f16_f32 v138, v34, v35
	v_cvt_pk_f16_f32 v139, v36, v37
	ds_write_b64 v130, v[138:139] offset:5120
	v_mul_f32_e32 v232, 0xbfb8aa3b, v38
	v_mul_f32_e32 v233, 0xbfb8aa3b, v39
	v_mul_f32_e32 v234, 0xbfb8aa3b, v40
	v_mul_f32_e32 v235, 0xbfb8aa3b, v41
	v_exp_f32_e32 v232, v232
	v_exp_f32_e32 v233, v233
	v_exp_f32_e32 v234, v234
	v_exp_f32_e32 v235, v235
	v_add_f32_e32 v232, 1.0, v232
	v_add_f32_e32 v233, 1.0, v233
	v_add_f32_e32 v234, 1.0, v234
	v_add_f32_e32 v235, 1.0, v235
	v_rcp_f32_e32 v232, v232
	v_rcp_f32_e32 v233, v233
	v_rcp_f32_e32 v234, v234
	v_rcp_f32_e32 v235, v235
	v_mul_f32_e32 v38, v38, v232
	v_mul_f32_e32 v39, v39, v233
	v_mul_f32_e32 v40, v40, v234
	v_mul_f32_e32 v41, v41, v235
	v_mul_f32_e32 v38, v38, v54
	v_mul_f32_e32 v39, v39, v55
	v_mul_f32_e32 v40, v40, v56
	v_mul_f32_e32 v41, v41, v57
	v_cvt_pk_f16_f32 v140, v38, v39
	v_cvt_pk_f16_f32 v141, v40, v41
	ds_write_b64 v130, v[140:141] offset:5136
	v_mul_f32_e32 v232, 0xbfb8aa3b, v42
	v_mul_f32_e32 v233, 0xbfb8aa3b, v43
	v_mul_f32_e32 v234, 0xbfb8aa3b, v44
	v_mul_f32_e32 v235, 0xbfb8aa3b, v45
	v_exp_f32_e32 v232, v232
	v_exp_f32_e32 v233, v233
	v_exp_f32_e32 v234, v234
	v_exp_f32_e32 v235, v235
	v_add_f32_e32 v232, 1.0, v232
	v_add_f32_e32 v233, 1.0, v233
	v_add_f32_e32 v234, 1.0, v234
	v_add_f32_e32 v235, 1.0, v235
	v_rcp_f32_e32 v232, v232
	v_rcp_f32_e32 v233, v233
	v_rcp_f32_e32 v234, v234
	v_rcp_f32_e32 v235, v235
	v_mul_f32_e32 v42, v42, v232
	v_mul_f32_e32 v43, v43, v233
	v_mul_f32_e32 v44, v44, v234
	v_mul_f32_e32 v45, v45, v235
	v_mul_f32_e32 v42, v42, v58
	v_mul_f32_e32 v43, v43, v59
	v_mul_f32_e32 v44, v44, v60
	v_mul_f32_e32 v45, v45, v61
	v_cvt_pk_f16_f32 v142, v42, v43
	v_cvt_pk_f16_f32 v143, v44, v45
	ds_write_b64 v130, v[142:143] offset:5152
	v_mul_f32_e32 v232, 0xbfb8aa3b, v46
	v_mul_f32_e32 v233, 0xbfb8aa3b, v47
	v_mul_f32_e32 v234, 0xbfb8aa3b, v48
	v_mul_f32_e32 v235, 0xbfb8aa3b, v49
	v_exp_f32_e32 v232, v232
	v_exp_f32_e32 v233, v233
	v_exp_f32_e32 v234, v234
	v_exp_f32_e32 v235, v235
	v_add_f32_e32 v232, 1.0, v232
	v_add_f32_e32 v233, 1.0, v233
	v_add_f32_e32 v234, 1.0, v234
	v_add_f32_e32 v235, 1.0, v235
	v_rcp_f32_e32 v232, v232
	v_rcp_f32_e32 v233, v233
	v_rcp_f32_e32 v234, v234
	v_rcp_f32_e32 v235, v235
	v_mul_f32_e32 v46, v46, v232
	v_mul_f32_e32 v47, v47, v233
	v_mul_f32_e32 v48, v48, v234
	v_mul_f32_e32 v49, v49, v235
	v_mul_f32_e32 v46, v46, v62
	v_mul_f32_e32 v47, v47, v63
	v_mul_f32_e32 v48, v48, v64
	v_mul_f32_e32 v49, v49, v65
	v_cvt_pk_f16_f32 v144, v46, v47
	v_cvt_pk_f16_f32 v145, v48, v49
	ds_write_b64 v130, v[144:145] offset:5168
	v_mul_f32_e32 v232, 0xbfb8aa3b, v2
	v_mul_f32_e32 v233, 0xbfb8aa3b, v3
	v_mul_f32_e32 v234, 0xbfb8aa3b, v4
	v_mul_f32_e32 v235, 0xbfb8aa3b, v5
	v_exp_f32_e32 v232, v232
	v_exp_f32_e32 v233, v233
	v_exp_f32_e32 v234, v234
	v_exp_f32_e32 v235, v235
	v_add_f32_e32 v232, 1.0, v232
	v_add_f32_e32 v233, 1.0, v233
	v_add_f32_e32 v234, 1.0, v234
	v_add_f32_e32 v235, 1.0, v235
	v_rcp_f32_e32 v232, v232
	v_rcp_f32_e32 v233, v233
	v_rcp_f32_e32 v234, v234
	v_rcp_f32_e32 v235, v235
	v_mul_f32_e32 v2, v2, v232
	v_mul_f32_e32 v3, v3, v233
	v_mul_f32_e32 v4, v4, v234
	v_mul_f32_e32 v5, v5, v235
	v_mul_f32_e32 v2, v2, v18
	v_mul_f32_e32 v3, v3, v19
	v_mul_f32_e32 v4, v4, v20
	v_mul_f32_e32 v5, v5, v21
	v_cvt_pk_f16_f32 v138, v2, v3
	v_cvt_pk_f16_f32 v139, v4, v5
	ds_write_b64 v130, v[138:139] offset:7680
	v_mul_f32_e32 v232, 0xbfb8aa3b, v6
	v_mul_f32_e32 v233, 0xbfb8aa3b, v7
	v_mul_f32_e32 v234, 0xbfb8aa3b, v8
	v_mul_f32_e32 v235, 0xbfb8aa3b, v9
	v_exp_f32_e32 v232, v232
	v_exp_f32_e32 v233, v233
	v_exp_f32_e32 v234, v234
	v_exp_f32_e32 v235, v235
	v_add_f32_e32 v232, 1.0, v232
	v_add_f32_e32 v233, 1.0, v233
	v_add_f32_e32 v234, 1.0, v234
	v_add_f32_e32 v235, 1.0, v235
	v_rcp_f32_e32 v232, v232
	v_rcp_f32_e32 v233, v233
	v_rcp_f32_e32 v234, v234
	v_rcp_f32_e32 v235, v235
	v_mul_f32_e32 v6, v6, v232
	v_mul_f32_e32 v7, v7, v233
	v_mul_f32_e32 v8, v8, v234
	v_mul_f32_e32 v9, v9, v235
	v_mul_f32_e32 v6, v6, v22
	v_mul_f32_e32 v7, v7, v23
	v_mul_f32_e32 v8, v8, v24
	v_mul_f32_e32 v9, v9, v25
	v_cvt_pk_f16_f32 v140, v6, v7
	v_cvt_pk_f16_f32 v141, v8, v9
	ds_write_b64 v130, v[140:141] offset:7696
	v_mul_f32_e32 v232, 0xbfb8aa3b, v10
	v_mul_f32_e32 v233, 0xbfb8aa3b, v11
	v_mul_f32_e32 v234, 0xbfb8aa3b, v12
	v_mul_f32_e32 v235, 0xbfb8aa3b, v13
	v_exp_f32_e32 v232, v232
	v_exp_f32_e32 v233, v233
	v_exp_f32_e32 v234, v234
	v_exp_f32_e32 v235, v235
	v_add_f32_e32 v232, 1.0, v232
	v_add_f32_e32 v233, 1.0, v233
	v_add_f32_e32 v234, 1.0, v234
	v_add_f32_e32 v235, 1.0, v235
	v_rcp_f32_e32 v232, v232
	v_rcp_f32_e32 v233, v233
	v_rcp_f32_e32 v234, v234
	v_rcp_f32_e32 v235, v235
	v_mul_f32_e32 v10, v10, v232
	v_mul_f32_e32 v11, v11, v233
	v_mul_f32_e32 v12, v12, v234
	v_mul_f32_e32 v13, v13, v235
	v_mul_f32_e32 v10, v10, v26
	v_mul_f32_e32 v11, v11, v27
	v_mul_f32_e32 v12, v12, v28
	v_mul_f32_e32 v13, v13, v29
	v_cvt_pk_f16_f32 v142, v10, v11
	v_cvt_pk_f16_f32 v143, v12, v13
	ds_write_b64 v130, v[142:143] offset:7712
	v_mul_f32_e32 v232, 0xbfb8aa3b, v14
	v_mul_f32_e32 v233, 0xbfb8aa3b, v15
	v_mul_f32_e32 v234, 0xbfb8aa3b, v16
	v_mul_f32_e32 v235, 0xbfb8aa3b, v17
	v_exp_f32_e32 v232, v232
	v_exp_f32_e32 v233, v233
	v_exp_f32_e32 v234, v234
	v_exp_f32_e32 v235, v235
	v_add_f32_e32 v232, 1.0, v232
	v_add_f32_e32 v233, 1.0, v233
	v_add_f32_e32 v234, 1.0, v234
	v_add_f32_e32 v235, 1.0, v235
	v_rcp_f32_e32 v232, v232
	v_rcp_f32_e32 v233, v233
	v_rcp_f32_e32 v234, v234
	v_rcp_f32_e32 v235, v235
	v_mul_f32_e32 v14, v14, v232
	v_mul_f32_e32 v15, v15, v233
	v_mul_f32_e32 v16, v16, v234
	v_mul_f32_e32 v17, v17, v235
	v_mul_f32_e32 v14, v14, v30
	v_mul_f32_e32 v15, v15, v31
	v_mul_f32_e32 v16, v16, v32
	v_mul_f32_e32 v17, v17, v33
	v_cvt_pk_f16_f32 v144, v14, v15
	v_cvt_pk_f16_f32 v145, v16, v17
	ds_write_b64 v130, v[144:145] offset:7728
	ds_read_b128 v[150:153], v131 offset:0
	ds_read_b128 v[154:157], v131 offset:1280
	ds_read_b128 v[158:161], v131 offset:2560
	ds_read_b128 v[162:165], v131 offset:3840
	ds_read_b128 v[216:219], v131 offset:5120
	ds_read_b128 v[220:223], v131 offset:6400
	ds_read_b128 v[224:227], v131 offset:7680
	ds_read_b128 v[228:231], v131 offset:8960
	s_waitcnt lgkmcnt(7)
; DI float silu_(float x) { return x / (1.f + __expf(-x)); }
; DI void phase_ffn1_dense(const Params& p, int bid, int nb, h16* lds) {
;     ...
;   for (int u = bid; u < 64 * 22; u += nb) {
;     const int m0 = (u / 22) * 256, n0 = (u % 22) * 256;
;     f16v acc[4][2]; acc256_zero(acc);
;     gemm256_main<false>(x16, DM, nullptr, m0, w13, 1024, n0, 1024, lds, acc);
;     gemm256_epilogue(acc, m0, n0, [&](int m, int n, f4v v0, f4v v1) {
;       f4v hq;
; #pragma unroll
;       for (int i = 0; i < 4; ++i) hq[i] = silu_(v0[i]) * v1[i];
;       st_h4(&H[(size_t)m * 2816 + (n >> 6) * 32 + (n & 31)], hq);
;     });
	global_store_dwordx4 v[132:133], v[150:153], off
	v_lshl_add_u64 v[132:133], v[132:133], 0, s[76:77]
	s_waitcnt lgkmcnt(6)
	global_store_dwordx4 v[132:133], v[154:157], off
	v_lshl_add_u64 v[132:133], v[132:133], 0, s[76:77]
	s_waitcnt lgkmcnt(5)
	global_store_dwordx4 v[132:133], v[158:161], off
	v_lshl_add_u64 v[132:133], v[132:133], 0, s[76:77]
	s_waitcnt lgkmcnt(4)
	global_store_dwordx4 v[132:133], v[162:165], off
	v_lshl_add_u64 v[132:133], v[132:133], 0, s[76:77]
	s_waitcnt lgkmcnt(3)
	global_store_dwordx4 v[132:133], v[216:219], off
	v_lshl_add_u64 v[132:133], v[132:133], 0, s[76:77]
	s_waitcnt lgkmcnt(2)
	global_store_dwordx4 v[132:133], v[220:223], off
	v_lshl_add_u64 v[132:133], v[132:133], 0, s[76:77]
	s_waitcnt lgkmcnt(1)
	global_store_dwordx4 v[132:133], v[224:227], off
	v_lshl_add_u64 v[132:133], v[132:133], 0, s[76:77]
	s_waitcnt lgkmcnt(0)
	global_store_dwordx4 v[132:133], v[228:231], off
	v_lshl_add_u64 v[132:133], v[132:133], 0, s[76:77]
	s_add_i32 s2, s2, s16
	s_cmpk_lt_i32 s3, 0x580
	s_cbranch_scc1 .LBB0_1626
